# global loads, prefetch waits moved, pipelined x+=g*acc epilogue, FF1 stagger
# speedup vs baseline: 1.0133x; 1.0133x over previous
.LBB0_13:
	s_or_b64 exec, exec, s[14:15]
	global_load_dword v4, v[6:7], off
	v_add_u32_e32 v7, 0x200, v9
	v_cmp_lt_i32_e32 vcc, s20, v9
	v_lshl_add_u64 v[2:3], v[2:3], 0, s[10:11]
	s_or_b64 s[8:9], vcc, s[8:9]
	v_mov_b32_e32 v9, v7
	s_waitcnt vmcnt(0) lgkmcnt(0)
	v_mul_f32_e32 v6, 0xbfb8aa3b, v4
	v_exp_f32_e32 v6, v6
	s_nop 0
	v_add_f32_e32 v6, 1.0, v6
	v_rcp_f32_e32 v6, v6
	s_nop 0
	v_mul_f32_e32 v4, v4, v6
	ds_write_b32 v8, v4
	v_add_u32_e32 v8, 0x800, v8
	s_andn2_b64 exec, exec, s[8:9]
	s_cbranch_execz .LBB0_18

.LBB0_21:
	v_add_co_u32_e64 v38, s[6:7], s18, v118
	v_mov_b32_e32 v121, s40
	s_nop 0
	v_addc_co_u32_e64 v39, s[6:7], -1, v119, s[6:7]
	v_add_co_u32_e64 v40, s[6:7], s19, v118
	s_add_i32 s39, s39, 16
	s_nop 0
	v_addc_co_u32_e64 v41, s[6:7], -1, v119, s[6:7]
	global_load_dwordx4 v[122:125], v[38:39], off
	global_load_dwordx4 v[126:129], v[40:41], off
	ds_read_b128 v[78:81], v121
	ds_read_b128 v[50:53], v121 offset:16
	ds_read_b128 v[74:77], v121 offset:4096
	ds_read_b128 v[54:57], v121 offset:4112
	ds_read_b128 v[82:85], v121 offset:8192
	ds_read_b128 v[58:61], v121 offset:8208
	ds_read_b128 v[86:89], v121 offset:12288
	ds_read_b128 v[62:65], v121 offset:12304
	ds_read_b128 v[90:93], v121 offset:16384
	ds_read_b128 v[66:69], v121 offset:16400
	ds_read_b128 v[94:97], v121 offset:20480
	ds_read_b128 v[70:73], v121 offset:20496
	ds_read_b128 v[98:101], v121 offset:24576
	ds_read_b128 v[38:41], v121 offset:24592
	ds_read_b128 v[102:105], v121 offset:28672
	ds_read_b128 v[42:45], v121 offset:28688
	ds_read_b128 v[106:109], v121 offset:32768
	ds_read_b128 v[46:49], v121 offset:32784
	s_add_i32 s40, s40, 64
	s_cmp_ge_i32 s39, s15
	s_waitcnt vmcnt(0) lgkmcnt(0)
	v_fmac_f32_e32 v6, v122, v74
	v_fmac_f32_e32 v7, v123, v74
	v_fmac_f32_e32 v8, v124, v74
	v_fmac_f32_e32 v9, v125, v74
	v_add_co_u32_e64 v74, s[6:7], s20, v118
	v_fmac_f32_e32 v9, v129, v75
	v_fmac_f32_e32 v8, v128, v75
	v_fmac_f32_e32 v7, v127, v75
	v_fmac_f32_e32 v6, v126, v75
	v_addc_co_u32_e64 v75, s[6:7], -1, v119, s[6:7]
	v_fmac_f32_e32 v2, v122, v78
	v_fmac_f32_e32 v3, v123, v78
	v_fmac_f32_e32 v4, v124, v78
	v_fmac_f32_e32 v5, v125, v78
	v_fmac_f32_e32 v10, v122, v82
	v_fmac_f32_e32 v11, v123, v82
	v_fmac_f32_e32 v12, v124, v82
	v_fmac_f32_e32 v13, v125, v82
	v_fmac_f32_e32 v14, v122, v86
	v_fmac_f32_e32 v15, v123, v86
	v_fmac_f32_e32 v16, v124, v86
	v_fmac_f32_e32 v17, v125, v86
	v_fmac_f32_e32 v18, v122, v90
	v_fmac_f32_e32 v19, v123, v90
	v_fmac_f32_e32 v20, v124, v90
	v_fmac_f32_e32 v21, v125, v90
	v_fmac_f32_e32 v22, v122, v94
	v_fmac_f32_e32 v23, v123, v94
	v_fmac_f32_e32 v24, v124, v94
	v_fmac_f32_e32 v25, v125, v94
	v_fmac_f32_e32 v26, v122, v98
	v_fmac_f32_e32 v27, v123, v98
	v_fmac_f32_e32 v28, v124, v98
	v_fmac_f32_e32 v29, v125, v98
	v_fmac_f32_e32 v30, v122, v102
	v_fmac_f32_e32 v31, v123, v102
	v_fmac_f32_e32 v32, v124, v102
	v_fmac_f32_e32 v33, v125, v102
	v_fmac_f32_e32 v34, v122, v106
	v_fmac_f32_e32 v35, v123, v106
	v_fmac_f32_e32 v36, v124, v106
	v_fmac_f32_e32 v37, v125, v106
	v_add_co_u32_e64 v78, s[6:7], s21, v118
	v_fmac_f32_e32 v5, v129, v79
	v_fmac_f32_e32 v4, v128, v79
	v_fmac_f32_e32 v3, v127, v79
	v_fmac_f32_e32 v2, v126, v79
	v_fmac_f32_e32 v13, v129, v83
	v_fmac_f32_e32 v12, v128, v83
	v_fmac_f32_e32 v11, v127, v83
	v_fmac_f32_e32 v10, v126, v83
	v_fmac_f32_e32 v17, v129, v87
	v_fmac_f32_e32 v16, v128, v87
	v_fmac_f32_e32 v15, v127, v87
	v_fmac_f32_e32 v14, v126, v87
	v_fmac_f32_e32 v21, v129, v91
	v_fmac_f32_e32 v20, v128, v91
	v_fmac_f32_e32 v19, v127, v91
	v_fmac_f32_e32 v18, v126, v91
	v_fmac_f32_e32 v25, v129, v95
	v_fmac_f32_e32 v24, v128, v95
	v_fmac_f32_e32 v23, v127, v95
	v_fmac_f32_e32 v22, v126, v95
	v_fmac_f32_e32 v29, v129, v99
	v_fmac_f32_e32 v28, v128, v99
	v_fmac_f32_e32 v27, v127, v99
	v_fmac_f32_e32 v26, v126, v99
	v_fmac_f32_e32 v33, v129, v103
	v_fmac_f32_e32 v32, v128, v103
	v_fmac_f32_e32 v31, v127, v103
	v_fmac_f32_e32 v30, v126, v103
	v_fmac_f32_e32 v37, v129, v107
	v_fmac_f32_e32 v36, v128, v107
	v_fmac_f32_e32 v35, v127, v107
	v_fmac_f32_e32 v34, v126, v107
	v_addc_co_u32_e64 v79, s[6:7], -1, v119, s[6:7]
	global_load_dwordx4 v[122:125], v[74:75], off
	global_load_dwordx4 v[126:129], v[78:79], off
	v_add_co_u32_e64 v74, s[6:7], s22, v118
	s_waitcnt vmcnt(0) lgkmcnt(0)
	v_fmac_f32_e32 v2, v122, v80
	v_addc_co_u32_e64 v75, s[6:7], -1, v119, s[6:7]
	v_add_co_u32_e64 v78, s[6:7], s23, v118
	v_fmac_f32_e32 v3, v123, v80
	v_fmac_f32_e32 v4, v124, v80
	v_fmac_f32_e32 v5, v125, v80
	v_fmac_f32_e32 v6, v122, v76
	v_fmac_f32_e32 v7, v123, v76
	v_fmac_f32_e32 v8, v124, v76
	v_fmac_f32_e32 v9, v125, v76
	v_addc_co_u32_e64 v79, s[6:7], -1, v119, s[6:7]
	v_fmac_f32_e32 v5, v129, v81
	v_fmac_f32_e32 v4, v128, v81
	v_fmac_f32_e32 v3, v127, v81
	v_fmac_f32_e32 v2, v126, v81
	v_fmac_f32_e32 v9, v129, v77
	v_fmac_f32_e32 v8, v128, v77
	v_fmac_f32_e32 v7, v127, v77
	v_fmac_f32_e32 v6, v126, v77
	global_load_dwordx4 v[74:77], v[74:75], off
	s_nop 0
	global_load_dwordx4 v[78:81], v[78:79], off
	v_fmac_f32_e32 v26, v122, v100
	v_fmac_f32_e32 v27, v123, v100
	v_fmac_f32_e32 v28, v124, v100
	v_fmac_f32_e32 v29, v125, v100
	v_fmac_f32_e32 v29, v129, v101
	v_fmac_f32_e32 v28, v128, v101
	v_fmac_f32_e32 v27, v127, v101
	v_fmac_f32_e32 v26, v126, v101
	v_fmac_f32_e32 v10, v122, v84
	v_fmac_f32_e32 v11, v123, v84
	v_fmac_f32_e32 v12, v124, v84
	v_fmac_f32_e32 v13, v125, v84
	v_fmac_f32_e32 v14, v122, v88
	v_fmac_f32_e32 v15, v123, v88
	v_fmac_f32_e32 v16, v124, v88
	v_fmac_f32_e32 v17, v125, v88
	v_fmac_f32_e32 v18, v122, v92
	v_fmac_f32_e32 v19, v123, v92
	v_fmac_f32_e32 v20, v124, v92
	v_fmac_f32_e32 v21, v125, v92
	v_fmac_f32_e32 v22, v122, v96
	v_fmac_f32_e32 v23, v123, v96
	v_fmac_f32_e32 v24, v124, v96
	v_fmac_f32_e32 v25, v125, v96
	v_fmac_f32_e32 v30, v122, v104
	v_fmac_f32_e32 v31, v123, v104
	v_fmac_f32_e32 v32, v124, v104
	v_fmac_f32_e32 v33, v125, v104
	v_fmac_f32_e32 v34, v122, v108
	v_fmac_f32_e32 v35, v123, v108
	v_fmac_f32_e32 v36, v124, v108
	v_fmac_f32_e32 v37, v125, v108
	v_fmac_f32_e32 v13, v129, v85
	v_fmac_f32_e32 v12, v128, v85
	v_fmac_f32_e32 v11, v127, v85
	v_fmac_f32_e32 v10, v126, v85
	v_fmac_f32_e32 v17, v129, v89
	v_fmac_f32_e32 v16, v128, v89
	v_fmac_f32_e32 v15, v127, v89
	v_fmac_f32_e32 v14, v126, v89
	v_fmac_f32_e32 v21, v129, v93
	v_fmac_f32_e32 v20, v128, v93
	v_fmac_f32_e32 v19, v127, v93
	v_fmac_f32_e32 v18, v126, v93
	v_fmac_f32_e32 v25, v129, v97
	v_fmac_f32_e32 v24, v128, v97
	v_fmac_f32_e32 v23, v127, v97
	v_fmac_f32_e32 v22, v126, v97
	v_fmac_f32_e32 v33, v129, v105
	v_fmac_f32_e32 v32, v128, v105
	v_fmac_f32_e32 v31, v127, v105
	v_fmac_f32_e32 v30, v126, v105
	v_fmac_f32_e32 v37, v129, v109
	v_fmac_f32_e32 v36, v128, v109
	v_fmac_f32_e32 v35, v127, v109
	v_fmac_f32_e32 v34, v126, v109
	s_waitcnt vmcnt(0) lgkmcnt(0)
	v_fmac_f32_e32 v26, v74, v38
	v_fmac_f32_e32 v27, v75, v38
	v_fmac_f32_e32 v28, v76, v38
	v_fmac_f32_e32 v29, v77, v38
	v_add_co_u32_e64 v38, s[6:7], s24, v118
	v_fmac_f32_e32 v29, v81, v39
	v_fmac_f32_e32 v28, v80, v39
	v_fmac_f32_e32 v27, v79, v39
	v_fmac_f32_e32 v26, v78, v39
	v_addc_co_u32_e64 v39, s[6:7], -1, v119, s[6:7]
	v_fmac_f32_e32 v2, v74, v50
	v_fmac_f32_e32 v3, v75, v50
	v_fmac_f32_e32 v4, v76, v50
	v_fmac_f32_e32 v5, v77, v50
	v_fmac_f32_e32 v6, v74, v54
	v_fmac_f32_e32 v7, v75, v54
	v_fmac_f32_e32 v8, v76, v54
	v_fmac_f32_e32 v9, v77, v54
	v_fmac_f32_e32 v10, v74, v58
	v_fmac_f32_e32 v11, v75, v58
	v_fmac_f32_e32 v12, v76, v58
	v_fmac_f32_e32 v13, v77, v58
	v_fmac_f32_e32 v14, v74, v62
	v_fmac_f32_e32 v15, v75, v62
	v_fmac_f32_e32 v16, v76, v62
	v_fmac_f32_e32 v17, v77, v62
	v_fmac_f32_e32 v18, v74, v66
	v_fmac_f32_e32 v19, v75, v66
	v_fmac_f32_e32 v20, v76, v66
	v_fmac_f32_e32 v21, v77, v66
	v_fmac_f32_e32 v22, v74, v70
	v_fmac_f32_e32 v23, v75, v70
	v_fmac_f32_e32 v24, v76, v70
	v_fmac_f32_e32 v25, v77, v70
	v_fmac_f32_e32 v30, v74, v42
	v_fmac_f32_e32 v31, v75, v42
	v_fmac_f32_e32 v32, v76, v42
	v_fmac_f32_e32 v33, v77, v42
	v_fmac_f32_e32 v34, v74, v46
	v_fmac_f32_e32 v35, v75, v46
	v_fmac_f32_e32 v36, v76, v46
	v_fmac_f32_e32 v37, v77, v46
	v_add_co_u32_e64 v42, s[6:7], s25, v118
	v_fmac_f32_e32 v5, v81, v51
	v_fmac_f32_e32 v4, v80, v51
	v_fmac_f32_e32 v3, v79, v51
	v_fmac_f32_e32 v2, v78, v51
	v_fmac_f32_e32 v9, v81, v55
	v_fmac_f32_e32 v8, v80, v55
	v_fmac_f32_e32 v7, v79, v55
	v_fmac_f32_e32 v6, v78, v55
	v_fmac_f32_e32 v13, v81, v59
	v_fmac_f32_e32 v12, v80, v59
	v_fmac_f32_e32 v11, v79, v59
	v_fmac_f32_e32 v10, v78, v59
	v_fmac_f32_e32 v17, v81, v63
	v_fmac_f32_e32 v16, v80, v63
	v_fmac_f32_e32 v15, v79, v63
	v_fmac_f32_e32 v14, v78, v63
	v_fmac_f32_e32 v21, v81, v67
	v_fmac_f32_e32 v20, v80, v67
	v_fmac_f32_e32 v19, v79, v67
	v_fmac_f32_e32 v18, v78, v67
	v_fmac_f32_e32 v25, v81, v71
	v_fmac_f32_e32 v24, v80, v71
	v_fmac_f32_e32 v23, v79, v71
	v_fmac_f32_e32 v22, v78, v71
	v_fmac_f32_e32 v33, v81, v43
	v_fmac_f32_e32 v32, v80, v43
	v_fmac_f32_e32 v31, v79, v43
	v_fmac_f32_e32 v30, v78, v43
	v_fmac_f32_e32 v37, v81, v47
	v_fmac_f32_e32 v36, v80, v47
	v_fmac_f32_e32 v35, v79, v47
	v_fmac_f32_e32 v34, v78, v47
	v_addc_co_u32_e64 v43, s[6:7], -1, v119, s[6:7]
	global_load_dwordx4 v[74:77], v[38:39], off
	global_load_dwordx4 v[78:81], v[42:43], off
	v_add_co_u32_e64 v38, s[6:7], s26, v118
	s_waitcnt vmcnt(0) lgkmcnt(0)
	v_fmac_f32_e32 v2, v74, v52
	v_addc_co_u32_e64 v39, s[6:7], -1, v119, s[6:7]
	v_add_co_u32_e64 v42, s[6:7], s27, v118
	v_fmac_f32_e32 v3, v75, v52
	s_nop 0
	v_addc_co_u32_e64 v43, s[6:7], -1, v119, s[6:7]
	global_load_dwordx4 v[122:125], v[38:39], off
	global_load_dwordx4 v[126:129], v[42:43], off
	v_fmac_f32_e32 v4, v76, v52
	v_fmac_f32_e32 v5, v77, v52
	v_fmac_f32_e32 v6, v74, v56
	v_fmac_f32_e32 v7, v75, v56
	v_fmac_f32_e32 v8, v76, v56
	v_fmac_f32_e32 v9, v77, v56
	v_fmac_f32_e32 v10, v74, v60
	v_fmac_f32_e32 v11, v75, v60
	v_fmac_f32_e32 v12, v76, v60
	v_fmac_f32_e32 v13, v77, v60
	v_fmac_f32_e32 v14, v74, v64
	v_fmac_f32_e32 v15, v75, v64
	v_fmac_f32_e32 v16, v76, v64
	v_fmac_f32_e32 v17, v77, v64
	v_fmac_f32_e32 v18, v74, v68
	v_fmac_f32_e32 v19, v75, v68
	v_fmac_f32_e32 v20, v76, v68
	v_fmac_f32_e32 v21, v77, v68
	v_fmac_f32_e32 v22, v74, v72
	v_fmac_f32_e32 v23, v75, v72
	v_fmac_f32_e32 v24, v76, v72
	v_fmac_f32_e32 v25, v77, v72
	v_fmac_f32_e32 v26, v74, v40
	v_fmac_f32_e32 v27, v75, v40
	v_fmac_f32_e32 v28, v76, v40
	v_fmac_f32_e32 v29, v77, v40
	v_fmac_f32_e32 v30, v74, v44
	v_fmac_f32_e32 v31, v75, v44
	v_fmac_f32_e32 v32, v76, v44
	v_fmac_f32_e32 v33, v77, v44
	v_fmac_f32_e32 v34, v74, v48
	v_fmac_f32_e32 v35, v75, v48
	v_fmac_f32_e32 v36, v76, v48
	v_fmac_f32_e32 v37, v77, v48
	ds_read_b128 v[74:77], v121 offset:32
	v_fmac_f32_e32 v5, v81, v53
	v_fmac_f32_e32 v4, v80, v53
	v_fmac_f32_e32 v3, v79, v53
	v_fmac_f32_e32 v2, v78, v53
	v_fmac_f32_e32 v9, v81, v57
	v_fmac_f32_e32 v8, v80, v57
	v_fmac_f32_e32 v7, v79, v57
	v_fmac_f32_e32 v6, v78, v57
	v_fmac_f32_e32 v13, v81, v61
	v_fmac_f32_e32 v12, v80, v61
	v_fmac_f32_e32 v11, v79, v61
	v_fmac_f32_e32 v10, v78, v61
	v_fmac_f32_e32 v17, v81, v65
	v_fmac_f32_e32 v16, v80, v65
	v_fmac_f32_e32 v15, v79, v65
	v_fmac_f32_e32 v14, v78, v65
	v_fmac_f32_e32 v21, v81, v69
	v_fmac_f32_e32 v20, v80, v69
	v_fmac_f32_e32 v19, v79, v69
	v_fmac_f32_e32 v18, v78, v69
	v_fmac_f32_e32 v25, v81, v73
	v_fmac_f32_e32 v24, v80, v73
	v_fmac_f32_e32 v23, v79, v73
	v_fmac_f32_e32 v22, v78, v73
	v_fmac_f32_e32 v29, v81, v41
	v_fmac_f32_e32 v28, v80, v41
	v_fmac_f32_e32 v27, v79, v41
	v_fmac_f32_e32 v26, v78, v41
	v_fmac_f32_e32 v33, v81, v45
	v_fmac_f32_e32 v32, v80, v45
	v_fmac_f32_e32 v31, v79, v45
	v_fmac_f32_e32 v30, v78, v45
	v_fmac_f32_e32 v37, v81, v49
	v_fmac_f32_e32 v36, v80, v49
	v_fmac_f32_e32 v35, v79, v49
	v_fmac_f32_e32 v34, v78, v49
	ds_read_b128 v[54:57], v121 offset:48
	ds_read_b128 v[78:81], v121 offset:4128
	ds_read_b128 v[58:61], v121 offset:4144
	ds_read_b128 v[82:85], v121 offset:8224
	ds_read_b128 v[62:65], v121 offset:8240
	ds_read_b128 v[86:89], v121 offset:12320
	ds_read_b128 v[66:69], v121 offset:12336
	ds_read_b128 v[90:93], v121 offset:16416
	ds_read_b128 v[70:73], v121 offset:16432
	ds_read_b128 v[94:97], v121 offset:20512
	ds_read_b128 v[38:41], v121 offset:20528
	ds_read_b128 v[98:101], v121 offset:24608
	ds_read_b128 v[42:45], v121 offset:24624
	ds_read_b128 v[102:105], v121 offset:28704
	ds_read_b128 v[46:49], v121 offset:28720
	ds_read_b128 v[106:109], v121 offset:32800
	ds_read_b128 v[50:53], v121 offset:32816
	s_waitcnt vmcnt(0) lgkmcnt(0)
	v_fmac_f32_e32 v2, v122, v74
	v_fmac_f32_e32 v3, v123, v74
	v_fmac_f32_e32 v4, v124, v74
	v_fmac_f32_e32 v5, v125, v74
	v_add_co_u32_e64 v74, s[6:7], s28, v118
	v_fmac_f32_e32 v5, v129, v75
	v_fmac_f32_e32 v4, v128, v75
	v_fmac_f32_e32 v3, v127, v75
	v_fmac_f32_e32 v2, v126, v75
	v_addc_co_u32_e64 v75, s[6:7], -1, v119, s[6:7]
	v_fmac_f32_e32 v6, v122, v78
	v_fmac_f32_e32 v7, v123, v78
	v_fmac_f32_e32 v8, v124, v78
	v_fmac_f32_e32 v9, v125, v78
	v_fmac_f32_e32 v10, v122, v82
	v_fmac_f32_e32 v11, v123, v82
	v_fmac_f32_e32 v12, v124, v82
	v_fmac_f32_e32 v13, v125, v82
	v_fmac_f32_e32 v14, v122, v86
	v_fmac_f32_e32 v15, v123, v86
	v_fmac_f32_e32 v16, v124, v86
	v_fmac_f32_e32 v17, v125, v86
	v_fmac_f32_e32 v18, v122, v90
	v_fmac_f32_e32 v19, v123, v90
	v_fmac_f32_e32 v20, v124, v90
	v_fmac_f32_e32 v21, v125, v90
	v_fmac_f32_e32 v22, v122, v94
	v_fmac_f32_e32 v23, v123, v94
	v_fmac_f32_e32 v24, v124, v94
	v_fmac_f32_e32 v25, v125, v94
	v_fmac_f32_e32 v26, v122, v98
	v_fmac_f32_e32 v27, v123, v98
	v_fmac_f32_e32 v28, v124, v98
	v_fmac_f32_e32 v29, v125, v98
	v_fmac_f32_e32 v30, v122, v102
	v_fmac_f32_e32 v31, v123, v102
	v_fmac_f32_e32 v32, v124, v102
	v_fmac_f32_e32 v33, v125, v102
	v_fmac_f32_e32 v34, v122, v106
	v_fmac_f32_e32 v35, v123, v106
	v_fmac_f32_e32 v36, v124, v106
	v_fmac_f32_e32 v37, v125, v106
	v_add_co_u32_e64 v78, s[6:7], s29, v118
	v_fmac_f32_e32 v9, v129, v79
	v_fmac_f32_e32 v8, v128, v79
	v_fmac_f32_e32 v7, v127, v79
	v_fmac_f32_e32 v6, v126, v79
	v_fmac_f32_e32 v13, v129, v83
	v_fmac_f32_e32 v12, v128, v83
	v_fmac_f32_e32 v11, v127, v83
	v_fmac_f32_e32 v10, v126, v83
	v_fmac_f32_e32 v17, v129, v87
	v_fmac_f32_e32 v16, v128, v87
	v_fmac_f32_e32 v15, v127, v87
	v_fmac_f32_e32 v14, v126, v87
	v_fmac_f32_e32 v21, v129, v91
	v_fmac_f32_e32 v20, v128, v91
	v_fmac_f32_e32 v19, v127, v91
	v_fmac_f32_e32 v18, v126, v91
	v_fmac_f32_e32 v25, v129, v95
	v_fmac_f32_e32 v24, v128, v95
	v_fmac_f32_e32 v23, v127, v95
	v_fmac_f32_e32 v22, v126, v95
	v_fmac_f32_e32 v29, v129, v99
	v_fmac_f32_e32 v28, v128, v99
	v_fmac_f32_e32 v27, v127, v99
	v_fmac_f32_e32 v26, v126, v99
	v_fmac_f32_e32 v33, v129, v103
	v_fmac_f32_e32 v32, v128, v103
	v_fmac_f32_e32 v31, v127, v103
	v_fmac_f32_e32 v30, v126, v103
	v_fmac_f32_e32 v37, v129, v107
	v_fmac_f32_e32 v36, v128, v107
	v_fmac_f32_e32 v35, v127, v107
	v_fmac_f32_e32 v34, v126, v107
	v_addc_co_u32_e64 v79, s[6:7], -1, v119, s[6:7]
	global_load_dwordx4 v[122:125], v[74:75], off
	global_load_dwordx4 v[126:129], v[78:79], off
	v_add_co_u32_e64 v74, s[6:7], s30, v118
	s_waitcnt vmcnt(0) lgkmcnt(0)
	v_fmac_f32_e32 v2, v122, v76
	v_addc_co_u32_e64 v75, s[6:7], -1, v119, s[6:7]
	v_add_co_u32_e64 v78, s[6:7], s31, v118
	v_fmac_f32_e32 v3, v123, v76
	v_fmac_f32_e32 v4, v124, v76
	v_fmac_f32_e32 v5, v125, v76
	v_fmac_f32_e32 v6, v122, v80
	v_fmac_f32_e32 v7, v123, v80
	v_fmac_f32_e32 v8, v124, v80
	v_fmac_f32_e32 v9, v125, v80
	v_addc_co_u32_e64 v79, s[6:7], -1, v119, s[6:7]
	v_fmac_f32_e32 v5, v129, v77
	v_fmac_f32_e32 v4, v128, v77
	v_fmac_f32_e32 v3, v127, v77
	v_fmac_f32_e32 v2, v126, v77
	v_fmac_f32_e32 v9, v129, v81
	v_fmac_f32_e32 v8, v128, v81
	v_fmac_f32_e32 v7, v127, v81
	v_fmac_f32_e32 v6, v126, v81
	global_load_dwordx4 v[74:77], v[74:75], off
	s_nop 0
	global_load_dwordx4 v[78:81], v[78:79], off
	v_fmac_f32_e32 v22, v122, v96
	v_fmac_f32_e32 v23, v123, v96
	v_fmac_f32_e32 v24, v124, v96
	v_fmac_f32_e32 v25, v125, v96
	v_fmac_f32_e32 v25, v129, v97
	v_fmac_f32_e32 v24, v128, v97
	v_fmac_f32_e32 v23, v127, v97
	v_fmac_f32_e32 v22, v126, v97
	v_fmac_f32_e32 v10, v122, v84
	v_fmac_f32_e32 v11, v123, v84
	v_fmac_f32_e32 v12, v124, v84
	v_fmac_f32_e32 v13, v125, v84
	v_fmac_f32_e32 v14, v122, v88
	v_fmac_f32_e32 v15, v123, v88
	v_fmac_f32_e32 v16, v124, v88
	v_fmac_f32_e32 v17, v125, v88
	v_fmac_f32_e32 v18, v122, v92
	v_fmac_f32_e32 v19, v123, v92
	v_fmac_f32_e32 v20, v124, v92
	v_fmac_f32_e32 v21, v125, v92
	v_fmac_f32_e32 v26, v122, v100
	v_fmac_f32_e32 v27, v123, v100
	v_fmac_f32_e32 v28, v124, v100
	v_fmac_f32_e32 v29, v125, v100
	v_fmac_f32_e32 v30, v122, v104
	v_fmac_f32_e32 v31, v123, v104
	v_fmac_f32_e32 v32, v124, v104
	v_fmac_f32_e32 v33, v125, v104
	v_fmac_f32_e32 v34, v122, v108
	v_fmac_f32_e32 v35, v123, v108
	v_fmac_f32_e32 v36, v124, v108
	v_fmac_f32_e32 v37, v125, v108
	v_fmac_f32_e32 v13, v129, v85
	v_fmac_f32_e32 v12, v128, v85
	v_fmac_f32_e32 v11, v127, v85
	v_fmac_f32_e32 v10, v126, v85
	v_fmac_f32_e32 v17, v129, v89
	v_fmac_f32_e32 v16, v128, v89
	v_fmac_f32_e32 v15, v127, v89
	v_fmac_f32_e32 v14, v126, v89
	v_fmac_f32_e32 v21, v129, v93
	v_fmac_f32_e32 v20, v128, v93
	v_fmac_f32_e32 v19, v127, v93
	v_fmac_f32_e32 v18, v126, v93
	v_fmac_f32_e32 v29, v129, v101
	v_fmac_f32_e32 v28, v128, v101
	v_fmac_f32_e32 v27, v127, v101
	v_fmac_f32_e32 v26, v126, v101
	v_fmac_f32_e32 v33, v129, v105
	v_fmac_f32_e32 v32, v128, v105
	v_fmac_f32_e32 v31, v127, v105
	v_fmac_f32_e32 v30, v126, v105
	v_fmac_f32_e32 v37, v129, v109
	v_fmac_f32_e32 v36, v128, v109
	v_fmac_f32_e32 v35, v127, v109
	v_fmac_f32_e32 v34, v126, v109
	s_waitcnt vmcnt(0) lgkmcnt(0)
	v_fmac_f32_e32 v22, v74, v38
	v_fmac_f32_e32 v23, v75, v38
	v_fmac_f32_e32 v24, v76, v38
	v_fmac_f32_e32 v25, v77, v38
	v_add_co_u32_e64 v38, s[6:7], s34, v118
	v_fmac_f32_e32 v25, v81, v39
	v_fmac_f32_e32 v24, v80, v39
	v_fmac_f32_e32 v23, v79, v39
	v_fmac_f32_e32 v22, v78, v39
	v_addc_co_u32_e64 v39, s[6:7], -1, v119, s[6:7]
	v_fmac_f32_e32 v2, v74, v54
	v_fmac_f32_e32 v3, v75, v54
	v_fmac_f32_e32 v4, v76, v54
	v_fmac_f32_e32 v5, v77, v54
	v_fmac_f32_e32 v6, v74, v58
	v_fmac_f32_e32 v7, v75, v58
	v_fmac_f32_e32 v8, v76, v58
	v_fmac_f32_e32 v9, v77, v58
	v_fmac_f32_e32 v10, v74, v62
	v_fmac_f32_e32 v11, v75, v62
	v_fmac_f32_e32 v12, v76, v62
	v_fmac_f32_e32 v13, v77, v62
	v_fmac_f32_e32 v14, v74, v66
	v_fmac_f32_e32 v15, v75, v66
	v_fmac_f32_e32 v16, v76, v66
	v_fmac_f32_e32 v17, v77, v66
	v_fmac_f32_e32 v18, v74, v70
	v_fmac_f32_e32 v19, v75, v70
	v_fmac_f32_e32 v20, v76, v70
	v_fmac_f32_e32 v21, v77, v70
	v_fmac_f32_e32 v26, v74, v42
	v_fmac_f32_e32 v27, v75, v42
	v_fmac_f32_e32 v28, v76, v42
	v_fmac_f32_e32 v29, v77, v42
	v_fmac_f32_e32 v30, v74, v46
	v_fmac_f32_e32 v31, v75, v46
	v_fmac_f32_e32 v32, v76, v46
	v_fmac_f32_e32 v33, v77, v46
	v_fmac_f32_e32 v34, v74, v50
	v_fmac_f32_e32 v35, v75, v50
	v_fmac_f32_e32 v36, v76, v50
	v_fmac_f32_e32 v37, v77, v50
	global_load_dwordx4 v[74:77], v[38:39], off
	v_fmac_f32_e32 v5, v81, v55
	v_fmac_f32_e32 v4, v80, v55
	v_fmac_f32_e32 v3, v79, v55
	v_fmac_f32_e32 v2, v78, v55
	v_fmac_f32_e32 v9, v81, v59
	v_fmac_f32_e32 v8, v80, v59
	v_fmac_f32_e32 v7, v79, v59
	v_fmac_f32_e32 v6, v78, v59
	v_fmac_f32_e32 v13, v81, v63
	v_fmac_f32_e32 v12, v80, v63
	v_fmac_f32_e32 v11, v79, v63
	v_fmac_f32_e32 v10, v78, v63
	v_fmac_f32_e32 v17, v81, v67
	v_fmac_f32_e32 v16, v80, v67
	v_fmac_f32_e32 v15, v79, v67
	v_fmac_f32_e32 v14, v78, v67
	v_fmac_f32_e32 v21, v81, v71
	v_fmac_f32_e32 v20, v80, v71
	v_fmac_f32_e32 v19, v79, v71
	v_fmac_f32_e32 v18, v78, v71
	v_fmac_f32_e32 v29, v81, v43
	v_fmac_f32_e32 v28, v80, v43
	v_fmac_f32_e32 v27, v79, v43
	v_fmac_f32_e32 v26, v78, v43
	v_fmac_f32_e32 v33, v81, v47
	v_fmac_f32_e32 v32, v80, v47
	v_fmac_f32_e32 v31, v79, v47
	v_fmac_f32_e32 v30, v78, v47
	v_fmac_f32_e32 v37, v81, v51
	v_fmac_f32_e32 v36, v80, v51
	v_fmac_f32_e32 v35, v79, v51
	v_fmac_f32_e32 v34, v78, v51
	s_waitcnt vmcnt(0) lgkmcnt(0)
	v_fmac_f32_e32 v2, v74, v56
	v_fmac_f32_e32 v3, v75, v56
	v_fmac_f32_e32 v4, v76, v56
	v_fmac_f32_e32 v5, v77, v56
	v_fmac_f32_e32 v6, v74, v60
	v_fmac_f32_e32 v7, v75, v60
	v_fmac_f32_e32 v8, v76, v60
	v_fmac_f32_e32 v9, v77, v60
	v_fmac_f32_e32 v10, v74, v64
	v_fmac_f32_e32 v11, v75, v64
	v_fmac_f32_e32 v12, v76, v64
	v_fmac_f32_e32 v13, v77, v64
	v_fmac_f32_e32 v14, v74, v68
	v_fmac_f32_e32 v15, v75, v68
	v_fmac_f32_e32 v16, v76, v68
	v_fmac_f32_e32 v17, v77, v68
	v_fmac_f32_e32 v18, v74, v72
	v_fmac_f32_e32 v19, v75, v72
	v_fmac_f32_e32 v20, v76, v72
	v_fmac_f32_e32 v21, v77, v72
	v_fmac_f32_e32 v22, v74, v40
	v_fmac_f32_e32 v23, v75, v40
	v_fmac_f32_e32 v24, v76, v40
	v_fmac_f32_e32 v25, v77, v40
	v_fmac_f32_e32 v26, v74, v44
	v_fmac_f32_e32 v27, v75, v44
	v_fmac_f32_e32 v28, v76, v44
	v_fmac_f32_e32 v29, v77, v44
	v_fmac_f32_e32 v30, v74, v48
	v_fmac_f32_e32 v31, v75, v48
	v_fmac_f32_e32 v32, v76, v48
	v_fmac_f32_e32 v33, v77, v48
	v_fmac_f32_e32 v34, v74, v52
	v_fmac_f32_e32 v35, v75, v52
	v_fmac_f32_e32 v36, v76, v52
	v_fmac_f32_e32 v37, v77, v52
	global_load_dwordx4 v[74:77], v[118:119], off
	v_lshl_add_u64 v[118:119], v[118:119], 0, s[8:9]
	s_waitcnt vmcnt(0) lgkmcnt(0)
	v_fmac_f32_e32 v5, v77, v57
	v_fmac_f32_e32 v4, v76, v57
	v_fmac_f32_e32 v3, v75, v57
	v_fmac_f32_e32 v2, v74, v57
	v_fmac_f32_e32 v9, v77, v61
	v_fmac_f32_e32 v8, v76, v61
	v_fmac_f32_e32 v7, v75, v61
	v_fmac_f32_e32 v6, v74, v61
	v_fmac_f32_e32 v13, v77, v65
	v_fmac_f32_e32 v12, v76, v65
	v_fmac_f32_e32 v11, v75, v65
	v_fmac_f32_e32 v10, v74, v65
	v_fmac_f32_e32 v17, v77, v69
	v_fmac_f32_e32 v16, v76, v69
	v_fmac_f32_e32 v15, v75, v69
	v_fmac_f32_e32 v14, v74, v69
	v_fmac_f32_e32 v21, v77, v73
	v_fmac_f32_e32 v20, v76, v73
	v_fmac_f32_e32 v19, v75, v73
	v_fmac_f32_e32 v18, v74, v73
	v_fmac_f32_e32 v25, v77, v41
	v_fmac_f32_e32 v24, v76, v41
	v_fmac_f32_e32 v23, v75, v41
	v_fmac_f32_e32 v22, v74, v41
	v_fmac_f32_e32 v29, v77, v45
	v_fmac_f32_e32 v28, v76, v45
	v_fmac_f32_e32 v27, v75, v45
	v_fmac_f32_e32 v26, v74, v45
	v_fmac_f32_e32 v33, v77, v49
	v_fmac_f32_e32 v32, v76, v49
	v_fmac_f32_e32 v31, v75, v49
	v_fmac_f32_e32 v30, v74, v49
	v_fmac_f32_e32 v37, v77, v53
	v_fmac_f32_e32 v36, v76, v53
	v_fmac_f32_e32 v35, v75, v53
	v_fmac_f32_e32 v34, v74, v53
	s_cbranch_scc0 .LBB0_21
	s_mulk_i32 s14, 0x2400
	v_add_u32_e32 v38, s14, v111
	ds_write_b128 v38, v[2:5] offset:36864
	ds_write_b128 v38, v[6:9] offset:37888
	ds_write_b128 v38, v[10:13] offset:38912
	ds_write_b128 v38, v[14:17] offset:39936
	ds_write_b128 v38, v[18:21] offset:40960
	ds_write_b128 v38, v[22:25] offset:41984
	ds_write_b128 v38, v[26:29] offset:43008
	ds_write_b128 v38, v[30:33] offset:44032
	ds_write_b128 v38, v[34:37] offset:45056
	s_waitcnt lgkmcnt(0)
	s_barrier
	s_and_saveexec_b64 s[14:15], vcc
	s_cbranch_execz .LBB0_19
	v_mov_b32_e32 v2, s35
	ds_read_b64 v[2:3], v2
	s_mul_i32 s6, s38, 0x1800
	s_add_i32 s6, s6, s10
	v_or_b32_sdwa v4, s6, v112 dst_sel:DWORD dst_unused:UNUSED_PAD src0_sel:DWORD src1_sel:BYTE_0
	s_mul_i32 s38, s38, 9
	v_ashrrev_i32_e32 v5, 31, v4
	v_lshl_add_u64 v[6:7], s[10:11], 2, v[116:117]
	s_mov_b64 s[10:11], 0
	v_mov_b32_e32 v8, v112
.LBB0_24:
	s_waitcnt lgkmcnt(0)
	v_readfirstlane_b32 s6, v3
	v_readfirstlane_b32 s7, v2
	s_nop 0
	v_mov_b32_e32 v11, s6
	v_mov_b32_e32 v10, s7
	v_lshl_add_u64 v[10:11], v[4:5], 2, v[10:11]
	global_load_dword v9, v[10:11], off
	v_ashrrev_i32_e32 v10, 8, v8
	v_add_u32_e32 v11, 0x200, v8
	v_lshl_add_u32 v12, v10, 10, v113
	v_cmp_lt_i32_e64 s[6:7], s36, v8
	v_add_u32_e32 v14, s38, v10
	v_mov_b32_e32 v8, v11
	v_add_u32_e32 v18, 0x9000, v12
	ds_read2st64_b32 v[10:11], v12 offset0:144 offset1:180
	ds_read2st64_b32 v[12:13], v12 offset0:216 offset1:252
	ds_read2st64_b32 v[16:17], v18 offset0:144 offset1:180
	ds_read2st64_b32 v[18:19], v18 offset0:216 offset1:252
	s_or_b64 s[10:11], s[6:7], s[10:11]
	v_mad_i64_i32 v[14:15], s[6:7], v14, s17, v[6:7]
	s_waitcnt vmcnt(0) lgkmcnt(0)
	v_add_f32_e32 v9, v9, v10
	v_add_f32_e32 v9, v9, v11
	v_add_f32_e32 v9, v9, v12
	v_add_f32_e32 v9, v9, v13
	v_add_f32_e32 v9, v9, v16
	v_add_f32_e32 v9, v9, v17
	v_add_f32_e32 v9, v9, v18
	v_add_f32_e32 v9, v9, v19
	global_store_dword v[14:15], v9, off
	s_andn2_b64 exec, exec, s[10:11]
	s_cbranch_execnz .LBB0_24
	s_branch .LBB0_19

.LBB0_39:
	s_lshl_b32 s20, s56, 13
	s_lshr_b32 s6, s56, 1
	s_and_b32 s20, s20, 0x7c000
	s_add_u32 s20, s18, s20
	s_addc_u32 s21, s19, 0
	s_lshl_b64 s[18:19], s[6:7], 13
	s_add_i32 s6, s90, 0xd200
	s_and_b32 s6, s6, 32
	s_lshl_b32 s56, s6, 2
	s_add_u32 s20, s20, s56
	s_addc_u32 s21, s21, 0
	v_lshl_add_u64 v[24:25], s[20:21], 0, v[2:3]
	v_mov_b32_e32 v7, v3
	v_lshl_add_u64 v[24:25], v[24:25], 0, v[6:7]
	v_add_co_u32_e32 v26, vcc, s30, v24
	global_load_dword v7, v[24:25], off
	global_load_dword v9, v[24:25], off offset:512
	global_load_dword v23, v[24:25], off offset:1024
	global_load_dword v30, v[24:25], off offset:1536
	global_load_dword v31, v[24:25], off offset:2048
	global_load_dword v32, v[24:25], off offset:2560
	global_load_dword v33, v[24:25], off offset:3072
	global_load_dword v34, v[24:25], off offset:3584
	v_addc_co_u32_e32 v27, vcc, 0, v25, vcc
	global_load_dword v35, v[26:27], off
	global_load_dword v36, v[26:27], off offset:512
	global_load_dword v37, v[26:27], off offset:1024
	global_load_dword v38, v[26:27], off offset:1536
	global_load_dword v39, v[26:27], off offset:2048
	global_load_dword v40, v[26:27], off offset:2560
	global_load_dword v41, v[26:27], off offset:3072
	global_load_dword v42, v[26:27], off offset:3584
	v_add_co_u32_e32 v26, vcc, s31, v24
	v_lshl_add_u64 v[28:29], v[4:5], 0, s[18:19]
	s_nop 0
	v_addc_co_u32_e32 v27, vcc, 0, v25, vcc
	v_add_co_u32_e32 v24, vcc, s34, v24
	global_load_dword v43, v[26:27], off
	global_load_dword v44, v[26:27], off offset:512
	global_load_dword v45, v[26:27], off offset:1024
	global_load_dword v46, v[26:27], off offset:1536
	global_load_dword v47, v[26:27], off offset:2048
	global_load_dword v48, v[26:27], off offset:2560
	global_load_dword v49, v[26:27], off offset:3072
	s_nop 0
	global_load_dword v26, v[26:27], off offset:3584
	v_addc_co_u32_e32 v25, vcc, 0, v25, vcc
	global_load_dword v27, v[24:25], off
	global_load_dword v50, v[24:25], off offset:512
	global_load_dword v51, v[24:25], off offset:1024
	global_load_dword v52, v[24:25], off offset:1536
	global_load_dword v53, v[24:25], off offset:2048
	global_load_dword v54, v[24:25], off offset:2560
	global_load_dword v55, v[24:25], off offset:3072
	global_load_dword v56, v[24:25], off offset:3584
	v_or_b32_e32 v24, s6, v11
	v_mov_b32_e32 v25, v3
	v_lshlrev_b32_e32 v24, 7, v24
	v_or_b32_e32 v57, s6, v13
	s_mov_b64 s[18:19], 0
	s_waitcnt vmcnt(0) lgkmcnt(0)
	ds_write2_b32 v10, v7, v9 offset1:66
	ds_write2_b32 v10, v23, v30 offset0:132 offset1:198
	ds_write2_b32 v16, v31, v32 offset0:8 offset1:74
	ds_write2_b32 v16, v33, v34 offset0:140 offset1:206
	ds_write2_b32 v17, v35, v36 offset0:16 offset1:82
	ds_write2_b32 v17, v37, v38 offset0:148 offset1:214
	ds_write2_b32 v18, v39, v40 offset0:24 offset1:90
	ds_write2_b32 v18, v41, v42 offset0:156 offset1:222
	ds_write2_b32 v19, v43, v44 offset0:32 offset1:98
	ds_write2_b32 v19, v45, v46 offset0:164 offset1:230
	ds_write2_b32 v20, v47, v48 offset0:40 offset1:106
	ds_write2_b32 v20, v49, v26 offset0:172 offset1:238
	ds_write2_b32 v21, v27, v50 offset0:48 offset1:114
	ds_write2_b32 v21, v51, v52 offset0:180 offset1:246
	ds_write2_b32 v22, v53, v54 offset0:56 offset1:122
	ds_write2_b32 v22, v55, v56 offset0:188 offset1:254
	s_waitcnt lgkmcnt(0)
	ds_read_b32 v7, v12
	ds_read_b32 v9, v12 offset:132
	ds_read_b32 v23, v12 offset:264
	ds_read_b32 v26, v12 offset:396
	ds_read_b32 v27, v12 offset:528
	ds_read_b32 v32, v12 offset:660
	ds_read_b32 v33, v12 offset:792
	ds_read_b32 v34, v12 offset:924
	v_lshl_add_u64 v[30:31], v[28:29], 0, v[24:25]
	s_waitcnt lgkmcnt(6)
	v_cvt_pk_bf16_f32 v24, v7, v9
	s_waitcnt lgkmcnt(4)
	v_cvt_pk_bf16_f32 v25, v23, v26
	s_waitcnt lgkmcnt(2)
	v_cvt_pk_bf16_f32 v26, v27, v32
	s_waitcnt lgkmcnt(0)
	v_cvt_pk_bf16_f32 v27, v33, v34
	global_store_dwordx4 v[30:31], v[24:27], off
	ds_read_b32 v7, v12 offset:32
	ds_read_b32 v9, v12 offset:164
	ds_read_b32 v23, v12 offset:296
	ds_read_b32 v25, v12 offset:428
	ds_read_b32 v26, v12 offset:560
	ds_read_b32 v27, v12 offset:692
	ds_read_b32 v31, v12 offset:824
	ds_read_b32 v32, v12 offset:956
	v_lshlrev_b32_e32 v30, 7, v57
	s_waitcnt lgkmcnt(0)
	v_cvt_pk_bf16_f32 v24, v7, v9
	v_cvt_pk_bf16_f32 v26, v26, v27
	v_cvt_pk_bf16_f32 v25, v23, v25
	v_cvt_pk_bf16_f32 v27, v31, v32
	v_mov_b32_e32 v31, v3
	v_lshl_add_u64 v[30:31], v[28:29], 0, v[30:31]
	global_store_dwordx4 v[30:31], v[24:27], off
	ds_read_b32 v7, v12 offset:64
	ds_read_b32 v9, v12 offset:196
	ds_read_b32 v23, v12 offset:328
	ds_read_b32 v25, v12 offset:460
	ds_read_b32 v26, v12 offset:592
	ds_read_b32 v27, v12 offset:724
	ds_read_b32 v30, v12 offset:856
	ds_read_b32 v31, v12 offset:988
	s_waitcnt lgkmcnt(0)
	v_cvt_pk_bf16_f32 v24, v7, v9
	v_or_b32_e32 v7, s6, v14
	v_cvt_pk_bf16_f32 v26, v26, v27
	v_cvt_pk_bf16_f32 v25, v23, v25
	v_cvt_pk_bf16_f32 v27, v30, v31
	v_lshlrev_b32_e32 v30, 7, v7
	v_mov_b32_e32 v31, v3
	v_lshl_add_u64 v[30:31], v[28:29], 0, v[30:31]
	global_store_dwordx4 v[30:31], v[24:27], off
	ds_read_b32 v7, v12 offset:96
	ds_read_b32 v9, v12 offset:228
	ds_read_b32 v23, v12 offset:360
	ds_read_b32 v25, v12 offset:492
	ds_read_b32 v26, v12 offset:624
	ds_read_b32 v27, v12 offset:756
	ds_read_b32 v30, v12 offset:888
	ds_read_b32 v31, v12 offset:1020
	s_waitcnt lgkmcnt(0)
	v_cvt_pk_bf16_f32 v24, v7, v9
	v_or_b32_e32 v7, s6, v15
	v_cvt_pk_bf16_f32 v26, v26, v27
	v_cvt_pk_bf16_f32 v25, v23, v25
	v_cvt_pk_bf16_f32 v27, v30, v31
	v_lshlrev_b32_e32 v30, 7, v7
	v_mov_b32_e32 v31, v3
	v_lshl_add_u64 v[28:29], v[28:29], 0, v[30:31]
	global_store_dwordx4 v[28:29], v[24:27], off
	s_waitcnt lgkmcnt(0)
.LBB0_40:
	s_and_b64 vcc, exec, s[18:19]
	s_cbranch_vccz .LBB0_33
	v_mov_b32_e32 v7, s35
	s_mul_hi_i32 s6, s93, 0xb48a39d5
	ds_read_b64 v[24:25], v7
	s_add_i32 s6, s6, s93
	s_lshr_b32 s18, s6, 31
	s_ashr_i32 s6, s6, 12
	s_add_i32 s18, s6, s18
	s_mul_i32 s6, s18, 0xffffe950
	s_add_i32 s57, s93, s6
	s_waitcnt lgkmcnt(0)
	v_readfirstlane_b32 s20, v24
	s_ashr_i32 s19, s18, 31
	s_mul_i32 s56, s18, 0x1720000
	v_readfirstlane_b32 s6, v25
	s_mul_hi_i32 s21, s18, 0x1720000
	s_add_u32 s20, s20, s56
	s_addc_u32 s21, s6, s21
	s_add_u32 s6, s20, 0x2000000
	s_addc_u32 s56, s21, 0
	s_cmpk_gt_i32 s57, 0x48f
	s_mov_b64 s[20:21], -1
	s_cbranch_scc0 .LBB0_55
	s_cmpk_gt_u32 s57, 0x68f
	s_cbranch_scc0 .LBB0_52
	s_cmpk_gt_u32 s57, 0xe8f
	s_cbranch_scc0 .LBB0_49
	s_cmpk_gt_u32 s57, 0x168f
	s_cbranch_scc0 .LBB0_46
	v_mov_b32_e32 v7, s36
	ds_read_b64 v[24:25], v7
	s_lshl_b64 s[20:21], s[18:19], 18
	s_mul_i32 s94, s18, 0xffff4a80
	v_mov_b32_e32 v27, v3
	s_waitcnt lgkmcnt(0)
	v_readfirstlane_b32 s96, v24
	v_readfirstlane_b32 s95, v25
	s_add_u32 s96, s96, s20
	s_addc_u32 s21, s95, s21
	s_add_i32 s20, s92, s94
	s_and_b32 s97, s20, 0x7c0
	s_add_i32 s20, s90, 0xd200
	s_and_b32 s20, s20, 0xe0
	s_lshl_b32 s94, s20, 2
	s_add_u32 s94, s96, s94
	v_or_b32_e32 v7, s97, v1
	s_addc_u32 s95, s21, 0
	v_lshl_add_u64 v[24:25], s[94:95], 0, v[2:3]
	v_lshlrev_b32_e32 v26, 10, v7
	v_lshl_add_u64 v[24:25], v[24:25], 0, v[26:27]
	v_add_co_u32_e32 v26, vcc, s30, v24
	s_movk_i32 s21, 0x5000
	s_nop 0
	v_addc_co_u32_e32 v27, vcc, 0, v25, vcc
	v_add_co_u32_e32 v28, vcc, s31, v24
	s_nop 1
	v_addc_co_u32_e32 v29, vcc, 0, v25, vcc
	v_add_co_u32_e32 v30, vcc, s34, v24
	s_nop 1
	v_addc_co_u32_e32 v31, vcc, 0, v25, vcc
	global_load_dword v7, v[24:25], off
	global_load_dword v9, v[24:25], off offset:2048
	global_load_dword v23, v[26:27], off
	global_load_dword v34, v[26:27], off offset:2048
	global_load_dword v35, v[28:29], off
	global_load_dword v36, v[28:29], off offset:2048
	global_load_dword v37, v[30:31], off
	global_load_dword v38, v[30:31], off offset:2048
	v_add_co_u32_e32 v26, vcc, s37, v24
	s_nop 1
	v_addc_co_u32_e32 v27, vcc, 0, v25, vcc
	v_add_co_u32_e32 v28, vcc, s21, v24
	s_movk_i32 s21, 0x7000
	s_nop 0
	v_addc_co_u32_e32 v29, vcc, 0, v25, vcc
	v_add_co_u32_e32 v30, vcc, s38, v24
	s_nop 1
	v_addc_co_u32_e32 v31, vcc, 0, v25, vcc
	v_add_co_u32_e32 v32, vcc, s21, v24
	s_mov_b32 s21, 0xb000
	s_nop 0
	v_addc_co_u32_e32 v33, vcc, 0, v25, vcc
	global_load_dword v39, v[26:27], off
	global_load_dword v40, v[26:27], off offset:2048
	global_load_dword v41, v[28:29], off
	global_load_dword v42, v[28:29], off offset:2048
	global_load_dword v43, v[30:31], off
	global_load_dword v44, v[30:31], off offset:2048
	global_load_dword v45, v[32:33], off
	global_load_dword v46, v[32:33], off offset:2048
	v_add_co_u32_e32 v26, vcc, s39, v24
	s_nop 1
	v_addc_co_u32_e32 v27, vcc, 0, v25, vcc
	v_add_co_u32_e32 v28, vcc, s40, v24
	s_nop 1
	v_addc_co_u32_e32 v29, vcc, 0, v25, vcc
	v_add_co_u32_e32 v30, vcc, s41, v24
	s_nop 1
	v_addc_co_u32_e32 v31, vcc, 0, v25, vcc
	v_add_co_u32_e32 v32, vcc, s21, v24
	s_mov_b32 s21, 0xf000
	s_nop 0
	v_addc_co_u32_e32 v33, vcc, 0, v25, vcc
	global_load_dword v47, v[26:27], off
	global_load_dword v48, v[26:27], off offset:2048
	global_load_dword v49, v[28:29], off
	global_load_dword v50, v[28:29], off offset:2048
	global_load_dword v51, v[30:31], off
	global_load_dword v52, v[30:31], off offset:2048
	global_load_dword v53, v[32:33], off
	s_nop 0
	global_load_dword v32, v[32:33], off offset:2048
	v_add_co_u32_e32 v26, vcc, s42, v24
	s_nop 1
	v_addc_co_u32_e32 v27, vcc, 0, v25, vcc
	v_add_co_u32_e32 v28, vcc, s43, v24
	s_nop 1
	v_addc_co_u32_e32 v29, vcc, 0, v25, vcc
	v_add_co_u32_e32 v30, vcc, s44, v24
	s_nop 1
	v_addc_co_u32_e32 v31, vcc, 0, v25, vcc
	v_add_co_u32_e32 v24, vcc, s21, v24
	s_lshl_b32 s21, s97, 1
	s_nop 0
	v_addc_co_u32_e32 v25, vcc, 0, v25, vcc
	global_load_dword v33, v[26:27], off
	s_nop 0
	global_load_dword v26, v[26:27], off offset:2048
	s_nop 0
	global_load_dword v27, v[28:29], off
	s_nop 0
	global_load_dword v28, v[28:29], off offset:2048
	s_nop 0
	global_load_dword v29, v[30:31], off
	s_nop 0
	global_load_dword v30, v[30:31], off offset:2048
	s_nop 0
	global_load_dword v31, v[24:25], off
	s_nop 0
	global_load_dword v24, v[24:25], off offset:2048
	s_add_u32 s94, s6, s21
	s_addc_u32 s95, s56, 0
	s_waitcnt vmcnt(0) lgkmcnt(0)
	ds_write2_b32 v10, v7, v9 offset1:66
	ds_write2_b32 v10, v23, v34 offset0:132 offset1:198
	ds_write2_b32 v16, v35, v36 offset0:8 offset1:74
	ds_write2_b32 v16, v37, v38 offset0:140 offset1:206
	ds_write2_b32 v17, v39, v40 offset0:16 offset1:82
	ds_write2_b32 v17, v41, v42 offset0:148 offset1:214
	ds_write2_b32 v18, v43, v44 offset0:24 offset1:90
	ds_write2_b32 v18, v45, v46 offset0:156 offset1:222
	ds_write2_b32 v19, v47, v48 offset0:32 offset1:98
	ds_write2_b32 v19, v49, v50 offset0:164 offset1:230
	ds_write2_b32 v20, v51, v52 offset0:40 offset1:106
	ds_write2_b32 v20, v53, v32 offset0:172 offset1:238
	ds_write2_b32 v21, v33, v26 offset0:48 offset1:114
	ds_write2_b32 v21, v27, v28 offset0:180 offset1:246
	ds_write2_b32 v22, v29, v30 offset0:56 offset1:122
	ds_write2_b32 v22, v31, v24 offset0:188 offset1:254
	s_waitcnt lgkmcnt(0)
	v_mov_b32_e32 v9, v3
	v_lshl_add_u64 v[24:25], s[94:95], 0, v[8:9]
	ds_read_b32 v7, v12
	ds_read_b32 v9, v12 offset:132
	ds_read_b32 v23, v12 offset:264
	ds_read_b32 v26, v12 offset:396
	ds_read_b32 v27, v12 offset:528
	ds_read_b32 v30, v12 offset:660
	ds_read_b32 v31, v12 offset:792
	ds_read_b32 v32, v12 offset:924
	v_lshl_add_u64 v[28:29], v[24:25], 0, s[8:9]
	s_waitcnt lgkmcnt(6)
	v_cvt_pk_bf16_f32 v24, v7, v9
	v_or_b32_e32 v7, s20, v11
	s_waitcnt lgkmcnt(4)
	v_cvt_pk_bf16_f32 v25, v23, v26
	s_waitcnt lgkmcnt(2)
	v_cvt_pk_bf16_f32 v26, v27, v30
	s_waitcnt lgkmcnt(0)
	v_cvt_pk_bf16_f32 v27, v31, v32
	v_lshlrev_b32_e32 v30, 9, v7
	v_mov_b32_e32 v31, v3
	v_lshl_add_u64 v[30:31], v[28:29], 0, v[30:31]
	global_store_dwordx4 v[30:31], v[24:27], off
	ds_read_b32 v7, v12 offset:32
	ds_read_b32 v9, v12 offset:164
	ds_read_b32 v23, v12 offset:296
	ds_read_b32 v25, v12 offset:428
	ds_read_b32 v26, v12 offset:560
	ds_read_b32 v27, v12 offset:692
	ds_read_b32 v30, v12 offset:824
	ds_read_b32 v31, v12 offset:956
	s_waitcnt lgkmcnt(0)
	v_cvt_pk_bf16_f32 v24, v7, v9
	v_or_b32_e32 v7, s20, v13
	v_cvt_pk_bf16_f32 v26, v26, v27
	v_cvt_pk_bf16_f32 v25, v23, v25
	v_cvt_pk_bf16_f32 v27, v30, v31
	v_lshlrev_b32_e32 v30, 9, v7
	v_mov_b32_e32 v31, v3
	v_lshl_add_u64 v[30:31], v[28:29], 0, v[30:31]
	global_store_dwordx4 v[30:31], v[24:27], off
	ds_read_b32 v7, v12 offset:64
	ds_read_b32 v9, v12 offset:196
	ds_read_b32 v23, v12 offset:328
	ds_read_b32 v25, v12 offset:460
	ds_read_b32 v26, v12 offset:592
	ds_read_b32 v27, v12 offset:724
	ds_read_b32 v30, v12 offset:856
	ds_read_b32 v31, v12 offset:988
	s_waitcnt lgkmcnt(0)
	v_cvt_pk_bf16_f32 v24, v7, v9
	v_or_b32_e32 v7, s20, v14
	v_cvt_pk_bf16_f32 v26, v26, v27
	v_cvt_pk_bf16_f32 v25, v23, v25
	v_cvt_pk_bf16_f32 v27, v30, v31
	v_lshlrev_b32_e32 v30, 9, v7
	v_mov_b32_e32 v31, v3
	v_lshl_add_u64 v[30:31], v[28:29], 0, v[30:31]
	global_store_dwordx4 v[30:31], v[24:27], off
	ds_read_b32 v7, v12 offset:96
	ds_read_b32 v9, v12 offset:228
	ds_read_b32 v23, v12 offset:360
	ds_read_b32 v25, v12 offset:492
	ds_read_b32 v26, v12 offset:624
	ds_read_b32 v27, v12 offset:756
	ds_read_b32 v30, v12 offset:888
	ds_read_b32 v31, v12 offset:1020
	s_waitcnt lgkmcnt(0)
	v_cvt_pk_bf16_f32 v24, v7, v9
	v_or_b32_e32 v7, s20, v15
	v_cvt_pk_bf16_f32 v26, v26, v27
	v_cvt_pk_bf16_f32 v25, v23, v25
	v_cvt_pk_bf16_f32 v27, v30, v31
	v_lshlrev_b32_e32 v30, 9, v7
	v_mov_b32_e32 v31, v3
	v_lshl_add_u64 v[28:29], v[28:29], 0, v[30:31]
	global_store_dwordx4 v[28:29], v[24:27], off
	s_waitcnt lgkmcnt(0)
	s_mov_b64 s[20:21], 0
.LBB0_46:
	s_andn2_b64 vcc, exec, s[20:21]
	s_cbranch_vccnz .LBB0_48
	v_mov_b32_e32 v7, s45
	ds_read_b64 v[24:25], v7
	s_lshl_b64 s[20:21], s[18:19], 24
	s_mul_i32 s94, s18, 0xffffd2a0
	v_mov_b32_e32 v27, v3
	s_waitcnt lgkmcnt(0)
	v_readfirstlane_b32 s96, v24
	v_readfirstlane_b32 s95, v25
	s_add_u32 s96, s96, s20
	s_addc_u32 s95, s95, s21
	s_add_i32 s20, s91, s94
	s_addk_i32 s20, 0xec00
	s_and_b32 s21, s20, 0x1ffc0
	s_lshl_b32 s20, s18, 9
	s_sub_i32 s20, s90, s20
	s_add_i32 s20, s20, 0xffff0000
	s_and_b32 s20, s20, 0x3e0
	s_lshl_b32 s94, s20, 2
	s_add_u32 s94, s96, s94
	v_or_b32_e32 v7, s21, v1
	s_addc_u32 s95, s95, 0
	v_lshl_add_u64 v[24:25], s[94:95], 0, v[2:3]
	v_lshlrev_b32_e32 v26, 12, v7
	v_lshl_add_u64 v[24:25], v[24:25], 0, v[26:27]
	v_add_co_u32_e32 v26, vcc, s31, v24
	s_lshl_b32 s21, s21, 1
	s_nop 0
	v_addc_co_u32_e32 v27, vcc, 0, v25, vcc
	v_add_co_u32_e32 v28, vcc, s37, v24
	s_add_u32 s94, s6, s21
	s_nop 0
	v_addc_co_u32_e32 v29, vcc, 0, v25, vcc
	v_add_co_u32_e32 v30, vcc, s38, v24
	s_addc_u32 s95, s56, 0
	s_nop 0
	v_addc_co_u32_e32 v31, vcc, 0, v25, vcc
	v_add_co_u32_e32 v32, vcc, s39, v24
	s_nop 1
	v_addc_co_u32_e32 v33, vcc, 0, v25, vcc
	v_add_co_u32_e32 v34, vcc, s41, v24
	s_nop 1
	v_addc_co_u32_e32 v35, vcc, 0, v25, vcc
	v_add_co_u32_e32 v36, vcc, s42, v24
	s_nop 1
	v_addc_co_u32_e32 v37, vcc, 0, v25, vcc
	v_add_co_u32_e32 v38, vcc, s44, v24
	s_nop 1
	v_addc_co_u32_e32 v39, vcc, 0, v25, vcc
	global_load_dword v7, v[24:25], off
	global_load_dword v9, v[26:27], off
	global_load_dword v23, v[28:29], off
	global_load_dword v42, v[30:31], off
	global_load_dword v43, v[32:33], off
	global_load_dword v44, v[34:35], off
	global_load_dword v45, v[36:37], off
	global_load_dword v46, v[38:39], off
	v_add_co_u32_e32 v26, vcc, s46, v24
	s_nop 1
	v_addc_co_u32_e32 v27, vcc, 0, v25, vcc
	v_add_co_u32_e32 v28, vcc, s47, v24
	s_nop 1
	v_addc_co_u32_e32 v29, vcc, 0, v25, vcc
	v_add_co_u32_e32 v30, vcc, s48, v24
	s_nop 1
	v_addc_co_u32_e32 v31, vcc, 0, v25, vcc
	v_add_co_u32_e32 v32, vcc, s49, v24
	s_nop 1
	v_addc_co_u32_e32 v33, vcc, 0, v25, vcc
	v_add_co_u32_e32 v34, vcc, s50, v24
	s_nop 1
	v_addc_co_u32_e32 v35, vcc, 0, v25, vcc
	v_add_co_u32_e32 v36, vcc, s51, v24
	s_nop 1
	v_addc_co_u32_e32 v37, vcc, 0, v25, vcc
	v_add_co_u32_e32 v38, vcc, s52, v24
	s_nop 1
	v_addc_co_u32_e32 v39, vcc, 0, v25, vcc
	v_add_co_u32_e32 v40, vcc, s53, v24
	s_nop 1
	v_addc_co_u32_e32 v41, vcc, 0, v25, vcc
	global_load_dword v47, v[26:27], off
	global_load_dword v48, v[28:29], off
	global_load_dword v49, v[30:31], off
	global_load_dword v50, v[32:33], off
	global_load_dword v51, v[34:35], off
	global_load_dword v52, v[36:37], off
	global_load_dword v53, v[38:39], off
	global_load_dword v54, v[40:41], off
	v_add_co_u32_e32 v26, vcc, s58, v24
	s_nop 1
	v_addc_co_u32_e32 v27, vcc, 0, v25, vcc
	v_add_co_u32_e32 v28, vcc, s59, v24
	s_nop 1
	v_addc_co_u32_e32 v29, vcc, 0, v25, vcc
	v_add_co_u32_e32 v30, vcc, s60, v24
	s_nop 1
	v_addc_co_u32_e32 v31, vcc, 0, v25, vcc
	v_add_co_u32_e32 v32, vcc, s61, v24
	s_nop 1
	v_addc_co_u32_e32 v33, vcc, 0, v25, vcc
	v_add_co_u32_e32 v34, vcc, s62, v24
	s_nop 1
	v_addc_co_u32_e32 v35, vcc, 0, v25, vcc
	v_add_co_u32_e32 v36, vcc, s63, v24
	s_nop 1
	v_addc_co_u32_e32 v37, vcc, 0, v25, vcc
	v_add_co_u32_e32 v38, vcc, s64, v24
	s_nop 1
	v_addc_co_u32_e32 v39, vcc, 0, v25, vcc
	v_add_co_u32_e32 v40, vcc, s65, v24
	s_nop 1
	v_addc_co_u32_e32 v41, vcc, 0, v25, vcc
	global_load_dword v55, v[26:27], off
	global_load_dword v56, v[28:29], off
	global_load_dword v57, v[30:31], off
	global_load_dword v58, v[32:33], off
	global_load_dword v59, v[34:35], off
	global_load_dword v60, v[36:37], off
	global_load_dword v61, v[38:39], off
	s_nop 0
	global_load_dword v40, v[40:41], off
	v_add_co_u32_e32 v26, vcc, s66, v24
	s_nop 1
	v_addc_co_u32_e32 v27, vcc, 0, v25, vcc
	v_add_co_u32_e32 v28, vcc, s67, v24
	s_nop 1
	v_addc_co_u32_e32 v29, vcc, 0, v25, vcc
	v_add_co_u32_e32 v30, vcc, s68, v24
	s_nop 1
	v_addc_co_u32_e32 v31, vcc, 0, v25, vcc
	v_add_co_u32_e32 v32, vcc, s69, v24
	s_nop 1
	v_addc_co_u32_e32 v33, vcc, 0, v25, vcc
	v_add_co_u32_e32 v34, vcc, s70, v24
	s_nop 1
	v_addc_co_u32_e32 v35, vcc, 0, v25, vcc
	v_add_co_u32_e32 v36, vcc, s71, v24
	s_nop 1
	v_addc_co_u32_e32 v37, vcc, 0, v25, vcc
	v_add_co_u32_e32 v38, vcc, s72, v24
	s_nop 1
	v_addc_co_u32_e32 v39, vcc, 0, v25, vcc
	v_add_co_u32_e32 v24, vcc, s73, v24
	s_nop 1
	v_addc_co_u32_e32 v25, vcc, 0, v25, vcc
	global_load_dword v26, v[26:27], off
	s_nop 0
	global_load_dword v27, v[28:29], off
	s_nop 0
	global_load_dword v28, v[30:31], off
	global_load_dword v29, v[32:33], off
	s_nop 0
	global_load_dword v30, v[34:35], off
	global_load_dword v31, v[36:37], off
	global_load_dword v32, v[38:39], off
	s_nop 0
	global_load_dword v24, v[24:25], off
	s_waitcnt vmcnt(0) lgkmcnt(0)
	ds_write2_b32 v10, v7, v9 offset1:66
	ds_write2_b32 v10, v23, v42 offset0:132 offset1:198
	ds_write2_b32 v16, v43, v44 offset0:8 offset1:74
	ds_write2_b32 v16, v45, v46 offset0:140 offset1:206
	ds_write2_b32 v17, v47, v48 offset0:16 offset1:82
	ds_write2_b32 v17, v49, v50 offset0:148 offset1:214
	ds_write2_b32 v18, v51, v52 offset0:24 offset1:90
	ds_write2_b32 v18, v53, v54 offset0:156 offset1:222
	ds_write2_b32 v19, v55, v56 offset0:32 offset1:98
	ds_write2_b32 v19, v57, v58 offset0:164 offset1:230
	ds_write2_b32 v20, v59, v60 offset0:40 offset1:106
	ds_write2_b32 v20, v61, v40 offset0:172 offset1:238
	ds_write2_b32 v21, v26, v27 offset0:48 offset1:114
	ds_write2_b32 v21, v28, v29 offset0:180 offset1:246
	ds_write2_b32 v22, v30, v31 offset0:56 offset1:122
	ds_write2_b32 v22, v32, v24 offset0:188 offset1:254
	s_waitcnt lgkmcnt(0)
	v_mov_b32_e32 v9, v3
	v_lshl_add_u64 v[24:25], s[94:95], 0, v[8:9]
	ds_read_b32 v7, v12
	ds_read_b32 v9, v12 offset:132
	ds_read_b32 v23, v12 offset:264
	ds_read_b32 v26, v12 offset:396
	ds_read_b32 v27, v12 offset:528
	ds_read_b32 v30, v12 offset:660
	ds_read_b32 v31, v12 offset:792
	ds_read_b32 v32, v12 offset:924
	v_lshl_add_u64 v[28:29], v[24:25], 0, s[10:11]
	s_waitcnt lgkmcnt(6)
	v_cvt_pk_bf16_f32 v24, v7, v9
	v_or_b32_e32 v7, s20, v11
	s_waitcnt lgkmcnt(4)
	v_cvt_pk_bf16_f32 v25, v23, v26
	s_waitcnt lgkmcnt(2)
	v_cvt_pk_bf16_f32 v26, v27, v30
	s_waitcnt lgkmcnt(0)
	v_cvt_pk_bf16_f32 v27, v31, v32
	v_lshlrev_b32_e32 v30, 13, v7
	v_mov_b32_e32 v31, v3
	v_lshl_add_u64 v[30:31], v[28:29], 0, v[30:31]
	global_store_dwordx4 v[30:31], v[24:27], off
	ds_read_b32 v7, v12 offset:32
	ds_read_b32 v9, v12 offset:164
	ds_read_b32 v23, v12 offset:296
	ds_read_b32 v25, v12 offset:428
	ds_read_b32 v26, v12 offset:560
	ds_read_b32 v27, v12 offset:692
	ds_read_b32 v30, v12 offset:824
	ds_read_b32 v31, v12 offset:956
	s_waitcnt lgkmcnt(0)
	v_cvt_pk_bf16_f32 v24, v7, v9
	v_or_b32_e32 v7, s20, v13
	v_cvt_pk_bf16_f32 v26, v26, v27
	v_cvt_pk_bf16_f32 v25, v23, v25
	v_cvt_pk_bf16_f32 v27, v30, v31
	v_lshlrev_b32_e32 v30, 13, v7
	v_mov_b32_e32 v31, v3
	v_lshl_add_u64 v[30:31], v[28:29], 0, v[30:31]
	global_store_dwordx4 v[30:31], v[24:27], off
	ds_read_b32 v7, v12 offset:64
	ds_read_b32 v9, v12 offset:196
	ds_read_b32 v23, v12 offset:328
	ds_read_b32 v25, v12 offset:460
	ds_read_b32 v26, v12 offset:592
	ds_read_b32 v27, v12 offset:724
	ds_read_b32 v30, v12 offset:856
	ds_read_b32 v31, v12 offset:988
	s_waitcnt lgkmcnt(0)
	v_cvt_pk_bf16_f32 v24, v7, v9
	v_or_b32_e32 v7, s20, v14
	v_cvt_pk_bf16_f32 v26, v26, v27
	v_cvt_pk_bf16_f32 v25, v23, v25
	v_cvt_pk_bf16_f32 v27, v30, v31
	v_lshlrev_b32_e32 v30, 13, v7
	v_mov_b32_e32 v31, v3
	v_lshl_add_u64 v[30:31], v[28:29], 0, v[30:31]
	global_store_dwordx4 v[30:31], v[24:27], off
	ds_read_b32 v7, v12 offset:96
	ds_read_b32 v9, v12 offset:228
	ds_read_b32 v23, v12 offset:360
	ds_read_b32 v25, v12 offset:492
	ds_read_b32 v26, v12 offset:624
	ds_read_b32 v27, v12 offset:756
	ds_read_b32 v30, v12 offset:888
	ds_read_b32 v31, v12 offset:1020
	s_waitcnt lgkmcnt(0)
	v_cvt_pk_bf16_f32 v24, v7, v9
	v_or_b32_e32 v7, s20, v15
	v_cvt_pk_bf16_f32 v26, v26, v27
	v_cvt_pk_bf16_f32 v25, v23, v25
	v_cvt_pk_bf16_f32 v27, v30, v31
	v_lshlrev_b32_e32 v30, 13, v7
	v_mov_b32_e32 v31, v3
	v_lshl_add_u64 v[28:29], v[28:29], 0, v[30:31]
	global_store_dwordx4 v[28:29], v[24:27], off
	s_waitcnt lgkmcnt(0)

.LBB0_49:
	s_andn2_b64 vcc, exec, s[20:21]
	s_cbranch_vccnz .LBB0_51
	v_mov_b32_e32 v7, s74
	ds_read_b64 v[24:25], v7
	s_add_i32 s94, s57, 0xfffff970
	s_lshl_b64 s[20:21], s[18:19], 24
	v_mov_b32_e32 v27, v3
	s_waitcnt lgkmcnt(0)
	v_readfirstlane_b32 s96, v24
	v_readfirstlane_b32 s95, v25
	s_add_u32 s96, s96, s20
	s_addc_u32 s95, s95, s21
	s_lshr_b32 s20, s94, 1
	s_and_b32 s21, s20, 0x7fc0
	s_mul_i32 s20, s18, 0xfffd2a00
	s_add_i32 s20, s90, s20
	s_and_b32 s20, s20, 0xfe0
	s_lshl_b32 s94, s20, 2
	s_add_u32 s94, s96, s94
	v_or_b32_e32 v7, s21, v1
	s_addc_u32 s95, s95, 0
	v_lshl_add_u64 v[24:25], s[94:95], 0, v[2:3]
	v_lshlrev_b32_e32 v26, 14, v7
	v_lshl_add_u64 v[24:25], v[24:25], 0, v[26:27]
	v_add_co_u32_e32 v26, vcc, s39, v24
	s_mov_b32 s94, 0x40000
	s_nop 0
	v_addc_co_u32_e32 v27, vcc, 0, v25, vcc
	v_add_co_u32_e32 v28, vcc, s46, v24
	s_lshl_b32 s21, s21, 1
	s_nop 0
	v_addc_co_u32_e32 v29, vcc, 0, v25, vcc
	v_add_co_u32_e32 v30, vcc, s50, v24
	s_nop 1
	v_addc_co_u32_e32 v31, vcc, 0, v25, vcc
	v_add_co_u32_e32 v32, vcc, s58, v24
	s_nop 1
	v_addc_co_u32_e32 v33, vcc, 0, v25, vcc
	v_add_co_u32_e32 v34, vcc, s62, v24
	s_nop 1
	v_addc_co_u32_e32 v35, vcc, 0, v25, vcc
	v_add_co_u32_e32 v36, vcc, s66, v24
	s_nop 1
	v_addc_co_u32_e32 v37, vcc, 0, v25, vcc
	v_add_co_u32_e32 v38, vcc, s70, v24
	s_nop 1
	v_addc_co_u32_e32 v39, vcc, 0, v25, vcc
	global_load_dword v7, v[24:25], off
	global_load_dword v9, v[26:27], off
	global_load_dword v23, v[28:29], off
	global_load_dword v42, v[30:31], off
	global_load_dword v43, v[32:33], off
	global_load_dword v44, v[34:35], off
	global_load_dword v45, v[36:37], off
	global_load_dword v46, v[38:39], off
	v_add_co_u32_e32 v26, vcc, s94, v24
	s_mov_b32 s94, 0x48000
	s_nop 0
	v_addc_co_u32_e32 v27, vcc, 0, v25, vcc
	v_add_co_u32_e32 v28, vcc, s94, v24
	s_mov_b32 s94, 0x50000
	s_nop 0
	v_addc_co_u32_e32 v29, vcc, 0, v25, vcc
	v_add_co_u32_e32 v30, vcc, s94, v24
	s_mov_b32 s94, 0x58000
	s_nop 0
	v_addc_co_u32_e32 v31, vcc, 0, v25, vcc
	v_add_co_u32_e32 v32, vcc, s94, v24
	s_mov_b32 s94, 0x60000
	s_nop 0
	v_addc_co_u32_e32 v33, vcc, 0, v25, vcc
	v_add_co_u32_e32 v34, vcc, s94, v24
	s_mov_b32 s94, 0x70000
	s_nop 0
	v_addc_co_u32_e32 v35, vcc, 0, v25, vcc
	v_add_co_u32_e32 v36, vcc, s75, v24
	s_nop 1
	v_addc_co_u32_e32 v37, vcc, 0, v25, vcc
	v_add_co_u32_e32 v38, vcc, s94, v24
	s_mov_b32 s94, 0x78000
	s_nop 0
	v_addc_co_u32_e32 v39, vcc, 0, v25, vcc
	v_add_co_u32_e32 v40, vcc, s94, v24
	s_mov_b32 s94, 0x80000
	s_nop 0
	v_addc_co_u32_e32 v41, vcc, 0, v25, vcc
	global_load_dword v47, v[26:27], off
	global_load_dword v48, v[28:29], off
	global_load_dword v49, v[30:31], off
	global_load_dword v50, v[32:33], off
	global_load_dword v51, v[34:35], off
	global_load_dword v52, v[36:37], off
	global_load_dword v53, v[38:39], off
	global_load_dword v54, v[40:41], off
	v_add_co_u32_e32 v26, vcc, s94, v24
	s_mov_b32 s94, 0x90000
	s_nop 0
	v_addc_co_u32_e32 v27, vcc, 0, v25, vcc
	v_add_co_u32_e32 v28, vcc, s76, v24
	s_nop 1
	v_addc_co_u32_e32 v29, vcc, 0, v25, vcc
	v_add_co_u32_e32 v30, vcc, s94, v24
	s_mov_b32 s94, 0x98000
	s_nop 0
	v_addc_co_u32_e32 v31, vcc, 0, v25, vcc
	v_add_co_u32_e32 v32, vcc, s94, v24
	s_mov_b32 s94, 0xa0000
	s_nop 0
	v_addc_co_u32_e32 v33, vcc, 0, v25, vcc
	v_add_co_u32_e32 v34, vcc, s94, v24
	s_mov_b32 s94, 0xa8000
	s_nop 0
	v_addc_co_u32_e32 v35, vcc, 0, v25, vcc
	v_add_co_u32_e32 v36, vcc, s94, v24
	s_mov_b32 s94, 0xb0000
	s_nop 0
	v_addc_co_u32_e32 v37, vcc, 0, v25, vcc
	v_add_co_u32_e32 v38, vcc, s94, v24
	s_mov_b32 s94, 0xb8000
	s_nop 0
	v_addc_co_u32_e32 v39, vcc, 0, v25, vcc
	v_add_co_u32_e32 v40, vcc, s94, v24
	s_mov_b32 s94, 0xc0000
	s_nop 0
	v_addc_co_u32_e32 v41, vcc, 0, v25, vcc
	global_load_dword v55, v[26:27], off
	global_load_dword v56, v[28:29], off
	global_load_dword v57, v[30:31], off
	global_load_dword v58, v[32:33], off
	global_load_dword v59, v[34:35], off
	global_load_dword v60, v[36:37], off
	global_load_dword v61, v[38:39], off
	s_nop 0
	global_load_dword v40, v[40:41], off
	v_add_co_u32_e32 v26, vcc, s94, v24
	s_mov_b32 s94, 0xc8000
	s_nop 0
	v_addc_co_u32_e32 v27, vcc, 0, v25, vcc
	v_add_co_u32_e32 v28, vcc, s94, v24
	s_mov_b32 s94, 0xd0000
	s_nop 0
	v_addc_co_u32_e32 v29, vcc, 0, v25, vcc
	v_add_co_u32_e32 v30, vcc, s94, v24
	s_mov_b32 s94, 0xd8000
	s_nop 0
	v_addc_co_u32_e32 v31, vcc, 0, v25, vcc
	v_add_co_u32_e32 v32, vcc, s94, v24
	s_mov_b32 s94, 0xe0000
	s_nop 0
	v_addc_co_u32_e32 v33, vcc, 0, v25, vcc
	v_add_co_u32_e32 v34, vcc, s94, v24
	s_mov_b32 s94, 0xe8000
	s_nop 0
	v_addc_co_u32_e32 v35, vcc, 0, v25, vcc
	v_add_co_u32_e32 v36, vcc, s94, v24
	s_mov_b32 s94, 0xf0000
	s_nop 0
	v_addc_co_u32_e32 v37, vcc, 0, v25, vcc
	v_add_co_u32_e32 v38, vcc, s94, v24
	s_mov_b32 s94, 0xf8000
	s_nop 0
	v_addc_co_u32_e32 v39, vcc, 0, v25, vcc
	v_add_co_u32_e32 v24, vcc, s94, v24
	s_add_u32 s94, s6, s21
	s_nop 0
	v_addc_co_u32_e32 v25, vcc, 0, v25, vcc
	global_load_dword v26, v[26:27], off
	s_nop 0
	global_load_dword v27, v[28:29], off
	s_nop 0
	global_load_dword v28, v[30:31], off
	global_load_dword v29, v[32:33], off
	s_nop 0
	global_load_dword v30, v[34:35], off
	global_load_dword v31, v[36:37], off
	global_load_dword v32, v[38:39], off
	s_nop 0
	global_load_dword v24, v[24:25], off
	s_waitcnt vmcnt(0) lgkmcnt(0)
	ds_write2_b32 v10, v7, v9 offset1:66
	ds_write2_b32 v10, v23, v42 offset0:132 offset1:198
	ds_write2_b32 v16, v43, v44 offset0:8 offset1:74
	ds_write2_b32 v16, v45, v46 offset0:140 offset1:206
	ds_write2_b32 v17, v47, v48 offset0:16 offset1:82
	ds_write2_b32 v17, v49, v50 offset0:148 offset1:214
	ds_write2_b32 v18, v51, v52 offset0:24 offset1:90
	ds_write2_b32 v18, v53, v54 offset0:156 offset1:222
	ds_write2_b32 v19, v55, v56 offset0:32 offset1:98
	ds_write2_b32 v19, v57, v58 offset0:164 offset1:230
	ds_write2_b32 v20, v59, v60 offset0:40 offset1:106
	ds_write2_b32 v20, v61, v40 offset0:172 offset1:238
	ds_write2_b32 v21, v26, v27 offset0:48 offset1:114
	ds_write2_b32 v21, v28, v29 offset0:180 offset1:246
	ds_write2_b32 v22, v30, v31 offset0:56 offset1:122
	ds_write2_b32 v22, v32, v24 offset0:188 offset1:254
	s_waitcnt lgkmcnt(0)
	s_addc_u32 s95, s56, 0
	v_mov_b32_e32 v9, v3
	v_lshl_add_u64 v[24:25], s[94:95], 0, v[8:9]
	ds_read_b32 v7, v12
	ds_read_b32 v9, v12 offset:132
	ds_read_b32 v23, v12 offset:264
	ds_read_b32 v26, v12 offset:396
	ds_read_b32 v27, v12 offset:528
	ds_read_b32 v30, v12 offset:660
	ds_read_b32 v31, v12 offset:792
	ds_read_b32 v32, v12 offset:924
	v_lshl_add_u64 v[28:29], v[24:25], 0, s[14:15]
	s_waitcnt lgkmcnt(6)
	v_cvt_pk_bf16_f32 v24, v7, v9
	v_or_b32_e32 v7, s20, v11
	s_waitcnt lgkmcnt(4)
	v_cvt_pk_bf16_f32 v25, v23, v26
	s_waitcnt lgkmcnt(2)
	v_cvt_pk_bf16_f32 v26, v27, v30
	s_waitcnt lgkmcnt(0)
	v_cvt_pk_bf16_f32 v27, v31, v32
	v_lshlrev_b32_e32 v30, 11, v7
	v_mov_b32_e32 v31, v3
	v_lshl_add_u64 v[30:31], v[28:29], 0, v[30:31]
	global_store_dwordx4 v[30:31], v[24:27], off
	ds_read_b32 v7, v12 offset:32
	ds_read_b32 v9, v12 offset:164
	ds_read_b32 v23, v12 offset:296
	ds_read_b32 v25, v12 offset:428
	ds_read_b32 v26, v12 offset:560
	ds_read_b32 v27, v12 offset:692
	ds_read_b32 v30, v12 offset:824
	ds_read_b32 v31, v12 offset:956
	s_waitcnt lgkmcnt(0)
	v_cvt_pk_bf16_f32 v24, v7, v9
	v_or_b32_e32 v7, s20, v13
	v_cvt_pk_bf16_f32 v26, v26, v27
	v_cvt_pk_bf16_f32 v25, v23, v25
	v_cvt_pk_bf16_f32 v27, v30, v31
	v_lshlrev_b32_e32 v30, 11, v7
	v_mov_b32_e32 v31, v3
	v_lshl_add_u64 v[30:31], v[28:29], 0, v[30:31]
	global_store_dwordx4 v[30:31], v[24:27], off
	ds_read_b32 v7, v12 offset:64
	ds_read_b32 v9, v12 offset:196
	ds_read_b32 v23, v12 offset:328
	ds_read_b32 v25, v12 offset:460
	ds_read_b32 v26, v12 offset:592
	ds_read_b32 v27, v12 offset:724
	ds_read_b32 v30, v12 offset:856
	ds_read_b32 v31, v12 offset:988
	s_waitcnt lgkmcnt(0)
	v_cvt_pk_bf16_f32 v24, v7, v9
	v_or_b32_e32 v7, s20, v14
	v_cvt_pk_bf16_f32 v26, v26, v27
	v_cvt_pk_bf16_f32 v25, v23, v25
	v_cvt_pk_bf16_f32 v27, v30, v31
	v_lshlrev_b32_e32 v30, 11, v7
	v_mov_b32_e32 v31, v3
	v_lshl_add_u64 v[30:31], v[28:29], 0, v[30:31]
	global_store_dwordx4 v[30:31], v[24:27], off
	ds_read_b32 v7, v12 offset:96
	ds_read_b32 v9, v12 offset:228
	ds_read_b32 v23, v12 offset:360
	ds_read_b32 v25, v12 offset:492
	ds_read_b32 v26, v12 offset:624
	ds_read_b32 v27, v12 offset:756
	ds_read_b32 v30, v12 offset:888
	ds_read_b32 v31, v12 offset:1020
	s_waitcnt lgkmcnt(0)
	v_cvt_pk_bf16_f32 v24, v7, v9
	v_or_b32_e32 v7, s20, v15
	v_cvt_pk_bf16_f32 v26, v26, v27
	v_cvt_pk_bf16_f32 v25, v23, v25
	v_cvt_pk_bf16_f32 v27, v30, v31
	v_lshlrev_b32_e32 v30, 11, v7
	v_mov_b32_e32 v31, v3
	v_lshl_add_u64 v[28:29], v[28:29], 0, v[30:31]
	global_store_dwordx4 v[28:29], v[24:27], off
	s_waitcnt lgkmcnt(0)

.LBB0_52:
	s_andn2_b64 vcc, exec, s[20:21]
	s_cbranch_vccnz .LBB0_54
	v_mov_b32_e32 v7, s77
	ds_read_b64 v[24:25], v7
	s_lshl_b64 s[20:21], s[18:19], 22
	s_mul_i32 s19, s18, 0xffffd2a0
	v_mov_b32_e32 v27, v3
	s_waitcnt lgkmcnt(0)
	v_readfirstlane_b32 s95, v24
	v_readfirstlane_b32 s94, v25
	s_add_u32 s95, s95, s20
	s_addc_u32 s21, s94, s21
	s_add_i32 s19, s91, s19
	s_and_b32 s20, s19, 0x1ffc0
	s_lshl_b32 s19, s18, 9
	s_sub_i32 s19, s90, s19
	s_addk_i32 s19, 0x4000
	s_and_b32 s19, s19, 0x3e0
	s_lshl_b32 s94, s19, 2
	s_add_u32 s94, s95, s94
	v_or_b32_e32 v7, s20, v1
	s_addc_u32 s95, s21, 0
	v_lshl_add_u64 v[24:25], s[94:95], 0, v[2:3]
	v_lshlrev_b32_e32 v26, 12, v7
	v_lshl_add_u64 v[24:25], v[24:25], 0, v[26:27]
	v_add_co_u32_e32 v26, vcc, s31, v24
	s_lshl_b32 s20, s20, 1
	s_nop 0
	v_addc_co_u32_e32 v27, vcc, 0, v25, vcc
	v_add_co_u32_e32 v28, vcc, s37, v24
	s_add_u32 s20, s6, s20
	s_nop 0
	v_addc_co_u32_e32 v29, vcc, 0, v25, vcc
	v_add_co_u32_e32 v30, vcc, s38, v24
	s_addc_u32 s21, s56, 0
	s_nop 0
	v_addc_co_u32_e32 v31, vcc, 0, v25, vcc
	v_add_co_u32_e32 v32, vcc, s39, v24
	s_nop 1
	v_addc_co_u32_e32 v33, vcc, 0, v25, vcc
	v_add_co_u32_e32 v34, vcc, s41, v24
	s_nop 1
	v_addc_co_u32_e32 v35, vcc, 0, v25, vcc
	v_add_co_u32_e32 v36, vcc, s42, v24
	s_nop 1
	v_addc_co_u32_e32 v37, vcc, 0, v25, vcc
	v_add_co_u32_e32 v38, vcc, s44, v24
	s_nop 1
	v_addc_co_u32_e32 v39, vcc, 0, v25, vcc
	global_load_dword v7, v[24:25], off
	global_load_dword v9, v[26:27], off
	global_load_dword v23, v[28:29], off
	global_load_dword v42, v[30:31], off
	global_load_dword v43, v[32:33], off
	global_load_dword v44, v[34:35], off
	global_load_dword v45, v[36:37], off
	global_load_dword v46, v[38:39], off
	v_add_co_u32_e32 v26, vcc, s46, v24
	s_nop 1
	v_addc_co_u32_e32 v27, vcc, 0, v25, vcc
	v_add_co_u32_e32 v28, vcc, s47, v24
	s_nop 1
	v_addc_co_u32_e32 v29, vcc, 0, v25, vcc
	v_add_co_u32_e32 v30, vcc, s48, v24
	s_nop 1
	v_addc_co_u32_e32 v31, vcc, 0, v25, vcc
	v_add_co_u32_e32 v32, vcc, s49, v24
	s_nop 1
	v_addc_co_u32_e32 v33, vcc, 0, v25, vcc
	v_add_co_u32_e32 v34, vcc, s50, v24
	s_nop 1
	v_addc_co_u32_e32 v35, vcc, 0, v25, vcc
	v_add_co_u32_e32 v36, vcc, s51, v24
	s_nop 1
	v_addc_co_u32_e32 v37, vcc, 0, v25, vcc
	v_add_co_u32_e32 v38, vcc, s52, v24
	s_nop 1
	v_addc_co_u32_e32 v39, vcc, 0, v25, vcc
	v_add_co_u32_e32 v40, vcc, s53, v24
	s_nop 1
	v_addc_co_u32_e32 v41, vcc, 0, v25, vcc
	global_load_dword v47, v[26:27], off
	global_load_dword v48, v[28:29], off
	global_load_dword v49, v[30:31], off
	global_load_dword v50, v[32:33], off
	global_load_dword v51, v[34:35], off
	global_load_dword v52, v[36:37], off
	global_load_dword v53, v[38:39], off
	global_load_dword v54, v[40:41], off
	v_add_co_u32_e32 v26, vcc, s58, v24
	s_nop 1
	v_addc_co_u32_e32 v27, vcc, 0, v25, vcc
	v_add_co_u32_e32 v28, vcc, s59, v24
	s_nop 1
	v_addc_co_u32_e32 v29, vcc, 0, v25, vcc
	v_add_co_u32_e32 v30, vcc, s60, v24
	s_nop 1
	v_addc_co_u32_e32 v31, vcc, 0, v25, vcc
	v_add_co_u32_e32 v32, vcc, s61, v24
	s_nop 1
	v_addc_co_u32_e32 v33, vcc, 0, v25, vcc
	v_add_co_u32_e32 v34, vcc, s62, v24
	s_nop 1
	v_addc_co_u32_e32 v35, vcc, 0, v25, vcc
	v_add_co_u32_e32 v36, vcc, s63, v24
	s_nop 1
	v_addc_co_u32_e32 v37, vcc, 0, v25, vcc
	v_add_co_u32_e32 v38, vcc, s64, v24
	s_nop 1
	v_addc_co_u32_e32 v39, vcc, 0, v25, vcc
	v_add_co_u32_e32 v40, vcc, s65, v24
	s_nop 1
	v_addc_co_u32_e32 v41, vcc, 0, v25, vcc
	global_load_dword v55, v[26:27], off
	global_load_dword v56, v[28:29], off
	global_load_dword v57, v[30:31], off
	global_load_dword v58, v[32:33], off
	global_load_dword v59, v[34:35], off
	global_load_dword v60, v[36:37], off
	global_load_dword v61, v[38:39], off
	s_nop 0
	global_load_dword v40, v[40:41], off
	v_add_co_u32_e32 v26, vcc, s66, v24
	s_nop 1
	v_addc_co_u32_e32 v27, vcc, 0, v25, vcc
	v_add_co_u32_e32 v28, vcc, s67, v24
	s_nop 1
	v_addc_co_u32_e32 v29, vcc, 0, v25, vcc
	v_add_co_u32_e32 v30, vcc, s68, v24
	s_nop 1
	v_addc_co_u32_e32 v31, vcc, 0, v25, vcc
	v_add_co_u32_e32 v32, vcc, s69, v24
	s_nop 1
	v_addc_co_u32_e32 v33, vcc, 0, v25, vcc
	v_add_co_u32_e32 v34, vcc, s70, v24
	s_nop 1
	v_addc_co_u32_e32 v35, vcc, 0, v25, vcc
	v_add_co_u32_e32 v36, vcc, s71, v24
	s_nop 1
	v_addc_co_u32_e32 v37, vcc, 0, v25, vcc
	v_add_co_u32_e32 v38, vcc, s72, v24
	s_nop 1
	v_addc_co_u32_e32 v39, vcc, 0, v25, vcc
	v_add_co_u32_e32 v24, vcc, s73, v24
	s_nop 1
	v_addc_co_u32_e32 v25, vcc, 0, v25, vcc
	global_load_dword v26, v[26:27], off
	s_nop 0
	global_load_dword v27, v[28:29], off
	s_nop 0
	global_load_dword v28, v[30:31], off
	global_load_dword v29, v[32:33], off
	s_nop 0
	global_load_dword v30, v[34:35], off
	global_load_dword v31, v[36:37], off
	global_load_dword v32, v[38:39], off
	s_nop 0
	global_load_dword v24, v[24:25], off
	s_waitcnt vmcnt(0) lgkmcnt(0)
	ds_write2_b32 v10, v7, v9 offset1:66
	ds_write2_b32 v10, v23, v42 offset0:132 offset1:198
	ds_write2_b32 v16, v43, v44 offset0:8 offset1:74
	ds_write2_b32 v16, v45, v46 offset0:140 offset1:206
	ds_write2_b32 v17, v47, v48 offset0:16 offset1:82
	ds_write2_b32 v17, v49, v50 offset0:148 offset1:214
	ds_write2_b32 v18, v51, v52 offset0:24 offset1:90
	ds_write2_b32 v18, v53, v54 offset0:156 offset1:222
	ds_write2_b32 v19, v55, v56 offset0:32 offset1:98
	ds_write2_b32 v19, v57, v58 offset0:164 offset1:230
	ds_write2_b32 v20, v59, v60 offset0:40 offset1:106
	ds_write2_b32 v20, v61, v40 offset0:172 offset1:238
	ds_write2_b32 v21, v26, v27 offset0:48 offset1:114
	ds_write2_b32 v21, v28, v29 offset0:180 offset1:246
	ds_write2_b32 v22, v30, v31 offset0:56 offset1:122
	ds_write2_b32 v22, v32, v24 offset0:188 offset1:254
	s_waitcnt lgkmcnt(0)
	v_mov_b32_e32 v9, v3
	v_lshl_add_u64 v[24:25], s[20:21], 0, v[8:9]
	ds_read_b32 v7, v12
	ds_read_b32 v9, v12 offset:132
	ds_read_b32 v23, v12 offset:264
	ds_read_b32 v26, v12 offset:396
	ds_read_b32 v27, v12 offset:528
	ds_read_b32 v30, v12 offset:660
	ds_read_b32 v31, v12 offset:792
	ds_read_b32 v32, v12 offset:924
	v_lshl_add_u64 v[28:29], v[24:25], 0, s[16:17]
	s_waitcnt lgkmcnt(6)
	v_cvt_pk_bf16_f32 v24, v7, v9
	v_or_b32_e32 v7, s19, v11
	s_waitcnt lgkmcnt(4)
	v_cvt_pk_bf16_f32 v25, v23, v26
	s_waitcnt lgkmcnt(2)
	v_cvt_pk_bf16_f32 v26, v27, v30
	s_waitcnt lgkmcnt(0)
	v_cvt_pk_bf16_f32 v27, v31, v32
	v_lshlrev_b32_e32 v30, 11, v7
	v_mov_b32_e32 v31, v3
	v_lshl_add_u64 v[30:31], v[28:29], 0, v[30:31]
	global_store_dwordx4 v[30:31], v[24:27], off
	ds_read_b32 v7, v12 offset:32
	ds_read_b32 v9, v12 offset:164
	ds_read_b32 v23, v12 offset:296
	ds_read_b32 v25, v12 offset:428
	ds_read_b32 v26, v12 offset:560
	ds_read_b32 v27, v12 offset:692
	ds_read_b32 v30, v12 offset:824
	ds_read_b32 v31, v12 offset:956
	s_waitcnt lgkmcnt(0)
	v_cvt_pk_bf16_f32 v24, v7, v9
	v_or_b32_e32 v7, s19, v13
	v_cvt_pk_bf16_f32 v26, v26, v27
	v_cvt_pk_bf16_f32 v25, v23, v25
	v_cvt_pk_bf16_f32 v27, v30, v31
	v_lshlrev_b32_e32 v30, 11, v7
	v_mov_b32_e32 v31, v3
	v_lshl_add_u64 v[30:31], v[28:29], 0, v[30:31]
	global_store_dwordx4 v[30:31], v[24:27], off
	ds_read_b32 v7, v12 offset:64
	ds_read_b32 v9, v12 offset:196
	ds_read_b32 v23, v12 offset:328
	ds_read_b32 v25, v12 offset:460
	ds_read_b32 v26, v12 offset:592
	ds_read_b32 v27, v12 offset:724
	ds_read_b32 v30, v12 offset:856
	ds_read_b32 v31, v12 offset:988
	s_waitcnt lgkmcnt(0)
	v_cvt_pk_bf16_f32 v24, v7, v9
	v_or_b32_e32 v7, s19, v14
	v_cvt_pk_bf16_f32 v26, v26, v27
	v_cvt_pk_bf16_f32 v25, v23, v25
	v_cvt_pk_bf16_f32 v27, v30, v31
	v_lshlrev_b32_e32 v30, 11, v7
	v_mov_b32_e32 v31, v3
	v_lshl_add_u64 v[30:31], v[28:29], 0, v[30:31]
	global_store_dwordx4 v[30:31], v[24:27], off
	ds_read_b32 v7, v12 offset:96
	ds_read_b32 v9, v12 offset:228
	ds_read_b32 v23, v12 offset:360
	ds_read_b32 v25, v12 offset:492
	ds_read_b32 v26, v12 offset:624
	ds_read_b32 v27, v12 offset:756
	ds_read_b32 v30, v12 offset:888
	ds_read_b32 v31, v12 offset:1020
	s_waitcnt lgkmcnt(0)
	v_cvt_pk_bf16_f32 v24, v7, v9
	v_or_b32_e32 v7, s19, v15
	v_cvt_pk_bf16_f32 v26, v26, v27
	v_cvt_pk_bf16_f32 v25, v23, v25
	v_cvt_pk_bf16_f32 v27, v30, v31
	v_lshlrev_b32_e32 v30, 11, v7
	v_mov_b32_e32 v31, v3
	v_lshl_add_u64 v[28:29], v[28:29], 0, v[30:31]
	global_store_dwordx4 v[28:29], v[24:27], off
	s_waitcnt lgkmcnt(0)

.LBB0_55:
	s_andn2_b64 vcc, exec, s[20:21]
	s_cbranch_vccnz .LBB0_33
	v_mov_b32_e32 v7, s78
	ds_read_b64 v[24:25], v7
	s_mul_hi_i32 s19, s18, 0x920000
	s_mul_i32 s18, s18, 0x920000
	s_mul_i32 s20, s57, 0xffffe071
	s_waitcnt lgkmcnt(0)
	v_readfirstlane_b32 s94, v24
	v_readfirstlane_b32 s21, v25
	s_add_u32 s96, s94, s18
	s_addc_u32 s19, s21, s19
	s_lshr_b32 s18, s20, 16
	s_add_i32 s18, s18, s57
	s_sext_i32_i16 s20, s18
	s_ashr_i32 s20, s20, 6
	s_bfe_u32 s18, s18, 0x1000f
	s_add_i32 s18, s20, s18
	s_sext_i32_i16 s20, s18
	s_mulk_i32 s18, 0x49
	s_sub_i32 s57, s57, s18
	s_sext_i32_i16 s95, s57
	s_lshl_b32 s18, s20, 6
	s_lshl_b32 s94, s95, 5
	s_cmp_gt_i32 s95, 48
	s_cselect_b64 s[20:21], -1, 0
	s_cmp_lg_u64 s[20:21], 0
	s_subb_u32 s20, s95, 0
	s_lshl_b32 s20, s20, 5
	s_and_b32 s21, s57, 0xffff
	s_cmp_lg_u32 s21, 48
	s_cselect_b32 s20, s20, 0x900
	s_ashr_i32 s95, s94, 31
	s_lshl_b64 s[94:95], s[94:95], 2
	v_or_b32_e32 v7, s18, v1
	s_add_u32 s94, s96, s94
	s_addc_u32 s95, s19, s95
	v_mul_i32_i24_e32 v26, 0x2480, v7
	v_lshl_add_u64 v[24:25], s[94:95], 0, v[2:3]
	v_ashrrev_i32_e32 v27, 31, v26
	v_lshl_add_u64 v[24:25], v[24:25], 0, v[26:27]
	v_add_co_u32_e32 v26, vcc, s37, v24
	s_mov_b32 s19, 0x1b000
	s_nop 0
	v_addc_co_u32_e32 v27, vcc, 0, v25, vcc
	v_add_co_u32_e32 v28, vcc, s40, v24
	s_nop 1
	v_addc_co_u32_e32 v29, vcc, 0, v25, vcc
	v_add_co_u32_e32 v30, vcc, s43, v24
	s_nop 1
	v_addc_co_u32_e32 v31, vcc, 0, v25, vcc
	v_add_co_u32_e32 v32, vcc, s47, v24
	s_nop 1
	v_addc_co_u32_e32 v33, vcc, 0, v25, vcc
	v_add_co_u32_e32 v34, vcc, s49, v24
	s_nop 1
	v_addc_co_u32_e32 v35, vcc, 0, v25, vcc
	v_add_co_u32_e32 v36, vcc, s19, v24
	s_mov_b32 s19, 0x1f000
	s_nop 0
	v_addc_co_u32_e32 v37, vcc, 0, v25, vcc
	v_add_co_u32_e32 v38, vcc, s19, v24
	s_mov_b32 s19, 0x29000
	s_nop 0
	v_addc_co_u32_e32 v39, vcc, 0, v25, vcc
	global_load_dword v7, v[24:25], off
	global_load_dword v9, v[26:27], off offset:2304
	global_load_dword v23, v[28:29], off offset:512
	global_load_dword v42, v[30:31], off offset:2816
	global_load_dword v43, v[32:33], off offset:1024
	global_load_dword v44, v[34:35], off offset:3328
	global_load_dword v45, v[36:37], off offset:1536
	global_load_dword v46, v[38:39], off offset:3840
	v_add_co_u32_e32 v26, vcc, s60, v24
	s_nop 1
	v_addc_co_u32_e32 v27, vcc, 0, v25, vcc
	v_add_co_u32_e32 v28, vcc, s19, v24
	s_mov_b32 s19, 0x2d000
	s_nop 0
	v_addc_co_u32_e32 v29, vcc, 0, v25, vcc
	v_add_co_u32_e32 v30, vcc, s19, v24
	s_mov_b32 s19, 0x3b000
	s_nop 0
	v_addc_co_u32_e32 v31, vcc, 0, v25, vcc
	v_add_co_u32_e32 v32, vcc, s67, v24
	s_nop 1
	v_addc_co_u32_e32 v33, vcc, 0, v25, vcc
	v_add_co_u32_e32 v34, vcc, s69, v24
	s_nop 1
	v_addc_co_u32_e32 v35, vcc, 0, v25, vcc
	v_add_co_u32_e32 v36, vcc, s19, v24
	s_mov_b32 s19, 0x3f000
	s_nop 0
	v_addc_co_u32_e32 v37, vcc, 0, v25, vcc
	v_add_co_u32_e32 v38, vcc, s19, v24
	s_mov_b32 s19, 0x44000
	s_nop 0
	v_addc_co_u32_e32 v39, vcc, 0, v25, vcc
	v_add_co_u32_e32 v40, vcc, s19, v24
	s_mov_b32 s19, 0x49000
	s_nop 0
	v_addc_co_u32_e32 v41, vcc, 0, v25, vcc
	global_load_dword v47, v[26:27], off offset:2048
	global_load_dword v48, v[28:29], off offset:256
	global_load_dword v49, v[30:31], off offset:2560
	global_load_dword v50, v[32:33], off offset:768
	global_load_dword v51, v[34:35], off offset:3072
	global_load_dword v52, v[36:37], off offset:1280
	global_load_dword v53, v[38:39], off offset:3584
	global_load_dword v54, v[40:41], off offset:1792
	v_add_co_u32_e32 v26, vcc, s19, v24
	s_mov_b32 s19, 0x4d000
	s_nop 0
	v_addc_co_u32_e32 v27, vcc, 0, v25, vcc
	v_add_co_u32_e32 v28, vcc, s19, v24
	s_mov_b32 s19, 0x52000
	s_nop 0
	v_addc_co_u32_e32 v29, vcc, 0, v25, vcc
	v_add_co_u32_e32 v30, vcc, s19, v24
	s_mov_b32 s19, 0x56000
	s_nop 0
	v_addc_co_u32_e32 v31, vcc, 0, v25, vcc
	v_add_co_u32_e32 v32, vcc, s19, v24
	s_ashr_i32 s19, s18, 31
	s_nop 0
	v_addc_co_u32_e32 v33, vcc, 0, v25, vcc
	v_add_co_u32_e32 v34, vcc, s79, v24
	s_lshl_b64 s[18:19], s[18:19], 1
	s_nop 0
	v_addc_co_u32_e32 v35, vcc, 0, v25, vcc
	v_add_co_u32_e32 v36, vcc, s80, v24
	s_add_u32 s18, s6, s18
	s_nop 0
	v_addc_co_u32_e32 v37, vcc, 0, v25, vcc
	v_add_co_u32_e32 v38, vcc, s81, v24
	s_addc_u32 s19, s56, s19
	s_nop 0
	v_addc_co_u32_e32 v39, vcc, 0, v25, vcc
	v_add_co_u32_e32 v40, vcc, s75, v24
	s_nop 1
	v_addc_co_u32_e32 v41, vcc, 0, v25, vcc
	global_load_dword v55, v[26:27], off
	global_load_dword v56, v[28:29], off offset:2304
	global_load_dword v57, v[30:31], off offset:512
	global_load_dword v58, v[32:33], off offset:2816
	global_load_dword v59, v[34:35], off offset:1024
	global_load_dword v60, v[36:37], off offset:3328
	global_load_dword v61, v[38:39], off offset:1536
	s_nop 0
	global_load_dword v40, v[40:41], off offset:3840
	v_add_co_u32_e32 v26, vcc, s82, v24
	s_nop 1
	v_addc_co_u32_e32 v27, vcc, 0, v25, vcc
	v_add_co_u32_e32 v28, vcc, s83, v24
	s_nop 1
	v_addc_co_u32_e32 v29, vcc, 0, v25, vcc
	v_add_co_u32_e32 v30, vcc, s84, v24
	s_nop 1
	v_addc_co_u32_e32 v31, vcc, 0, v25, vcc
	v_add_co_u32_e32 v32, vcc, s85, v24
	s_nop 1
	v_addc_co_u32_e32 v33, vcc, 0, v25, vcc
	v_add_co_u32_e32 v34, vcc, s86, v24
	s_nop 1
	v_addc_co_u32_e32 v35, vcc, 0, v25, vcc
	v_add_co_u32_e32 v36, vcc, s87, v24
	s_nop 1
	v_addc_co_u32_e32 v37, vcc, 0, v25, vcc
	v_add_co_u32_e32 v38, vcc, s76, v24
	s_nop 1
	v_addc_co_u32_e32 v39, vcc, 0, v25, vcc
	v_add_co_u32_e32 v24, vcc, s88, v24
	s_nop 1
	v_addc_co_u32_e32 v25, vcc, 0, v25, vcc
	global_load_dword v26, v[26:27], off offset:2048
	s_nop 0
	global_load_dword v27, v[28:29], off offset:256
	s_nop 0
	global_load_dword v28, v[30:31], off offset:2560
	global_load_dword v29, v[32:33], off offset:768
	s_nop 0
	global_load_dword v30, v[34:35], off offset:3072
	global_load_dword v31, v[36:37], off offset:1280
	global_load_dword v32, v[38:39], off offset:3584
	s_nop 0
	global_load_dword v24, v[24:25], off offset:1792
	s_waitcnt vmcnt(0) lgkmcnt(0)
	ds_write2_b32 v10, v7, v9 offset1:66
	ds_write2_b32 v10, v23, v42 offset0:132 offset1:198
	ds_write2_b32 v16, v43, v44 offset0:8 offset1:74
	ds_write2_b32 v16, v45, v46 offset0:140 offset1:206
	ds_write2_b32 v17, v47, v48 offset0:16 offset1:82
	ds_write2_b32 v17, v49, v50 offset0:148 offset1:214
	ds_write2_b32 v18, v51, v52 offset0:24 offset1:90
	ds_write2_b32 v18, v53, v54 offset0:156 offset1:222
	ds_write2_b32 v19, v55, v56 offset0:32 offset1:98
	ds_write2_b32 v19, v57, v58 offset0:164 offset1:230
	ds_write2_b32 v20, v59, v60 offset0:40 offset1:106
	ds_write2_b32 v20, v61, v40 offset0:172 offset1:238
	ds_write2_b32 v21, v26, v27 offset0:48 offset1:114
	ds_write2_b32 v21, v28, v29 offset0:180 offset1:246
	ds_write2_b32 v22, v30, v31 offset0:56 offset1:122
	ds_write2_b32 v22, v32, v24 offset0:188 offset1:254
	s_waitcnt lgkmcnt(0)
	ds_read_b32 v7, v12
	ds_read_b32 v23, v12 offset:132
	ds_read_b32 v25, v12 offset:264
	ds_read_b32 v26, v12 offset:396
	ds_read_b32 v27, v12 offset:528
	ds_read_b32 v30, v12 offset:660
	ds_read_b32 v31, v12 offset:792
	ds_read_b32 v32, v12 offset:924
	s_waitcnt lgkmcnt(4)
	v_cvt_pk_bf16_f32 v25, v25, v26
	v_mov_b32_e32 v9, v3
	s_waitcnt lgkmcnt(2)
	v_cvt_pk_bf16_f32 v26, v27, v30
	v_or_b32_e32 v30, s20, v11
	s_waitcnt lgkmcnt(0)
	v_cvt_pk_bf16_f32 v27, v31, v32
	v_ashrrev_i32_e32 v31, 31, v30
	v_lshl_add_u64 v[28:29], s[18:19], 0, v[8:9]
	v_lshlrev_b64 v[30:31], 11, v[30:31]
	v_cvt_pk_bf16_f32 v24, v7, v23
	v_lshl_add_u64 v[30:31], v[28:29], 0, v[30:31]
	global_store_dwordx4 v[30:31], v[24:27], off
	ds_read_b32 v7, v12 offset:32
	ds_read_b32 v9, v12 offset:164
	ds_read_b32 v23, v12 offset:296
	ds_read_b32 v25, v12 offset:428
	ds_read_b32 v26, v12 offset:560
	ds_read_b32 v27, v12 offset:692
	ds_read_b32 v30, v12 offset:824
	ds_read_b32 v31, v12 offset:956
	s_waitcnt lgkmcnt(0)
	v_cvt_pk_bf16_f32 v24, v7, v9
	v_cvt_pk_bf16_f32 v25, v23, v25
	v_cvt_pk_bf16_f32 v26, v26, v27
	v_cvt_pk_bf16_f32 v27, v30, v31
	v_or_b32_e32 v30, s20, v13
	v_ashrrev_i32_e32 v31, 31, v30
	v_lshlrev_b64 v[30:31], 11, v[30:31]
	v_lshl_add_u64 v[30:31], v[28:29], 0, v[30:31]
	global_store_dwordx4 v[30:31], v[24:27], off
	ds_read_b32 v7, v12 offset:64
	ds_read_b32 v9, v12 offset:196
	ds_read_b32 v23, v12 offset:328
	ds_read_b32 v25, v12 offset:460
	ds_read_b32 v26, v12 offset:592
	ds_read_b32 v27, v12 offset:724
	ds_read_b32 v30, v12 offset:856
	ds_read_b32 v31, v12 offset:988
	s_waitcnt lgkmcnt(0)
	v_cvt_pk_bf16_f32 v24, v7, v9
	v_cvt_pk_bf16_f32 v25, v23, v25
	v_cvt_pk_bf16_f32 v26, v26, v27
	v_cvt_pk_bf16_f32 v27, v30, v31
	v_or_b32_e32 v30, s20, v14
	v_ashrrev_i32_e32 v31, 31, v30
	v_lshlrev_b64 v[30:31], 11, v[30:31]
	v_lshl_add_u64 v[30:31], v[28:29], 0, v[30:31]
	global_store_dwordx4 v[30:31], v[24:27], off
	ds_read_b32 v7, v12 offset:96
	ds_read_b32 v9, v12 offset:228
	ds_read_b32 v23, v12 offset:360
	ds_read_b32 v25, v12 offset:492
	ds_read_b32 v26, v12 offset:624
	ds_read_b32 v27, v12 offset:756
	ds_read_b32 v30, v12 offset:888
	ds_read_b32 v31, v12 offset:1020
	s_waitcnt lgkmcnt(0)
	v_cvt_pk_bf16_f32 v24, v7, v9
	v_cvt_pk_bf16_f32 v25, v23, v25
	v_cvt_pk_bf16_f32 v26, v26, v27
	v_cvt_pk_bf16_f32 v27, v30, v31
	v_or_b32_e32 v30, s20, v15
	v_ashrrev_i32_e32 v31, 31, v30
	v_lshlrev_b64 v[30:31], 11, v[30:31]
	v_lshl_add_u64 v[28:29], v[28:29], 0, v[30:31]
	global_store_dwordx4 v[28:29], v[24:27], off
	s_waitcnt lgkmcnt(0)
	s_branch .LBB0_33

.LBB0_60:
	v_mul_hi_i32 v8, v1, s3
	v_add_u32_e32 v8, v8, v1
	v_lshrrev_b32_e32 v9, 31, v8
	v_ashrrev_i32_e32 v8, 14, v8
	v_add_u32_e32 v8, v8, v9
	v_mul_i32_i24_e32 v10, 0x7000, v8
	v_sub_u32_e32 v10, v1, v10
	v_mad_i64_i32 v[8:9], s[14:15], v8, s10, v[6:7]
	v_add_u32_e32 v1, s72, v1
	v_ashrrev_i32_e32 v11, 31, v10
	v_cmp_lt_i32_e32 vcc, s11, v1
	v_lshl_add_u64 v[8:9], v[10:11], 4, v[8:9]
	s_or_b64 s[8:9], vcc, s[8:9]
	v_add_co_u32_e32 v8, vcc, 0x2490000, v8
	s_nop 1
	v_addc_co_u32_e32 v9, vcc, 0, v9, vcc
	global_store_dwordx4 v[8:9], v[2:5], off
	s_andn2_b64 exec, exec, s[8:9]
	s_cbranch_execnz .LBB0_60

.LBB0_63:
	s_or_b64 exec, exec, s[6:7]
	v_mul_f32_e32 v51, v50, v50
	v_fmamk_f32 v56, v51, 0xb94c1982, v15
	v_fmaak_f32 v56, v51, v56, 0xbe2aaa9d
	v_mul_f32_e32 v56, v51, v56
	v_fmac_f32_e32 v50, v50, v56
	v_fmamk_f32 v56, v51, 0x37d75334, v34
	v_fmaak_f32 v56, v51, v56, 0x3d2aabf7
	v_fmaak_f32 v56, v51, v56, 0xbf000004
	v_fma_f32 v51, v51, v56, 1.0
	v_and_b32_e32 v56, 1, v49
	v_lshlrev_b32_e32 v49, 30, v49
	v_cmp_eq_u32_e32 vcc, 0, v56
	v_and_b32_e32 v49, 0x80000000, v49
	v_xor_b32_e32 v42, v42, v41
	v_cndmask_b32_e32 v50, v51, v50, vcc
	v_xor_b32_e32 v42, v42, v49
	v_xor_b32_e32 v42, v42, v50
	v_cmp_class_f32_e64 vcc, v41, s41
	v_mul_f32_e32 v64, v33, v40
	v_mul_f32_e32 v40, 0x3fb8aa3b, v64
	v_cndmask_b32_e32 v41, v38, v42, vcc
	v_mul_f32_e32 v42, v44, v44
	v_fmamk_f32 v49, v42, 0xb94c1982, v15
	v_fmaak_f32 v49, v42, v49, 0xbe2aaa9d
	v_mul_f32_e32 v49, v42, v49
	v_fmac_f32_e32 v44, v44, v49
	v_fmamk_f32 v49, v42, 0x37d75334, v34
	v_fmaak_f32 v49, v42, v49, 0x3d2aabf7
	v_fmaak_f32 v49, v42, v49, 0xbf000004
	v_fma_f32 v42, v42, v49, 1.0
	v_and_b32_e32 v49, 1, v43
	v_cmp_eq_u32_e64 s[6:7], 0, v49
	v_rndne_f32_e32 v65, v40
	v_cvt_i32_f32_e32 v66, v65
	v_cndmask_b32_e64 v42, -v44, v42, s[6:7]
	v_fma_f32 v44, v64, s3, -v40
	v_fmac_f32_e32 v44, 0x32a5705f, v64
	v_sub_f32_e32 v40, v40, v65
	v_add_f32_e32 v40, v40, v44
	v_exp_f32_e32 v40, v40
	v_lshlrev_b32_e32 v43, 30, v43
	v_bitop3_b32 v42, v43, v42, s42 bitop3:0x6c
	v_cndmask_b32_e32 v67, v38, v42, vcc
	v_ldexp_f32 v40, v40, v66
	v_cmp_ngt_f32_e32 vcc, s26, v64
	v_mul_f32_e32 v44, v48, v48
	v_readfirstlane_b32 s7, v9
	v_cndmask_b32_e32 v40, 0, v40, vcc
	v_cmp_nlt_f32_e32 vcc, s27, v64
	v_readfirstlane_b32 s6, v8
	v_fmamk_f32 v69, v65, 0xbf317218, v64
	v_cndmask_b32_e32 v42, v1, v40, vcc
	v_fmamk_f32 v40, v44, 0xb94c1982, v15
	v_fmaak_f32 v49, v44, v40, 0xbe2aaa9d
	v_mul_f32_e32 v40, v42, v67
	v_mul_f32_e32 v41, v42, v41
	v_add_f32_e32 v43, v40, v40
	v_mul_f32_e32 v42, v41, v41
	v_mul_f32_e32 v43, v43, v41
	v_fma_f32 v42, v40, v40, -v42
	v_mul_f32_e32 v50, v43, v43
	v_fma_f32 v50, v42, v42, -v50
	v_add_f32_e32 v42, v42, v42
	v_mul_f32_e32 v42, v43, v42
	v_mul_f32_e32 v43, v42, v42
	v_fma_f32 v43, v50, v50, -v43
	v_add_f32_e32 v50, v50, v50
	v_mul_f32_e32 v42, v42, v50
	v_mul_f32_e32 v50, v42, v42
	v_fma_f32 v50, v43, v43, -v50
	v_add_f32_e32 v43, v43, v43
	v_mul_f32_e32 v42, v42, v43
	v_mul_f32_e32 v43, v42, v42
	v_fma_f32 v43, v50, v50, -v43
	v_add_f32_e32 v50, v50, v50
	v_mul_f32_e32 v50, v42, v50
	v_mul_f32_e32 v42, v50, v50
	v_fma_f32 v42, v43, v43, -v42
	v_add_f32_e32 v43, v43, v43
	v_mul_f32_e32 v43, v50, v43
	v_add_co_u32_e32 v50, vcc, -12, v26
	v_fmac_f32_e32 v69, 0x3102e308, v65
	s_nop 0
	v_addc_co_u32_e32 v51, vcc, -1, v27, vcc
	global_store_dwordx4 v[50:51], v[40:43], off
	v_lshl_add_u64 v[50:51], s[6:7], 0, v[24:25]
	v_readfirstlane_b32 s7, v11
	v_readfirstlane_b32 s6, v10
	v_mul_f32_e32 v40, v44, v49
	v_fmac_f32_e32 v48, v48, v40
	v_lshl_add_u64 v[72:73], s[6:7], 0, v[24:25]
	v_fmamk_f32 v40, v44, 0x37d75334, v34
	global_load_dwordx4 v[56:59], v[72:73], off
	global_load_dwordx4 v[60:63], v[50:51], off
	v_fmaak_f32 v40, v44, v40, 0x3d2aabf7
	v_and_b32_e32 v42, 1, v47
	v_fmaak_f32 v40, v44, v40, 0xbf000004
	v_cmp_eq_u32_e32 vcc, 0, v42
	v_lshlrev_b32_e32 v42, 30, v47
	v_fma_f32 v40, v44, v40, 1.0
	v_and_b32_e32 v42, 0x80000000, v42
	v_xor_b32_e32 v43, v46, v45
	v_cndmask_b32_e32 v40, v40, v48, vcc
	v_xor_b32_e32 v42, v43, v42
	v_xor_b32_e32 v40, v42, v40
	v_cmp_class_f32_e64 vcc, v45, s41
	global_load_dwordx4 v[42:45], v[72:73], off offset:16
	global_load_dwordx4 v[46:49], v[50:51], off offset:16
	v_fmamk_f32 v70, v69, 0x395133b1, v35
	v_fmaak_f32 v70, v69, v70, 0x3c0887f9
	v_fmaak_f32 v70, v69, v70, 0x3d2aaa81
	v_fmaak_f32 v70, v69, v70, 0x3e2aaaab
	v_cndmask_b32_e32 v40, v38, v40, vcc
	v_fma_f32 v70, v69, v70, 0.5
	v_ldexp_f32 v66, 1.0, v66
	v_cmp_eq_f32_e32 vcc, s43, v65
	v_mul_f32_e32 v70, v69, v70
	v_fmac_f32_e32 v69, v69, v70
	v_cndmask_b32_e32 v65, v66, v39, vcc
	v_add_f32_e32 v66, -1.0, v65
	v_fmac_f32_e32 v66, v65, v69
	v_add_f32_e32 v65, v66, v66
	v_cndmask_b32_e32 v65, v66, v65, vcc
	v_cmp_nlt_f32_e32 vcc, s44, v64
	v_mul_f32_e32 v68, v32, v32
	v_fmac_f32_e32 v68, v33, v33
	v_cndmask_b32_e32 v65, v1, v65, vcc
	v_cmp_ngt_f32_e32 vcc, s45, v64
	v_add_u32_e32 v14, s72, v14
	v_lshl_add_u64 v[24:25], v[24:25], 0, s[16:17]
	v_cndmask_b32_e32 v64, -1.0, v65, vcc
	v_add_f32_e32 v65, v40, v40
	v_mul_f32_e32 v40, v40, v65
	v_fma_f32 v40, v64, v67, -v40
	v_mul_f32_e32 v64, v33, v40
	v_fmac_f32_e32 v64, v32, v41
	v_div_scale_f32 v65, s[6:7], v68, v68, v64
	v_rcp_f32_e32 v66, v65
	v_mul_f32_e32 v32, v32, v40
	v_fma_f32 v32, v33, v41, -v32
	v_lshl_add_u64 v[26:27], v[26:27], 0, s[0:1]
	v_fma_f32 v33, -v65, v66, 1.0
	v_fmac_f32_e32 v66, v33, v66
	v_div_scale_f32 v33, vcc, v64, v68, v64
	v_mul_f32_e32 v40, v33, v66
	v_fma_f32 v41, -v65, v40, v33
	v_fmac_f32_e32 v40, v41, v66
	v_div_scale_f32 v41, s[6:7], v68, v68, v32
	v_fma_f32 v33, -v65, v40, v33
	v_rcp_f32_e32 v65, v41
	v_div_fmas_f32 v33, v33, v66, v40
	v_div_fixup_f32 v74, v33, v68, v64
	v_readfirstlane_b32 s7, v13
	v_fma_f32 v33, -v41, v65, 1.0
	v_fmac_f32_e32 v65, v33, v65
	v_div_scale_f32 v33, vcc, v32, v68, v32
	v_mul_f32_e32 v40, v33, v65
	v_fma_f32 v64, -v41, v40, v33
	v_fmac_f32_e32 v40, v64, v65
	v_fma_f32 v33, -v41, v40, v33
	v_div_fmas_f32 v33, v33, v65, v40
	v_div_fixup_f32 v75, v33, v68, v32
	global_load_dwordx4 v[64:67], v[72:73], off offset:32
	global_load_dwordx4 v[68:71], v[50:51], off offset:32
	v_lshlrev_b64 v[32:33], 13, v[30:31]
	v_lshl_add_u64 v[32:33], v[20:21], 0, v[32:33]
	v_lshlrev_b64 v[30:31], 12, v[30:31]
	v_readfirstlane_b32 s6, v12
	v_lshl_add_u64 v[28:29], v[28:29], 0, s[18:19]
	s_waitcnt vmcnt(0) lgkmcnt(0)
	v_mul_f32_e32 v40, v56, v75
	v_mul_f32_e32 v41, v57, v75
	v_fma_f32 v41, v61, v74, -v41
	v_fma_f32 v40, v60, v74, -v40
	v_mul_f32_e32 v76, v56, v74
	v_cvt_pk_bf16_f32 v40, v40, v41
	v_mul_f32_e32 v41, v75, v58
	v_mul_f32_e32 v56, v75, v59
	v_fma_f32 v56, v74, v63, -v56
	v_fma_f32 v41, v74, v62, -v41
	v_cvt_pk_bf16_f32 v41, v41, v56
	v_mul_f32_e32 v77, v57, v74
	v_mul_f32_e32 v78, v74, v58
	v_mul_f32_e32 v80, v74, v42
	v_mul_f32_e32 v42, v75, v42
	v_mul_f32_e32 v56, v75, v43
	v_mul_f32_e32 v79, v74, v59
	v_fma_f32 v56, v74, v47, -v56
	v_fma_f32 v42, v74, v46, -v42
	v_fmac_f32_e32 v76, v60, v75
	v_fmac_f32_e32 v77, v61, v75
	v_fmac_f32_e32 v78, v75, v62
	v_fmac_f32_e32 v79, v75, v63
	v_cvt_pk_bf16_f32 v42, v42, v56
	global_load_dwordx4 v[56:59], v[72:73], off offset:48
	global_load_dwordx4 v[60:63], v[50:51], off offset:48
	v_fmac_f32_e32 v80, v75, v46
	v_mul_f32_e32 v46, v74, v43
	v_fmac_f32_e32 v46, v75, v47
	v_mul_f32_e32 v47, v74, v44
	v_mul_f32_e32 v43, v75, v44
	v_mul_f32_e32 v44, v75, v45
	v_fma_f32 v44, v74, v49, -v44
	v_fma_f32 v43, v74, v48, -v43
	v_cvt_pk_bf16_f32 v43, v43, v44
	global_store_dwordx4 v[32:33], v[40:43], off
	v_fmac_f32_e32 v47, v75, v48
	s_nop 0
	v_mul_f32_e32 v40, v74, v45
	v_fmac_f32_e32 v40, v75, v49
	v_lshl_add_u64 v[44:45], s[6:7], 0, v[30:31]
	v_readfirstlane_b32 s7, v17
	v_readfirstlane_b32 s6, v16
	v_cvt_pk_bf16_f32 v43, v47, v40
	v_cvt_pk_bf16_f32 v42, v80, v46
	v_lshl_add_u64 v[46:47], s[6:7], 0, v[30:31]
	v_lshl_add_u64 v[46:47], v[46:47], 0, v[18:19]
	v_cvt_pk_bf16_f32 v41, v78, v79
	v_cvt_pk_bf16_f32 v40, v76, v77
	v_lshl_add_u64 v[44:45], v[44:45], 0, v[18:19]
	global_load_dword v48, v[46:47], off
	global_load_dword v49, v[46:47], off offset:256
	global_load_dword v50, v[46:47], off offset:512
	global_load_dword v51, v[46:47], off offset:768
	global_load_dword v72, v[44:45], off
	global_load_dword v73, v[44:45], off offset:256
	global_load_dword v76, v[44:45], off offset:512
	global_load_dword v77, v[44:45], off offset:768
	global_load_dword v78, v[44:45], off offset:1024
	global_load_dword v79, v[44:45], off offset:1280
	global_load_dword v80, v[44:45], off offset:1536
	global_load_dword v81, v[44:45], off offset:1792
	global_load_dword v82, v[46:47], off offset:1024
	global_load_dword v83, v[46:47], off offset:1280
	global_load_dword v84, v[46:47], off offset:1536
	global_load_dword v85, v[46:47], off offset:1792
	global_load_dword v86, v[46:47], off offset:2048
	global_load_dword v87, v[46:47], off offset:2304
	global_load_dword v88, v[46:47], off offset:2560
	global_load_dword v89, v[46:47], off offset:2816
	global_load_dword v90, v[44:45], off offset:2048
	global_load_dword v91, v[44:45], off offset:2304
	global_load_dword v92, v[44:45], off offset:2560
	global_load_dword v93, v[44:45], off offset:2816
	global_load_dword v94, v[44:45], off offset:3072
	global_load_dword v95, v[44:45], off offset:3328
	global_load_dword v96, v[44:45], off offset:3584
	global_load_dword v97, v[44:45], off offset:3840
	global_load_dword v98, v[46:47], off offset:3072
	global_load_dword v99, v[46:47], off offset:3328
	global_load_dword v100, v[46:47], off offset:3584
	global_load_dword v101, v[46:47], off offset:3840
	v_add_co_u32_e32 v44, vcc, s46, v32
	v_lshl_add_u64 v[30:31], v[22:23], 0, v[30:31]
	s_nop 0
	v_addc_co_u32_e32 v45, vcc, 0, v33, vcc
	global_store_dwordx4 v[44:45], v[40:43], off
	global_store_dwordx4 v[32:33], v[52:55], off offset:32
	global_store_dwordx4 v[44:45], v[52:55], off offset:32
	v_cmp_lt_i32_e32 vcc, s47, v14
	s_or_b64 s[20:21], vcc, s[20:21]
	v_mul_f32_e32 v40, v75, v64
	v_mul_f32_e32 v41, v75, v65
	v_fma_f32 v41, v74, v69, -v41
	v_fma_f32 v40, v74, v68, -v40
	v_cvt_pk_bf16_f32 v40, v40, v41
	v_mul_f32_e32 v41, v75, v66
	v_mul_f32_e32 v42, v75, v67
	v_fma_f32 v42, v74, v71, -v42
	v_fma_f32 v41, v74, v70, -v41
	v_cvt_pk_bf16_f32 v41, v41, v42
	v_mul_f32_e32 v46, v74, v64
	v_mul_f32_e32 v64, v74, v66
	v_mul_f32_e32 v47, v74, v65
	v_mul_f32_e32 v65, v74, v67
	v_fmac_f32_e32 v46, v75, v68
	v_fmac_f32_e32 v47, v75, v69
	v_fmac_f32_e32 v64, v75, v70
	v_fmac_f32_e32 v65, v75, v71
	s_waitcnt vmcnt(0) lgkmcnt(0)
	v_mul_f32_e32 v42, v75, v56
	v_mul_f32_e32 v43, v75, v57
	v_fma_f32 v43, v74, v61, -v43
	v_fma_f32 v42, v74, v60, -v42
	v_mul_f32_e32 v66, v74, v56
	v_cvt_pk_bf16_f32 v42, v42, v43
	v_mul_f32_e32 v56, v74, v57
	v_mul_f32_e32 v57, v74, v58
	v_mul_f32_e32 v43, v75, v58
	v_mul_f32_e32 v58, v75, v59
	v_fma_f32 v58, v74, v63, -v58
	v_fma_f32 v43, v74, v62, -v43
	v_cvt_pk_bf16_f32 v43, v43, v58
	global_store_dwordx4 v[32:33], v[40:43], off offset:16
	v_fmac_f32_e32 v66, v75, v60
	v_fmac_f32_e32 v56, v75, v61
	v_mul_f32_e32 v40, v74, v59
	v_fmac_f32_e32 v57, v75, v62
	v_fmac_f32_e32 v40, v75, v63
	v_cvt_pk_bf16_f32 v43, v57, v40
	v_cvt_pk_bf16_f32 v42, v66, v56
	v_cvt_pk_bf16_f32 v41, v64, v65
	v_cvt_pk_bf16_f32 v40, v46, v47
	global_store_dwordx4 v[44:45], v[40:43], off offset:16
	global_store_dwordx4 v[32:33], v[52:55], off offset:48
	global_store_dwordx4 v[44:45], v[52:55], off offset:48
	v_cvt_pk_bf16_f32 v32, v72, -v48
	global_store_dword v[30:31], v32, off
	v_cvt_pk_bf16_f32 v32, v73, -v49
	global_store_dword v[30:31], v32, off offset:256
	v_cvt_pk_bf16_f32 v32, v76, -v50
	global_store_dword v[30:31], v32, off offset:512
	v_cvt_pk_bf16_f32 v32, v77, -v51
	global_store_dword v[30:31], v32, off offset:768
	v_cvt_pk_bf16_f32 v32, v78, -v82
	global_store_dword v[30:31], v32, off offset:1024
	v_cvt_pk_bf16_f32 v32, v79, -v83
	global_store_dword v[30:31], v32, off offset:1280
	v_cvt_pk_bf16_f32 v32, v80, -v84
	global_store_dword v[30:31], v32, off offset:1536
	v_cvt_pk_bf16_f32 v32, v81, -v85
	global_store_dword v[30:31], v32, off offset:1792
	v_cvt_pk_bf16_f32 v32, v90, -v86
	global_store_dword v[30:31], v32, off offset:2048
	v_cvt_pk_bf16_f32 v32, v91, -v87
	global_store_dword v[30:31], v32, off offset:2304
	v_cvt_pk_bf16_f32 v32, v92, -v88
	global_store_dword v[30:31], v32, off offset:2560
	v_cvt_pk_bf16_f32 v32, v93, -v89
	global_store_dword v[30:31], v32, off offset:2816
	v_cvt_pk_bf16_f32 v32, v94, -v98
	global_store_dword v[30:31], v32, off offset:3072
	v_cvt_pk_bf16_f32 v32, v95, -v99
	global_store_dword v[30:31], v32, off offset:3328
	v_cvt_pk_bf16_f32 v32, v96, -v100
	global_store_dword v[30:31], v32, off offset:3584
	v_cvt_pk_bf16_f32 v32, v97, -v101
	global_store_dword v[30:31], v32, off offset:3840
	s_andn2_b64 exec, exec, s[20:21]
	s_cbranch_execz .LBB0_76
.LBB0_64:
	v_ashrrev_i32_e32 v30, 6, v14
	s_waitcnt lgkmcnt(0)
	v_readfirstlane_b32 s6, v7
	v_readfirstlane_b32 s7, v6
	v_ashrrev_i32_e32 v31, 31, v30
	v_mov_b32_e32 v33, s6
	v_mov_b32_e32 v32, s7
	v_lshl_add_u64 v[32:33], v[30:31], 2, v[32:33]
	global_load_dword v42, v[32:33], off
	v_readfirstlane_b32 s7, v5
	v_readfirstlane_b32 s6, v4
	s_waitcnt vmcnt(0) lgkmcnt(0)
	v_cmp_ngt_f32_e32 vcc, s26, v42
	v_lshl_add_u64 v[32:33], s[6:7], 0, v[28:29]
	global_load_dword v32, v[32:33], off
	v_readfirstlane_b32 s7, v3
	v_readfirstlane_b32 s6, v2
	s_nop 1
	v_lshl_add_u64 v[40:41], s[6:7], 0, v[28:29]
	global_load_dword v33, v[40:41], off
	v_mul_f32_e32 v40, 0x3fb8aa3b, v42
	v_fma_f32 v41, v42, s3, -v40
	v_rndne_f32_e32 v43, v40
	v_fmac_f32_e32 v41, 0x32a5705f, v42
	v_sub_f32_e32 v40, v40, v43
	v_add_f32_e32 v40, v40, v41
	v_cvt_i32_f32_e32 v43, v43
	v_exp_f32_e32 v40, v40
	s_nop 0
	v_ldexp_f32 v40, v40, v43
	v_cndmask_b32_e32 v40, 0, v40, vcc
	v_cmp_nlt_f32_e32 vcc, s27, v42
	s_nop 1
	v_cndmask_b32_e32 v40, v1, v40, vcc
	s_waitcnt vmcnt(0) lgkmcnt(0)
	v_mul_f32_e32 v41, v32, v40
	v_and_b32_e32 v42, 0x7fffffff, v41
	v_lshrrev_b32_e32 v43, 23, v42
	v_and_b32_e32 v44, 0x7fffff, v42
	v_cmp_nlt_f32_e64 s[22:23], |v41|, s28
	v_add_u32_e32 v46, 0xffffff88, v43
	v_or_b32_e32 v45, 0x800000, v44
	s_and_saveexec_b64 s[6:7], s[22:23]
	s_xor_b64 s[24:25], exec, s[6:7]
	s_cbranch_execz .LBB0_66
	v_mad_u64_u32 v[48:49], s[10:11], v45, s29, 0
	v_mov_b32_e32 v50, v49
	v_mov_b32_e32 v51, v19
	v_mad_u64_u32 v[50:51], s[10:11], v45, s30, v[50:51]
	v_mov_b32_e32 v56, v51
	v_mov_b32_e32 v57, v19
	v_mad_u64_u32 v[56:57], s[10:11], v45, s31, v[56:57]
	v_cmp_lt_u32_e32 vcc, 63, v46
	v_mov_b32_e32 v58, v57
	v_mov_b32_e32 v59, v19
	v_cndmask_b32_e32 v43, 0, v36, vcc
	v_mad_u64_u32 v[58:59], s[10:11], v45, s34, v[58:59]
	v_add_u32_e32 v43, v43, v46
	v_mov_b32_e32 v60, v59
	v_mov_b32_e32 v61, v19
	v_cmp_lt_u32_e64 s[6:7], 31, v43
	v_mad_u64_u32 v[60:61], s[10:11], v45, s35, v[60:61]
	s_nop 0
	v_cndmask_b32_e64 v44, 0, v37, s[6:7]
	v_mov_b32_e32 v62, v61
	v_mov_b32_e32 v63, v19
	v_add_u32_e32 v43, v44, v43
	v_mad_u64_u32 v[62:63], s[10:11], v45, s36, v[62:63]
	v_cmp_lt_u32_e64 s[8:9], 31, v43
	v_mov_b32_e32 v64, v63
	v_mov_b32_e32 v65, v19
	v_cndmask_b32_e64 v44, 0, v37, s[8:9]
	v_mad_u64_u32 v[64:65], s[10:11], v45, s37, v[64:65]
	v_add_u32_e32 v43, v44, v43
	v_cndmask_b32_e32 v44, v62, v58, vcc
	v_cndmask_b32_e32 v47, v64, v60, vcc
	v_cndmask_b32_e32 v51, v65, v62, vcc
	v_cndmask_b32_e64 v49, v47, v44, s[6:7]
	v_cndmask_b32_e64 v47, v51, v47, s[6:7]
	v_cndmask_b32_e32 v51, v60, v56, vcc
	v_cndmask_b32_e64 v44, v44, v51, s[6:7]
	v_cndmask_b32_e64 v47, v47, v49, s[8:9]
	v_cndmask_b32_e64 v49, v49, v44, s[8:9]
	v_sub_u32_e32 v57, 32, v43
	v_alignbit_b32 v59, v47, v49, v57
	v_cmp_eq_u32_e64 s[10:11], 0, v43
	v_cndmask_b32_e32 v48, v56, v48, vcc
	s_nop 0
	v_cndmask_b32_e64 v43, v59, v47, s[10:11]
	v_cndmask_b32_e32 v47, v58, v50, vcc
	v_cndmask_b32_e64 v50, v51, v47, s[6:7]
	v_cndmask_b32_e64 v44, v44, v50, s[8:9]
	v_alignbit_b32 v51, v49, v44, v57
	v_cndmask_b32_e64 v47, v47, v48, s[6:7]
	v_cndmask_b32_e64 v49, v51, v49, s[10:11]
	v_bfe_u32 v59, v43, 29, 1
	v_cndmask_b32_e64 v47, v50, v47, s[8:9]
	v_alignbit_b32 v51, v43, v49, 30
	v_sub_u32_e32 v60, 0, v59
	v_alignbit_b32 v48, v44, v47, v57
	v_xor_b32_e32 v51, v51, v60
	v_cndmask_b32_e64 v44, v48, v44, s[10:11]
	v_alignbit_b32 v48, v49, v44, 30
	v_ffbh_u32_e32 v49, v51
	v_min_u32_e32 v49, 32, v49
	v_alignbit_b32 v44, v44, v47, 30
	v_xor_b32_e32 v48, v48, v60
	v_sub_u32_e32 v50, 31, v49
	v_xor_b32_e32 v44, v44, v60
	v_alignbit_b32 v51, v51, v48, v50
	v_alignbit_b32 v44, v48, v44, v50
	v_alignbit_b32 v47, v51, v44, 9
	v_ffbh_u32_e32 v48, v47
	v_min_u32_e32 v48, 32, v48
	v_lshrrev_b32_e32 v58, 29, v43
	v_not_b32_e32 v50, v48
	v_alignbit_b32 v44, v47, v44, v50
	v_lshlrev_b32_e32 v47, 31, v58
	v_or_b32_e32 v50, 0x33000000, v47
	v_add_lshl_u32 v48, v48, v49, 23
	v_lshrrev_b32_e32 v44, 9, v44
	v_sub_u32_e32 v48, v50, v48
	v_or_b32_e32 v47, 0.5, v47
	v_lshlrev_b32_e32 v49, 23, v49
	v_or_b32_e32 v44, v48, v44
	v_lshrrev_b32_e32 v48, 9, v51
	v_sub_u32_e32 v47, v47, v49
	v_or_b32_e32 v47, v48, v47
	v_mul_f32_e32 v48, 0x3fc90fda, v47
	v_fma_f32 v49, v47, s38, -v48
	v_fmac_f32_e32 v49, 0x33a22168, v47
	v_fmac_f32_e32 v49, 0x3fc90fda, v44
	v_lshrrev_b32_e32 v43, 30, v43
	v_add_f32_e32 v44, v48, v49
	v_add_u32_e32 v43, v59, v43

.LBB0_95:
	global_load_dword v25, v[0:1], off offset:1024 sc1
	global_load_dword v10, v[0:1], off offset:1280 sc1
	global_load_dword v11, v[0:1], off offset:1536 sc1
	global_load_dword v12, v[0:1], off offset:1792 sc1
	global_load_dword v13, v[0:1], off offset:2048 sc1
	global_load_dword v14, v[0:1], off offset:2304 sc1
	global_load_dword v15, v[0:1], off offset:2560 sc1
	global_load_dword v16, v[0:1], off offset:2816 sc1
	global_load_dword v17, v[0:1], off offset:3072 sc1
	global_load_dword v18, v[0:1], off offset:3328 sc1
	global_load_dword v19, v[0:1], off offset:3584 sc1
	global_load_dword v20, v[0:1], off offset:3840 sc1
	global_load_dword v21, v[2:3], off sc1
	global_load_dword v22, v[4:5], off sc1
	global_load_dword v23, v[6:7], off sc1
	global_load_dword v24, v[8:9], off sc1
	s_or_b64 s[10:11], s[10:11], exec
	s_or_b64 s[8:9], s[8:9], exec
	s_waitcnt vmcnt(0) lgkmcnt(0)
	v_add_u32_e32 v26, v10, v25
	v_add_u32_e32 v26, v26, v11
	v_add_u32_e32 v26, v26, v12
	v_add_u32_e32 v26, v26, v13
	v_add_u32_e32 v26, v26, v14
	v_add_u32_e32 v26, v26, v15
	v_add_u32_e32 v26, v26, v16
	v_add_u32_e32 v26, v26, v17
	v_add_u32_e32 v26, v26, v18
	v_add_u32_e32 v26, v26, v19
	v_add_u32_e32 v26, v26, v20
	v_add_u32_e32 v26, v26, v21
	v_add_u32_e32 v26, v26, v22
	v_add_u32_e32 v26, v26, v23
	v_add_u32_e32 v26, v26, v24
	v_cmp_ne_u32_e32 vcc, s3, v26
	s_and_saveexec_b64 s[12:13], vcc
	s_cbranch_execz .LBB0_94
	s_and_b32 s16, s22, 0xff
	s_mov_b64 s[14:15], -1
	s_cmp_eq_u32 s16, 0
	s_mov_b64 s[18:19], -1
	s_mov_b64 s[16:17], -1
	s_sleep 1
	s_cbranch_scc1 .LBB0_98
	s_and_saveexec_b64 s[20:21], s[18:19]
	s_cbranch_execz .LBB0_93
	s_branch .LBB0_101
.LBB0_98:
	global_load_dword v26, v[0:1], off offset:512 sc1
	s_mov_b64 s[18:19], 0
	s_waitcnt vmcnt(0) lgkmcnt(0)
	v_cmp_eq_u32_e32 vcc, 0, v26
	s_and_saveexec_b64 s[20:21], vcc
	s_cmp_lt_u32 s22, 0x400001
	s_cselect_b64 s[18:19], -1, 0
	s_xor_b64 s[16:17], exec, -1
	s_and_b64 s[18:19], s[18:19], exec
	s_or_b64 exec, exec, s[20:21]
	s_and_saveexec_b64 s[20:21], s[18:19]
	s_cbranch_execz .LBB0_93

.LBB0_105:
	s_lshl_b32 s4, s33, 6
	s_lshl_b32 s3, s33, 8
	s_add_u32 s28, s56, s3
	s_addc_u32 s3, s57, 0
	v_mov_b32_e32 v1, s28
	v_add_co_u32_e32 v4, vcc, 0x1000, v1
	v_mov_b32_e32 v1, s3
	s_nop 0
	v_addc_co_u32_e32 v5, vcc, 0, v1, vcc
	v_mov_b32_e32 v1, 1
	flat_atomic_add v1, v[4:5], v1 offset:1024 sc0
	v_cvt_f32_u32_e32 v3, v2
	v_sub_u32_e32 v4, 0, v2
	s_mov_b32 s5, 0
	v_rcp_iflag_f32_e32 v3, v3
	s_nop 0
	v_mul_f32_e32 v3, 0x4f7ffffe, v3
	v_cvt_u32_f32_e32 v3, v3
	v_mul_lo_u32 v4, v4, v3
	v_mul_hi_u32 v4, v3, v4
	v_add_u32_e32 v3, v3, v4
	s_waitcnt vmcnt(0) lgkmcnt(0)
	v_mul_hi_u32 v3, v1, v3
	v_mul_lo_u32 v5, v3, v2
	v_add_u32_e32 v4, 1, v1
	v_sub_u32_e32 v1, v1, v5
	v_add_u32_e32 v6, 1, v3
	v_cmp_ge_u32_e32 vcc, v1, v2
	v_sub_u32_e32 v5, v1, v2
	s_nop 0
	v_cndmask_b32_e32 v3, v3, v6, vcc
	v_cndmask_b32_e32 v1, v1, v5, vcc
	v_add_u32_e32 v5, 1, v3
	v_cmp_ge_u32_e32 vcc, v1, v2
	s_nop 1
	v_cndmask_b32_e32 v1, v3, v5, vcc
	v_mad_u64_u32 v[2:3], s[6:7], v2, v1, v[2:3]
	v_cmp_ne_u32_e32 vcc, v4, v2
	s_and_saveexec_b64 s[6:7], vcc
	s_xor_b64 s[6:7], exec, s[6:7]
	s_cbranch_execz .LBB0_118
	v_mov_b32_e32 v0, s28
	v_add_co_u32_e32 v2, vcc, 0x2000, v0
	v_mov_b32_e32 v0, s3
	s_nop 0
	v_addc_co_u32_e32 v3, vcc, 0, v0, vcc
	global_load_dword v0, v[2:3], off offset:1024 sc1
	s_add_u32 s10, s28, 0x2400
	s_addc_u32 s11, s3, 0
	s_waitcnt vmcnt(0) lgkmcnt(0)
	v_cmp_eq_u32_e32 vcc, v0, v1
	s_and_saveexec_b64 s[8:9], vcc
	s_cbranch_execz .LBB0_117
	s_mov_b32 s26, 1
	s_mov_b64 s[12:13], 0
	s_branch .LBB0_109

.LBB0_109:
	s_and_b32 s20, s26, 0xff
	s_mov_b64 s[18:19], -1
	s_cmp_lg_u32 s20, 0
	s_mov_b64 s[20:21], -1
	s_sleep 1
	s_cbranch_scc1 .LBB0_113
	v_mov_b64_e32 v[2:3], s[56:57]
	global_load_dword v0, v[2:3], off offset:512 sc1
	s_mov_b64 s[20:21], 0
	s_mov_b64 s[22:23], -1
	s_waitcnt vmcnt(0) lgkmcnt(0)
	v_cmp_eq_u32_e32 vcc, 0, v0
	s_and_saveexec_b64 s[24:25], vcc
	s_cmp_lt_u32 s26, 0x400001
	s_cselect_b64 s[20:21], -1, 0
	s_xor_b64 s[22:23], exec, -1
	s_and_b64 s[20:21], s[20:21], exec
	s_or_b64 exec, exec, s[24:25]
.LBB0_113:
	s_andn2_b64 s[16:17], s[16:17], exec
	s_and_b64 s[22:23], s[22:23], exec
	s_or_b64 s[16:17], s[16:17], s[22:23]
	s_and_saveexec_b64 s[22:23], s[20:21]
	s_cbranch_execz .LBB0_108
	v_mov_b64_e32 v[2:3], s[10:11]
	global_load_dword v0, v[2:3], off sc1
	s_add_i32 s26, s26, 1
	s_or_b64 s[16:17], s[16:17], exec
	s_waitcnt vmcnt(0) lgkmcnt(0)
	v_cmp_ne_u32_e32 vcc, v0, v1
	s_orn2_b64 s[18:19], vcc, exec
	s_branch .LBB0_108

.LBB0_118:
	s_andn2_saveexec_b64 s[6:7], s[6:7]
	s_cbranch_execz .LBB0_134
	v_mov_b32_e32 v1, s56
	v_add_co_u32_e32 v2, vcc, 0x3000, v1
	v_mov_b32_e32 v1, s57
	buffer_wbl2 sc1
	s_waitcnt vmcnt(0)
	v_addc_co_u32_e32 v3, vcc, 0, v1, vcc
	v_mov_b32_e32 v1, 1
	flat_atomic_add v1, v[2:3], v1 offset:1024 sc0
	v_cvt_f32_u32_e32 v2, v0
	v_sub_u32_e32 v3, 0, v0
	s_add_u32 s8, s56, 0x3500
	s_addc_u32 s9, s57, 0
	v_rcp_iflag_f32_e32 v2, v2
	s_mov_b64 s[12:13], -1
	v_mul_f32_e32 v2, 0x4f7ffffe, v2
	v_cvt_u32_f32_e32 v2, v2
	v_mul_lo_u32 v3, v3, v2
	v_mul_hi_u32 v3, v2, v3
	v_add_u32_e32 v2, v2, v3
	s_waitcnt vmcnt(0) lgkmcnt(0)
	v_mul_hi_u32 v2, v1, v2
	v_mul_lo_u32 v4, v2, v0
	v_add_u32_e32 v3, 1, v1
	v_sub_u32_e32 v1, v1, v4
	v_add_u32_e32 v5, 1, v2
	v_cmp_ge_u32_e32 vcc, v1, v0
	v_sub_u32_e32 v4, v1, v0
	s_nop 0
	v_cndmask_b32_e32 v2, v2, v5, vcc
	v_cndmask_b32_e32 v1, v1, v4, vcc
	v_add_u32_e32 v4, 1, v2
	v_cmp_ge_u32_e32 vcc, v1, v0
	s_nop 1
	v_cndmask_b32_e32 v2, v2, v4, vcc
	v_mad_u64_u32 v[0:1], s[10:11], v0, v2, v[0:1]
	v_cmp_ne_u32_e32 vcc, v3, v0
	v_mov_b64_e32 v[0:1], s[8:9]
	s_and_saveexec_b64 s[10:11], vcc
	s_cbranch_execz .LBB0_131
	v_mov_b64_e32 v[0:1], s[8:9]
	global_load_dword v0, v[0:1], off sc1
	s_mov_b64 s[16:17], 0
	s_waitcnt vmcnt(0) lgkmcnt(0)
	v_cmp_eq_u32_e32 vcc, v0, v2
	s_and_saveexec_b64 s[14:15], vcc
	s_cbranch_execz .LBB0_130
	s_add_u32 s12, s56, 0x200
	s_addc_u32 s13, s57, 0
	s_mov_b32 s29, 1
	s_branch .LBB0_123

.LBB0_125:
	v_mov_b64_e32 v[0:1], s[12:13]
	global_load_dword v0, v[0:1], off sc1
	s_mov_b64 s[22:23], 0
	s_mov_b64 s[20:21], -1
	s_waitcnt vmcnt(0) lgkmcnt(0)
	v_cmp_eq_u32_e32 vcc, 0, v0
	s_and_saveexec_b64 s[24:25], vcc
	s_cmp_lt_u32 s29, 0x400001
	s_cselect_b64 s[22:23], -1, 0
	s_xor_b64 s[20:21], exec, -1
	s_and_b64 s[22:23], s[22:23], exec
	s_or_b64 exec, exec, s[24:25]
	s_mov_b64 s[24:25], -1
	s_and_saveexec_b64 s[26:27], s[22:23]
	s_cbranch_execz .LBB0_122
.LBB0_128:
	v_mov_b64_e32 v[0:1], s[8:9]
	global_load_dword v0, v[0:1], off sc1
	s_add_i32 s29, s29, 1
	s_or_b64 s[20:21], s[20:21], exec
	s_waitcnt vmcnt(0) lgkmcnt(0)
	v_cmp_ne_u32_e32 vcc, v0, v2
	s_orn2_b64 s[24:25], vcc, exec
	s_branch .LBB0_122

.LBB0_166:
	v_mov_b32_e32 v3, v204
	v_mov_b32_e32 v0, s59
	ds_read_b64 v[8:9], v0
	s_and_b32 s8, s20, 3
	v_mov_b32_e32 v0, s45
	v_ashrrev_i32_e32 v17, 3, v3
	ds_read2_b64 v[4:7], v0 offset1:1
	s_waitcnt lgkmcnt(0)
	v_readfirstlane_b32 s26, v8
	v_readfirstlane_b32 s23, v9
	s_add_u32 s6, s26, 0xe000000
	s_addc_u32 s7, s23, 0
	v_add_u32_e32 v0, s9, v17
	v_mov_b64_e32 v[8:9], s[6:7]
	v_mad_i64_i32 v[10:11], s[28:29], v0, s94, v[8:9]
	v_lshlrev_b32_e32 v0, 3, v3
	v_and_b32_e32 v0, 56, v0
	v_lshl_add_u64 v[10:11], v[10:11], 0, v[0:1]
	v_add_co_u32_e32 v10, vcc, s91, v10
	v_add_u32_e32 v13, 0x400, v3
	s_nop 0
	v_addc_co_u32_e32 v11, vcc, 0, v11, vcc
	global_load_dwordx2 v[52:53], v[10:11], off offset:512
	v_add_u32_e32 v10, 0x200, v3
	v_add_u32_e32 v14, 0x600, v3
	v_ashrrev_i32_e32 v0, 6, v3
	v_lshrrev_b32_e32 v11, 6, v10
	v_ashrrev_i32_e32 v10, 6, v10
	v_ashrrev_i32_e32 v13, 6, v13
	v_lshrrev_b32_e32 v15, 6, v14
	v_ashrrev_i32_e32 v14, 6, v14
	v_and_b32_e32 v0, -16, v0
	v_and_b32_e32 v10, -16, v10
	v_and_b32_e32 v13, -16, v13
	v_and_b32_e32 v14, -16, v14
	v_bfe_u32 v12, v3, 6, 4
	v_add_u32_e32 v0, s21, v0
	v_add_u32_e32 v10, s21, v10
	v_add_u32_e32 v13, s21, v13
	v_add_u32_e32 v14, s21, v14
	v_readfirstlane_b32 s28, v4
	v_or_b32_e32 v4, v0, v12
	v_and_or_b32 v10, v11, 15, v10
	v_or_b32_e32 v12, v13, v12
	v_and_or_b32 v14, v15, 15, v14
	v_readfirstlane_b32 s29, v5
	v_ashrrev_i32_e32 v5, 31, v4
	v_ashrrev_i32_e32 v11, 31, v10
	v_ashrrev_i32_e32 v13, 31, v12
	v_ashrrev_i32_e32 v15, 31, v14
	v_lshlrev_b64 v[4:5], 10, v[4:5]
	v_lshlrev_b64 v[10:11], 10, v[10:11]
	v_lshlrev_b64 v[12:13], 10, v[12:13]
	v_lshlrev_b64 v[14:15], 10, v[14:15]
	v_and_b32_e32 v16, 63, v3
	s_lshl_b32 s27, s8, 6
	v_lshl_add_u64 v[4:5], s[28:29], 0, v[4:5]
	s_lshl_b32 s78, s8, 8
	v_lshl_add_u64 v[10:11], s[28:29], 0, v[10:11]
	v_lshl_add_u64 v[12:13], s[28:29], 0, v[12:13]
	v_lshl_add_u64 v[14:15], s[28:29], 0, v[14:15]
	v_lshl_add_u64 v[4:5], v[4:5], 0, s[78:79]
	v_lshlrev_b32_e32 v0, 2, v16
	v_lshl_add_u64 v[10:11], v[10:11], 0, s[78:79]
	v_lshl_add_u64 v[12:13], v[12:13], 0, s[78:79]
	v_lshl_add_u64 v[14:15], v[14:15], 0, s[78:79]
	v_readfirstlane_b32 s28, v3
	s_or_b32 s27, s27, s84
	v_lshl_add_u64 v[4:5], v[4:5], 0, v[0:1]
	v_lshl_add_u64 v[10:11], v[10:11], 0, v[0:1]
	v_lshl_add_u64 v[12:13], v[12:13], 0, v[0:1]
	v_lshl_add_u64 v[14:15], v[14:15], 0, v[0:1]
	v_or_b32_e32 v0, s27, v16
	s_ashr_i32 s27, s28, 3
	s_and_b32 s27, s27, -8
	v_readfirstlane_b32 s29, v7
	v_readfirstlane_b32 s35, v6
	s_add_i32 s27, s27, s9
	s_lshl_b32 s28, s8, 7
	global_load_dword v59, v[4:5], off
	global_load_dword v58, v[10:11], off
	global_load_dword v57, v[12:13], off
	global_load_dword v56, v[14:15], off
	v_mov_b32_e32 v4, s35
	v_mov_b32_e32 v5, s29
	s_add_u32 s6, s6, s28
	v_lshl_add_u64 v[4:5], v[0:1], 2, v[4:5]
	s_addc_u32 s7, s7, 0
	v_lshlrev_b32_e32 v0, 1, v16
	global_load_dword v127, v[4:5], off
	global_load_dword v125, v[4:5], off offset:1024
	v_lshl_add_u64 v[4:5], s[6:7], 0, v[0:1]
	v_mad_i64_i32 v[6:7], s[6:7], s27, v216, v[4:5]
	s_add_i32 s6, s27, 1
	s_nop 0
	v_mad_i64_i32 v[10:11], s[6:7], s6, v216, v[4:5]
	s_add_i32 s6, s27, 2
	s_nop 0
	v_mad_i64_i32 v[12:13], s[6:7], s6, v216, v[4:5]
	s_add_i32 s6, s27, 3
	s_nop 0
	v_mad_i64_i32 v[14:15], s[6:7], s6, v216, v[4:5]
	s_add_i32 s6, s27, 4
	global_load_ushort v89, v[6:7], off offset:512
	global_load_ushort v87, v[10:11], off offset:512
	global_load_ushort v84, v[12:13], off offset:512
	global_load_ushort v83, v[14:15], off offset:512
	global_load_ushort v55, v[14:15], off
	global_load_ushort v78, v[12:13], off
	global_load_ushort v79, v[10:11], off
	global_load_ushort v81, v[6:7], off
	v_mad_i64_i32 v[6:7], s[6:7], s6, v216, v[4:5]
	s_add_i32 s6, s27, 5
	s_nop 0
	v_mad_i64_i32 v[10:11], s[6:7], s6, v216, v[4:5]
	s_add_i32 s6, s27, 6
	v_and_b32_e32 v0, 0x7f, v3
	v_and_b32_e32 v3, -16, v17
	v_mad_i64_i32 v[12:13], s[6:7], s6, v216, v[4:5]
	s_add_i32 s27, s27, 7
	v_add_u32_e32 v3, s9, v3
	v_mad_i64_i32 v[4:5], s[6:7], s27, v216, v[4:5]
	global_load_ushort v91, v[6:7], off offset:512
	global_load_ushort v90, v[10:11], off offset:512
	global_load_ushort v88, v[12:13], off offset:512
	global_load_ushort v86, v[4:5], off offset:512
	global_load_ushort v54, v[4:5], off
	global_load_ushort v80, v[12:13], off
	global_load_ushort v82, v[10:11], off
	global_load_ushort v85, v[6:7], off
	v_add_u32_e32 v6, 1, v3
	v_add_u32_e32 v10, 2, v3
	v_add_u32_e32 v12, 3, v3
	v_add_u32_e32 v14, 4, v3
	v_add_u32_e32 v16, 5, v3
	v_add_u32_e32 v18, 6, v3
	v_mad_i64_i32 v[4:5], s[6:7], v3, s94, v[8:9]
	v_mad_i64_i32 v[6:7], s[6:7], v6, s94, v[8:9]
	v_mad_i64_i32 v[10:11], s[6:7], v10, s94, v[8:9]
	v_mad_i64_i32 v[12:13], s[6:7], v12, s94, v[8:9]
	v_mad_i64_i32 v[14:15], s[6:7], v14, s94, v[8:9]
	v_mad_i64_i32 v[16:17], s[6:7], v16, s94, v[8:9]
	v_mad_i64_i32 v[18:19], s[6:7], v18, s94, v[8:9]
	v_add_u32_e32 v20, 7, v3
	v_lshl_add_u64 v[4:5], v[4:5], 0, s[78:79]
	v_lshlrev_b32_e32 v0, 1, v0
	v_lshl_add_u64 v[6:7], v[6:7], 0, s[78:79]
	v_lshl_add_u64 v[10:11], v[10:11], 0, s[78:79]
	v_lshl_add_u64 v[12:13], v[12:13], 0, s[78:79]
	v_lshl_add_u64 v[14:15], v[14:15], 0, s[78:79]
	v_lshl_add_u64 v[16:17], v[16:17], 0, s[78:79]
	v_lshl_add_u64 v[18:19], v[18:19], 0, s[78:79]
	v_mad_i64_i32 v[20:21], s[6:7], v20, s94, v[8:9]
	v_lshl_add_u64 v[4:5], v[4:5], 0, v[0:1]
	v_lshl_add_u64 v[6:7], v[6:7], 0, v[0:1]
	v_lshl_add_u64 v[10:11], v[10:11], 0, v[0:1]
	v_lshl_add_u64 v[12:13], v[12:13], 0, v[0:1]
	v_lshl_add_u64 v[14:15], v[14:15], 0, v[0:1]
	v_lshl_add_u64 v[16:17], v[16:17], 0, v[0:1]
	v_lshl_add_u64 v[18:19], v[18:19], 0, v[0:1]
	v_lshl_add_u64 v[20:21], v[20:21], 0, s[78:79]
	v_lshl_add_u64 v[20:21], v[20:21], 0, v[0:1]
	global_load_ushort v30, v[4:5], off offset:1024
	global_load_ushort v31, v[6:7], off offset:1024
	global_load_ushort v32, v[10:11], off offset:1024
	global_load_ushort v33, v[12:13], off offset:1024
	global_load_ushort v34, v[14:15], off offset:1024
	global_load_ushort v35, v[16:17], off offset:1024
	global_load_ushort v36, v[18:19], off offset:1024
	global_load_ushort v37, v[20:21], off offset:1024
	v_add_u32_e32 v4, 8, v3
	v_add_u32_e32 v6, 9, v3
	v_add_u32_e32 v10, 10, v3
	v_add_u32_e32 v12, 11, v3
	v_add_u32_e32 v14, 12, v3
	v_add_u32_e32 v16, 13, v3
	v_add_u32_e32 v18, 14, v3
	v_add_u32_e32 v3, 15, v3
	v_mad_i64_i32 v[4:5], s[6:7], v4, s94, v[8:9]
	v_mad_i64_i32 v[6:7], s[6:7], v6, s94, v[8:9]
	v_mad_i64_i32 v[10:11], s[6:7], v10, s94, v[8:9]
	v_mad_i64_i32 v[12:13], s[6:7], v12, s94, v[8:9]
	v_mad_i64_i32 v[14:15], s[6:7], v14, s94, v[8:9]
	v_mad_i64_i32 v[16:17], s[6:7], v16, s94, v[8:9]
	v_mad_i64_i32 v[18:19], s[6:7], v18, s94, v[8:9]
	v_mad_i64_i32 v[8:9], s[6:7], v3, s94, v[8:9]
	s_lshl_b32 s6, s11, 3
	s_lshl_b32 s7, s8, 1
	s_or_b32 s6, s6, s7
	s_mul_hi_i32 s7, s6, 0x44
	s_mulk_i32 s6, 0x44
	s_ashr_i32 s11, s22, 31
	s_add_u32 s6, s6, s22
	s_addc_u32 s7, s7, s11
	s_lshl_b64 s[6:7], s[6:7], 14
	s_add_u32 s6, s26, s6
	s_addc_u32 s7, s23, s7
	s_ashr_i32 s11, s10, 2
	v_bfe_u32 v22, v2, 4, 2
	v_and_b32_e32 v24, 15, v2
	v_bfi_b32 v2, -16, s11, v2
	v_lshl_add_u64 v[4:5], v[4:5], 0, s[78:79]
	v_ashrrev_i32_e32 v3, 31, v2
	v_lshl_add_u64 v[4:5], v[4:5], 0, v[0:1]
	v_lshl_add_u64 v[6:7], v[6:7], 0, s[78:79]
	v_lshl_add_u64 v[10:11], v[10:11], 0, s[78:79]
	v_lshl_add_u64 v[12:13], v[12:13], 0, s[78:79]
	v_lshl_add_u64 v[14:15], v[14:15], 0, s[78:79]
	v_lshl_add_u64 v[16:17], v[16:17], 0, s[78:79]
	v_lshl_add_u64 v[18:19], v[18:19], 0, s[78:79]
	v_lshl_add_u64 v[8:9], v[8:9], 0, s[78:79]
	v_lshlrev_b64 v[2:3], 7, v[2:3]
	v_lshl_add_u64 v[6:7], v[6:7], 0, v[0:1]
	v_lshl_add_u64 v[10:11], v[10:11], 0, v[0:1]
	v_lshl_add_u64 v[12:13], v[12:13], 0, v[0:1]
	v_lshl_add_u64 v[14:15], v[14:15], 0, v[0:1]
	v_lshl_add_u64 v[16:17], v[16:17], 0, v[0:1]
	v_lshl_add_u64 v[18:19], v[18:19], 0, v[0:1]
	v_lshl_add_u64 v[8:9], v[8:9], 0, v[0:1]
	global_load_ushort v38, v[4:5], off offset:1024
	global_load_ushort v39, v[6:7], off offset:1024
	global_load_ushort v40, v[10:11], off offset:1024
	global_load_ushort v41, v[12:13], off offset:1024
	global_load_ushort v42, v[14:15], off offset:1024
	global_load_ushort v43, v[16:17], off offset:1024
	global_load_ushort v44, v[18:19], off offset:1024
	global_load_ushort v45, v[8:9], off offset:1024
	v_lshl_add_u64 v[2:3], s[6:7], 0, v[2:3]
	v_lshlrev_b32_e32 v4, 4, v22
	v_mov_b32_e32 v5, v1
	v_lshl_add_u64 v[2:3], v[2:3], 0, v[4:5]
	s_mov_b64 s[6:7], 0x18c00000
	v_lshl_add_u64 v[6:7], v[2:3], 0, s[6:7]
	s_mov_b32 s6, 0x18c00000
	v_add_co_u32_e32 v8, vcc, s6, v2
	s_mov_b64 s[6:7], 0x18d10000
	s_nop 0
	v_addc_co_u32_e32 v9, vcc, 0, v3, vcc
	global_load_dwordx4 v[8:11], v[8:9], off
	s_nop 0
	global_load_dwordx4 v[12:15], v[6:7], off offset:64
	v_lshl_add_u64 v[6:7], v[2:3], 0, s[6:7]
	s_mov_b32 s6, 0x18d10000
	v_add_co_u32_e32 v2, vcc, s6, v2
	v_lshlrev_b32_e32 v0, 3, v22
	s_nop 0
	v_addc_co_u32_e32 v3, vcc, 0, v3, vcc
	global_load_dwordx4 v[16:19], v[2:3], off
	global_load_dwordx4 v[20:23], v[6:7], off offset:64
	v_add_u32_e32 v28, s9, v24
	v_mov_b64_e32 v[2:3], s[4:5]
	s_and_b32 s10, s11, -16
	v_mad_i64_i32 v[6:7], s[4:5], v28, s94, v[2:3]
	v_add_u32_e32 v24, 16, v28
	v_add_u32_e32 v26, 32, v28
	v_add_u32_e32 v28, 48, v28
	s_ashr_i32 s11, s10, 31
	v_mad_i64_i32 v[24:25], s[6:7], v24, s94, v[2:3]
	v_mad_i64_i32 v[26:27], s[6:7], v26, s94, v[2:3]
	v_mad_i64_i32 v[2:3], s[6:7], v28, s94, v[2:3]
	v_lshl_add_u64 v[6:7], v[6:7], 0, s[78:79]
	s_lshl_b64 s[4:5], s[10:11], 1
	v_lshl_add_u64 v[24:25], v[24:25], 0, s[78:79]
	v_lshl_add_u64 v[26:27], v[26:27], 0, s[78:79]
	v_lshl_add_u64 v[2:3], v[2:3], 0, s[78:79]
	v_lshl_add_u64 v[6:7], v[6:7], 0, s[4:5]
	v_lshl_add_u64 v[24:25], v[24:25], 0, s[4:5]
	v_lshl_add_u64 v[26:27], v[26:27], 0, s[4:5]
	v_lshl_add_u64 v[2:3], v[2:3], 0, s[4:5]
	v_readlane_b32 s4, v245, 46
	v_lshl_add_u64 v[6:7], v[6:7], 0, v[0:1]
	v_lshl_add_u64 v[24:25], v[24:25], 0, v[0:1]
	v_lshl_add_u64 v[26:27], v[26:27], 0, v[0:1]
	v_lshl_add_u64 v[2:3], v[2:3], 0, v[0:1]
	v_mov_b32_e32 v0, s4
	ds_read_b64 v[28:29], v0
	s_mov_b32 s9, 0xe000000
	v_add_co_u32_e32 v6, vcc, s9, v6
	s_lshl_b64 s[4:5], s[84:85], 2
	s_nop 0
	v_addc_co_u32_e32 v7, vcc, 0, v7, vcc
	s_waitcnt lgkmcnt(0)
	v_readfirstlane_b32 s7, v28
	v_add_co_u32_e32 v24, vcc, s9, v24
	v_readfirstlane_b32 s6, v29
	s_add_u32 s4, s7, s4
	v_addc_co_u32_e32 v25, vcc, 0, v25, vcc
	s_addc_u32 s5, s6, s5
	s_lshl_b32 s6, s8, 9
	v_add_co_u32_e32 v26, vcc, s9, v26
	s_add_u32 s6, s4, s6
	s_nop 0
	v_addc_co_u32_e32 v27, vcc, 0, v27, vcc
	s_addc_u32 s7, s5, 0
	s_lshl_b64 s[4:5], s[10:11], 2
	v_add_co_u32_e32 v2, vcc, s9, v2
	s_add_u32 s4, s6, s4
	s_nop 0
	v_addc_co_u32_e32 v3, vcc, 0, v3, vcc
	global_load_dwordx2 v[68:69], v[6:7], off offset:2048
	global_load_dwordx2 v[66:67], v[24:25], off offset:2048
	global_load_dwordx2 v[62:63], v[26:27], off offset:2048
	global_load_dwordx2 v[60:61], v[2:3], off offset:2048
	s_addc_u32 s5, s7, s5
	v_lshl_add_u64 v[2:3], s[4:5], 0, v[4:5]
	global_load_dwordx4 v[4:7], v[2:3], off
	s_waitcnt vmcnt(0)
	v_perm_b32 v48, v39, v38, s2
	v_perm_b32 v49, v41, v40, s2
	v_perm_b32 v50, v43, v42, s2
	v_perm_b32 v51, v45, v44, s2
	v_perm_b32 v44, v31, v30, s2
	v_perm_b32 v45, v33, v32, s2
	v_perm_b32 v46, v35, v34, s2
	v_perm_b32 v47, v37, v36, s2
	s_andn2_b64 vcc, exec, s[0:1]
	s_cbranch_vccz .LBB0_176
	s_branch .LBB0_262

.LBB0_177:
	s_or_b64 exec, exec, s[6:7]
	s_waitcnt lgkmcnt(0)
	v_lshl_add_u32 v16, v123, 2, 0
	s_barrier
	s_waitcnt vmcnt(0)
	ds_read_b32 v13, v16 offset:20480
	ds_read_b32 v14, v16 offset:20736
	ds_read_b32 v15, v16 offset:20992
	ds_read_b32 v17, v16 offset:21248
	ds_read_b32 v18, v16 offset:21504
	ds_read_b32 v19, v16 offset:21760
	ds_read_b32 v20, v16 offset:22016
	ds_read_b32 v21, v16 offset:22272
	s_waitcnt lgkmcnt(0)
	v_add_f32_e32 v13, 0, v13
	v_add_f32_e32 v13, v13, v14
	v_add_f32_e32 v13, v13, v15
	v_add_f32_e32 v13, v13, v17
	v_lshlrev_b32_e32 v14, 16, v68
	v_add_f32_e32 v13, v13, v18
	v_mul_f32_e32 v17, 0xbfb8aa3b, v14
	v_add_f32_e32 v13, v13, v19
	v_exp_f32_e32 v17, v17
	v_add_f32_e32 v13, v13, v20
	v_add_f32_e32 v13, v13, v21
	v_fmamk_f32 v13, v13, 0x3c000000, v210
	v_rsq_f32_e32 v13, v13
	v_and_b32_e32 v15, 0xffff0000, v68
	v_add_f32_e32 v17, 1.0, v17
	v_rcp_f32_e32 v17, v17
	v_mul_f32_e32 v21, 0xbfb8aa3b, v15
	v_exp_f32_e32 v21, v21
	v_mul_f32_e32 v20, v52, v13
	v_mul_f32_e32 v20, v4, v20
	v_mul_f32_e32 v14, v17, v14
	v_mul_f32_e32 v14, v14, v20
	v_add_f32_e32 v20, 1.0, v21
	v_rcp_f32_e32 v20, v20
	v_mul_f32_e32 v17, v53, v13
	v_lshlrev_b32_e32 v18, 16, v69
	v_and_b32_e32 v19, 0xffff0000, v69
	v_mul_f32_e32 v17, v5, v17
	v_mul_f32_e32 v15, v20, v15
	v_mul_f32_e32 v21, 0xbfb8aa3b, v18
	v_mul_f32_e32 v15, v15, v17
	v_mul_f32_e32 v17, 0xbfb8aa3b, v19
	v_exp_f32_e32 v21, v21
	v_exp_f32_e32 v17, v17
	v_cvt_pk_bf16_f32 v14, v14, v15
	s_and_b32 s6, s22, 0x180
	v_add_f32_e32 v15, 1.0, v21
	v_add_f32_e32 v17, 1.0, v17
	v_rcp_f32_e32 v15, v15
	v_rcp_f32_e32 v17, v17
	v_mul_f32_e32 v20, v54, v13
	v_mul_f32_e32 v13, v55, v13
	s_add_i32 s8, s8, s6
	v_mul_f32_e32 v20, v6, v20
	v_mul_f32_e32 v15, v15, v18
	v_mul_f32_e32 v13, v7, v13
	v_mul_f32_e32 v17, v17, v19
	v_add_u32_e32 v12, s26, v123
	v_or_b32_e32 v2, s8, v2
	v_mul_f32_e32 v15, v15, v20
	v_mul_f32_e32 v13, v17, v13
	v_ashrrev_i32_e32 v3, 31, v2
	v_cvt_pk_bf16_f32 v15, v15, v13
	v_ashrrev_i32_e32 v13, 31, v12
	v_lshl_add_u64 v[2:3], v[2:3], 1, s[4:5]
	v_lshlrev_b64 v[12:13], 11, v[12:13]
	v_lshl_add_u64 v[2:3], v[2:3], 0, v[12:13]
	v_add_co_u32_e32 v12, vcc, s88, v2
	s_mov_b32 s4, 0x8808000
	s_nop 0
	v_addc_co_u32_e32 v13, vcc, 0, v3, vcc
	global_store_dwordx2 v[12:13], v[14:15], off
	ds_read_b32 v12, v16 offset:20544
	ds_read_b32 v13, v16 offset:20800
	ds_read_b32 v14, v16 offset:21056
	ds_read_b32 v15, v16 offset:21312
	ds_read_b32 v17, v16 offset:21568
	ds_read_b32 v18, v16 offset:21824
	ds_read_b32 v19, v16 offset:22080
	ds_read_b32 v20, v16 offset:22336
	s_waitcnt lgkmcnt(0)
	v_add_f32_e32 v12, 0, v12
	v_add_f32_e32 v12, v12, v13
	v_add_f32_e32 v12, v12, v14
	v_add_f32_e32 v12, v12, v15
	v_add_f32_e32 v12, v12, v17
	v_add_f32_e32 v12, v12, v18
	v_add_f32_e32 v12, v12, v19
	v_add_f32_e32 v12, v12, v20
	v_fmamk_f32 v12, v12, 0x3c000000, v210
	v_rsq_f32_e32 v13, v12
	v_lshlrev_b32_e32 v12, 16, v66
	v_mul_f32_e32 v15, 0xbfb8aa3b, v12
	v_exp_f32_e32 v15, v15
	v_and_b32_e32 v14, 0xffff0000, v66
	v_mul_f32_e32 v20, 0xbfb8aa3b, v14
	v_exp_f32_e32 v20, v20
	v_add_f32_e32 v15, 1.0, v15
	v_rcp_f32_e32 v15, v15
	v_mul_f32_e32 v19, v48, v13
	v_mul_f32_e32 v19, v4, v19
	v_lshlrev_b32_e32 v17, 16, v67
	v_mul_f32_e32 v12, v15, v12
	v_mul_f32_e32 v12, v12, v19
	v_add_f32_e32 v19, 1.0, v20
	v_rcp_f32_e32 v19, v19
	v_mul_f32_e32 v15, v49, v13
	v_and_b32_e32 v18, 0xffff0000, v67
	v_mul_f32_e32 v15, v5, v15
	v_mul_f32_e32 v14, v19, v14
	v_mul_f32_e32 v20, 0xbfb8aa3b, v17
	v_mul_f32_e32 v14, v14, v15
	v_mul_f32_e32 v15, 0xbfb8aa3b, v18
	v_exp_f32_e32 v20, v20
	v_exp_f32_e32 v15, v15
	v_cvt_pk_bf16_f32 v12, v12, v14
	v_mul_f32_e32 v19, v50, v13
	v_add_f32_e32 v14, 1.0, v20
	v_add_f32_e32 v15, 1.0, v15
	v_rcp_f32_e32 v14, v14
	v_rcp_f32_e32 v15, v15
	v_mul_f32_e32 v13, v51, v13
	v_mul_f32_e32 v19, v6, v19
	v_mul_f32_e32 v14, v14, v17
	v_mul_f32_e32 v13, v7, v13
	v_mul_f32_e32 v15, v15, v18
	v_mul_f32_e32 v14, v14, v19
	v_mul_f32_e32 v13, v15, v13
	v_cvt_pk_bf16_f32 v13, v14, v13
	v_add_co_u32_e32 v14, vcc, s4, v2
	s_mov_b32 s4, 0x8810000
	s_nop 0
	v_addc_co_u32_e32 v15, vcc, 0, v3, vcc
	global_store_dwordx2 v[14:15], v[12:13], off
	ds_read_b32 v12, v16 offset:20608
	ds_read_b32 v13, v16 offset:20864
	ds_read_b32 v14, v16 offset:21120
	ds_read_b32 v15, v16 offset:21376
	ds_read_b32 v17, v16 offset:21632
	ds_read_b32 v18, v16 offset:21888
	ds_read_b32 v19, v16 offset:22144
	ds_read_b32 v20, v16 offset:22400
	s_waitcnt lgkmcnt(0)
	v_add_f32_e32 v12, 0, v12
	v_add_f32_e32 v12, v12, v13
	v_add_f32_e32 v12, v12, v14
	v_add_f32_e32 v12, v12, v15
	v_add_f32_e32 v12, v12, v17
	v_add_f32_e32 v12, v12, v18
	v_add_f32_e32 v12, v12, v19
	v_add_f32_e32 v12, v12, v20
	v_fmamk_f32 v12, v12, 0x3c000000, v210
	v_rsq_f32_e32 v13, v12
	v_lshlrev_b32_e32 v12, 16, v62
	v_mul_f32_e32 v15, 0xbfb8aa3b, v12
	v_exp_f32_e32 v15, v15
	v_and_b32_e32 v14, 0xffff0000, v62
	v_mul_f32_e32 v20, 0xbfb8aa3b, v14
	v_exp_f32_e32 v20, v20
	v_add_f32_e32 v15, 1.0, v15
	v_rcp_f32_e32 v15, v15
	v_mul_f32_e32 v19, v44, v13
	v_mul_f32_e32 v19, v4, v19
	v_lshlrev_b32_e32 v17, 16, v63
	v_mul_f32_e32 v12, v15, v12
	v_mul_f32_e32 v12, v12, v19
	v_add_f32_e32 v19, 1.0, v20
	v_rcp_f32_e32 v19, v19
	v_mul_f32_e32 v15, v45, v13
	v_and_b32_e32 v18, 0xffff0000, v63
	v_mul_f32_e32 v15, v5, v15
	v_mul_f32_e32 v14, v19, v14
	v_mul_f32_e32 v20, 0xbfb8aa3b, v17
	v_mul_f32_e32 v14, v14, v15
	v_mul_f32_e32 v15, 0xbfb8aa3b, v18
	v_exp_f32_e32 v20, v20
	v_exp_f32_e32 v15, v15
	v_cvt_pk_bf16_f32 v12, v12, v14
	v_mul_f32_e32 v19, v46, v13
	v_add_f32_e32 v14, 1.0, v20
	v_add_f32_e32 v15, 1.0, v15
	v_rcp_f32_e32 v14, v14
	v_rcp_f32_e32 v15, v15
	v_mul_f32_e32 v13, v47, v13
	v_mul_f32_e32 v19, v6, v19
	v_mul_f32_e32 v14, v14, v17
	v_mul_f32_e32 v13, v7, v13
	v_mul_f32_e32 v15, v15, v18
	v_mul_f32_e32 v14, v14, v19
	v_mul_f32_e32 v13, v15, v13
	v_cvt_pk_bf16_f32 v13, v14, v13
	v_add_co_u32_e32 v14, vcc, s4, v2
	s_mov_b32 s4, 0x8818000
	s_nop 0
	v_addc_co_u32_e32 v15, vcc, 0, v3, vcc
	global_store_dwordx2 v[14:15], v[12:13], off
	ds_read_b32 v12, v16 offset:20672
	ds_read_b32 v13, v16 offset:20928
	ds_read_b32 v14, v16 offset:21184
	ds_read_b32 v15, v16 offset:21440
	ds_read_b32 v17, v16 offset:21696
	ds_read_b32 v18, v16 offset:21952
	ds_read_b32 v19, v16 offset:22208
	ds_read_b32 v16, v16 offset:22464
	s_waitcnt lgkmcnt(0)
	v_add_f32_e32 v12, 0, v12
	v_add_f32_e32 v12, v12, v13
	v_add_f32_e32 v12, v12, v14
	v_add_f32_e32 v12, v12, v15
	v_add_f32_e32 v12, v12, v17
	v_add_f32_e32 v12, v12, v18
	v_add_f32_e32 v12, v12, v19
	v_add_f32_e32 v12, v12, v16
	v_fmamk_f32 v12, v12, 0x3c000000, v210
	v_rsq_f32_e32 v12, v12
	v_and_b32_e32 v14, 0xffff0000, v60
	v_lshlrev_b32_e32 v13, 16, v60
	v_mul_f32_e32 v15, 0xbfb8aa3b, v13
	v_mul_f32_e32 v8, v8, v12
	v_mul_f32_e32 v4, v4, v8
	v_mul_f32_e32 v8, 0xbfb8aa3b, v14
	v_exp_f32_e32 v8, v8
	v_exp_f32_e32 v15, v15
	v_lshlrev_b32_e32 v16, 16, v61
	v_mul_f32_e32 v9, v9, v12
	v_add_f32_e32 v8, 1.0, v8
	v_rcp_f32_e32 v8, v8
	v_add_f32_e32 v15, 1.0, v15
	v_rcp_f32_e32 v15, v15
	v_mul_f32_e32 v5, v5, v9
	v_mul_f32_e32 v9, 0xbfb8aa3b, v16
	v_and_b32_e32 v17, 0xffff0000, v61
	v_exp_f32_e32 v9, v9
	v_mul_f32_e32 v8, v8, v14
	v_mul_f32_e32 v5, v8, v5
	v_mul_f32_e32 v8, 0xbfb8aa3b, v17
	v_mul_f32_e32 v13, v15, v13
	v_exp_f32_e32 v8, v8
	v_mul_f32_e32 v4, v13, v4
	v_cvt_pk_bf16_f32 v4, v4, v5
	v_add_f32_e32 v5, 1.0, v9
	v_rcp_f32_e32 v5, v5
	v_add_f32_e32 v8, 1.0, v8
	v_rcp_f32_e32 v8, v8
	v_mul_f32_e32 v9, v10, v12
	v_mul_f32_e32 v6, v6, v9
	v_mul_f32_e32 v5, v5, v16
	v_mul_f32_e32 v5, v5, v6
	v_mul_f32_e32 v6, v11, v12
	v_mul_f32_e32 v6, v7, v6
	v_mul_f32_e32 v7, v8, v17
	v_mul_f32_e32 v6, v7, v6
	v_add_co_u32_e32 v2, vcc, s4, v2
	v_cvt_pk_bf16_f32 v5, v5, v6
	s_nop 0
	v_addc_co_u32_e32 v3, vcc, 0, v3, vcc
	global_store_dwordx2 v[2:3], v[4:5], off
	v_mov_b64_e32 v[8:9], v[24:25]
	v_mov_b64_e32 v[12:13], v[28:29]
	v_mov_b64_e32 v[16:17], v[32:33]
	v_mov_b64_e32 v[20:21], v[36:37]
	v_perm_b32 v120, v184, v183, s2
	v_perm_b32 v118, v190, v189, s2
	v_perm_b32 v0, v192, v191, s2
	v_perm_b32 v119, v194, v193, s2
	v_perm_b32 v121, v186, v185, s2
	v_perm_b32 v122, v188, v187, s2
	v_mov_b64_e32 v[4:5], v[40:41]
	v_perm_b32 v44, v120, v114, s2
	v_alignbit_b32 v45, v121, v120, 16
	v_alignbit_b32 v46, v122, v121, 16
	v_alignbit_b32 v47, v115, v122, 16
	v_perm_b32 v48, v118, v117, s2
	v_alignbit_b32 v49, v0, v118, 16
	v_alignbit_b32 v50, v119, v0, 16
	v_alignbit_b32 v51, v116, v119, 16
	s_add_i32 s22, s22, s33
	s_andn2_b64 vcc, exec, s[0:1]
	s_mov_b32 s8, s23
	v_mov_b64_e32 v[52:53], v[64:65]
	v_mov_b64_e32 v[10:11], v[26:27]
	v_mov_b64_e32 v[14:15], v[30:31]
	v_mov_b64_e32 v[18:19], v[34:35]
	v_mov_b64_e32 v[22:23], v[38:39]
	v_mov_b64_e32 v[68:69], v[70:71]
	v_mov_b64_e32 v[66:67], v[72:73]
	v_mov_b64_e32 v[62:63], v[74:75]
	v_mov_b64_e32 v[60:61], v[76:77]
	v_mov_b64_e32 v[6:7], v[42:43]
	v_mov_b32_e32 v54, v106
	v_mov_b32_e32 v80, v107
	v_mov_b32_e32 v82, v108
	v_mov_b32_e32 v85, v109
	v_mov_b32_e32 v55, v98
	v_mov_b32_e32 v78, v99
	v_mov_b32_e32 v79, v100
	v_mov_b32_e32 v81, v101
	v_mov_b32_e32 v86, v110
	v_mov_b32_e32 v88, v111
	v_mov_b32_e32 v90, v112
	v_mov_b32_e32 v91, v113
	v_mov_b32_e32 v83, v102
	v_mov_b32_e32 v84, v103
	v_mov_b32_e32 v87, v104
	v_mov_b32_e32 v89, v105
	v_mov_b32_e32 v125, v92
	v_mov_b32_e32 v127, v97
	v_mov_b32_e32 v56, v93
	v_mov_b32_e32 v57, v94
	v_mov_b32_e32 v58, v95
	v_mov_b32_e32 v59, v96
	s_cbranch_vccz .LBB0_262

.LBB0_183:
	v_mov_b32_e32 v3, v204
	v_mov_b32_e32 v0, s59
	ds_read_b64 v[28:29], v0
	s_and_b32 s9, s23, 3
	v_mov_b32_e32 v0, s45
	v_ashrrev_i32_e32 v37, 3, v3
	ds_read2_b64 v[24:27], v0 offset1:1
	s_waitcnt lgkmcnt(0)
	v_readfirstlane_b32 s29, v28
	v_readfirstlane_b32 s28, v29
	s_add_u32 s6, s29, 0xe000000
	s_addc_u32 s7, s28, 0
	v_add_u32_e32 v0, s10, v37
	v_mov_b64_e32 v[28:29], s[6:7]
	v_mad_i64_i32 v[30:31], s[36:37], v0, s94, v[28:29]
	v_lshlrev_b32_e32 v0, 3, v3
	v_and_b32_e32 v0, 56, v0
	v_lshl_add_u64 v[30:31], v[30:31], 0, v[0:1]
	v_add_co_u32_e32 v30, vcc, s91, v30
	v_add_u32_e32 v33, 0x400, v3
	s_nop 0
	v_addc_co_u32_e32 v31, vcc, 0, v31, vcc
	global_load_dwordx2 v[64:65], v[30:31], off offset:512
	v_add_u32_e32 v30, 0x200, v3
	v_add_u32_e32 v34, 0x600, v3
	v_ashrrev_i32_e32 v0, 6, v3
	v_lshrrev_b32_e32 v31, 6, v30
	v_ashrrev_i32_e32 v30, 6, v30
	v_ashrrev_i32_e32 v33, 6, v33
	v_lshrrev_b32_e32 v35, 6, v34
	v_ashrrev_i32_e32 v34, 6, v34
	v_and_b32_e32 v0, -16, v0
	v_and_b32_e32 v30, -16, v30
	v_and_b32_e32 v33, -16, v33
	v_and_b32_e32 v34, -16, v34
	v_bfe_u32 v32, v3, 6, 4
	v_add_u32_e32 v0, s21, v0
	v_add_u32_e32 v30, s21, v30
	v_add_u32_e32 v33, s21, v33
	v_add_u32_e32 v34, s21, v34
	v_readfirstlane_b32 s36, v24
	v_or_b32_e32 v24, v0, v32
	v_and_or_b32 v30, v31, 15, v30
	v_or_b32_e32 v32, v33, v32
	v_and_or_b32 v34, v35, 15, v34
	v_readfirstlane_b32 s37, v25
	v_ashrrev_i32_e32 v25, 31, v24
	v_ashrrev_i32_e32 v31, 31, v30
	v_ashrrev_i32_e32 v33, 31, v32
	v_ashrrev_i32_e32 v35, 31, v34
	v_lshlrev_b64 v[24:25], 10, v[24:25]
	v_lshlrev_b64 v[30:31], 10, v[30:31]
	v_lshlrev_b64 v[32:33], 10, v[32:33]
	v_lshlrev_b64 v[34:35], 10, v[34:35]
	v_and_b32_e32 v36, 63, v3
	s_lshl_b32 s35, s9, 6
	v_lshl_add_u64 v[24:25], s[36:37], 0, v[24:25]
	s_lshl_b32 s78, s9, 8
	v_lshl_add_u64 v[30:31], s[36:37], 0, v[30:31]
	v_lshl_add_u64 v[32:33], s[36:37], 0, v[32:33]
	v_lshl_add_u64 v[34:35], s[36:37], 0, v[34:35]
	v_lshl_add_u64 v[24:25], v[24:25], 0, s[78:79]
	v_lshlrev_b32_e32 v0, 2, v36
	v_lshl_add_u64 v[30:31], v[30:31], 0, s[78:79]
	v_lshl_add_u64 v[32:33], v[32:33], 0, s[78:79]
	v_lshl_add_u64 v[34:35], v[34:35], 0, s[78:79]
	v_readfirstlane_b32 s36, v3
	s_or_b32 s35, s35, s84
	v_lshl_add_u64 v[24:25], v[24:25], 0, v[0:1]
	v_lshl_add_u64 v[30:31], v[30:31], 0, v[0:1]
	v_lshl_add_u64 v[32:33], v[32:33], 0, v[0:1]
	v_lshl_add_u64 v[34:35], v[34:35], 0, v[0:1]
	v_or_b32_e32 v0, s35, v36
	s_ashr_i32 s35, s36, 3
	s_and_b32 s35, s35, -8
	v_readfirstlane_b32 s37, v27
	v_readfirstlane_b32 s38, v26
	s_add_i32 s35, s35, s10
	s_lshl_b32 s36, s9, 7
	global_load_dword v96, v[24:25], off
	global_load_dword v95, v[30:31], off
	global_load_dword v94, v[32:33], off
	global_load_dword v93, v[34:35], off
	v_mov_b32_e32 v24, s38
	v_mov_b32_e32 v25, s37
	s_add_u32 s6, s6, s36
	v_lshl_add_u64 v[24:25], v[0:1], 2, v[24:25]
	s_addc_u32 s7, s7, 0
	v_lshlrev_b32_e32 v0, 1, v36
	global_load_dword v97, v[24:25], off
	global_load_dword v92, v[24:25], off offset:1024
	v_lshl_add_u64 v[24:25], s[6:7], 0, v[0:1]
	v_mad_i64_i32 v[26:27], s[6:7], s35, v216, v[24:25]
	s_add_i32 s6, s35, 1
	s_nop 0
	v_mad_i64_i32 v[30:31], s[6:7], s6, v216, v[24:25]
	s_add_i32 s6, s35, 2
	s_nop 0
	v_mad_i64_i32 v[32:33], s[6:7], s6, v216, v[24:25]
	s_add_i32 s6, s35, 3
	s_nop 0
	v_mad_i64_i32 v[34:35], s[6:7], s6, v216, v[24:25]
	s_add_i32 s6, s35, 4
	global_load_ushort v105, v[26:27], off offset:512
	global_load_ushort v104, v[30:31], off offset:512
	global_load_ushort v103, v[32:33], off offset:512
	global_load_ushort v102, v[34:35], off offset:512
	global_load_ushort v98, v[34:35], off
	global_load_ushort v99, v[32:33], off
	global_load_ushort v100, v[30:31], off
	global_load_ushort v101, v[26:27], off
	v_mad_i64_i32 v[26:27], s[6:7], s6, v216, v[24:25]
	s_add_i32 s6, s35, 5
	s_nop 0
	v_mad_i64_i32 v[30:31], s[6:7], s6, v216, v[24:25]
	s_add_i32 s6, s35, 6
	v_and_b32_e32 v0, 0x7f, v3
	v_and_b32_e32 v3, -16, v37
	v_mad_i64_i32 v[32:33], s[6:7], s6, v216, v[24:25]
	s_add_i32 s35, s35, 7
	v_add_u32_e32 v3, s10, v3
	v_mad_i64_i32 v[24:25], s[6:7], s35, v216, v[24:25]
	global_load_ushort v113, v[26:27], off offset:512
	global_load_ushort v112, v[30:31], off offset:512
	global_load_ushort v111, v[32:33], off offset:512
	global_load_ushort v110, v[24:25], off offset:512
	global_load_ushort v106, v[24:25], off
	global_load_ushort v107, v[32:33], off
	global_load_ushort v108, v[30:31], off
	global_load_ushort v109, v[26:27], off
	v_add_u32_e32 v26, 1, v3
	v_add_u32_e32 v30, 2, v3
	v_add_u32_e32 v32, 3, v3
	v_add_u32_e32 v34, 4, v3
	v_add_u32_e32 v36, 5, v3
	v_add_u32_e32 v38, 6, v3
	v_mad_i64_i32 v[24:25], s[6:7], v3, s94, v[28:29]
	v_mad_i64_i32 v[26:27], s[6:7], v26, s94, v[28:29]
	v_mad_i64_i32 v[30:31], s[6:7], v30, s94, v[28:29]
	v_mad_i64_i32 v[32:33], s[6:7], v32, s94, v[28:29]
	v_mad_i64_i32 v[34:35], s[6:7], v34, s94, v[28:29]
	v_mad_i64_i32 v[36:37], s[6:7], v36, s94, v[28:29]
	v_mad_i64_i32 v[38:39], s[6:7], v38, s94, v[28:29]
	v_add_u32_e32 v40, 7, v3
	v_lshl_add_u64 v[24:25], v[24:25], 0, s[78:79]
	v_lshlrev_b32_e32 v0, 1, v0
	v_lshl_add_u64 v[26:27], v[26:27], 0, s[78:79]
	v_lshl_add_u64 v[30:31], v[30:31], 0, s[78:79]
	v_lshl_add_u64 v[32:33], v[32:33], 0, s[78:79]
	v_lshl_add_u64 v[34:35], v[34:35], 0, s[78:79]
	v_lshl_add_u64 v[36:37], v[36:37], 0, s[78:79]
	v_lshl_add_u64 v[38:39], v[38:39], 0, s[78:79]
	v_mad_i64_i32 v[40:41], s[6:7], v40, s94, v[28:29]
	v_lshl_add_u64 v[24:25], v[24:25], 0, v[0:1]
	v_lshl_add_u64 v[26:27], v[26:27], 0, v[0:1]
	v_lshl_add_u64 v[30:31], v[30:31], 0, v[0:1]
	v_lshl_add_u64 v[32:33], v[32:33], 0, v[0:1]
	v_lshl_add_u64 v[34:35], v[34:35], 0, v[0:1]
	v_lshl_add_u64 v[36:37], v[36:37], 0, v[0:1]
	v_lshl_add_u64 v[38:39], v[38:39], 0, v[0:1]
	v_lshl_add_u64 v[40:41], v[40:41], 0, s[78:79]
	v_lshl_add_u64 v[40:41], v[40:41], 0, v[0:1]
	global_load_ushort v114, v[24:25], off offset:1024
	global_load_ushort v183, v[26:27], off offset:1024
	global_load_ushort v184, v[30:31], off offset:1024
	global_load_ushort v185, v[32:33], off offset:1024
	global_load_ushort v186, v[34:35], off offset:1024
	global_load_ushort v187, v[36:37], off offset:1024
	global_load_ushort v188, v[38:39], off offset:1024
	global_load_ushort v115, v[40:41], off offset:1024
	v_add_u32_e32 v24, 8, v3
	v_add_u32_e32 v26, 9, v3
	v_add_u32_e32 v30, 10, v3
	v_add_u32_e32 v32, 11, v3
	v_add_u32_e32 v34, 12, v3
	v_add_u32_e32 v36, 13, v3
	v_add_u32_e32 v38, 14, v3
	v_add_u32_e32 v3, 15, v3
	v_mad_i64_i32 v[24:25], s[6:7], v24, s94, v[28:29]
	v_mad_i64_i32 v[26:27], s[6:7], v26, s94, v[28:29]
	v_mad_i64_i32 v[30:31], s[6:7], v30, s94, v[28:29]
	v_mad_i64_i32 v[32:33], s[6:7], v32, s94, v[28:29]
	v_mad_i64_i32 v[34:35], s[6:7], v34, s94, v[28:29]
	v_mad_i64_i32 v[36:37], s[6:7], v36, s94, v[28:29]
	v_mad_i64_i32 v[38:39], s[6:7], v38, s94, v[28:29]
	v_mad_i64_i32 v[28:29], s[6:7], v3, s94, v[28:29]
	s_lshl_b32 s6, s26, 3
	s_lshl_b32 s7, s9, 1
	s_or_b32 s6, s6, s7
	s_mul_hi_i32 s7, s6, 0x44
	s_mulk_i32 s6, 0x44
	s_ashr_i32 s26, s27, 31
	s_add_u32 s6, s6, s27
	s_addc_u32 s7, s7, s26
	s_lshl_b64 s[6:7], s[6:7], 14
	s_add_u32 s6, s29, s6
	s_addc_u32 s7, s28, s7
	s_ashr_i32 s11, s11, 2
	v_bfe_u32 v42, v2, 4, 2
	v_and_b32_e32 v43, 15, v2
	v_bfi_b32 v2, -16, s11, v2
	v_ashrrev_i32_e32 v3, 31, v2
	v_lshlrev_b64 v[2:3], 7, v[2:3]
	v_lshl_add_u64 v[24:25], v[24:25], 0, s[78:79]
	v_lshl_add_u64 v[28:29], v[28:29], 0, s[78:79]
	v_lshl_add_u64 v[2:3], s[6:7], 0, v[2:3]
	v_lshlrev_b32_e32 v40, 4, v42
	v_mov_b32_e32 v41, v1
	v_lshl_add_u64 v[24:25], v[24:25], 0, v[0:1]
	v_lshl_add_u64 v[26:27], v[26:27], 0, s[78:79]
	v_lshl_add_u64 v[30:31], v[30:31], 0, s[78:79]
	v_lshl_add_u64 v[32:33], v[32:33], 0, s[78:79]
	v_lshl_add_u64 v[34:35], v[34:35], 0, s[78:79]
	v_lshl_add_u64 v[36:37], v[36:37], 0, s[78:79]
	v_lshl_add_u64 v[38:39], v[38:39], 0, s[78:79]
	v_lshl_add_u64 v[28:29], v[28:29], 0, v[0:1]
	v_lshl_add_u64 v[2:3], v[2:3], 0, v[40:41]
	s_mov_b64 s[6:7], 0x18c00000
	v_lshl_add_u64 v[26:27], v[26:27], 0, v[0:1]
	v_lshl_add_u64 v[30:31], v[30:31], 0, v[0:1]
	v_lshl_add_u64 v[32:33], v[32:33], 0, v[0:1]
	v_lshl_add_u64 v[34:35], v[34:35], 0, v[0:1]
	v_lshl_add_u64 v[36:37], v[36:37], 0, v[0:1]
	v_lshl_add_u64 v[38:39], v[38:39], 0, v[0:1]
	global_load_ushort v117, v[24:25], off offset:1024
	global_load_ushort v189, v[26:27], off offset:1024
	global_load_ushort v190, v[30:31], off offset:1024
	global_load_ushort v191, v[32:33], off offset:1024
	global_load_ushort v192, v[34:35], off offset:1024
	global_load_ushort v193, v[36:37], off offset:1024
	global_load_ushort v194, v[38:39], off offset:1024
	global_load_ushort v116, v[28:29], off offset:1024
	v_lshl_add_u64 v[28:29], v[2:3], 0, s[6:7]
	s_mov_b32 s6, 0x18c00000
	v_add_co_u32_e32 v24, vcc, s6, v2
	s_mov_b64 s[6:7], 0x18d10000
	s_nop 0
	v_addc_co_u32_e32 v25, vcc, 0, v3, vcc
	v_lshl_add_u64 v[36:37], v[2:3], 0, s[6:7]
	s_mov_b32 s6, 0x18d10000
	v_add_co_u32_e32 v2, vcc, s6, v2
	s_and_b32 s26, s11, -16
	s_nop 0
	v_addc_co_u32_e32 v3, vcc, 0, v3, vcc
	global_load_dwordx4 v[24:27], v[24:25], off
	s_nop 0
	global_load_dwordx4 v[28:31], v[28:29], off offset:64
	s_nop 0
	global_load_dwordx4 v[32:35], v[2:3], off
	s_nop 0
	global_load_dwordx4 v[36:39], v[36:37], off offset:64
	v_add_u32_e32 v76, s10, v43
	v_mov_b64_e32 v[2:3], s[4:5]
	v_lshlrev_b32_e32 v0, 3, v42
	s_ashr_i32 s27, s26, 31
	v_mad_i64_i32 v[42:43], s[4:5], v76, s94, v[2:3]
	v_lshl_add_u64 v[42:43], v[42:43], 0, s[78:79]
	s_lshl_b64 s[4:5], s[26:27], 1
	v_add_u32_e32 v70, 16, v76
	v_lshl_add_u64 v[42:43], v[42:43], 0, s[4:5]
	v_mad_i64_i32 v[70:71], s[6:7], v70, s94, v[2:3]
	v_lshl_add_u64 v[42:43], v[42:43], 0, v[0:1]
	s_mov_b32 s10, 0xe000000
	v_lshl_add_u64 v[70:71], v[70:71], 0, s[78:79]
	v_add_co_u32_e32 v42, vcc, s10, v42
	v_lshl_add_u64 v[70:71], v[70:71], 0, s[4:5]
	s_nop 0
	v_addc_co_u32_e32 v43, vcc, 0, v43, vcc
	v_lshl_add_u64 v[70:71], v[70:71], 0, v[0:1]
	v_add_co_u32_e32 v72, vcc, s10, v70
	v_add_u32_e32 v70, 32, v76
	s_nop 0
	v_addc_co_u32_e32 v73, vcc, 0, v71, vcc
	v_mad_i64_i32 v[70:71], s[6:7], v70, s94, v[2:3]
	v_lshl_add_u64 v[70:71], v[70:71], 0, s[78:79]
	v_lshl_add_u64 v[70:71], v[70:71], 0, s[4:5]
	v_lshl_add_u64 v[70:71], v[70:71], 0, v[0:1]
	v_add_co_u32_e32 v74, vcc, s10, v70
	v_add_u32_e32 v70, 48, v76
	v_mad_i64_i32 v[2:3], s[6:7], v70, s94, v[2:3]
	v_lshl_add_u64 v[2:3], v[2:3], 0, s[78:79]
	v_lshl_add_u64 v[2:3], v[2:3], 0, s[4:5]
	v_readlane_b32 s4, v245, 46
	v_lshl_add_u64 v[2:3], v[2:3], 0, v[0:1]
	v_addc_co_u32_e32 v75, vcc, 0, v71, vcc
	v_mov_b32_e32 v0, s4
	ds_read_b64 v[118:119], v0
	s_lshl_b64 s[4:5], s[84:85], 2
	v_add_co_u32_e32 v2, vcc, s10, v2
	s_waitcnt lgkmcnt(0)
	v_readfirstlane_b32 s7, v118
	v_readfirstlane_b32 s6, v119
	s_add_u32 s4, s7, s4
	s_addc_u32 s5, s6, s5
	s_lshl_b32 s6, s9, 9
	s_add_u32 s6, s4, s6
	s_addc_u32 s7, s5, 0
	s_lshl_b64 s[4:5], s[26:27], 2
	s_add_u32 s4, s6, s4
	v_addc_co_u32_e32 v3, vcc, 0, v3, vcc
	global_load_dwordx2 v[70:71], v[42:43], off offset:2048
	s_nop 0
	global_load_dwordx2 v[72:73], v[72:73], off offset:2048
	s_nop 0
	global_load_dwordx2 v[74:75], v[74:75], off offset:2048
	s_nop 0
	global_load_dwordx2 v[76:77], v[2:3], off offset:2048
	s_addc_u32 s5, s7, s5
	v_lshl_add_u64 v[2:3], s[4:5], 0, v[40:41]
	global_load_dwordx4 v[40:43], v[2:3], off

.LBB0_264:
	s_or_b64 exec, exec, s[10:11]
	v_and_b32_e32 v22, 0xf8, v31
	v_lshlrev_b32_e32 v0, 1, v22
	v_lshl_add_u64 v[2:3], v[2:3], 0, v[0:1]
	global_load_dwordx4 v[10:13], v[2:3], off
	global_load_dwordx4 v[14:17], v[2:3], off offset:512
	global_load_dwordx4 v[6:9], v[2:3], off offset:1024
	v_mov_b64_e32 v[2:3], s[0:1]
	v_mad_u64_u32 v[28:29], s[10:11], v26, s94, v[2:3]
	v_mov_b32_e32 v2, v29
	v_mad_u64_u32 v[2:3], s[10:11], v27, s94, v[2:3]
	v_mov_b32_e32 v29, v2
	v_lshl_add_u64 v[2:3], v[28:29], 0, v[0:1]
	s_mov_b32 s10, 0xe000000
	v_lshlrev_b32_e32 v24, 1, v19
	v_mov_b32_e32 v19, v1
	v_add_co_u32_e32 v2, vcc, s10, v2
	v_mad_i64_i32 v[20:21], s[10:11], v24, s87, v[18:19]
	v_or_b32_e32 v24, 1, v24
	v_mad_i64_i32 v[18:19], s[10:11], v24, s87, v[18:19]
	v_lshlrev_b64 v[20:21], 10, v[20:21]
	v_lshlrev_b64 v[18:19], 10, v[18:19]
	v_addc_co_u32_e32 v3, vcc, 0, v3, vcc
	v_lshl_add_u64 v[20:21], s[6:7], 0, v[20:21]
	v_lshlrev_b32_e32 v22, 2, v22
	v_mov_b32_e32 v23, v1
	v_lshl_add_u64 v[18:19], s[6:7], 0, v[18:19]
	s_waitcnt lgkmcnt(0)
	global_load_dwordx4 v[2:5], v[2:3], off offset:3584
	v_lshl_add_u64 v[20:21], v[20:21], 0, v[22:23]
	v_lshl_add_u64 v[22:23], v[18:19], 0, v[22:23]
	global_load_dwordx4 v[32:35], v[20:21], off
	s_nop 0
	global_load_dwordx4 v[18:21], v[20:21], off offset:16
	s_nop 0
	global_load_dwordx4 v[36:39], v[22:23], off
	s_nop 0
	global_load_dwordx4 v[22:25], v[22:23], off offset:16
	s_movk_i32 s22, 0xf400
	v_add_u32_e32 v30, s72, v30
	v_add_u32_e32 v31, s73, v31
	s_waitcnt vmcnt(0)
	v_lshlrev_b32_e32 v40, 16, v10
	v_lshlrev_b32_e32 v41, 16, v14
	v_and_b32_e32 v10, 0xffff0000, v10
	v_and_b32_e32 v14, 0xffff0000, v14
	s_waitcnt lgkmcnt(0)
	v_fmac_f32_e32 v40, v32, v41
	v_lshlrev_b32_e32 v32, 16, v6
	v_fmac_f32_e32 v10, v33, v14
	v_and_b32_e32 v6, 0xffff0000, v6
	v_fmac_f32_e32 v10, v37, v6
	v_lshlrev_b32_e32 v6, 16, v2
	v_mul_f32_e32 v14, v6, v6
	v_fmamk_f32 v14, v14, 0xbdd2d3e8, v211
	v_mul_f32_e32 v14, v14, v6
	v_exp_f32_e32 v14, v14
	v_and_b32_e32 v2, 0xffff0000, v2
	v_fmac_f32_e32 v40, v36, v32
	v_add_f32_e32 v14, 1.0, v14
	v_rcp_f32_e32 v14, v14
	s_nop 0
	v_mul_f32_e32 v6, v14, v6
	v_mul_f32_e32 v14, v2, v2
	v_fmamk_f32 v14, v14, 0xbdd2d3e8, v211
	v_mul_f32_e32 v14, v14, v2
	v_exp_f32_e32 v14, v14
	v_mul_f32_e32 v6, v40, v6
	v_add_f32_e32 v14, 1.0, v14
	v_rcp_f32_e32 v14, v14
	s_nop 0
	v_mul_f32_e32 v2, v14, v2
	v_mul_f32_e32 v2, v10, v2
	v_cvt_pk_bf16_f32 v2, v6, v2
	v_lshlrev_b32_e32 v6, 16, v11
	v_lshlrev_b32_e32 v10, 16, v15
	v_fmac_f32_e32 v6, v34, v10
	v_lshlrev_b32_e32 v10, 16, v7
	v_fmac_f32_e32 v6, v38, v10
	v_and_b32_e32 v10, 0xffff0000, v11
	v_and_b32_e32 v11, 0xffff0000, v15
	v_fmac_f32_e32 v10, v35, v11
	v_and_b32_e32 v7, 0xffff0000, v7
	v_fmac_f32_e32 v10, v39, v7
	v_lshlrev_b32_e32 v7, 16, v3
	v_mul_f32_e32 v11, v7, v7
	v_fmamk_f32 v11, v11, 0xbdd2d3e8, v211
	v_mul_f32_e32 v11, v11, v7
	v_exp_f32_e32 v11, v11
	v_and_b32_e32 v3, 0xffff0000, v3
	v_add_f32_e32 v11, 1.0, v11
	v_rcp_f32_e32 v11, v11
	s_nop 0
	v_mul_f32_e32 v7, v11, v7
	v_mul_f32_e32 v6, v6, v7
	v_mul_f32_e32 v7, v3, v3
	v_fmamk_f32 v7, v7, 0xbdd2d3e8, v211
	v_mul_f32_e32 v7, v7, v3
	v_exp_f32_e32 v7, v7
	s_nop 0
	v_add_f32_e32 v7, 1.0, v7
	v_rcp_f32_e32 v7, v7
	s_nop 0
	v_mul_f32_e32 v3, v7, v3
	v_mul_f32_e32 v3, v10, v3
	v_cvt_pk_bf16_f32 v3, v6, v3
	v_lshlrev_b32_e32 v6, 16, v12
	v_lshlrev_b32_e32 v7, 16, v16
	v_fmac_f32_e32 v6, v18, v7
	v_lshlrev_b32_e32 v7, 16, v8
	v_fmac_f32_e32 v6, v22, v7
	v_and_b32_e32 v7, 0xffff0000, v12
	v_and_b32_e32 v10, 0xffff0000, v16
	v_fmac_f32_e32 v7, v19, v10
	v_and_b32_e32 v8, 0xffff0000, v8
	v_fmac_f32_e32 v7, v23, v8
	v_lshlrev_b32_e32 v8, 16, v4
	v_mul_f32_e32 v10, v8, v8
	v_fmamk_f32 v10, v10, 0xbdd2d3e8, v211
	v_mul_f32_e32 v10, v10, v8
	v_exp_f32_e32 v10, v10
	v_and_b32_e32 v4, 0xffff0000, v4
	v_add_f32_e32 v10, 1.0, v10
	v_rcp_f32_e32 v10, v10
	s_nop 0
	v_mul_f32_e32 v8, v10, v8
	v_mul_f32_e32 v6, v6, v8
	v_mul_f32_e32 v8, v4, v4
	v_fmamk_f32 v8, v8, 0xbdd2d3e8, v211
	v_mul_f32_e32 v8, v8, v4
	v_exp_f32_e32 v8, v8
	s_nop 0
	v_add_f32_e32 v8, 1.0, v8
	v_rcp_f32_e32 v8, v8
	s_nop 0
	v_mul_f32_e32 v4, v8, v4
	v_mul_f32_e32 v4, v7, v4
	v_cvt_pk_bf16_f32 v4, v6, v4
	v_lshlrev_b32_e32 v6, 16, v13
	v_lshlrev_b32_e32 v7, 16, v17
	v_fmac_f32_e32 v6, v20, v7
	v_lshlrev_b32_e32 v7, 16, v9
	v_fmac_f32_e32 v6, v24, v7
	v_and_b32_e32 v7, 0xffff0000, v13
	v_and_b32_e32 v8, 0xffff0000, v17
	v_fmac_f32_e32 v7, v21, v8
	v_and_b32_e32 v8, 0xffff0000, v9
	v_fmac_f32_e32 v7, v25, v8
	v_lshlrev_b32_e32 v8, 16, v5
	v_mul_f32_e32 v9, v8, v8
	v_fmamk_f32 v9, v9, 0xbdd2d3e8, v211
	v_mul_f32_e32 v9, v9, v8
	v_exp_f32_e32 v9, v9
	v_and_b32_e32 v5, 0xffff0000, v5
	v_add_f32_e32 v9, 1.0, v9
	v_rcp_f32_e32 v9, v9
	s_nop 0
	v_mul_f32_e32 v8, v9, v8
	v_mul_f32_e32 v6, v6, v8
	v_mul_f32_e32 v8, v5, v5
	v_fmamk_f32 v8, v8, 0xbdd2d3e8, v211
	v_mul_f32_e32 v8, v8, v5
	v_exp_f32_e32 v8, v8
	s_nop 0
	v_add_f32_e32 v8, 1.0, v8
	v_rcp_f32_e32 v8, v8
	s_nop 0
	v_mul_f32_e32 v5, v8, v5
	v_mul_f32_e32 v5, v7, v5
	v_cvt_pk_bf16_f32 v5, v6, v5
	v_mad_u64_u32 v[6:7], s[10:11], v26, s22, v[28:29]
	v_mov_b32_e32 v8, v7
	v_mad_u64_u32 v[8:9], s[10:11], v27, s22, v[8:9]
	v_sub_u32_e32 v7, v8, v26
	v_lshl_add_u64 v[6:7], v[6:7], 0, v[0:1]
	v_add_co_u32_e32 v6, vcc, 0x8800000, v6
	v_readlane_b32 s10, v244, 22
	s_nop 0
	v_addc_co_u32_e32 v7, vcc, 0, v7, vcc
	v_cmp_le_i32_e32 vcc, s10, v30
	s_or_b64 s[8:9], vcc, s[8:9]
	global_store_dwordx4 v[6:7], v[2:5], off offset:1024
	s_andn2_b64 exec, exec, s[8:9]
	s_cbranch_execz .LBB0_273

.LBB0_275:
	s_or_b64 exec, exec, s[4:5]
	s_waitcnt lgkmcnt(0)
	v_mfma_f32_16x16x32_bf16 v[42:45], v[72:75], v[42:45], 0
	v_mul_f32_e32 v63, v33, v62
	v_fma_f32 v63, v32, v0, -v63
	v_mul_f32_e32 v0, v33, v0
	v_mfma_f32_16x16x32_bf16 v[68:71], v[72:75], v[68:71], 0
	s_nop 7
	ds_write2_b32 v80, v42, v68 offset1:16
	ds_write2_b32 v80, v43, v69 offset0:132 offset1:148
	ds_write2_b32 v82, v44, v70 offset0:8 offset1:24
	v_mfma_f32_16x16x32_bf16 v[64:67], v[72:75], v[64:67], 0
	v_fmac_f32_e32 v0, v32, v62
	v_readlane_b32 s4, v245, 53
	v_mfma_f32_16x16x32_bf16 v[50:53], v[72:75], v[50:53], 0
	ds_write2_b32 v82, v45, v71 offset0:140 offset1:156
	s_nop 6
	ds_write2_b32 v80, v64, v50 offset0:32 offset1:48
	ds_write2_b32 v80, v65, v51 offset0:164 offset1:180
	v_mfma_f32_16x16x32_bf16 v[54:57], v[72:75], v[54:57], 0
	v_mfma_f32_16x16x32_bf16 v[42:45], v[72:75], v[46:49], 0
	ds_write2_b32 v82, v66, v52 offset0:40 offset1:56
	ds_write2_b32 v82, v67, v53 offset0:172 offset1:188
	s_nop 5
	ds_write2_b32 v80, v54, v42 offset0:64 offset1:80
	ds_write2_b32 v80, v55, v43 offset0:196 offset1:212
	ds_write2_b32 v82, v56, v44 offset0:72 offset1:88
	ds_write2_b32 v82, v57, v45 offset0:204 offset1:220
	v_mfma_f32_16x16x32_bf16 v[38:41], v[72:75], v[38:41], 0
	v_mfma_f32_16x16x32_bf16 v[34:37], v[72:75], v[34:37], 0
	s_nop 7
	ds_write2_b32 v80, v38, v34 offset0:96 offset1:112
	ds_write2_b32 v80, v39, v35 offset0:228 offset1:244
	ds_write2_b32 v82, v40, v36 offset0:104 offset1:120
	ds_write2_b32 v82, v41, v37 offset0:236 offset1:252
	s_waitcnt lgkmcnt(0)
	ds_read2st64_b32 v[10:11], v84 offset0:42 offset1:43
	ds_read2st64_b32 v[34:35], v85 offset0:40 offset1:41
	ds_read2st64_b32 v[36:37], v86 offset0:38 offset1:39
	ds_read2st64_b32 v[38:39], v87 offset0:36 offset1:37
	ds_read2st64_b32 v[40:41], v88 offset0:34 offset1:35
	ds_read2st64_b32 v[42:43], v89 offset0:32 offset1:33
	ds_read2st64_b32 v[44:45], v90 offset0:30 offset1:31
	ds_read2st64_b32 v[46:47], v91 offset0:28 offset1:29
	ds_read2st64_b32 v[48:49], v92 offset0:26 offset1:27
	ds_read2st64_b32 v[50:51], v93 offset0:24 offset1:25
	ds_read2st64_b32 v[52:53], v94 offset0:22 offset1:23
	ds_read2st64_b32 v[54:55], v95 offset0:20 offset1:21
	ds_read2st64_b32 v[56:57], v96 offset0:18 offset1:19
	ds_read2st64_b32 v[64:65], v97 offset0:16 offset1:17
	ds_read2st64_b32 v[66:67], v98 offset0:14 offset1:15
	ds_read2st64_b32 v[68:69], v83 offset0:12 offset1:13
	s_waitcnt lgkmcnt(14)
	v_add_f32_e32 v10, v63, v10
	v_add_f32_e32 v0, v0, v11
	v_cvt_pk_bf16_f32 v11, v10, v0
	v_mul_f32_e32 v62, v33, v0
	v_mul_f32_e32 v0, v32, v0
	v_fma_f32 v62, v32, v10, -v62
	v_fmac_f32_e32 v0, v33, v10
	v_add_f32_e32 v34, v34, v62
	v_add_f32_e32 v0, v35, v0
	v_cvt_pk_bf16_f32 v10, v34, v0
	ds_write2_b32 v99, v10, v11 offset0:120 offset1:188
	v_mul_f32_e32 v11, v33, v34
	v_mul_f32_e32 v10, v33, v0
	v_fmac_f32_e32 v11, v32, v0
	v_fma_f32 v10, v32, v34, -v10
	s_waitcnt lgkmcnt(14)
	v_add_f32_e32 v0, v37, v11
	v_add_f32_e32 v10, v36, v10
	v_mul_f32_e32 v34, v33, v0
	v_cvt_pk_bf16_f32 v11, v10, v0
	v_fma_f32 v34, v32, v10, -v34
	v_mul_f32_e32 v10, v33, v10
	v_fmac_f32_e32 v10, v32, v0
	s_waitcnt lgkmcnt(13)
	v_add_f32_e32 v34, v38, v34
	v_add_f32_e32 v0, v39, v10
	v_cvt_pk_bf16_f32 v10, v34, v0
	ds_write2_b32 v100, v10, v11 offset0:112 offset1:180
	v_mul_f32_e32 v11, v33, v34
	v_mul_f32_e32 v10, v33, v0
	v_fmac_f32_e32 v11, v32, v0
	v_fma_f32 v10, v32, v34, -v10
	s_waitcnt lgkmcnt(13)
	v_add_f32_e32 v0, v41, v11
	v_add_f32_e32 v10, v40, v10
	v_mul_f32_e32 v34, v33, v0
	v_cvt_pk_bf16_f32 v11, v10, v0
	v_fma_f32 v34, v32, v10, -v34
	v_mul_f32_e32 v10, v33, v10
	v_fmac_f32_e32 v10, v32, v0
	s_waitcnt lgkmcnt(12)
	v_add_f32_e32 v34, v42, v34
	v_add_f32_e32 v0, v43, v10
	v_cvt_pk_bf16_f32 v10, v34, v0
	ds_write2_b32 v101, v10, v11 offset0:104 offset1:172
	v_mul_f32_e32 v11, v33, v34
	v_mul_f32_e32 v10, v33, v0
	v_fmac_f32_e32 v11, v32, v0
	v_fma_f32 v10, v32, v34, -v10
	s_waitcnt lgkmcnt(12)
	v_add_f32_e32 v0, v45, v11
	v_add_f32_e32 v10, v44, v10
	v_mul_f32_e32 v34, v33, v0
	v_cvt_pk_bf16_f32 v11, v10, v0
	v_fma_f32 v34, v32, v10, -v34
	v_mul_f32_e32 v10, v33, v10
	v_fmac_f32_e32 v10, v32, v0
	s_waitcnt lgkmcnt(11)
	v_add_f32_e32 v34, v46, v34
	v_add_f32_e32 v0, v47, v10
	v_cvt_pk_bf16_f32 v10, v34, v0
	ds_write2_b32 v102, v10, v11 offset0:96 offset1:164
	v_mul_f32_e32 v11, v33, v34
	v_mul_f32_e32 v10, v33, v0
	v_fmac_f32_e32 v11, v32, v0
	v_fma_f32 v10, v32, v34, -v10
	s_waitcnt lgkmcnt(11)
	v_add_f32_e32 v0, v49, v11
	v_add_f32_e32 v10, v48, v10
	v_mul_f32_e32 v34, v33, v0
	v_cvt_pk_bf16_f32 v11, v10, v0
	v_fma_f32 v34, v32, v10, -v34
	v_mul_f32_e32 v10, v33, v10
	v_fmac_f32_e32 v10, v32, v0
	s_waitcnt lgkmcnt(10)
	v_add_f32_e32 v34, v50, v34
	v_add_f32_e32 v0, v51, v10
	v_cvt_pk_bf16_f32 v10, v34, v0
	ds_write2_b32 v103, v10, v11 offset0:88 offset1:156
	v_mul_f32_e32 v11, v33, v34
	v_mul_f32_e32 v10, v33, v0
	v_fmac_f32_e32 v11, v32, v0
	v_fma_f32 v10, v32, v34, -v10
	s_waitcnt lgkmcnt(10)
	v_add_f32_e32 v0, v53, v11
	v_add_f32_e32 v10, v52, v10
	v_mul_f32_e32 v34, v33, v0
	v_cvt_pk_bf16_f32 v11, v10, v0
	v_fma_f32 v34, v32, v10, -v34
	v_mul_f32_e32 v10, v33, v10
	v_fmac_f32_e32 v10, v32, v0
	s_waitcnt lgkmcnt(9)
	v_add_f32_e32 v34, v54, v34
	v_add_f32_e32 v0, v55, v10
	v_cvt_pk_bf16_f32 v10, v34, v0
	ds_write2_b32 v104, v10, v11 offset0:80 offset1:148
	v_mul_f32_e32 v11, v33, v34
	v_mul_f32_e32 v10, v33, v0
	v_fmac_f32_e32 v11, v32, v0
	v_fma_f32 v10, v32, v34, -v10
	s_waitcnt lgkmcnt(9)
	v_add_f32_e32 v0, v57, v11
	v_add_f32_e32 v10, v56, v10
	v_mul_f32_e32 v34, v33, v0
	v_cvt_pk_bf16_f32 v11, v10, v0
	v_fma_f32 v34, v32, v10, -v34
	v_mul_f32_e32 v10, v33, v10
	v_fmac_f32_e32 v10, v32, v0
	s_waitcnt lgkmcnt(8)
	v_add_f32_e32 v34, v64, v34
	v_add_f32_e32 v0, v65, v10
	v_cvt_pk_bf16_f32 v10, v34, v0
	ds_write2_b32 v105, v10, v11 offset0:72 offset1:140
	v_mul_f32_e32 v11, v33, v34
	v_mul_f32_e32 v10, v33, v0
	v_fmac_f32_e32 v11, v32, v0
	v_fma_f32 v10, v32, v34, -v10
	s_waitcnt lgkmcnt(8)
	v_add_f32_e32 v0, v67, v11
	v_add_f32_e32 v10, v66, v10
	v_mul_f32_e32 v34, v33, v0
	v_cvt_pk_bf16_f32 v11, v10, v0
	v_fma_f32 v34, v32, v10, -v34
	v_mul_f32_e32 v10, v33, v10
	v_fmac_f32_e32 v10, v32, v0
	s_waitcnt lgkmcnt(7)
	v_add_f32_e32 v34, v68, v34
	v_add_f32_e32 v0, v69, v10
	v_cvt_pk_bf16_f32 v0, v34, v0
	ds_write2_b32 v106, v0, v11 offset0:64 offset1:132
	s_waitcnt lgkmcnt(0)
	v_mov_b32_e32 v0, s4
	ds_read_b64 v[10:11], v0
	s_lshr_b32 s4, s23, 6
	v_lshrrev_b32_e32 v0, 2, v78
	v_and_b32_e32 v46, 15, v78
	s_mulk_i32 s4, 0x3e00
	v_and_b32_e32 v47, 12, v0
	ds_read_b128 v[32:35], v79 offset:11520
	ds_read_b128 v[36:39], v79 offset:11584
	s_add_i32 s4, s4, 0
	v_lshlrev_b32_e32 v0, 1, v46
	v_mul_u32_u24_e32 v41, 48, v47
	v_add3_u32 v48, s4, v0, v41
	s_waitcnt lgkmcnt(2)
	v_readfirstlane_b32 s4, v11
	v_readfirstlane_b32 s5, v10
	s_waitcnt lgkmcnt(1)
	v_mfma_f32_16x16x32_bf16 v[2:5], v[32:35], v[20:23], v[2:5]
	v_mov_b32_e32 v11, s4
	v_mov_b32_e32 v10, s5
	v_readlane_b32 s4, v245, 4
	s_add_i32 s4, s0, s4
	v_mov_b32_e32 v40, s59
	v_or_b32_e32 v20, s4, v46
	v_ashrrev_i32_e32 v21, 31, v20
	v_lshl_add_u64 v[10:11], v[20:21], 2, v[10:11]
	ds_read_u16 v49, v48
	ds_read_b64 v[44:45], v40
	global_load_dword v10, v[10:11], off
	ds_read_b128 v[40:43], v79 offset:11648
	ds_read_b128 v[20:23], v79 offset:11712
	s_waitcnt lgkmcnt(0)
	v_mfma_f32_16x16x32_bf16 v[2:5], v[36:39], v[28:31], v[2:5]
	v_readlane_b32 s5, v245, 5
	v_readfirstlane_b32 s5, v44
	s_lshl_b64 s[0:1], s[0:1], 1
	v_mfma_f32_16x16x32_bf16 v[2:5], v[40:43], v[24:27], v[2:5]
	v_readfirstlane_b32 s4, v45
	s_add_u32 s0, s5, s0
	s_addc_u32 s1, s4, s1
	v_mfma_f32_16x16x32_bf16 v[16:19], v[20:23], v[16:19], v[2:5]
	s_lshl_b32 s4, s22, 6
	s_add_i32 s10, s10, s54
	s_add_i32 s17, s17, s60
	s_nop 0
	v_lshl_add_u64 v[2:3], s[0:1], 0, v[0:1]
	v_lshlrev_b32_e32 v0, 16, v49
	s_mov_b64 s[0:1], 0xcc00000
	v_lshl_add_u64 v[2:3], v[2:3], 0, s[0:1]
	s_lshl_b32 s0, s20, 12
	s_lshl_b32 s1, s20, 8
	s_add_i32 s0, s22, s0
	s_add_i32 s1, s1, s4
	s_add_i32 s0, s0, -4
	s_add_i32 s1, s1, 0x8000
	v_lshl_add_u32 v5, v47, 6, s0
	s_waitcnt vmcnt(0)
	v_fma_f32 v0, v10, v0, v16
	v_mul_f32_e32 v4, v0, v0
	v_fmamk_f32 v4, v4, 0xbdd2d3e8, v211
	v_mul_f32_e32 v4, v0, v4
	v_exp_f32_e32 v4, v4
	s_nop 0
	v_add_f32_e32 v4, 1.0, v4
	v_rcp_f32_e32 v4, v4
	s_nop 0
	v_mul_f32_e32 v0, v0, v4
	v_or_b32_e32 v4, s1, v47
	v_cndmask_b32_e64 v4, v5, v4, s[36:37]
	v_ashrrev_i32_e32 v5, 31, v4
	v_lshlrev_b64 v[4:5], 9, v[4:5]
	v_cvt_pk_bf16_f32 v0, v0, s0
	v_lshl_add_u64 v[4:5], v[2:3], 0, v[4:5]
	global_store_short v[4:5], v0, off
	ds_read_u16 v0, v48 offset:48
	v_or_b32_e32 v5, 1, v47
	s_waitcnt lgkmcnt(0)
	v_lshlrev_b32_e32 v0, 16, v0
	v_fma_f32 v0, v10, v0, v17
	v_mul_f32_e32 v4, v0, v0
	v_fmamk_f32 v4, v4, 0xbdd2d3e8, v211
	v_mul_f32_e32 v4, v0, v4
	v_exp_f32_e32 v4, v4
	s_nop 0
	v_add_f32_e32 v4, 1.0, v4
	v_rcp_f32_e32 v4, v4
	s_nop 0
	v_mul_f32_e32 v0, v0, v4
	v_or_b32_e32 v4, s1, v5
	v_lshl_add_u32 v5, v5, 6, s0
	v_cndmask_b32_e64 v4, v5, v4, s[36:37]
	v_ashrrev_i32_e32 v5, 31, v4
	v_lshlrev_b64 v[4:5], 9, v[4:5]
	v_cvt_pk_bf16_f32 v0, v0, s0
	v_lshl_add_u64 v[4:5], v[2:3], 0, v[4:5]
	global_store_short v[4:5], v0, off
	ds_read_u16 v0, v48 offset:96
	v_or_b32_e32 v5, 2, v47
	s_waitcnt lgkmcnt(0)
	v_lshlrev_b32_e32 v0, 16, v0
	v_fma_f32 v0, v10, v0, v18
	v_mul_f32_e32 v4, v0, v0
	v_fmamk_f32 v4, v4, 0xbdd2d3e8, v211
	v_mul_f32_e32 v4, v0, v4
	v_exp_f32_e32 v4, v4
	s_nop 0
	v_add_f32_e32 v4, 1.0, v4
	v_rcp_f32_e32 v4, v4
	s_nop 0
	v_mul_f32_e32 v0, v0, v4
	v_or_b32_e32 v4, s1, v5
	v_lshl_add_u32 v5, v5, 6, s0
	v_cndmask_b32_e64 v4, v5, v4, s[36:37]
	v_ashrrev_i32_e32 v5, 31, v4
	v_lshlrev_b64 v[4:5], 9, v[4:5]
	v_cvt_pk_bf16_f32 v0, v0, s0
	v_lshl_add_u64 v[4:5], v[2:3], 0, v[4:5]
	global_store_short v[4:5], v0, off
	ds_read_u16 v0, v48 offset:144
	v_or_b32_e32 v4, 3, v47
	v_or_b32_e32 v5, s1, v4
	v_lshl_add_u32 v4, v4, 6, s0
	v_cndmask_b32_e64 v4, v4, v5, s[36:37]
	s_waitcnt lgkmcnt(0)
	v_lshlrev_b32_e32 v0, 16, v0
	v_fmac_f32_e32 v19, v10, v0
	v_mul_f32_e32 v0, v19, v19
	v_fmamk_f32 v0, v0, 0xbdd2d3e8, v211
	v_mul_f32_e32 v0, v19, v0
	v_exp_f32_e32 v0, v0
	v_ashrrev_i32_e32 v5, 31, v4
	v_lshlrev_b64 v[4:5], 9, v[4:5]
	v_lshl_add_u64 v[4:5], v[2:3], 0, v[4:5]
	v_add_f32_e32 v0, 1.0, v0
	v_rcp_f32_e32 v0, v0
	s_nop 0
	v_mul_f32_e32 v0, v19, v0
	v_cvt_pk_bf16_f32 v0, v0, s0
	global_store_short v[4:5], v0, off
	ds_read_u16 v0, v48 offset:768
	v_or_b32_e32 v5, 16, v47
	s_waitcnt lgkmcnt(0)
	v_lshlrev_b32_e32 v0, 16, v0
	v_fma_f32 v0, v10, v0, v6
	v_mul_f32_e32 v4, v0, v0
	v_fmamk_f32 v4, v4, 0xbdd2d3e8, v211
	v_mul_f32_e32 v4, v0, v4
	v_exp_f32_e32 v4, v4
	s_nop 0
	v_add_f32_e32 v4, 1.0, v4
	v_rcp_f32_e32 v4, v4
	s_nop 0
	v_mul_f32_e32 v0, v0, v4
	v_or_b32_e32 v4, s1, v5
	v_lshl_add_u32 v5, v5, 6, s0
	v_cndmask_b32_e64 v4, v5, v4, s[36:37]
	v_ashrrev_i32_e32 v5, 31, v4
	v_lshlrev_b64 v[4:5], 9, v[4:5]
	v_cvt_pk_bf16_f32 v0, v0, s0
	v_lshl_add_u64 v[4:5], v[2:3], 0, v[4:5]
	global_store_short v[4:5], v0, off
	ds_read_u16 v0, v48 offset:816
	v_or_b32_e32 v5, 17, v47
	s_waitcnt lgkmcnt(0)
	v_lshlrev_b32_e32 v0, 16, v0
	v_fma_f32 v0, v10, v0, v7
	v_mul_f32_e32 v4, v0, v0
	v_fmamk_f32 v4, v4, 0xbdd2d3e8, v211
	v_mul_f32_e32 v4, v0, v4
	v_exp_f32_e32 v4, v4
	s_nop 0
	v_add_f32_e32 v4, 1.0, v4
	v_rcp_f32_e32 v4, v4
	s_nop 0
	v_mul_f32_e32 v0, v0, v4
	v_or_b32_e32 v4, s1, v5
	v_lshl_add_u32 v5, v5, 6, s0
	v_cndmask_b32_e64 v4, v5, v4, s[36:37]
	v_ashrrev_i32_e32 v5, 31, v4
	v_lshlrev_b64 v[4:5], 9, v[4:5]
	v_cvt_pk_bf16_f32 v0, v0, s0
	v_lshl_add_u64 v[4:5], v[2:3], 0, v[4:5]
	global_store_short v[4:5], v0, off
	ds_read_u16 v0, v48 offset:864
	v_or_b32_e32 v5, 18, v47
	s_waitcnt lgkmcnt(0)
	v_lshlrev_b32_e32 v0, 16, v0
	v_fma_f32 v0, v10, v0, v8
	v_mul_f32_e32 v4, v0, v0
	v_fmamk_f32 v4, v4, 0xbdd2d3e8, v211
	v_mul_f32_e32 v4, v0, v4
	v_exp_f32_e32 v4, v4
	s_nop 0
	v_add_f32_e32 v4, 1.0, v4
	v_rcp_f32_e32 v4, v4
	s_nop 0
	v_mul_f32_e32 v0, v0, v4
	v_or_b32_e32 v4, s1, v5
	v_lshl_add_u32 v5, v5, 6, s0
	v_cndmask_b32_e64 v4, v5, v4, s[36:37]
	v_ashrrev_i32_e32 v5, 31, v4
	v_lshlrev_b64 v[4:5], 9, v[4:5]
	v_cvt_pk_bf16_f32 v0, v0, s0
	v_lshl_add_u64 v[4:5], v[2:3], 0, v[4:5]
	global_store_short v[4:5], v0, off
	ds_read_u16 v0, v48 offset:912
	v_or_b32_e32 v4, 19, v47
	v_or_b32_e32 v5, s1, v4
	v_lshl_add_u32 v4, v4, 6, s0
	v_cndmask_b32_e64 v4, v4, v5, s[36:37]
	s_waitcnt lgkmcnt(0)
	v_lshlrev_b32_e32 v0, 16, v0
	v_fmac_f32_e32 v9, v10, v0
	v_mul_f32_e32 v0, v9, v9
	v_fmamk_f32 v0, v0, 0xbdd2d3e8, v211
	v_mul_f32_e32 v0, v9, v0
	v_exp_f32_e32 v0, v0
	v_ashrrev_i32_e32 v5, 31, v4
	v_lshlrev_b64 v[4:5], 9, v[4:5]
	v_lshl_add_u64 v[4:5], v[2:3], 0, v[4:5]
	v_add_f32_e32 v0, 1.0, v0
	v_rcp_f32_e32 v0, v0
	s_nop 0
	v_mul_f32_e32 v0, v9, v0
	v_cvt_pk_bf16_f32 v0, v0, s0
	global_store_short v[4:5], v0, off
	ds_read_u16 v0, v48 offset:1536
	v_or_b32_e32 v5, 32, v47
	s_waitcnt lgkmcnt(0)
	v_lshlrev_b32_e32 v0, 16, v0
	v_fma_f32 v0, v10, v0, v58
	v_mul_f32_e32 v4, v0, v0
	v_fmamk_f32 v4, v4, 0xbdd2d3e8, v211
	v_mul_f32_e32 v4, v0, v4
	v_exp_f32_e32 v4, v4
	s_nop 0
	v_add_f32_e32 v4, 1.0, v4
	v_rcp_f32_e32 v4, v4
	s_nop 0
	v_mul_f32_e32 v0, v0, v4
	v_or_b32_e32 v4, s1, v5
	v_lshl_add_u32 v5, v5, 6, s0
	v_cndmask_b32_e64 v4, v5, v4, s[36:37]
	v_ashrrev_i32_e32 v5, 31, v4
	v_lshlrev_b64 v[4:5], 9, v[4:5]
	v_cvt_pk_bf16_f32 v0, v0, s0
	v_lshl_add_u64 v[4:5], v[2:3], 0, v[4:5]
	global_store_short v[4:5], v0, off
	ds_read_u16 v0, v48 offset:1584
	v_or_b32_e32 v5, 33, v47
	s_waitcnt lgkmcnt(0)
	v_lshlrev_b32_e32 v0, 16, v0
	v_fma_f32 v0, v10, v0, v59
	v_mul_f32_e32 v4, v0, v0
	v_fmamk_f32 v4, v4, 0xbdd2d3e8, v211
	v_mul_f32_e32 v4, v0, v4
	v_exp_f32_e32 v4, v4
	s_nop 0
	v_add_f32_e32 v4, 1.0, v4
	v_rcp_f32_e32 v4, v4
	s_nop 0
	v_mul_f32_e32 v0, v0, v4
	v_or_b32_e32 v4, s1, v5
	v_lshl_add_u32 v5, v5, 6, s0
	v_cndmask_b32_e64 v4, v5, v4, s[36:37]
	v_ashrrev_i32_e32 v5, 31, v4
	v_lshlrev_b64 v[4:5], 9, v[4:5]
	v_cvt_pk_bf16_f32 v0, v0, s0
	v_lshl_add_u64 v[4:5], v[2:3], 0, v[4:5]
	global_store_short v[4:5], v0, off
	ds_read_u16 v0, v48 offset:1632
	v_or_b32_e32 v5, 34, v47
	s_waitcnt lgkmcnt(0)
	v_lshlrev_b32_e32 v0, 16, v0
	v_fma_f32 v0, v10, v0, v60
	v_mul_f32_e32 v4, v0, v0
	v_fmamk_f32 v4, v4, 0xbdd2d3e8, v211
	v_mul_f32_e32 v4, v0, v4
	v_exp_f32_e32 v4, v4
	s_nop 0
	v_add_f32_e32 v4, 1.0, v4
	v_rcp_f32_e32 v4, v4
	s_nop 0
	v_mul_f32_e32 v0, v0, v4
	v_or_b32_e32 v4, s1, v5
	v_lshl_add_u32 v5, v5, 6, s0
	v_cndmask_b32_e64 v4, v5, v4, s[36:37]
	v_ashrrev_i32_e32 v5, 31, v4
	v_lshlrev_b64 v[4:5], 9, v[4:5]
	v_cvt_pk_bf16_f32 v0, v0, s0
	v_lshl_add_u64 v[4:5], v[2:3], 0, v[4:5]
	global_store_short v[4:5], v0, off
	ds_read_u16 v0, v48 offset:1680
	v_or_b32_e32 v4, 35, v47
	v_or_b32_e32 v5, s1, v4
	v_lshl_add_u32 v4, v4, 6, s0
	v_cndmask_b32_e64 v4, v4, v5, s[36:37]
	s_waitcnt lgkmcnt(0)
	v_lshlrev_b32_e32 v0, 16, v0
	v_fmac_f32_e32 v61, v10, v0
	v_mul_f32_e32 v0, v61, v61
	v_fmamk_f32 v0, v0, 0xbdd2d3e8, v211
	v_mul_f32_e32 v0, v61, v0
	v_exp_f32_e32 v0, v0
	v_ashrrev_i32_e32 v5, 31, v4
	v_lshlrev_b64 v[4:5], 9, v[4:5]
	v_lshl_add_u64 v[4:5], v[2:3], 0, v[4:5]
	v_add_f32_e32 v0, 1.0, v0
	v_rcp_f32_e32 v0, v0
	s_nop 0
	v_mul_f32_e32 v0, v61, v0
	v_cvt_pk_bf16_f32 v0, v0, s0
	global_store_short v[4:5], v0, off
	ds_read_u16 v0, v48 offset:2304
	v_or_b32_e32 v5, 48, v47
	s_waitcnt lgkmcnt(0)
	v_lshlrev_b32_e32 v0, 16, v0
	v_fma_f32 v0, v10, v0, v12
	v_mul_f32_e32 v4, v0, v0
	v_fmamk_f32 v4, v4, 0xbdd2d3e8, v211
	v_mul_f32_e32 v4, v0, v4
	v_exp_f32_e32 v4, v4
	s_nop 0
	v_add_f32_e32 v4, 1.0, v4
	v_rcp_f32_e32 v4, v4
	s_nop 0
	v_mul_f32_e32 v0, v0, v4
	v_or_b32_e32 v4, s1, v5
	v_lshl_add_u32 v5, v5, 6, s0
	v_cndmask_b32_e64 v4, v5, v4, s[36:37]
	v_ashrrev_i32_e32 v5, 31, v4
	v_lshlrev_b64 v[4:5], 9, v[4:5]
	v_cvt_pk_bf16_f32 v0, v0, s0
	v_lshl_add_u64 v[4:5], v[2:3], 0, v[4:5]
	global_store_short v[4:5], v0, off
	ds_read_u16 v0, v48 offset:2352
	v_or_b32_e32 v5, 49, v47
	s_waitcnt lgkmcnt(0)
	v_lshlrev_b32_e32 v0, 16, v0
	v_fma_f32 v0, v10, v0, v13
	v_mul_f32_e32 v4, v0, v0
	v_fmamk_f32 v4, v4, 0xbdd2d3e8, v211
	v_mul_f32_e32 v4, v0, v4
	v_exp_f32_e32 v4, v4
	s_nop 0
	v_add_f32_e32 v4, 1.0, v4
	v_rcp_f32_e32 v4, v4
	s_nop 0
	v_mul_f32_e32 v0, v0, v4
	v_or_b32_e32 v4, s1, v5
	v_lshl_add_u32 v5, v5, 6, s0
	v_cndmask_b32_e64 v4, v5, v4, s[36:37]
	v_ashrrev_i32_e32 v5, 31, v4
	v_lshlrev_b64 v[4:5], 9, v[4:5]
	v_cvt_pk_bf16_f32 v0, v0, s0
	v_lshl_add_u64 v[4:5], v[2:3], 0, v[4:5]
	global_store_short v[4:5], v0, off
	ds_read_u16 v0, v48 offset:2400
	v_or_b32_e32 v5, 50, v47
	s_waitcnt lgkmcnt(0)
	v_lshlrev_b32_e32 v0, 16, v0
	v_fma_f32 v0, v10, v0, v14
	v_mul_f32_e32 v4, v0, v0
	v_fmamk_f32 v4, v4, 0xbdd2d3e8, v211
	v_mul_f32_e32 v4, v0, v4
	v_exp_f32_e32 v4, v4
	s_nop 0
	v_add_f32_e32 v4, 1.0, v4
	v_rcp_f32_e32 v4, v4
	s_nop 0
	v_mul_f32_e32 v0, v0, v4
	v_or_b32_e32 v4, s1, v5
	v_lshl_add_u32 v5, v5, 6, s0
	v_cndmask_b32_e64 v4, v5, v4, s[36:37]
	v_ashrrev_i32_e32 v5, 31, v4
	v_lshlrev_b64 v[4:5], 9, v[4:5]
	v_cvt_pk_bf16_f32 v0, v0, s0
	v_lshl_add_u64 v[4:5], v[2:3], 0, v[4:5]
	global_store_short v[4:5], v0, off
	ds_read_u16 v0, v48 offset:2448
	v_or_b32_e32 v4, 51, v47
	v_or_b32_e32 v5, s1, v4
	v_lshl_add_u32 v4, v4, 6, s0
	v_cndmask_b32_e64 v4, v4, v5, s[36:37]
	s_waitcnt lgkmcnt(0)
	v_lshlrev_b32_e32 v0, 16, v0
	v_fmac_f32_e32 v15, v10, v0
	v_mul_f32_e32 v0, v15, v15
	v_fmamk_f32 v0, v0, 0xbdd2d3e8, v211
	v_mul_f32_e32 v0, v15, v0
	v_exp_f32_e32 v0, v0
	v_ashrrev_i32_e32 v5, 31, v4
	v_lshlrev_b64 v[4:5], 9, v[4:5]
	v_lshl_add_u64 v[2:3], v[2:3], 0, v[4:5]
	v_add_f32_e32 v0, 1.0, v0
	v_rcp_f32_e32 v0, v0
	s_nop 0
	v_mul_f32_e32 v0, v15, v0
	v_cvt_pk_bf16_f32 v0, v0, s0
	global_store_short v[2:3], v0, off
	s_waitcnt lgkmcnt(0)
	v_readlane_b32 s0, v244, 24
	s_cmp_lt_i32 s10, s0
	s_cbranch_scc0 .LBB0_296

.LBB0_280:
	s_and_b32 s4, s17, 8
	v_mov_b64_e32 v[4:5], s[0:1]
	s_add_i32 s4, s4, s11
	v_mad_i64_i32 v[2:3], s[0:1], v2, s94, v[4:5]
	s_lshl_b32 s0, s4, 4
	s_ashr_i32 s1, s0, 31
	s_lshr_b32 s5, s6, 6
	v_lshl_add_u64 v[2:3], s[0:1], 1, v[2:3]
	s_mov_b64 s[6:7], 0xe001000
	v_lshl_add_u64 v[6:7], v[2:3], 0, s[6:7]
	v_add_co_u32_e32 v2, vcc, 0xe001000, v2
	s_mulk_i32 s5, 0x3e00
	s_nop 0
	v_addc_co_u32_e32 v3, vcc, 0, v3, vcc
	global_load_dwordx4 v[2:5], v[2:3], off
	s_nop 0
	global_load_dwordx4 v[6:9], v[6:7], off offset:16
	s_add_i32 s5, s5, 0
	v_mad_u32_u24 v0, v0, 48, s5
	v_mov_b32_e32 v62, v204
	s_add_i32 s6, s4, s21
	s_ashr_i32 s7, s6, 31
	s_lshl_b64 s[26:27], s[6:7], 13
	s_waitcnt vmcnt(0) lgkmcnt(0)
	ds_write_b128 v0, v[2:5]
	ds_write_b128 v0, v[6:9] offset:16
	v_mov_b32_e32 v0, s59
	s_waitcnt lgkmcnt(0)
	ds_read_b64 v[2:3], v0
	v_and_b32_e32 v61, 63, v62
	v_readfirstlane_b32 s5, v62
	s_lshr_b32 s5, s5, 6
	s_mulk_i32 s5, 0x3e00
	s_waitcnt lgkmcnt(0)
	v_readfirstlane_b32 s8, v2
	v_lshl_or_b32 v2, s6, 6, v61
	v_readfirstlane_b32 s9, v3
	v_ashrrev_i32_e32 v3, 31, v2
	s_add_i32 s28, s5, 0
	v_lshl_add_u64 v[2:3], v[2:3], 4, s[8:9]
	s_mov_b32 s5, 0x200000
	v_add_co_u32_e32 v2, vcc, s5, v2
	s_add_u32 s26, s8, s26
	v_and_b32_e32 v60, 15, v62
	v_addc_co_u32_e32 v3, vcc, 0, v3, vcc
	s_addc_u32 s27, s9, s27
	v_and_b32_e32 v0, 48, v62
	global_load_dwordx4 v[6:9], v[2:3], off
	v_lshl_add_u64 v[2:3], s[26:27], 0, v[0:1]
	v_lshlrev_b32_e32 v4, 6, v60
	v_mov_b32_e32 v5, v1
	v_lshl_add_u64 v[2:3], v[2:3], 0, v[4:5]
	s_mov_b32 s5, 0x240000
	s_waitcnt vmcnt(0) lgkmcnt(0)
	v_add_co_u32_e32 v8, vcc, s5, v2
	s_mov_b64 s[26:27], 0x240000
	s_nop 0
	v_addc_co_u32_e32 v9, vcc, 0, v3, vcc
	s_mov_b32 s5, 0x241000
	v_lshl_add_u64 v[4:5], v[2:3], 0, s[26:27]
	v_add_co_u32_e32 v2, vcc, s5, v2
	s_lshl_b64 s[6:7], s[6:7], 12
	s_nop 0
	v_addc_co_u32_e32 v3, vcc, 0, v3, vcc
	s_add_u32 s6, s8, s6
	global_load_dwordx4 v[52:55], v[8:9], off
	global_load_dwordx4 v[56:59], v[4:5], off offset:1024
	global_load_dwordx4 v[44:47], v[4:5], off offset:2048
	global_load_dwordx4 v[48:51], v[4:5], off offset:3072
	global_load_dwordx4 v[40:43], v[2:3], off
	global_load_dwordx4 v[36:39], v[2:3], off offset:1024
	global_load_dwordx4 v[32:35], v[2:3], off offset:2048
	global_load_dwordx4 v[28:31], v[2:3], off offset:3072
	s_addc_u32 s7, s9, s7
	v_lshlrev_b32_e32 v2, 8, v60
	v_mov_b32_e32 v3, v1
	v_lshl_add_u64 v[2:3], s[6:7], 0, v[2:3]
	v_lshl_add_u64 v[2:3], v[2:3], 0, v[0:1]
	s_mov_b64 s[6:7], 0x380000
	v_lshl_add_u64 v[4:5], v[2:3], 0, s[6:7]
	s_mov_b32 s5, 0x380000
	s_lshl_b32 s26, s20, 1
	s_mul_i32 s6, s20, 0x88
	s_ashr_i32 s27, s22, 31
	v_add_co_u32_e32 v2, vcc, s5, v2
	s_mul_hi_i32 s5, s26, 0x44
	s_add_u32 s6, s6, s22
	s_addc_u32 s7, s5, s27
	s_ashr_i32 s5, s4, 31
	s_lshl_b64 s[38:39], s[6:7], 10
	s_lshl_b64 s[6:7], s[4:5], 6
	s_add_u32 s5, s38, s6
	v_addc_co_u32_e32 v3, vcc, 0, v3, vcc
	s_addc_u32 s29, s39, s7
	global_load_dwordx4 v[24:27], v[2:3], off
	global_load_dwordx4 v[20:23], v[4:5], off offset:64
	global_load_dwordx4 v[16:19], v[4:5], off offset:128
	global_load_dwordx4 v[12:15], v[4:5], off offset:192
	v_or_b32_e32 v2, s5, v61
	v_mov_b32_e32 v3, s29
	v_lshl_add_u64 v[2:3], v[2:3], 3, s[8:9]
	v_add_co_u32_e32 v2, vcc, 0x1500000, v2
	v_mov_b32_e32 v8, 0
	s_nop 0
	v_addc_co_u32_e32 v3, vcc, 0, v3, vcc
	global_load_dwordx2 v[10:11], v[2:3], off
	v_add_u32_e32 v2, s28, v0
	v_cmp_gt_u32_e32 vcc, 32, v61
	v_mad_u32_u24 v95, v60, 48, v2
	v_mov_b32_e32 v2, 0
	v_mov_b32_e32 v3, 0
	v_mov_b32_e32 v4, 0
	v_mov_b32_e32 v5, 0
	s_and_saveexec_b64 s[8:9], vcc
	ds_read_b128 v[2:5], v95
	s_or_b64 exec, exec, s[8:9]
	s_waitcnt vmcnt(0) lgkmcnt(0)
	v_mfma_f32_16x16x32_bf16 v[64:67], v[2:5], v[52:55], 0
	v_bfe_u32 v9, v62, 4, 2
	v_lshlrev_b32_e32 v79, 2, v61
	v_mov_b32_e32 v61, s28
	v_mfma_f32_16x16x32_bf16 v[70:73], v[2:5], v[56:59], 0
	s_movk_i32 s5, 0x110
	v_lshlrev_b32_e32 v68, 2, v60
	v_mad_u32_u24 v112, v60, s5, v61
	v_mul_u32_u24_e32 v9, 0x840, v9
	v_mfma_f32_16x16x32_bf16 v[60:63], v[2:5], v[44:47], 0
	v_add3_u32 v9, s28, v68, v9
	v_add_u32_e32 v68, 0xc00, v9
	v_add_u32_e32 v69, 0x1000, v9
	v_mfma_f32_16x16x32_bf16 v[74:77], v[2:5], v[48:51], 0
	ds_write2_b32 v68, v64, v70 offset1:16
	ds_write2_b32 v68, v65, v71 offset0:132 offset1:148
	ds_write2_b32 v69, v66, v72 offset0:8 offset1:24
	v_mfma_f32_16x16x32_bf16 v[80:83], v[2:5], v[40:43], 0
	ds_write2_b32 v69, v67, v73 offset0:140 offset1:156
	s_nop 2
	ds_write2_b32 v68, v60, v74 offset0:32 offset1:48
	ds_write2_b32 v68, v61, v75 offset0:164 offset1:180
	v_add_u32_e32 v70, s28, v79
	v_mul_f32_e32 v9, v7, v11
	v_mfma_f32_16x16x32_bf16 v[64:67], v[2:5], v[36:39], 0
	ds_write2_b32 v69, v62, v76 offset0:40 offset1:56
	ds_write2_b32 v69, v63, v77 offset0:172 offset1:188
	s_nop 5
	ds_write2_b32 v68, v80, v64 offset0:64 offset1:80
	ds_write2_b32 v68, v81, v65 offset0:196 offset1:212
	ds_write2_b32 v69, v82, v66 offset0:72 offset1:88
	ds_write2_b32 v69, v83, v67 offset0:204 offset1:220
	v_mfma_f32_16x16x32_bf16 v[60:63], v[2:5], v[32:35], 0
	v_add_u32_e32 v71, 16, v70
	v_fma_f32 v9, v6, v10, -v9
	v_add_u32_e32 v72, 32, v70
	v_mfma_f32_16x16x32_bf16 v[2:5], v[2:5], v[28:31], 0
	s_nop 7
	ds_write2_b32 v68, v60, v2 offset0:96 offset1:112
	ds_write2_b32 v68, v61, v3 offset0:228 offset1:244
	ds_write2_b32 v69, v62, v4 offset0:104 offset1:120
	ds_write2_b32 v69, v63, v5 offset0:236 offset1:252
	s_waitcnt lgkmcnt(0)
	ds_read2st64_b32 v[2:3], v70 offset0:12 offset1:13
	ds_read2st64_b32 v[4:5], v71 offset0:14 offset1:15
	ds_read2st64_b32 v[60:61], v72 offset0:16 offset1:17
	v_add_u32_e32 v87, 0x2c00, v70
	v_add_u32_e32 v73, 48, v70
	s_waitcnt lgkmcnt(2)
	v_add_f32_e32 v2, v9, v2
	v_mul_f32_e32 v9, v7, v10
	v_fmac_f32_e32 v9, v6, v11
	v_add_f32_e32 v3, v9, v3
	v_cvt_pk_bf16_f32 v9, v2, v3
	v_mul_f32_e32 v10, v7, v3
	v_mul_f32_e32 v3, v6, v3
	v_fma_f32 v10, v6, v2, -v10
	v_fmac_f32_e32 v3, v7, v2
	s_waitcnt lgkmcnt(1)
	v_add_f32_e32 v4, v4, v10
	v_add_f32_e32 v2, v5, v3
	v_cvt_pk_bf16_f32 v3, v4, v2
	ds_write2_b32 v87, v9, v3 offset0:64 offset1:132
	v_mul_f32_e32 v3, v7, v2
	v_fma_f32 v3, v6, v4, -v3
	v_mul_f32_e32 v4, v7, v4
	ds_read2st64_b32 v[62:63], v73 offset0:18 offset1:19
	v_fmac_f32_e32 v4, v6, v2
	s_waitcnt lgkmcnt(2)
	v_add_f32_e32 v2, v61, v4
	v_add_f32_e32 v3, v60, v3
	v_mul_f32_e32 v5, v7, v2
	v_add_u32_e32 v74, 64, v70
	v_cvt_pk_bf16_f32 v4, v3, v2
	v_fma_f32 v5, v6, v3, -v5
	v_mul_f32_e32 v3, v7, v3
	ds_read2st64_b32 v[64:65], v74 offset0:20 offset1:21
	v_fmac_f32_e32 v3, v6, v2
	s_waitcnt lgkmcnt(1)
	v_add_f32_e32 v5, v62, v5
	v_add_f32_e32 v2, v63, v3
	v_cvt_pk_bf16_f32 v3, v5, v2
	v_add_u32_e32 v88, 0x2e00, v70
	v_add_u32_e32 v75, 0x50, v70
	ds_write2_b32 v88, v4, v3 offset0:72 offset1:140
	v_mul_f32_e32 v4, v7, v5
	ds_read2st64_b32 v[66:67], v75 offset0:22 offset1:23
	v_mul_f32_e32 v3, v7, v2
	v_fmac_f32_e32 v4, v6, v2
	v_fma_f32 v3, v6, v5, -v3
	s_waitcnt lgkmcnt(2)
	v_add_f32_e32 v2, v65, v4
	v_add_f32_e32 v3, v64, v3
	v_mul_f32_e32 v5, v7, v2
	v_add_u32_e32 v76, 0x60, v70
	v_cvt_pk_bf16_f32 v4, v3, v2
	v_fma_f32 v5, v6, v3, -v5
	v_mul_f32_e32 v3, v7, v3
	ds_read2st64_b32 v[90:91], v76 offset0:24 offset1:25
	v_fmac_f32_e32 v3, v6, v2
	s_waitcnt lgkmcnt(1)
	v_add_f32_e32 v5, v66, v5
	v_add_f32_e32 v2, v67, v3
	v_cvt_pk_bf16_f32 v3, v5, v2
	v_add_u32_e32 v89, 0x3000, v70
	v_add_u32_e32 v77, 0x70, v70
	ds_write2_b32 v89, v4, v3 offset0:80 offset1:148
	v_mul_f32_e32 v4, v7, v5
	ds_read2st64_b32 v[92:93], v77 offset0:26 offset1:27
	v_mul_f32_e32 v3, v7, v2
	v_fmac_f32_e32 v4, v6, v2
	v_fma_f32 v3, v6, v5, -v3
	s_waitcnt lgkmcnt(2)
	v_add_f32_e32 v2, v91, v4
	v_add_f32_e32 v3, v90, v3
	v_mul_f32_e32 v5, v7, v2
	v_add_u32_e32 v79, 0x80, v70
	v_cvt_pk_bf16_f32 v4, v3, v2
	v_fma_f32 v5, v6, v3, -v5
	v_mul_f32_e32 v3, v7, v3
	ds_read2st64_b32 v[96:97], v79 offset0:28 offset1:29
	v_fmac_f32_e32 v3, v6, v2
	s_waitcnt lgkmcnt(1)
	v_add_f32_e32 v5, v92, v5
	v_add_f32_e32 v2, v93, v3
	v_cvt_pk_bf16_f32 v3, v5, v2
	v_add_u32_e32 v90, 0x3200, v70
	v_add_u32_e32 v80, 0x90, v70
	ds_write2_b32 v90, v4, v3 offset0:88 offset1:156
	v_mul_f32_e32 v4, v7, v5
	ds_read2st64_b32 v[98:99], v80 offset0:30 offset1:31
	v_mul_f32_e32 v3, v7, v2
	v_fmac_f32_e32 v4, v6, v2
	v_fma_f32 v3, v6, v5, -v3
	s_waitcnt lgkmcnt(2)
	v_add_f32_e32 v2, v97, v4
	v_add_f32_e32 v3, v96, v3
	v_mul_f32_e32 v5, v7, v2
	v_add_u32_e32 v81, 0xa0, v70
	v_cvt_pk_bf16_f32 v4, v3, v2
	v_fma_f32 v5, v6, v3, -v5
	v_mul_f32_e32 v3, v7, v3
	ds_read2st64_b32 v[100:101], v81 offset0:32 offset1:33
	v_fmac_f32_e32 v3, v6, v2
	s_waitcnt lgkmcnt(1)
	v_add_f32_e32 v5, v98, v5
	v_add_f32_e32 v2, v99, v3
	v_cvt_pk_bf16_f32 v3, v5, v2
	v_add_u32_e32 v91, 0x3400, v70
	v_add_u32_e32 v82, 0xb0, v70
	ds_write2_b32 v91, v4, v3 offset0:96 offset1:164
	v_mul_f32_e32 v4, v7, v5
	ds_read2st64_b32 v[102:103], v82 offset0:34 offset1:35
	v_mul_f32_e32 v3, v7, v2
	v_fmac_f32_e32 v4, v6, v2
	v_fma_f32 v3, v6, v5, -v3
	s_waitcnt lgkmcnt(2)
	v_add_f32_e32 v2, v101, v4
	v_add_f32_e32 v3, v100, v3
	v_mul_f32_e32 v5, v7, v2
	v_add_u32_e32 v83, 0xc0, v70
	v_cvt_pk_bf16_f32 v4, v3, v2
	v_fma_f32 v5, v6, v3, -v5
	v_mul_f32_e32 v3, v7, v3
	ds_read2st64_b32 v[104:105], v83 offset0:36 offset1:37
	v_fmac_f32_e32 v3, v6, v2
	s_waitcnt lgkmcnt(1)
	v_add_f32_e32 v5, v102, v5
	v_add_f32_e32 v2, v103, v3
	v_cvt_pk_bf16_f32 v3, v5, v2
	v_add_u32_e32 v92, 0x3600, v70
	v_add_u32_e32 v84, 0xd0, v70
	ds_write2_b32 v92, v4, v3 offset0:104 offset1:172
	v_mul_f32_e32 v4, v7, v5
	ds_read2st64_b32 v[106:107], v84 offset0:38 offset1:39
	v_mul_f32_e32 v3, v7, v2
	v_fmac_f32_e32 v4, v6, v2
	v_fma_f32 v3, v6, v5, -v3
	s_waitcnt lgkmcnt(2)
	v_add_f32_e32 v2, v105, v4
	v_add_f32_e32 v3, v104, v3
	v_mul_f32_e32 v5, v7, v2
	v_add_u32_e32 v85, 0xe0, v70
	v_cvt_pk_bf16_f32 v4, v3, v2
	v_fma_f32 v5, v6, v3, -v5
	v_mul_f32_e32 v3, v7, v3
	ds_read2st64_b32 v[108:109], v85 offset0:40 offset1:41
	v_fmac_f32_e32 v3, v6, v2
	s_waitcnt lgkmcnt(1)
	v_add_f32_e32 v5, v106, v5
	v_add_f32_e32 v2, v107, v3
	v_cvt_pk_bf16_f32 v3, v5, v2
	v_add_u32_e32 v93, 0x3800, v70
	v_add_u32_e32 v86, 0xf0, v70
	ds_write2_b32 v93, v4, v3 offset0:112 offset1:180
	v_mul_f32_e32 v4, v7, v5
	ds_read2st64_b32 v[110:111], v86 offset0:42 offset1:43
	v_mul_f32_e32 v3, v7, v2
	v_fmac_f32_e32 v4, v6, v2
	v_fma_f32 v3, v6, v5, -v3
	s_waitcnt lgkmcnt(2)
	v_add_f32_e32 v2, v109, v4
	v_add_f32_e32 v3, v108, v3
	v_mul_f32_e32 v5, v7, v2
	v_cvt_pk_bf16_f32 v4, v3, v2
	v_fma_f32 v5, v6, v3, -v5
	v_mul_f32_e32 v3, v7, v3
	v_fmac_f32_e32 v3, v6, v2
	s_waitcnt lgkmcnt(0)
	v_add_f32_e32 v60, v110, v5
	v_add_f32_e32 v61, v111, v3
	v_cvt_pk_bf16_f32 v2, v60, v61
	v_add_u32_e32 v94, 0x3a00, v70
	ds_write2_b32 v94, v4, v2 offset0:120 offset1:188
	s_waitcnt lgkmcnt(0)
	v_add_u32_e32 v0, v112, v0
	ds_read_b128 v[2:5], v0 offset:11520
	ds_read_b128 v[62:65], v0 offset:11584
	s_waitcnt lgkmcnt(1)
	v_mfma_f32_16x16x32_bf16 v[2:5], v[2:5], v[24:27], 0
	ds_read_b128 v[96:99], v0 offset:11648
	v_mov_b32_e32 v9, 0
	v_mov_b32_e32 v10, 0
	s_waitcnt lgkmcnt(1)
	v_mfma_f32_16x16x32_bf16 v[2:5], v[62:65], v[20:23], v[2:5]
	ds_read_b128 v[62:65], v0 offset:11712
	v_mov_b32_e32 v11, 0
	s_waitcnt lgkmcnt(1)
	v_mfma_f32_16x16x32_bf16 v[2:5], v[96:99], v[16:19], v[2:5]
	s_waitcnt lgkmcnt(0)
	v_mfma_f32_16x16x32_bf16 v[2:5], v[62:65], v[12:15], v[2:5]
	s_and_saveexec_b64 s[8:9], vcc
	ds_read_b128 v[8:11], v95 offset:768
	s_or_b64 exec, exec, s[8:9]
	s_waitcnt lgkmcnt(0)
	v_mfma_f32_16x16x32_bf16 v[62:65], v[8:11], v[52:55], 0
	v_mul_f32_e32 v118, v7, v61
	v_fma_f32 v118, v6, v60, -v118
	v_mul_f32_e32 v60, v7, v60
	v_mfma_f32_16x16x32_bf16 v[96:99], v[8:11], v[56:59], 0
	s_nop 7
	ds_write2_b32 v68, v62, v96 offset1:16
	ds_write2_b32 v68, v63, v97 offset0:132 offset1:148
	ds_write2_b32 v69, v64, v98 offset0:8 offset1:24
	v_mfma_f32_16x16x32_bf16 v[100:103], v[8:11], v[44:47], 0
	v_fmac_f32_e32 v60, v6, v61
	v_mfma_f32_16x16x32_bf16 v[104:107], v[8:11], v[48:51], 0
	ds_write2_b32 v69, v65, v99 offset0:140 offset1:156
	s_nop 6
	ds_write2_b32 v68, v100, v104 offset0:32 offset1:48
	ds_write2_b32 v68, v101, v105 offset0:164 offset1:180
	v_mfma_f32_16x16x32_bf16 v[108:111], v[8:11], v[40:43], 0
	v_mfma_f32_16x16x32_bf16 v[62:65], v[8:11], v[36:39], 0
	ds_write2_b32 v69, v102, v106 offset0:40 offset1:56
	ds_write2_b32 v69, v103, v107 offset0:172 offset1:188
	s_nop 5
	ds_write2_b32 v68, v108, v62 offset0:64 offset1:80
	ds_write2_b32 v68, v109, v63 offset0:196 offset1:212
	ds_write2_b32 v69, v110, v64 offset0:72 offset1:88
	ds_write2_b32 v69, v111, v65 offset0:204 offset1:220
	v_mfma_f32_16x16x32_bf16 v[96:99], v[8:11], v[32:35], 0
	v_mfma_f32_16x16x32_bf16 v[8:11], v[8:11], v[28:31], 0
	s_nop 7
	ds_write2_b32 v68, v96, v8 offset0:96 offset1:112
	ds_write2_b32 v68, v97, v9 offset0:228 offset1:244
	ds_write2_b32 v69, v98, v10 offset0:104 offset1:120
	ds_write2_b32 v69, v99, v11 offset0:236 offset1:252
	s_waitcnt lgkmcnt(0)
	ds_read2st64_b32 v[8:9], v70 offset0:12 offset1:13
	ds_read2st64_b32 v[10:11], v71 offset0:14 offset1:15
	ds_read2st64_b32 v[62:63], v72 offset0:16 offset1:17
	ds_read2st64_b32 v[64:65], v73 offset0:18 offset1:19
	ds_read2st64_b32 v[66:67], v74 offset0:20 offset1:21
	ds_read2st64_b32 v[96:97], v75 offset0:22 offset1:23
	ds_read2st64_b32 v[98:99], v76 offset0:24 offset1:25
	ds_read2st64_b32 v[100:101], v77 offset0:26 offset1:27
	ds_read2st64_b32 v[102:103], v79 offset0:28 offset1:29
	ds_read2st64_b32 v[104:105], v80 offset0:30 offset1:31
	ds_read2st64_b32 v[106:107], v81 offset0:32 offset1:33
	ds_read2st64_b32 v[108:109], v82 offset0:34 offset1:35
	ds_read2st64_b32 v[110:111], v83 offset0:36 offset1:37
	ds_read2st64_b32 v[112:113], v84 offset0:38 offset1:39
	ds_read2st64_b32 v[114:115], v85 offset0:40 offset1:41
	ds_read2st64_b32 v[116:117], v86 offset0:42 offset1:43
	s_waitcnt lgkmcnt(14)
	v_add_f32_e32 v8, v118, v8
	v_add_f32_e32 v9, v60, v9
	v_cvt_pk_bf16_f32 v60, v8, v9
	v_mul_f32_e32 v61, v7, v9
	v_mul_f32_e32 v9, v6, v9
	v_fma_f32 v61, v6, v8, -v61
	v_fmac_f32_e32 v9, v7, v8
	v_add_f32_e32 v10, v10, v61
	v_add_f32_e32 v8, v11, v9
	v_cvt_pk_bf16_f32 v9, v10, v8
	ds_write2_b32 v87, v60, v9 offset0:64 offset1:132
	v_mul_f32_e32 v9, v7, v8
	v_fma_f32 v9, v6, v10, -v9
	v_mul_f32_e32 v10, v7, v10
	v_fmac_f32_e32 v10, v6, v8
	s_waitcnt lgkmcnt(14)
	v_add_f32_e32 v8, v63, v10
	v_add_f32_e32 v9, v62, v9
	v_mul_f32_e32 v11, v7, v8
	v_cvt_pk_bf16_f32 v10, v9, v8
	v_fma_f32 v11, v6, v9, -v11
	v_mul_f32_e32 v9, v7, v9
	v_fmac_f32_e32 v9, v6, v8
	s_waitcnt lgkmcnt(13)
	v_add_f32_e32 v11, v64, v11
	v_add_f32_e32 v8, v65, v9
	v_cvt_pk_bf16_f32 v9, v11, v8
	ds_write2_b32 v88, v10, v9 offset0:72 offset1:140
	v_mul_f32_e32 v10, v7, v11
	v_mul_f32_e32 v9, v7, v8
	v_fmac_f32_e32 v10, v6, v8
	v_fma_f32 v9, v6, v11, -v9
	s_waitcnt lgkmcnt(13)
	v_add_f32_e32 v8, v67, v10
	v_add_f32_e32 v9, v66, v9
	v_mul_f32_e32 v11, v7, v8
	v_cvt_pk_bf16_f32 v10, v9, v8
	v_fma_f32 v11, v6, v9, -v11
	v_mul_f32_e32 v9, v7, v9
	v_fmac_f32_e32 v9, v6, v8
	s_waitcnt lgkmcnt(12)
	v_add_f32_e32 v11, v96, v11
	v_add_f32_e32 v8, v97, v9
	v_cvt_pk_bf16_f32 v9, v11, v8
	ds_write2_b32 v89, v10, v9 offset0:80 offset1:148
	v_mul_f32_e32 v10, v7, v11
	v_mul_f32_e32 v9, v7, v8
	v_fmac_f32_e32 v10, v6, v8
	v_fma_f32 v9, v6, v11, -v9
	s_waitcnt lgkmcnt(12)
	v_add_f32_e32 v8, v99, v10
	v_add_f32_e32 v9, v98, v9
	v_mul_f32_e32 v11, v7, v8
	v_cvt_pk_bf16_f32 v10, v9, v8
	v_fma_f32 v11, v6, v9, -v11
	v_mul_f32_e32 v9, v7, v9
	v_fmac_f32_e32 v9, v6, v8
	s_waitcnt lgkmcnt(11)
	v_add_f32_e32 v11, v100, v11
	v_add_f32_e32 v8, v101, v9
	v_cvt_pk_bf16_f32 v9, v11, v8
	ds_write2_b32 v90, v10, v9 offset0:88 offset1:156
	v_mul_f32_e32 v10, v7, v11
	v_mul_f32_e32 v9, v7, v8
	v_fmac_f32_e32 v10, v6, v8
	v_fma_f32 v9, v6, v11, -v9
	s_waitcnt lgkmcnt(11)
	v_add_f32_e32 v8, v103, v10
	v_add_f32_e32 v9, v102, v9
	v_mul_f32_e32 v11, v7, v8
	v_cvt_pk_bf16_f32 v10, v9, v8
	v_fma_f32 v11, v6, v9, -v11
	v_mul_f32_e32 v9, v7, v9
	v_fmac_f32_e32 v9, v6, v8
	s_waitcnt lgkmcnt(10)
	v_add_f32_e32 v11, v104, v11
	v_add_f32_e32 v8, v105, v9
	v_cvt_pk_bf16_f32 v9, v11, v8
	ds_write2_b32 v91, v10, v9 offset0:96 offset1:164
	v_mul_f32_e32 v10, v7, v11
	v_mul_f32_e32 v9, v7, v8
	v_fmac_f32_e32 v10, v6, v8
	v_fma_f32 v9, v6, v11, -v9
	s_waitcnt lgkmcnt(10)
	v_add_f32_e32 v8, v107, v10
	v_add_f32_e32 v9, v106, v9
	v_mul_f32_e32 v11, v7, v8
	v_cvt_pk_bf16_f32 v10, v9, v8
	v_fma_f32 v11, v6, v9, -v11
	v_mul_f32_e32 v9, v7, v9
	v_fmac_f32_e32 v9, v6, v8
	s_waitcnt lgkmcnt(9)
	v_add_f32_e32 v11, v108, v11
	v_add_f32_e32 v8, v109, v9
	v_cvt_pk_bf16_f32 v9, v11, v8
	ds_write2_b32 v92, v10, v9 offset0:104 offset1:172
	v_mul_f32_e32 v10, v7, v11
	v_mul_f32_e32 v9, v7, v8
	v_fmac_f32_e32 v10, v6, v8
	v_fma_f32 v9, v6, v11, -v9
	s_waitcnt lgkmcnt(9)
	v_add_f32_e32 v8, v111, v10
	v_add_f32_e32 v9, v110, v9
	v_mul_f32_e32 v11, v7, v8
	v_cvt_pk_bf16_f32 v10, v9, v8
	v_fma_f32 v11, v6, v9, -v11
	v_mul_f32_e32 v9, v7, v9
	v_fmac_f32_e32 v9, v6, v8
	s_waitcnt lgkmcnt(8)
	v_add_f32_e32 v11, v112, v11
	v_add_f32_e32 v8, v113, v9
	v_cvt_pk_bf16_f32 v9, v11, v8
	ds_write2_b32 v93, v10, v9 offset0:112 offset1:180
	v_mul_f32_e32 v10, v7, v11
	v_mul_f32_e32 v9, v7, v8
	v_fmac_f32_e32 v10, v6, v8
	v_fma_f32 v9, v6, v11, -v9
	s_waitcnt lgkmcnt(8)
	v_add_f32_e32 v8, v115, v10
	v_add_f32_e32 v9, v114, v9
	v_mul_f32_e32 v11, v7, v8
	v_cvt_pk_bf16_f32 v10, v9, v8
	v_fma_f32 v11, v6, v9, -v11
	v_mul_f32_e32 v9, v7, v9
	v_fmac_f32_e32 v9, v6, v8
	s_waitcnt lgkmcnt(7)
	v_add_f32_e32 v65, v116, v11
	v_add_f32_e32 v66, v117, v9
	v_cvt_pk_bf16_f32 v8, v65, v66
	ds_write2_b32 v94, v10, v8 offset0:120 offset1:188
	s_waitcnt lgkmcnt(0)
	ds_read_b128 v[8:11], v0 offset:11520
	ds_read_b128 v[60:63], v0 offset:11584
	s_waitcnt lgkmcnt(1)
	v_mfma_f32_16x16x32_bf16 v[8:11], v[8:11], v[24:27], 0
	ds_read_b128 v[96:99], v0 offset:11648
	v_mov_b32_e32 v64, 0
	s_waitcnt lgkmcnt(1)
	v_mfma_f32_16x16x32_bf16 v[8:11], v[60:63], v[20:23], v[8:11]
	ds_read_b128 v[60:63], v0 offset:11712
	s_waitcnt lgkmcnt(1)
	v_mfma_f32_16x16x32_bf16 v[8:11], v[96:99], v[16:19], v[8:11]
	s_waitcnt lgkmcnt(0)
	v_mfma_f32_16x16x32_bf16 v[8:11], v[60:63], v[12:15], v[8:11]
	v_mov_b32_e32 v60, 0
	v_mov_b32_e32 v61, 0
	v_mov_b32_e32 v62, 0
	v_mov_b32_e32 v63, 0
	s_and_saveexec_b64 s[8:9], vcc
	ds_read_b128 v[60:63], v95 offset:1536
	s_or_b64 exec, exec, s[8:9]
	s_waitcnt lgkmcnt(0)
	v_mfma_f32_16x16x32_bf16 v[96:99], v[60:63], v[52:55], 0
	v_mul_f32_e32 v67, v7, v66
	v_fma_f32 v67, v6, v65, -v67
	v_mul_f32_e32 v65, v7, v65
	v_mfma_f32_16x16x32_bf16 v[100:103], v[60:63], v[56:59], 0
	s_nop 7
	ds_write2_b32 v68, v96, v100 offset1:16
	ds_write2_b32 v68, v97, v101 offset0:132 offset1:148
	ds_write2_b32 v69, v98, v102 offset0:8 offset1:24
	v_mfma_f32_16x16x32_bf16 v[104:107], v[60:63], v[44:47], 0
	v_fmac_f32_e32 v65, v6, v66
	v_mfma_f32_16x16x32_bf16 v[108:111], v[60:63], v[48:51], 0
	ds_write2_b32 v69, v99, v103 offset0:140 offset1:156
	s_nop 6
	ds_write2_b32 v68, v104, v108 offset0:32 offset1:48
	ds_write2_b32 v68, v105, v109 offset0:164 offset1:180
	v_mfma_f32_16x16x32_bf16 v[112:115], v[60:63], v[40:43], 0
	v_mfma_f32_16x16x32_bf16 v[96:99], v[60:63], v[36:39], 0
	ds_write2_b32 v69, v106, v110 offset0:40 offset1:56
	ds_write2_b32 v69, v107, v111 offset0:172 offset1:188
	s_nop 5
	ds_write2_b32 v68, v112, v96 offset0:64 offset1:80
	ds_write2_b32 v68, v113, v97 offset0:196 offset1:212
	ds_write2_b32 v69, v114, v98 offset0:72 offset1:88
	ds_write2_b32 v69, v115, v99 offset0:204 offset1:220
	v_mfma_f32_16x16x32_bf16 v[100:103], v[60:63], v[32:35], 0
	v_mfma_f32_16x16x32_bf16 v[60:63], v[60:63], v[28:31], 0
	s_nop 7
	ds_write2_b32 v68, v100, v60 offset0:96 offset1:112
	ds_write2_b32 v68, v101, v61 offset0:228 offset1:244
	ds_write2_b32 v69, v102, v62 offset0:104 offset1:120
	ds_write2_b32 v69, v103, v63 offset0:236 offset1:252
	s_waitcnt lgkmcnt(0)
	ds_read2st64_b32 v[60:61], v70 offset0:12 offset1:13
	ds_read2st64_b32 v[62:63], v71 offset0:14 offset1:15
	ds_read2st64_b32 v[96:97], v72 offset0:16 offset1:17
	ds_read2st64_b32 v[98:99], v73 offset0:18 offset1:19
	ds_read2st64_b32 v[100:101], v74 offset0:20 offset1:21
	ds_read2st64_b32 v[102:103], v75 offset0:22 offset1:23
	ds_read2st64_b32 v[104:105], v76 offset0:24 offset1:25
	ds_read2st64_b32 v[106:107], v77 offset0:26 offset1:27
	ds_read2st64_b32 v[108:109], v79 offset0:28 offset1:29
	ds_read2st64_b32 v[110:111], v80 offset0:30 offset1:31
	ds_read2st64_b32 v[112:113], v81 offset0:32 offset1:33
	ds_read2st64_b32 v[114:115], v82 offset0:34 offset1:35
	ds_read2st64_b32 v[116:117], v83 offset0:36 offset1:37
	ds_read2st64_b32 v[118:119], v84 offset0:38 offset1:39
	ds_read2st64_b32 v[120:121], v85 offset0:40 offset1:41
	ds_read2st64_b32 v[122:123], v86 offset0:42 offset1:43
	s_waitcnt lgkmcnt(14)
	v_add_f32_e32 v60, v67, v60
	v_add_f32_e32 v61, v65, v61
	v_cvt_pk_bf16_f32 v65, v60, v61
	v_mul_f32_e32 v66, v7, v61
	v_mul_f32_e32 v61, v6, v61
	v_fma_f32 v66, v6, v60, -v66
	v_fmac_f32_e32 v61, v7, v60
	v_add_f32_e32 v62, v62, v66
	v_add_f32_e32 v60, v63, v61
	v_cvt_pk_bf16_f32 v61, v62, v60
	ds_write2_b32 v87, v65, v61 offset0:64 offset1:132
	v_mul_f32_e32 v61, v7, v60
	v_fma_f32 v61, v6, v62, -v61
	v_mul_f32_e32 v62, v7, v62
	v_fmac_f32_e32 v62, v6, v60
	s_waitcnt lgkmcnt(14)
	v_add_f32_e32 v60, v97, v62
	v_add_f32_e32 v61, v96, v61
	v_mul_f32_e32 v63, v7, v60
	v_cvt_pk_bf16_f32 v62, v61, v60
	v_fma_f32 v63, v6, v61, -v63
	v_mul_f32_e32 v61, v7, v61
	v_fmac_f32_e32 v61, v6, v60
	s_waitcnt lgkmcnt(13)
	v_add_f32_e32 v63, v98, v63
	v_add_f32_e32 v60, v99, v61
	v_cvt_pk_bf16_f32 v61, v63, v60
	ds_write2_b32 v88, v62, v61 offset0:72 offset1:140
	v_mul_f32_e32 v62, v7, v63
	v_mul_f32_e32 v61, v7, v60
	v_fmac_f32_e32 v62, v6, v60
	v_fma_f32 v61, v6, v63, -v61
	s_waitcnt lgkmcnt(13)
	v_add_f32_e32 v60, v101, v62
	v_add_f32_e32 v61, v100, v61
	v_mul_f32_e32 v63, v7, v60
	v_cvt_pk_bf16_f32 v62, v61, v60
	v_fma_f32 v63, v6, v61, -v63
	v_mul_f32_e32 v61, v7, v61
	v_fmac_f32_e32 v61, v6, v60
	s_waitcnt lgkmcnt(12)
	v_add_f32_e32 v63, v102, v63
	v_add_f32_e32 v60, v103, v61
	v_cvt_pk_bf16_f32 v61, v63, v60
	ds_write2_b32 v89, v62, v61 offset0:80 offset1:148
	v_mul_f32_e32 v62, v7, v63
	v_mul_f32_e32 v61, v7, v60
	v_fmac_f32_e32 v62, v6, v60
	v_fma_f32 v61, v6, v63, -v61
	s_waitcnt lgkmcnt(12)
	v_add_f32_e32 v60, v105, v62
	v_add_f32_e32 v61, v104, v61
	v_mul_f32_e32 v63, v7, v60
	v_cvt_pk_bf16_f32 v62, v61, v60
	v_fma_f32 v63, v6, v61, -v63
	v_mul_f32_e32 v61, v7, v61
	v_fmac_f32_e32 v61, v6, v60
	s_waitcnt lgkmcnt(11)
	v_add_f32_e32 v63, v106, v63
	v_add_f32_e32 v60, v107, v61
	v_cvt_pk_bf16_f32 v61, v63, v60
	ds_write2_b32 v90, v62, v61 offset0:88 offset1:156
	v_mul_f32_e32 v62, v7, v63
	v_mul_f32_e32 v61, v7, v60
	v_fmac_f32_e32 v62, v6, v60
	v_fma_f32 v61, v6, v63, -v61
	s_waitcnt lgkmcnt(11)
	v_add_f32_e32 v60, v109, v62
	v_add_f32_e32 v61, v108, v61
	v_mul_f32_e32 v63, v7, v60
	v_cvt_pk_bf16_f32 v62, v61, v60
	v_fma_f32 v63, v6, v61, -v63
	v_mul_f32_e32 v61, v7, v61
	v_fmac_f32_e32 v61, v6, v60
	s_waitcnt lgkmcnt(10)
	v_add_f32_e32 v63, v110, v63
	v_add_f32_e32 v60, v111, v61
	v_cvt_pk_bf16_f32 v61, v63, v60
	ds_write2_b32 v91, v62, v61 offset0:96 offset1:164
	v_mul_f32_e32 v62, v7, v63
	v_mul_f32_e32 v61, v7, v60
	v_fmac_f32_e32 v62, v6, v60
	v_fma_f32 v61, v6, v63, -v61
	s_waitcnt lgkmcnt(10)
	v_add_f32_e32 v60, v113, v62
	v_add_f32_e32 v61, v112, v61
	v_mul_f32_e32 v63, v7, v60
	v_cvt_pk_bf16_f32 v62, v61, v60
	v_fma_f32 v63, v6, v61, -v63
	v_mul_f32_e32 v61, v7, v61
	v_fmac_f32_e32 v61, v6, v60
	s_waitcnt lgkmcnt(9)
	v_add_f32_e32 v63, v114, v63
	v_add_f32_e32 v60, v115, v61
	v_cvt_pk_bf16_f32 v61, v63, v60
	ds_write2_b32 v92, v62, v61 offset0:104 offset1:172
	v_mul_f32_e32 v62, v7, v63
	v_mul_f32_e32 v61, v7, v60
	v_fmac_f32_e32 v62, v6, v60
	v_fma_f32 v61, v6, v63, -v61
	s_waitcnt lgkmcnt(9)
	v_add_f32_e32 v60, v117, v62
	v_add_f32_e32 v61, v116, v61
	v_mul_f32_e32 v63, v7, v60
	v_cvt_pk_bf16_f32 v62, v61, v60
	v_fma_f32 v63, v6, v61, -v63
	v_mul_f32_e32 v61, v7, v61
	v_fmac_f32_e32 v61, v6, v60
	s_waitcnt lgkmcnt(8)
	v_add_f32_e32 v63, v118, v63
	v_add_f32_e32 v60, v119, v61
	v_cvt_pk_bf16_f32 v61, v63, v60
	ds_write2_b32 v93, v62, v61 offset0:112 offset1:180
	v_mul_f32_e32 v62, v7, v63
	v_mul_f32_e32 v61, v7, v60
	v_fmac_f32_e32 v62, v6, v60
	v_fma_f32 v61, v6, v63, -v61
	s_waitcnt lgkmcnt(8)
	v_add_f32_e32 v60, v121, v62
	v_add_f32_e32 v61, v120, v61
	v_mul_f32_e32 v63, v7, v60
	v_cvt_pk_bf16_f32 v62, v61, v60
	v_fma_f32 v63, v6, v61, -v63
	v_mul_f32_e32 v61, v7, v61
	v_fmac_f32_e32 v61, v6, v60
	s_waitcnt lgkmcnt(7)
	v_add_f32_e32 v96, v122, v63
	v_add_f32_e32 v97, v123, v61
	v_cvt_pk_bf16_f32 v60, v96, v97
	ds_write2_b32 v94, v62, v60 offset0:120 offset1:188
	s_waitcnt lgkmcnt(0)
	ds_read_b128 v[60:63], v0 offset:11520
	ds_read_b128 v[98:101], v0 offset:11584
	s_waitcnt lgkmcnt(1)
	v_mfma_f32_16x16x32_bf16 v[60:63], v[60:63], v[24:27], 0
	ds_read_b128 v[102:105], v0 offset:11648
	v_mov_b32_e32 v65, 0
	v_mov_b32_e32 v66, 0
	s_waitcnt lgkmcnt(1)
	v_mfma_f32_16x16x32_bf16 v[60:63], v[98:101], v[20:23], v[60:63]
	ds_read_b128 v[98:101], v0 offset:11712
	v_mov_b32_e32 v67, 0
	s_waitcnt lgkmcnt(1)
	v_mfma_f32_16x16x32_bf16 v[60:63], v[102:105], v[16:19], v[60:63]
	s_waitcnt lgkmcnt(0)
	v_mfma_f32_16x16x32_bf16 v[60:63], v[98:101], v[12:15], v[60:63]
	s_and_saveexec_b64 s[8:9], vcc
	ds_read_b128 v[64:67], v95 offset:2304
	s_or_b64 exec, exec, s[8:9]
	s_waitcnt lgkmcnt(0)
	v_mfma_f32_16x16x32_bf16 v[52:55], v[64:67], v[52:55], 0
	s_mov_b32 s9, 0x200000
	v_mfma_f32_16x16x32_bf16 v[56:59], v[64:67], v[56:59], 0
	s_nop 7
	ds_write2_b32 v68, v52, v56 offset1:16
	ds_write2_b32 v68, v53, v57 offset0:132 offset1:148
	ds_write2_b32 v69, v54, v58 offset0:8 offset1:24
	ds_write2_b32 v69, v55, v59 offset0:140 offset1:156
	v_mfma_f32_16x16x32_bf16 v[44:47], v[64:67], v[44:47], 0
	v_mfma_f32_16x16x32_bf16 v[48:51], v[64:67], v[48:51], 0
	s_nop 7
	ds_write2_b32 v68, v44, v48 offset0:32 offset1:48
	ds_write2_b32 v68, v45, v49 offset0:164 offset1:180
	ds_write2_b32 v69, v46, v50 offset0:40 offset1:56
	ds_write2_b32 v69, v47, v51 offset0:172 offset1:188
	v_mfma_f32_16x16x32_bf16 v[40:43], v[64:67], v[40:43], 0
	v_mfma_f32_16x16x32_bf16 v[36:39], v[64:67], v[36:39], 0
	s_nop 7
	ds_write2_b32 v68, v40, v36 offset0:64 offset1:80
	ds_write2_b32 v68, v41, v37 offset0:196 offset1:212
	ds_write2_b32 v69, v42, v38 offset0:72 offset1:88
	ds_write2_b32 v69, v43, v39 offset0:204 offset1:220
	v_mfma_f32_16x16x32_bf16 v[32:35], v[64:67], v[32:35], 0
	v_mfma_f32_16x16x32_bf16 v[28:31], v[64:67], v[28:31], 0
	s_nop 7
	ds_write2_b32 v68, v32, v28 offset0:96 offset1:112
	ds_write2_b32 v68, v33, v29 offset0:228 offset1:244
	ds_write2_b32 v69, v34, v30 offset0:104 offset1:120
	ds_write2_b32 v69, v35, v31 offset0:236 offset1:252
	s_waitcnt lgkmcnt(0)
	v_mul_f32_e32 v64, v7, v97
	ds_read2st64_b32 v[28:29], v70 offset0:12 offset1:13
	ds_read2st64_b32 v[30:31], v71 offset0:14 offset1:15
	ds_read2st64_b32 v[32:33], v72 offset0:16 offset1:17
	ds_read2st64_b32 v[34:35], v73 offset0:18 offset1:19
	ds_read2st64_b32 v[36:37], v74 offset0:20 offset1:21
	ds_read2st64_b32 v[38:39], v75 offset0:22 offset1:23
	ds_read2st64_b32 v[40:41], v76 offset0:24 offset1:25
	ds_read2st64_b32 v[42:43], v77 offset0:26 offset1:27
	ds_read2st64_b32 v[44:45], v79 offset0:28 offset1:29
	ds_read2st64_b32 v[46:47], v80 offset0:30 offset1:31
	ds_read2st64_b32 v[48:49], v81 offset0:32 offset1:33
	ds_read2st64_b32 v[50:51], v82 offset0:34 offset1:35
	ds_read2st64_b32 v[52:53], v83 offset0:36 offset1:37
	ds_read2st64_b32 v[54:55], v84 offset0:38 offset1:39
	ds_read2st64_b32 v[56:57], v85 offset0:40 offset1:41
	ds_read2st64_b32 v[58:59], v86 offset0:42 offset1:43
	v_fma_f32 v64, v6, v96, -v64
	s_waitcnt lgkmcnt(14)
	v_add_f32_e32 v28, v64, v28
	v_mul_f32_e32 v64, v7, v96
	v_fmac_f32_e32 v64, v6, v97
	v_add_f32_e32 v29, v64, v29
	v_cvt_pk_bf16_f32 v64, v28, v29
	v_mul_f32_e32 v65, v7, v29
	v_mul_f32_e32 v29, v6, v29
	v_fma_f32 v65, v6, v28, -v65
	v_fmac_f32_e32 v29, v7, v28
	v_add_f32_e32 v30, v30, v65
	v_add_f32_e32 v28, v31, v29
	v_cvt_pk_bf16_f32 v29, v30, v28
	ds_write2_b32 v87, v64, v29 offset0:64 offset1:132
	v_mul_f32_e32 v29, v7, v28
	v_fma_f32 v29, v6, v30, -v29
	v_mul_f32_e32 v30, v7, v30
	v_fmac_f32_e32 v30, v6, v28
	s_waitcnt lgkmcnt(14)
	v_add_f32_e32 v28, v33, v30
	v_add_f32_e32 v29, v32, v29
	v_mul_f32_e32 v31, v7, v28
	v_cvt_pk_bf16_f32 v30, v29, v28
	v_fma_f32 v31, v6, v29, -v31
	v_mul_f32_e32 v29, v7, v29
	v_fmac_f32_e32 v29, v6, v28
	s_waitcnt lgkmcnt(13)
	v_add_f32_e32 v31, v34, v31
	v_add_f32_e32 v28, v35, v29
	v_cvt_pk_bf16_f32 v29, v31, v28
	ds_write2_b32 v88, v30, v29 offset0:72 offset1:140
	v_mul_f32_e32 v30, v7, v31
	v_mul_f32_e32 v29, v7, v28
	v_fmac_f32_e32 v30, v6, v28
	v_fma_f32 v29, v6, v31, -v29
	s_waitcnt lgkmcnt(13)
	v_add_f32_e32 v28, v37, v30
	v_add_f32_e32 v29, v36, v29
	v_mul_f32_e32 v31, v7, v28
	v_cvt_pk_bf16_f32 v30, v29, v28
	v_fma_f32 v31, v6, v29, -v31
	v_mul_f32_e32 v29, v7, v29
	v_fmac_f32_e32 v29, v6, v28
	s_waitcnt lgkmcnt(12)
	v_add_f32_e32 v31, v38, v31
	v_add_f32_e32 v28, v39, v29
	v_cvt_pk_bf16_f32 v29, v31, v28
	ds_write2_b32 v89, v30, v29 offset0:80 offset1:148
	v_mul_f32_e32 v30, v7, v31
	v_mul_f32_e32 v29, v7, v28
	v_fmac_f32_e32 v30, v6, v28
	v_fma_f32 v29, v6, v31, -v29
	s_waitcnt lgkmcnt(12)
	v_add_f32_e32 v28, v41, v30
	v_add_f32_e32 v29, v40, v29
	v_mul_f32_e32 v31, v7, v28
	v_cvt_pk_bf16_f32 v30, v29, v28
	v_fma_f32 v31, v6, v29, -v31
	v_mul_f32_e32 v29, v7, v29
	v_fmac_f32_e32 v29, v6, v28
	s_waitcnt lgkmcnt(11)
	v_add_f32_e32 v31, v42, v31
	v_add_f32_e32 v28, v43, v29
	v_cvt_pk_bf16_f32 v29, v31, v28
	ds_write2_b32 v90, v30, v29 offset0:88 offset1:156
	v_mul_f32_e32 v30, v7, v31
	v_mul_f32_e32 v29, v7, v28
	v_fmac_f32_e32 v30, v6, v28
	v_fma_f32 v29, v6, v31, -v29
	s_waitcnt lgkmcnt(11)
	v_add_f32_e32 v28, v45, v30
	v_add_f32_e32 v29, v44, v29
	v_mul_f32_e32 v31, v7, v28
	v_cvt_pk_bf16_f32 v30, v29, v28
	v_fma_f32 v31, v6, v29, -v31
	v_mul_f32_e32 v29, v7, v29
	v_fmac_f32_e32 v29, v6, v28
	s_waitcnt lgkmcnt(10)
	v_add_f32_e32 v31, v46, v31
	v_add_f32_e32 v28, v47, v29
	v_cvt_pk_bf16_f32 v29, v31, v28
	ds_write2_b32 v91, v30, v29 offset0:96 offset1:164
	v_mul_f32_e32 v30, v7, v31
	v_mul_f32_e32 v29, v7, v28
	v_fmac_f32_e32 v30, v6, v28
	v_fma_f32 v29, v6, v31, -v29
	s_waitcnt lgkmcnt(10)
	v_add_f32_e32 v28, v49, v30
	v_add_f32_e32 v29, v48, v29
	v_mul_f32_e32 v31, v7, v28
	v_cvt_pk_bf16_f32 v30, v29, v28
	v_fma_f32 v31, v6, v29, -v31
	v_mul_f32_e32 v29, v7, v29
	v_fmac_f32_e32 v29, v6, v28
	s_waitcnt lgkmcnt(9)
	v_add_f32_e32 v31, v50, v31
	v_add_f32_e32 v28, v51, v29
	v_cvt_pk_bf16_f32 v29, v31, v28
	ds_write2_b32 v92, v30, v29 offset0:104 offset1:172
	v_mul_f32_e32 v30, v7, v31
	v_mul_f32_e32 v29, v7, v28
	v_fmac_f32_e32 v30, v6, v28
	v_fma_f32 v29, v6, v31, -v29
	s_waitcnt lgkmcnt(9)
	v_add_f32_e32 v28, v53, v30
	v_add_f32_e32 v29, v52, v29
	v_mul_f32_e32 v31, v7, v28
	v_cvt_pk_bf16_f32 v30, v29, v28
	v_fma_f32 v31, v6, v29, -v31
	v_mul_f32_e32 v29, v7, v29
	v_fmac_f32_e32 v29, v6, v28
	s_waitcnt lgkmcnt(8)
	v_add_f32_e32 v31, v54, v31
	v_add_f32_e32 v28, v55, v29
	v_cvt_pk_bf16_f32 v29, v31, v28
	ds_write2_b32 v93, v30, v29 offset0:112 offset1:180
	v_mul_f32_e32 v29, v7, v28
	v_mul_f32_e32 v30, v7, v31
	v_fma_f32 v29, v6, v31, -v29
	v_fmac_f32_e32 v30, v6, v28
	s_waitcnt lgkmcnt(8)
	v_add_f32_e32 v29, v56, v29
	v_add_f32_e32 v28, v57, v30
	v_mul_f32_e32 v31, v7, v28
	v_mul_f32_e32 v7, v7, v29
	v_fma_f32 v31, v6, v29, -v31
	v_fmac_f32_e32 v7, v6, v28
	s_waitcnt lgkmcnt(7)
	v_add_f32_e32 v31, v58, v31
	v_add_f32_e32 v6, v59, v7
	v_cvt_pk_bf16_f32 v30, v29, v28
	v_cvt_pk_bf16_f32 v6, v31, v6
	ds_write2_b32 v94, v30, v6 offset0:120 offset1:188
	s_waitcnt lgkmcnt(0)
	ds_read_b128 v[28:31], v0 offset:11520
	s_waitcnt lgkmcnt(0)
	v_mfma_f32_16x16x32_bf16 v[24:27], v[28:31], v[24:27], 0
	ds_read_b128 v[28:31], v0 offset:11584
	v_mov_b32_e32 v73, v204
	v_mov_b32_e32 v72, 0
	s_waitcnt lgkmcnt(0)
	v_mfma_f32_16x16x32_bf16 v[20:23], v[28:31], v[20:23], v[24:27]
	s_nop 2
	ds_read_b128 v[24:27], v0 offset:11648
	v_mov_b32_e32 v75, 0
	v_mov_b32_e32 v76, 0
	s_waitcnt lgkmcnt(0)
	v_mfma_f32_16x16x32_bf16 v[16:19], v[24:27], v[16:19], v[20:23]
	s_nop 2
	ds_read_b128 v[20:23], v0 offset:11712
	v_mov_b32_e32 v0, s59
	ds_read_b64 v[6:7], v0
	v_readfirstlane_b32 s5, v73
	s_lshr_b32 s5, s5, 6
	s_mulk_i32 s5, 0x3e00
	s_add_i32 s8, s5, 0
	v_readlane_b32 s5, v244, 25
	v_and_b32_e32 v59, 63, v73
	s_add_i32 s28, s4, s5
	s_waitcnt lgkmcnt(0)
	v_readfirstlane_b32 s4, v6
	v_lshl_or_b32 v6, s28, 6, v59
	v_readfirstlane_b32 s5, v7
	v_ashrrev_i32_e32 v7, 31, v6
	s_ashr_i32 s29, s28, 31
	v_lshl_add_u64 v[6:7], v[6:7], 4, s[4:5]
	s_lshl_b64 s[38:39], s[28:29], 13
	v_add_co_u32_e32 v6, vcc, s9, v6
	s_add_u32 s38, s4, s38
	v_and_b32_e32 v58, 15, v73
	v_addc_co_u32_e32 v7, vcc, 0, v7, vcc
	s_addc_u32 s39, s5, s39
	v_and_b32_e32 v0, 48, v73
	v_mfma_f32_16x16x32_bf16 v[12:15], v[20:23], v[12:15], v[16:19]
	global_load_dwordx4 v[32:35], v[6:7], off
	v_lshl_add_u64 v[6:7], s[38:39], 0, v[0:1]
	s_mov_b32 s9, 0x240000
	v_lshlrev_b32_e32 v16, 6, v58
	v_mov_b32_e32 v17, v1
	v_lshl_add_u64 v[6:7], v[6:7], 0, v[16:17]
	v_add_co_u32_e32 v18, vcc, s9, v6
	s_mov_b64 s[38:39], 0x240000
	s_nop 0
	v_addc_co_u32_e32 v19, vcc, 0, v7, vcc
	s_mov_b32 s9, 0x241000
	v_lshl_add_u64 v[16:17], v[6:7], 0, s[38:39]
	v_add_co_u32_e32 v6, vcc, s9, v6
	s_lshl_b64 s[28:29], s[28:29], 12
	s_nop 0
	v_addc_co_u32_e32 v7, vcc, 0, v7, vcc
	s_add_u32 s28, s4, s28
	global_load_dwordx4 v[42:45], v[18:19], off
	global_load_dwordx4 v[68:71], v[16:17], off offset:1024
	global_load_dwordx4 v[64:67], v[16:17], off offset:2048
	global_load_dwordx4 v[50:53], v[16:17], off offset:3072
	global_load_dwordx4 v[54:57], v[6:7], off
	global_load_dwordx4 v[46:49], v[6:7], off offset:1024
	global_load_dwordx4 v[38:41], v[6:7], off offset:2048
	s_waitcnt vmcnt(0) lgkmcnt(0)
	global_load_dwordx4 v[34:37], v[6:7], off offset:3072
	s_addc_u32 s29, s5, s29
	v_lshlrev_b32_e32 v6, 8, v58
	v_mov_b32_e32 v7, v1
	v_lshl_add_u64 v[6:7], s[28:29], 0, v[6:7]
	v_lshl_add_u64 v[6:7], v[6:7], 0, v[0:1]
	s_mov_b64 s[28:29], 0x380000
	s_mov_b32 s9, 0x380000
	v_lshl_add_u64 v[16:17], v[6:7], 0, s[28:29]
	v_add_co_u32_e32 v6, vcc, s9, v6
	s_or_b32 s9, s26, 1
	s_mul_hi_i32 s28, s9, 0x44
	s_mulk_i32 s9, 0x44
	s_add_u32 s26, s9, s22
	s_addc_u32 s27, s28, s27
	s_lshl_b64 s[26:27], s[26:27], 10
	s_add_u32 s6, s26, s6
	v_addc_co_u32_e32 v7, vcc, 0, v7, vcc
	s_addc_u32 s7, s27, s7
	global_load_dwordx4 v[20:23], v[6:7], off
	global_load_dwordx4 v[28:31], v[16:17], off offset:64
	global_load_dwordx4 v[24:27], v[16:17], off offset:128
	s_nop 0
	global_load_dwordx4 v[16:19], v[16:17], off offset:192
	v_or_b32_e32 v6, s6, v59
	v_mov_b32_e32 v7, s7
	v_lshl_add_u64 v[6:7], v[6:7], 3, s[4:5]
	v_add_co_u32_e32 v6, vcc, 0x1500000, v6
	v_add_u32_e32 v74, s8, v0
	s_nop 0
	v_addc_co_u32_e32 v7, vcc, 0, v7, vcc
	global_load_dwordx2 v[6:7], v[6:7], off
	v_cmp_gt_u32_e32 vcc, 32, v59
	v_mad_u32_u24 v81, v58, 48, v74
	v_mov_b32_e32 v74, 0
	v_mov_b32_e32 v77, 0
	s_and_saveexec_b64 s[4:5], vcc
	ds_read_b128 v[74:77], v81 offset:2304
	s_or_b64 exec, exec, s[4:5]
	s_waitcnt lgkmcnt(0)
	v_mfma_f32_16x16x32_bf16 v[82:85], v[74:77], v[42:45], 0
	v_bfe_u32 v73, v73, 4, 2
	v_mov_b32_e32 v80, s8
	s_movk_i32 s4, 0x110
	v_mfma_f32_16x16x32_bf16 v[86:89], v[74:77], v[68:71], 0
	v_lshlrev_b32_e32 v79, 2, v58
	v_mad_u32_u24 v126, v58, s4, v80
	v_mul_u32_u24_e32 v58, 0x840, v73
	v_mfma_f32_16x16x32_bf16 v[90:93], v[74:77], v[64:67], 0
	v_add3_u32 v58, s8, v79, v58
	v_add_u32_e32 v80, 0xc00, v58
	s_nop 1
	ds_write2_b32 v80, v82, v86 offset1:16
	v_mfma_f32_16x16x32_bf16 v[94:97], v[74:77], v[50:53], 0
	v_add_u32_e32 v82, 0x1000, v58
	ds_write2_b32 v80, v83, v87 offset0:132 offset1:148
	ds_write2_b32 v82, v84, v88 offset0:8 offset1:24
	v_mfma_f32_16x16x32_bf16 v[98:101], v[74:77], v[54:57], 0
	ds_write2_b32 v82, v85, v89 offset0:140 offset1:156
	s_nop 2
	ds_write2_b32 v80, v90, v94 offset0:32 offset1:48
	ds_write2_b32 v80, v91, v95 offset0:164 offset1:180
	v_lshlrev_b32_e32 v59, 2, v59
	v_add_u32_e32 v83, s8, v59
	v_mfma_f32_16x16x32_bf16 v[84:87], v[74:77], v[46:49], 0
	ds_write2_b32 v82, v92, v96 offset0:40 offset1:56
	ds_write2_b32 v82, v93, v97 offset0:172 offset1:188
	s_nop 5
	ds_write2_b32 v80, v98, v84 offset0:64 offset1:80
	ds_write2_b32 v80, v99, v85 offset0:196 offset1:212
	ds_write2_b32 v82, v100, v86 offset0:72 offset1:88
	ds_write2_b32 v82, v101, v87 offset0:204 offset1:220
	v_mfma_f32_16x16x32_bf16 v[88:91], v[74:77], v[38:41], 0
	v_add_u32_e32 v84, 0xf0, v83
	v_add_u32_e32 v85, 0xe0, v83
	s_waitcnt vmcnt(0)
	v_mul_f32_e32 v73, v33, v7
	v_mfma_f32_16x16x32_bf16 v[74:77], v[74:77], v[34:37], 0
	s_nop 7
	ds_write2_b32 v80, v88, v74 offset0:96 offset1:112
	ds_write2_b32 v80, v89, v75 offset0:228 offset1:244
	ds_write2_b32 v82, v90, v76 offset0:104 offset1:120
	ds_write2_b32 v82, v91, v77 offset0:236 offset1:252
	s_waitcnt lgkmcnt(0)
	ds_read2st64_b32 v[58:59], v84 offset0:42 offset1:43
	ds_read2st64_b32 v[74:75], v85 offset0:40 offset1:41
	v_fma_f32 v73, v32, v6, -v73
	v_mul_f32_e32 v6, v33, v6
	v_fmac_f32_e32 v6, v32, v7
	s_waitcnt lgkmcnt(1)
	v_add_f32_e32 v58, v73, v58
	v_add_f32_e32 v6, v6, v59
	v_add_u32_e32 v86, 0xd0, v83
	v_cvt_pk_bf16_f32 v7, v58, v6
	v_mul_f32_e32 v59, v33, v6
	v_mul_f32_e32 v6, v32, v6
	ds_read2st64_b32 v[76:77], v86 offset0:38 offset1:39
	v_fma_f32 v59, v32, v58, -v59
	v_fmac_f32_e32 v6, v33, v58
	s_waitcnt lgkmcnt(1)
	v_add_f32_e32 v59, v74, v59
	v_add_f32_e32 v6, v75, v6
	v_add_u32_e32 v87, 0xc0, v83
	v_add_u32_e32 v88, 0xb0, v83
	v_add_u32_e32 v89, 0xa0, v83
	v_add_u32_e32 v90, 0x90, v83
	v_add_u32_e32 v91, 0x80, v83
	v_add_u32_e32 v92, 0x70, v83
	v_add_u32_e32 v93, 0x60, v83
	v_add_u32_e32 v94, 0x50, v83
	v_add_u32_e32 v95, 64, v83
	v_add_u32_e32 v96, 48, v83
	v_add_u32_e32 v97, 32, v83
	v_add_u32_e32 v98, 16, v83
	v_cvt_pk_bf16_f32 v58, v59, v6
	v_add_u32_e32 v99, 0x3a00, v83
	ds_read2st64_b32 v[100:101], v87 offset0:36 offset1:37
	ds_read2st64_b32 v[102:103], v88 offset0:34 offset1:35
	ds_read2st64_b32 v[104:105], v89 offset0:32 offset1:33
	ds_read2st64_b32 v[106:107], v90 offset0:30 offset1:31
	ds_read2st64_b32 v[108:109], v91 offset0:28 offset1:29
	ds_read2st64_b32 v[110:111], v92 offset0:26 offset1:27
	ds_read2st64_b32 v[112:113], v93 offset0:24 offset1:25
	ds_read2st64_b32 v[114:115], v94 offset0:22 offset1:23
	ds_read2st64_b32 v[116:117], v95 offset0:20 offset1:21
	ds_read2st64_b32 v[118:119], v96 offset0:18 offset1:19
	ds_read2st64_b32 v[120:121], v97 offset0:16 offset1:17
	ds_read2st64_b32 v[122:123], v98 offset0:14 offset1:15
	ds_read2st64_b32 v[124:125], v83 offset0:12 offset1:13
	ds_write2_b32 v99, v58, v7 offset0:120 offset1:188
	v_mul_f32_e32 v58, v33, v59
	v_mul_f32_e32 v7, v33, v6
	v_fmac_f32_e32 v58, v32, v6
	v_fma_f32 v7, v32, v59, -v7
	s_waitcnt lgkmcnt(14)
	v_add_f32_e32 v6, v77, v58
	v_add_f32_e32 v7, v76, v7
	v_mul_f32_e32 v59, v33, v6
	v_cvt_pk_bf16_f32 v58, v7, v6
	v_fma_f32 v59, v32, v7, -v59
	v_mul_f32_e32 v7, v33, v7
	v_fmac_f32_e32 v7, v32, v6
	s_waitcnt lgkmcnt(13)
	v_add_f32_e32 v59, v100, v59
	v_add_f32_e32 v6, v101, v7
	v_cvt_pk_bf16_f32 v7, v59, v6
	v_add_u32_e32 v100, 0x3800, v83
	ds_write2_b32 v100, v7, v58 offset0:112 offset1:180
	v_mul_f32_e32 v58, v33, v59
	v_mul_f32_e32 v7, v33, v6
	v_fmac_f32_e32 v58, v32, v6
	v_fma_f32 v7, v32, v59, -v7
	s_waitcnt lgkmcnt(13)
	v_add_f32_e32 v6, v103, v58
	v_add_f32_e32 v7, v102, v7
	v_mul_f32_e32 v59, v33, v6
	v_cvt_pk_bf16_f32 v58, v7, v6
	v_fma_f32 v59, v32, v7, -v59
	v_mul_f32_e32 v7, v33, v7
	v_fmac_f32_e32 v7, v32, v6
	s_waitcnt lgkmcnt(12)
	v_add_f32_e32 v59, v104, v59
	v_add_f32_e32 v6, v105, v7
	v_cvt_pk_bf16_f32 v7, v59, v6
	v_add_u32_e32 v101, 0x3600, v83
	ds_write2_b32 v101, v7, v58 offset0:104 offset1:172
	v_mul_f32_e32 v58, v33, v59
	v_mul_f32_e32 v7, v33, v6
	v_fmac_f32_e32 v58, v32, v6
	v_fma_f32 v7, v32, v59, -v7
	s_waitcnt lgkmcnt(12)
	v_add_f32_e32 v6, v107, v58
	v_add_f32_e32 v7, v106, v7
	v_mul_f32_e32 v59, v33, v6
	v_cvt_pk_bf16_f32 v58, v7, v6
	v_fma_f32 v59, v32, v7, -v59
	v_mul_f32_e32 v7, v33, v7
	v_fmac_f32_e32 v7, v32, v6
	s_waitcnt lgkmcnt(11)
	v_add_f32_e32 v59, v108, v59
	v_add_f32_e32 v6, v109, v7
	v_cvt_pk_bf16_f32 v7, v59, v6
	v_add_u32_e32 v102, 0x3400, v83
	ds_write2_b32 v102, v7, v58 offset0:96 offset1:164
	v_mul_f32_e32 v58, v33, v59
	v_mul_f32_e32 v7, v33, v6
	v_fmac_f32_e32 v58, v32, v6
	v_fma_f32 v7, v32, v59, -v7
	s_waitcnt lgkmcnt(11)
	v_add_f32_e32 v6, v111, v58
	v_add_f32_e32 v7, v110, v7
	v_mul_f32_e32 v59, v33, v6
	v_cvt_pk_bf16_f32 v58, v7, v6
	v_fma_f32 v59, v32, v7, -v59
	v_mul_f32_e32 v7, v33, v7
	v_fmac_f32_e32 v7, v32, v6
	s_waitcnt lgkmcnt(10)
	v_add_f32_e32 v59, v112, v59
	v_add_f32_e32 v6, v113, v7
	v_cvt_pk_bf16_f32 v7, v59, v6
	v_add_u32_e32 v103, 0x3200, v83
	ds_write2_b32 v103, v7, v58 offset0:88 offset1:156
	v_mul_f32_e32 v58, v33, v59
	v_mul_f32_e32 v7, v33, v6
	v_fmac_f32_e32 v58, v32, v6
	v_fma_f32 v7, v32, v59, -v7
	s_waitcnt lgkmcnt(10)
	v_add_f32_e32 v6, v115, v58
	v_add_f32_e32 v7, v114, v7
	v_mul_f32_e32 v59, v33, v6
	v_cvt_pk_bf16_f32 v58, v7, v6
	v_fma_f32 v59, v32, v7, -v59
	v_mul_f32_e32 v7, v33, v7
	v_fmac_f32_e32 v7, v32, v6
	s_waitcnt lgkmcnt(9)
	v_add_f32_e32 v59, v116, v59
	v_add_f32_e32 v6, v117, v7
	v_cvt_pk_bf16_f32 v7, v59, v6
	v_add_u32_e32 v104, 0x3000, v83
	ds_write2_b32 v104, v7, v58 offset0:80 offset1:148
	v_mul_f32_e32 v58, v33, v59
	v_mul_f32_e32 v7, v33, v6
	v_fmac_f32_e32 v58, v32, v6
	v_fma_f32 v7, v32, v59, -v7
	s_waitcnt lgkmcnt(9)
	v_add_f32_e32 v6, v119, v58
	v_add_f32_e32 v7, v118, v7
	v_mul_f32_e32 v59, v33, v6
	v_cvt_pk_bf16_f32 v58, v7, v6
	v_fma_f32 v59, v32, v7, -v59
	v_mul_f32_e32 v7, v33, v7
	v_fmac_f32_e32 v7, v32, v6
	s_waitcnt lgkmcnt(8)
	v_add_f32_e32 v59, v120, v59
	v_add_f32_e32 v6, v121, v7
	v_cvt_pk_bf16_f32 v7, v59, v6
	v_add_u32_e32 v105, 0x2e00, v83
	ds_write2_b32 v105, v7, v58 offset0:72 offset1:140
	v_mul_f32_e32 v58, v33, v59
	v_mul_f32_e32 v7, v33, v6
	v_fmac_f32_e32 v58, v32, v6
	v_fma_f32 v7, v32, v59, -v7
	s_waitcnt lgkmcnt(8)
	v_add_f32_e32 v58, v123, v58
	v_add_f32_e32 v7, v122, v7
	v_mul_f32_e32 v6, v33, v58
	v_cvt_pk_bf16_f32 v59, v7, v58
	v_fma_f32 v6, v32, v7, -v6
	v_mul_f32_e32 v7, v33, v7
	v_fmac_f32_e32 v7, v32, v58
	s_waitcnt lgkmcnt(7)
	v_add_f32_e32 v6, v124, v6
	v_add_f32_e32 v7, v125, v7
	v_cvt_pk_bf16_f32 v58, v6, v7
	v_add_u32_e32 v106, 0x2c00, v83
	ds_write2_b32 v106, v58, v59 offset0:64 offset1:132
	s_waitcnt lgkmcnt(0)
	v_add_u32_e32 v79, v126, v0
	ds_read_b128 v[74:77], v79 offset:11520
	ds_read_b128 v[108:111], v79 offset:11584
	s_waitcnt lgkmcnt(1)
	v_mfma_f32_16x16x32_bf16 v[12:15], v[74:77], v[20:23], v[12:15]
	ds_read_b128 v[74:77], v79 offset:11648
	v_mov_b32_e32 v73, 0
	s_waitcnt lgkmcnt(1)
	v_mfma_f32_16x16x32_bf16 v[12:15], v[108:111], v[28:31], v[12:15]
	ds_read_b128 v[108:111], v79 offset:11712
	s_waitcnt lgkmcnt(1)
	v_mfma_f32_16x16x32_bf16 v[12:15], v[74:77], v[24:27], v[12:15]
	v_mov_b32_e32 v74, 0
	v_mov_b32_e32 v75, 0
	s_waitcnt lgkmcnt(0)
	v_mfma_f32_16x16x32_bf16 v[12:15], v[108:111], v[16:19], v[12:15]
	s_and_saveexec_b64 s[4:5], vcc
	ds_read_b128 v[72:75], v81 offset:1536
	s_or_b64 exec, exec, s[4:5]
	s_waitcnt lgkmcnt(0)
	v_mfma_f32_16x16x32_bf16 v[108:111], v[72:75], v[42:45], 0
	v_mul_f32_e32 v0, v33, v7
	v_fma_f32 v0, v32, v6, -v0
	v_mul_f32_e32 v6, v33, v6
	v_mfma_f32_16x16x32_bf16 v[112:115], v[72:75], v[68:71], 0
	s_nop 7
	ds_write2_b32 v80, v108, v112 offset1:16
	ds_write2_b32 v80, v109, v113 offset0:132 offset1:148
	ds_write2_b32 v82, v110, v114 offset0:8 offset1:24
	v_mfma_f32_16x16x32_bf16 v[116:119], v[72:75], v[64:67], 0
	v_fmac_f32_e32 v6, v32, v7
	v_mfma_f32_16x16x32_bf16 v[120:123], v[72:75], v[50:53], 0
	ds_write2_b32 v82, v111, v115 offset0:140 offset1:156
	s_nop 6
	ds_write2_b32 v80, v116, v120 offset0:32 offset1:48
	ds_write2_b32 v80, v117, v121 offset0:164 offset1:180
	v_mfma_f32_16x16x32_bf16 v[124:127], v[72:75], v[54:57], 0
	v_mfma_f32_16x16x32_bf16 v[108:111], v[72:75], v[46:49], 0
	ds_write2_b32 v82, v118, v122 offset0:40 offset1:56
	ds_write2_b32 v82, v119, v123 offset0:172 offset1:188
	s_nop 5
	ds_write2_b32 v80, v124, v108 offset0:64 offset1:80
	ds_write2_b32 v80, v125, v109 offset0:196 offset1:212
	ds_write2_b32 v82, v126, v110 offset0:72 offset1:88
	ds_write2_b32 v82, v127, v111 offset0:204 offset1:220
	v_mfma_f32_16x16x32_bf16 v[112:115], v[72:75], v[38:41], 0
	v_mfma_f32_16x16x32_bf16 v[72:75], v[72:75], v[34:37], 0
	s_nop 7
	ds_write2_b32 v80, v112, v72 offset0:96 offset1:112
	ds_write2_b32 v80, v113, v73 offset0:228 offset1:244
	ds_write2_b32 v82, v114, v74 offset0:104 offset1:120
	ds_write2_b32 v82, v115, v75 offset0:236 offset1:252
	s_waitcnt lgkmcnt(0)
	ds_read2st64_b32 v[58:59], v84 offset0:42 offset1:43
	ds_read2st64_b32 v[72:73], v85 offset0:40 offset1:41
	ds_read2st64_b32 v[74:75], v86 offset0:38 offset1:39
	ds_read2st64_b32 v[76:77], v87 offset0:36 offset1:37
	ds_read2st64_b32 v[108:109], v88 offset0:34 offset1:35
	ds_read2st64_b32 v[110:111], v89 offset0:32 offset1:33
	ds_read2st64_b32 v[112:113], v90 offset0:30 offset1:31
	ds_read2st64_b32 v[114:115], v91 offset0:28 offset1:29
	ds_read2st64_b32 v[116:117], v92 offset0:26 offset1:27
	ds_read2st64_b32 v[118:119], v93 offset0:24 offset1:25
	ds_read2st64_b32 v[120:121], v94 offset0:22 offset1:23
	ds_read2st64_b32 v[122:123], v95 offset0:20 offset1:21
	ds_read2st64_b32 v[124:125], v96 offset0:18 offset1:19
	ds_read2st64_b32 v[126:127], v97 offset0:16 offset1:17
	ds_read2st64_b32 v[128:129], v98 offset0:14 offset1:15
	ds_read2st64_b32 v[130:131], v83 offset0:12 offset1:13
	s_waitcnt lgkmcnt(14)
	v_add_f32_e32 v0, v0, v58
	v_add_f32_e32 v6, v6, v59
	v_cvt_pk_bf16_f32 v7, v0, v6
	v_mul_f32_e32 v58, v33, v6
	v_mul_f32_e32 v6, v32, v6
	v_fma_f32 v58, v32, v0, -v58
	v_fmac_f32_e32 v6, v33, v0
	v_add_f32_e32 v58, v72, v58
	v_add_f32_e32 v0, v73, v6
	v_cvt_pk_bf16_f32 v6, v58, v0
	ds_write2_b32 v99, v6, v7 offset0:120 offset1:188
	v_mul_f32_e32 v7, v33, v58
	v_mul_f32_e32 v6, v33, v0
	v_fmac_f32_e32 v7, v32, v0
	v_fma_f32 v6, v32, v58, -v6
	s_waitcnt lgkmcnt(14)
	v_add_f32_e32 v0, v75, v7
	v_add_f32_e32 v6, v74, v6
	v_mul_f32_e32 v58, v33, v0
	v_cvt_pk_bf16_f32 v7, v6, v0
	v_fma_f32 v58, v32, v6, -v58
	v_mul_f32_e32 v6, v33, v6
	v_fmac_f32_e32 v6, v32, v0
	s_waitcnt lgkmcnt(13)
	v_add_f32_e32 v58, v76, v58
	v_add_f32_e32 v0, v77, v6
	v_cvt_pk_bf16_f32 v6, v58, v0
	ds_write2_b32 v100, v6, v7 offset0:112 offset1:180
	v_mul_f32_e32 v7, v33, v58
	v_mul_f32_e32 v6, v33, v0
	v_fmac_f32_e32 v7, v32, v0
	v_fma_f32 v6, v32, v58, -v6
	s_waitcnt lgkmcnt(13)
	v_add_f32_e32 v0, v109, v7
	v_add_f32_e32 v6, v108, v6
	v_mul_f32_e32 v58, v33, v0
	v_cvt_pk_bf16_f32 v7, v6, v0
	v_fma_f32 v58, v32, v6, -v58
	v_mul_f32_e32 v6, v33, v6
	v_fmac_f32_e32 v6, v32, v0
	s_waitcnt lgkmcnt(12)
	v_add_f32_e32 v58, v110, v58
	v_add_f32_e32 v0, v111, v6
	v_cvt_pk_bf16_f32 v6, v58, v0
	ds_write2_b32 v101, v6, v7 offset0:104 offset1:172
	v_mul_f32_e32 v7, v33, v58
	v_mul_f32_e32 v6, v33, v0
	v_fmac_f32_e32 v7, v32, v0
	v_fma_f32 v6, v32, v58, -v6
	s_waitcnt lgkmcnt(12)
	v_add_f32_e32 v0, v113, v7
	v_add_f32_e32 v6, v112, v6
	v_mul_f32_e32 v58, v33, v0
	v_cvt_pk_bf16_f32 v7, v6, v0
	v_fma_f32 v58, v32, v6, -v58
	v_mul_f32_e32 v6, v33, v6
	v_fmac_f32_e32 v6, v32, v0
	s_waitcnt lgkmcnt(11)
	v_add_f32_e32 v58, v114, v58
	v_add_f32_e32 v0, v115, v6
	v_cvt_pk_bf16_f32 v6, v58, v0
	ds_write2_b32 v102, v6, v7 offset0:96 offset1:164
	v_mul_f32_e32 v7, v33, v58
	v_mul_f32_e32 v6, v33, v0
	v_fmac_f32_e32 v7, v32, v0
	v_fma_f32 v6, v32, v58, -v6
	s_waitcnt lgkmcnt(11)
	v_add_f32_e32 v0, v117, v7
	v_add_f32_e32 v6, v116, v6
	v_mul_f32_e32 v58, v33, v0
	v_cvt_pk_bf16_f32 v7, v6, v0
	v_fma_f32 v58, v32, v6, -v58
	v_mul_f32_e32 v6, v33, v6
	v_fmac_f32_e32 v6, v32, v0
	s_waitcnt lgkmcnt(10)
	v_add_f32_e32 v58, v118, v58
	v_add_f32_e32 v0, v119, v6
	v_cvt_pk_bf16_f32 v6, v58, v0
	ds_write2_b32 v103, v6, v7 offset0:88 offset1:156
	v_mul_f32_e32 v7, v33, v58
	v_mul_f32_e32 v6, v33, v0
	v_fmac_f32_e32 v7, v32, v0
	v_fma_f32 v6, v32, v58, -v6
	s_waitcnt lgkmcnt(10)
	v_add_f32_e32 v0, v121, v7
	v_add_f32_e32 v6, v120, v6
	v_mul_f32_e32 v58, v33, v0
	v_cvt_pk_bf16_f32 v7, v6, v0
	v_fma_f32 v58, v32, v6, -v58
	v_mul_f32_e32 v6, v33, v6
	v_fmac_f32_e32 v6, v32, v0
	s_waitcnt lgkmcnt(9)
	v_add_f32_e32 v58, v122, v58
	v_add_f32_e32 v0, v123, v6
	v_cvt_pk_bf16_f32 v6, v58, v0
	ds_write2_b32 v104, v6, v7 offset0:80 offset1:148
	v_mul_f32_e32 v7, v33, v58
	v_mul_f32_e32 v6, v33, v0
	v_fmac_f32_e32 v7, v32, v0
	v_fma_f32 v6, v32, v58, -v6
	s_waitcnt lgkmcnt(9)
	v_add_f32_e32 v0, v125, v7
	v_add_f32_e32 v6, v124, v6
	v_mul_f32_e32 v58, v33, v0
	v_cvt_pk_bf16_f32 v7, v6, v0
	v_fma_f32 v58, v32, v6, -v58
	v_mul_f32_e32 v6, v33, v6
	v_fmac_f32_e32 v6, v32, v0
	s_waitcnt lgkmcnt(8)
	v_add_f32_e32 v58, v126, v58
	v_add_f32_e32 v0, v127, v6
	v_cvt_pk_bf16_f32 v6, v58, v0
	ds_write2_b32 v105, v6, v7 offset0:72 offset1:140
	v_mul_f32_e32 v7, v33, v58
	v_mul_f32_e32 v6, v33, v0
	v_fmac_f32_e32 v7, v32, v0
	v_fma_f32 v6, v32, v58, -v6
	s_waitcnt lgkmcnt(8)
	v_add_f32_e32 v7, v129, v7
	v_add_f32_e32 v6, v128, v6
	v_mul_f32_e32 v0, v33, v7
	v_cvt_pk_bf16_f32 v58, v6, v7
	v_fma_f32 v0, v32, v6, -v0
	v_mul_f32_e32 v6, v33, v6
	v_fmac_f32_e32 v6, v32, v7
	s_waitcnt lgkmcnt(7)
	v_add_f32_e32 v0, v130, v0
	v_add_f32_e32 v6, v131, v6
	v_cvt_pk_bf16_f32 v7, v0, v6
	ds_write2_b32 v106, v7, v58 offset0:64 offset1:132
	s_waitcnt lgkmcnt(0)
	ds_read_b128 v[72:75], v79 offset:11520
	ds_read_b128 v[108:111], v79 offset:11584
	s_waitcnt lgkmcnt(1)
	v_mfma_f32_16x16x32_bf16 v[58:61], v[72:75], v[20:23], v[60:63]
	ds_read_b128 v[72:75], v79 offset:11648
	v_mov_b32_e32 v76, 0
	v_mov_b32_e32 v77, 0
	s_waitcnt lgkmcnt(1)
	v_mfma_f32_16x16x32_bf16 v[58:61], v[108:111], v[28:31], v[58:61]
	ds_read_b128 v[108:111], v79 offset:11712
	s_waitcnt lgkmcnt(1)
	v_mfma_f32_16x16x32_bf16 v[58:61], v[72:75], v[24:27], v[58:61]
	v_mov_b32_e32 v72, 0
	v_mov_b32_e32 v74, 0
	v_mov_b32_e32 v75, 0
	s_waitcnt lgkmcnt(0)
	v_mfma_f32_16x16x32_bf16 v[58:61], v[108:111], v[16:19], v[58:61]
	s_and_saveexec_b64 s[4:5], vcc
	ds_read_b128 v[74:77], v81 offset:768
	s_or_b64 exec, exec, s[4:5]
	s_waitcnt lgkmcnt(0)
	v_mfma_f32_16x16x32_bf16 v[108:111], v[74:77], v[42:45], 0
	v_mul_f32_e32 v7, v33, v6
	v_fma_f32 v7, v32, v0, -v7
	v_mul_f32_e32 v0, v33, v0
	v_mfma_f32_16x16x32_bf16 v[112:115], v[74:77], v[68:71], 0
	s_nop 7
	ds_write2_b32 v80, v108, v112 offset1:16
	ds_write2_b32 v80, v109, v113 offset0:132 offset1:148
	ds_write2_b32 v82, v110, v114 offset0:8 offset1:24
	v_mfma_f32_16x16x32_bf16 v[116:119], v[74:77], v[64:67], 0
	v_fmac_f32_e32 v0, v32, v6
	v_mov_b32_e32 v73, 0
	v_mfma_f32_16x16x32_bf16 v[120:123], v[74:77], v[50:53], 0
	ds_write2_b32 v82, v111, v115 offset0:140 offset1:156
	s_nop 6
	ds_write2_b32 v80, v116, v120 offset0:32 offset1:48
	ds_write2_b32 v80, v117, v121 offset0:164 offset1:180
	v_mfma_f32_16x16x32_bf16 v[124:127], v[74:77], v[54:57], 0
	v_mfma_f32_16x16x32_bf16 v[108:111], v[74:77], v[46:49], 0
	ds_write2_b32 v82, v118, v122 offset0:40 offset1:56
	ds_write2_b32 v82, v119, v123 offset0:172 offset1:188
	s_nop 5
	ds_write2_b32 v80, v124, v108 offset0:64 offset1:80
	ds_write2_b32 v80, v125, v109 offset0:196 offset1:212
	ds_write2_b32 v82, v126, v110 offset0:72 offset1:88
	ds_write2_b32 v82, v127, v111 offset0:204 offset1:220
	v_mfma_f32_16x16x32_bf16 v[112:115], v[74:77], v[38:41], 0
	v_mfma_f32_16x16x32_bf16 v[74:77], v[74:77], v[34:37], 0
	s_nop 7
	ds_write2_b32 v80, v112, v74 offset0:96 offset1:112
	ds_write2_b32 v80, v113, v75 offset0:228 offset1:244
	ds_write2_b32 v82, v114, v76 offset0:104 offset1:120
	ds_write2_b32 v82, v115, v77 offset0:236 offset1:252
	s_waitcnt lgkmcnt(0)
	ds_read2st64_b32 v[62:63], v84 offset0:42 offset1:43
	ds_read2st64_b32 v[74:75], v85 offset0:40 offset1:41
	ds_read2st64_b32 v[76:77], v86 offset0:38 offset1:39
	ds_read2st64_b32 v[108:109], v87 offset0:36 offset1:37
	ds_read2st64_b32 v[110:111], v88 offset0:34 offset1:35
	ds_read2st64_b32 v[112:113], v89 offset0:32 offset1:33
	ds_read2st64_b32 v[114:115], v90 offset0:30 offset1:31
	ds_read2st64_b32 v[116:117], v91 offset0:28 offset1:29
	ds_read2st64_b32 v[118:119], v92 offset0:26 offset1:27
	ds_read2st64_b32 v[120:121], v93 offset0:24 offset1:25
	ds_read2st64_b32 v[122:123], v94 offset0:22 offset1:23
	ds_read2st64_b32 v[124:125], v95 offset0:20 offset1:21
	ds_read2st64_b32 v[126:127], v96 offset0:18 offset1:19
	ds_read2st64_b32 v[128:129], v97 offset0:16 offset1:17
	ds_read2st64_b32 v[130:131], v98 offset0:14 offset1:15
	ds_read2st64_b32 v[132:133], v83 offset0:12 offset1:13
	s_waitcnt lgkmcnt(14)
	v_add_f32_e32 v7, v7, v62
	v_add_f32_e32 v0, v0, v63
	v_cvt_pk_bf16_f32 v6, v7, v0
	v_mul_f32_e32 v62, v33, v0
	v_mul_f32_e32 v0, v32, v0
	v_fma_f32 v62, v32, v7, -v62
	v_fmac_f32_e32 v0, v33, v7
	v_add_f32_e32 v62, v74, v62
	v_add_f32_e32 v0, v75, v0
	v_cvt_pk_bf16_f32 v7, v62, v0
	ds_write2_b32 v99, v7, v6 offset0:120 offset1:188
	v_mul_f32_e32 v7, v33, v62
	v_mul_f32_e32 v6, v33, v0
	v_fmac_f32_e32 v7, v32, v0
	v_fma_f32 v6, v32, v62, -v6
	s_waitcnt lgkmcnt(14)
	v_add_f32_e32 v0, v77, v7
	v_add_f32_e32 v6, v76, v6
	v_mul_f32_e32 v62, v33, v0
	v_cvt_pk_bf16_f32 v7, v6, v0
	v_fma_f32 v62, v32, v6, -v62
	v_mul_f32_e32 v6, v33, v6
	v_fmac_f32_e32 v6, v32, v0
	s_waitcnt lgkmcnt(13)
	v_add_f32_e32 v62, v108, v62
	v_add_f32_e32 v0, v109, v6
	v_cvt_pk_bf16_f32 v6, v62, v0
	ds_write2_b32 v100, v6, v7 offset0:112 offset1:180
	v_mul_f32_e32 v7, v33, v62
	v_mul_f32_e32 v6, v33, v0
	v_fmac_f32_e32 v7, v32, v0
	v_fma_f32 v6, v32, v62, -v6
	s_waitcnt lgkmcnt(13)
	v_add_f32_e32 v0, v111, v7
	v_add_f32_e32 v6, v110, v6
	v_mul_f32_e32 v62, v33, v0
	v_cvt_pk_bf16_f32 v7, v6, v0
	v_fma_f32 v62, v32, v6, -v62
	v_mul_f32_e32 v6, v33, v6
	v_fmac_f32_e32 v6, v32, v0
	s_waitcnt lgkmcnt(12)
	v_add_f32_e32 v62, v112, v62
	v_add_f32_e32 v0, v113, v6
	v_cvt_pk_bf16_f32 v6, v62, v0
	ds_write2_b32 v101, v6, v7 offset0:104 offset1:172
	v_mul_f32_e32 v7, v33, v62
	v_mul_f32_e32 v6, v33, v0
	v_fmac_f32_e32 v7, v32, v0
	v_fma_f32 v6, v32, v62, -v6
	s_waitcnt lgkmcnt(12)
	v_add_f32_e32 v0, v115, v7
	v_add_f32_e32 v6, v114, v6
	v_mul_f32_e32 v62, v33, v0
	v_cvt_pk_bf16_f32 v7, v6, v0
	v_fma_f32 v62, v32, v6, -v62
	v_mul_f32_e32 v6, v33, v6
	v_fmac_f32_e32 v6, v32, v0
	s_waitcnt lgkmcnt(11)
	v_add_f32_e32 v62, v116, v62
	v_add_f32_e32 v0, v117, v6
	v_cvt_pk_bf16_f32 v6, v62, v0
	ds_write2_b32 v102, v6, v7 offset0:96 offset1:164
	v_mul_f32_e32 v7, v33, v62
	v_mul_f32_e32 v6, v33, v0
	v_fmac_f32_e32 v7, v32, v0
	v_fma_f32 v6, v32, v62, -v6
	s_waitcnt lgkmcnt(11)
	v_add_f32_e32 v0, v119, v7
	v_add_f32_e32 v6, v118, v6
	v_mul_f32_e32 v62, v33, v0
	v_cvt_pk_bf16_f32 v7, v6, v0
	v_fma_f32 v62, v32, v6, -v62
	v_mul_f32_e32 v6, v33, v6
	v_fmac_f32_e32 v6, v32, v0
	s_waitcnt lgkmcnt(10)
	v_add_f32_e32 v62, v120, v62
	v_add_f32_e32 v0, v121, v6
	v_cvt_pk_bf16_f32 v6, v62, v0
	ds_write2_b32 v103, v6, v7 offset0:88 offset1:156
	v_mul_f32_e32 v7, v33, v62
	v_mul_f32_e32 v6, v33, v0
	v_fmac_f32_e32 v7, v32, v0
	v_fma_f32 v6, v32, v62, -v6
	s_waitcnt lgkmcnt(10)
	v_add_f32_e32 v0, v123, v7
	v_add_f32_e32 v6, v122, v6
	v_mul_f32_e32 v62, v33, v0
	v_cvt_pk_bf16_f32 v7, v6, v0
	v_fma_f32 v62, v32, v6, -v62
	v_mul_f32_e32 v6, v33, v6
	v_fmac_f32_e32 v6, v32, v0
	s_waitcnt lgkmcnt(9)
	v_add_f32_e32 v62, v124, v62
	v_add_f32_e32 v0, v125, v6
	v_cvt_pk_bf16_f32 v6, v62, v0
	ds_write2_b32 v104, v6, v7 offset0:80 offset1:148
	v_mul_f32_e32 v7, v33, v62
	v_mul_f32_e32 v6, v33, v0
	v_fmac_f32_e32 v7, v32, v0
	v_fma_f32 v6, v32, v62, -v6
	s_waitcnt lgkmcnt(9)
	v_add_f32_e32 v0, v127, v7
	v_add_f32_e32 v6, v126, v6
	v_mul_f32_e32 v62, v33, v0
	v_cvt_pk_bf16_f32 v7, v6, v0
	v_fma_f32 v62, v32, v6, -v62
	v_mul_f32_e32 v6, v33, v6
	v_fmac_f32_e32 v6, v32, v0
	s_waitcnt lgkmcnt(8)
	v_add_f32_e32 v62, v128, v62
	v_add_f32_e32 v0, v129, v6
	v_cvt_pk_bf16_f32 v6, v62, v0
	ds_write2_b32 v105, v6, v7 offset0:72 offset1:140
	v_mul_f32_e32 v7, v33, v62
	v_mul_f32_e32 v6, v33, v0
	v_fmac_f32_e32 v7, v32, v0
	v_fma_f32 v6, v32, v62, -v6
	s_waitcnt lgkmcnt(8)
	v_add_f32_e32 v7, v131, v7
	v_add_f32_e32 v6, v130, v6
	v_mul_f32_e32 v0, v33, v7
	v_cvt_pk_bf16_f32 v63, v6, v7
	v_fma_f32 v0, v32, v6, -v0
	v_mul_f32_e32 v6, v33, v6
	v_fmac_f32_e32 v6, v32, v7
	s_waitcnt lgkmcnt(7)
	v_add_f32_e32 v0, v132, v0
	v_add_f32_e32 v62, v133, v6
	v_cvt_pk_bf16_f32 v6, v0, v62
	ds_write2_b32 v106, v6, v63 offset0:64 offset1:132
	s_waitcnt lgkmcnt(0)
	ds_read_b128 v[74:77], v79 offset:11520
	ds_read_b128 v[108:111], v79 offset:11584
	s_waitcnt lgkmcnt(1)
	v_mfma_f32_16x16x32_bf16 v[6:9], v[74:77], v[20:23], v[8:11]
	ds_read_b128 v[74:77], v79 offset:11648
	s_waitcnt lgkmcnt(1)
	v_mfma_f32_16x16x32_bf16 v[6:9], v[108:111], v[28:31], v[6:9]
	ds_read_b128 v[108:111], v79 offset:11712
	s_waitcnt lgkmcnt(1)
	v_mfma_f32_16x16x32_bf16 v[6:9], v[74:77], v[24:27], v[6:9]
	v_mov_b32_e32 v74, 0
	v_mov_b32_e32 v75, 0
	s_waitcnt lgkmcnt(0)
	v_mfma_f32_16x16x32_bf16 v[6:9], v[108:111], v[16:19], v[6:9]
	s_and_saveexec_b64 s[4:5], vcc
	s_cbranch_execz .LBB0_275
	ds_read_b128 v[72:75], v81
	s_branch .LBB0_275

.LBB0_300:
	v_mov_b32_e32 v0, s59
	ds_read_b64 v[18:19], v0
	v_ashrrev_i32_e32 v0, 11, v92
	v_mul_i32_i24_e32 v20, 0x44, v0
	v_ashrrev_i32_e32 v21, 31, v20
	v_lshlrev_b32_e32 v0, 3, v92
	s_waitcnt lgkmcnt(0)
	v_readfirstlane_b32 s9, v19
	v_readfirstlane_b32 s8, v18
	v_lshlrev_b64 v[18:19], 14, v[20:21]
	v_and_b32_e32 v0, 0x3ff8, v0
	v_lshl_add_u64 v[18:19], s[8:9], 0, v[18:19]
	v_lshl_add_u64 v[22:23], v[18:19], 0, v[0:1]
	v_lshlrev_b64 v[18:19], 8, v[20:21]
	v_lshlrev_b32_e32 v0, 4, v92
	v_cmp_gt_i32_e64 s[36:37], s91, v92
	v_lshl_add_u64 v[18:19], s[8:9], 0, v[18:19]
	v_and_b32_e32 v0, 0xf0, v0
	v_cndmask_b32_e64 v28, 0, v92, s[36:37]
	v_lshl_add_u64 v[24:25], v[18:19], 0, v[0:1]
	v_lshrrev_b32_e32 v0, 8, v28
	v_mul_i32_i24_e32 v18, 0x44, v0
	v_ashrrev_i32_e32 v19, 31, v18
	v_lshlrev_b64 v[18:19], 10, v[18:19]
	v_lshlrev_b32_sdwa v0, v220, v28 dst_sel:DWORD dst_unused:UNUSED_PAD src0_sel:DWORD src1_sel:BYTE_0
	v_lshl_add_u64 v[18:19], s[8:9], 0, v[18:19]
	v_lshl_add_u64 v[26:27], v[18:19], 0, v[0:1]
	v_add_u32_e32 v0, 0xfffff000, v92
	s_movk_i32 s10, 0x4000
	v_cmp_gt_u32_e64 s[38:39], s10, v0
	v_readlane_b32 s10, v244, 26
	s_mov_b32 s17, 7
	v_cndmask_b32_e64 v0, 0, v0, s[38:39]
	v_ashrrev_i32_e32 v30, 10, v0
	v_and_b32_e32 v31, 1, v30
	v_and_b32_e32 v29, 0x3ff, v0
	v_lshlrev_b32_e32 v0, 10, v31
	v_or3_b32 v0, v0, s10, v29
	v_lshlrev_b32_e32 v0, 4, v0
	v_lshl_add_u64 v[18:19], s[8:9], 0, v[0:1]
	s_mov_b32 s10, 0x200000
	v_add_co_u32_e32 v18, vcc, s10, v18
	s_mov_b64 s[10:11], 0x18c00000
	s_nop 0
	v_addc_co_u32_e32 v19, vcc, 0, v19, vcc
	global_load_dwordx4 v[18:21], v[18:19], off
	s_waitcnt vmcnt(0) lgkmcnt(0)
	v_lshl_add_u64 v[18:19], v[22:23], 0, s[10:11]
	v_mul_i32_i24_e32 v22, 0x44, v30
	v_ashrrev_i32_e32 v23, 31, v22
	s_mov_b64 s[10:11], 0x500000
	v_lshlrev_b64 v[22:23], 13, v[22:23]
	v_lshl_add_u64 v[62:63], v[24:25], 0, s[10:11]
	s_mov_b64 s[10:11], 0x700000
	v_lshl_or_b32 v22, v29, 3, v22
	v_lshl_add_u64 v[64:65], v[26:27], 0, s[10:11]
	s_mov_b64 s[10:11], 0x810000
	v_lshl_add_u64 v[22:23], s[8:9], 0, v[22:23]
	s_mov_b64 s[8:9], 0xc00000
	v_and_b32_e32 v0, 0x800, v92
	v_lshl_add_u64 v[66:67], v[26:27], 0, s[10:11]
	s_mov_b64 s[10:11], 0xa00000
	v_lshl_add_u64 v[70:71], v[22:23], 0, s[8:9]
	s_mov_b64 s[8:9], 0x1500000
	v_cmp_eq_u32_e64 s[40:41], 0, v0
	v_and_b32_e32 v0, 0x100, v28
	v_lshl_add_u64 v[68:69], v[26:27], 0, s[10:11]
	v_lshl_add_u64 v[72:73], v[22:23], 0, s[8:9]
	v_cmp_eq_u32_e64 s[42:43], 0, v0
	v_cmp_eq_u32_e64 s[44:45], 0, v31
	s_mov_b32 s20, 64
	v_mov_b32_e32 v114, 0
	v_mov_b32_e32 v113, 0
	v_mov_b32_e32 v112, 0
	v_mov_b32_e32 v111, 0
	v_mov_b32_e32 v110, 0
	v_mov_b32_e32 v74, 0
	v_mov_b32_e32 v75, v93
	s_branch .LBB0_302

.LBB0_302:
	s_add_i32 s22, s17, -7
	s_cmp_eq_u32 s17, 7
	s_cselect_b32 s8, 3, 0x47
	s_add_i32 s28, s8, s20
	s_sub_i32 s52, s28, 64
	v_mov_b32_e32 v0, s52
	v_mov_b32_e32 v22, s22
	v_cndmask_b32_e64 v22, v0, v22, s[40:41]
	v_ashrrev_i32_e32 v23, 31, v22
	v_lshlrev_b64 v[24:25], 14, v[22:23]
	s_add_i32 s26, s17, -6
	s_add_i32 s29, s28, 0xffffffbf
	v_lshl_add_u64 v[78:79], v[18:19], 0, v[24:25]
	v_mov_b32_e32 v0, s29
	v_mov_b32_e32 v24, s26
	v_cndmask_b32_e64 v24, v0, v24, s[40:41]
	v_ashrrev_i32_e32 v25, 31, v24
	v_lshlrev_b64 v[26:27], 14, v[24:25]
	s_add_i32 s27, s17, -5
	s_add_i32 s35, s28, 0xffffffbe
	v_lshl_add_u64 v[80:81], v[18:19], 0, v[26:27]
	v_mov_b32_e32 v0, s35
	v_mov_b32_e32 v26, s27
	v_cndmask_b32_e64 v26, v0, v26, s[40:41]
	v_ashrrev_i32_e32 v27, 31, v26
	v_lshlrev_b64 v[28:29], 14, v[26:27]
	s_add_i32 s23, s17, -4
	s_addk_i32 s28, 0xffbd
	v_lshl_add_u64 v[82:83], v[18:19], 0, v[28:29]
	v_mov_b32_e32 v0, s28
	v_mov_b32_e32 v28, s23
	v_lshlrev_b32_e32 v22, 6, v22
	v_lshlrev_b32_e32 v24, 6, v24
	v_cndmask_b32_e64 v28, v0, v28, s[40:41]
	v_ashrrev_i32_e32 v23, 31, v22
	v_ashrrev_i32_e32 v25, 31, v24
	v_ashrrev_i32_e32 v29, 31, v28
	v_lshl_add_u64 v[22:23], v[22:23], 2, v[62:63]
	v_lshl_add_u64 v[24:25], v[24:25], 2, v[62:63]
	v_lshlrev_b32_e32 v26, 6, v26
	v_lshlrev_b64 v[34:35], 14, v[28:29]
	v_lshlrev_b32_e32 v28, 6, v28
	global_load_dwordx4 v[30:33], v[22:23], off
	s_nop 0
	global_load_dwordx4 v[22:25], v[24:25], off
	v_ashrrev_i32_e32 v27, 31, v26
	v_lshl_add_u64 v[84:85], v[18:19], 0, v[34:35]
	global_load_dwordx2 v[90:91], v[78:79], off
	global_load_dwordx2 v[88:89], v[80:81], off
	global_load_dwordx2 v[86:87], v[82:83], off
	global_load_dwordx2 v[76:77], v[84:85], off
	v_ashrrev_i32_e32 v29, 31, v28
	v_lshl_add_u64 v[26:27], v[26:27], 2, v[62:63]
	v_lshl_add_u64 v[28:29], v[28:29], 2, v[62:63]
	global_load_dwordx4 v[34:37], v[26:27], off
	s_nop 0
	global_load_dwordx4 v[26:29], v[28:29], off
	s_cmpk_lg_i32 s17, 0x47
	s_cselect_b64 s[48:49], -1, 0
	s_cmpk_eq_i32 s17, 0x47
	s_cbranch_scc1 .LBB0_307
	s_add_i32 s8, s17, -3
	s_add_i32 s9, s20, 3
	v_mov_b32_e32 v0, s9
	v_mov_b32_e32 v14, s8
	v_cndmask_b32_e64 v14, v0, v14, s[40:41]
	v_mov_b32_e32 v15, v1
	v_lshlrev_b32_e32 v0, 6, v14
	v_lshlrev_b64 v[14:15], 14, v[14:15]
	v_lshl_add_u64 v[16:17], v[0:1], 2, v[62:63]
	v_lshl_add_u64 v[14:15], v[18:19], 0, v[14:15]
	global_load_dwordx2 v[46:47], v[14:15], off
	s_nop 0
	global_load_dwordx4 v[14:17], v[16:17], off
	s_cmp_lt_u32 s22, 63
	s_cselect_b64 s[10:11], -1, 0
	s_cmp_gt_u32 s22, 62
	s_cbranch_scc0 .LBB0_308

.LBB0_305:
	s_add_i32 s46, s17, -1
	s_add_i32 s47, s20, 1
	v_mov_b32_e32 v0, s47
	v_mov_b32_e32 v6, s46
	v_cndmask_b32_e64 v8, v0, v6, s[40:41]
	v_lshlrev_b32_e32 v0, 6, v8
	v_lshl_add_u64 v[6:7], v[0:1], 2, v[62:63]
	v_lshlrev_b32_e32 v0, 14, v8
	v_lshl_add_u64 v[8:9], v[18:19], 0, v[0:1]
	global_load_dwordx2 v[50:51], v[8:9], off
	s_nop 0
	global_load_dwordx4 v[6:9], v[6:7], off
	v_cndmask_b32_e64 v0, 0, 1, s[48:49]
	v_cmp_ne_u32_e64 s[46:47], 1, v0
	s_andn2_b64 vcc, exec, s[48:49]
	s_cbranch_vccz .LBB0_310

.LBB0_308:
	s_add_i32 s8, s17, -2
	s_add_i32 s9, s20, 2
	v_mov_b32_e32 v0, s9
	v_mov_b32_e32 v10, s8
	v_cndmask_b32_e64 v12, v0, v10, s[40:41]
	v_lshlrev_b32_e32 v0, 6, v12
	v_lshl_add_u64 v[10:11], v[0:1], 2, v[62:63]
	v_lshlrev_b32_e32 v0, 14, v12
	v_lshl_add_u64 v[12:13], v[18:19], 0, v[0:1]
	global_load_dwordx2 v[48:49], v[12:13], off
	s_nop 0
	global_load_dwordx4 v[10:13], v[10:11], off
	s_cmp_lt_u32 s22, 62
	s_cselect_b64 s[8:9], -1, 0
	s_cmp_gt_u32 s22, 61
	s_cbranch_scc0 .LBB0_305

.LBB0_310:
	v_mov_b32_e32 v0, s20
	v_mov_b32_e32 v2, s17
	v_cndmask_b32_e64 v2, v0, v2, s[40:41]
	v_mov_b32_e32 v3, v1
	v_lshlrev_b32_e32 v0, 6, v2
	v_lshlrev_b64 v[2:3], 14, v[2:3]
	v_lshl_add_u64 v[4:5], v[0:1], 2, v[62:63]
	v_lshl_add_u64 v[2:3], v[18:19], 0, v[2:3]
	global_load_dwordx2 v[52:53], v[2:3], off
	s_nop 0
	global_load_dwordx4 v[2:5], v[4:5], off
	s_and_saveexec_b64 s[48:49], s[36:37]
	s_cbranch_execz .LBB0_319
.LBB0_311:
	v_mov_b32_e32 v0, s52
	v_mov_b32_e32 v98, s22
	v_cndmask_b32_e64 v0, v0, v98, s[42:43]
	v_lshlrev_b32_e32 v104, 8, v0
	v_ashrrev_i32_e32 v105, 31, v104
	v_lshlrev_b64 v[104:105], 2, v[104:105]
	v_lshl_add_u64 v[106:107], v[64:65], 0, v[104:105]
	v_lshl_add_u64 v[104:105], v[66:67], 0, v[104:105]
	global_load_dword v98, v[106:107], off
	global_load_dword v103, v[104:105], off
	v_mov_b32_e32 v0, s29
	v_mov_b32_e32 v104, s26
	v_cndmask_b32_e64 v0, v0, v104, s[42:43]
	v_lshlrev_b32_e32 v104, 8, v0
	v_ashrrev_i32_e32 v105, 31, v104
	v_lshlrev_b64 v[106:107], 2, v[104:105]
	v_lshl_add_u64 v[104:105], v[64:65], 0, v[106:107]
	v_lshl_add_u64 v[106:107], v[66:67], 0, v[106:107]
	global_load_dword v104, v[104:105], off
	v_mov_b32_e32 v0, s35
	global_load_dword v105, v[106:107], off
	v_mov_b32_e32 v106, s27
	v_cndmask_b32_e64 v0, v0, v106, s[42:43]
	v_lshlrev_b32_e32 v106, 8, v0
	v_ashrrev_i32_e32 v107, 31, v106
	v_lshlrev_b64 v[108:109], 2, v[106:107]
	v_lshl_add_u64 v[106:107], v[64:65], 0, v[108:109]
	v_lshl_add_u64 v[108:109], v[66:67], 0, v[108:109]
	global_load_dword v106, v[106:107], off
	v_mov_b32_e32 v0, s28
	global_load_dword v107, v[108:109], off
	v_mov_b32_e32 v108, s23
	v_cndmask_b32_e64 v0, v0, v108, s[42:43]
	v_lshlrev_b32_e32 v108, 8, v0
	v_ashrrev_i32_e32 v109, 31, v108
	v_lshlrev_b64 v[116:117], 2, v[108:109]
	v_lshl_add_u64 v[108:109], v[64:65], 0, v[116:117]
	v_lshl_add_u64 v[116:117], v[66:67], 0, v[116:117]
	global_load_dword v108, v[108:109], off
	s_and_b64 vcc, exec, s[46:47]
	global_load_dword v109, v[116:117], off
	s_cbranch_vccnz .LBB0_315
	s_add_i32 s50, s17, -3
	s_add_i32 s51, s20, 3
	v_mov_b32_e32 v0, s51
	v_mov_b32_e32 v97, s50
	v_cndmask_b32_e64 v0, v0, v97, s[42:43]
	v_lshlrev_b32_e32 v0, 8, v0
	v_lshlrev_b64 v[116:117], 2, v[0:1]
	v_lshl_add_u64 v[118:119], v[66:67], 0, v[116:117]
	v_lshl_add_u64 v[116:117], v[64:65], 0, v[116:117]
	global_load_dword v97, v[116:117], off
	global_load_dword v102, v[118:119], off
	s_andn2_b64 vcc, exec, s[10:11]
	s_cbranch_vccz .LBB0_316

.LBB0_314:
	s_add_i32 s50, s17, -1
	s_add_i32 s51, s20, 1
	v_mov_b32_e32 v0, s51
	v_mov_b32_e32 v95, s50
	v_cndmask_b32_e64 v0, v0, v95, s[42:43]
	v_lshlrev_b32_e32 v0, 8, v0
	v_lshlrev_b64 v[116:117], 2, v[0:1]
	v_lshl_add_u64 v[118:119], v[66:67], 0, v[116:117]
	v_lshl_add_u64 v[116:117], v[64:65], 0, v[116:117]
	global_load_dword v95, v[116:117], off
	global_load_dword v100, v[118:119], off
	s_and_b64 vcc, exec, s[46:47]
	s_cbranch_vccz .LBB0_318
	s_branch .LBB0_319

.LBB0_316:
	s_add_i32 s50, s17, -2
	s_add_i32 s51, s20, 2
	v_mov_b32_e32 v0, s51
	v_mov_b32_e32 v96, s50
	v_cndmask_b32_e64 v0, v0, v96, s[42:43]
	v_lshlrev_b32_e32 v0, 8, v0
	v_lshlrev_b64 v[116:117], 2, v[0:1]
	v_lshl_add_u64 v[118:119], v[66:67], 0, v[116:117]
	v_lshl_add_u64 v[116:117], v[64:65], 0, v[116:117]
	global_load_dword v96, v[116:117], off
	global_load_dword v101, v[118:119], off
	s_andn2_b64 vcc, exec, s[8:9]
	s_cbranch_vccz .LBB0_314

.LBB0_318:
	v_mov_b32_e32 v0, s20
	v_mov_b32_e32 v94, s17
	v_cndmask_b32_e64 v0, v0, v94, s[42:43]
	v_lshlrev_b32_e32 v0, 8, v0
	v_lshlrev_b64 v[116:117], 2, v[0:1]
	v_lshl_add_u64 v[118:119], v[66:67], 0, v[116:117]
	v_lshl_add_u64 v[116:117], v[64:65], 0, v[116:117]
	global_load_dword v94, v[116:117], off
	global_load_dword v99, v[118:119], off
.LBB0_319:
	s_or_b64 exec, exec, s[48:49]
	s_and_saveexec_b64 s[48:49], s[38:39]
	s_cbranch_execz .LBB0_328
	v_mov_b32_e32 v0, s52
	v_mov_b32_e32 v54, s22
	v_cndmask_b32_e64 v54, v0, v54, s[44:45]
	v_mov_b32_e32 v0, s29
	v_mov_b32_e32 v56, s26
	v_cndmask_b32_e64 v56, v0, v56, s[44:45]
	v_mov_b32_e32 v0, s35
	v_mov_b32_e32 v58, s27
	v_cndmask_b32_e64 v58, v0, v58, s[44:45]
	v_mov_b32_e32 v0, s28
	v_mov_b32_e32 v60, s23
	v_cndmask_b32_e64 v60, v0, v60, s[44:45]
	v_ashrrev_i32_e32 v55, 31, v54
	v_ashrrev_i32_e32 v57, 31, v56
	v_ashrrev_i32_e32 v59, 31, v58
	v_ashrrev_i32_e32 v61, 31, v60
	v_lshlrev_b64 v[54:55], 13, v[54:55]
	v_lshlrev_b64 v[56:57], 13, v[56:57]
	v_lshlrev_b64 v[58:59], 13, v[58:59]
	v_lshlrev_b64 v[60:61], 13, v[60:61]
	v_lshl_add_u64 v[54:55], v[70:71], 0, v[54:55]
	v_lshl_add_u64 v[56:57], v[70:71], 0, v[56:57]
	v_lshl_add_u64 v[58:59], v[70:71], 0, v[58:59]
	v_lshl_add_u64 v[60:61], v[70:71], 0, v[60:61]
	global_load_dwordx2 v[54:55], v[54:55], off
	s_nop 0
	global_load_dwordx2 v[56:57], v[56:57], off
	s_nop 0
	global_load_dwordx2 v[58:59], v[58:59], off
	s_nop 0
	global_load_dwordx2 v[60:61], v[60:61], off
	s_and_b64 vcc, exec, s[46:47]
	s_cbranch_vccnz .LBB0_324
	s_add_i32 s50, s17, -3
	s_add_i32 s51, s20, 3
	v_mov_b32_e32 v0, s51
	v_mov_b32_e32 v44, s50
	v_cndmask_b32_e64 v0, v0, v44, s[44:45]
	v_lshlrev_b64 v[44:45], 13, v[0:1]
	v_lshl_add_u64 v[44:45], v[70:71], 0, v[44:45]
	global_load_dwordx2 v[44:45], v[44:45], off
	s_andn2_b64 vcc, exec, s[10:11]
	s_cbranch_vccz .LBB0_325

.LBB0_323:
	s_add_i32 s50, s17, -1
	s_add_i32 s51, s20, 1
	v_mov_b32_e32 v0, s51
	v_mov_b32_e32 v40, s50
	v_cndmask_b32_e64 v0, v0, v40, s[44:45]
	v_lshlrev_b32_e32 v0, 13, v0
	v_lshl_add_u64 v[40:41], v[70:71], 0, v[0:1]
	global_load_dwordx2 v[40:41], v[40:41], off
	s_and_b64 vcc, exec, s[46:47]
	s_cbranch_vccz .LBB0_327
	s_branch .LBB0_328

.LBB0_325:
	s_add_i32 s50, s17, -2
	s_add_i32 s51, s20, 2
	v_mov_b32_e32 v0, s51
	v_mov_b32_e32 v42, s50
	v_cndmask_b32_e64 v0, v0, v42, s[44:45]
	v_lshlrev_b32_e32 v0, 13, v0
	v_lshl_add_u64 v[42:43], v[70:71], 0, v[0:1]
	global_load_dwordx2 v[42:43], v[42:43], off
	s_andn2_b64 vcc, exec, s[8:9]
	s_cbranch_vccz .LBB0_323

.LBB0_327:
	v_mov_b32_e32 v0, s20
	v_mov_b32_e32 v38, s17
	v_cndmask_b32_e64 v0, v0, v38, s[44:45]
	v_lshlrev_b64 v[38:39], 13, v[0:1]
	v_lshl_add_u64 v[38:39], v[70:71], 0, v[38:39]
	global_load_dwordx2 v[38:39], v[38:39], off
.LBB0_328:
	s_or_b64 exec, exec, s[48:49]
	v_cvt_pk_bf16_f32 v116, v114, v113
	v_cvt_pk_bf16_f32 v117, v112, v111
	global_store_dwordx2 v[78:79], v[116:117], off
	s_waitcnt vmcnt(0) lgkmcnt(0)
	v_lshlrev_b32_e32 v79, 16, v91
	v_lshlrev_b32_e32 v0, 16, v90
	v_and_b32_e32 v78, 0xffff0000, v90
	v_fmac_f32_e32 v79, v112, v32
	v_and_b32_e32 v32, 0xffff0000, v91
	v_fmac_f32_e32 v0, v114, v30
	v_fmac_f32_e32 v78, v113, v31
	v_fmac_f32_e32 v32, v111, v33
	v_cvt_pk_bf16_f32 v30, v0, v78
	v_cvt_pk_bf16_f32 v31, v79, v32
	global_store_dwordx2 v[80:81], v[30:31], off
	v_lshlrev_b32_e32 v30, 16, v88
	v_lshlrev_b32_e32 v31, 16, v89
	v_fmac_f32_e32 v30, v22, v0
	v_and_b32_e32 v0, 0xffff0000, v88
	v_fmac_f32_e32 v31, v24, v79
	v_and_b32_e32 v24, 0xffff0000, v89
	v_fmac_f32_e32 v0, v23, v78
	v_fmac_f32_e32 v24, v25, v32
	v_lshlrev_b32_e32 v25, 16, v86
	v_cvt_pk_bf16_f32 v22, v30, v0
	v_fmac_f32_e32 v25, v34, v30
	v_and_b32_e32 v30, 0xffff0000, v86
	v_fmac_f32_e32 v30, v35, v0
	v_lshlrev_b32_e32 v0, 16, v87
	v_cvt_pk_bf16_f32 v23, v31, v24
	v_fmac_f32_e32 v0, v36, v31
	v_and_b32_e32 v31, 0xffff0000, v87
	v_fmac_f32_e32 v31, v37, v24
	v_lshlrev_b32_e32 v114, 16, v76
	v_and_b32_e32 v113, 0xffff0000, v76
	v_lshlrev_b32_e32 v112, 16, v77
	v_and_b32_e32 v111, 0xffff0000, v77
	global_store_dwordx2 v[82:83], v[22:23], off
	v_cvt_pk_bf16_f32 v22, v25, v30
	v_cvt_pk_bf16_f32 v23, v0, v31
	v_fmac_f32_e32 v114, v26, v25
	v_fmac_f32_e32 v113, v27, v30
	v_fmac_f32_e32 v112, v28, v0
	s_and_b64 vcc, exec, s[46:47]
	v_fmac_f32_e32 v111, v29, v31
	global_store_dwordx2 v[84:85], v[22:23], off
	s_cbranch_vccnz .LBB0_333
	s_add_i32 s48, s17, -3
	s_add_i32 s49, s20, 3
	v_mov_b32_e32 v0, s49
	v_mov_b32_e32 v22, s48
	v_cndmask_b32_e64 v0, v0, v22, s[40:41]
	v_lshlrev_b64 v[24:25], 14, v[0:1]
	v_cvt_pk_bf16_f32 v22, v114, v113
	v_cvt_pk_bf16_f32 v23, v112, v111
	v_lshl_add_u64 v[24:25], v[18:19], 0, v[24:25]
	global_store_dwordx2 v[24:25], v[22:23], off
	v_lshlrev_b32_e32 v0, 16, v46
	v_and_b32_e32 v22, 0xffff0000, v46
	v_lshlrev_b32_e32 v23, 16, v47
	v_and_b32_e32 v24, 0xffff0000, v47
	v_fmac_f32_e32 v0, v14, v114
	v_fmac_f32_e32 v22, v15, v113
	v_fmac_f32_e32 v23, v16, v112
	v_fmac_f32_e32 v24, v17, v111
	v_mov_b32_e32 v111, v24
	v_mov_b32_e32 v112, v23
	v_mov_b32_e32 v113, v22
	v_mov_b32_e32 v114, v0
	v_cndmask_b32_e64 v0, 0, 1, s[10:11]
	v_cmp_ne_u32_e64 s[48:49], 1, v0
	s_andn2_b64 vcc, exec, s[10:11]
	s_cbranch_vccz .LBB0_334

.LBB0_331:
	s_add_i32 s8, s17, -1
	s_add_i32 s9, s20, 1
	v_mov_b32_e32 v0, s9
	v_mov_b32_e32 v22, s8
	v_cndmask_b32_e64 v0, v0, v22, s[40:41]
	v_lshlrev_b32_e32 v0, 14, v0
	v_cvt_pk_bf16_f32 v22, v114, v113
	v_cvt_pk_bf16_f32 v23, v112, v111
	v_lshl_add_u64 v[24:25], v[18:19], 0, v[0:1]
	global_store_dwordx2 v[24:25], v[22:23], off
	v_lshlrev_b32_e32 v0, 16, v50
	v_and_b32_e32 v22, 0xffff0000, v50
	v_lshlrev_b32_e32 v23, 16, v51
	v_and_b32_e32 v24, 0xffff0000, v51
	v_fmac_f32_e32 v0, v6, v114
	v_fmac_f32_e32 v22, v7, v113
	v_fmac_f32_e32 v23, v8, v112
	v_fmac_f32_e32 v24, v9, v111
	v_mov_b32_e32 v111, v24
	v_mov_b32_e32 v112, v23
	v_mov_b32_e32 v113, v22
	v_mov_b32_e32 v114, v0
	s_and_b64 vcc, exec, s[46:47]
	s_cbranch_vccz .LBB0_336

.LBB0_334:
	s_add_i32 s10, s17, -2
	s_add_i32 s11, s20, 2
	v_mov_b32_e32 v0, s11
	v_mov_b32_e32 v22, s10
	v_cndmask_b32_e64 v0, v0, v22, s[40:41]
	v_lshlrev_b32_e32 v0, 14, v0
	v_cvt_pk_bf16_f32 v22, v114, v113
	v_cvt_pk_bf16_f32 v23, v112, v111
	v_lshl_add_u64 v[24:25], v[18:19], 0, v[0:1]
	global_store_dwordx2 v[24:25], v[22:23], off
	v_lshlrev_b32_e32 v0, 16, v48
	v_and_b32_e32 v22, 0xffff0000, v48
	v_lshlrev_b32_e32 v23, 16, v49
	v_and_b32_e32 v24, 0xffff0000, v49
	v_fmac_f32_e32 v0, v10, v114
	v_fmac_f32_e32 v22, v11, v113
	v_fmac_f32_e32 v23, v12, v112
	v_fmac_f32_e32 v24, v13, v111
	v_mov_b32_e32 v111, v24
	v_mov_b32_e32 v112, v23
	v_mov_b32_e32 v113, v22
	v_mov_b32_e32 v114, v0
	v_cndmask_b32_e64 v0, 0, 1, s[8:9]
	v_cmp_ne_u32_e64 s[50:51], 1, v0
	s_andn2_b64 vcc, exec, s[8:9]
	s_cbranch_vccz .LBB0_331

.LBB0_336:
	v_mov_b32_e32 v0, s20
	v_mov_b32_e32 v22, s17
	v_cndmask_b32_e64 v0, v0, v22, s[40:41]
	v_lshlrev_b64 v[24:25], 14, v[0:1]
	v_cvt_pk_bf16_f32 v22, v114, v113
	v_cvt_pk_bf16_f32 v23, v112, v111
	v_lshl_add_u64 v[24:25], v[18:19], 0, v[24:25]
	global_store_dwordx2 v[24:25], v[22:23], off
	v_lshlrev_b32_e32 v0, 16, v52
	v_and_b32_e32 v22, 0xffff0000, v52
	v_lshlrev_b32_e32 v23, 16, v53
	v_and_b32_e32 v24, 0xffff0000, v53
	v_fmac_f32_e32 v0, v2, v114
	v_fmac_f32_e32 v22, v3, v113
	v_fmac_f32_e32 v23, v4, v112
	v_fmac_f32_e32 v24, v5, v111
	v_mov_b32_e32 v111, v24
	v_mov_b32_e32 v112, v23
	v_mov_b32_e32 v113, v22
	v_mov_b32_e32 v114, v0
	s_and_saveexec_b64 s[8:9], s[36:37]
	s_cbranch_execz .LBB0_345
.LBB0_337:
	v_mov_b32_e32 v0, s52
	v_mov_b32_e32 v22, s22
	v_cndmask_b32_e64 v0, v0, v22, s[42:43]
	v_lshlrev_b32_e32 v22, 8, v0
	v_ashrrev_i32_e32 v23, 31, v22
	v_lshl_add_u64 v[22:23], v[22:23], 2, v[68:69]
	global_store_dword v[22:23], v110, off
	v_mov_b32_e32 v22, s29
	v_mov_b32_e32 v23, s26
	v_cndmask_b32_e64 v22, v22, v23, s[42:43]
	v_lshlrev_b32_e32 v22, 8, v22
	v_ashrrev_i32_e32 v23, 31, v22
	v_fma_f32 v0, v110, v98, v103
	v_lshl_add_u64 v[22:23], v[22:23], 2, v[68:69]
	global_store_dword v[22:23], v0, off
	v_mov_b32_e32 v22, s35
	v_mov_b32_e32 v23, s27
	v_cndmask_b32_e64 v22, v22, v23, s[42:43]
	v_lshlrev_b32_e32 v22, 8, v22
	v_ashrrev_i32_e32 v23, 31, v22
	v_fma_f32 v0, v104, v0, v105
	v_lshl_add_u64 v[22:23], v[22:23], 2, v[68:69]
	global_store_dword v[22:23], v0, off
	v_mov_b32_e32 v22, s28
	v_mov_b32_e32 v23, s23
	v_cndmask_b32_e64 v22, v22, v23, s[42:43]
	v_lshlrev_b32_e32 v22, 8, v22
	v_fma_f32 v0, v106, v0, v107
	v_ashrrev_i32_e32 v23, 31, v22
	v_lshl_add_u64 v[22:23], v[22:23], 2, v[68:69]
	s_and_b64 vcc, exec, s[46:47]
	v_fma_f32 v110, v108, v0, v109
	global_store_dword v[22:23], v0, off
	s_cbranch_vccnz .LBB0_341
	s_add_i32 s10, s17, -3
	s_add_i32 s11, s20, 3
	v_mov_b32_e32 v0, s11
	v_mov_b32_e32 v22, s10
	v_cndmask_b32_e64 v0, v0, v22, s[42:43]
	v_lshlrev_b32_e32 v0, 8, v0
	v_fma_f32 v24, v97, v110, v102
	v_lshl_add_u64 v[22:23], v[0:1], 2, v[68:69]
	global_store_dword v[22:23], v110, off
	v_mov_b32_e32 v110, v24
	s_and_b64 vcc, exec, s[48:49]
	s_cbranch_vccz .LBB0_342

.LBB0_340:
	s_add_i32 s10, s17, -1
	s_add_i32 s11, s20, 1
	v_mov_b32_e32 v0, s11
	v_mov_b32_e32 v22, s10
	v_cndmask_b32_e64 v0, v0, v22, s[42:43]
	v_lshlrev_b32_e32 v0, 8, v0
	v_fma_f32 v24, v95, v110, v100
	v_lshl_add_u64 v[22:23], v[0:1], 2, v[68:69]
	global_store_dword v[22:23], v110, off
	v_mov_b32_e32 v110, v24
	s_and_b64 vcc, exec, s[46:47]
	s_cbranch_vccz .LBB0_344
	s_branch .LBB0_345

.LBB0_342:
	s_add_i32 s10, s17, -2
	s_add_i32 s11, s20, 2
	v_mov_b32_e32 v0, s11
	v_mov_b32_e32 v22, s10
	v_cndmask_b32_e64 v0, v0, v22, s[42:43]
	v_lshlrev_b32_e32 v0, 8, v0
	v_fma_f32 v24, v96, v110, v101
	v_lshl_add_u64 v[22:23], v[0:1], 2, v[68:69]
	global_store_dword v[22:23], v110, off
	v_mov_b32_e32 v110, v24
	s_and_b64 vcc, exec, s[50:51]
	s_cbranch_vccz .LBB0_340

.LBB0_344:
	v_mov_b32_e32 v0, s20
	v_mov_b32_e32 v22, s17
	v_cndmask_b32_e64 v0, v0, v22, s[42:43]
	v_lshlrev_b32_e32 v0, 8, v0
	v_fma_f32 v24, v94, v110, v99
	v_lshl_add_u64 v[22:23], v[0:1], 2, v[68:69]
	global_store_dword v[22:23], v110, off
	v_mov_b32_e32 v110, v24
.LBB0_345:
	s_or_b64 exec, exec, s[8:9]
	s_and_saveexec_b64 s[8:9], s[38:39]
	s_cbranch_execz .LBB0_301
	v_mov_b32_e32 v0, s52
	v_mov_b32_e32 v22, s22
	v_cndmask_b32_e64 v22, v0, v22, s[44:45]
	v_ashrrev_i32_e32 v23, 31, v22
	v_lshlrev_b64 v[22:23], 13, v[22:23]
	v_mul_f32_e32 v0, v21, v75
	v_lshl_add_u64 v[22:23], v[72:73], 0, v[22:23]
	v_fma_f32 v0, v20, v74, -v0
	global_store_dwordx2 v[22:23], v[74:75], off
	v_add_f32_e32 v22, v0, v54
	v_mul_f32_e32 v0, v20, v75
	v_fmac_f32_e32 v0, v21, v74
	v_add_f32_e32 v23, v0, v55
	v_mov_b32_e32 v0, s29
	v_mov_b32_e32 v24, s26
	v_cndmask_b32_e64 v24, v0, v24, s[44:45]
	v_ashrrev_i32_e32 v25, 31, v24
	v_lshlrev_b64 v[24:25], 13, v[24:25]
	v_mul_f32_e32 v0, v21, v23
	v_lshl_add_u64 v[24:25], v[72:73], 0, v[24:25]
	v_fma_f32 v0, v20, v22, -v0
	global_store_dwordx2 v[24:25], v[22:23], off
	v_add_f32_e32 v24, v56, v0
	v_mul_f32_e32 v0, v21, v22
	v_fmac_f32_e32 v0, v20, v23
	v_add_f32_e32 v25, v57, v0
	v_mov_b32_e32 v0, s35
	v_mov_b32_e32 v22, s27
	v_cndmask_b32_e64 v22, v0, v22, s[44:45]
	v_ashrrev_i32_e32 v23, 31, v22
	v_lshlrev_b64 v[22:23], 13, v[22:23]
	v_mul_f32_e32 v0, v21, v25
	v_lshl_add_u64 v[22:23], v[72:73], 0, v[22:23]
	v_fma_f32 v0, v20, v24, -v0
	global_store_dwordx2 v[22:23], v[24:25], off
	v_add_f32_e32 v22, v58, v0
	v_mul_f32_e32 v0, v21, v24
	v_fmac_f32_e32 v0, v20, v25
	v_add_f32_e32 v23, v59, v0
	v_mov_b32_e32 v0, s28
	v_mov_b32_e32 v24, s23
	v_cndmask_b32_e64 v24, v0, v24, s[44:45]
	v_mul_f32_e32 v0, v21, v23
	v_fma_f32 v0, v20, v22, -v0
	v_ashrrev_i32_e32 v25, 31, v24
	v_add_f32_e32 v74, v60, v0
	v_mul_f32_e32 v0, v21, v22
	v_lshlrev_b64 v[24:25], 13, v[24:25]
	v_fmac_f32_e32 v0, v20, v23
	v_lshl_add_u64 v[24:25], v[72:73], 0, v[24:25]
	s_and_b64 vcc, exec, s[46:47]
	v_add_f32_e32 v75, v61, v0
	global_store_dwordx2 v[24:25], v[22:23], off
	s_cbranch_vccnz .LBB0_350
	s_add_i32 s10, s17, -3
	s_add_i32 s11, s20, 3
	v_mov_b32_e32 v0, s11
	v_mov_b32_e32 v22, s10
	v_cndmask_b32_e64 v0, v0, v22, s[44:45]
	v_lshlrev_b64 v[22:23], 13, v[0:1]
	v_lshl_add_u64 v[22:23], v[72:73], 0, v[22:23]
	v_mul_f32_e32 v0, v21, v75
	global_store_dwordx2 v[22:23], v[74:75], off
	v_fma_f32 v0, v20, v74, -v0
	v_mul_f32_e32 v22, v21, v74
	v_add_f32_e32 v0, v44, v0
	v_fmac_f32_e32 v22, v20, v75
	v_add_f32_e32 v75, v45, v22
	v_mov_b32_e32 v74, v0
	s_and_b64 vcc, exec, s[48:49]
	s_cbranch_vccz .LBB0_351

.LBB0_349:
	s_add_i32 s10, s17, -1
	s_add_i32 s11, s20, 1
	v_mov_b32_e32 v0, s11
	v_mov_b32_e32 v22, s10
	v_cndmask_b32_e64 v0, v0, v22, s[44:45]
	v_lshlrev_b32_e32 v0, 13, v0
	v_lshl_add_u64 v[22:23], v[72:73], 0, v[0:1]
	v_mul_f32_e32 v0, v21, v75
	global_store_dwordx2 v[22:23], v[74:75], off
	v_fma_f32 v0, v20, v74, -v0
	v_mul_f32_e32 v22, v21, v74
	v_add_f32_e32 v0, v40, v0
	v_fmac_f32_e32 v22, v20, v75
	v_add_f32_e32 v75, v41, v22
	v_mov_b32_e32 v74, v0
	s_and_b64 vcc, exec, s[46:47]
	s_cbranch_vccnz .LBB0_301
	s_branch .LBB0_353

.LBB0_351:
	s_add_i32 s10, s17, -2
	s_add_i32 s11, s20, 2
	v_mov_b32_e32 v0, s11
	v_mov_b32_e32 v22, s10
	v_cndmask_b32_e64 v0, v0, v22, s[44:45]
	v_lshlrev_b32_e32 v0, 13, v0
	v_lshl_add_u64 v[22:23], v[72:73], 0, v[0:1]
	v_mul_f32_e32 v0, v21, v75
	global_store_dwordx2 v[22:23], v[74:75], off
	v_fma_f32 v0, v20, v74, -v0
	v_mul_f32_e32 v22, v21, v74
	v_add_f32_e32 v0, v42, v0
	v_fmac_f32_e32 v22, v20, v75
	v_add_f32_e32 v75, v43, v22
	v_mov_b32_e32 v74, v0
	s_and_b64 vcc, exec, s[50:51]
	s_cbranch_vccz .LBB0_349

.LBB0_353:
	v_mov_b32_e32 v0, s20
	v_mov_b32_e32 v22, s17
	v_cndmask_b32_e64 v0, v0, v22, s[44:45]
	v_lshlrev_b64 v[22:23], 13, v[0:1]
	v_lshl_add_u64 v[22:23], v[72:73], 0, v[22:23]
	v_mul_f32_e32 v0, v21, v75
	global_store_dwordx2 v[22:23], v[74:75], off
	v_fma_f32 v0, v20, v74, -v0
	v_mul_f32_e32 v22, v21, v74
	v_add_f32_e32 v0, v38, v0
	v_fmac_f32_e32 v22, v20, v75
	v_add_f32_e32 v75, v39, v22
	v_mov_b32_e32 v74, v0
	s_branch .LBB0_301

.LBB0_361:
	v_mov_b32_e32 v26, v204
	v_mov_b32_e32 v0, s59
	ds_read_b64 v[6:7], v0
	v_mov_b32_e32 v0, s45
	ds_read2_b64 v[2:5], v0 offset1:1
	s_and_b32 s7, s20, 3
	v_ashrrev_i32_e32 v27, 3, v26
	s_waitcnt lgkmcnt(0)
	v_readfirstlane_b32 s4, v6
	v_readfirstlane_b32 s5, v7
	s_add_u32 s4, s4, 0xe000000
	v_and_b32_e32 v0, -16, v27
	s_addc_u32 s5, s5, 0
	v_add_u32_e32 v22, s6, v0
	v_readfirstlane_b32 s8, v5
	v_readfirstlane_b32 s9, v4
	v_add_u32_e32 v0, 8, v22
	v_mov_b64_e32 v[4:5], s[4:5]
	v_add_u32_e32 v8, 9, v22
	v_add_u32_e32 v10, 10, v22
	v_add_u32_e32 v12, 11, v22
	v_add_u32_e32 v14, 12, v22
	v_add_u32_e32 v16, 13, v22
	v_add_u32_e32 v18, 14, v22
	v_add_u32_e32 v20, 15, v22
	v_readfirstlane_b32 s1, v3
	v_readfirstlane_b32 s0, v2
	v_mov_b32_e32 v2, s9
	v_mov_b32_e32 v3, s8
	v_mad_i64_i32 v[6:7], s[8:9], v0, s94, v[4:5]
	s_lshl_b32 s78, s7, 8
	v_and_b32_e32 v0, 0x7f, v26
	v_mad_i64_i32 v[8:9], s[8:9], v8, s94, v[4:5]
	v_mad_i64_i32 v[10:11], s[8:9], v10, s94, v[4:5]
	v_mad_i64_i32 v[12:13], s[8:9], v12, s94, v[4:5]
	v_mad_i64_i32 v[14:15], s[8:9], v14, s94, v[4:5]
	v_mad_i64_i32 v[16:17], s[8:9], v16, s94, v[4:5]
	v_mad_i64_i32 v[18:19], s[8:9], v18, s94, v[4:5]
	v_mad_i64_i32 v[20:21], s[8:9], v20, s94, v[4:5]
	v_lshl_add_u64 v[6:7], v[6:7], 0, s[78:79]
	v_lshlrev_b32_e32 v0, 1, v0
	v_lshl_add_u64 v[8:9], v[8:9], 0, s[78:79]
	v_lshl_add_u64 v[10:11], v[10:11], 0, s[78:79]
	v_lshl_add_u64 v[12:13], v[12:13], 0, s[78:79]
	v_lshl_add_u64 v[14:15], v[14:15], 0, s[78:79]
	v_lshl_add_u64 v[16:17], v[16:17], 0, s[78:79]
	v_lshl_add_u64 v[18:19], v[18:19], 0, s[78:79]
	v_lshl_add_u64 v[20:21], v[20:21], 0, s[78:79]
	v_lshl_add_u64 v[6:7], v[6:7], 0, v[0:1]
	v_lshl_add_u64 v[8:9], v[8:9], 0, v[0:1]
	v_lshl_add_u64 v[10:11], v[10:11], 0, v[0:1]
	v_lshl_add_u64 v[12:13], v[12:13], 0, v[0:1]
	v_lshl_add_u64 v[14:15], v[14:15], 0, v[0:1]
	v_lshl_add_u64 v[16:17], v[16:17], 0, v[0:1]
	v_lshl_add_u64 v[18:19], v[18:19], 0, v[0:1]
	v_lshl_add_u64 v[20:21], v[20:21], 0, v[0:1]
	global_load_ushort v28, v[6:7], off offset:1024
	global_load_ushort v29, v[8:9], off offset:1024
	global_load_ushort v30, v[10:11], off offset:1024
	global_load_ushort v31, v[12:13], off offset:1024
	global_load_ushort v32, v[14:15], off offset:1024
	global_load_ushort v33, v[16:17], off offset:1024
	global_load_ushort v34, v[18:19], off offset:1024
	global_load_ushort v35, v[20:21], off offset:1024
	v_add_u32_e32 v8, 1, v22
	v_add_u32_e32 v10, 2, v22
	v_add_u32_e32 v12, 3, v22
	v_add_u32_e32 v14, 4, v22
	v_add_u32_e32 v16, 5, v22
	v_add_u32_e32 v18, 6, v22
	v_add_u32_e32 v20, 7, v22
	s_lshl_b32 s11, s7, 7
	v_mad_i64_i32 v[6:7], s[8:9], v22, s94, v[4:5]
	v_mad_i64_i32 v[8:9], s[8:9], v8, s94, v[4:5]
	v_mad_i64_i32 v[10:11], s[8:9], v10, s94, v[4:5]
	v_mad_i64_i32 v[12:13], s[8:9], v12, s94, v[4:5]
	v_mad_i64_i32 v[14:15], s[8:9], v14, s94, v[4:5]
	v_mad_i64_i32 v[16:17], s[8:9], v16, s94, v[4:5]
	v_mad_i64_i32 v[18:19], s[8:9], v18, s94, v[4:5]
	v_mad_i64_i32 v[20:21], s[8:9], v20, s94, v[4:5]
	s_lshl_b32 s7, s7, 6
	v_lshl_add_u64 v[6:7], v[6:7], 0, s[78:79]
	v_lshl_add_u64 v[8:9], v[8:9], 0, s[78:79]
	v_lshl_add_u64 v[10:11], v[10:11], 0, s[78:79]
	v_lshl_add_u64 v[12:13], v[12:13], 0, s[78:79]
	v_lshl_add_u64 v[14:15], v[14:15], 0, s[78:79]
	v_lshl_add_u64 v[16:17], v[16:17], 0, s[78:79]
	v_lshl_add_u64 v[18:19], v[18:19], 0, s[78:79]
	v_lshl_add_u64 v[20:21], v[20:21], 0, s[78:79]
	s_add_u32 s4, s4, s11
	v_and_b32_e32 v44, 63, v26
	v_readfirstlane_b32 s10, v26
	v_lshl_add_u64 v[6:7], v[6:7], 0, v[0:1]
	v_lshl_add_u64 v[8:9], v[8:9], 0, v[0:1]
	v_lshl_add_u64 v[10:11], v[10:11], 0, v[0:1]
	v_lshl_add_u64 v[12:13], v[12:13], 0, v[0:1]
	v_lshl_add_u64 v[14:15], v[14:15], 0, v[0:1]
	v_lshl_add_u64 v[16:17], v[16:17], 0, v[0:1]
	v_lshl_add_u64 v[18:19], v[18:19], 0, v[0:1]
	v_lshl_add_u64 v[20:21], v[20:21], 0, v[0:1]
	s_addc_u32 s5, s5, 0
	v_lshlrev_b32_e32 v0, 1, v44
	global_load_ushort v36, v[6:7], off offset:1024
	global_load_ushort v37, v[8:9], off offset:1024
	global_load_ushort v38, v[10:11], off offset:1024
	global_load_ushort v39, v[12:13], off offset:1024
	global_load_ushort v40, v[14:15], off offset:1024
	global_load_ushort v41, v[16:17], off offset:1024
	global_load_ushort v42, v[18:19], off offset:1024
	global_load_ushort v43, v[20:21], off offset:1024
	v_lshl_add_u64 v[6:7], s[4:5], 0, v[0:1]
	s_ashr_i32 s4, s10, 3
	s_and_b32 s4, s4, -8
	s_add_i32 s8, s4, s6
	s_add_i32 s4, s8, 7
	v_mad_i64_i32 v[8:9], s[4:5], s4, v216, v[6:7]
	s_add_i32 s4, s8, 6
	s_nop 0
	v_mad_i64_i32 v[10:11], s[4:5], s4, v216, v[6:7]
	s_add_i32 s4, s8, 5
	s_nop 0
	v_mad_i64_i32 v[12:13], s[4:5], s4, v216, v[6:7]
	s_add_i32 s4, s8, 4
	s_nop 0
	v_mad_i64_i32 v[18:19], s[4:5], s4, v216, v[6:7]
	s_add_i32 s4, s8, 3
	s_nop 0
	v_mad_i64_i32 v[20:21], s[4:5], s4, v216, v[6:7]
	s_add_i32 s4, s8, 2
	s_nop 0
	v_mad_i64_i32 v[22:23], s[4:5], s4, v216, v[6:7]
	s_add_i32 s4, s8, 1
	s_nop 0
	v_mad_i64_i32 v[24:25], s[4:5], s4, v216, v[6:7]
	v_mad_i64_i32 v[6:7], s[4:5], s8, v216, v[6:7]
	s_or_b32 s4, s7, s84
	s_nop 0
	v_or_b32_e32 v0, s4, v44
	global_load_ushort v14, v[8:9], off offset:512
	global_load_ushort v15, v[10:11], off offset:512
	global_load_ushort v16, v[12:13], off offset:512
	global_load_ushort v17, v[18:19], off offset:512
	s_nop 0
	global_load_ushort v18, v[20:21], off offset:512
	global_load_ushort v19, v[22:23], off offset:512
	s_nop 0
	global_load_ushort v20, v[24:25], off offset:512
	global_load_ushort v21, v[6:7], off offset:512
	v_lshl_add_u64 v[2:3], v[0:1], 2, v[2:3]
	v_add_u32_e32 v0, 0x600, v26
	v_add_u32_e32 v6, 0x400, v26
	v_add_u32_e32 v8, 0x200, v26
	global_load_dword v60, v[2:3], off offset:1024
	global_load_dword v61, v[2:3], off
	v_ashrrev_i32_e32 v2, 6, v0
	v_ashrrev_i32_e32 v6, 6, v6
	v_ashrrev_i32_e32 v9, 6, v8
	v_ashrrev_i32_e32 v11, 6, v26
	v_and_b32_e32 v2, -16, v2
	v_and_b32_e32 v6, -16, v6
	v_and_b32_e32 v9, -16, v9
	v_and_b32_e32 v11, -16, v11
	v_add_u32_e32 v2, s21, v2
	v_lshrrev_b32_e32 v0, 6, v0
	v_add_u32_e32 v6, s21, v6
	v_bfe_u32 v10, v26, 6, 4
	v_add_u32_e32 v9, s21, v9
	v_lshrrev_b32_e32 v8, 6, v8
	v_add_u32_e32 v11, s21, v11
	v_and_or_b32 v2, v0, 15, v2
	v_or_b32_e32 v6, v6, v10
	v_and_or_b32 v8, v8, 15, v9
	v_or_b32_e32 v10, v11, v10
	v_ashrrev_i32_e32 v3, 31, v2
	v_ashrrev_i32_e32 v7, 31, v6
	v_ashrrev_i32_e32 v9, 31, v8
	v_ashrrev_i32_e32 v11, 31, v10
	v_lshlrev_b64 v[2:3], 10, v[2:3]
	v_lshlrev_b64 v[6:7], 10, v[6:7]
	v_lshlrev_b64 v[8:9], 10, v[8:9]
	v_lshlrev_b64 v[10:11], 10, v[10:11]
	v_lshl_add_u64 v[2:3], s[0:1], 0, v[2:3]
	v_lshl_add_u64 v[6:7], s[0:1], 0, v[6:7]
	v_lshl_add_u64 v[8:9], s[0:1], 0, v[8:9]
	v_lshl_add_u64 v[10:11], s[0:1], 0, v[10:11]
	v_lshl_add_u64 v[2:3], v[2:3], 0, s[78:79]
	v_lshlrev_b32_e32 v0, 2, v44
	v_lshl_add_u64 v[6:7], v[6:7], 0, s[78:79]
	v_lshl_add_u64 v[8:9], v[8:9], 0, s[78:79]
	v_lshl_add_u64 v[10:11], v[10:11], 0, s[78:79]
	v_lshl_add_u64 v[2:3], v[2:3], 0, v[0:1]
	v_lshl_add_u64 v[6:7], v[6:7], 0, v[0:1]
	v_lshl_add_u64 v[8:9], v[8:9], 0, v[0:1]
	v_lshl_add_u64 v[10:11], v[10:11], 0, v[0:1]
	v_add_u32_e32 v0, s6, v27
	global_load_dword v23, v[2:3], off
	global_load_dword v24, v[6:7], off
	global_load_dword v25, v[8:9], off
	global_load_dword v22, v[10:11], off
	v_mad_i64_i32 v[2:3], s[0:1], v0, s94, v[4:5]
	v_lshlrev_b32_e32 v0, 3, v26
	v_and_b32_e32 v0, 56, v0
	v_lshl_add_u64 v[2:3], v[2:3], 0, v[0:1]
	v_add_co_u32_e32 v2, vcc, s91, v2
	v_mov_b32_e32 v0, v1
	s_nop 0
	v_addc_co_u32_e32 v3, vcc, 0, v3, vcc
	global_load_dwordx2 v[12:13], v[2:3], off offset:512
	s_waitcnt vmcnt(0) lgkmcnt(0)
	v_perm_b32 v2, v37, v36, s2
	v_perm_b32 v3, v39, v38, s2
	v_perm_b32 v4, v41, v40, s2
	v_perm_b32 v5, v43, v42, s2
	v_perm_b32 v6, v29, v28, s2
	v_perm_b32 v7, v31, v30, s2
	v_perm_b32 v8, v33, v32, s2
	v_perm_b32 v9, v35, v34, s2
	s_lshl_b32 s8, s20, 1
	v_mov_b32_e32 v53, 0
	v_mov_b32_e32 v36, 0
	v_mov_b32_e32 v52, 0
	s_mov_b32 s6, s20
	v_mov_b64_e32 v[10:11], v[0:1]
	v_mov_b32_e32 v54, 0
	v_mov_b32_e32 v51, 0
	v_mov_b32_e32 v50, 0
	v_mov_b32_e32 v42, 0
	v_mov_b32_e32 v43, 0
	v_mov_b32_e32 v44, 0
	v_mov_b32_e32 v45, 0
	v_mov_b32_e32 v46, 0
	v_mov_b32_e32 v47, 0
	v_mov_b32_e32 v48, 0
	v_mov_b32_e32 v49, 0
	v_mov_b32_e32 v41, 0
	v_mov_b32_e32 v37, 0
	v_mov_b32_e32 v38, 0
	v_mov_b32_e32 v39, 0
	v_mov_b32_e32 v40, 0
	v_mov_b32_e32 v55, 0
	v_mov_b32_e32 v56, 0
	v_mov_b32_e32 v57, 0
	v_mov_b32_e32 v58, 0
	v_mov_b32_e32 v59, 0
	s_branch .LBB0_363
.LBB0_362:
	s_waitcnt vmcnt(0)
	v_perm_b32 v57, v174, v173, s2
	v_perm_b32 v59, v178, v177, s2
	v_perm_b32 v53, v179, v58, s2
	v_perm_b32 v58, v176, v175, s2
	v_perm_b32 v55, v181, v180, s2
	v_perm_b32 v56, v56, v182, s2
	v_mov_b32_e32 v0, s59
	s_waitcnt lgkmcnt(0)
	s_barrier
	ds_read_b64 v[6:7], v0
	v_and_b32_e32 v8, 15, v62
	v_lshrrev_b32_e32 v0, 1, v62
	v_and_b32_e32 v0, 24, v0
	v_lshl_or_b32 v28, s10, 4, v8
	s_movk_i32 s10, 0x90
	v_lshlrev_b32_e32 v9, 1, v0
	v_mul_lo_u32 v2, v28, s10
	s_waitcnt lgkmcnt(0)
	v_readfirstlane_b32 s11, v6
	v_mul_u32_u24_e32 v6, 0x90, v8
	v_add3_u32 v32, s92, v2, v9
	v_add3_u32 v33, 0, v9, v6
	ds_read_b128 v[2:5], v32
	v_readfirstlane_b32 s10, v7
	ds_read_b128 v[6:9], v33 offset:22528
	ds_read_b128 v[12:15], v33 offset:22592
	ds_read_b128 v[16:19], v32 offset:64
	ds_read_b128 v[20:23], v33 offset:31744
	ds_read_b128 v[24:27], v33 offset:31808
	s_waitcnt lgkmcnt(0)
	v_mfma_f32_16x16x32_bf16 v[6:9], v[6:9], v[2:5], 0
	s_add_u32 s11, s11, 0x18c00000
	s_addc_u32 s10, s10, 0
	s_lshl_b64 s[6:7], s[6:7], 14
	v_mfma_f32_16x16x32_bf16 v[2:5], v[20:23], v[2:5], 0
	s_add_u32 s6, s11, s6
	s_addc_u32 s7, s10, s7
	s_lshl_b64 s[4:5], s[4:5], 14
	v_mfma_f32_16x16x32_bf16 v[6:9], v[12:15], v[16:19], v[6:9]
	s_add_u32 s4, s11, s4
	v_ashrrev_i32_e32 v29, 31, v28
	s_addc_u32 s5, s10, s5
	v_mfma_f32_16x16x32_bf16 v[2:5], v[24:27], v[16:19], v[2:5]
	v_lshlrev_b64 v[12:13], 7, v[28:29]
	v_lshl_add_u64 v[14:15], s[6:7], 0, v[12:13]
	v_lshl_add_u64 v[12:13], s[4:5], 0, v[12:13]
	v_lshl_add_u64 v[28:29], v[14:15], 0, v[0:1]
	v_lshl_add_u64 v[30:31], v[12:13], 0, v[0:1]
	v_cvt_pk_bf16_f32 v6, v6, v7
	v_cvt_pk_bf16_f32 v7, v8, v9
	s_nop 0
	v_cvt_pk_bf16_f32 v2, v2, v3
	v_cvt_pk_bf16_f32 v3, v4, v5
	global_store_dwordx2 v[28:29], v[6:7], off
	global_store_dwordx2 v[30:31], v[2:3], off
	ds_read_b128 v[2:5], v33 offset:24832
	ds_read_b128 v[6:9], v33 offset:24896
	ds_read_b128 v[12:15], v32
	ds_read_b128 v[16:19], v32 offset:64
	s_waitcnt lgkmcnt(0)
	v_mfma_f32_16x16x32_bf16 v[2:5], v[2:5], v[12:15], 0
	ds_read_b128 v[20:23], v33 offset:34048
	s_add_i32 s8, s8, s83
	s_andn2_b64 vcc, exec, s[0:1]
	v_mfma_f32_16x16x32_bf16 v[2:5], v[6:9], v[16:19], v[2:5]
	ds_read_b128 v[6:9], v33 offset:34112
	s_mov_b32 s6, s9
	v_mov_b32_e32 v60, v36
	s_waitcnt lgkmcnt(0)
	v_mfma_f32_16x16x32_bf16 v[12:15], v[20:23], v[12:15], 0
	v_mov_b32_e32 v61, v41
	s_nop 1
	v_cvt_pk_bf16_f32 v2, v2, v3
	v_cvt_pk_bf16_f32 v3, v4, v5
	v_mfma_f32_16x16x32_bf16 v[6:9], v[6:9], v[16:19], v[12:15]
	global_store_dwordx2 v[28:29], v[2:3], off offset:32
	v_mov_b32_e32 v24, v38
	v_mov_b32_e32 v25, v39
	s_nop 4
	v_cvt_pk_bf16_f32 v2, v6, v7
	v_cvt_pk_bf16_f32 v3, v8, v9
	global_store_dwordx2 v[30:31], v[2:3], off offset:32
	ds_read_b128 v[2:5], v33 offset:27136
	ds_read_b128 v[6:9], v33 offset:27200
	ds_read_b128 v[12:15], v32
	ds_read_b128 v[16:19], v32 offset:64
	s_waitcnt lgkmcnt(0)
	v_mfma_f32_16x16x32_bf16 v[2:5], v[2:5], v[12:15], 0
	ds_read_b128 v[20:23], v33 offset:36352
	v_mfma_f32_16x16x32_bf16 v[2:5], v[6:9], v[16:19], v[2:5]
	ds_read_b128 v[6:9], v33 offset:36416
	s_waitcnt lgkmcnt(0)
	v_mfma_f32_16x16x32_bf16 v[12:15], v[20:23], v[12:15], 0
	s_nop 4
	v_cvt_pk_bf16_f32 v2, v2, v3
	v_mfma_f32_16x16x32_bf16 v[6:9], v[6:9], v[16:19], v[12:15]
	v_cvt_pk_bf16_f32 v3, v4, v5
	global_store_dwordx2 v[28:29], v[2:3], off offset:64
	s_nop 5
	v_cvt_pk_bf16_f32 v2, v6, v7
	v_cvt_pk_bf16_f32 v3, v8, v9
	global_store_dwordx2 v[30:31], v[2:3], off offset:64
	ds_read_b128 v[2:5], v33 offset:29440
	ds_read_b128 v[6:9], v33 offset:29504
	ds_read_b128 v[12:15], v32
	ds_read_b128 v[16:19], v32 offset:64
	s_waitcnt lgkmcnt(0)
	v_mfma_f32_16x16x32_bf16 v[2:5], v[2:5], v[12:15], 0
	ds_read_b128 v[20:23], v33 offset:38656
	v_mfma_f32_16x16x32_bf16 v[2:5], v[6:9], v[16:19], v[2:5]
	ds_read_b128 v[6:9], v33 offset:38720
	s_waitcnt lgkmcnt(0)
	v_mfma_f32_16x16x32_bf16 v[12:15], v[20:23], v[12:15], 0
	v_mov_b32_e32 v22, v40
	s_nop 3
	v_cvt_pk_bf16_f32 v2, v2, v3
	v_cvt_pk_bf16_f32 v3, v4, v5
	v_mfma_f32_16x16x32_bf16 v[6:9], v[6:9], v[16:19], v[12:15]
	global_store_dwordx2 v[28:29], v[2:3], off offset:96
	v_alignbit_b32 v4, v59, v58, 16
	v_alignbit_b32 v5, v51, v59, 16
	v_mov_b64_e32 v[12:13], v[10:11]
	v_mov_b32_e32 v14, v42
	s_nop 2
	v_cvt_pk_bf16_f32 v2, v6, v7
	v_cvt_pk_bf16_f32 v3, v8, v9
	global_store_dwordx2 v[30:31], v[2:3], off offset:96
	v_perm_b32 v2, v57, v50, s2
	v_alignbit_b32 v3, v58, v57, 16
	v_perm_b32 v6, v53, v54, s2
	v_alignbit_b32 v7, v55, v53, 16
	v_alignbit_b32 v8, v56, v55, 16
	v_alignbit_b32 v9, v52, v56, 16
	v_mov_b32_e32 v15, v43
	v_mov_b32_e32 v16, v44
	v_mov_b32_e32 v17, v45
	v_mov_b32_e32 v18, v46
	v_mov_b32_e32 v19, v47
	v_mov_b32_e32 v20, v48
	v_mov_b32_e32 v21, v49
	v_mov_b32_e32 v23, v37
	s_waitcnt lgkmcnt(0)
	s_barrier
	s_cbranch_vccz .LBB0_371

.LBB0_368:
	v_mov_b32_e32 v54, v204
	v_mov_b32_e32 v0, s59
	ds_read_b64 v[10:11], v0
	s_and_b32 s22, s9, 3
	v_mov_b32_e32 v0, s45
	v_ashrrev_i32_e32 v55, 3, v54
	ds_read2_b64 v[26:29], v0 offset1:1
	s_waitcnt lgkmcnt(0)
	v_readfirstlane_b32 s4, v10
	v_readfirstlane_b32 s5, v11
	s_add_u32 s4, s4, 0xe000000
	s_addc_u32 s5, s5, 0
	v_add_u32_e32 v0, s7, v55
	v_mov_b64_e32 v[30:31], s[4:5]
	v_mad_i64_i32 v[10:11], s[10:11], v0, s94, v[30:31]
	v_lshlrev_b32_e32 v0, 3, v54
	v_and_b32_e32 v0, 56, v0
	v_add_u32_e32 v36, 0x600, v54
	v_lshl_add_u64 v[10:11], v[10:11], 0, v[0:1]
	v_ashrrev_i32_e32 v0, 6, v54
	v_add_u32_e32 v32, 0x200, v54
	v_add_u32_e32 v35, 0x400, v54
	v_lshrrev_b32_e32 v37, 6, v36
	v_ashrrev_i32_e32 v36, 6, v36
	v_and_b32_e32 v0, -16, v0
	v_lshrrev_b32_e32 v33, 6, v32
	v_ashrrev_i32_e32 v32, 6, v32
	v_ashrrev_i32_e32 v35, 6, v35
	v_and_b32_e32 v36, -16, v36
	v_bfe_u32 v34, v54, 6, 4
	v_add_u32_e32 v0, s21, v0
	v_and_b32_e32 v32, -16, v32
	v_and_b32_e32 v35, -16, v35
	v_add_u32_e32 v36, s21, v36
	s_waitcnt lgkmcnt(0)
	v_readfirstlane_b32 s10, v26
	v_or_b32_e32 v26, v0, v34
	v_add_u32_e32 v32, s21, v32
	v_add_u32_e32 v35, s21, v35
	v_and_or_b32 v36, v37, 15, v36
	v_readfirstlane_b32 s11, v27
	v_ashrrev_i32_e32 v27, 31, v26
	v_and_or_b32 v32, v33, 15, v32
	v_or_b32_e32 v34, v35, v34
	v_ashrrev_i32_e32 v37, 31, v36
	v_lshlrev_b64 v[26:27], 10, v[26:27]
	v_ashrrev_i32_e32 v33, 31, v32
	v_ashrrev_i32_e32 v35, 31, v34
	v_lshlrev_b64 v[36:37], 10, v[36:37]
	v_and_b32_e32 v42, 63, v54
	v_lshl_add_u64 v[26:27], s[10:11], 0, v[26:27]
	s_lshl_b32 s78, s22, 8
	v_lshlrev_b64 v[32:33], 10, v[32:33]
	v_lshlrev_b64 v[34:35], 10, v[34:35]
	v_lshl_add_u64 v[36:37], s[10:11], 0, v[36:37]
	v_add_co_u32_e32 v10, vcc, s91, v10
	v_lshl_add_u64 v[26:27], v[26:27], 0, s[78:79]
	v_lshlrev_b32_e32 v0, 2, v42
	v_lshl_add_u64 v[32:33], s[10:11], 0, v[32:33]
	v_lshl_add_u64 v[34:35], s[10:11], 0, v[34:35]
	v_lshl_add_u64 v[36:37], v[36:37], 0, s[78:79]
	v_readfirstlane_b32 s10, v54
	v_addc_co_u32_e32 v11, vcc, 0, v11, vcc
	s_lshl_b32 s23, s22, 6
	v_lshl_add_u64 v[26:27], v[26:27], 0, v[0:1]
	v_lshl_add_u64 v[32:33], v[32:33], 0, s[78:79]
	v_lshl_add_u64 v[34:35], v[34:35], 0, s[78:79]
	v_lshl_add_u64 v[36:37], v[36:37], 0, v[0:1]
	v_readfirstlane_b32 s11, v29
	s_ashr_i32 s10, s10, 3
	global_load_dwordx2 v[10:11], v[10:11], off offset:512
	v_lshl_add_u64 v[32:33], v[32:33], 0, v[0:1]
	v_lshl_add_u64 v[34:35], v[34:35], 0, v[0:1]
	global_load_dword v40, v[26:27], off
	global_load_dword v39, v[32:33], off
	global_load_dword v38, v[34:35], off
	s_nop 0
	global_load_dword v37, v[36:37], off
	v_mov_b32_e32 v27, s11
	s_or_b32 s11, s23, s84
	s_and_b32 s10, s10, -8
	v_readfirstlane_b32 s26, v28
	v_or_b32_e32 v0, s11, v42
	s_add_i32 s10, s10, s7
	s_lshl_b32 s11, s22, 7
	v_mov_b32_e32 v26, s26
	s_add_u32 s4, s4, s11
	v_lshl_add_u64 v[26:27], v[0:1], 2, v[26:27]
	s_addc_u32 s5, s5, 0
	v_lshlrev_b32_e32 v0, 1, v42
	global_load_dword v41, v[26:27], off
	global_load_dword v36, v[26:27], off offset:1024
	v_lshl_add_u64 v[26:27], s[4:5], 0, v[0:1]
	v_mad_i64_i32 v[28:29], s[4:5], s10, v216, v[26:27]
	s_add_i32 s4, s10, 1
	s_nop 0
	v_mad_i64_i32 v[32:33], s[4:5], s4, v216, v[26:27]
	s_add_i32 s4, s10, 2
	s_nop 0
	v_mad_i64_i32 v[34:35], s[4:5], s4, v216, v[26:27]
	s_add_i32 s4, s10, 3
	s_nop 0
	v_mad_i64_i32 v[42:43], s[4:5], s4, v216, v[26:27]
	s_add_i32 s4, s10, 4
	s_nop 0
	v_mad_i64_i32 v[44:45], s[4:5], s4, v216, v[26:27]
	s_add_i32 s4, s10, 5
	s_nop 0
	v_mad_i64_i32 v[50:51], s[4:5], s4, v216, v[26:27]
	s_add_i32 s4, s10, 6
	s_add_i32 s10, s10, 7
	v_mad_i64_i32 v[52:53], s[4:5], s4, v216, v[26:27]
	v_mad_i64_i32 v[26:27], s[4:5], s10, v216, v[26:27]
	global_load_ushort v49, v[28:29], off offset:512
	global_load_ushort v48, v[32:33], off offset:512
	global_load_ushort v47, v[34:35], off offset:512
	global_load_ushort v46, v[42:43], off offset:512
	s_nop 0
	global_load_ushort v45, v[44:45], off offset:512
	s_nop 0
	global_load_ushort v44, v[50:51], off offset:512
	global_load_ushort v43, v[52:53], off offset:512
	global_load_ushort v42, v[26:27], off offset:512
	v_and_b32_e32 v26, -16, v55
	v_add_u32_e32 v62, s7, v26
	v_add_u32_e32 v50, 4, v62
	v_and_b32_e32 v0, 0x7f, v54
	v_mad_i64_i32 v[50:51], s[4:5], v50, s94, v[30:31]
	v_lshlrev_b32_e32 v0, 1, v0
	v_lshl_add_u64 v[50:51], v[50:51], 0, s[78:79]
	v_lshl_add_u64 v[52:53], v[50:51], 0, v[0:1]
	v_add_u32_e32 v50, 5, v62
	v_mad_i64_i32 v[50:51], s[4:5], v50, s94, v[30:31]
	v_lshl_add_u64 v[50:51], v[50:51], 0, s[78:79]
	v_lshl_add_u64 v[54:55], v[50:51], 0, v[0:1]
	v_add_u32_e32 v50, 6, v62
	v_mad_i64_i32 v[50:51], s[4:5], v50, s94, v[30:31]
	v_add_u32_e32 v28, 1, v62
	v_add_u32_e32 v32, 2, v62
	v_add_u32_e32 v34, 3, v62
	v_lshl_add_u64 v[50:51], v[50:51], 0, s[78:79]
	v_mad_i64_i32 v[26:27], s[4:5], v62, s94, v[30:31]
	v_mad_i64_i32 v[28:29], s[4:5], v28, s94, v[30:31]
	v_mad_i64_i32 v[32:33], s[4:5], v32, s94, v[30:31]
	v_mad_i64_i32 v[34:35], s[4:5], v34, s94, v[30:31]
	v_lshl_add_u64 v[56:57], v[50:51], 0, v[0:1]
	v_add_u32_e32 v50, 7, v62
	v_lshl_add_u64 v[26:27], v[26:27], 0, s[78:79]
	v_lshl_add_u64 v[28:29], v[28:29], 0, s[78:79]
	v_lshl_add_u64 v[32:33], v[32:33], 0, s[78:79]
	v_lshl_add_u64 v[34:35], v[34:35], 0, s[78:79]
	v_mad_i64_i32 v[50:51], s[4:5], v50, s94, v[30:31]
	v_lshl_add_u64 v[26:27], v[26:27], 0, v[0:1]
	v_lshl_add_u64 v[28:29], v[28:29], 0, v[0:1]
	v_lshl_add_u64 v[32:33], v[32:33], 0, v[0:1]
	v_lshl_add_u64 v[34:35], v[34:35], 0, v[0:1]
	v_lshl_add_u64 v[50:51], v[50:51], 0, s[78:79]
	v_lshl_add_u64 v[58:59], v[50:51], 0, v[0:1]
	global_load_ushort v50, v[26:27], off offset:1024
	global_load_ushort v173, v[28:29], off offset:1024
	global_load_ushort v174, v[32:33], off offset:1024
	global_load_ushort v175, v[34:35], off offset:1024
	global_load_ushort v176, v[52:53], off offset:1024
	global_load_ushort v177, v[54:55], off offset:1024
	global_load_ushort v178, v[56:57], off offset:1024
	global_load_ushort v51, v[58:59], off offset:1024
	v_add_u32_e32 v28, 9, v62
	v_add_u32_e32 v32, 10, v62
	v_add_u32_e32 v34, 11, v62
	v_add_u32_e32 v56, 14, v62
	v_mad_i64_i32 v[28:29], s[4:5], v28, s94, v[30:31]
	v_mad_i64_i32 v[32:33], s[4:5], v32, s94, v[30:31]
	v_mad_i64_i32 v[34:35], s[4:5], v34, s94, v[30:31]
	v_add_u32_e32 v52, 12, v62
	v_add_u32_e32 v54, 13, v62
	v_mad_i64_i32 v[56:57], s[4:5], v56, s94, v[30:31]
	v_lshl_add_u64 v[28:29], v[28:29], 0, s[78:79]
	v_lshl_add_u64 v[32:33], v[32:33], 0, s[78:79]
	v_lshl_add_u64 v[34:35], v[34:35], 0, s[78:79]
	v_mad_i64_i32 v[52:53], s[4:5], v52, s94, v[30:31]
	v_mad_i64_i32 v[54:55], s[4:5], v54, s94, v[30:31]
	v_lshl_add_u64 v[56:57], v[56:57], 0, s[78:79]
	v_lshl_add_u64 v[28:29], v[28:29], 0, v[0:1]
	v_lshl_add_u64 v[32:33], v[32:33], 0, v[0:1]
	v_lshl_add_u64 v[34:35], v[34:35], 0, v[0:1]
	v_lshl_add_u64 v[52:53], v[52:53], 0, s[78:79]
	v_lshl_add_u64 v[54:55], v[54:55], 0, s[78:79]
	v_lshl_add_u64 v[56:57], v[56:57], 0, v[0:1]
	v_lshl_add_u64 v[52:53], v[52:53], 0, v[0:1]
	v_lshl_add_u64 v[54:55], v[54:55], 0, v[0:1]
	global_load_ushort v58, v[28:29], off offset:1024
	s_nop 0
	global_load_ushort v179, v[32:33], off offset:1024
	s_nop 0
	global_load_ushort v180, v[34:35], off offset:1024
	s_nop 0
	global_load_ushort v181, v[52:53], off offset:1024
	global_load_ushort v182, v[54:55], off offset:1024
	s_nop 0
	global_load_ushort v56, v[56:57], off offset:1024
	v_add_u32_e32 v28, 15, v62
	v_add_u32_e32 v26, 8, v62
	v_mad_i64_i32 v[28:29], s[4:5], v28, s94, v[30:31]
	v_mad_i64_i32 v[26:27], s[4:5], v26, s94, v[30:31]
	v_lshl_add_u64 v[28:29], v[28:29], 0, s[78:79]
	v_lshl_add_u64 v[26:27], v[26:27], 0, s[78:79]
	v_lshl_add_u64 v[28:29], v[28:29], 0, v[0:1]
	v_lshl_add_u64 v[26:27], v[26:27], 0, v[0:1]
	global_load_ushort v52, v[28:29], off offset:1024
	global_load_ushort v54, v[26:27], off offset:1024
	s_waitcnt lgkmcnt(0)
.LBB0_369:
	v_mov_b32_e32 v62, v204
	v_mov_b32_e32 v30, v204
	s_ashr_i32 s4, s6, 2
	s_mul_hi_i32 s5, s4, 0x78787879
	v_lshl_add_u32 v0, v30, 4, 0
	v_lshlrev_b32_e32 v26, 16, v12
	v_and_b32_e32 v27, 0xffff0000, v12
	v_lshlrev_b32_e32 v28, 16, v13
	v_and_b32_e32 v29, 0xffff0000, v13
	v_mad_u64_u32 v[12:13], s[22:23], v30, -12, v[0:1]
	s_lshr_b32 s6, s5, 31
	s_ashr_i32 s5, s5, 5
	ds_write_b128 v0, v[26:29]
	ds_write2st64_b32 v12, v22, v25 offset0:32 offset1:40
	ds_write2st64_b32 v12, v24, v23 offset0:48 offset1:56
	v_ashrrev_i32_e32 v12, 3, v30
	s_add_i32 s5, s5, s6
	v_and_b32_e32 v0, 0x7f, v30
	v_lshlrev_b32_e32 v12, 1, v12
	s_mul_i32 s6, s5, 0x44
	v_readfirstlane_b32 s7, v30
	v_mul_u32_u24_e32 v0, 0x90, v0
	v_and_b32_e32 v12, 0xffffffe0, v12
	s_sub_i32 s4, s4, s6
	s_ashr_i32 s6, s7, 6
	v_add3_u32 v0, s92, v0, v12
	ds_write_b128 v0, v[2:5]
	ds_write_b128 v0, v[6:9] offset:16
	v_lshlrev_b32_e32 v2, 2, v30
	s_lshl_b32 s22, s6, 10
	v_and_b32_e32 v71, 0xfc, v2
	s_add_i32 s22, s22, 0
	v_add_u32_e32 v70, 0, v71
	v_mov_b32_e32 v72, s22
	v_lshlrev_b32_e32 v69, 16, v21
	v_lshlrev_b32_e32 v68, 16, v20
	v_lshlrev_b32_e32 v67, 16, v19
	v_lshlrev_b32_e32 v66, 16, v18
	v_lshlrev_b32_e32 v65, 16, v17
	v_lshlrev_b32_e32 v64, 16, v16
	v_lshlrev_b32_e32 v63, 16, v15
	v_lshlrev_b32_e32 v0, 16, v14
	s_waitcnt lgkmcnt(0)
	s_barrier
	ds_read2st64_b32 v[28:29], v70 offset0:32 offset1:33
	ds_read2st64_b32 v[30:31], v70 offset0:34 offset1:35
	ds_read2st64_b32 v[26:27], v70 offset0:36 offset1:37
	ds_read2st64_b32 v[24:25], v70 offset0:38 offset1:39
	ds_read2st64_b32 v[34:35], v70 offset0:48 offset1:49
	ds_read2st64_b32 v[32:33], v70 offset0:50 offset1:51
	ds_read2st64_b32 v[22:23], v70 offset0:52 offset1:53
	ds_read2st64_b32 v[20:21], v70 offset0:54 offset1:55
	ds_read2st64_b32 v[12:13], v70 offset0:40 offset1:41
	ds_read2st64_b32 v[14:15], v70 offset0:42 offset1:43
	ds_read2st64_b32 v[8:9], v70 offset0:44 offset1:45
	ds_read2st64_b32 v[6:7], v70 offset0:46 offset1:47
	ds_read2st64_b32 v[18:19], v70 offset0:56 offset1:57
	ds_read2st64_b32 v[16:17], v70 offset0:58 offset1:59
	ds_read2st64_b32 v[4:5], v70 offset0:60 offset1:61
	ds_read2st64_b32 v[2:3], v70 offset0:62 offset1:63
	ds_read_b128 v[74:77], v72
	ds_read_b128 v[78:81], v72 offset:64
	ds_read_b128 v[82:85], v72 offset:16
	ds_read_b128 v[86:89], v72 offset:32
	ds_read_b128 v[90:93], v72 offset:48
	s_waitcnt lgkmcnt(0)
	v_mul_f32_e32 v73, v29, v75
	v_fmac_f32_e32 v73, v28, v74
	v_fmac_f32_e32 v73, v30, v76
	v_fmac_f32_e32 v73, v31, v77
	ds_read_b128 v[74:77], v72 offset:80
	s_waitcnt lgkmcnt(4)
	v_mul_f32_e32 v79, v35, v79
	v_fmac_f32_e32 v79, v34, v78
	v_fmac_f32_e32 v79, v32, v80
	v_fmac_f32_e32 v79, v33, v81
	s_waitcnt lgkmcnt(0)
	v_mul_f32_e32 v75, v23, v75
	v_fmac_f32_e32 v75, v22, v74
	v_fmac_f32_e32 v75, v20, v76
	v_add_f32_e32 v78, v60, v79
	v_mul_f32_e32 v79, v27, v83
	v_fmac_f32_e32 v75, v21, v77
	v_fmac_f32_e32 v79, v26, v82
	v_add_f32_e32 v82, v78, v75
	ds_read_b128 v[74:77], v72 offset:96
	v_mul_f32_e32 v78, v13, v87
	v_fmac_f32_e32 v79, v24, v84
	v_fmac_f32_e32 v78, v12, v86
	v_add_f32_e32 v73, v61, v73
	v_fmac_f32_e32 v79, v25, v85
	v_fmac_f32_e32 v78, v14, v88
	v_add_f32_e32 v73, v73, v79
	v_fmac_f32_e32 v78, v15, v89
	v_add_f32_e32 v73, v73, v78
	ds_read_b128 v[78:81], v72 offset:112
	s_waitcnt lgkmcnt(0)
	v_mul_f32_e32 v75, v19, v75
	v_fmac_f32_e32 v75, v18, v74
	v_fmac_f32_e32 v75, v16, v76
	v_fmac_f32_e32 v75, v17, v77
	v_add_f32_e32 v74, v82, v75
	v_mul_f32_e32 v75, v9, v91
	v_fmac_f32_e32 v75, v8, v90
	v_fmac_f32_e32 v75, v6, v92
	v_fmac_f32_e32 v75, v7, v93
	v_add_f32_e32 v73, v73, v75
	s_waitcnt lgkmcnt(0)
	v_mul_f32_e32 v75, v5, v79
	v_fmac_f32_e32 v75, v4, v78
	v_mul_f32_e64 v76, |v73|, s58
	v_fmac_f32_e32 v75, v2, v80
	v_exp_f32_e32 v76, v76
	v_fmac_f32_e32 v75, v3, v81
	v_add_f32_e32 v75, v74, v75
	v_mul_f32_e64 v74, |v75|, s58
	v_exp_f32_e32 v74, v74
	v_add_f32_e32 v76, 1.0, v76
	v_log_f32_e32 v76, v76
	v_min_f32_e32 v73, 0, v73
	v_add_f32_e32 v74, 1.0, v74
	v_log_f32_e32 v80, v74
	v_fma_f32 v74, v73, s82, -v76
	ds_read_b128 v[76:79], v72 offset:128
	v_min_f32_e32 v73, 0, v75
	v_fma_f32 v73, v73, s82, -v80
	ds_read_b128 v[80:83], v72 offset:192
	ds_read_b128 v[84:87], v72 offset:144
	s_mov_b32 s22, 0x3d800000
	s_waitcnt lgkmcnt(0)
	v_mul_f32_e32 v75, v29, v77
	v_fmac_f32_e32 v75, v28, v76
	v_fmac_f32_e32 v75, v30, v78
	v_fmac_f32_e32 v75, v31, v79
	ds_read_b128 v[76:79], v72 offset:208
	s_waitcnt lgkmcnt(2)
	v_mul_f32_e32 v81, v35, v81
	v_fmac_f32_e32 v81, v34, v80
	s_waitcnt lgkmcnt(1)
	v_mul_f32_e32 v80, v27, v85
	v_fmac_f32_e32 v80, v26, v84
	v_fmac_f32_e32 v81, v32, v82
	v_fmac_f32_e32 v80, v24, v86
	v_add_f32_e32 v75, v61, v75
	v_fmac_f32_e32 v81, v33, v83
	v_fmac_f32_e32 v80, v25, v87
	v_add_f32_e32 v88, v60, v81
	v_add_f32_e32 v75, v75, v80
	ds_read_b128 v[80:83], v72 offset:160
	s_waitcnt lgkmcnt(0)
	v_mul_f32_e32 v77, v23, v77
	v_fmac_f32_e32 v77, v22, v76
	v_fmac_f32_e32 v77, v20, v78
	v_fmac_f32_e32 v77, v21, v79
	v_add_f32_e32 v88, v88, v77
	ds_read_b128 v[76:79], v72 offset:224
	ds_read_b128 v[84:87], v72 offset:176
	s_waitcnt lgkmcnt(2)
	v_mul_f32_e32 v81, v13, v81
	v_fmac_f32_e32 v81, v12, v80
	v_fmac_f32_e32 v81, v14, v82
	s_waitcnt lgkmcnt(0)
	v_mul_f32_e32 v77, v19, v77
	v_fmac_f32_e32 v77, v18, v76
	v_fmac_f32_e32 v81, v15, v83
	v_fmac_f32_e32 v77, v16, v78
	v_add_f32_e32 v75, v75, v81
	ds_read_b128 v[80:83], v72 offset:240
	v_fmac_f32_e32 v77, v17, v79
	v_add_f32_e32 v76, v88, v77
	s_waitcnt lgkmcnt(1)
	v_mul_f32_e32 v77, v9, v85
	v_fmac_f32_e32 v77, v8, v84
	v_fmac_f32_e32 v77, v6, v86
	v_fmac_f32_e32 v77, v7, v87
	v_add_f32_e32 v75, v75, v77
	s_waitcnt lgkmcnt(0)
	v_mul_f32_e32 v77, v5, v81
	v_fmac_f32_e32 v77, v4, v80
	v_mul_f32_e64 v78, |v75|, s58
	v_fmac_f32_e32 v77, v2, v82
	v_exp_f32_e32 v78, v78
	v_fmac_f32_e32 v77, v3, v83
	v_add_f32_e32 v77, v76, v77
	v_mul_f32_e64 v76, |v77|, s58
	v_exp_f32_e32 v76, v76
	v_add_f32_e32 v78, 1.0, v78
	v_log_f32_e32 v78, v78
	v_min_f32_e32 v75, 0, v75
	v_add_f32_e32 v76, 1.0, v76
	v_log_f32_e32 v82, v76
	v_fma_f32 v76, v75, s82, -v78
	ds_read_b128 v[78:81], v72 offset:256
	v_min_f32_e32 v75, 0, v77
	v_fma_f32 v75, v75, s82, -v82
	ds_read_b128 v[82:85], v72 offset:320
	ds_read_b128 v[86:89], v72 offset:272
	s_and_b32 s7, s7, 0x3fffffc0
	s_waitcnt lgkmcnt(0)
	v_mul_f32_e32 v77, v29, v79
	v_fmac_f32_e32 v77, v28, v78
	v_fmac_f32_e32 v77, v30, v80
	v_fmac_f32_e32 v77, v31, v81
	ds_read_b128 v[78:81], v72 offset:336
	s_waitcnt lgkmcnt(2)
	v_mul_f32_e32 v83, v35, v83
	v_fmac_f32_e32 v83, v34, v82
	s_waitcnt lgkmcnt(1)
	v_mul_f32_e32 v82, v27, v87
	v_fmac_f32_e32 v82, v26, v86
	v_fmac_f32_e32 v83, v32, v84
	v_fmac_f32_e32 v82, v24, v88
	v_add_f32_e32 v77, v61, v77
	v_fmac_f32_e32 v83, v33, v85
	v_fmac_f32_e32 v82, v25, v89
	v_add_f32_e32 v90, v60, v83
	v_add_f32_e32 v77, v77, v82
	ds_read_b128 v[82:85], v72 offset:288
	s_waitcnt lgkmcnt(0)
	v_mul_f32_e32 v79, v23, v79
	v_fmac_f32_e32 v79, v22, v78
	v_fmac_f32_e32 v79, v20, v80
	v_fmac_f32_e32 v79, v21, v81
	v_add_f32_e32 v90, v90, v79
	ds_read_b128 v[78:81], v72 offset:352
	ds_read_b128 v[86:89], v72 offset:304
	s_waitcnt lgkmcnt(2)
	v_mul_f32_e32 v83, v13, v83
	v_fmac_f32_e32 v83, v12, v82
	v_fmac_f32_e32 v83, v14, v84
	s_waitcnt lgkmcnt(0)
	v_mul_f32_e32 v79, v19, v79
	v_fmac_f32_e32 v79, v18, v78
	v_fmac_f32_e32 v83, v15, v85
	v_fmac_f32_e32 v79, v16, v80
	v_add_f32_e32 v77, v77, v83
	ds_read_b128 v[82:85], v72 offset:368
	v_fmac_f32_e32 v79, v17, v81
	v_add_f32_e32 v78, v90, v79
	s_waitcnt lgkmcnt(1)
	v_mul_f32_e32 v79, v9, v87
	v_fmac_f32_e32 v79, v8, v86
	v_fmac_f32_e32 v79, v6, v88
	v_fmac_f32_e32 v79, v7, v89
	v_add_f32_e32 v77, v77, v79
	s_waitcnt lgkmcnt(0)
	v_mul_f32_e32 v79, v5, v83
	v_fmac_f32_e32 v79, v4, v82
	v_mul_f32_e64 v80, |v77|, s58
	v_fmac_f32_e32 v79, v2, v84
	v_exp_f32_e32 v80, v80
	v_fmac_f32_e32 v79, v3, v85
	v_add_f32_e32 v79, v78, v79
	v_mul_f32_e64 v78, |v79|, s58
	v_exp_f32_e32 v78, v78
	v_add_f32_e32 v80, 1.0, v80
	v_log_f32_e32 v80, v80
	v_min_f32_e32 v77, 0, v77
	v_add_f32_e32 v78, 1.0, v78
	v_log_f32_e32 v84, v78
	v_fma_f32 v78, v77, s82, -v80
	ds_read_b128 v[80:83], v72 offset:384
	v_min_f32_e32 v77, 0, v79
	v_fma_f32 v77, v77, s82, -v84
	ds_read_b128 v[84:87], v72 offset:448
	ds_read_b128 v[88:91], v72 offset:400
	s_lshl_b32 s7, s7, 2
	s_waitcnt lgkmcnt(0)
	v_mul_f32_e32 v79, v29, v81
	v_fmac_f32_e32 v79, v28, v80
	v_fmac_f32_e32 v79, v30, v82
	v_fmac_f32_e32 v79, v31, v83
	ds_read_b128 v[80:83], v72 offset:464
	s_waitcnt lgkmcnt(2)
	v_mul_f32_e32 v85, v35, v85
	v_fmac_f32_e32 v85, v34, v84
	s_waitcnt lgkmcnt(1)
	v_mul_f32_e32 v84, v27, v89
	v_fmac_f32_e32 v84, v26, v88
	v_fmac_f32_e32 v85, v32, v86
	v_fmac_f32_e32 v84, v24, v90
	v_add_f32_e32 v79, v61, v79
	v_fmac_f32_e32 v85, v33, v87
	v_fmac_f32_e32 v84, v25, v91
	v_add_f32_e32 v92, v60, v85
	v_add_f32_e32 v79, v79, v84
	ds_read_b128 v[84:87], v72 offset:416
	s_waitcnt lgkmcnt(0)
	v_mul_f32_e32 v81, v23, v81
	v_fmac_f32_e32 v81, v22, v80
	v_fmac_f32_e32 v81, v20, v82
	v_fmac_f32_e32 v81, v21, v83
	v_add_f32_e32 v92, v92, v81
	ds_read_b128 v[80:83], v72 offset:480
	ds_read_b128 v[88:91], v72 offset:432
	s_waitcnt lgkmcnt(2)
	v_mul_f32_e32 v85, v13, v85
	v_fmac_f32_e32 v85, v12, v84
	v_fmac_f32_e32 v85, v14, v86
	s_waitcnt lgkmcnt(0)
	v_mul_f32_e32 v81, v19, v81
	v_fmac_f32_e32 v81, v18, v80
	v_fmac_f32_e32 v85, v15, v87
	v_fmac_f32_e32 v81, v16, v82
	v_add_f32_e32 v79, v79, v85
	ds_read_b128 v[84:87], v72 offset:496
	v_fmac_f32_e32 v81, v17, v83
	v_add_f32_e32 v80, v92, v81
	s_waitcnt lgkmcnt(1)
	v_mul_f32_e32 v81, v9, v89
	v_fmac_f32_e32 v81, v8, v88
	v_fmac_f32_e32 v81, v6, v90
	v_fmac_f32_e32 v81, v7, v91
	v_add_f32_e32 v79, v79, v81
	s_waitcnt lgkmcnt(0)
	v_mul_f32_e32 v81, v5, v85
	v_fmac_f32_e32 v81, v4, v84
	v_mul_f32_e64 v82, |v79|, s58
	v_fmac_f32_e32 v81, v2, v86
	v_exp_f32_e32 v82, v82
	v_fmac_f32_e32 v81, v3, v87
	v_add_f32_e32 v84, v80, v81
	v_mul_f32_e64 v80, |v84|, s58
	v_exp_f32_e32 v80, v80
	v_add_f32_e32 v81, 1.0, v82
	v_log_f32_e32 v81, v81
	v_min_f32_e32 v79, 0, v79
	v_add_f32_e32 v80, 1.0, v80
	v_log_f32_e32 v85, v80
	v_fma_f32 v79, v79, s82, -v81
	ds_read_b128 v[80:83], v72 offset:512
	v_min_f32_e32 v84, 0, v84
	v_fma_f32 v92, v84, s82, -v85
	ds_read_b128 v[84:87], v72 offset:576
	ds_read_b128 v[88:91], v72 offset:528
	v_readfirstlane_b32 s11, v62
	s_waitcnt lgkmcnt(0)
	v_mul_f32_e32 v81, v29, v81
	v_fmac_f32_e32 v81, v28, v80
	v_fmac_f32_e32 v81, v30, v82
	v_fmac_f32_e32 v81, v31, v83
	v_add_f32_e32 v93, v61, v81
	ds_read_b128 v[80:83], v72 offset:592
	s_waitcnt lgkmcnt(2)
	v_mul_f32_e32 v85, v35, v85
	v_fmac_f32_e32 v85, v34, v84
	s_waitcnt lgkmcnt(1)
	v_mul_f32_e32 v84, v27, v89
	v_fmac_f32_e32 v84, v26, v88
	v_fmac_f32_e32 v85, v32, v86
	v_fmac_f32_e32 v84, v24, v90
	v_fmac_f32_e32 v85, v33, v87
	v_fmac_f32_e32 v84, v25, v91
	v_add_f32_e32 v94, v60, v85
	v_add_f32_e32 v93, v93, v84
	ds_read_b128 v[84:87], v72 offset:544
	s_waitcnt lgkmcnt(0)
	v_mul_f32_e32 v81, v23, v81
	v_fmac_f32_e32 v81, v22, v80
	v_fmac_f32_e32 v81, v20, v82
	v_fmac_f32_e32 v81, v21, v83
	v_add_f32_e32 v94, v94, v81
	ds_read_b128 v[80:83], v72 offset:608
	ds_read_b128 v[88:91], v72 offset:560
	s_waitcnt lgkmcnt(2)
	v_mul_f32_e32 v85, v13, v85
	v_fmac_f32_e32 v85, v12, v84
	v_fmac_f32_e32 v85, v14, v86
	s_waitcnt lgkmcnt(0)
	v_mul_f32_e32 v81, v19, v81
	v_fmac_f32_e32 v81, v18, v80
	v_fmac_f32_e32 v85, v15, v87
	v_fmac_f32_e32 v81, v16, v82
	v_add_f32_e32 v93, v93, v85
	ds_read_b128 v[84:87], v72 offset:624
	v_fmac_f32_e32 v81, v17, v83
	v_add_f32_e32 v80, v94, v81
	s_waitcnt lgkmcnt(1)
	v_mul_f32_e32 v81, v9, v89
	v_fmac_f32_e32 v81, v8, v88
	v_fmac_f32_e32 v81, v6, v90
	v_fmac_f32_e32 v81, v7, v91
	v_add_f32_e32 v81, v93, v81
	s_waitcnt lgkmcnt(0)
	v_mul_f32_e32 v82, v5, v85
	v_fmac_f32_e32 v82, v4, v84
	v_mul_f32_e64 v83, |v81|, s58
	v_fmac_f32_e32 v82, v2, v86
	v_exp_f32_e32 v83, v83
	v_fmac_f32_e32 v82, v3, v87
	v_add_f32_e32 v84, v80, v82
	v_mul_f32_e64 v80, |v84|, s58
	v_exp_f32_e32 v80, v80
	v_add_f32_e32 v82, 1.0, v83
	v_log_f32_e32 v82, v82
	v_min_f32_e32 v81, 0, v81
	v_add_f32_e32 v80, 1.0, v80
	v_log_f32_e32 v85, v80
	v_fma_f32 v93, v81, s82, -v82
	ds_read_b128 v[80:83], v72 offset:640
	v_min_f32_e32 v84, 0, v84
	v_fma_f32 v94, v84, s82, -v85
	ds_read_b128 v[84:87], v72 offset:704
	ds_read_b128 v[88:91], v72 offset:656
	s_add_i32 s7, s7, 0
	s_waitcnt lgkmcnt(0)
	v_mul_f32_e32 v81, v29, v81
	v_fmac_f32_e32 v81, v28, v80
	v_fmac_f32_e32 v81, v30, v82
	v_fmac_f32_e32 v81, v31, v83
	v_add_f32_e32 v95, v61, v81
	ds_read_b128 v[80:83], v72 offset:720
	s_waitcnt lgkmcnt(2)
	v_mul_f32_e32 v85, v35, v85
	v_fmac_f32_e32 v85, v34, v84
	s_waitcnt lgkmcnt(1)
	v_mul_f32_e32 v84, v27, v89
	v_fmac_f32_e32 v84, v26, v88
	v_fmac_f32_e32 v85, v32, v86
	v_fmac_f32_e32 v84, v24, v90
	v_fmac_f32_e32 v85, v33, v87
	v_fmac_f32_e32 v84, v25, v91
	v_add_f32_e32 v96, v60, v85
	v_add_f32_e32 v95, v95, v84
	ds_read_b128 v[84:87], v72 offset:672
	s_waitcnt lgkmcnt(0)
	v_mul_f32_e32 v81, v23, v81
	v_fmac_f32_e32 v81, v22, v80
	v_fmac_f32_e32 v81, v20, v82
	v_fmac_f32_e32 v81, v21, v83
	v_add_f32_e32 v96, v96, v81
	ds_read_b128 v[80:83], v72 offset:736
	ds_read_b128 v[88:91], v72 offset:688
	s_waitcnt lgkmcnt(2)
	v_mul_f32_e32 v85, v13, v85
	v_fmac_f32_e32 v85, v12, v84
	v_fmac_f32_e32 v85, v14, v86
	s_waitcnt lgkmcnt(0)
	v_mul_f32_e32 v81, v19, v81
	v_fmac_f32_e32 v81, v18, v80
	v_fmac_f32_e32 v85, v15, v87
	v_fmac_f32_e32 v81, v16, v82
	v_add_f32_e32 v95, v95, v85
	ds_read_b128 v[84:87], v72 offset:752
	v_fmac_f32_e32 v81, v17, v83
	v_add_f32_e32 v80, v96, v81
	s_waitcnt lgkmcnt(1)
	v_mul_f32_e32 v81, v9, v89
	v_fmac_f32_e32 v81, v8, v88
	v_fmac_f32_e32 v81, v6, v90
	v_fmac_f32_e32 v81, v7, v91
	v_add_f32_e32 v81, v95, v81
	s_waitcnt lgkmcnt(0)
	v_mul_f32_e32 v82, v5, v85
	v_fmac_f32_e32 v82, v4, v84
	v_mul_f32_e64 v83, |v81|, s58
	v_fmac_f32_e32 v82, v2, v86
	v_exp_f32_e32 v83, v83
	v_fmac_f32_e32 v82, v3, v87
	v_add_f32_e32 v84, v80, v82
	v_mul_f32_e64 v80, |v84|, s58
	v_exp_f32_e32 v80, v80
	v_add_f32_e32 v82, 1.0, v83
	v_log_f32_e32 v82, v82
	v_min_f32_e32 v81, 0, v81
	v_add_f32_e32 v80, 1.0, v80
	v_log_f32_e32 v85, v80
	v_fma_f32 v95, v81, s82, -v82
	ds_read_b128 v[80:83], v72 offset:768
	v_min_f32_e32 v84, 0, v84
	v_fma_f32 v96, v84, s82, -v85
	ds_read_b128 v[84:87], v72 offset:832
	ds_read_b128 v[88:91], v72 offset:784
	s_ashr_i32 s10, s11, 6
	s_waitcnt lgkmcnt(0)
	v_mul_f32_e32 v81, v29, v81
	v_fmac_f32_e32 v81, v28, v80
	v_fmac_f32_e32 v81, v30, v82
	v_fmac_f32_e32 v81, v31, v83
	v_add_f32_e32 v97, v61, v81
	ds_read_b128 v[80:83], v72 offset:848
	s_waitcnt lgkmcnt(2)
	v_mul_f32_e32 v85, v35, v85
	v_fmac_f32_e32 v85, v34, v84
	s_waitcnt lgkmcnt(1)
	v_mul_f32_e32 v84, v27, v89
	v_fmac_f32_e32 v84, v26, v88
	v_fmac_f32_e32 v85, v32, v86
	v_fmac_f32_e32 v84, v24, v90
	v_fmac_f32_e32 v85, v33, v87
	v_fmac_f32_e32 v84, v25, v91
	v_add_f32_e32 v98, v60, v85
	v_add_f32_e32 v97, v97, v84
	ds_read_b128 v[84:87], v72 offset:800
	s_waitcnt lgkmcnt(0)
	v_mul_f32_e32 v81, v23, v81
	v_fmac_f32_e32 v81, v22, v80
	v_fmac_f32_e32 v81, v20, v82
	v_fmac_f32_e32 v81, v21, v83
	v_add_f32_e32 v98, v98, v81
	ds_read_b128 v[80:83], v72 offset:864
	ds_read_b128 v[88:91], v72 offset:816
	s_waitcnt lgkmcnt(2)
	v_mul_f32_e32 v85, v13, v85
	v_fmac_f32_e32 v85, v12, v84
	v_fmac_f32_e32 v85, v14, v86
	s_waitcnt lgkmcnt(0)
	v_mul_f32_e32 v81, v19, v81
	v_fmac_f32_e32 v81, v18, v80
	v_fmac_f32_e32 v81, v16, v82
	v_fmac_f32_e32 v81, v17, v83
	v_fmac_f32_e32 v85, v15, v87
	v_add_f32_e32 v80, v98, v81
	s_waitcnt lgkmcnt(0)
	v_mul_f32_e32 v81, v9, v89
	v_add_f32_e32 v97, v97, v85
	ds_read_b128 v[84:87], v72 offset:880
	v_fmac_f32_e32 v81, v8, v88
	v_fmac_f32_e32 v81, v6, v90
	v_fmac_f32_e32 v81, v7, v91
	v_add_f32_e32 v81, v97, v81
	v_mul_f32_e64 v83, |v81|, s58
	s_waitcnt lgkmcnt(0)
	v_mul_f32_e32 v82, v5, v85
	v_exp_f32_e32 v83, v83
	v_fmac_f32_e32 v82, v4, v84
	v_fmac_f32_e32 v82, v2, v86
	v_fmac_f32_e32 v82, v3, v87
	v_add_f32_e32 v80, v80, v82
	v_add_f32_e32 v82, 1.0, v83
	v_log_f32_e32 v82, v82
	v_min_f32_e32 v81, 0, v81
	v_mul_f32_e64 v83, |v80|, s58
	v_exp_f32_e32 v84, v83
	v_fma_f32 v97, v81, s82, -v82
	v_min_f32_e32 v98, 0, v80
	ds_read_b128 v[80:83], v72 offset:896
	v_add_f32_e32 v84, 1.0, v84
	v_log_f32_e32 v99, v84
	ds_read_b128 v[84:87], v72 offset:960
	ds_read_b128 v[88:91], v72 offset:912
	s_cmp_gt_i32 s6, 0
	s_waitcnt lgkmcnt(0)
	v_mul_f32_e32 v29, v29, v81
	v_fmac_f32_e32 v29, v28, v80
	v_fmac_f32_e32 v29, v30, v82
	v_fmac_f32_e32 v29, v31, v83
	v_add_f32_e32 v61, v61, v29
	ds_read_b128 v[28:31], v72 offset:976
	s_waitcnt lgkmcnt(1)
	v_mul_f32_e32 v27, v27, v89
	v_fmac_f32_e32 v27, v26, v88
	v_fmac_f32_e32 v27, v24, v90
	v_fmac_f32_e32 v27, v25, v91
	s_waitcnt lgkmcnt(0)
	v_mul_f32_e32 v26, v23, v29
	v_fmac_f32_e32 v26, v22, v28
	ds_read_b128 v[22:25], v72 offset:928
	v_mul_f32_e32 v35, v35, v85
	v_fmac_f32_e32 v35, v34, v84
	v_fmac_f32_e32 v35, v32, v86
	v_fmac_f32_e32 v35, v33, v87
	s_waitcnt lgkmcnt(0)
	v_mul_f32_e32 v13, v13, v23
	v_fmac_f32_e32 v13, v12, v22
	v_fmac_f32_e32 v26, v20, v30
	v_fmac_f32_e32 v13, v14, v24
	v_add_f32_e32 v32, v60, v35
	v_add_f32_e32 v34, v61, v27
	v_fmac_f32_e32 v26, v21, v31
	v_fmac_f32_e32 v13, v15, v25
	v_add_f32_e32 v20, v32, v26
	ds_read_b128 v[26:29], v72 offset:992
	ds_read_b128 v[30:33], v72 offset:944
	v_add_f32_e32 v21, v34, v13
	ds_read_b128 v[12:15], v72 offset:1008
	s_cselect_b64 vcc, -1, 0
	s_waitcnt lgkmcnt(0)
	v_mul_f32_e32 v19, v19, v27
	v_fmac_f32_e32 v19, v18, v26
	v_fmac_f32_e32 v19, v16, v28
	s_waitcnt lgkmcnt(0)
	v_mul_f32_e32 v5, v5, v13
	v_fmac_f32_e32 v5, v4, v12
	v_fmac_f32_e32 v19, v17, v29
	v_fmac_f32_e32 v5, v2, v14
	v_add_f32_e32 v16, v20, v19
	v_fmac_f32_e32 v5, v3, v15
	v_add_f32_e32 v2, v16, v5
	v_mul_f32_e64 v4, |v2|, s58
	v_exp_f32_e32 v4, v4
	v_mul_f32_e32 v9, v9, v31
	v_fmac_f32_e32 v9, v8, v30
	v_fmac_f32_e32 v9, v6, v32
	v_fmac_f32_e32 v9, v7, v33
	v_add_f32_e32 v4, 1.0, v4
	v_add_f32_e32 v6, v21, v9
	v_log_f32_e32 v4, v4
	v_mul_f32_e64 v3, |v6|, s58
	v_exp_f32_e32 v3, v3
	v_min_f32_e32 v2, 0, v2
	v_fma_f32 v2, v2, s82, -v4
	v_fma_f32 v5, v98, s82, -v99
	v_fma_f32 v20, v74, s22, 0
	v_fma_f32 v28, v2, s22, 0
	v_add_f32_e32 v3, 1.0, v3
	v_fmamk_f32 v21, v76, 0x3d800000, v20
	v_fmamk_f32 v29, v5, 0x3d800000, v28
	v_log_f32_e32 v3, v3
	v_fmamk_f32 v22, v78, 0x3d800000, v21
	v_fmamk_f32 v30, v96, 0x3d800000, v29
	v_fmamk_f32 v23, v79, 0x3d800000, v22
	v_fmamk_f32 v31, v94, 0x3d800000, v30
	v_fmamk_f32 v24, v93, 0x3d800000, v23
	v_fmamk_f32 v32, v92, 0x3d800000, v31
	v_min_f32_e32 v6, 0, v6
	v_fmamk_f32 v25, v95, 0x3d800000, v24
	v_fmamk_f32 v33, v77, 0x3d800000, v32
	v_fma_f32 v3, v6, s82, -v3
	v_fmamk_f32 v26, v97, 0x3d800000, v25
	v_fmamk_f32 v34, v75, 0x3d800000, v33
	v_fmamk_f32 v27, v3, 0x3d800000, v26
	v_fmamk_f32 v35, v73, 0x3d800000, v34
	v_add_u32_e32 v2, s7, v71
	ds_write2st64_b32 v2, v27, v35 offset0:64 offset1:72
	s_waitcnt lgkmcnt(0)
	s_barrier
	ds_read2st64_b32 v[2:3], v70 offset0:64 offset1:65
	ds_read2st64_b32 v[4:5], v70 offset0:72 offset1:73
	ds_read2st64_b32 v[6:7], v70 offset0:66 offset1:67
	ds_read2st64_b32 v[8:9], v70 offset0:68 offset1:69
	ds_read2st64_b32 v[12:13], v70 offset0:70 offset1:71
	s_waitcnt lgkmcnt(0)
	v_add_f32_e32 v2, 0, v2
	s_cmp_lt_i32 s6, 0
	v_cndmask_b32_e32 v60, 0, v2, vcc
	s_waitcnt lgkmcnt(3)
	v_add_f32_e32 v4, 0, v4
	s_cselect_b64 vcc, -1, 0
	s_cmp_gt_i32 s6, 1
	ds_read2st64_b32 v[14:15], v70 offset0:74 offset1:75
	ds_read2st64_b32 v[16:17], v70 offset0:76 offset1:77
	ds_read2st64_b32 v[18:19], v70 offset0:78 offset1:79
	v_cndmask_b32_e32 v61, 0, v4, vcc
	v_add_f32_e32 v2, v2, v3
	v_add_f32_e32 v3, v60, v3
	s_cselect_b64 vcc, -1, 0
	s_cmp_lt_i32 s6, 1
	v_cndmask_b32_e32 v3, v60, v3, vcc
	v_add_f32_e32 v60, v61, v5
	s_cselect_b64 vcc, -1, 0
	s_cmp_gt_i32 s6, 2
	v_cndmask_b32_e32 v60, 0, v60, vcc
	s_waitcnt lgkmcnt(5)
	v_add_f32_e32 v2, v2, v6
	v_add_f32_e32 v6, v3, v6
	s_cselect_b64 vcc, -1, 0
	s_cmp_lt_i32 s6, 2
	v_cndmask_b32_e32 v3, v3, v6, vcc
	s_waitcnt lgkmcnt(0)
	v_add_f32_e32 v6, v60, v14
	s_cselect_b64 vcc, -1, 0
	s_cmp_gt_i32 s6, 3
	v_cndmask_b32_e32 v6, 0, v6, vcc
	v_add_f32_e32 v2, v2, v7
	v_add_f32_e32 v7, v3, v7
	s_cselect_b64 vcc, -1, 0
	s_cmp_lt_i32 s6, 3
	v_cndmask_b32_e32 v3, v3, v7, vcc
	v_add_f32_e32 v6, v6, v15
	s_cselect_b64 vcc, -1, 0
	s_cmp_gt_i32 s6, 4
	v_cndmask_b32_e32 v6, 0, v6, vcc
	v_add_f32_e32 v7, v3, v8
	s_cselect_b64 vcc, -1, 0
	s_cmp_lt_i32 s6, 4
	v_cndmask_b32_e32 v3, v3, v7, vcc
	s_waitcnt lgkmcnt(1)
	v_add_f32_e32 v6, v6, v16
	s_cselect_b64 vcc, -1, 0
	s_cmp_gt_i32 s6, 5
	v_cndmask_b32_e32 v6, 0, v6, vcc
	v_add_f32_e32 v7, v3, v9
	s_cselect_b64 vcc, -1, 0
	s_cmp_lt_i32 s6, 5
	v_cndmask_b32_e32 v3, v3, v7, vcc
	v_add_f32_e32 v6, v6, v17
	s_cselect_b64 vcc, -1, 0
	s_cmp_gt_i32 s6, 6
	v_cndmask_b32_e32 v6, 0, v6, vcc
	v_add_f32_e32 v7, v3, v12
	s_cselect_b64 vcc, -1, 0
	s_cmp_lt_i32 s6, 6
	v_add_f32_e32 v2, v2, v8
	v_cndmask_b32_e32 v3, v3, v7, vcc
	s_waitcnt lgkmcnt(0)
	v_add_f32_e32 v6, v6, v18
	s_cselect_b64 vcc, -1, 0
	s_cmp_gt_i32 s6, 7
	v_add_f32_e32 v2, v2, v9
	v_cndmask_b32_e32 v6, 0, v6, vcc
	v_add_f32_e32 v7, v3, v13
	s_cselect_b64 vcc, -1, 0
	v_add_f32_e32 v2, v2, v12
	v_cndmask_b32_e32 v3, v3, v7, vcc
	v_add_f32_e32 v2, v2, v13
	v_add_f32_e32 v7, v20, v3
	v_add_f32_e32 v9, v21, v3
	v_add_f32_e32 v13, v22, v3
	v_add_f32_e32 v21, v23, v3
	v_add_f32_e32 v23, v24, v3
	v_add_f32_e32 v25, v25, v3
	v_add_f32_e32 v26, v26, v3
	v_add_f32_e32 v27, v27, v3
	v_add_f32_e32 v3, v4, v5
	v_add_f32_e32 v3, v3, v14
	v_add_f32_e32 v3, v3, v15
	s_cmp_lt_i32 s6, 7
	v_add_f32_e32 v3, v3, v16
	v_add_f32_e32 v6, v6, v19
	s_cselect_b64 vcc, -1, 0
	v_add_f32_e32 v3, v3, v17
	v_cndmask_b32_e32 v6, 0, v6, vcc
	v_add_f32_e32 v3, v3, v18
	v_add_f32_e32 v8, v35, v6
	v_add_f32_e32 v3, v3, v19
	v_sub_f32_e32 v4, v2, v7
	v_sub_f32_e32 v5, v3, v8
	v_sub_f32_e32 v7, v2, v9
	v_exp_f32_e32 v5, v5
	v_exp_f32_e32 v7, v7
	v_add_f32_e32 v12, v34, v6
	v_add_f32_e32 v22, v32, v6
	v_mul_f32_e32 v8, v5, v69
	v_mul_f32_e32 v9, v7, v68
	v_sub_f32_e32 v5, v3, v12
	v_sub_f32_e32 v7, v2, v13
	v_exp_f32_e32 v5, v5
	v_exp_f32_e32 v7, v7
	v_add_f32_e32 v20, v33, v6
	v_add_f32_e32 v30, v30, v6
	v_mul_f32_e32 v15, v5, v68
	v_mul_f32_e32 v5, v7, v67
	v_sub_f32_e32 v7, v3, v22
	v_exp_f32_e32 v7, v7
	v_add_f32_e32 v29, v29, v6
	v_sub_f32_e32 v12, v3, v20
	v_sub_f32_e32 v13, v2, v21
	v_mul_f32_e32 v18, v7, v66
	v_sub_f32_e32 v7, v3, v30
	v_sub_f32_e32 v19, v2, v26
	v_sub_f32_e32 v20, v3, v29
	v_sub_f32_e32 v21, v2, v27
	v_exp_f32_e32 v7, v7
	v_exp_f32_e32 v19, v19
	v_exp_f32_e32 v20, v20
	v_exp_f32_e32 v21, v21
	v_add_f32_e32 v24, v31, v6
	v_add_f32_e32 v6, v28, v6
	v_mul_f32_e32 v22, v7, v64
	v_mul_f32_e32 v7, v19, v63
	v_mul_f32_e32 v19, v20, v63
	v_mul_f32_e32 v20, v21, v0
	v_sub_f32_e32 v6, v3, v6
	v_exp_f32_e32 v12, v12
	v_exp_f32_e32 v13, v13
	v_cvt_pk_bf16_f32 v7, v7, v20
	v_exp_f32_e32 v20, v6
	v_mul_f32_e32 v12, v12, v67
	v_mul_f32_e32 v13, v13, v66
	v_cvt_pk_bf16_f32 v5, v5, v13
	v_mul_f32_e32 v0, v20, v0
	v_cvt_pk_bf16_f32 v13, v12, v18
	v_cvt_pk_bf16_f32 v12, v8, v15
	v_cvt_pk_bf16_f32 v15, v19, v0
	v_and_b32_e32 v0, 63, v62
	s_lshl_b32 s6, s10, 4
	v_mul_u32_u24_e32 v8, 0x48, v0
	s_add_i32 s6, s6, 0
	v_lshl_add_u32 v8, v8, 1, s6
	s_lshl_b32 s5, s5, 3
	s_and_b32 s6, s8, 6
	v_sub_f32_e32 v14, v2, v23
	v_sub_f32_e32 v16, v3, v24
	v_sub_f32_e32 v17, v2, v25
	s_or_b32 s5, s5, s6
	v_exp_f32_e32 v4, v4
	v_exp_f32_e32 v14, v14
	v_exp_f32_e32 v16, v16
	v_exp_f32_e32 v17, v17
	s_mul_hi_i32 s7, s5, 0x44
	s_mulk_i32 s5, 0x44
	s_ashr_i32 s22, s4, 31
	s_add_u32 s6, s5, s4
	s_addc_u32 s7, s7, s22
	s_add_u32 s4, s6, 0x44
	v_mul_f32_e32 v4, v4, v69
	v_mul_f32_e32 v14, v14, v65
	v_mul_f32_e32 v16, v16, v65
	v_mul_f32_e32 v17, v17, v64
	s_addc_u32 s5, s7, 0
	v_cvt_pk_bf16_f32 v6, v14, v17
	v_cvt_pk_bf16_f32 v4, v4, v9
	v_cvt_pk_bf16_f32 v14, v16, v22
	s_cmp_gt_u32 s11, 63
	ds_write_b128 v8, v[4:7] offset:22528
	ds_write_b128 v8, v[12:15] offset:31744
	s_cbranch_scc1 .LBB0_362
	v_mov_b32_e32 v4, s59
	ds_read_b64 v[4:5], v4
	v_exp_f32_e32 v2, v2
	v_lshlrev_b32_e32 v0, 2, v0
	s_waitcnt lgkmcnt(0)
	v_readfirstlane_b32 s22, v4
	v_readfirstlane_b32 s11, v5
	s_add_u32 s26, s22, 0x500000
	s_addc_u32 s11, s11, 0
	s_lshl_b64 s[22:23], s[6:7], 8
	s_add_u32 s22, s26, s22
	s_addc_u32 s23, s11, s23
	v_lshl_add_u64 v[4:5], s[22:23], 0, v[0:1]
	global_store_dword v[4:5], v2, off
	v_exp_f32_e32 v4, v3
	s_lshl_b64 s[22:23], s[4:5], 8
	s_add_u32 s22, s26, s22
	s_addc_u32 s23, s11, s23
	v_lshl_add_u64 v[2:3], s[22:23], 0, v[0:1]
	global_store_dword v[2:3], v4, off
	s_branch .LBB0_362

.LBB0_376:
	s_and_b32 s6, s8, 3
	s_ashr_i32 s7, s11, 6
	s_add_i32 s29, s28, 0xffffff00
	s_and_b64 s[4:5], s[4:5], exec
	s_cselect_b32 s4, s28, s29
	s_lshl_b32 s5, s7, 3
	s_add_i32 s28, s5, -3
	s_lshl_b32 s29, s6, 7
	v_and_b32_e32 v7, 63, v6
	s_add_u32 s36, s27, s29
	s_addc_u32 s37, s26, 0
	v_lshlrev_b32_e32 v0, 1, v7
	v_lshl_add_u64 v[4:5], s[36:37], 0, v[0:1]
	s_mov_b64 s[26:27], 0xe000c00
	v_lshl_add_u64 v[4:5], v[4:5], 0, s[26:27]
	s_add_i32 s26, s4, s28
	v_mov_b32_e32 v36, 0
	s_cmp_ge_u32 s26, s23
	v_mov_b32_e32 v37, 0
	s_cbranch_scc1 .LBB0_378
	s_add_i32 s26, s22, s28
	v_mad_i64_i32 v[8:9], s[26:27], s26, v216, v[4:5]
	global_load_ushort v37, v[8:9], off
.LBB0_378:
	s_add_i32 s26, s5, -2
	s_add_i32 s27, s4, s26
	s_cmp_ge_u32 s27, s23
	s_cbranch_scc1 .LBB0_380
	s_add_i32 s26, s22, s26
	v_mad_i64_i32 v[8:9], s[26:27], s26, v216, v[4:5]
	global_load_ushort v36, v[8:9], off
.LBB0_380:
	s_add_i32 s26, s5, -1
	s_add_i32 s27, s4, s26
	v_mov_b32_e32 v40, 0
	s_cmp_ge_u32 s27, s23
	v_mov_b32_e32 v76, 0
	s_cbranch_scc1 .LBB0_382
	s_add_i32 s26, s22, s26
	v_mad_i64_i32 v[8:9], s[26:27], s26, v216, v[4:5]
	global_load_ushort v76, v[8:9], off
.LBB0_382:
	s_add_i32 s26, s4, s5
	s_cmp_ge_u32 s26, s23
	s_cbranch_scc1 .LBB0_384
	s_add_i32 s26, s22, s5
	v_mad_i64_i32 v[8:9], s[26:27], s26, v216, v[4:5]
	global_load_ushort v40, v[8:9], off
.LBB0_384:
	s_or_b32 s26, s5, 1
	s_add_i32 s27, s4, s26
	v_mov_b32_e32 v77, 0
	s_cmp_ge_u32 s27, s23
	v_mov_b32_e32 v78, 0
	s_cbranch_scc1 .LBB0_386
	s_add_i32 s26, s22, s26
	v_mad_i64_i32 v[8:9], s[26:27], s26, v216, v[4:5]
	global_load_ushort v78, v[8:9], off
.LBB0_386:
	s_or_b32 s26, s5, 2
	s_add_i32 s27, s4, s26
	s_cmp_ge_u32 s27, s23
	s_cbranch_scc1 .LBB0_388
	s_add_i32 s26, s22, s26
	v_mad_i64_i32 v[8:9], s[26:27], s26, v216, v[4:5]
	global_load_ushort v77, v[8:9], off
.LBB0_388:
	s_or_b32 s26, s5, 3
	s_add_i32 s27, s4, s26
	v_mov_b32_e32 v79, 0
	s_cmp_ge_u32 s27, s23
	v_mov_b32_e32 v80, 0
	s_cbranch_scc1 .LBB0_390
	s_add_i32 s26, s22, s26
	v_mad_i64_i32 v[8:9], s[26:27], s26, v216, v[4:5]
	global_load_ushort v80, v[8:9], off
.LBB0_390:
	s_or_b32 s26, s5, 4
	s_add_i32 s27, s4, s26
	s_cmp_ge_u32 s27, s23
	s_cbranch_scc1 .LBB0_392
	s_add_i32 s26, s22, s26
	v_mad_i64_i32 v[8:9], s[26:27], s26, v216, v[4:5]
	global_load_ushort v79, v[8:9], off
.LBB0_392:
	s_or_b32 s26, s5, 5
	s_add_i32 s27, s4, s26
	v_mov_b32_e32 v81, 0
	s_cmp_ge_u32 s27, s23
	v_mov_b32_e32 v85, 0
	s_cbranch_scc1 .LBB0_394
	s_add_i32 s26, s22, s26
	v_mad_i64_i32 v[8:9], s[26:27], s26, v216, v[4:5]
	global_load_ushort v85, v[8:9], off
.LBB0_394:
	s_or_b32 s26, s5, 6
	s_add_i32 s27, s4, s26
	s_cmp_ge_u32 s27, s23
	s_cbranch_scc1 .LBB0_396
	s_add_i32 s26, s22, s26
	v_mad_i64_i32 v[8:9], s[26:27], s26, v216, v[4:5]
	global_load_ushort v81, v[8:9], off
.LBB0_396:
	s_or_b32 s26, s5, 7
	s_add_i32 s27, s4, s26
	v_mov_b32_e32 v86, 0
	s_cmp_ge_u32 s27, s23
	v_mov_b32_e32 v88, 0
	s_cbranch_scc1 .LBB0_398
	s_add_i32 s26, s22, s26
	v_mad_i64_i32 v[8:9], s[26:27], s26, v216, v[4:5]
	global_load_ushort v88, v[8:9], off
.LBB0_398:
	s_add_i32 s26, s5, 8
	s_add_i32 s27, s4, s26
	s_cmp_ge_u32 s27, s23
	s_cbranch_scc1 .LBB0_400
	s_add_i32 s26, s22, s26
	v_mad_i64_i32 v[8:9], s[26:27], s26, v216, v[4:5]
	global_load_ushort v86, v[8:9], off
.LBB0_400:
	s_add_i32 s26, s5, 9
	s_add_i32 s27, s4, s26
	v_mov_b32_e32 v87, 0
	s_cmp_ge_u32 s27, s23
	v_mov_b32_e32 v89, 0
	s_cbranch_scc1 .LBB0_402
	s_add_i32 s26, s22, s26
	v_mad_i64_i32 v[8:9], s[26:27], s26, v216, v[4:5]
	global_load_ushort v89, v[8:9], off
.LBB0_402:
	s_add_i32 s5, s5, 10
	s_add_i32 s4, s4, s5
	s_cmp_ge_u32 s4, s23
	s_cbranch_scc1 .LBB0_404
	s_add_i32 s4, s22, s5
	v_mad_i64_i32 v[4:5], s[4:5], s4, v216, v[4:5]
	global_load_ushort v87, v[4:5], off
.LBB0_404:
	v_readlane_b32 s4, v245, 54
	s_lshl_b32 s22, s6, 6
	v_readlane_b32 s23, v244, 28
	v_mov_b32_e32 v0, s4
	ds_read_b128 v[8:11], v0
	v_or_b32_e32 v5, s22, v7
	v_lshlrev_b32_e32 v0, 2, v5
	v_readfirstlane_b32 s26, v2
	v_and_b32_e32 v4, 15, v6
	s_waitcnt lgkmcnt(0)
	v_readfirstlane_b32 s4, v8
	v_readfirstlane_b32 s5, v9
	s_add_u32 s4, s4, s23
	s_addc_u32 s5, s5, 0
	v_lshl_add_u64 v[8:9], s[4:5], 0, v[0:1]
	v_add_co_u32_e32 v12, vcc, s91, v8
	v_readfirstlane_b32 s5, v11
	v_readfirstlane_b32 s4, v10
	v_or_b32_e32 v0, s84, v5
	v_addc_co_u32_e32 v13, vcc, 0, v9, vcc
	global_load_dword v84, v[8:9], off
	global_load_dword v83, v[8:9], off offset:1024
	global_load_dword v82, v[8:9], off offset:2048
	global_load_dword v43, v[8:9], off offset:3072
	global_load_dword v42, v[12:13], off
	global_load_dword v41, v[12:13], off offset:1024
	global_load_dword v39, v[12:13], off offset:2048
	global_load_dword v38, v[12:13], off offset:3072
	v_lshl_add_u64 v[8:9], v[0:1], 2, s[4:5]
	v_add_u32_e32 v0, s84, v5
	v_lshl_add_u64 v[10:11], v[0:1], 2, s[4:5]
	s_lshl_b32 s4, s7, 4
	s_and_b32 s23, s4, 48
	s_ashr_i32 s4, s11, 5
	s_and_b32 s4, s4, -8
	v_readlane_b32 s5, v244, 27
	s_add_i32 s4, s4, s5
	s_ashr_i32 s5, s4, 31
	s_lshl_b64 s[4:5], s[4:5], 15
	v_readfirstlane_b32 s7, v3
	s_add_u32 s4, s26, s4
	s_addc_u32 s5, s7, s5
	s_lshl_b32 s6, s6, 13
	s_add_u32 s4, s4, s6
	v_or_b32_e32 v0, s23, v4
	s_addc_u32 s5, s5, 0
	v_lshlrev_b32_e32 v0, 7, v0
	v_lshl_add_u64 v[2:3], s[4:5], 0, v[0:1]
	v_and_b32_e32 v0, 48, v6
	v_lshl_add_u64 v[2:3], v[2:3], 0, v[0:1]
	global_load_dword v73, v[8:9], off
	global_load_dword v72, v[10:11], off offset:1024
	s_mov_b64 s[4:5], 0x400000
	v_add_co_u32_e32 v8, vcc, 0x400000, v2
	v_lshl_add_u64 v[6:7], v[2:3], 0, s[4:5]
	s_nop 0
	v_addc_co_u32_e32 v9, vcc, 0, v3, vcc
	s_mov_b64 s[4:5], 0x408000
	global_load_dwordx4 v[28:31], v[8:9], off
	global_load_dwordx4 v[20:23], v[6:7], off offset:64
	v_lshl_add_u64 v[6:7], v[2:3], 0, s[4:5]
	v_add_co_u32_e32 v2, vcc, 0x408000, v2
	s_cmpk_lt_u32 s11, 0x100
	s_nop 0
	v_addc_co_u32_e32 v3, vcc, 0, v3, vcc
	global_load_dwordx4 v[32:35], v[2:3], off
	global_load_dwordx4 v[24:27], v[6:7], off offset:64
	s_mov_b64 s[6:7], -1
	s_cbranch_scc1 .LBB0_406
	v_readlane_b32 s4, v245, 55
	s_mov_b64 s[6:7], 0
	s_nop 0
	v_mov_b32_e32 v0, s4
	ds_read_b64 v[2:3], v0
	s_waitcnt lgkmcnt(0)
	v_readfirstlane_b32 s5, v3
	v_readfirstlane_b32 s4, v2

.LBB0_408:
	v_or_b32_e32 v0, s22, v4
	v_or_b32_e32 v6, s23, v0
	v_or_b32_e32 v0, s84, v6
	v_readlane_b32 s6, v245, 57
	v_lshlrev_b64 v[2:3], 2, v[0:1]
	v_add_u32_e32 v0, s84, v6
	v_mov_b32_e32 v6, s6
	ds_read_b64 v[6:7], v6
	v_lshlrev_b64 v[8:9], 2, v[0:1]
	v_lshl_add_u64 v[4:5], s[4:5], 0, v[2:3]
	v_lshl_add_u64 v[10:11], s[4:5], 0, v[8:9]
	global_load_dword v75, v[4:5], off
	global_load_dword v74, v[10:11], off offset:1024
	s_waitcnt lgkmcnt(0)
	v_readfirstlane_b32 s5, v7
	v_readfirstlane_b32 s4, v6
	s_nop 1
	v_lshl_add_u64 v[2:3], s[4:5], 0, v[2:3]
	v_lshl_add_u64 v[4:5], s[4:5], 0, v[8:9]
	global_load_dword v92, v[2:3], off
	global_load_dword v91, v[4:5], off offset:1024
	s_andn2_b64 vcc, exec, s[0:1]
	s_cbranch_vccz .LBB0_410
	s_branch .LBB0_592

.LBB0_411:
	s_mul_i32 s4, s9, 0x600
	s_mul_hi_u32 s5, s8, 0x600
	s_add_i32 s5, s5, s4
	s_mul_i32 s4, s8, 0x600
	s_add_u32 s4, s6, s4
	v_fmac_f32_e32 v24, v22, v23
	s_addc_u32 s5, s7, s5
	s_waitcnt lgkmcnt(0)
	v_add_f32_e32 v2, v24, v25
	v_mul_f32_e32 v3, v22, v26
	v_cvt_pk_bf16_f32 v20, v3, v20
	v_cvt_pk_bf16_f32 v21, v2, s0
	v_lshl_add_u64 v[2:3], s[4:5], 0, v[0:1]
	global_store_short v[2:3], v21, off
	global_store_short v[2:3], v20, off offset:512
	global_store_short_d16_hi v[2:3], v20, off offset:1024
	v_mov_b64_e32 v[30:31], v[6:7]
	v_mov_b64_e32 v[22:23], v[10:11]
	v_mov_b64_e32 v[34:35], v[14:15]
	v_mov_b64_e32 v[26:27], v[18:19]
	s_add_i32 s22, s22, s86
	s_andn2_b64 vcc, exec, s[0:1]
	s_mov_b32 s8, s23
	v_mov_b64_e32 v[28:29], v[4:5]
	v_mov_b64_e32 v[20:21], v[8:9]
	v_mov_b64_e32 v[32:33], v[12:13]
	v_mov_b64_e32 v[24:25], v[16:17]
	v_mov_b32_e32 v91, v68
	v_mov_b32_e32 v92, v71
	v_mov_b32_e32 v74, v69
	v_mov_b32_e32 v75, v70
	v_mov_b32_e32 v72, v66
	v_mov_b32_e32 v73, v67
	v_mov_b32_e32 v38, v62
	v_mov_b32_e32 v39, v63
	v_mov_b32_e32 v41, v64
	v_mov_b32_e32 v42, v65
	v_mov_b32_e32 v43, v58
	v_mov_b32_e32 v82, v59
	v_mov_b32_e32 v83, v60
	v_mov_b32_e32 v84, v61
	v_mov_b32_e32 v87, v55
	v_mov_b32_e32 v89, v57
	v_mov_b32_e32 v86, v54
	v_mov_b32_e32 v88, v56
	v_mov_b32_e32 v81, v52
	v_mov_b32_e32 v85, v53
	v_mov_b32_e32 v79, v50
	v_mov_b32_e32 v80, v51
	v_mov_b32_e32 v77, v48
	v_mov_b32_e32 v78, v49
	v_mov_b32_e32 v40, v46
	v_mov_b32_e32 v76, v47
	v_mov_b32_e32 v36, v44
	v_mov_b32_e32 v37, v45
	s_cbranch_vccz .LBB0_592

.LBB0_417:
	s_and_b32 s6, s23, 3
	s_ashr_i32 s7, s9, 6
	s_add_i32 s29, s28, 0xffffff00
	s_and_b64 s[4:5], s[4:5], exec
	s_cselect_b32 s4, s28, s29
	s_lshl_b32 s5, s7, 3
	s_add_i32 s28, s5, -3
	s_lshl_b32 s29, s6, 7
	v_and_b32_e32 v7, 63, v6
	s_add_u32 s36, s27, s29
	s_addc_u32 s37, s26, 0
	v_lshlrev_b32_e32 v0, 1, v7
	v_lshl_add_u64 v[4:5], s[36:37], 0, v[0:1]
	s_mov_b64 s[26:27], 0xe000c00
	v_lshl_add_u64 v[4:5], v[4:5], 0, s[26:27]
	s_add_i32 s26, s4, s28
	v_mov_b32_e32 v44, 0
	s_cmp_ge_u32 s26, s11
	v_mov_b32_e32 v45, 0
	s_cbranch_scc1 .LBB0_419
	s_add_i32 s26, s10, s28
	v_mad_i64_i32 v[8:9], s[26:27], s26, v216, v[4:5]
	global_load_ushort v45, v[8:9], off
.LBB0_419:
	s_add_i32 s26, s5, -2
	s_add_i32 s27, s4, s26
	s_cmp_ge_u32 s27, s11
	s_cbranch_scc1 .LBB0_421
	s_add_i32 s26, s10, s26
	v_mad_i64_i32 v[8:9], s[26:27], s26, v216, v[4:5]
	global_load_ushort v44, v[8:9], off
.LBB0_421:
	s_add_i32 s26, s5, -1
	s_add_i32 s27, s4, s26
	v_mov_b32_e32 v46, 0
	s_cmp_ge_u32 s27, s11
	v_mov_b32_e32 v47, 0
	s_cbranch_scc1 .LBB0_423
	s_add_i32 s26, s10, s26
	v_mad_i64_i32 v[8:9], s[26:27], s26, v216, v[4:5]
	global_load_ushort v47, v[8:9], off
.LBB0_423:
	s_add_i32 s26, s4, s5
	s_cmp_ge_u32 s26, s11
	s_cbranch_scc1 .LBB0_425
	s_add_i32 s26, s10, s5
	v_mad_i64_i32 v[8:9], s[26:27], s26, v216, v[4:5]
	global_load_ushort v46, v[8:9], off
.LBB0_425:
	s_or_b32 s26, s5, 1
	s_add_i32 s27, s4, s26
	v_mov_b32_e32 v48, 0
	s_cmp_ge_u32 s27, s11
	v_mov_b32_e32 v49, 0
	s_cbranch_scc1 .LBB0_427
	s_add_i32 s26, s10, s26
	v_mad_i64_i32 v[8:9], s[26:27], s26, v216, v[4:5]
	global_load_ushort v49, v[8:9], off
.LBB0_427:
	s_or_b32 s26, s5, 2
	s_add_i32 s27, s4, s26
	s_cmp_ge_u32 s27, s11
	s_cbranch_scc1 .LBB0_429
	s_add_i32 s26, s10, s26
	v_mad_i64_i32 v[8:9], s[26:27], s26, v216, v[4:5]
	global_load_ushort v48, v[8:9], off
.LBB0_429:
	s_or_b32 s26, s5, 3
	s_add_i32 s27, s4, s26
	v_mov_b32_e32 v50, 0
	s_cmp_ge_u32 s27, s11
	v_mov_b32_e32 v51, 0
	s_cbranch_scc1 .LBB0_431
	s_add_i32 s26, s10, s26
	v_mad_i64_i32 v[8:9], s[26:27], s26, v216, v[4:5]
	global_load_ushort v51, v[8:9], off
.LBB0_431:
	s_or_b32 s26, s5, 4
	s_add_i32 s27, s4, s26
	s_cmp_ge_u32 s27, s11
	s_cbranch_scc1 .LBB0_433
	s_add_i32 s26, s10, s26
	v_mad_i64_i32 v[8:9], s[26:27], s26, v216, v[4:5]
	global_load_ushort v50, v[8:9], off
.LBB0_433:
	s_or_b32 s26, s5, 5
	s_add_i32 s27, s4, s26
	v_mov_b32_e32 v52, 0
	s_cmp_ge_u32 s27, s11
	v_mov_b32_e32 v53, 0
	s_cbranch_scc1 .LBB0_435
	s_add_i32 s26, s10, s26
	v_mad_i64_i32 v[8:9], s[26:27], s26, v216, v[4:5]
	global_load_ushort v53, v[8:9], off
.LBB0_435:
	s_or_b32 s26, s5, 6
	s_add_i32 s27, s4, s26
	s_cmp_ge_u32 s27, s11
	s_cbranch_scc1 .LBB0_437
	s_add_i32 s26, s10, s26
	v_mad_i64_i32 v[8:9], s[26:27], s26, v216, v[4:5]
	global_load_ushort v52, v[8:9], off
.LBB0_437:
	s_or_b32 s26, s5, 7
	s_add_i32 s27, s4, s26
	v_mov_b32_e32 v54, 0
	s_cmp_ge_u32 s27, s11
	v_mov_b32_e32 v56, 0
	s_cbranch_scc1 .LBB0_439
	s_add_i32 s26, s10, s26
	v_mad_i64_i32 v[8:9], s[26:27], s26, v216, v[4:5]
	global_load_ushort v56, v[8:9], off
.LBB0_439:
	s_add_i32 s26, s5, 8
	s_add_i32 s27, s4, s26
	s_cmp_ge_u32 s27, s11
	s_cbranch_scc1 .LBB0_441
	s_add_i32 s26, s10, s26
	v_mad_i64_i32 v[8:9], s[26:27], s26, v216, v[4:5]
	global_load_ushort v54, v[8:9], off
.LBB0_441:
	s_add_i32 s26, s5, 9
	s_add_i32 s27, s4, s26
	v_mov_b32_e32 v55, 0
	s_cmp_ge_u32 s27, s11
	v_mov_b32_e32 v57, 0
	s_cbranch_scc1 .LBB0_443
	s_add_i32 s26, s10, s26
	v_mad_i64_i32 v[8:9], s[26:27], s26, v216, v[4:5]
	global_load_ushort v57, v[8:9], off
.LBB0_443:
	s_add_i32 s5, s5, 10
	s_add_i32 s4, s4, s5
	s_cmp_ge_u32 s4, s11
	s_cbranch_scc1 .LBB0_445
	s_add_i32 s4, s10, s5
	v_mad_i64_i32 v[4:5], s[4:5], s4, v216, v[4:5]
	global_load_ushort v55, v[4:5], off
.LBB0_445:
	v_readlane_b32 s4, v245, 54
	s_lshl_b32 s10, s6, 6
	v_readlane_b32 s11, v244, 28
	v_mov_b32_e32 v0, s4
	ds_read_b128 v[8:11], v0
	v_or_b32_e32 v7, s10, v7
	v_lshlrev_b32_e32 v0, 2, v7
	v_readfirstlane_b32 s26, v2
	v_and_b32_e32 v68, 15, v6
	s_waitcnt lgkmcnt(0)
	v_readfirstlane_b32 s4, v8
	v_readfirstlane_b32 s5, v9
	s_add_u32 s4, s4, s11
	s_addc_u32 s5, s5, 0
	v_lshl_add_u64 v[4:5], s[4:5], 0, v[0:1]
	v_add_co_u32_e32 v8, vcc, s91, v4
	v_readfirstlane_b32 s5, v11
	v_readfirstlane_b32 s4, v10
	v_or_b32_e32 v0, s84, v7
	v_addc_co_u32_e32 v9, vcc, 0, v5, vcc
	global_load_dword v61, v[4:5], off
	global_load_dword v60, v[4:5], off offset:1024
	global_load_dword v59, v[4:5], off offset:2048
	global_load_dword v58, v[4:5], off offset:3072
	global_load_dword v65, v[8:9], off
	global_load_dword v64, v[8:9], off offset:1024
	global_load_dword v63, v[8:9], off offset:2048
	global_load_dword v62, v[8:9], off offset:3072
	v_lshl_add_u64 v[4:5], v[0:1], 2, s[4:5]
	v_add_u32_e32 v0, s84, v7
	v_lshl_add_u64 v[8:9], v[0:1], 2, s[4:5]
	s_lshl_b32 s4, s7, 4
	s_and_b32 s11, s4, 48
	s_ashr_i32 s4, s9, 5
	s_and_b32 s4, s4, -8
	v_readlane_b32 s5, v244, 27
	s_add_i32 s4, s4, s5
	s_ashr_i32 s5, s4, 31
	s_lshl_b64 s[4:5], s[4:5], 15
	v_readfirstlane_b32 s7, v3
	s_add_u32 s4, s26, s4
	s_addc_u32 s5, s7, s5
	s_lshl_b32 s6, s6, 13
	s_add_u32 s4, s4, s6
	v_or_b32_e32 v0, s11, v68
	s_addc_u32 s5, s5, 0
	v_lshlrev_b32_e32 v0, 7, v0
	v_lshl_add_u64 v[2:3], s[4:5], 0, v[0:1]
	v_and_b32_e32 v0, 48, v6
	v_lshl_add_u64 v[2:3], v[2:3], 0, v[0:1]
	global_load_dword v67, v[4:5], off
	global_load_dword v66, v[8:9], off offset:1024
	s_mov_b64 s[4:5], 0x400000
	v_add_co_u32_e32 v4, vcc, 0x400000, v2
	v_lshl_add_u64 v[8:9], v[2:3], 0, s[4:5]
	s_nop 0
	v_addc_co_u32_e32 v5, vcc, 0, v3, vcc
	s_mov_b64 s[4:5], 0x408000
	v_lshl_add_u64 v[16:17], v[2:3], 0, s[4:5]
	v_add_co_u32_e32 v2, vcc, 0x408000, v2
	global_load_dwordx4 v[4:7], v[4:5], off
	s_nop 0
	global_load_dwordx4 v[8:11], v[8:9], off offset:64
	v_addc_co_u32_e32 v3, vcc, 0, v3, vcc
	global_load_dwordx4 v[12:15], v[2:3], off
	s_nop 0
	global_load_dwordx4 v[16:19], v[16:17], off offset:64
	s_cmpk_lt_u32 s9, 0x100
	s_mov_b64 s[6:7], -1
	s_cbranch_scc1 .LBB0_447
	v_readlane_b32 s4, v245, 55
	s_mov_b64 s[6:7], 0
	s_nop 0
	v_mov_b32_e32 v0, s4
	ds_read_b64 v[2:3], v0
	s_waitcnt lgkmcnt(0)
	v_readfirstlane_b32 s5, v3
	v_readfirstlane_b32 s4, v2

.LBB0_449:
	v_or_b32_e32 v0, s10, v68
	v_or_b32_e32 v70, s11, v0
	v_or_b32_e32 v0, s84, v70
	v_readlane_b32 s6, v245, 57
	v_lshlrev_b64 v[2:3], 2, v[0:1]
	v_add_u32_e32 v0, s84, v70
	v_mov_b32_e32 v70, s6
	ds_read_b64 v[94:95], v70
	v_lshlrev_b64 v[96:97], 2, v[0:1]
	v_lshl_add_u64 v[68:69], s[4:5], 0, v[2:3]
	v_lshl_add_u64 v[98:99], s[4:5], 0, v[96:97]
	global_load_dword v70, v[68:69], off
	s_nop 0
	global_load_dword v69, v[98:99], off offset:1024
	s_waitcnt lgkmcnt(0)
	v_readfirstlane_b32 s5, v95
	v_readfirstlane_b32 s4, v94
	s_nop 1
	v_lshl_add_u64 v[2:3], s[4:5], 0, v[2:3]
	v_lshl_add_u64 v[94:95], s[4:5], 0, v[96:97]
	global_load_dword v71, v[2:3], off
	global_load_dword v68, v[94:95], off offset:1024

.LBB0_454:
	v_lshlrev_b32_e32 v0, 16, v37
	v_lshlrev_b32_e32 v3, 16, v36
	v_lshlrev_b32_e32 v80, 16, v80
	v_lshlrev_b32_e32 v95, 16, v85
	v_fma_f32 v85, v84, v0, v73
	s_ashr_i32 s10, s27, 6
	v_lshlrev_b32_e32 v36, 16, v76
	v_lshlrev_b32_e32 v90, 16, v77
	v_fmac_f32_e32 v85, v83, v3
	v_fma_f32 v0, v42, v80, v72
	v_and_b32_e32 v2, 63, v93
	v_lshlrev_b32_e32 v37, 16, v40
	v_lshlrev_b32_e32 v40, 16, v78
	v_fmac_f32_e32 v85, v82, v36
	v_fmac_f32_e32 v0, v41, v90
	s_mul_i32 s4, s10, 0x240
	v_lshlrev_b32_e32 v94, 16, v79
	v_lshlrev_b32_e32 v98, 16, v86
	s_lshl_b32 s9, s10, 3
	v_fmac_f32_e32 v85, v43, v37
	v_fmac_f32_e32 v0, v39, v40
	v_or_b32_e32 v77, s4, v2
	v_fma_f32 v86, v84, v3, v73
	v_fmac_f32_e32 v0, v38, v37
	v_cvt_pk_bf16_f32 v76, v85, s0
	v_lshl_add_u32 v77, v77, 1, 0
	s_or_b32 s28, s9, 1
	v_fmac_f32_e32 v86, v83, v36
	v_fma_f32 v3, v42, v94, v72
	ds_write_b16 v77, v76 offset:17920
	v_cvt_pk_bf16_f32 v76, v0, s0
	v_fmac_f32_e32 v86, v82, v37
	v_fmac_f32_e32 v3, v41, v80
	s_mul_i32 s4, s28, 0x48
	ds_write_b16 v77, v76 offset:27136
	v_fmac_f32_e32 v86, v43, v40
	v_fmac_f32_e32 v3, v39, v90
	v_add_u32_e32 v77, s4, v2
	v_fmac_f32_e32 v3, v38, v40
	v_cvt_pk_bf16_f32 v76, v86, s0
	v_lshl_add_u32 v101, v77, 1, 0
	v_lshlrev_b32_e32 v100, 16, v87
	ds_write_b16 v101, v76 offset:17920
	v_cvt_pk_bf16_f32 v76, v3, s0
	v_fma_f32 v87, v84, v36, v73
	ds_write_b16 v101, v76 offset:27136
	v_fmac_f32_e32 v87, v83, v37
	v_fma_f32 v76, v42, v95, v72
	v_lshlrev_b32_e32 v96, 16, v81
	v_lshlrev_b32_e32 v97, 16, v88
	v_fmac_f32_e32 v87, v82, v40
	v_fmac_f32_e32 v76, v41, v94
	v_fma_f32 v88, v84, v37, v73
	v_fmac_f32_e32 v87, v43, v90
	v_fmac_f32_e32 v76, v39, v80
	v_fmac_f32_e32 v88, v83, v40
	v_fma_f32 v77, v42, v96, v72
	v_lshlrev_b32_e32 v99, 16, v89
	v_fmac_f32_e32 v76, v38, v90
	v_cvt_pk_bf16_f32 v36, v87, s0
	v_fmac_f32_e32 v88, v82, v90
	v_fmac_f32_e32 v77, v41, v95
	v_fma_f32 v89, v84, v40, v73
	ds_write_b16 v101, v36 offset:18064
	v_cvt_pk_bf16_f32 v36, v76, s0
	v_fmac_f32_e32 v88, v43, v80
	v_fmac_f32_e32 v77, v39, v94
	v_fmac_f32_e32 v89, v83, v90
	v_fma_f32 v78, v42, v97, v72
	ds_write_b16 v101, v36 offset:27280
	v_fmac_f32_e32 v77, v38, v80
	v_cvt_pk_bf16_f32 v36, v88, s0
	v_fmac_f32_e32 v89, v82, v80
	v_fmac_f32_e32 v78, v41, v96
	v_fma_f32 v90, v84, v90, v73
	ds_write_b16 v101, v36 offset:18208
	v_cvt_pk_bf16_f32 v36, v77, s0
	v_fmac_f32_e32 v89, v43, v94
	v_fmac_f32_e32 v78, v39, v95
	v_fmac_f32_e32 v90, v83, v80
	v_fma_f32 v79, v42, v98, v72
	ds_write_b16 v101, v36 offset:27424
	v_fmac_f32_e32 v78, v38, v94
	v_cvt_pk_bf16_f32 v36, v89, s0
	v_fmac_f32_e32 v90, v82, v94
	v_fmac_f32_e32 v79, v41, v97
	v_fma_f32 v81, v84, v80, v73
	ds_write_b16 v101, v36 offset:18352
	v_cvt_pk_bf16_f32 v36, v78, s0
	v_fmac_f32_e32 v90, v43, v95
	v_fmac_f32_e32 v79, v39, v96
	v_fmac_f32_e32 v81, v83, v94
	v_fma_f32 v80, v42, v99, v72
	ds_write_b16 v101, v36 offset:27568
	v_fmac_f32_e32 v79, v38, v95
	v_cvt_pk_bf16_f32 v36, v90, s0
	v_fmac_f32_e32 v81, v82, v95
	v_fmac_f32_e32 v80, v41, v98
	v_fmac_f32_e32 v73, v84, v94
	ds_write_b16 v101, v36 offset:18496
	v_cvt_pk_bf16_f32 v36, v79, s0
	v_fmac_f32_e32 v81, v43, v96
	v_fmac_f32_e32 v80, v39, v97
	v_fmac_f32_e32 v73, v83, v95
	v_fmac_f32_e32 v72, v42, v100
	ds_write_b16 v101, v36 offset:27712
	v_fmac_f32_e32 v80, v38, v96
	v_cvt_pk_bf16_f32 v36, v81, s0
	v_fmac_f32_e32 v73, v82, v96
	v_fmac_f32_e32 v72, v41, v99
	ds_write_b16 v101, v36 offset:18640
	v_cvt_pk_bf16_f32 v36, v80, s0
	v_fmac_f32_e32 v73, v43, v97
	v_fmac_f32_e32 v72, v39, v98
	ds_write_b16 v101, v36 offset:27856
	v_fmac_f32_e32 v72, v38, v97
	v_cvt_pk_bf16_f32 v36, v73, s0
	ds_write_b16 v101, v36 offset:18784
	v_cvt_pk_bf16_f32 v36, v72, s0
	ds_write_b16 v101, v36 offset:28000
	s_waitcnt lgkmcnt(0)
	v_mul_f32_e32 v36, 0xbfb8aa3b, v92
	v_exp_f32_e32 v36, v36
	s_mov_b32 s4, 0x3cf5c28f
	s_barrier
	v_cmp_ngt_f32_e32 vcc, s4, v36
	s_and_saveexec_b64 s[4:5], vcc
	s_xor_b64 s[4:5], exec, s[4:5]
	v_add_f32_e32 v36, 1.0, v36
	v_log_f32_e32 v36, v36
	s_nop 0
	v_mul_f32_e32 v83, 0x3f317218, v36
	s_andn2_saveexec_b64 s[4:5], s[4:5]
	v_fmamk_f32 v37, v36, 0xbe800000, v212
	v_fma_f32 v37, -v36, v37, 0.5
	v_fma_f32 v37, -v36, v37, 1.0
	v_mul_f32_e32 v83, v36, v37
	s_or_b64 exec, exec, s[4:5]
	v_mul_f32_e32 v36, 0xbfb8aa3b, v91
	v_exp_f32_e32 v36, v36
	s_mov_b32 s4, 0x3cf5c28f
	v_cmp_ngt_f32_e32 vcc, s4, v36
	s_and_saveexec_b64 s[4:5], vcc
	s_xor_b64 s[4:5], exec, s[4:5]
	v_add_f32_e32 v36, 1.0, v36
	v_log_f32_e32 v36, v36
	s_nop 0
	v_mul_f32_e32 v91, 0x3f317218, v36
	s_andn2_saveexec_b64 s[4:5], s[4:5]
	v_fmamk_f32 v37, v36, 0xbe800000, v212
	v_fma_f32 v37, -v36, v37, 0.5
	v_fma_f32 v37, -v36, v37, 1.0
	v_mul_f32_e32 v91, v36, v37
	s_or_b64 exec, exec, s[4:5]
	v_and_b32_e32 v92, 15, v93
	v_mul_u32_u24_e32 v37, 0x48, v92
	v_and_b32_e32 v36, 48, v2
	v_lshlrev_b32_e32 v37, 1, v37
	v_add3_u32 v93, 0, v36, v37
	ds_read_b128 v[36:39], v93 offset:17920
	ds_read_b128 v[40:43], v93 offset:17984
	ds_read_b128 v[94:97], v93 offset:27136
	ds_read_b128 v[98:101], v93 offset:27200
	s_cmpk_gt_u32 s27, 0xff
	s_waitcnt lgkmcnt(3)
	v_mfma_f32_16x16x32_bf16 v[36:39], v[36:39], v[28:31], 0
	s_cselect_b64 s[4:5], -1, 0
	s_lshl_b32 s29, s10, 4
	v_and_or_b32 v82, s29, 48, v92
	s_waitcnt lgkmcnt(1)
	v_mfma_f32_16x16x32_bf16 v[102:105], v[94:97], v[32:35], 0
	v_lshrrev_b32_e32 v94, 4, v2
	s_mov_b64 s[6:7], -1
	s_and_b64 vcc, exec, s[4:5]
	v_mfma_f32_16x16x32_bf16 v[40:43], v[40:43], v[20:23], v[36:39]
	s_waitcnt lgkmcnt(0)
	v_mfma_f32_16x16x32_bf16 v[36:39], v[98:101], v[24:27], v[102:105]
	s_nop 5
	v_add_f32_e32 v40, v75, v40
	s_nop 0
	v_add_f32_e32 v36, v74, v36
	v_mul_f32_e32 v40, 0xbfb8aa3b, v40
	v_mul_f32_e32 v36, 0xbfb8aa3b, v36
	v_exp_f32_e32 v40, v40
	v_exp_f32_e32 v36, v36
	v_add_f32_e32 v40, 1.0, v40
	v_add_f32_e32 v36, 1.0, v36
	v_rcp_f32_e32 v40, v40
	v_rcp_f32_e32 v36, v36
	s_cbranch_vccz .LBB0_464
	s_movk_i32 s6, 0x104
	v_mad_u32_u24 v84, v94, s6, v82
	v_lshl_add_u32 v84, v84, 2, 0
	ds_write_b32 v84, v40 offset:52992
	v_add_u32_e32 v84, 0x15100, v84
	ds_write_b32 v84, v36
	s_mov_b64 s[6:7], 0

.LBB0_526:
	s_mul_i32 s4, s10, 0x208
	v_add_lshl_u32 v82, s4, v2, 2
	v_add_u32_e32 v20, 0, v82
	s_waitcnt lgkmcnt(0)
	s_barrier
	ds_read2st64_b32 v[20:21], v20 offset0:142 offset1:207
	s_mulk_i32 s28, 0x41
	v_add_lshl_u32 v35, s28, v2, 2
	v_add_u32_e32 v24, 0, v35
	v_add_u32_e32 v28, 0x9000, v24
	s_waitcnt lgkmcnt(0)
	v_exp_f32_e32 v42, v20
	v_add_u32_e32 v20, 0x8c00, v24
	s_and_b32 s4, s22, 0xc0
	v_or_b32_e32 v41, s4, v2
	v_fma_f32 v22, -v42, v42, 1.0
	v_max_f32_e32 v22, 0, v22
	v_sqrt_f32_e32 v25, v22
	ds_read2_b32 v[22:23], v20 offset0:128 offset1:193
	v_mul_f32_e32 v20, v85, v21
	s_add_i32 s4, 0, 0x11000
	v_mul_f32_e32 v39, v20, v25
	v_add_u32_e32 v20, 0xce00, v24
	s_waitcnt lgkmcnt(0)
	v_exp_f32_e32 v38, v22
	v_exp_f32_e32 v36, v23
	ds_read2_b32 v[20:21], v20 offset0:64 offset1:129
	v_fma_f32 v25, 0, v42, v39
	v_fma_f32 v22, -v38, v38, 1.0
	v_max_f32_e32 v22, 0, v22
	v_sqrt_f32_e32 v26, v22
	v_fma_f32 v22, -v36, v36, 1.0
	v_max_f32_e32 v22, 0, v22
	v_sqrt_f32_e32 v27, v22
	ds_read2_b32 v[22:23], v28 offset0:2 offset1:67
	s_waitcnt lgkmcnt(1)
	v_mul_f32_e32 v20, v86, v20
	v_mul_f32_e32 v37, v20, v26
	v_mul_f32_e32 v21, v87, v21
	v_fma_f32 v20, v38, v25, v37
	s_waitcnt lgkmcnt(0)
	v_exp_f32_e32 v33, v22
	v_mul_f32_e32 v34, v21, v27
	v_fma_f32 v25, v36, v20, v34
	v_add_u32_e32 v20, 0xd000, v24
	ds_read2_b32 v[20:21], v20 offset0:66 offset1:131
	v_fma_f32 v22, -v33, v33, 1.0
	v_max_f32_e32 v22, 0, v22
	v_sqrt_f32_e32 v26, v22
	v_exp_f32_e32 v31, v23
	ds_read2_b32 v[22:23], v28 offset0:132 offset1:197
	s_waitcnt lgkmcnt(1)
	v_mul_f32_e32 v20, v88, v20
	v_mul_f32_e32 v32, v20, v26
	v_fma_f32 v20, -v31, v31, 1.0
	v_max_f32_e32 v20, 0, v20
	v_sqrt_f32_e32 v20, v20
	s_waitcnt lgkmcnt(0)
	v_exp_f32_e32 v28, v22
	v_mul_f32_e32 v21, v89, v21
	v_fma_f32 v22, v33, v25, v32
	v_mul_f32_e32 v29, v21, v20
	v_add_u32_e32 v20, 0xd200, v24
	v_fma_f32 v25, -v28, v28, 1.0
	ds_read2_b32 v[20:21], v20 offset0:68 offset1:133
	v_max_f32_e32 v25, 0, v25
	v_sqrt_f32_e32 v25, v25
	v_exp_f32_e32 v26, v23
	v_fma_f32 v23, v31, v22, v29
	s_waitcnt lgkmcnt(0)
	v_mul_f32_e32 v20, v90, v20
	v_mul_f32_e32 v27, v20, v25
	v_fma_f32 v20, -v26, v26, 1.0
	v_add_u32_e32 v22, 0x618, v35
	s_add_i32 s5, 0, 0x15100
	v_add_u32_e32 v30, 0x514, v35
	v_add_u32_e32 v43, 0x410, v35
	v_max_f32_e32 v20, 0, v20
	v_add_u32_e32 v25, s4, v22
	v_add_u32_e32 v22, s5, v22
	v_add_u32_e32 v40, s4, v30
	v_add_u32_e32 v30, s5, v30
	v_add_u32_e32 v74, s4, v43
	v_add_u32_e32 v43, s5, v43
	v_sqrt_f32_e32 v20, v20
	ds_read_b32 v75, v24 offset:37912
	ds_read_b32 v24, v24 offset:54552
	ds_read_b32 v25, v25
	ds_read_b32 v83, v22
	ds_read_b32 v40, v40
	ds_read_b32 v30, v30
	ds_read_b32 v84, v74
	ds_read_b32 v43, v43
	s_waitcnt lgkmcnt(7)
	v_exp_f32_e32 v22, v75
	v_mul_f32_e32 v21, v81, v21
	v_fma_f32 v75, v28, v23, v27
	v_mul_f32_e32 v23, v21, v20
	v_fma_f32 v20, -v22, v22, 1.0
	v_max_f32_e32 v20, 0, v20
	v_sqrt_f32_e32 v20, v20
	s_waitcnt lgkmcnt(5)
	v_exp_f32_e32 v74, v25
	v_mul_f32_e32 v24, v73, v24
	s_waitcnt lgkmcnt(3)
	v_exp_f32_e32 v73, v40
	v_mul_f32_e32 v24, v24, v20
	v_fma_f32 v20, -v74, v74, 1.0
	v_max_f32_e32 v20, 0, v20
	v_sqrt_f32_e32 v20, v20
	v_mul_f32_e32 v25, v72, v83
	s_waitcnt lgkmcnt(2)
	v_mul_f32_e32 v30, v80, v30
	v_add_u32_e32 v80, 0x30c, v35
	v_add_u32_e32 v83, 0x208, v35
	v_add_u32_e32 v85, 0x104, v35
	v_fma_f32 v21, v26, v75, v23
	s_waitcnt lgkmcnt(1)
	v_exp_f32_e32 v75, v84
	v_add_u32_e32 v81, s4, v80
	v_add_u32_e32 v80, s5, v80
	v_add_u32_e32 v84, s4, v83
	v_add_u32_e32 v83, s5, v83
	v_add_u32_e32 v86, s4, v85
	v_add_u32_e32 v85, s5, v85
	v_add_u32_e32 v87, s4, v35
	v_add_u32_e32 v35, s5, v35
	ds_read_b32 v81, v81
	ds_read_b32 v88, v80
	ds_read_b32 v84, v84
	ds_read_b32 v83, v83
	ds_read_b32 v86, v86
	ds_read_b32 v85, v85
	ds_read_b32 v87, v87
	ds_read_b32 v89, v35
	s_waitcnt lgkmcnt(7)
	v_exp_f32_e32 v80, v81
	v_mul_f32_e32 v25, v25, v20
	v_fma_f32 v20, -v73, v73, 1.0
	v_max_f32_e32 v20, 0, v20
	v_sqrt_f32_e32 v20, v20
	v_fma_f32 v72, -v75, v75, 1.0
	v_max_f32_e32 v72, 0, v72
	v_mul_f32_e32 v35, v79, v43
	v_fma_f32 v43, -v80, v80, 1.0
	v_sqrt_f32_e32 v72, v72
	v_max_f32_e32 v43, 0, v43
	v_sqrt_f32_e32 v43, v43
	s_waitcnt lgkmcnt(5)
	v_exp_f32_e32 v79, v84
	v_fma_f32 v40, 0, v74, v25
	v_mul_f32_e32 v30, v30, v20
	v_fma_f32 v20, v73, v40, v30
	v_mul_f32_e32 v40, v74, v73
	v_mul_f32_e32 v35, v35, v72
	v_mul_f32_e32 v72, v40, v75
	v_mul_f32_e32 v40, v78, v88
	v_mul_f32_e32 v40, v40, v43
	v_fma_f32 v43, -v79, v79, 1.0
	v_max_f32_e32 v43, 0, v43
	v_sqrt_f32_e32 v43, v43
	s_waitcnt lgkmcnt(3)
	v_exp_f32_e32 v78, v86
	v_mul_f32_e32 v77, v77, v83
	v_mul_f32_e32 v72, v72, v80
	v_mul_f32_e32 v43, v77, v43
	v_fma_f32 v77, -v78, v78, 1.0
	v_max_f32_e32 v77, 0, v77
	v_sqrt_f32_e32 v81, v77
	v_mul_f32_e32 v83, v72, v79
	s_waitcnt lgkmcnt(2)
	v_mul_f32_e32 v72, v76, v85
	s_waitcnt lgkmcnt(1)
	v_exp_f32_e32 v77, v87
	v_mul_f32_e32 v72, v72, v81
	v_add_u32_e32 v81, s4, v82
	ds_read_b32 v81, v81
	v_fma_f32 v76, -v77, v77, 1.0
	v_max_f32_e32 v76, 0, v76
	v_add_u32_e32 v82, s5, v82
	v_sqrt_f32_e32 v76, v76
	ds_read_b32 v82, v82
	s_waitcnt lgkmcnt(1)
	v_exp_f32_e32 v81, v81
	v_mul_f32_e32 v3, v3, v89
	v_mul_f32_e32 v76, v3, v76
	v_fma_f32 v20, v75, v20, v35
	v_fma_f32 v3, -v81, v81, 1.0
	v_max_f32_e32 v3, 0, v3
	v_sqrt_f32_e32 v3, v3
	v_fma_f32 v20, v80, v20, v40
	v_fma_f32 v20, v79, v20, v43
	v_fma_f32 v20, v78, v20, v72
	s_waitcnt lgkmcnt(0)
	v_mul_f32_e32 v0, v0, v82
	v_fma_f32 v20, v77, v20, v76
	v_mul_f32_e32 v82, v0, v3
	v_fma_f32 v0, v81, v20, v82
	v_mul_f32_e32 v20, v42, v38
	v_mul_f32_e32 v20, v20, v36
	v_mul_f32_e32 v20, v20, v33
	s_and_b32 s4, s27, 0x3fffffc0
	v_mul_f32_e32 v83, v83, v78
	v_mul_f32_e32 v20, v20, v31
	s_lshl_b32 s4, s4, 2
	v_mul_f32_e32 v83, v83, v77
	v_mul_f32_e32 v20, v20, v28
	s_add_i32 s4, s4, 0
	v_mul_f32_e32 v3, v83, v81
	v_mul_f32_e32 v20, v20, v26
	v_lshl_add_u32 v83, v2, 2, s4
	v_fma_f32 v21, v22, v21, v24
	v_mul_f32_e32 v20, v20, v22
	v_add_u32_e32 v83, 0x19200, v83
	s_cmp_gt_u32 s27, 63
	ds_write2st64_b32 v83, v20, v21 offset1:8
	ds_write2st64_b32 v83, v3, v0 offset0:16 offset1:24
	s_waitcnt lgkmcnt(0)
	s_barrier
	s_waitcnt vmcnt(0)
	s_cbranch_scc1 .LBB0_528
	v_lshl_add_u32 v0, v2, 2, 0
	v_add_u32_e32 v3, 0x19200, v0
	ds_read2st64_b32 v[20:21], v3 offset0:8 offset1:9
	ds_read2st64_b32 v[84:85], v3 offset1:1
	ds_read2st64_b32 v[86:87], v3 offset0:2 offset1:3
	ds_read2st64_b32 v[88:89], v3 offset0:4 offset1:5
	ds_read2st64_b32 v[90:91], v3 offset0:6 offset1:7
	ds_read2st64_b32 v[92:93], v3 offset0:10 offset1:11
	ds_read2st64_b32 v[94:95], v3 offset0:12 offset1:13
	ds_read2st64_b32 v[96:97], v3 offset0:14 offset1:15
	s_waitcnt lgkmcnt(6)
	v_fma_f32 v3, 0, v84, v20
	v_fmac_f32_e32 v21, v3, v85
	s_waitcnt lgkmcnt(2)
	v_fma_f32 v3, v21, v86, v92
	v_fmac_f32_e32 v93, v3, v87
	s_waitcnt lgkmcnt(1)
	v_fma_f32 v3, v93, v88, v94
	v_fmac_f32_e32 v95, v3, v89
	s_waitcnt lgkmcnt(0)
	v_fma_f32 v3, v95, v90, v96
	v_fmac_f32_e32 v97, v3, v91
	v_add_u32_e32 v3, 0x1a900, v0
	v_add_u32_e32 v20, 0x1b100, v0
	v_add_u32_e32 v21, 0x1a800, v0
	v_add_u32_e32 v83, 0x1b000, v0
	v_add_u32_e32 v92, 0x1a700, v0
	v_add_u32_e32 v93, 0x1af00, v0
	v_add_u32_e32 v94, 0x1a600, v0
	v_add_u32_e32 v95, 0x1ae00, v0
	ds_read_b32 v3, v3
	ds_read_b32 v20, v20
	ds_read_b32 v21, v21
	ds_read_b32 v83, v83
	ds_read_b32 v92, v92
	ds_read_b32 v93, v93
	ds_read_b32 v94, v94
	ds_read_b32 v95, v95
	s_waitcnt lgkmcnt(6)
	v_fmac_f32_e32 v20, 0, v3
	s_waitcnt lgkmcnt(4)
	v_fmac_f32_e32 v83, v20, v21
	v_mul_f32_e32 v3, v3, v21
	s_waitcnt lgkmcnt(2)
	v_fmac_f32_e32 v93, v83, v92
	v_mul_f32_e32 v3, v3, v92
	s_waitcnt lgkmcnt(0)
	v_fmac_f32_e32 v95, v93, v94
	v_mul_f32_e32 v3, v3, v94
	v_add_u32_e32 v20, 0x1a500, v0
	v_add_u32_e32 v21, 0x1ad00, v0
	v_add_u32_e32 v83, 0x1a400, v0
	v_add_u32_e32 v92, 0x1ac00, v0
	v_add_u32_e32 v93, 0x1a300, v0
	v_add_u32_e32 v94, 0x1ab00, v0
	v_add_u32_e32 v96, 0x1a200, v0
	v_add_u32_e32 v0, 0x1aa00, v0
	ds_read_b32 v20, v20
	ds_read_b32 v21, v21
	ds_read_b32 v83, v83
	ds_read_b32 v92, v92
	ds_read_b32 v93, v93
	ds_read_b32 v94, v94
	ds_read_b32 v96, v96
	ds_read_b32 v98, v0
	s_waitcnt lgkmcnt(7)
	v_mul_f32_e32 v0, v3, v20
	s_waitcnt lgkmcnt(5)
	v_mul_f32_e32 v0, v0, v83
	s_waitcnt lgkmcnt(3)
	v_mul_f32_e32 v0, v0, v93
	s_waitcnt lgkmcnt(1)
	v_mul_f32_e32 v3, v0, v96
	v_mul_f32_e32 v0, v84, v85
	v_mul_f32_e32 v0, v0, v86
	v_mul_f32_e32 v0, v0, v87
	v_mul_f32_e32 v0, v0, v88
	v_mul_f32_e32 v0, v0, v89
	v_fmac_f32_e32 v21, v95, v20
	v_mul_f32_e32 v0, v0, v90
	v_fmac_f32_e32 v92, v21, v83
	v_mul_f32_e32 v83, v0, v91
	s_mul_i32 s6, s26, 0x88
	v_mov_b32_e32 v0, s59
	s_ashr_i32 s5, s6, 31
	s_ashr_i32 s7, s11, 31
	ds_read_b64 v[20:21], v0
	s_add_u32 s4, s6, s11
	s_addc_u32 s5, s5, s7
	s_addk_i32 s6, 0x44
	s_ashr_i32 s26, s6, 31
	s_add_u32 s6, s6, s11
	s_addc_u32 s7, s26, s7
	s_waitcnt lgkmcnt(0)
	v_readfirstlane_b32 s26, v20
	v_readfirstlane_b32 s11, v21
	s_add_u32 s26, s26, 0x700000
	s_addc_u32 s11, s11, 0
	s_lshl_b64 s[4:5], s[4:5], 10
	s_add_u32 s4, s26, s4
	s_addc_u32 s5, s11, s5
	v_lshlrev_b32_e32 v0, 2, v41
	v_lshl_add_u64 v[20:21], s[4:5], 0, v[0:1]
	s_mov_b32 s4, 0x110000
	global_store_dword v[20:21], v83, off
	v_add_co_u32_e32 v20, vcc, s4, v20
	s_lshl_b64 s[4:5], s[6:7], 10
	s_add_u32 s4, s26, s4
	v_addc_co_u32_e32 v21, vcc, 0, v21, vcc
	s_addc_u32 s5, s11, s5
	global_store_dword v[20:21], v97, off
	v_lshl_add_u64 v[20:21], s[4:5], 0, v[0:1]
	v_fmac_f32_e32 v94, v92, v93
	global_store_dword v[20:21], v3, off
	v_add_co_u32_e32 v20, vcc, 0x110000, v20
	v_fmac_f32_e32 v98, v94, v96
	s_nop 0
	v_addc_co_u32_e32 v21, vcc, 0, v21, vcc
	global_store_dword v[20:21], v98, off

.LBB0_557:
	v_mul_f32_e32 v84, v42, v20
	v_fmac_f32_e32 v25, v74, v83
	v_mul_f32_e32 v20, v74, v0
	v_fmac_f32_e32 v39, v42, v21
	v_fmac_f32_e32 v30, v73, v25
	v_mul_f32_e32 v21, v73, v20
	v_fmac_f32_e32 v35, v75, v30
	v_mul_f32_e32 v42, v75, v21
	v_fmac_f32_e32 v40, v80, v35
	v_mul_f32_e32 v73, v80, v42
	v_fmac_f32_e32 v43, v79, v40
	v_mul_f32_e32 v74, v79, v73
	v_fmac_f32_e32 v72, v78, v43
	v_mul_f32_e32 v75, v78, v74
	s_mul_i32 s5, s9, 0x600
	s_mul_hi_u32 s9, s8, 0x600
	v_fmac_f32_e32 v76, v77, v72
	v_mul_f32_e32 v77, v77, v75
	s_add_i32 s9, s9, s5
	s_mul_i32 s5, s8, 0x600
	v_fmac_f32_e32 v82, v81, v76
	v_mul_f32_e32 v0, v81, v77
	s_add_u32 s6, s6, s5
	v_add_f32_e32 v78, v39, v82
	s_addc_u32 s7, s7, s9
	v_cvt_pk_bf16_f32 v80, v84, v0
	v_lshlrev_b32_e32 v0, 1, v41
	v_cvt_pk_bf16_f32 v81, v78, s0
	v_lshl_add_u64 v[78:79], s[6:7], 0, v[0:1]
	s_cmpk_lt_i32 s4, 0x7fff
	s_mov_b64 s[10:11], -1
	global_store_short v[78:79], v81, off
	global_store_short v[78:79], v80, off offset:512
	global_store_short_d16_hi v[78:79], v80, off offset:1024
	s_cbranch_scc1 .LBB0_559
	s_waitcnt lgkmcnt(0)
	v_readfirstlane_b32 s6, v2
	v_readfirstlane_b32 s5, v3
	s_add_u32 s6, s6, 0xdd00000
	s_addc_u32 s7, s5, 0
	s_add_i32 s78, s4, 0xffff8001
	s_mov_b64 s[10:11], 0
	s_mov_b64 s[8:9], s[78:79]

.LBB0_561:
	s_mul_i32 s5, s9, 0x600
	s_mul_hi_u32 s9, s8, 0x600
	s_add_i32 s9, s9, s5
	s_mul_i32 s5, s8, 0x600
	v_fmac_f32_e32 v37, v38, v39
	s_add_u32 s6, s6, s5
	v_mul_f32_e32 v38, v38, v84
	v_add_f32_e32 v39, v37, v76
	s_addc_u32 s7, s7, s9
	v_cvt_pk_bf16_f32 v41, v38, v77
	v_cvt_pk_bf16_f32 v39, v39, s0
	v_lshl_add_u64 v[76:77], s[6:7], 0, v[0:1]
	s_cmpk_lt_i32 s4, 0x7ffe
	s_mov_b64 s[10:11], -1
	global_store_short v[76:77], v39, off
	global_store_short v[76:77], v41, off offset:512
	global_store_short_d16_hi v[76:77], v41, off offset:1024
	s_cbranch_scc1 .LBB0_563
	s_waitcnt lgkmcnt(0)
	v_readfirstlane_b32 s6, v2
	v_readfirstlane_b32 s5, v3
	s_add_u32 s6, s6, 0xdd00000
	s_addc_u32 s7, s5, 0
	s_add_i32 s78, s4, 0xffff8002
	s_mov_b64 s[10:11], 0
	s_mov_b64 s[8:9], s[78:79]

.LBB0_565:
	s_mul_i32 s5, s9, 0x600
	s_mul_hi_u32 s9, s8, 0x600
	s_add_i32 s9, s9, s5
	s_mul_i32 s5, s8, 0x600
	v_fmac_f32_e32 v34, v36, v37
	s_add_u32 s6, s6, s5
	v_add_f32_e32 v37, v34, v72
	s_addc_u32 s7, s7, s9
	v_mul_f32_e32 v36, v36, v38
	v_cvt_pk_bf16_f32 v37, v37, s0
	v_lshl_add_u64 v[38:39], s[6:7], 0, v[0:1]
	s_cmpk_lt_i32 s4, 0x7ffd
	s_mov_b64 s[10:11], -1
	v_cvt_pk_bf16_f32 v41, v36, v75
	global_store_short v[38:39], v37, off
	global_store_short v[38:39], v41, off offset:512
	global_store_short_d16_hi v[38:39], v41, off offset:1024
	s_cbranch_scc1 .LBB0_567
	s_waitcnt lgkmcnt(0)
	v_readfirstlane_b32 s6, v2
	v_readfirstlane_b32 s5, v3
	s_add_u32 s6, s6, 0xdd00000
	s_addc_u32 s7, s5, 0
	s_add_i32 s78, s4, 0xffff8003
	s_mov_b64 s[10:11], 0
	s_mov_b64 s[8:9], s[78:79]

.LBB0_569:
	s_mul_i32 s5, s9, 0x600
	s_mul_hi_u32 s9, s8, 0x600
	s_add_i32 s9, s9, s5
	s_mul_i32 s5, s8, 0x600
	v_fmac_f32_e32 v32, v33, v34
	s_add_u32 s6, s6, s5
	v_add_f32_e32 v34, v32, v43
	s_addc_u32 s7, s7, s9
	v_mul_f32_e32 v33, v33, v36
	v_cvt_pk_bf16_f32 v34, v34, s0
	v_lshl_add_u64 v[36:37], s[6:7], 0, v[0:1]
	s_cmpk_lt_i32 s4, 0x7ffc
	s_mov_b64 s[10:11], -1
	v_cvt_pk_bf16_f32 v38, v33, v74
	global_store_short v[36:37], v34, off
	global_store_short v[36:37], v38, off offset:512
	global_store_short_d16_hi v[36:37], v38, off offset:1024
	s_cbranch_scc1 .LBB0_571
	s_waitcnt lgkmcnt(0)
	v_readfirstlane_b32 s6, v2
	v_readfirstlane_b32 s5, v3
	s_add_u32 s6, s6, 0xdd00000
	s_addc_u32 s7, s5, 0
	s_add_i32 s78, s4, 0xffff8004
	s_mov_b64 s[10:11], 0
	s_mov_b64 s[8:9], s[78:79]

.LBB0_573:
	s_mul_i32 s5, s9, 0x600
	s_mul_hi_u32 s9, s8, 0x600
	s_add_i32 s9, s9, s5
	s_mul_i32 s5, s8, 0x600
	v_fmac_f32_e32 v29, v31, v32
	s_add_u32 s6, s6, s5
	v_add_f32_e32 v32, v29, v40
	s_addc_u32 s7, s7, s9
	v_mul_f32_e32 v31, v31, v33
	v_cvt_pk_bf16_f32 v36, v32, s0
	v_lshl_add_u64 v[32:33], s[6:7], 0, v[0:1]
	s_cmpk_lt_i32 s4, 0x7ffb
	s_mov_b64 s[10:11], -1
	v_cvt_pk_bf16_f32 v34, v31, v73
	global_store_short v[32:33], v36, off
	global_store_short v[32:33], v34, off offset:512
	global_store_short_d16_hi v[32:33], v34, off offset:1024
	s_cbranch_scc1 .LBB0_575
	s_waitcnt lgkmcnt(0)
	v_readfirstlane_b32 s6, v2
	v_readfirstlane_b32 s5, v3
	s_add_u32 s6, s6, 0xdd00000
	s_addc_u32 s7, s5, 0
	s_add_i32 s78, s4, 0xffff8005
	s_mov_b64 s[10:11], 0
	s_mov_b64 s[8:9], s[78:79]

.LBB0_577:
	s_mul_i32 s5, s9, 0x600
	s_mul_hi_u32 s9, s8, 0x600
	s_add_i32 s9, s9, s5
	s_mul_i32 s5, s8, 0x600
	v_fmac_f32_e32 v27, v28, v29
	s_add_u32 s6, s6, s5
	v_add_f32_e32 v29, v27, v35
	s_addc_u32 s7, s7, s9
	v_mul_f32_e32 v28, v28, v31
	v_cvt_pk_bf16_f32 v29, v29, s0
	v_lshl_add_u64 v[32:33], s[6:7], 0, v[0:1]
	s_cmpk_lt_i32 s4, 0x7ffa
	s_mov_b64 s[10:11], -1
	v_cvt_pk_bf16_f32 v31, v28, v42
	global_store_short v[32:33], v29, off
	global_store_short v[32:33], v31, off offset:512
	global_store_short_d16_hi v[32:33], v31, off offset:1024
	s_cbranch_scc1 .LBB0_579
	s_waitcnt lgkmcnt(0)
	v_readfirstlane_b32 s6, v2
	v_readfirstlane_b32 s5, v3
	s_add_u32 s6, s6, 0xdd00000
	s_addc_u32 s7, s5, 0
	s_add_i32 s78, s4, 0xffff8006
	s_mov_b64 s[10:11], 0
	s_mov_b64 s[8:9], s[78:79]

.LBB0_581:
	s_mul_i32 s5, s9, 0x600
	s_mul_hi_u32 s9, s8, 0x600
	s_add_i32 s9, s9, s5
	s_mul_i32 s5, s8, 0x600
	v_fmac_f32_e32 v23, v26, v27
	s_add_u32 s6, s6, s5
	v_add_f32_e32 v27, v23, v30
	s_addc_u32 s7, s7, s9
	v_mul_f32_e32 v26, v26, v28
	v_cvt_pk_bf16_f32 v27, v27, s0
	v_lshl_add_u64 v[28:29], s[6:7], 0, v[0:1]
	s_cmpk_lt_i32 s4, 0x7ff9
	s_mov_b64 s[10:11], -1
	v_cvt_pk_bf16_f32 v21, v26, v21
	global_store_short v[28:29], v27, off
	global_store_short v[28:29], v21, off offset:512
	global_store_short_d16_hi v[28:29], v21, off offset:1024
	s_cbranch_scc1 .LBB0_583
	s_waitcnt lgkmcnt(0)
	v_readfirstlane_b32 s6, v2
	v_readfirstlane_b32 s5, v3
	s_add_u32 s6, s6, 0xdd00000
	s_addc_u32 s7, s5, 0
	s_add_i32 s78, s4, 0xffff8007
	s_mov_b64 s[10:11], 0
	s_mov_b64 s[8:9], s[78:79]

.LBB0_594:
	s_or_b64 exec, exec, s[0:1]
	v_mul_f32_e32 v0, 0, v3
	v_fma_f32 v159, 0, v2, v0
	v_add_f32_e32 v135, v159, v135
	v_fma_f32 v0, v2, 0, -v0
	v_mul_f32_e32 v159, v2, v135
	v_add_f32_e32 v0, v0, v134
	v_mul_f32_e32 v134, v3, v135
	v_fmac_f32_e32 v159, v3, v0
	v_fma_f32 v0, v2, v0, -v134
	v_add_f32_e32 v0, v132, v0
	v_add_f32_e32 v133, v133, v159
	v_mul_f32_e32 v132, v3, v0
	v_fmac_f32_e32 v132, v2, v133
	v_add_f32_e32 v131, v131, v132
	v_mul_f32_e32 v132, v3, v133
	v_fma_f32 v0, v2, v0, -v132
	v_add_f32_e32 v0, v130, v0
	v_mul_f32_e32 v130, v3, v0
	v_fmac_f32_e32 v130, v2, v131
	v_add_f32_e32 v127, v127, v130
	v_mul_f32_e32 v130, v3, v131
	v_fma_f32 v0, v2, v0, -v130
	v_add_f32_e32 v0, v126, v0
	v_mul_f32_e32 v126, v3, v0
	v_fmac_f32_e32 v126, v2, v127
	v_add_f32_e32 v123, v123, v126
	v_mul_f32_e32 v126, v3, v127
	v_fma_f32 v0, v2, v0, -v126
	v_add_f32_e32 v0, v122, v0
	v_mul_f32_e32 v122, v3, v0
	v_fmac_f32_e32 v122, v2, v123
	v_add_f32_e32 v119, v119, v122
	v_mul_f32_e32 v122, v3, v123
	v_fma_f32 v0, v2, v0, -v122
	v_add_f32_e32 v0, v118, v0
	v_mul_f32_e32 v118, v3, v0
	v_fmac_f32_e32 v118, v2, v119
	v_add_f32_e32 v117, v117, v118
	v_mul_f32_e32 v118, v3, v119
	v_fma_f32 v0, v2, v0, -v118
	v_add_f32_e32 v0, v116, v0
	v_mul_f32_e32 v116, v3, v0
	v_fmac_f32_e32 v116, v2, v117
	v_add_f32_e32 v113, v113, v116
	v_mul_f32_e32 v116, v3, v117
	v_fma_f32 v0, v2, v0, -v116
	v_add_f32_e32 v0, v112, v0
	v_mul_f32_e32 v112, v3, v0
	v_fmac_f32_e32 v112, v2, v113
	v_add_f32_e32 v109, v109, v112
	v_mul_f32_e32 v112, v3, v113
	v_fma_f32 v0, v2, v0, -v112
	v_add_f32_e32 v0, v108, v0
	v_mul_f32_e32 v108, v3, v0
	v_fmac_f32_e32 v108, v2, v109
	v_add_f32_e32 v103, v103, v108
	v_mul_f32_e32 v108, v3, v109
	v_fma_f32 v0, v2, v0, -v108
	v_add_f32_e32 v0, v102, v0
	v_mul_f32_e32 v102, v3, v0
	v_fmac_f32_e32 v102, v2, v103
	v_add_f32_e32 v97, v97, v102
	v_mul_f32_e32 v102, v3, v103
	v_fma_f32 v0, v2, v0, -v102
	v_add_f32_e32 v0, v96, v0
	v_mul_f32_e32 v96, v3, v0
	v_fmac_f32_e32 v96, v2, v97
	v_add_f32_e32 v91, v91, v96
	v_mul_f32_e32 v96, v3, v97
	v_fma_f32 v0, v2, v0, -v96
	v_add_f32_e32 v0, v90, v0
	v_mul_f32_e32 v90, v3, v0
	v_fmac_f32_e32 v90, v2, v91
	v_add_f32_e32 v87, v87, v90
	v_mul_f32_e32 v90, v3, v91
	v_fma_f32 v0, v2, v0, -v90
	v_add_f32_e32 v0, v86, v0
	v_mul_f32_e32 v86, v3, v0
	v_fmac_f32_e32 v86, v2, v87
	v_add_f32_e32 v83, v83, v86
	v_mul_f32_e32 v86, v3, v87
	v_fma_f32 v0, v2, v0, -v86
	v_add_f32_e32 v0, v82, v0
	v_mul_f32_e32 v82, v3, v0
	v_fmac_f32_e32 v82, v2, v83
	v_add_f32_e32 v77, v77, v82
	v_mul_f32_e32 v82, v3, v83
	v_fma_f32 v0, v2, v0, -v82
	v_add_f32_e32 v0, v76, v0
	v_mul_f32_e32 v76, v3, v0
	v_fmac_f32_e32 v76, v2, v77
	v_add_f32_e32 v71, v71, v76
	v_mul_f32_e32 v76, v3, v77
	v_fma_f32 v0, v2, v0, -v76
	v_add_f32_e32 v0, v70, v0
	v_mul_f32_e32 v70, v3, v0
	v_fmac_f32_e32 v70, v2, v71
	v_mul_f32_e32 v71, v3, v71
	v_add_f32_e32 v70, v70, v129
	v_fma_f32 v0, v2, v0, -v71
	v_mul_f32_e32 v76, v2, v70
	v_add_f32_e32 v0, v0, v128
	v_mul_f32_e32 v70, v3, v70
	v_fmac_f32_e32 v76, v3, v0
	v_fma_f32 v0, v2, v0, -v70
	v_add_f32_e32 v0, v124, v0
	v_add_f32_e32 v71, v125, v76
	v_mul_f32_e32 v70, v3, v0
	v_fmac_f32_e32 v70, v2, v71
	v_mul_f32_e32 v71, v3, v71
	v_fma_f32 v0, v2, v0, -v71
	v_add_f32_e32 v0, v120, v0
	v_add_f32_e32 v70, v121, v70
	v_mul_f32_e32 v71, v3, v0
	v_fmac_f32_e32 v71, v2, v70
	v_mul_f32_e32 v70, v3, v70
	v_fma_f32 v0, v2, v0, -v70
	v_add_f32_e32 v0, v114, v0
	v_add_f32_e32 v71, v115, v71
	v_mul_f32_e32 v70, v3, v0
	v_fmac_f32_e32 v70, v2, v71
	v_mul_f32_e32 v71, v3, v71
	v_fma_f32 v0, v2, v0, -v71
	v_add_f32_e32 v0, v110, v0
	v_add_f32_e32 v70, v111, v70
	v_mul_f32_e32 v71, v3, v0
	v_fmac_f32_e32 v71, v2, v70
	v_mul_f32_e32 v70, v3, v70
	v_fma_f32 v0, v2, v0, -v70
	v_add_f32_e32 v0, v104, v0
	v_add_f32_e32 v71, v105, v71
	v_mul_f32_e32 v70, v3, v0
	v_fmac_f32_e32 v70, v2, v71
	v_mul_f32_e32 v71, v3, v71
	v_fma_f32 v0, v2, v0, -v71
	v_add_f32_e32 v0, v98, v0
	v_add_f32_e32 v70, v99, v70
	v_mul_f32_e32 v71, v3, v0
	v_fmac_f32_e32 v71, v2, v70
	v_mul_f32_e32 v70, v3, v70
	v_fma_f32 v0, v2, v0, -v70
	v_add_f32_e32 v0, v92, v0
	v_add_f32_e32 v71, v93, v71
	v_mul_f32_e32 v70, v3, v0
	v_fmac_f32_e32 v70, v2, v71
	v_mul_f32_e32 v71, v3, v71
	v_fma_f32 v0, v2, v0, -v71
	v_add_f32_e32 v0, v84, v0
	v_add_f32_e32 v70, v85, v70
	v_mul_f32_e32 v71, v3, v0
	v_fmac_f32_e32 v71, v2, v70
	v_mul_f32_e32 v70, v3, v70
	v_fma_f32 v0, v2, v0, -v70
	v_add_f32_e32 v0, v78, v0
	v_add_f32_e32 v71, v79, v71
	v_mul_f32_e32 v70, v3, v0
	v_fmac_f32_e32 v70, v2, v71
	v_mul_f32_e32 v71, v3, v71
	v_fma_f32 v0, v2, v0, -v71
	v_add_f32_e32 v0, v72, v0
	v_add_f32_e32 v70, v73, v70
	v_mul_f32_e32 v71, v3, v0
	v_fmac_f32_e32 v71, v2, v70
	v_mul_f32_e32 v70, v3, v70
	v_fma_f32 v0, v2, v0, -v70
	v_add_f32_e32 v0, v66, v0
	v_add_f32_e32 v67, v67, v71
	v_mul_f32_e32 v66, v3, v0
	v_fmac_f32_e32 v66, v2, v67
	v_add_f32_e32 v63, v63, v66
	v_mul_f32_e32 v66, v3, v67
	v_fma_f32 v0, v2, v0, -v66
	v_add_f32_e32 v0, v62, v0
	v_mul_f32_e32 v62, v3, v0
	v_fmac_f32_e32 v62, v2, v63
	v_add_f32_e32 v59, v59, v62
	v_mul_f32_e32 v62, v3, v63
	v_fma_f32 v0, v2, v0, -v62
	v_add_f32_e32 v0, v58, v0
	v_mul_f32_e32 v58, v3, v0
	v_fmac_f32_e32 v58, v2, v59
	v_add_f32_e32 v55, v55, v58
	v_mul_f32_e32 v58, v3, v59
	v_fma_f32 v0, v2, v0, -v58
	v_add_f32_e32 v0, v54, v0
	v_mul_f32_e32 v54, v3, v0
	v_fmac_f32_e32 v54, v2, v55
	v_add_f32_e32 v51, v51, v54
	v_mul_f32_e32 v54, v3, v55
	v_fma_f32 v0, v2, v0, -v54
	v_add_f32_e32 v0, v50, v0
	v_mul_f32_e32 v50, v3, v0
	v_fmac_f32_e32 v50, v2, v51
	v_mul_f32_e32 v51, v3, v51
	s_waitcnt lgkmcnt(14)
	v_add_f32_e32 v50, v50, v107
	v_fma_f32 v0, v2, v0, -v51
	v_mul_f32_e32 v54, v2, v50
	v_add_f32_e32 v0, v0, v106
	v_mul_f32_e32 v50, v3, v50
	v_fmac_f32_e32 v54, v3, v0
	v_fma_f32 v0, v2, v0, -v50
	v_add_f32_e32 v0, v100, v0
	v_add_f32_e32 v51, v101, v54
	v_mul_f32_e32 v50, v3, v0
	v_fmac_f32_e32 v50, v2, v51
	v_mul_f32_e32 v51, v3, v51
	v_fma_f32 v0, v2, v0, -v51
	s_waitcnt lgkmcnt(13)
	v_add_f32_e32 v0, v94, v0
	v_add_f32_e32 v50, v95, v50
	v_mul_f32_e32 v51, v3, v0
	v_fmac_f32_e32 v51, v2, v50
	v_mul_f32_e32 v50, v3, v50
	v_fma_f32 v0, v2, v0, -v50
	s_waitcnt lgkmcnt(12)
	v_add_f32_e32 v0, v88, v0
	v_add_f32_e32 v51, v89, v51
	v_mul_f32_e32 v50, v3, v0
	v_fmac_f32_e32 v50, v2, v51
	v_mul_f32_e32 v51, v3, v51
	v_fma_f32 v0, v2, v0, -v51
	s_waitcnt lgkmcnt(11)
	v_add_f32_e32 v0, v80, v0
	v_add_f32_e32 v50, v81, v50
	v_mul_f32_e32 v51, v3, v0
	v_fmac_f32_e32 v51, v2, v50
	v_mul_f32_e32 v50, v3, v50
	v_fma_f32 v0, v2, v0, -v50
	s_waitcnt lgkmcnt(10)
	v_add_f32_e32 v0, v74, v0
	v_add_f32_e32 v51, v75, v51
	v_mul_f32_e32 v50, v3, v0
	v_fmac_f32_e32 v50, v2, v51
	v_mul_f32_e32 v51, v3, v51
	v_fma_f32 v0, v2, v0, -v51
	s_waitcnt lgkmcnt(9)
	v_add_f32_e32 v0, v68, v0
	v_add_f32_e32 v50, v69, v50
	v_mul_f32_e32 v51, v3, v0
	v_fmac_f32_e32 v51, v2, v50
	v_mul_f32_e32 v50, v3, v50
	v_fma_f32 v0, v2, v0, -v50
	s_waitcnt lgkmcnt(8)
	v_add_f32_e32 v0, v64, v0
	v_add_f32_e32 v51, v65, v51
	v_mul_f32_e32 v50, v3, v0
	v_fmac_f32_e32 v50, v2, v51
	v_mul_f32_e32 v51, v3, v51
	v_fma_f32 v0, v2, v0, -v51
	s_waitcnt lgkmcnt(7)
	v_add_f32_e32 v0, v60, v0
	v_add_f32_e32 v50, v61, v50
	v_mul_f32_e32 v51, v3, v0
	v_fmac_f32_e32 v51, v2, v50
	v_mul_f32_e32 v50, v3, v50
	v_fma_f32 v0, v2, v0, -v50
	s_waitcnt lgkmcnt(6)
	v_add_f32_e32 v0, v56, v0
	v_add_f32_e32 v51, v57, v51
	v_mul_f32_e32 v50, v3, v0
	v_fmac_f32_e32 v50, v2, v51
	v_mul_f32_e32 v51, v3, v51
	v_fma_f32 v0, v2, v0, -v51
	s_waitcnt lgkmcnt(5)
	v_add_f32_e32 v0, v52, v0
	v_add_f32_e32 v50, v53, v50
	v_mul_f32_e32 v51, v3, v0
	v_fmac_f32_e32 v51, v2, v50
	v_mul_f32_e32 v50, v3, v50
	v_fma_f32 v0, v2, v0, -v50
	s_waitcnt lgkmcnt(4)
	v_add_f32_e32 v0, v48, v0
	v_add_f32_e32 v49, v49, v51
	v_mul_f32_e32 v48, v3, v0
	v_fmac_f32_e32 v48, v2, v49
	s_waitcnt lgkmcnt(3)
	v_add_f32_e32 v47, v47, v48
	v_mul_f32_e32 v48, v3, v49
	v_fma_f32 v0, v2, v0, -v48
	v_add_f32_e32 v0, v46, v0
	v_mul_f32_e32 v46, v3, v0
	v_fmac_f32_e32 v46, v2, v47
	s_waitcnt lgkmcnt(2)
	v_add_f32_e32 v45, v45, v46
	v_mul_f32_e32 v46, v3, v47
	v_fma_f32 v0, v2, v0, -v46
	v_add_f32_e32 v0, v44, v0
	v_mul_f32_e32 v44, v3, v0
	v_fmac_f32_e32 v44, v2, v45
	s_waitcnt lgkmcnt(1)
	v_add_f32_e32 v43, v43, v44
	v_mul_f32_e32 v44, v3, v45
	v_fma_f32 v0, v2, v0, -v44
	v_add_f32_e32 v0, v42, v0
	v_mul_f32_e32 v42, v3, v0
	s_waitcnt lgkmcnt(0)
	v_mfma_f32_16x16x32_bf16 v[32:35], v[36:39], v[32:35], 0
	v_fmac_f32_e32 v42, v2, v43
	v_add_f32_e32 v41, v41, v42
	v_mul_f32_e32 v42, v3, v43
	v_mfma_f32_16x16x32_bf16 v[28:31], v[36:39], v[28:31], 0
	v_fma_f32 v0, v2, v0, -v42
	v_add_f32_e32 v0, v40, v0
	s_nop 5
	ds_write2_b32 v137, v32, v28 offset1:16
	ds_write2_b32 v137, v33, v29 offset0:132 offset1:148
	ds_write2_b32 v138, v34, v30 offset0:8 offset1:24
	v_mfma_f32_16x16x32_bf16 v[24:27], v[36:39], v[24:27], 0
	s_or_b32 s0, s11, 1
	s_mul_hi_i32 s1, s0, 0x44
	s_mulk_i32 s0, 0x44
	v_mfma_f32_16x16x32_bf16 v[16:19], v[36:39], v[16:19], 0
	ds_write2_b32 v138, v35, v31 offset0:140 offset1:156
	s_nop 6
	ds_write2_b32 v137, v24, v16 offset0:32 offset1:48
	ds_write2_b32 v137, v25, v17 offset0:164 offset1:180
	v_mfma_f32_16x16x32_bf16 v[20:23], v[36:39], v[20:23], 0
	s_add_u32 s0, s0, s9
	s_addc_u32 s1, s1, s10
	s_lshl_b64 s[0:1], s[0:1], 10
	v_mfma_f32_16x16x32_bf16 v[12:15], v[36:39], v[12:15], 0
	ds_write2_b32 v138, v26, v18 offset0:40 offset1:56
	ds_write2_b32 v138, v27, v19 offset0:172 offset1:188
	s_nop 5
	ds_write2_b32 v137, v20, v12 offset0:64 offset1:80
	ds_write2_b32 v137, v21, v13 offset0:196 offset1:212
	ds_write2_b32 v138, v22, v14 offset0:72 offset1:88
	ds_write2_b32 v138, v23, v15 offset0:204 offset1:220
	v_mfma_f32_16x16x32_bf16 v[8:11], v[36:39], v[8:11], 0
	s_add_u32 s0, s0, s4
	s_addc_u32 s1, s1, s5
	s_add_i32 s6, s6, s54
	v_mfma_f32_16x16x32_bf16 v[4:7], v[36:39], v[4:7], 0
	v_mul_f32_e32 v36, v3, v41
	s_nop 6
	ds_write2_b32 v137, v8, v4 offset0:96 offset1:112
	ds_write2_b32 v137, v9, v5 offset0:228 offset1:244
	ds_write2_b32 v138, v10, v6 offset0:104 offset1:120
	ds_write2_b32 v138, v11, v7 offset0:236 offset1:252
	v_fma_f32 v36, v2, v0, -v36
	v_mul_f32_e32 v0, v3, v0
	s_waitcnt lgkmcnt(0)
	v_fmac_f32_e32 v0, v2, v41
	ds_read2st64_b32 v[4:5], v140 offset0:42 offset1:43
	ds_read2st64_b32 v[6:7], v141 offset0:40 offset1:41
	ds_read2st64_b32 v[8:9], v146 offset0:38 offset1:39
	ds_read2st64_b32 v[10:11], v147 offset0:36 offset1:37
	ds_read2st64_b32 v[12:13], v148 offset0:34 offset1:35
	ds_read2st64_b32 v[14:15], v149 offset0:32 offset1:33
	ds_read2st64_b32 v[16:17], v150 offset0:30 offset1:31
	ds_read2st64_b32 v[18:19], v151 offset0:28 offset1:29
	ds_read2st64_b32 v[20:21], v152 offset0:26 offset1:27
	ds_read2st64_b32 v[22:23], v153 offset0:24 offset1:25
	ds_read2st64_b32 v[24:25], v154 offset0:22 offset1:23
	ds_read2st64_b32 v[26:27], v155 offset0:20 offset1:21
	ds_read2st64_b32 v[28:29], v156 offset0:18 offset1:19
	ds_read2st64_b32 v[30:31], v157 offset0:16 offset1:17
	ds_read2st64_b32 v[32:33], v158 offset0:14 offset1:15
	ds_read2st64_b32 v[34:35], v139 offset0:12 offset1:13
	s_waitcnt lgkmcnt(14)
	v_add_f32_e32 v0, v0, v5
	v_add_f32_e32 v4, v36, v4
	v_mul_f32_e32 v5, v3, v0
	v_mul_f32_e32 v0, v2, v0
	v_fmac_f32_e32 v0, v3, v4
	v_fma_f32 v5, v2, v4, -v5
	v_add_f32_e32 v0, v7, v0
	v_add_f32_e32 v5, v6, v5
	v_mul_f32_e32 v4, v3, v0
	v_fma_f32 v4, v2, v5, -v4
	v_mul_f32_e32 v5, v3, v5
	v_fmac_f32_e32 v5, v2, v0
	s_waitcnt lgkmcnt(13)
	v_add_f32_e32 v0, v9, v5
	v_add_f32_e32 v4, v8, v4
	v_mul_f32_e32 v5, v3, v0
	v_fma_f32 v5, v2, v4, -v5
	v_mul_f32_e32 v4, v3, v4
	v_fmac_f32_e32 v4, v2, v0
	s_waitcnt lgkmcnt(12)
	v_add_f32_e32 v0, v11, v4
	v_add_f32_e32 v5, v10, v5
	v_mul_f32_e32 v4, v3, v0
	v_fma_f32 v4, v2, v5, -v4
	v_mul_f32_e32 v5, v3, v5
	v_fmac_f32_e32 v5, v2, v0
	s_waitcnt lgkmcnt(11)
	v_add_f32_e32 v0, v13, v5
	v_add_f32_e32 v4, v12, v4
	v_mul_f32_e32 v5, v3, v0
	v_fma_f32 v5, v2, v4, -v5
	v_mul_f32_e32 v4, v3, v4
	v_fmac_f32_e32 v4, v2, v0
	s_waitcnt lgkmcnt(10)
	v_add_f32_e32 v0, v15, v4
	v_add_f32_e32 v5, v14, v5
	v_mul_f32_e32 v4, v3, v0
	v_fma_f32 v4, v2, v5, -v4
	v_mul_f32_e32 v5, v3, v5
	v_fmac_f32_e32 v5, v2, v0
	s_waitcnt lgkmcnt(9)
	v_add_f32_e32 v0, v17, v5
	v_add_f32_e32 v4, v16, v4
	v_mul_f32_e32 v5, v3, v0
	v_fma_f32 v5, v2, v4, -v5
	v_mul_f32_e32 v4, v3, v4
	v_fmac_f32_e32 v4, v2, v0
	s_waitcnt lgkmcnt(8)
	v_add_f32_e32 v0, v19, v4
	v_add_f32_e32 v5, v18, v5
	v_mul_f32_e32 v4, v3, v0
	v_fma_f32 v4, v2, v5, -v4
	v_mul_f32_e32 v5, v3, v5
	v_fmac_f32_e32 v5, v2, v0
	s_waitcnt lgkmcnt(7)
	v_add_f32_e32 v0, v21, v5
	v_add_f32_e32 v4, v20, v4
	v_mul_f32_e32 v5, v3, v0
	v_fma_f32 v5, v2, v4, -v5
	v_mul_f32_e32 v4, v3, v4
	v_fmac_f32_e32 v4, v2, v0
	s_waitcnt lgkmcnt(6)
	v_add_f32_e32 v0, v23, v4
	v_add_f32_e32 v5, v22, v5
	v_mul_f32_e32 v4, v3, v0
	v_fma_f32 v4, v2, v5, -v4
	v_mul_f32_e32 v5, v3, v5
	v_fmac_f32_e32 v5, v2, v0
	s_waitcnt lgkmcnt(5)
	v_add_f32_e32 v0, v25, v5
	v_add_f32_e32 v4, v24, v4
	v_mul_f32_e32 v5, v3, v0
	v_fma_f32 v5, v2, v4, -v5
	v_mul_f32_e32 v4, v3, v4
	v_fmac_f32_e32 v4, v2, v0
	s_waitcnt lgkmcnt(4)
	v_add_f32_e32 v0, v27, v4
	v_add_f32_e32 v5, v26, v5
	v_mul_f32_e32 v4, v3, v0
	v_fma_f32 v4, v2, v5, -v4
	v_mul_f32_e32 v5, v3, v5
	v_fmac_f32_e32 v5, v2, v0
	s_waitcnt lgkmcnt(3)
	v_add_f32_e32 v0, v29, v5
	v_add_f32_e32 v4, v28, v4
	v_mul_f32_e32 v5, v3, v0
	v_fma_f32 v5, v2, v4, -v5
	v_mul_f32_e32 v4, v3, v4
	v_fmac_f32_e32 v4, v2, v0
	s_waitcnt lgkmcnt(2)
	v_add_f32_e32 v0, v31, v4
	v_add_f32_e32 v5, v30, v5
	v_mul_f32_e32 v4, v3, v0
	v_fma_f32 v4, v2, v5, -v4
	s_waitcnt lgkmcnt(1)
	v_add_f32_e32 v6, v32, v4
	v_mul_f32_e32 v4, v3, v5
	v_fmac_f32_e32 v4, v2, v0
	v_add_f32_e32 v0, v33, v4
	v_mul_f32_e32 v4, v3, v0
	v_mul_f32_e32 v3, v3, v6
	v_fmac_f32_e32 v3, v2, v0
	s_waitcnt lgkmcnt(0)
	v_mov_b32_e32 v0, s59
	v_fma_f32 v4, v2, v6, -v4
	s_waitcnt lgkmcnt(0)
	v_add_f32_e32 v5, v35, v3
	ds_read_b64 v[2:3], v0
	v_or_b32_e32 v6, s0, v136
	v_mov_b32_e32 v7, s1
	v_add_f32_e32 v4, v34, v4
	s_add_i32 s8, s8, s60
	s_waitcnt lgkmcnt(0)
	v_readfirstlane_b32 s0, v3
	v_readfirstlane_b32 s1, v2
	s_cmpk_lt_i32 s6, 0x440
	v_mov_b32_e32 v3, s0
	v_mov_b32_e32 v2, s1
	v_lshl_add_u64 v[2:3], v[6:7], 3, v[2:3]
	v_add_co_u32_e32 v2, vcc, 0xc00000, v2
	s_nop 1
	v_addc_co_u32_e32 v3, vcc, 0, v3, vcc
	global_store_dwordx2 v[2:3], v[4:5], off
	s_waitcnt lgkmcnt(0)
	s_cbranch_scc0 .LBB0_615

.LBB0_599:
	s_and_b32 s0, s8, 8
	v_mov_b64_e32 v[4:5], s[4:5]
	s_add_i32 s0, s0, s7
	v_mad_i64_i32 v[2:3], s[4:5], v2, s94, v[4:5]
	s_lshl_b32 s4, s0, 4
	s_ashr_i32 s5, s4, 31
	v_lshl_add_u64 v[2:3], s[4:5], 1, v[2:3]
	s_mov_b64 s[4:5], 0xe001000
	v_add_co_u32_e32 v6, vcc, 0xe001000, v2
	v_lshl_add_u64 v[4:5], v[2:3], 0, s[4:5]
	s_nop 0
	v_addc_co_u32_e32 v7, vcc, 0, v3, vcc
	global_load_dwordx4 v[2:5], v[4:5], off offset:16
	s_nop 0
	global_load_dwordx4 v[6:9], v[6:7], off
	s_lshr_b32 s1, s11, 6
	s_mulk_i32 s1, 0x3e00
	s_add_i32 s1, s1, 0
	v_mad_u32_u24 v0, v0, 48, s1
	s_waitcnt vmcnt(0)
	v_mov_b32_e32 v37, v204
	v_mov_b32_e32 v10, s59
	s_add_i32 s4, s0, s21
	s_ashr_i32 s5, s4, 31
	s_lshl_b64 s[22:23], s[4:5], 13
	v_mov_b32_e32 v11, v1
	s_mov_b32 s11, 0x200000
	v_mov_b32_e32 v36, 0
	v_mov_b32_e32 v38, 0
	v_mov_b32_e32 v39, 0
	v_mov_b32_e32 v40, 0
	v_mov_b32_e32 v41, 0
	s_waitcnt lgkmcnt(0)
	ds_write_b128 v0, v[2:5] offset:16
	ds_write_b128 v0, v[6:9]
	s_waitcnt lgkmcnt(0)
	ds_read_b64 v[2:3], v10
	v_readfirstlane_b32 s1, v37
	v_and_b32_e32 v136, 63, v37
	s_lshr_b32 s1, s1, 6
	v_lshl_or_b32 v4, s4, 6, v136
	s_mulk_i32 s1, 0x3e00
	v_ashrrev_i32_e32 v5, 31, v4
	s_add_i32 s1, s1, 0
	s_waitcnt lgkmcnt(0)
	v_readfirstlane_b32 s5, v3
	v_readfirstlane_b32 s4, v2
	v_and_b32_e32 v42, 15, v37
	v_and_b32_e32 v0, 48, v37
	v_lshl_add_u64 v[2:3], v[4:5], 4, s[4:5]
	s_add_u32 s4, s4, s22
	s_addc_u32 s5, s5, s23
	v_lshlrev_b32_e32 v10, 6, v42
	v_lshl_add_u64 v[4:5], s[4:5], 0, v[0:1]
	v_add_co_u32_e32 v2, vcc, s11, v2
	v_lshl_add_u64 v[6:7], v[4:5], 0, v[10:11]
	s_mov_b64 s[4:5], 0x240000
	v_addc_co_u32_e32 v3, vcc, 0, v3, vcc
	v_lshl_add_u64 v[8:9], v[6:7], 0, s[4:5]
	s_mov_b32 s4, 0x240000
	v_add_co_u32_e32 v10, vcc, s4, v6
	global_load_dwordx4 v[2:5], v[2:3], off
	s_nop 0
	global_load_dwordx4 v[28:31], v[8:9], off offset:1024
	global_load_dwordx4 v[20:23], v[8:9], off offset:2048
	global_load_dwordx4 v[12:15], v[8:9], off offset:3072
	s_mov_b64 s[36:37], vcc
	s_waitcnt vmcnt(0) lgkmcnt(0)
	v_add_co_u32_e32 v4, vcc, 0x241000, v6
	v_addc_co_u32_e64 v11, s[36:37], 0, v7, s[36:37]
	s_nop 0
	v_addc_co_u32_e32 v5, vcc, 0, v7, vcc
	global_load_dwordx4 v[32:35], v[10:11], off
	global_load_dwordx4 v[24:27], v[4:5], off
	global_load_dwordx4 v[16:19], v[4:5], off offset:1024
	s_nop 0
	global_load_dwordx4 v[8:11], v[4:5], off offset:2048
	s_nop 0
	global_load_dwordx4 v[4:7], v[4:5], off offset:3072
	v_add_u32_e32 v0, s1, v0
	v_cmp_gt_u32_e32 vcc, 32, v136
	v_mad_u32_u24 v158, v42, 48, v0
	s_and_saveexec_b64 s[4:5], vcc
	ds_read_b128 v[38:41], v158
	s_or_b64 exec, exec, s[4:5]
	s_waitcnt vmcnt(0) lgkmcnt(0)
	v_mfma_f32_16x16x32_bf16 v[44:47], v[38:41], v[32:35], 0
	v_bfe_u32 v0, v37, 4, 2
	v_lshlrev_b32_e32 v37, 2, v42
	v_mul_u32_u24_e32 v0, 0x840, v0
	v_mfma_f32_16x16x32_bf16 v[48:51], v[38:41], v[28:31], 0
	v_add3_u32 v37, s1, v37, v0
	v_add_u32_e32 v0, 0xc00, v37
	v_add_u32_e32 v137, 0x1000, v37
	v_mfma_f32_16x16x32_bf16 v[52:55], v[38:41], v[20:23], 0
	v_lshl_add_u32 v138, v136, 2, s1
	s_nop 2
	ds_write2_b32 v0, v44, v48 offset1:16
	ds_write2_b32 v0, v45, v49 offset0:132 offset1:148
	v_mfma_f32_16x16x32_bf16 v[56:59], v[38:41], v[12:15], 0
	ds_write2_b32 v137, v46, v50 offset0:8 offset1:24
	ds_write2_b32 v137, v47, v51 offset0:140 offset1:156
	s_nop 5
	ds_write2_b32 v0, v52, v56 offset0:32 offset1:48
	ds_write2_b32 v0, v53, v57 offset0:164 offset1:180
	v_mfma_f32_16x16x32_bf16 v[42:45], v[38:41], v[24:27], 0
	v_add_u32_e32 v139, 16, v138
	v_add_u32_e32 v140, 32, v138
	v_add_u32_e32 v141, 48, v138
	v_mfma_f32_16x16x32_bf16 v[46:49], v[38:41], v[16:19], 0
	ds_write2_b32 v137, v54, v58 offset0:40 offset1:56
	ds_write2_b32 v137, v55, v59 offset0:172 offset1:188
	s_nop 5
	ds_write2_b32 v0, v42, v46 offset0:64 offset1:80
	ds_write2_b32 v0, v43, v47 offset0:196 offset1:212
	ds_write2_b32 v137, v44, v48 offset0:72 offset1:88
	ds_write2_b32 v137, v45, v49 offset0:204 offset1:220
	v_mfma_f32_16x16x32_bf16 v[50:53], v[38:41], v[8:11], 0
	v_add_u32_e32 v146, 64, v138
	v_add_u32_e32 v147, 0x50, v138
	v_add_u32_e32 v148, 0x60, v138
	v_mfma_f32_16x16x32_bf16 v[38:41], v[38:41], v[4:7], 0
	s_nop 7
	ds_write2_b32 v0, v50, v38 offset0:96 offset1:112
	ds_write2_b32 v0, v51, v39 offset0:228 offset1:244
	ds_write2_b32 v137, v52, v40 offset0:104 offset1:120
	ds_write2_b32 v137, v53, v41 offset0:236 offset1:252
	s_waitcnt lgkmcnt(0)
	v_add_u32_e32 v149, 0x70, v138
	v_add_u32_e32 v150, 0x80, v138
	v_add_u32_e32 v151, 0x90, v138
	v_add_u32_e32 v152, 0xa0, v138
	v_add_u32_e32 v153, 0xb0, v138
	v_add_u32_e32 v154, 0xc0, v138
	v_add_u32_e32 v155, 0xd0, v138
	v_add_u32_e32 v156, 0xe0, v138
	v_add_u32_e32 v157, 0xf0, v138
	ds_read2st64_b32 v[134:135], v138 offset0:12 offset1:13
	ds_read2st64_b32 v[132:133], v139 offset0:14 offset1:15
	ds_read2st64_b32 v[130:131], v140 offset0:16 offset1:17
	ds_read2st64_b32 v[128:129], v141 offset0:18 offset1:19
	ds_read2st64_b32 v[124:125], v146 offset0:20 offset1:21
	ds_read2st64_b32 v[120:121], v147 offset0:22 offset1:23
	ds_read2st64_b32 v[116:117], v148 offset0:24 offset1:25
	ds_read2st64_b32 v[112:113], v149 offset0:26 offset1:27
	ds_read2st64_b32 v[108:109], v150 offset0:28 offset1:29
	ds_read2st64_b32 v[102:103], v151 offset0:30 offset1:31
	ds_read2st64_b32 v[98:99], v152 offset0:32 offset1:33
	ds_read2st64_b32 v[94:95], v153 offset0:34 offset1:35
	ds_read2st64_b32 v[88:89], v154 offset0:36 offset1:37
	ds_read2st64_b32 v[82:83], v155 offset0:38 offset1:39
	ds_read2st64_b32 v[76:77], v156 offset0:40 offset1:41
	ds_read2st64_b32 v[70:71], v157 offset0:42 offset1:43
	s_waitcnt lgkmcnt(0)
	v_mov_b32_e32 v37, 0
	v_mov_b32_e32 v38, 0
	v_mov_b32_e32 v39, 0
	s_and_saveexec_b64 s[4:5], vcc
	ds_read_b128 v[36:39], v158 offset:768
	s_or_b64 exec, exec, s[4:5]
	s_waitcnt lgkmcnt(0)
	v_mfma_f32_16x16x32_bf16 v[40:43], v[36:39], v[32:35], 0
	v_mfma_f32_16x16x32_bf16 v[44:47], v[36:39], v[28:31], 0
	s_nop 7
	ds_write2_b32 v0, v40, v44 offset1:16
	ds_write2_b32 v0, v41, v45 offset0:132 offset1:148
	ds_write2_b32 v137, v42, v46 offset0:8 offset1:24
	v_mfma_f32_16x16x32_bf16 v[48:51], v[36:39], v[20:23], 0
	v_mfma_f32_16x16x32_bf16 v[52:55], v[36:39], v[12:15], 0
	ds_write2_b32 v137, v43, v47 offset0:140 offset1:156
	s_nop 6
	ds_write2_b32 v0, v48, v52 offset0:32 offset1:48
	ds_write2_b32 v0, v49, v53 offset0:164 offset1:180
	v_mfma_f32_16x16x32_bf16 v[56:59], v[36:39], v[24:27], 0
	v_mfma_f32_16x16x32_bf16 v[40:43], v[36:39], v[16:19], 0
	ds_write2_b32 v137, v50, v54 offset0:40 offset1:56
	ds_write2_b32 v137, v51, v55 offset0:172 offset1:188
	s_nop 5
	ds_write2_b32 v0, v56, v40 offset0:64 offset1:80
	ds_write2_b32 v0, v57, v41 offset0:196 offset1:212
	ds_write2_b32 v137, v58, v42 offset0:72 offset1:88
	ds_write2_b32 v137, v59, v43 offset0:204 offset1:220
	v_mfma_f32_16x16x32_bf16 v[44:47], v[36:39], v[8:11], 0
	v_mov_b32_e32 v40, 0
	v_mov_b32_e32 v41, 0
	v_mfma_f32_16x16x32_bf16 v[36:39], v[36:39], v[4:7], 0
	s_nop 7
	ds_write2_b32 v0, v44, v36 offset0:96 offset1:112
	ds_write2_b32 v0, v45, v37 offset0:228 offset1:244
	ds_write2_b32 v137, v46, v38 offset0:104 offset1:120
	ds_write2_b32 v137, v47, v39 offset0:236 offset1:252
	s_waitcnt lgkmcnt(0)
	ds_read2st64_b32 v[126:127], v138 offset0:12 offset1:13
	ds_read2st64_b32 v[122:123], v139 offset0:14 offset1:15
	ds_read2st64_b32 v[118:119], v140 offset0:16 offset1:17
	ds_read2st64_b32 v[114:115], v141 offset0:18 offset1:19
	ds_read2st64_b32 v[110:111], v146 offset0:20 offset1:21
	ds_read2st64_b32 v[104:105], v147 offset0:22 offset1:23
	ds_read2st64_b32 v[96:97], v148 offset0:24 offset1:25
	ds_read2st64_b32 v[90:91], v149 offset0:26 offset1:27
	ds_read2st64_b32 v[84:85], v150 offset0:28 offset1:29
	ds_read2st64_b32 v[78:79], v151 offset0:30 offset1:31
	ds_read2st64_b32 v[72:73], v152 offset0:32 offset1:33
	ds_read2st64_b32 v[66:67], v153 offset0:34 offset1:35
	ds_read2st64_b32 v[62:63], v154 offset0:36 offset1:37
	ds_read2st64_b32 v[58:59], v155 offset0:38 offset1:39
	ds_read2st64_b32 v[54:55], v156 offset0:40 offset1:41
	ds_read2st64_b32 v[50:51], v157 offset0:42 offset1:43
	s_waitcnt lgkmcnt(0)
	v_mov_b32_e32 v36, 0
	v_mov_b32_e32 v38, 0
	v_mov_b32_e32 v39, 0
	s_and_saveexec_b64 s[4:5], vcc
	ds_read_b128 v[38:41], v158 offset:1536
	s_or_b64 exec, exec, s[4:5]
	s_waitcnt lgkmcnt(0)
	v_mfma_f32_16x16x32_bf16 v[42:45], v[38:41], v[32:35], 0
	v_mov_b32_e32 v37, 0
	v_mfma_f32_16x16x32_bf16 v[46:49], v[38:41], v[28:31], 0
	s_nop 7
	ds_write2_b32 v0, v42, v46 offset1:16
	ds_write2_b32 v0, v43, v47 offset0:132 offset1:148
	ds_write2_b32 v137, v44, v48 offset0:8 offset1:24
	v_mfma_f32_16x16x32_bf16 v[160:163], v[38:41], v[20:23], 0
	v_mfma_f32_16x16x32_bf16 v[164:167], v[38:41], v[12:15], 0
	ds_write2_b32 v137, v45, v49 offset0:140 offset1:156
	s_nop 6
	ds_write2_b32 v0, v160, v164 offset0:32 offset1:48
	ds_write2_b32 v0, v161, v165 offset0:164 offset1:180
	v_mfma_f32_16x16x32_bf16 v[168:171], v[38:41], v[24:27], 0
	v_mfma_f32_16x16x32_bf16 v[42:45], v[38:41], v[16:19], 0
	ds_write2_b32 v137, v162, v166 offset0:40 offset1:56
	ds_write2_b32 v137, v163, v167 offset0:172 offset1:188
	s_nop 5
	ds_write2_b32 v0, v168, v42 offset0:64 offset1:80
	ds_write2_b32 v0, v169, v43 offset0:196 offset1:212
	ds_write2_b32 v137, v170, v44 offset0:72 offset1:88
	ds_write2_b32 v137, v171, v45 offset0:204 offset1:220
	v_mfma_f32_16x16x32_bf16 v[46:49], v[38:41], v[8:11], 0
	v_mfma_f32_16x16x32_bf16 v[38:41], v[38:41], v[4:7], 0
	s_nop 7
	ds_write2_b32 v0, v46, v38 offset0:96 offset1:112
	ds_write2_b32 v0, v47, v39 offset0:228 offset1:244
	ds_write2_b32 v137, v48, v40 offset0:104 offset1:120
	ds_write2_b32 v137, v49, v41 offset0:236 offset1:252
	s_waitcnt lgkmcnt(0)
	ds_read2st64_b32 v[106:107], v138 offset0:12 offset1:13
	ds_read2st64_b32 v[100:101], v139 offset0:14 offset1:15
	ds_read2st64_b32 v[92:93], v140 offset0:16 offset1:17
	ds_read2st64_b32 v[86:87], v141 offset0:18 offset1:19
	ds_read2st64_b32 v[80:81], v146 offset0:20 offset1:21
	ds_read2st64_b32 v[74:75], v147 offset0:22 offset1:23
	ds_read2st64_b32 v[68:69], v148 offset0:24 offset1:25
	ds_read2st64_b32 v[64:65], v149 offset0:26 offset1:27
	ds_read2st64_b32 v[60:61], v150 offset0:28 offset1:29
	ds_read2st64_b32 v[56:57], v151 offset0:30 offset1:31
	ds_read2st64_b32 v[52:53], v152 offset0:32 offset1:33
	ds_read2st64_b32 v[48:49], v153 offset0:34 offset1:35
	ds_read2st64_b32 v[46:47], v154 offset0:36 offset1:37
	ds_read2st64_b32 v[44:45], v155 offset0:38 offset1:39
	ds_read2st64_b32 v[42:43], v156 offset0:40 offset1:41
	ds_read2st64_b32 v[40:41], v157 offset0:42 offset1:43
	s_waitcnt lgkmcnt(0)
	v_mov_b32_e32 v38, 0
	v_mov_b32_e32 v39, 0
	s_and_saveexec_b64 s[4:5], vcc
	ds_read_b128 v[36:39], v158 offset:2304
	s_or_b64 exec, exec, s[4:5]
	v_mul_f32_e32 v158, 0, v3
	v_fma_f32 v159, 0, v2, v158
	v_add_f32_e32 v135, v159, v135
	v_fma_f32 v158, v2, 0, -v158
	v_mul_f32_e32 v159, v2, v135
	v_add_f32_e32 v134, v158, v134
	v_mul_f32_e32 v135, v3, v135
	v_fmac_f32_e32 v159, v3, v134
	v_fma_f32 v134, v2, v134, -v135
	v_add_f32_e32 v132, v132, v134
	v_add_f32_e32 v133, v133, v159
	v_mul_f32_e32 v134, v3, v132
	v_fmac_f32_e32 v134, v2, v133
	v_mul_f32_e32 v133, v3, v133
	v_fma_f32 v132, v2, v132, -v133
	v_add_f32_e32 v130, v130, v132
	v_add_f32_e32 v131, v131, v134
	v_mul_f32_e32 v132, v3, v130
	v_fmac_f32_e32 v132, v2, v131
	v_mul_f32_e32 v131, v3, v131
	v_fma_f32 v130, v2, v130, -v131
	v_add_f32_e32 v128, v128, v130
	v_add_f32_e32 v129, v129, v132
	v_mul_f32_e32 v130, v3, v128
	v_fmac_f32_e32 v130, v2, v129
	v_mul_f32_e32 v129, v3, v129
	v_fma_f32 v128, v2, v128, -v129
	v_add_f32_e32 v124, v124, v128
	v_add_f32_e32 v125, v125, v130
	v_mul_f32_e32 v128, v3, v124
	v_fmac_f32_e32 v128, v2, v125
	v_mul_f32_e32 v125, v3, v125
	v_fma_f32 v124, v2, v124, -v125
	v_add_f32_e32 v120, v120, v124
	v_add_f32_e32 v121, v121, v128
	v_mul_f32_e32 v124, v3, v120
	v_fmac_f32_e32 v124, v2, v121
	v_mul_f32_e32 v121, v3, v121
	v_fma_f32 v120, v2, v120, -v121
	v_add_f32_e32 v116, v116, v120
	v_add_f32_e32 v117, v117, v124
	v_mul_f32_e32 v120, v3, v116
	v_fmac_f32_e32 v120, v2, v117
	v_mul_f32_e32 v117, v3, v117
	v_fma_f32 v116, v2, v116, -v117
	v_add_f32_e32 v112, v112, v116
	v_add_f32_e32 v113, v113, v120
	v_mul_f32_e32 v116, v3, v112
	v_fmac_f32_e32 v116, v2, v113
	v_mul_f32_e32 v113, v3, v113
	v_fma_f32 v112, v2, v112, -v113
	v_add_f32_e32 v108, v108, v112
	v_add_f32_e32 v109, v109, v116
	v_mul_f32_e32 v112, v3, v108
	v_fmac_f32_e32 v112, v2, v109
	v_mul_f32_e32 v109, v3, v109
	v_fma_f32 v108, v2, v108, -v109
	v_add_f32_e32 v102, v102, v108
	v_add_f32_e32 v103, v103, v112
	v_mul_f32_e32 v108, v3, v102
	v_fmac_f32_e32 v108, v2, v103
	v_mul_f32_e32 v103, v3, v103
	v_fma_f32 v102, v2, v102, -v103
	v_add_f32_e32 v98, v98, v102
	v_add_f32_e32 v99, v99, v108
	v_mul_f32_e32 v102, v3, v98
	v_fmac_f32_e32 v102, v2, v99
	v_mul_f32_e32 v99, v3, v99
	v_fma_f32 v98, v2, v98, -v99
	v_add_f32_e32 v94, v94, v98
	v_add_f32_e32 v95, v95, v102
	v_mul_f32_e32 v98, v3, v94
	v_fmac_f32_e32 v98, v2, v95
	v_mul_f32_e32 v95, v3, v95
	v_fma_f32 v94, v2, v94, -v95
	v_add_f32_e32 v88, v88, v94
	v_add_f32_e32 v89, v89, v98
	v_mul_f32_e32 v94, v3, v88
	v_fmac_f32_e32 v94, v2, v89
	v_mul_f32_e32 v89, v3, v89
	v_fma_f32 v88, v2, v88, -v89
	v_add_f32_e32 v82, v82, v88
	v_add_f32_e32 v83, v83, v94
	v_mul_f32_e32 v88, v3, v82
	v_fmac_f32_e32 v88, v2, v83
	v_mul_f32_e32 v83, v3, v83
	v_fma_f32 v82, v2, v82, -v83
	v_add_f32_e32 v76, v76, v82
	v_add_f32_e32 v77, v77, v88
	v_mul_f32_e32 v82, v3, v76
	v_fmac_f32_e32 v82, v2, v77
	v_mul_f32_e32 v77, v3, v77
	v_fma_f32 v76, v2, v76, -v77
	v_add_f32_e32 v70, v70, v76
	v_add_f32_e32 v71, v71, v82
	v_mul_f32_e32 v76, v3, v70
	v_fmac_f32_e32 v76, v2, v71
	v_mul_f32_e32 v71, v3, v71
	v_add_f32_e32 v76, v76, v127
	v_fma_f32 v70, v2, v70, -v71
	v_mul_f32_e32 v77, v2, v76
	v_add_f32_e32 v70, v70, v126
	v_mul_f32_e32 v76, v3, v76
	v_fmac_f32_e32 v77, v3, v70
	v_fma_f32 v70, v2, v70, -v76
	v_add_f32_e32 v70, v122, v70
	v_add_f32_e32 v71, v123, v77
	v_mul_f32_e32 v76, v3, v70
	v_fmac_f32_e32 v76, v2, v71
	v_mul_f32_e32 v71, v3, v71
	v_fma_f32 v70, v2, v70, -v71
	v_add_f32_e32 v70, v118, v70
	v_add_f32_e32 v76, v119, v76
	v_mul_f32_e32 v71, v3, v70
	v_fmac_f32_e32 v71, v2, v76
	v_mul_f32_e32 v76, v3, v76
	v_fma_f32 v70, v2, v70, -v76
	v_add_f32_e32 v70, v114, v70
	v_add_f32_e32 v71, v115, v71
	v_mul_f32_e32 v76, v3, v70
	v_fmac_f32_e32 v76, v2, v71
	v_mul_f32_e32 v71, v3, v71
	v_fma_f32 v70, v2, v70, -v71
	v_add_f32_e32 v70, v110, v70
	v_add_f32_e32 v76, v111, v76
	v_mul_f32_e32 v71, v3, v70
	v_fmac_f32_e32 v71, v2, v76
	v_mul_f32_e32 v76, v3, v76
	v_fma_f32 v70, v2, v70, -v76
	v_add_f32_e32 v70, v104, v70
	v_add_f32_e32 v71, v105, v71
	v_mul_f32_e32 v76, v3, v70
	v_fmac_f32_e32 v76, v2, v71
	v_mul_f32_e32 v71, v3, v71
	v_fma_f32 v70, v2, v70, -v71
	v_add_f32_e32 v70, v96, v70
	v_add_f32_e32 v76, v97, v76
	v_mul_f32_e32 v71, v3, v70
	v_fmac_f32_e32 v71, v2, v76
	v_mul_f32_e32 v76, v3, v76
	v_fma_f32 v70, v2, v70, -v76
	v_add_f32_e32 v70, v90, v70
	v_add_f32_e32 v71, v91, v71
	v_mul_f32_e32 v76, v3, v70
	v_fmac_f32_e32 v76, v2, v71
	v_mul_f32_e32 v71, v3, v71
	v_fma_f32 v70, v2, v70, -v71
	v_add_f32_e32 v70, v84, v70
	v_add_f32_e32 v76, v85, v76
	v_mul_f32_e32 v71, v3, v70
	v_fmac_f32_e32 v71, v2, v76
	v_mul_f32_e32 v76, v3, v76
	v_fma_f32 v70, v2, v70, -v76
	v_add_f32_e32 v70, v78, v70
	v_add_f32_e32 v71, v79, v71
	v_mul_f32_e32 v76, v3, v70
	v_fmac_f32_e32 v76, v2, v71
	v_mul_f32_e32 v71, v3, v71
	v_fma_f32 v70, v2, v70, -v71
	v_add_f32_e32 v70, v72, v70
	v_add_f32_e32 v73, v73, v76
	v_mul_f32_e32 v71, v3, v70
	v_fmac_f32_e32 v71, v2, v73
	v_add_f32_e32 v67, v67, v71
	v_mul_f32_e32 v71, v3, v73
	v_fma_f32 v70, v2, v70, -v71
	v_add_f32_e32 v66, v66, v70
	v_mul_f32_e32 v70, v3, v66
	v_fmac_f32_e32 v70, v2, v67
	v_mul_f32_e32 v67, v3, v67
	v_fma_f32 v66, v2, v66, -v67
	v_add_f32_e32 v62, v62, v66
	v_add_f32_e32 v63, v63, v70
	v_mul_f32_e32 v66, v3, v62
	v_fmac_f32_e32 v66, v2, v63
	v_mul_f32_e32 v63, v3, v63
	v_fma_f32 v62, v2, v62, -v63
	v_add_f32_e32 v58, v58, v62
	v_add_f32_e32 v59, v59, v66
	v_mul_f32_e32 v62, v3, v58
	v_fmac_f32_e32 v62, v2, v59
	v_mul_f32_e32 v59, v3, v59
	v_fma_f32 v58, v2, v58, -v59
	v_add_f32_e32 v54, v54, v58
	v_add_f32_e32 v55, v55, v62
	v_mul_f32_e32 v58, v3, v54
	v_fmac_f32_e32 v58, v2, v55
	v_mul_f32_e32 v55, v3, v55
	v_fma_f32 v54, v2, v54, -v55
	v_add_f32_e32 v50, v50, v54
	v_add_f32_e32 v51, v51, v58
	v_mul_f32_e32 v54, v3, v50
	v_fmac_f32_e32 v54, v2, v51
	v_mul_f32_e32 v51, v3, v51
	s_waitcnt lgkmcnt(14)
	v_add_f32_e32 v54, v54, v107
	v_fma_f32 v50, v2, v50, -v51
	v_mul_f32_e32 v55, v2, v54
	v_add_f32_e32 v50, v50, v106
	v_mul_f32_e32 v54, v3, v54
	v_fmac_f32_e32 v55, v3, v50
	v_fma_f32 v50, v2, v50, -v54
	v_add_f32_e32 v50, v100, v50
	v_add_f32_e32 v51, v101, v55
	v_mul_f32_e32 v54, v3, v50
	v_fmac_f32_e32 v54, v2, v51
	v_mul_f32_e32 v51, v3, v51
	v_fma_f32 v50, v2, v50, -v51
	s_waitcnt lgkmcnt(13)
	v_add_f32_e32 v50, v92, v50
	v_add_f32_e32 v54, v93, v54
	v_mul_f32_e32 v51, v3, v50
	v_fmac_f32_e32 v51, v2, v54
	v_mul_f32_e32 v54, v3, v54
	v_fma_f32 v50, v2, v50, -v54
	s_waitcnt lgkmcnt(12)
	v_add_f32_e32 v50, v86, v50
	v_add_f32_e32 v51, v87, v51
	v_mul_f32_e32 v54, v3, v50
	v_fmac_f32_e32 v54, v2, v51
	v_mul_f32_e32 v51, v3, v51
	v_fma_f32 v50, v2, v50, -v51
	s_waitcnt lgkmcnt(11)
	v_add_f32_e32 v50, v80, v50
	v_add_f32_e32 v54, v81, v54
	v_mul_f32_e32 v51, v3, v50
	v_fmac_f32_e32 v51, v2, v54
	v_mul_f32_e32 v54, v3, v54
	v_fma_f32 v50, v2, v50, -v54
	s_waitcnt lgkmcnt(10)
	v_add_f32_e32 v50, v74, v50
	v_add_f32_e32 v51, v75, v51
	v_mul_f32_e32 v54, v3, v50
	v_fmac_f32_e32 v54, v2, v51
	v_mul_f32_e32 v51, v3, v51
	v_fma_f32 v50, v2, v50, -v51
	s_waitcnt lgkmcnt(9)
	v_add_f32_e32 v50, v68, v50
	v_add_f32_e32 v54, v69, v54
	v_mul_f32_e32 v51, v3, v50
	v_fmac_f32_e32 v51, v2, v54
	v_mul_f32_e32 v54, v3, v54
	v_fma_f32 v50, v2, v50, -v54
	s_waitcnt lgkmcnt(8)
	v_add_f32_e32 v50, v64, v50
	v_add_f32_e32 v51, v65, v51
	v_mul_f32_e32 v54, v3, v50
	v_fmac_f32_e32 v54, v2, v51
	v_mul_f32_e32 v51, v3, v51
	v_fma_f32 v50, v2, v50, -v51
	s_waitcnt lgkmcnt(7)
	v_add_f32_e32 v50, v60, v50
	v_add_f32_e32 v54, v61, v54
	v_mul_f32_e32 v51, v3, v50
	v_fmac_f32_e32 v51, v2, v54
	v_mul_f32_e32 v54, v3, v54
	v_fma_f32 v50, v2, v50, -v54
	s_waitcnt lgkmcnt(6)
	v_add_f32_e32 v50, v56, v50
	v_add_f32_e32 v51, v57, v51
	v_mul_f32_e32 v54, v3, v50
	v_fmac_f32_e32 v54, v2, v51
	v_mul_f32_e32 v51, v3, v51
	v_fma_f32 v50, v2, v50, -v51
	s_waitcnt lgkmcnt(5)
	v_add_f32_e32 v50, v52, v50
	v_add_f32_e32 v53, v53, v54
	v_mul_f32_e32 v51, v3, v50
	v_fmac_f32_e32 v51, v2, v53
	s_waitcnt lgkmcnt(4)
	v_add_f32_e32 v49, v49, v51
	v_mul_f32_e32 v51, v3, v53
	v_fma_f32 v50, v2, v50, -v51
	v_add_f32_e32 v48, v48, v50
	v_mul_f32_e32 v50, v3, v48
	v_fmac_f32_e32 v50, v2, v49
	v_mul_f32_e32 v49, v3, v49
	v_fma_f32 v48, v2, v48, -v49
	s_waitcnt lgkmcnt(3)
	v_add_f32_e32 v46, v46, v48
	v_add_f32_e32 v47, v47, v50
	v_mul_f32_e32 v48, v3, v46
	v_fmac_f32_e32 v48, v2, v47
	v_mul_f32_e32 v47, v3, v47
	v_fma_f32 v46, v2, v46, -v47
	s_waitcnt lgkmcnt(2)
	v_add_f32_e32 v44, v44, v46
	v_add_f32_e32 v45, v45, v48
	v_mul_f32_e32 v46, v3, v44
	v_fmac_f32_e32 v46, v2, v45
	v_mul_f32_e32 v45, v3, v45
	s_waitcnt lgkmcnt(0)
	v_mfma_f32_16x16x32_bf16 v[32:35], v[36:39], v[32:35], 0
	v_fma_f32 v44, v2, v44, -v45
	v_add_f32_e32 v42, v42, v44
	v_add_f32_e32 v43, v43, v46
	v_mfma_f32_16x16x32_bf16 v[28:31], v[36:39], v[28:31], 0
	v_mul_f32_e32 v44, v3, v42
	v_fmac_f32_e32 v44, v2, v43
	v_mul_f32_e32 v43, v3, v43
	v_mfma_f32_16x16x32_bf16 v[20:23], v[36:39], v[20:23], 0
	v_add_f32_e32 v41, v41, v44
	v_fma_f32 v42, v2, v42, -v43
	s_nop 1
	ds_write2_b32 v0, v32, v28 offset1:16
	ds_write2_b32 v0, v33, v29 offset0:132 offset1:148
	ds_write2_b32 v137, v34, v30 offset0:8 offset1:24
	v_mfma_f32_16x16x32_bf16 v[12:15], v[36:39], v[12:15], 0
	ds_write2_b32 v137, v35, v31 offset0:140 offset1:156
	s_nop 6
	ds_write2_b32 v0, v20, v12 offset0:32 offset1:48
	ds_write2_b32 v0, v21, v13 offset0:164 offset1:180
	v_mfma_f32_16x16x32_bf16 v[24:27], v[36:39], v[24:27], 0
	v_add_f32_e32 v40, v40, v42
	s_lshl_b32 s11, s10, 1
	s_mul_i32 s1, s10, 0x88
	v_mfma_f32_16x16x32_bf16 v[16:19], v[36:39], v[16:19], 0
	ds_write2_b32 v137, v22, v14 offset0:40 offset1:56
	ds_write2_b32 v137, v23, v15 offset0:172 offset1:188
	s_nop 5
	ds_write2_b32 v0, v24, v16 offset0:64 offset1:80
	ds_write2_b32 v0, v25, v17 offset0:196 offset1:212
	ds_write2_b32 v137, v26, v18 offset0:72 offset1:88
	ds_write2_b32 v137, v27, v19 offset0:204 offset1:220
	v_mfma_f32_16x16x32_bf16 v[8:11], v[36:39], v[8:11], 0
	s_ashr_i32 s10, s9, 31
	s_mul_hi_i32 s5, s11, 0x44
	s_add_u32 s4, s1, s9
	v_mfma_f32_16x16x32_bf16 v[4:7], v[36:39], v[4:7], 0
	s_nop 7
	ds_write2_b32 v0, v8, v4 offset0:96 offset1:112
	ds_write2_b32 v0, v9, v5 offset0:228 offset1:244
	ds_write2_b32 v137, v10, v6 offset0:104 offset1:120
	ds_write2_b32 v137, v11, v7 offset0:236 offset1:252
	s_waitcnt lgkmcnt(0)
	v_mul_f32_e32 v0, v3, v41
	ds_read2st64_b32 v[4:5], v138 offset0:12 offset1:13
	ds_read2st64_b32 v[6:7], v139 offset0:14 offset1:15
	ds_read2st64_b32 v[8:9], v140 offset0:16 offset1:17
	ds_read2st64_b32 v[10:11], v141 offset0:18 offset1:19
	ds_read2st64_b32 v[12:13], v146 offset0:20 offset1:21
	ds_read2st64_b32 v[14:15], v147 offset0:22 offset1:23
	ds_read2st64_b32 v[16:17], v148 offset0:24 offset1:25
	ds_read2st64_b32 v[18:19], v149 offset0:26 offset1:27
	ds_read2st64_b32 v[20:21], v150 offset0:28 offset1:29
	ds_read2st64_b32 v[22:23], v151 offset0:30 offset1:31
	ds_read2st64_b32 v[24:25], v152 offset0:32 offset1:33
	ds_read2st64_b32 v[26:27], v153 offset0:34 offset1:35
	ds_read2st64_b32 v[28:29], v154 offset0:36 offset1:37
	ds_read2st64_b32 v[30:31], v155 offset0:38 offset1:39
	ds_read2st64_b32 v[32:33], v156 offset0:40 offset1:41
	ds_read2st64_b32 v[34:35], v157 offset0:42 offset1:43
	v_fma_f32 v0, v2, v40, -v0
	s_waitcnt lgkmcnt(14)
	v_add_f32_e32 v0, v0, v4
	v_mul_f32_e32 v4, v3, v40
	v_fmac_f32_e32 v4, v2, v41
	v_add_f32_e32 v4, v4, v5
	v_mul_f32_e32 v5, v3, v4
	v_mul_f32_e32 v4, v2, v4
	v_fmac_f32_e32 v4, v3, v0
	v_fma_f32 v5, v2, v0, -v5
	v_add_f32_e32 v0, v7, v4
	v_add_f32_e32 v5, v6, v5
	v_mul_f32_e32 v4, v3, v0
	v_fma_f32 v4, v2, v5, -v4
	v_mul_f32_e32 v5, v3, v5
	v_fmac_f32_e32 v5, v2, v0
	s_waitcnt lgkmcnt(13)
	v_add_f32_e32 v0, v9, v5
	v_add_f32_e32 v4, v8, v4
	v_mul_f32_e32 v5, v3, v0
	v_fma_f32 v5, v2, v4, -v5
	v_mul_f32_e32 v4, v3, v4
	v_fmac_f32_e32 v4, v2, v0
	s_waitcnt lgkmcnt(12)
	v_add_f32_e32 v0, v11, v4
	v_add_f32_e32 v5, v10, v5
	v_mul_f32_e32 v4, v3, v0
	v_fma_f32 v4, v2, v5, -v4
	v_mul_f32_e32 v5, v3, v5
	v_fmac_f32_e32 v5, v2, v0
	s_waitcnt lgkmcnt(11)
	v_add_f32_e32 v0, v13, v5
	v_add_f32_e32 v4, v12, v4
	v_mul_f32_e32 v5, v3, v0
	v_fma_f32 v5, v2, v4, -v5
	v_mul_f32_e32 v4, v3, v4
	v_fmac_f32_e32 v4, v2, v0
	s_waitcnt lgkmcnt(10)
	v_add_f32_e32 v0, v15, v4
	v_add_f32_e32 v5, v14, v5
	v_mul_f32_e32 v4, v3, v0
	v_fma_f32 v4, v2, v5, -v4
	v_mul_f32_e32 v5, v3, v5
	v_fmac_f32_e32 v5, v2, v0
	s_waitcnt lgkmcnt(9)
	v_add_f32_e32 v0, v17, v5
	v_add_f32_e32 v4, v16, v4
	v_mul_f32_e32 v5, v3, v0
	v_fma_f32 v5, v2, v4, -v5
	v_mul_f32_e32 v4, v3, v4
	v_fmac_f32_e32 v4, v2, v0
	s_waitcnt lgkmcnt(8)
	v_add_f32_e32 v0, v19, v4
	v_add_f32_e32 v5, v18, v5
	v_mul_f32_e32 v4, v3, v0
	v_fma_f32 v4, v2, v5, -v4
	v_mul_f32_e32 v5, v3, v5
	v_fmac_f32_e32 v5, v2, v0
	s_waitcnt lgkmcnt(7)
	v_add_f32_e32 v0, v21, v5
	v_add_f32_e32 v4, v20, v4
	v_mul_f32_e32 v5, v3, v0
	v_fma_f32 v5, v2, v4, -v5
	v_mul_f32_e32 v4, v3, v4
	v_fmac_f32_e32 v4, v2, v0
	s_waitcnt lgkmcnt(6)
	v_add_f32_e32 v0, v23, v4
	v_add_f32_e32 v5, v22, v5
	v_mul_f32_e32 v4, v3, v0
	v_fma_f32 v4, v2, v5, -v4
	v_mul_f32_e32 v5, v3, v5
	v_fmac_f32_e32 v5, v2, v0
	s_waitcnt lgkmcnt(5)
	v_add_f32_e32 v0, v25, v5
	v_add_f32_e32 v4, v24, v4
	v_mul_f32_e32 v5, v3, v0
	v_fma_f32 v5, v2, v4, -v5
	v_mul_f32_e32 v4, v3, v4
	v_fmac_f32_e32 v4, v2, v0
	s_waitcnt lgkmcnt(4)
	v_add_f32_e32 v0, v27, v4
	v_add_f32_e32 v5, v26, v5
	v_mul_f32_e32 v4, v3, v0
	v_fma_f32 v4, v2, v5, -v4
	v_mul_f32_e32 v5, v3, v5
	v_fmac_f32_e32 v5, v2, v0
	s_waitcnt lgkmcnt(3)
	v_add_f32_e32 v0, v29, v5
	v_add_f32_e32 v4, v28, v4
	v_mul_f32_e32 v5, v3, v0
	v_fma_f32 v5, v2, v4, -v5
	v_mul_f32_e32 v4, v3, v4
	v_fmac_f32_e32 v4, v2, v0
	s_waitcnt lgkmcnt(2)
	v_add_f32_e32 v0, v31, v4
	v_add_f32_e32 v5, v30, v5
	v_mul_f32_e32 v4, v3, v0
	v_fma_f32 v4, v2, v5, -v4
	s_waitcnt lgkmcnt(1)
	v_add_f32_e32 v6, v32, v4
	v_mul_f32_e32 v4, v3, v5
	v_fmac_f32_e32 v4, v2, v0
	v_add_f32_e32 v0, v33, v4
	v_mul_f32_e32 v4, v3, v0
	v_mul_f32_e32 v3, v3, v6
	v_fmac_f32_e32 v3, v2, v0
	s_waitcnt lgkmcnt(0)
	v_mov_b32_e32 v0, s59
	v_fma_f32 v4, v2, v6, -v4
	s_waitcnt lgkmcnt(0)
	v_add_f32_e32 v5, v35, v3
	ds_read_b64 v[2:3], v0
	s_addc_u32 s5, s5, s10
	s_ashr_i32 s1, s0, 31
	s_lshl_b64 s[22:23], s[4:5], 10
	s_lshl_b64 s[4:5], s[0:1], 6
	s_add_u32 s1, s22, s4
	s_addc_u32 s17, s23, s5
	v_or_b32_e32 v6, s1, v136
	v_mov_b32_e32 v7, s17
	s_waitcnt lgkmcnt(0)
	v_readfirstlane_b32 s1, v3
	v_readfirstlane_b32 s17, v2
	v_add_f32_e32 v4, v34, v4
	v_mov_b32_e32 v3, s1
	v_mov_b32_e32 v2, s17
	v_lshl_add_u64 v[2:3], v[6:7], 3, v[2:3]
	s_mov_b32 s1, 0xc00000
	v_add_co_u32_e32 v2, vcc, s1, v2
	v_mov_b32_e32 v42, v204
	s_nop 0
	v_addc_co_u32_e32 v3, vcc, 0, v3, vcc
	global_store_dwordx2 v[2:3], v[4:5], off
	ds_read_b64 v[2:3], v0
	v_readfirstlane_b32 s1, v42
	s_lshr_b32 s1, s1, 6
	s_mulk_i32 s1, 0x3e00
	s_add_i32 s17, s1, 0
	v_readlane_b32 s1, v244, 25
	v_and_b32_e32 v136, 63, v42
	s_add_i32 s0, s0, s1
	s_waitcnt lgkmcnt(0)
	v_readfirstlane_b32 s22, v2
	v_lshl_or_b32 v2, s0, 6, v136
	v_readfirstlane_b32 s23, v3
	v_ashrrev_i32_e32 v3, 31, v2
	s_mov_b32 s1, 0x200000
	v_lshl_add_u64 v[2:3], v[2:3], 4, s[22:23]
	v_add_co_u32_e32 v2, vcc, s1, v2
	s_ashr_i32 s1, s0, 31
	s_lshl_b64 s[0:1], s[0:1], 13
	s_add_u32 s0, s22, s0
	v_and_b32_e32 v37, 15, v42
	s_addc_u32 s1, s23, s1
	v_and_b32_e32 v0, 48, v42
	v_lshl_add_u64 v[4:5], s[0:1], 0, v[0:1]
	v_lshlrev_b32_e32 v6, 6, v37
	v_mov_b32_e32 v7, v1
	v_lshl_add_u64 v[6:7], v[4:5], 0, v[6:7]
	s_mov_b64 s[0:1], 0x240000
	v_addc_co_u32_e32 v3, vcc, 0, v3, vcc
	v_lshl_add_u64 v[8:9], v[6:7], 0, s[0:1]
	s_mov_b32 s0, 0x240000
	v_add_co_u32_e32 v10, vcc, s0, v6
	global_load_dwordx4 v[2:5], v[2:3], off
	s_nop 0
	global_load_dwordx4 v[28:31], v[8:9], off offset:1024
	global_load_dwordx4 v[24:27], v[8:9], off offset:2048
	global_load_dwordx4 v[16:19], v[8:9], off offset:3072
	v_addc_co_u32_e32 v11, vcc, 0, v7, vcc
	s_waitcnt vmcnt(0) lgkmcnt(0)
	v_add_co_u32_e32 v4, vcc, 0x241000, v6
	v_mul_u32_u24_e32 v38, 48, v37
	s_nop 0
	v_addc_co_u32_e32 v5, vcc, 0, v7, vcc
	global_load_dwordx4 v[32:35], v[10:11], off
	global_load_dwordx4 v[20:23], v[4:5], off
	global_load_dwordx4 v[12:15], v[4:5], off offset:1024
	s_nop 0
	global_load_dwordx4 v[8:11], v[4:5], off offset:2048
	s_nop 0
	global_load_dwordx4 v[4:7], v[4:5], off offset:3072
	v_cmp_gt_u32_e32 vcc, 32, v136
	v_mov_b32_e32 v36, 0
	v_add3_u32 v159, s17, v38, v0
	v_mov_b32_e32 v38, 0
	v_mov_b32_e32 v39, 0
	v_mov_b32_e32 v40, 0
	v_mov_b32_e32 v41, 0
	s_and_saveexec_b64 s[0:1], vcc
	ds_read_b128 v[38:41], v159 offset:2304
	s_or_b64 exec, exec, s[0:1]
	s_waitcnt vmcnt(0) lgkmcnt(0)
	v_mfma_f32_16x16x32_bf16 v[44:47], v[38:41], v[32:35], 0
	v_bfe_u32 v43, v42, 4, 2
	v_lshlrev_b32_e32 v37, 2, v37
	v_mul_u32_u24_e32 v43, 0x840, v43
	v_mfma_f32_16x16x32_bf16 v[48:51], v[38:41], v[28:31], 0
	v_add3_u32 v37, s17, v37, v43
	v_add_u32_e32 v137, 0xc00, v37
	v_add_u32_e32 v138, 0x1000, v37
	v_mfma_f32_16x16x32_bf16 v[52:55], v[38:41], v[24:27], 0
	v_lshl_add_u32 v139, v136, 2, s17
	s_nop 2
	ds_write2_b32 v137, v44, v48 offset1:16
	ds_write2_b32 v137, v45, v49 offset0:132 offset1:148
	v_mfma_f32_16x16x32_bf16 v[56:59], v[38:41], v[16:19], 0
	ds_write2_b32 v138, v46, v50 offset0:8 offset1:24
	ds_write2_b32 v138, v47, v51 offset0:140 offset1:156
	s_nop 5
	ds_write2_b32 v137, v52, v56 offset0:32 offset1:48
	ds_write2_b32 v137, v53, v57 offset0:164 offset1:180
	v_mfma_f32_16x16x32_bf16 v[60:63], v[38:41], v[20:23], 0
	v_add_u32_e32 v140, 0xf0, v139
	v_add_u32_e32 v141, 0xe0, v139
	v_add_u32_e32 v146, 0xd0, v139
	v_mfma_f32_16x16x32_bf16 v[44:47], v[38:41], v[12:15], 0
	ds_write2_b32 v138, v54, v58 offset0:40 offset1:56
	ds_write2_b32 v138, v55, v59 offset0:172 offset1:188
	s_nop 5
	ds_write2_b32 v137, v60, v44 offset0:64 offset1:80
	ds_write2_b32 v137, v61, v45 offset0:196 offset1:212
	ds_write2_b32 v138, v62, v46 offset0:72 offset1:88
	ds_write2_b32 v138, v63, v47 offset0:204 offset1:220
	v_mfma_f32_16x16x32_bf16 v[48:51], v[38:41], v[8:11], 0
	v_add_u32_e32 v147, 0xc0, v139
	v_add_u32_e32 v148, 0xb0, v139
	v_add_u32_e32 v149, 0xa0, v139
	v_mfma_f32_16x16x32_bf16 v[38:41], v[38:41], v[4:7], 0
	s_nop 7
	ds_write2_b32 v137, v48, v38 offset0:96 offset1:112
	ds_write2_b32 v137, v49, v39 offset0:228 offset1:244
	ds_write2_b32 v138, v50, v40 offset0:104 offset1:120
	ds_write2_b32 v138, v51, v41 offset0:236 offset1:252
	s_waitcnt lgkmcnt(0)
	v_add_u32_e32 v150, 0x90, v139
	v_add_u32_e32 v151, 0x80, v139
	v_add_u32_e32 v152, 0x70, v139
	v_add_u32_e32 v153, 0x60, v139
	v_add_u32_e32 v154, 0x50, v139
	v_add_u32_e32 v155, 64, v139
	v_add_u32_e32 v156, 48, v139
	v_add_u32_e32 v157, 32, v139
	v_add_u32_e32 v158, 16, v139
	ds_read2st64_b32 v[134:135], v140 offset0:42 offset1:43
	ds_read2st64_b32 v[132:133], v141 offset0:40 offset1:41
	ds_read2st64_b32 v[130:131], v146 offset0:38 offset1:39
	ds_read2st64_b32 v[126:127], v147 offset0:36 offset1:37
	ds_read2st64_b32 v[122:123], v148 offset0:34 offset1:35
	ds_read2st64_b32 v[118:119], v149 offset0:32 offset1:33
	ds_read2st64_b32 v[116:117], v150 offset0:30 offset1:31
	ds_read2st64_b32 v[112:113], v151 offset0:28 offset1:29
	ds_read2st64_b32 v[108:109], v152 offset0:26 offset1:27
	ds_read2st64_b32 v[102:103], v153 offset0:24 offset1:25
	ds_read2st64_b32 v[96:97], v154 offset0:22 offset1:23
	ds_read2st64_b32 v[90:91], v155 offset0:20 offset1:21
	ds_read2st64_b32 v[86:87], v156 offset0:18 offset1:19
	ds_read2st64_b32 v[82:83], v157 offset0:16 offset1:17
	ds_read2st64_b32 v[76:77], v158 offset0:14 offset1:15
	ds_read2st64_b32 v[70:71], v139 offset0:12 offset1:13
	s_waitcnt lgkmcnt(0)
	v_mov_b32_e32 v37, 0
	v_mov_b32_e32 v38, 0
	v_mov_b32_e32 v39, 0
	s_and_saveexec_b64 s[0:1], vcc
	v_or_b32_e32 v36, 0xfffff0, v42
	v_mul_i32_i24_e32 v36, 48, v36
	v_add3_u32 v0, s17, v36, v0
	ds_read_b128 v[36:39], v0 offset:2304
	s_or_b64 exec, exec, s[0:1]
	s_waitcnt lgkmcnt(0)
	v_mfma_f32_16x16x32_bf16 v[40:43], v[36:39], v[32:35], 0
	v_mfma_f32_16x16x32_bf16 v[44:47], v[36:39], v[28:31], 0
	s_nop 7
	ds_write2_b32 v137, v40, v44 offset1:16
	ds_write2_b32 v137, v41, v45 offset0:132 offset1:148
	ds_write2_b32 v138, v42, v46 offset0:8 offset1:24
	v_mfma_f32_16x16x32_bf16 v[48:51], v[36:39], v[24:27], 0
	v_mfma_f32_16x16x32_bf16 v[52:55], v[36:39], v[16:19], 0
	ds_write2_b32 v138, v43, v47 offset0:140 offset1:156
	s_nop 6
	ds_write2_b32 v137, v48, v52 offset0:32 offset1:48
	ds_write2_b32 v137, v49, v53 offset0:164 offset1:180
	v_mfma_f32_16x16x32_bf16 v[56:59], v[36:39], v[20:23], 0
	v_mfma_f32_16x16x32_bf16 v[40:43], v[36:39], v[12:15], 0
	ds_write2_b32 v138, v50, v54 offset0:40 offset1:56
	ds_write2_b32 v138, v51, v55 offset0:172 offset1:188
	s_nop 5
	ds_write2_b32 v137, v56, v40 offset0:64 offset1:80
	ds_write2_b32 v137, v57, v41 offset0:196 offset1:212
	ds_write2_b32 v138, v58, v42 offset0:72 offset1:88
	ds_write2_b32 v138, v59, v43 offset0:204 offset1:220
	v_mfma_f32_16x16x32_bf16 v[44:47], v[36:39], v[8:11], 0
	v_mov_b32_e32 v40, 0
	v_mov_b32_e32 v41, 0
	v_mfma_f32_16x16x32_bf16 v[36:39], v[36:39], v[4:7], 0
	s_nop 7
	ds_write2_b32 v137, v44, v36 offset0:96 offset1:112
	ds_write2_b32 v137, v45, v37 offset0:228 offset1:244
	ds_write2_b32 v138, v46, v38 offset0:104 offset1:120
	ds_write2_b32 v138, v47, v39 offset0:236 offset1:252
	s_waitcnt lgkmcnt(0)
	ds_read2st64_b32 v[128:129], v140 offset0:42 offset1:43
	ds_read2st64_b32 v[124:125], v141 offset0:40 offset1:41
	ds_read2st64_b32 v[120:121], v146 offset0:38 offset1:39
	ds_read2st64_b32 v[114:115], v147 offset0:36 offset1:37
	ds_read2st64_b32 v[110:111], v148 offset0:34 offset1:35
	ds_read2st64_b32 v[104:105], v149 offset0:32 offset1:33
	ds_read2st64_b32 v[98:99], v150 offset0:30 offset1:31
	ds_read2st64_b32 v[92:93], v151 offset0:28 offset1:29
	ds_read2st64_b32 v[84:85], v152 offset0:26 offset1:27
	ds_read2st64_b32 v[78:79], v153 offset0:24 offset1:25
	ds_read2st64_b32 v[72:73], v154 offset0:22 offset1:23
	ds_read2st64_b32 v[66:67], v155 offset0:20 offset1:21
	ds_read2st64_b32 v[62:63], v156 offset0:18 offset1:19
	ds_read2st64_b32 v[58:59], v157 offset0:16 offset1:17
	ds_read2st64_b32 v[54:55], v158 offset0:14 offset1:15
	ds_read2st64_b32 v[50:51], v139 offset0:12 offset1:13
	s_waitcnt lgkmcnt(0)
	v_mov_b32_e32 v36, 0
	v_mov_b32_e32 v38, 0
	v_mov_b32_e32 v39, 0
	s_and_saveexec_b64 s[0:1], vcc
	ds_read_b128 v[38:41], v159 offset:768
	s_or_b64 exec, exec, s[0:1]
	s_waitcnt lgkmcnt(0)
	v_mfma_f32_16x16x32_bf16 v[42:45], v[38:41], v[32:35], 0
	v_mov_b32_e32 v37, 0
	v_mfma_f32_16x16x32_bf16 v[46:49], v[38:41], v[28:31], 0
	s_nop 7
	ds_write2_b32 v137, v42, v46 offset1:16
	ds_write2_b32 v137, v43, v47 offset0:132 offset1:148
	ds_write2_b32 v138, v44, v48 offset0:8 offset1:24
	v_mfma_f32_16x16x32_bf16 v[160:163], v[38:41], v[24:27], 0
	v_mfma_f32_16x16x32_bf16 v[164:167], v[38:41], v[16:19], 0
	ds_write2_b32 v138, v45, v49 offset0:140 offset1:156
	s_nop 6
	ds_write2_b32 v137, v160, v164 offset0:32 offset1:48
	ds_write2_b32 v137, v161, v165 offset0:164 offset1:180
	v_mfma_f32_16x16x32_bf16 v[168:171], v[38:41], v[20:23], 0
	v_mfma_f32_16x16x32_bf16 v[42:45], v[38:41], v[12:15], 0
	ds_write2_b32 v138, v162, v166 offset0:40 offset1:56
	ds_write2_b32 v138, v163, v167 offset0:172 offset1:188
	s_nop 5
	ds_write2_b32 v137, v168, v42 offset0:64 offset1:80
	ds_write2_b32 v137, v169, v43 offset0:196 offset1:212
	ds_write2_b32 v138, v170, v44 offset0:72 offset1:88
	ds_write2_b32 v138, v171, v45 offset0:204 offset1:220
	v_mfma_f32_16x16x32_bf16 v[46:49], v[38:41], v[8:11], 0
	v_mfma_f32_16x16x32_bf16 v[38:41], v[38:41], v[4:7], 0
	s_nop 7
	ds_write2_b32 v137, v46, v38 offset0:96 offset1:112
	ds_write2_b32 v137, v47, v39 offset0:228 offset1:244
	ds_write2_b32 v138, v48, v40 offset0:104 offset1:120
	ds_write2_b32 v138, v49, v41 offset0:236 offset1:252
	s_waitcnt lgkmcnt(0)
	ds_read2st64_b32 v[106:107], v140 offset0:42 offset1:43
	ds_read2st64_b32 v[100:101], v141 offset0:40 offset1:41
	ds_read2st64_b32 v[94:95], v146 offset0:38 offset1:39
	ds_read2st64_b32 v[88:89], v147 offset0:36 offset1:37
	ds_read2st64_b32 v[80:81], v148 offset0:34 offset1:35
	ds_read2st64_b32 v[74:75], v149 offset0:32 offset1:33
	ds_read2st64_b32 v[68:69], v150 offset0:30 offset1:31
	ds_read2st64_b32 v[64:65], v151 offset0:28 offset1:29
	ds_read2st64_b32 v[60:61], v152 offset0:26 offset1:27
	ds_read2st64_b32 v[56:57], v153 offset0:24 offset1:25
	ds_read2st64_b32 v[52:53], v154 offset0:22 offset1:23
	ds_read2st64_b32 v[48:49], v155 offset0:20 offset1:21
	ds_read2st64_b32 v[46:47], v156 offset0:18 offset1:19
	ds_read2st64_b32 v[44:45], v157 offset0:16 offset1:17
	ds_read2st64_b32 v[42:43], v158 offset0:14 offset1:15
	ds_read2st64_b32 v[40:41], v139 offset0:12 offset1:13
	s_waitcnt lgkmcnt(0)
	v_mov_b32_e32 v38, 0
	v_mov_b32_e32 v39, 0
	s_and_saveexec_b64 s[0:1], vcc
	s_cbranch_execz .LBB0_594
	ds_read_b128 v[36:39], v159
	s_branch .LBB0_594

.LBB0_626:
	v_mov_b32_e32 v6, v204
	s_mov_b32 s23, s53
	s_lshl_b32 s23, s23, 3
	v_readfirstlane_b32 s6, v6
	s_ashr_i32 s6, s6, 6
	s_add_i32 s6, s23, s6
	s_cmp_ge_i32 s6, s25
	s_cbranch_scc1 .LBB0_633
	v_readlane_b32 s28, v244, 33
	v_readlane_b32 s29, v244, 34
	s_lshl_b64 s[28:29], s[28:29], 2
	s_add_u32 s28, s22, s28
	v_readlane_b32 s22, v244, 35
	v_readlane_b32 s23, v244, 36
	s_addc_u32 s29, s7, s29
	s_lshl_b64 s[22:23], s[22:23], 2
	s_add_u32 s7, s11, s22
	s_addc_u32 s23, s10, s23
	s_add_u32 s22, s7, 0x100000
	s_addc_u32 s23, s23, 0
	s_add_i32 s78, s6, 0xffff8000
	s_ashr_i32 s7, s6, 31
	s_cmp_lt_i32 s6, 0x8000
	s_cselect_b32 s37, s7, 0
	s_cselect_b32 s36, s6, s78
	s_cselect_b32 s27, s17, s5
	s_cselect_b32 s35, s20, s4
	s_lshl_b64 s[36:37], s[36:37], 12
	v_lshlrev_b32_e32 v0, 2, v6
	s_add_u32 s36, s35, s36
	v_and_b32_e32 v54, 0xfc, v0
	s_addc_u32 s37, s27, s37
	v_lshlrev_b32_e32 v0, 2, v54
	v_lshl_add_u64 v[2:3], s[36:37], 0, v[0:1]
	global_load_dwordx4 v[30:33], v[2:3], off
	global_load_dwordx4 v[22:25], v[2:3], off offset:1024
	global_load_dwordx4 v[10:13], v[2:3], off offset:2048
	s_nop 0
	global_load_dwordx4 v[2:5], v[2:3], off offset:3072
	s_cmp_lg_u64 s[8:9], 0
	s_cselect_b64 s[36:37], -1, 0
	v_lshl_add_u64 v[56:57], s[8:9], 0, v[0:1]
	s_lshl_b64 s[8:9], s[6:7], 11
	v_lshl_add_u64 v[58:59], s[28:29], 0, v[0:1]
	v_and_b32_e32 v0, 63, v6
	s_add_u32 s8, s11, s8
	v_lshlrev_b32_e32 v0, 3, v0
	s_addc_u32 s9, s10, s9
	v_lshl_add_u64 v[6:7], s[8:9], 0, v[0:1]
	s_mov_b64 s[8:9], 0x8800000
	v_or_b32_e32 v8, 0x100, v54
	v_or_b32_e32 v14, 0x200, v54
	v_or_b32_e32 v16, 0x300, v54
	v_lshl_add_u64 v[60:61], v[6:7], 0, s[8:9]
	s_add_i32 s27, s6, s60
	v_mov_b32_e32 v6, 0
	s_ashr_i32 s28, s27, 31
	s_xor_b64 s[6:7], s[36:37], -1
	v_lshlrev_b32_e32 v62, 2, v8
	v_lshlrev_b32_e32 v64, 2, v14
	v_lshlrev_b32_e32 v66, 2, v16
	v_mov_b32_e32 v7, v6
	v_mov_b32_e32 v8, v6
	v_mov_b32_e32 v9, v6
	v_mov_b32_e32 v14, v6
	v_mov_b32_e32 v15, v6
	v_mov_b32_e32 v16, v6
	v_mov_b32_e32 v17, v6
	v_mov_b32_e32 v18, v6
	v_mov_b32_e32 v19, v6
	v_mov_b32_e32 v20, v6
	v_mov_b32_e32 v21, v6
	v_mov_b32_e32 v26, v6
	v_mov_b32_e32 v27, v6
	v_mov_b32_e32 v28, v6
	v_mov_b32_e32 v29, v6
	s_branch .LBB0_629
.LBB0_628:
	s_min_i32 s10, s35, 0x8000
	s_ashr_i32 s10, s10, 12
	s_mul_hi_i32 s11, s10, 0x6000
	s_mulk_i32 s10, 0x6000
	s_add_u32 s35, s22, s10
	s_addc_u32 s37, s23, s11
	s_add_u32 s10, s35, 0x4000
	s_addc_u32 s11, s37, 0
	s_add_u32 s36, s35, 0x3000
	v_lshl_add_u64 v[38:39], s[10:11], 0, v[0:1]
	s_addc_u32 s37, s37, 0
	global_load_dwordx4 v[34:37], v[58:59], off
	v_lshl_add_u64 v[42:43], s[36:37], 0, v[0:1]
	global_load_dwordx4 v[38:41], v[38:39], off
	s_waitcnt vmcnt(0) lgkmcnt(0)
	v_mul_f32_e32 v0, v31, v31
	global_load_dwordx4 v[42:45], v[42:43], off
	v_mul_f32_e32 v46, v33, v33
	v_mul_f32_e32 v47, v23, v23
	v_mul_f32_e32 v48, v25, v25
	v_mul_f32_e32 v49, v11, v11
	v_mul_f32_e32 v50, v13, v13
	v_fmac_f32_e32 v0, v30, v30
	v_fmac_f32_e32 v46, v32, v32
	v_fmac_f32_e32 v47, v22, v22
	v_fmac_f32_e32 v48, v24, v24
	v_mul_f32_e32 v51, v3, v3
	v_mul_f32_e32 v52, v5, v5
	v_fmac_f32_e32 v49, v10, v10
	v_fmac_f32_e32 v50, v12, v12
	v_add_f32_e32 v0, v0, v46
	v_add_f32_e32 v46, v47, v48
	v_fmac_f32_e32 v51, v2, v2
	v_fmac_f32_e32 v52, v4, v4
	v_add_f32_e32 v47, v49, v50
	v_add_f32_e32 v0, v0, v46
	v_add_f32_e32 v48, v51, v52
	v_add_f32_e32 v0, v47, v0
	v_add_f32_e32 v0, v48, v0
	ds_bpermute_b32 v46, v205, v0
	v_mov_b32_e32 v63, v1
	v_mov_b32_e32 v65, v1
	v_mov_b32_e32 v67, v1
	s_add_u32 s27, s27, s60
	s_waitcnt lgkmcnt(0)
	v_add_f32_e32 v0, v0, v46
	ds_bpermute_b32 v46, v206, v0
	s_mov_b32 s78, s29
	s_addc_u32 s28, s28, s61
	s_and_b64 vcc, exec, s[8:9]
	s_waitcnt lgkmcnt(0)
	v_add_f32_e32 v0, v0, v46
	ds_bpermute_b32 v46, v207, v0
	s_waitcnt lgkmcnt(0)
	v_add_f32_e32 v0, v0, v46
	ds_bpermute_b32 v46, v208, v0
	s_waitcnt lgkmcnt(0)
	v_add_f32_e32 v0, v0, v46
	ds_bpermute_b32 v46, v209, v0
	s_waitcnt lgkmcnt(0)
	v_add_f32_e32 v0, v0, v46
	ds_bpermute_b32 v46, v215, v0
	s_waitcnt lgkmcnt(0)
	v_add_f32_e32 v0, v0, v46
	v_fmamk_f32 v0, v0, 0x3a800000, v210
	v_rsq_f32_e32 v0, v0
	s_nop 0
	v_mul_f32_e32 v33, v33, v0
	v_mul_f32_e32 v32, v32, v0
	v_mul_f32_e32 v31, v31, v0
	v_mul_f32_e32 v30, v30, v0
	v_mul_f32_e32 v25, v25, v0
	v_mul_f32_e32 v24, v24, v0
	v_mul_f32_e32 v23, v23, v0
	v_mul_f32_e32 v22, v22, v0
	v_mul_f32_e32 v13, v13, v0
	v_mul_f32_e32 v12, v12, v0
	v_mul_f32_e32 v11, v11, v0
	v_mul_f32_e32 v10, v10, v0
	v_mul_f32_e32 v30, v34, v30
	v_mul_f32_e32 v31, v35, v31
	v_mul_f32_e32 v32, v36, v32
	v_mul_f32_e32 v33, v37, v33
	v_add_f32_e32 v34, 1.0, v38
	v_add_f32_e32 v35, 1.0, v39
	v_add_f32_e32 v36, 1.0, v40
	v_add_f32_e32 v37, 1.0, v41
	s_waitcnt vmcnt(0)
	v_fma_f32 v33, v37, v33, v45
	v_fma_f32 v32, v36, v32, v44
	v_fma_f32 v31, v35, v31, v43
	v_fmac_f32_e32 v42, v34, v30
	v_cvt_pk_bf16_f32 v30, v42, v31
	v_cvt_pk_bf16_f32 v31, v32, v33
	global_store_dwordx2 v[60:61], v[30:31], off
	v_lshl_add_u64 v[34:35], s[10:11], 0, v[62:63]
	global_load_dwordx4 v[30:33], v[58:59], off offset:1024
	v_lshl_add_u64 v[38:39], s[36:37], 0, v[62:63]
	global_load_dwordx4 v[34:37], v[34:35], off
	v_mul_f32_e32 v46, v5, v0
	global_load_dwordx4 v[38:41], v[38:39], off
	v_mul_f32_e32 v47, v4, v0
	v_mul_f32_e32 v48, v3, v0
	v_mul_f32_e32 v0, v2, v0
	v_mov_b32_e32 v2, v26
	v_mov_b32_e32 v3, v27
	v_mov_b32_e32 v4, v28
	v_mov_b32_e32 v5, v29
	s_waitcnt vmcnt(0) lgkmcnt(0)
	v_mul_f32_e32 v22, v30, v22
	v_mul_f32_e32 v23, v31, v23
	v_mul_f32_e32 v24, v32, v24
	v_mul_f32_e32 v25, v33, v25
	v_add_f32_e32 v30, 1.0, v34
	v_add_f32_e32 v31, 1.0, v35
	v_add_f32_e32 v32, 1.0, v36
	v_add_f32_e32 v33, 1.0, v37
	v_fma_f32 v25, v33, v25, v41
	v_fma_f32 v24, v32, v24, v40
	v_fma_f32 v23, v31, v23, v39
	v_fmac_f32_e32 v38, v30, v22
	v_cvt_pk_bf16_f32 v22, v38, v23
	v_cvt_pk_bf16_f32 v23, v24, v25
	global_store_dwordx2 v[60:61], v[22:23], off offset:512
	v_lshl_add_u64 v[30:31], s[10:11], 0, v[64:65]
	global_load_dwordx4 v[22:25], v[58:59], off offset:2048
	v_lshl_add_u64 v[34:35], s[36:37], 0, v[64:65]
	global_load_dwordx4 v[30:33], v[30:31], off
	s_waitcnt vmcnt(0) lgkmcnt(0)
	v_mul_f32_e32 v10, v22, v10
	global_load_dwordx4 v[34:37], v[34:35], off
	v_mul_f32_e32 v11, v23, v11
	v_mul_f32_e32 v12, v24, v12
	v_mul_f32_e32 v13, v25, v13
	v_add_f32_e32 v22, 1.0, v30
	v_add_f32_e32 v23, 1.0, v31
	v_add_f32_e32 v24, 1.0, v32
	v_add_f32_e32 v25, 1.0, v33
	v_mov_b32_e32 v30, v6
	v_mov_b32_e32 v31, v7
	v_mov_b32_e32 v32, v8
	v_mov_b32_e32 v33, v9
	s_waitcnt vmcnt(0) lgkmcnt(0)
	v_fma_f32 v13, v25, v13, v37
	v_fma_f32 v12, v24, v12, v36
	v_fma_f32 v11, v23, v11, v35
	v_fmac_f32_e32 v34, v22, v10
	v_cvt_pk_bf16_f32 v10, v34, v11
	v_cvt_pk_bf16_f32 v11, v12, v13
	global_store_dwordx2 v[60:61], v[10:11], off offset:1024
	v_lshl_add_u64 v[10:11], s[10:11], 0, v[66:67]
	global_load_dwordx4 v[34:37], v[58:59], off offset:3072
	global_load_dwordx4 v[38:41], v[10:11], off
	v_lshl_add_u64 v[10:11], s[36:37], 0, v[66:67]
	global_load_dwordx4 v[42:45], v[10:11], off
	v_mov_b32_e32 v22, v14
	v_mov_b32_e32 v23, v15
	v_mov_b32_e32 v24, v16
	v_mov_b32_e32 v25, v17
	v_mov_b32_e32 v10, v18
	v_mov_b32_e32 v11, v19
	v_mov_b32_e32 v12, v20
	v_mov_b32_e32 v13, v21
	s_waitcnt vmcnt(0) lgkmcnt(0)
	v_mul_f32_e32 v0, v0, v34
	v_mul_f32_e32 v34, v48, v35
	v_mul_f32_e32 v35, v47, v36
	v_mul_f32_e32 v36, v46, v37
	v_add_f32_e32 v37, 1.0, v38
	v_add_f32_e32 v38, 1.0, v39
	v_add_f32_e32 v39, 1.0, v40
	v_add_f32_e32 v40, 1.0, v41
	v_fma_f32 v36, v36, v40, v45
	v_fma_f32 v35, v35, v39, v44
	v_fma_f32 v34, v34, v38, v43
	v_fmac_f32_e32 v42, v0, v37
	v_cvt_pk_bf16_f32 v34, v42, v34
	v_cvt_pk_bf16_f32 v35, v35, v36
	global_store_dwordx2 v[60:61], v[34:35], off offset:1536
	v_lshl_add_u64 v[60:61], v[60:61], 0, s[80:81]
	s_cbranch_vccnz .LBB0_633
.LBB0_629:
	s_add_i32 s29, s60, s78
	s_add_i32 s10, s29, 0x8000
	s_cmp_ge_i32 s10, s25
	s_cselect_b64 s[8:9], -1, 0
	s_and_b64 vcc, exec, s[8:9]
	v_lshlrev_b32_e32 v0, 2, v54
	s_cbranch_vccnz .LBB0_631
	s_cmp_lt_i32 s10, 0x8000
	s_cselect_b32 s11, s28, 0
	s_cselect_b32 s10, s27, s29
	s_cselect_b32 s35, s17, s5
	s_cselect_b32 s36, s20, s4
	s_lshl_b64 s[10:11], s[10:11], 12
	s_add_u32 s10, s36, s10
	s_addc_u32 s11, s35, s11
	v_lshl_add_u64 v[26:27], s[10:11], 0, v[0:1]
	global_load_dwordx4 v[6:9], v[26:27], off
	global_load_dwordx4 v[14:17], v[26:27], off offset:1024
	global_load_dwordx4 v[18:21], v[26:27], off offset:2048
	s_nop 0
	global_load_dwordx4 v[26:29], v[26:27], off offset:3072
.LBB0_631:
	s_add_i32 s35, s78, 0x8000
	s_cmp_lt_i32 s35, 0x8000
	s_cselect_b64 s[10:11], -1, 0
	s_or_b64 s[10:11], s[6:7], s[10:11]
	s_and_b64 vcc, exec, s[10:11]
	s_cbranch_vccnz .LBB0_628
	v_mov_b32_e32 v34, s59
	ds_read_b64 v[34:35], v34
	s_lshl_b64 s[10:11], s[78:79], 12
	s_mov_b64 s[38:39], 0xcc00000
	v_mov_b32_e32 v63, v1
	v_mov_b32_e32 v65, v1
	s_waitcnt lgkmcnt(0)
	v_readfirstlane_b32 s36, v34
	v_readfirstlane_b32 s37, v35
	s_add_u32 s36, s36, s10
	s_addc_u32 s37, s37, s11
	s_add_u32 s10, s36, 0xd400000
	v_lshl_add_u64 v[68:69], s[36:37], 0, v[0:1]
	s_addc_u32 s11, s37, 0
	v_add_co_u32_e32 v34, vcc, s89, v68
	s_add_u32 s36, s36, 0x1f800000
	s_nop 0
	v_addc_co_u32_e32 v35, vcc, 0, v69, vcc
	s_addc_u32 s37, s37, 0
	v_lshl_add_u64 v[38:39], s[10:11], 0, v[0:1]
	v_add_co_u32_e32 v42, vcc, s44, v68
	global_load_dwordx4 v[34:37], v[34:35], off
	s_nop 0
	v_addc_co_u32_e32 v43, vcc, 0, v69, vcc
	global_load_dwordx4 v[38:41], v[38:39], off
	v_lshl_add_u64 v[46:47], s[36:37], 0, v[0:1]
	global_load_dwordx4 v[42:45], v[42:43], off
	s_nop 0
	global_load_dwordx4 v[46:49], v[46:47], off
	s_nop 0
	global_load_dwordx4 v[50:53], v[56:57], off
	v_lshl_add_u64 v[88:89], v[68:69], 0, s[38:39]
	s_mov_b64 s[38:39], 0x1f000000
	v_lshl_add_u64 v[70:71], v[68:69], 0, s[38:39]
	v_add_co_u32_e32 v90, vcc, s90, v68
	v_lshl_add_u64 v[80:81], s[10:11], 0, v[62:63]
	v_lshl_add_u64 v[84:85], s[36:37], 0, v[62:63]
	v_addc_co_u32_e32 v91, vcc, 0, v69, vcc
	global_load_dwordx4 v[72:75], v[88:89], off offset:1024
	global_load_dwordx4 v[76:79], v[70:71], off offset:1024
	s_nop 0
	global_load_dwordx4 v[80:83], v[80:81], off
	s_mov_b64 s[38:39], 0x8000000
	global_load_dwordx4 v[84:87], v[84:85], off
	v_lshl_add_u64 v[68:69], v[68:69], 0, s[38:39]
	s_waitcnt vmcnt(0) lgkmcnt(0)
	v_add_f32_e32 v37, v37, v41
	v_add_f32_e32 v36, v36, v40
	v_add_f32_e32 v35, v35, v39
	v_add_f32_e32 v34, v34, v38
	v_add_f32_e32 v38, v45, v49
	v_add_f32_e32 v39, v44, v48
	v_add_f32_e32 v40, v43, v47
	v_add_f32_e32 v41, v42, v46
	v_add_f32_e32 v34, v34, v41
	v_add_f32_e32 v35, v35, v40
	v_add_f32_e32 v36, v36, v39
	v_add_f32_e32 v37, v37, v38
	v_fmac_f32_e32 v33, v53, v37
	v_fmac_f32_e32 v32, v52, v36
	v_fmac_f32_e32 v31, v51, v35
	v_fmac_f32_e32 v30, v50, v34
	global_store_dwordx4 v[90:91], v[30:33], off
	global_load_dwordx4 v[50:53], v[56:57], off offset:1024
	v_lshl_add_u64 v[42:43], s[10:11], 0, v[64:65]
	global_load_dwordx4 v[38:41], v[88:89], off offset:2048
	global_load_dwordx4 v[34:37], v[70:71], off offset:2048
	global_load_dwordx4 v[46:49], v[42:43], off
	v_lshl_add_u64 v[42:43], s[36:37], 0, v[64:65]
	v_add_f32_e32 v55, v75, v83
	v_add_f32_e32 v63, v74, v82
	v_add_f32_e32 v65, v73, v81
	v_add_f32_e32 v67, v72, v80
	v_add_f32_e32 v72, v79, v87
	v_add_f32_e32 v73, v78, v86
	v_add_f32_e32 v74, v77, v85
	v_add_f32_e32 v75, v76, v84
	v_add_f32_e32 v67, v67, v75
	v_add_f32_e32 v65, v65, v74
	v_add_f32_e32 v63, v63, v73
	v_add_f32_e32 v55, v55, v72
	global_load_dwordx4 v[42:45], v[42:43], off
	s_waitcnt vmcnt(0) lgkmcnt(0)
	v_fmac_f32_e32 v25, v53, v55
	v_fmac_f32_e32 v24, v52, v63
	v_fmac_f32_e32 v23, v51, v65
	v_fmac_f32_e32 v22, v50, v67
	global_store_dwordx4 v[68:69], v[22:25], off offset:1024
	global_load_dwordx4 v[50:53], v[56:57], off offset:2048
	v_mov_b32_e32 v67, v1
	v_lshl_add_u64 v[80:81], s[10:11], 0, v[66:67]
	v_add_f32_e32 v41, v41, v49
	v_add_f32_e32 v40, v40, v48
	v_add_f32_e32 v39, v39, v47
	v_add_f32_e32 v38, v38, v46
	global_load_dwordx4 v[72:75], v[88:89], off offset:3072
	global_load_dwordx4 v[76:79], v[70:71], off offset:3072
	s_nop 0
	global_load_dwordx4 v[80:83], v[80:81], off
	v_lshl_add_u64 v[70:71], s[36:37], 0, v[66:67]
	global_load_dwordx4 v[84:87], v[70:71], off
	v_add_f32_e32 v37, v37, v45
	v_add_f32_e32 v36, v36, v44
	v_add_f32_e32 v35, v35, v43
	v_add_f32_e32 v34, v34, v42
	v_add_f32_e32 v34, v38, v34
	v_add_f32_e32 v35, v39, v35
	v_add_f32_e32 v36, v40, v36
	v_add_f32_e32 v37, v41, v37
	s_waitcnt vmcnt(0) lgkmcnt(0)
	v_fmac_f32_e32 v13, v53, v37
	v_fmac_f32_e32 v12, v52, v36
	v_fmac_f32_e32 v11, v51, v35
	v_fmac_f32_e32 v10, v50, v34
	global_store_dwordx4 v[68:69], v[10:13], off offset:2048
	global_load_dwordx4 v[34:37], v[56:57], off offset:3072
	v_add_f32_e32 v38, v75, v83
	v_add_f32_e32 v39, v74, v82
	v_add_f32_e32 v40, v73, v81
	v_add_f32_e32 v41, v72, v80
	v_add_f32_e32 v42, v79, v87
	v_add_f32_e32 v43, v78, v86
	v_add_f32_e32 v44, v77, v85
	v_add_f32_e32 v45, v76, v84
	v_add_f32_e32 v41, v41, v45
	v_add_f32_e32 v40, v40, v44
	v_add_f32_e32 v39, v39, v43
	v_add_f32_e32 v38, v38, v42
	s_waitcnt vmcnt(0) lgkmcnt(0)
	v_fmac_f32_e32 v5, v37, v38
	v_fmac_f32_e32 v4, v36, v39
	v_fmac_f32_e32 v3, v35, v40
	v_fmac_f32_e32 v2, v34, v41
	global_store_dwordx4 v[68:69], v[2:5], off offset:3072
	s_branch .LBB0_628

.LBB0_642:
	s_cmp_lg_u32 s26, 3
	s_cbranch_scc1 .Lstag_next0
	s_cmpk_lt_u32 s53, 0x80
	s_cbranch_scc1 .Lstag_next0
	s_sleep 127
	s_sleep 127
	s_sleep 127

.LBB0_695:
	v_lshl_add_u32 v156, s87, 8, v222
	v_lshl_or_b32 v158, s91, 8, v224
	s_mov_b64 vcc, -1
	s_mov_b64 s[10:11], 0
	s_cmp_lt_i32 s26, 3
	s_mov_b64 s[38:39], 0
	s_mov_b64 s[52:53], 0
	s_cbranch_scc1 .LBB0_751
	s_cmp_gt_i32 s26, 4
	s_cbranch_scc0 .LBB0_700
	s_cmp_lt_i32 s26, 7
	s_mov_b64 s[52:53], -1
	s_cbranch_scc0 .LBB0_699
	v_mov_b32_e32 v130, s59
	ds_read_b64 v[130:131], v130
	s_add_i32 s33, s74, -2
	s_ashr_i32 s34, s74, 31
	s_cmp_lt_i32 s74, 2
	s_cselect_b32 s53, s34, 0
	s_cselect_b32 s52, s74, s33
	s_mov_b32 s33, 0x1f000000
	s_waitcnt lgkmcnt(0)
	v_readfirstlane_b32 s72, v130
	s_cselect_b32 s33, 0xcc00000, s33
	s_lshl_b64 s[52:53], s[52:53], 23
	v_readfirstlane_b32 s57, v131
	s_add_u32 s34, s72, s52
	s_addc_u32 s53, s57, s53
	s_add_u32 s52, s34, s33
	s_addc_u32 s53, s53, 0
	v_ashrrev_i32_e32 v159, 31, v158
	v_ashrrev_i32_e32 v157, 31, v156
	v_lshl_add_u64 v[130:131], v[158:159], 2, s[52:53]
	v_lshlrev_b64 v[132:133], 12, v[156:157]
	v_lshl_add_u64 v[130:131], v[130:131], 0, v[132:133]
	s_mov_b32 s33, 0x10000
	v_add_co_u32_e32 v134, vcc, s33, v130
	s_mov_b32 s33, 0x20000
	s_nop 0
	v_addc_co_u32_e32 v135, vcc, 0, v131, vcc
	v_add_co_u32_e32 v136, vcc, s33, v130
	s_mov_b32 s33, 0x30000
	s_nop 0
	v_addc_co_u32_e32 v137, vcc, 0, v131, vcc
	v_add_co_u32_e32 v138, vcc, s33, v130
	s_mov_b32 s33, 0x80000
	s_nop 0
	v_addc_co_u32_e32 v139, vcc, 0, v131, vcc
	v_add_co_u32_e32 v140, vcc, s33, v130
	s_mov_b64 s[52:53], 0x10000
	s_nop 0
	v_addc_co_u32_e32 v141, vcc, 0, v131, vcc
	s_mov_b32 s33, 0x90000
	v_lshl_add_u64 v[132:133], v[130:131], 0, s[52:53]
	s_mov_b64 s[52:53], 0x20000
	v_add_co_u32_e32 v160, vcc, s33, v130
	global_store_dwordx4 v[130:131], v[126:129], off
	global_store_dwordx4 v[130:131], v[122:125], off offset:16
	global_store_dwordx4 v[134:135], v[110:113], off
	global_store_dwordx4 v[132:133], v[106:109], off offset:16
	v_lshl_add_u64 v[134:135], v[130:131], 0, s[52:53]
	s_mov_b64 s[52:53], 0x30000
	v_addc_co_u32_e32 v161, vcc, 0, v131, vcc
	s_mov_b32 s33, 0xa0000
	global_store_dwordx4 v[136:137], v[94:97], off
	global_store_dwordx4 v[134:135], v[90:93], off offset:16
	v_lshl_add_u64 v[136:137], v[130:131], 0, s[52:53]
	s_mov_b64 s[52:53], 0x80000
	v_add_co_u32_e32 v162, vcc, s33, v130
	global_store_dwordx4 v[138:139], v[78:81], off
	global_store_dwordx4 v[136:137], v[74:77], off offset:16
	v_lshl_add_u64 v[138:139], v[130:131], 0, s[52:53]
	s_mov_b64 s[52:53], 0x90000
	v_addc_co_u32_e32 v163, vcc, 0, v131, vcc
	s_mov_b32 s33, 0xb0000
	global_store_dwordx4 v[140:141], v[62:65], off
	global_store_dwordx4 v[138:139], v[58:61], off offset:16
	v_lshl_add_u64 v[140:141], v[130:131], 0, s[52:53]
	s_mov_b64 s[52:53], 0xa0000
	v_add_co_u32_e32 v164, vcc, s33, v130
	global_store_dwordx4 v[160:161], v[46:49], off
	global_store_dwordx4 v[140:141], v[42:45], off offset:16
	v_lshl_add_u64 v[160:161], v[130:131], 0, s[52:53]
	s_mov_b64 s[52:53], 0xb0000
	v_addc_co_u32_e32 v165, vcc, 0, v131, vcc
	global_store_dwordx4 v[162:163], v[30:33], off
	global_store_dwordx4 v[160:161], v[26:29], off offset:16
	v_lshl_add_u64 v[162:163], v[130:131], 0, s[52:53]
	global_store_dwordx4 v[164:165], v[14:17], off
	global_store_dwordx4 v[162:163], v[10:13], off offset:16
	global_store_dwordx4 v[130:131], v[118:121], off offset:512
	global_store_dwordx4 v[130:131], v[114:117], off offset:528
	global_store_dwordx4 v[132:133], v[102:105], off offset:512
	global_store_dwordx4 v[132:133], v[98:101], off offset:528
	global_store_dwordx4 v[134:135], v[86:89], off offset:512
	global_store_dwordx4 v[134:135], v[82:85], off offset:528
	global_store_dwordx4 v[136:137], v[70:73], off offset:512
	global_store_dwordx4 v[136:137], v[66:69], off offset:528
	global_store_dwordx4 v[138:139], v[54:57], off offset:512
	global_store_dwordx4 v[138:139], v[50:53], off offset:528
	global_store_dwordx4 v[140:141], v[38:41], off offset:512
	global_store_dwordx4 v[140:141], v[34:37], off offset:528
	global_store_dwordx4 v[160:161], v[22:25], off offset:512
	global_store_dwordx4 v[160:161], v[18:21], off offset:528
	global_store_dwordx4 v[162:163], v[6:9], off offset:512
	global_store_dwordx4 v[162:163], v[2:5], off offset:528
	s_mov_b64 s[52:53], 0

.LBB0_711:
	v_mov_b32_e32 v130, s59
	ds_read_b64 v[130:131], v130
	s_min_i32 s33, s87, 0x80
	s_ashr_i32 s33, s33, 4
	v_readlane_b32 s39, v245, 2
	v_ashrrev_i32_e32 v157, 31, v156
	s_waitcnt lgkmcnt(0)
	v_readfirstlane_b32 s38, v130
	v_readfirstlane_b32 s34, v131
	s_add_u32 s38, s38, s39
	s_addc_u32 s34, s34, 0
	s_mul_hi_i32 s39, s33, 0x6000
	s_mulk_i32 s33, 0x6000
	s_add_u32 s33, s38, s33
	s_addc_u32 s34, s34, s39
	s_add_u32 s38, s33, s47
	s_addc_u32 s39, s34, 0
	v_ashrrev_i32_e32 v159, 31, v158
	v_lshlrev_b64 v[140:141], 10, v[156:157]
	v_lshl_add_u64 v[130:131], v[158:159], 2, s[38:39]
	s_mov_b64 s[38:39], 0x100000
	s_mov_b32 s33, 0x100000
	v_lshl_add_u64 v[140:141], v[140:141], 0, v[158:159]
	v_lshl_add_u64 v[138:139], v[130:131], 0, s[38:39]
	v_add_co_u32_e32 v130, vcc, s33, v130
	v_lshlrev_b64 v[166:167], 2, v[140:141]
	s_nop 0
	v_addc_co_u32_e32 v131, vcc, 0, v131, vcc
	v_lshl_add_u64 v[140:141], s[10:11], 0, v[166:167]
	s_sub_u32 s52, s52, s10
	s_subb_u32 s53, s53, s11
	global_load_dwordx4 v[160:163], v[138:139], off
	global_load_dwordx4 v[164:167], v[138:139], off offset:16
	global_load_dwordx4 v[168:171], v[138:139], off offset:512
	global_load_dwordx4 v[172:175], v[138:139], off offset:528
	global_load_dwordx4 v[176:179], v[140:141], off
	global_load_dwordx4 v[180:183], v[140:141], off offset:16
	s_mov_b64 s[10:11], 0x10000
	v_lshl_add_u64 v[200:201], v[140:141], 0, s[10:11]
	global_load_dwordx4 v[184:187], v[200:201], off
	global_load_dwordx4 v[188:191], v[200:201], off offset:16
	s_mov_b64 s[10:11], 0x20000
	v_lshl_add_u64 v[202:203], v[140:141], 0, s[10:11]
	global_load_dwordx4 v[192:195], v[202:203], off
	global_load_dwordx4 v[196:199], v[202:203], off offset:16
	s_mov_b64 s[10:11], 0x30000
	v_lshl_add_u64 v[200:201], v[140:141], 0, s[10:11]
	global_load_dwordx4 v[226:229], v[200:201], off
	global_load_dwordx4 v[230:233], v[200:201], off offset:16
	s_mov_b64 s[10:11], 0x80000
	v_lshl_add_u64 v[202:203], v[140:141], 0, s[10:11]
	global_load_dwordx4 v[234:237], v[202:203], off
	global_load_dwordx4 v[238:241], v[202:203], off offset:16
	s_mov_b64 s[10:11], 0x90000
	v_lshl_add_u64 v[200:201], v[140:141], 0, s[10:11]
	global_load_dwordx4 v[130:133], v[200:201], off
	global_load_dwordx4 v[134:137], v[200:201], off offset:16
	s_waitcnt vmcnt(10)
	v_fma_f32 v126, v126, v160, v176
	v_fma_f32 v127, v127, v161, v177
	v_fma_f32 v128, v128, v162, v178
	v_fma_f32 v129, v129, v163, v179
	v_fma_f32 v122, v122, v164, v180
	v_fma_f32 v123, v123, v165, v181
	v_fma_f32 v124, v124, v166, v182
	v_fma_f32 v125, v125, v167, v183
	v_lshl_add_u64 v[242:243], v[140:141], 0, s[52:53]
	global_store_dwordx4 v[242:243], v[126:129], off
	global_store_dwordx4 v[242:243], v[122:125], off offset:16
	s_mov_b64 s[10:11], 0xa0000
	v_lshl_add_u64 v[202:203], v[140:141], 0, s[10:11]
	global_load_dwordx4 v[176:179], v[202:203], off
	global_load_dwordx4 v[180:183], v[202:203], off offset:16
	s_waitcnt vmcnt(12)
	v_fma_f32 v110, v110, v160, v184
	v_fma_f32 v111, v111, v161, v185
	v_fma_f32 v112, v112, v162, v186
	v_fma_f32 v113, v113, v163, v187
	v_fma_f32 v106, v106, v164, v188
	v_fma_f32 v107, v107, v165, v189
	v_fma_f32 v108, v108, v166, v190
	v_fma_f32 v109, v109, v167, v191
	s_mov_b64 s[10:11], 0x10000
	v_lshl_add_u64 v[138:139], v[140:141], 0, s[10:11]
	v_lshl_add_u64 v[138:139], v[138:139], 0, s[52:53]
	global_store_dwordx4 v[138:139], v[110:113], off
	global_store_dwordx4 v[138:139], v[106:109], off offset:16
	s_mov_b64 s[10:11], 0xb0000
	v_lshl_add_u64 v[200:201], v[140:141], 0, s[10:11]
	global_load_dwordx4 v[184:187], v[200:201], off
	global_load_dwordx4 v[188:191], v[200:201], off offset:16
	s_waitcnt vmcnt(14)
	v_fma_f32 v94, v94, v160, v192
	v_fma_f32 v95, v95, v161, v193
	v_fma_f32 v96, v96, v162, v194
	v_fma_f32 v97, v97, v163, v195
	v_fma_f32 v90, v90, v164, v196
	v_fma_f32 v91, v91, v165, v197
	v_fma_f32 v92, v92, v166, v198
	v_fma_f32 v93, v93, v167, v199
	s_mov_b64 s[10:11], 0x20000
	v_lshl_add_u64 v[242:243], v[140:141], 0, s[10:11]
	v_lshl_add_u64 v[242:243], v[242:243], 0, s[52:53]
	global_store_dwordx4 v[242:243], v[94:97], off
	global_store_dwordx4 v[242:243], v[90:93], off offset:16
	global_load_dwordx4 v[192:195], v[140:141], off offset:512
	global_load_dwordx4 v[196:199], v[140:141], off offset:528
	s_waitcnt vmcnt(16)
	v_fma_f32 v78, v78, v160, v226
	v_fma_f32 v79, v79, v161, v227
	v_fma_f32 v80, v80, v162, v228
	v_fma_f32 v81, v81, v163, v229
	v_fma_f32 v74, v74, v164, v230
	v_fma_f32 v75, v75, v165, v231
	v_fma_f32 v76, v76, v166, v232
	v_fma_f32 v77, v77, v167, v233
	s_mov_b64 s[10:11], 0x30000
	v_lshl_add_u64 v[138:139], v[140:141], 0, s[10:11]
	v_lshl_add_u64 v[138:139], v[138:139], 0, s[52:53]
	global_store_dwordx4 v[138:139], v[78:81], off
	global_store_dwordx4 v[138:139], v[74:77], off offset:16
	s_mov_b64 s[10:11], 0x10000
	v_lshl_add_u64 v[202:203], v[140:141], 0, s[10:11]
	global_load_dwordx4 v[226:229], v[202:203], off offset:512
	global_load_dwordx4 v[230:233], v[202:203], off offset:528
	s_waitcnt vmcnt(18)
	v_fma_f32 v62, v62, v160, v234
	v_fma_f32 v63, v63, v161, v235
	v_fma_f32 v64, v64, v162, v236
	v_fma_f32 v65, v65, v163, v237
	v_fma_f32 v58, v58, v164, v238
	v_fma_f32 v59, v59, v165, v239
	v_fma_f32 v60, v60, v166, v240
	v_fma_f32 v61, v61, v167, v241
	s_mov_b64 s[10:11], 0x80000
	v_lshl_add_u64 v[242:243], v[140:141], 0, s[10:11]
	v_lshl_add_u64 v[242:243], v[242:243], 0, s[52:53]
	global_store_dwordx4 v[242:243], v[62:65], off
	global_store_dwordx4 v[242:243], v[58:61], off offset:16
	s_mov_b64 s[10:11], 0x20000
	v_lshl_add_u64 v[200:201], v[140:141], 0, s[10:11]
	global_load_dwordx4 v[234:237], v[200:201], off offset:512
	global_load_dwordx4 v[238:241], v[200:201], off offset:528
	s_waitcnt vmcnt(20)
	v_fma_f32 v46, v46, v160, v130
	v_fma_f32 v47, v47, v161, v131
	v_fma_f32 v48, v48, v162, v132
	v_fma_f32 v49, v49, v163, v133
	v_fma_f32 v42, v42, v164, v134
	v_fma_f32 v43, v43, v165, v135
	v_fma_f32 v44, v44, v166, v136
	v_fma_f32 v45, v45, v167, v137
	s_mov_b64 s[10:11], 0x90000
	v_lshl_add_u64 v[138:139], v[140:141], 0, s[10:11]
	v_lshl_add_u64 v[138:139], v[138:139], 0, s[52:53]
	global_store_dwordx4 v[138:139], v[46:49], off
	global_store_dwordx4 v[138:139], v[42:45], off offset:16
	s_mov_b64 s[10:11], 0x30000
	v_lshl_add_u64 v[202:203], v[140:141], 0, s[10:11]
	global_load_dwordx4 v[130:133], v[202:203], off offset:512
	global_load_dwordx4 v[134:137], v[202:203], off offset:528
	s_waitcnt vmcnt(20)
	v_fma_f32 v30, v30, v160, v176
	v_fma_f32 v31, v31, v161, v177
	v_fma_f32 v32, v32, v162, v178
	v_fma_f32 v33, v33, v163, v179
	v_fma_f32 v26, v26, v164, v180
	v_fma_f32 v27, v27, v165, v181
	v_fma_f32 v28, v28, v166, v182
	v_fma_f32 v29, v29, v167, v183
	s_mov_b64 s[10:11], 0xa0000
	v_lshl_add_u64 v[242:243], v[140:141], 0, s[10:11]
	v_lshl_add_u64 v[242:243], v[242:243], 0, s[52:53]
	global_store_dwordx4 v[242:243], v[30:33], off
	global_store_dwordx4 v[242:243], v[26:29], off offset:16
	s_mov_b64 s[10:11], 0x80000
	v_lshl_add_u64 v[200:201], v[140:141], 0, s[10:11]
	global_load_dwordx4 v[176:179], v[200:201], off offset:512
	global_load_dwordx4 v[180:183], v[200:201], off offset:528
	s_waitcnt vmcnt(20)
	v_fma_f32 v14, v14, v160, v184
	v_fma_f32 v15, v15, v161, v185
	v_fma_f32 v16, v16, v162, v186
	v_fma_f32 v17, v17, v163, v187
	v_fma_f32 v10, v10, v164, v188
	v_fma_f32 v11, v11, v165, v189
	v_fma_f32 v12, v12, v166, v190
	v_fma_f32 v13, v13, v167, v191
	s_mov_b64 s[10:11], 0xb0000
	v_lshl_add_u64 v[138:139], v[140:141], 0, s[10:11]
	v_lshl_add_u64 v[138:139], v[138:139], 0, s[52:53]
	global_store_dwordx4 v[138:139], v[14:17], off
	global_store_dwordx4 v[138:139], v[10:13], off offset:16
	s_mov_b64 s[10:11], 0x90000
	v_lshl_add_u64 v[202:203], v[140:141], 0, s[10:11]
	global_load_dwordx4 v[184:187], v[202:203], off offset:512
	global_load_dwordx4 v[188:191], v[202:203], off offset:528
	s_waitcnt vmcnt(20)
	v_fma_f32 v118, v118, v168, v192
	v_fma_f32 v119, v119, v169, v193
	v_fma_f32 v120, v120, v170, v194
	v_fma_f32 v121, v121, v171, v195
	v_fma_f32 v114, v114, v172, v196
	v_fma_f32 v115, v115, v173, v197
	v_fma_f32 v116, v116, v174, v198
	v_fma_f32 v117, v117, v175, v199
	v_lshl_add_u64 v[242:243], v[140:141], 0, s[52:53]
	global_store_dwordx4 v[242:243], v[118:121], off offset:512
	global_store_dwordx4 v[242:243], v[114:117], off offset:528
	s_mov_b64 s[10:11], 0xa0000
	v_lshl_add_u64 v[200:201], v[140:141], 0, s[10:11]
	global_load_dwordx4 v[192:195], v[200:201], off offset:512
	global_load_dwordx4 v[196:199], v[200:201], off offset:528
	s_waitcnt vmcnt(20)
	v_fma_f32 v102, v102, v168, v226
	v_fma_f32 v103, v103, v169, v227
	v_fma_f32 v104, v104, v170, v228
	v_fma_f32 v105, v105, v171, v229
	v_fma_f32 v98, v98, v172, v230
	v_fma_f32 v99, v99, v173, v231
	v_fma_f32 v100, v100, v174, v232
	v_fma_f32 v101, v101, v175, v233
	s_mov_b64 s[10:11], 0x10000
	v_lshl_add_u64 v[138:139], v[140:141], 0, s[10:11]
	v_lshl_add_u64 v[138:139], v[138:139], 0, s[52:53]
	global_store_dwordx4 v[138:139], v[102:105], off offset:512
	global_store_dwordx4 v[138:139], v[98:101], off offset:528
	s_mov_b64 s[10:11], 0xb0000
	v_lshl_add_u64 v[202:203], v[140:141], 0, s[10:11]
	global_load_dwordx4 v[226:229], v[202:203], off offset:512
	global_load_dwordx4 v[230:233], v[202:203], off offset:528
	s_waitcnt vmcnt(20)
	v_fma_f32 v86, v86, v168, v234
	v_fma_f32 v87, v87, v169, v235
	v_fma_f32 v88, v88, v170, v236
	v_fma_f32 v89, v89, v171, v237
	v_fma_f32 v82, v82, v172, v238
	v_fma_f32 v83, v83, v173, v239
	v_fma_f32 v84, v84, v174, v240
	v_fma_f32 v85, v85, v175, v241
	s_mov_b64 s[10:11], 0x20000
	v_lshl_add_u64 v[242:243], v[140:141], 0, s[10:11]
	v_lshl_add_u64 v[242:243], v[242:243], 0, s[52:53]
	global_store_dwordx4 v[242:243], v[86:89], off offset:512
	global_store_dwordx4 v[242:243], v[82:85], off offset:528
	s_waitcnt vmcnt(18)
	v_fma_f32 v70, v70, v168, v130
	v_fma_f32 v71, v71, v169, v131
	v_fma_f32 v72, v72, v170, v132
	v_fma_f32 v73, v73, v171, v133
	v_fma_f32 v66, v66, v172, v134
	v_fma_f32 v67, v67, v173, v135
	v_fma_f32 v68, v68, v174, v136
	v_fma_f32 v69, v69, v175, v137
	s_mov_b64 s[10:11], 0x30000
	v_lshl_add_u64 v[138:139], v[140:141], 0, s[10:11]
	v_lshl_add_u64 v[138:139], v[138:139], 0, s[52:53]
	global_store_dwordx4 v[138:139], v[70:73], off offset:512
	global_store_dwordx4 v[138:139], v[66:69], off offset:528
	s_waitcnt vmcnt(16)
	v_fma_f32 v54, v54, v168, v176
	v_fma_f32 v55, v55, v169, v177
	v_fma_f32 v56, v56, v170, v178
	v_fma_f32 v57, v57, v171, v179
	v_fma_f32 v50, v50, v172, v180
	v_fma_f32 v51, v51, v173, v181
	v_fma_f32 v52, v52, v174, v182
	v_fma_f32 v53, v53, v175, v183
	s_mov_b64 s[10:11], 0x80000
	v_lshl_add_u64 v[242:243], v[140:141], 0, s[10:11]
	v_lshl_add_u64 v[242:243], v[242:243], 0, s[52:53]
	global_store_dwordx4 v[242:243], v[54:57], off offset:512
	global_store_dwordx4 v[242:243], v[50:53], off offset:528
	s_waitcnt vmcnt(14)
	v_fma_f32 v38, v38, v168, v184
	v_fma_f32 v39, v39, v169, v185
	v_fma_f32 v40, v40, v170, v186
	v_fma_f32 v41, v41, v171, v187
	v_fma_f32 v34, v34, v172, v188
	v_fma_f32 v35, v35, v173, v189
	v_fma_f32 v36, v36, v174, v190
	v_fma_f32 v37, v37, v175, v191
	s_mov_b64 s[10:11], 0x90000
	v_lshl_add_u64 v[138:139], v[140:141], 0, s[10:11]
	v_lshl_add_u64 v[138:139], v[138:139], 0, s[52:53]
	global_store_dwordx4 v[138:139], v[38:41], off offset:512
	global_store_dwordx4 v[138:139], v[34:37], off offset:528
	s_waitcnt vmcnt(12)
	v_fma_f32 v22, v22, v168, v192
	v_fma_f32 v23, v23, v169, v193
	v_fma_f32 v24, v24, v170, v194
	v_fma_f32 v25, v25, v171, v195
	v_fma_f32 v18, v18, v172, v196
	v_fma_f32 v19, v19, v173, v197
	v_fma_f32 v20, v20, v174, v198
	v_fma_f32 v21, v21, v175, v199
	s_mov_b64 s[10:11], 0xa0000
	v_lshl_add_u64 v[242:243], v[140:141], 0, s[10:11]
	v_lshl_add_u64 v[242:243], v[242:243], 0, s[52:53]
	global_store_dwordx4 v[242:243], v[22:25], off offset:512
	global_store_dwordx4 v[242:243], v[18:21], off offset:528
	s_waitcnt vmcnt(10)
	v_fma_f32 v6, v6, v168, v226
	v_fma_f32 v7, v7, v169, v227
	v_fma_f32 v8, v8, v170, v228
	v_fma_f32 v9, v9, v171, v229
	v_fma_f32 v2, v2, v172, v230
	v_fma_f32 v3, v3, v173, v231
	v_fma_f32 v4, v4, v174, v232
	v_fma_f32 v5, v5, v175, v233
	s_mov_b64 s[10:11], 0xb0000
	v_lshl_add_u64 v[138:139], v[140:141], 0, s[10:11]
	v_lshl_add_u64 v[138:139], v[138:139], 0, s[52:53]
	global_store_dwordx4 v[138:139], v[6:9], off offset:512
	global_store_dwordx4 v[138:139], v[2:5], off offset:528
	s_mov_b64 s[38:39], 0
	s_mov_b64 s[10:11], 0
.LBB0_712:
	s_and_b64 vcc, exec, s[10:11]
	v_ashrrev_i32_e32 v159, 31, v158
	v_add_u32_e32 v170, 16, v156
	v_add_u32_e32 v168, 32, v156
	v_add_u32_e32 v166, 48, v156
	v_add_u32_e32 v164, 0x80, v156
	v_add_u32_e32 v162, 0x90, v156
	v_add_u32_e32 v160, 0xa0, v156
	s_cbranch_vccz .LBB0_714
	v_mov_b32_e32 v130, s59
	ds_read_b64 v[130:131], v130
	v_readlane_b32 s10, v245, 59
	v_lshlrev_b64 v[184:185], 1, v[158:159]
	v_ashrrev_i32_e32 v157, 31, v156
	v_ashrrev_i32_e32 v171, 31, v170
	s_waitcnt lgkmcnt(0)
	v_readfirstlane_b32 s52, v130
	v_mov_b32_e32 v130, s10
	v_readfirstlane_b32 s53, v131
	ds_read_b64 v[130:131], v130
	v_readlane_b32 s10, v245, 4
	v_readlane_b32 s11, v245, 5
	s_lshl_b64 s[10:11], s[10:11], 2
	v_lshl_add_u64 v[140:141], s[52:53], 0, v[184:185]
	s_waitcnt lgkmcnt(0)
	v_readfirstlane_b32 s34, v130
	v_readfirstlane_b32 s33, v131
	s_add_u32 s10, s34, s10
	s_addc_u32 s11, s33, s11
	v_lshl_add_u64 v[138:139], v[158:159], 2, s[10:11]
	global_load_dwordx4 v[134:137], v[138:139], off
	global_load_dwordx4 v[130:133], v[138:139], off offset:16
	s_mov_b64 s[10:11], 0xcc00000
	v_lshl_add_u64 v[198:199], v[140:141], 0, s[10:11]
	v_lshlrev_b64 v[140:141], 9, v[156:157]
	v_lshl_add_u64 v[140:141], v[198:199], 0, v[140:141]
	global_load_dwordx4 v[172:175], v[140:141], off
	v_ashrrev_i32_e32 v169, 31, v168
	v_ashrrev_i32_e32 v167, 31, v166
	s_waitcnt vmcnt(0) lgkmcnt(0)
	v_add_f32_e32 v165, v126, v134
	v_mul_f32_e32 v165, 0xbfb8aa3b, v165
	v_exp_f32_e32 v165, v165
	v_lshlrev_b32_e32 v161, 16, v172
	v_add_f32_e32 v165, 1.0, v165
	v_rcp_f32_e32 v165, v165
	v_and_b32_e32 v163, 0xffff0000, v172
	v_mul_f32_e32 v161, v165, v161
	v_add_f32_e32 v165, v127, v135
	v_mul_f32_e32 v165, 0xbfb8aa3b, v165
	v_exp_f32_e32 v165, v165
	s_nop 0
	v_add_f32_e32 v165, 1.0, v165
	v_rcp_f32_e32 v165, v165
	s_nop 0
	v_mul_f32_e32 v163, v165, v163
	v_add_f32_e32 v165, v128, v136
	v_mul_f32_e32 v165, 0xbfb8aa3b, v165
	v_exp_f32_e32 v165, v165
	v_cvt_pk_bf16_f32 v176, v161, v163
	v_lshlrev_b32_e32 v161, 16, v173
	v_and_b32_e32 v163, 0xffff0000, v173
	v_add_f32_e32 v165, 1.0, v165
	v_rcp_f32_e32 v165, v165
	v_lshlrev_b64 v[172:173], 11, v[156:157]
	v_lshl_add_u64 v[172:173], s[52:53], 0, v[172:173]
	v_mul_f32_e32 v161, v165, v161
	v_add_f32_e32 v165, v129, v137
	v_mul_f32_e32 v165, 0xbfb8aa3b, v165
	v_exp_f32_e32 v165, v165
	s_nop 0
	v_add_f32_e32 v165, 1.0, v165
	v_rcp_f32_e32 v165, v165
	s_nop 0
	v_mul_f32_e32 v163, v165, v163
	v_add_f32_e32 v165, v122, v130
	v_mul_f32_e32 v165, 0xbfb8aa3b, v165
	v_exp_f32_e32 v165, v165
	v_cvt_pk_bf16_f32 v177, v161, v163
	v_lshlrev_b32_e32 v161, 16, v174
	v_and_b32_e32 v163, 0xffff0000, v174
	v_add_f32_e32 v165, 1.0, v165
	v_rcp_f32_e32 v165, v165
	s_nop 0
	v_mul_f32_e32 v161, v165, v161
	v_add_f32_e32 v165, v123, v131
	v_mul_f32_e32 v165, 0xbfb8aa3b, v165
	v_exp_f32_e32 v165, v165
	s_nop 0
	v_add_f32_e32 v165, 1.0, v165
	v_rcp_f32_e32 v165, v165
	s_nop 0
	v_mul_f32_e32 v163, v165, v163
	v_add_f32_e32 v165, v124, v132
	v_mul_f32_e32 v165, 0xbfb8aa3b, v165
	v_exp_f32_e32 v165, v165
	v_cvt_pk_bf16_f32 v178, v161, v163
	v_lshlrev_b32_e32 v161, 16, v175
	v_and_b32_e32 v163, 0xffff0000, v175
	v_add_f32_e32 v165, 1.0, v165
	v_rcp_f32_e32 v165, v165
	v_lshl_add_u64 v[174:175], v[172:173], 0, v[184:185]
	v_lshl_add_u64 v[172:173], v[174:175], 0, s[30:31]
	v_add_co_u32_e32 v174, vcc, s88, v174
	v_mul_f32_e32 v161, v165, v161
	v_add_f32_e32 v165, v125, v133
	v_mul_f32_e32 v165, 0xbfb8aa3b, v165
	v_exp_f32_e32 v165, v165
	v_addc_co_u32_e32 v175, vcc, 0, v175, vcc
	v_add_f32_e32 v165, 1.0, v165
	v_rcp_f32_e32 v165, v165
	s_nop 0
	v_mul_f32_e32 v163, v165, v163
	v_cvt_pk_bf16_f32 v179, v161, v163
	global_store_dwordx4 v[174:175], v[176:179], off offset:1536
	v_lshlrev_b64 v[174:175], 9, v[170:171]
	v_add_f32_e32 v163, v110, v134
	v_lshl_add_u64 v[176:177], v[198:199], 0, v[174:175]
	global_load_dwordx4 v[178:181], v[176:177], off
	v_mul_f32_e32 v163, 0xbfb8aa3b, v163
	v_exp_f32_e32 v163, v163
	v_lshlrev_b64 v[174:175], 11, v[170:171]
	v_lshl_add_u64 v[174:175], s[52:53], 0, v[174:175]
	v_lshl_add_u64 v[182:183], v[174:175], 0, v[184:185]
	v_add_f32_e32 v163, 1.0, v163
	v_rcp_f32_e32 v163, v163
	v_lshl_add_u64 v[174:175], v[182:183], 0, s[30:31]
	v_add_co_u32_e32 v182, vcc, s88, v182
	v_ashrrev_i32_e32 v165, 31, v164
	s_nop 0
	v_addc_co_u32_e32 v183, vcc, 0, v183, vcc
	s_waitcnt vmcnt(0) lgkmcnt(0)
	v_lshlrev_b32_e32 v157, 16, v178
	v_mul_f32_e32 v157, v163, v157
	v_add_f32_e32 v163, v111, v135
	v_mul_f32_e32 v163, 0xbfb8aa3b, v163
	v_exp_f32_e32 v163, v163
	v_and_b32_e32 v161, 0xffff0000, v178
	v_add_f32_e32 v163, 1.0, v163
	v_rcp_f32_e32 v163, v163
	s_nop 0
	v_mul_f32_e32 v161, v163, v161
	v_add_f32_e32 v163, v112, v136
	v_mul_f32_e32 v163, 0xbfb8aa3b, v163
	v_exp_f32_e32 v163, v163
	v_cvt_pk_bf16_f32 v178, v157, v161
	v_lshlrev_b32_e32 v157, 16, v179
	v_and_b32_e32 v161, 0xffff0000, v179
	v_add_f32_e32 v163, 1.0, v163
	v_rcp_f32_e32 v163, v163
	s_nop 0
	v_mul_f32_e32 v157, v163, v157
	v_add_f32_e32 v163, v113, v137
	v_mul_f32_e32 v163, 0xbfb8aa3b, v163
	v_exp_f32_e32 v163, v163
	s_nop 0
	v_add_f32_e32 v163, 1.0, v163
	v_rcp_f32_e32 v163, v163
	s_nop 0
	v_mul_f32_e32 v161, v163, v161
	v_add_f32_e32 v163, v106, v130
	v_mul_f32_e32 v163, 0xbfb8aa3b, v163
	v_exp_f32_e32 v163, v163
	v_cvt_pk_bf16_f32 v179, v157, v161
	v_lshlrev_b32_e32 v157, 16, v180
	v_and_b32_e32 v161, 0xffff0000, v180
	v_add_f32_e32 v163, 1.0, v163
	v_rcp_f32_e32 v163, v163
	s_nop 0
	v_mul_f32_e32 v157, v163, v157
	v_add_f32_e32 v163, v107, v131
	v_mul_f32_e32 v163, 0xbfb8aa3b, v163
	v_exp_f32_e32 v163, v163
	s_nop 0
	v_add_f32_e32 v163, 1.0, v163
	v_rcp_f32_e32 v163, v163
	s_nop 0
	v_mul_f32_e32 v161, v163, v161
	v_add_f32_e32 v163, v108, v132
	v_mul_f32_e32 v163, 0xbfb8aa3b, v163
	v_exp_f32_e32 v163, v163
	v_cvt_pk_bf16_f32 v180, v157, v161
	v_lshlrev_b32_e32 v157, 16, v181
	v_and_b32_e32 v161, 0xffff0000, v181
	v_add_f32_e32 v163, 1.0, v163
	v_rcp_f32_e32 v163, v163
	s_nop 0
	v_mul_f32_e32 v157, v163, v157
	v_add_f32_e32 v163, v109, v133
	v_mul_f32_e32 v163, 0xbfb8aa3b, v163
	v_exp_f32_e32 v163, v163
	s_nop 0
	v_add_f32_e32 v163, 1.0, v163
	v_rcp_f32_e32 v163, v163
	s_nop 0
	v_mul_f32_e32 v161, v163, v161
	v_cvt_pk_bf16_f32 v181, v157, v161
	global_store_dwordx4 v[182:183], v[178:181], off offset:1536
	v_add_f32_e32 v163, v94, v134
	v_mul_f32_e32 v163, 0xbfb8aa3b, v163
	v_lshlrev_b64 v[178:179], 9, v[168:169]
	v_lshl_add_u64 v[180:181], v[198:199], 0, v[178:179]
	global_load_dwordx4 v[186:189], v[180:181], off
	v_exp_f32_e32 v163, v163
	v_lshlrev_b64 v[178:179], 11, v[168:169]
	v_lshl_add_u64 v[178:179], s[52:53], 0, v[178:179]
	v_lshl_add_u64 v[182:183], v[178:179], 0, v[184:185]
	v_add_f32_e32 v163, 1.0, v163
	v_rcp_f32_e32 v163, v163
	v_lshl_add_u64 v[178:179], v[182:183], 0, s[30:31]
	v_add_co_u32_e32 v182, vcc, s88, v182
	s_waitcnt vmcnt(0) lgkmcnt(0)
	v_lshlrev_b32_e32 v157, 16, v186
	v_mul_f32_e32 v157, v163, v157
	v_add_f32_e32 v163, v95, v135
	v_mul_f32_e32 v163, 0xbfb8aa3b, v163
	v_exp_f32_e32 v163, v163
	v_and_b32_e32 v161, 0xffff0000, v186
	v_addc_co_u32_e32 v183, vcc, 0, v183, vcc
	v_add_f32_e32 v163, 1.0, v163
	v_rcp_f32_e32 v163, v163
	s_nop 0
	v_mul_f32_e32 v161, v163, v161
	v_add_f32_e32 v163, v96, v136
	v_mul_f32_e32 v163, 0xbfb8aa3b, v163
	v_exp_f32_e32 v163, v163
	v_cvt_pk_bf16_f32 v186, v157, v161
	v_lshlrev_b32_e32 v157, 16, v187
	v_and_b32_e32 v161, 0xffff0000, v187
	v_add_f32_e32 v163, 1.0, v163
	v_rcp_f32_e32 v163, v163
	s_nop 0
	v_mul_f32_e32 v157, v163, v157
	v_add_f32_e32 v163, v97, v137
	v_mul_f32_e32 v163, 0xbfb8aa3b, v163
	v_exp_f32_e32 v163, v163
	s_nop 0
	v_add_f32_e32 v163, 1.0, v163
	v_rcp_f32_e32 v163, v163
	s_nop 0
	v_mul_f32_e32 v161, v163, v161
	v_add_f32_e32 v163, v90, v130
	v_mul_f32_e32 v163, 0xbfb8aa3b, v163
	v_exp_f32_e32 v163, v163
	v_cvt_pk_bf16_f32 v187, v157, v161
	v_lshlrev_b32_e32 v157, 16, v188
	v_and_b32_e32 v161, 0xffff0000, v188
	v_add_f32_e32 v163, 1.0, v163
	v_rcp_f32_e32 v163, v163
	s_nop 0
	v_mul_f32_e32 v157, v163, v157
	v_add_f32_e32 v163, v91, v131
	v_mul_f32_e32 v163, 0xbfb8aa3b, v163
	v_exp_f32_e32 v163, v163
	s_nop 0
	v_add_f32_e32 v163, 1.0, v163
	v_rcp_f32_e32 v163, v163
	s_nop 0
	v_mul_f32_e32 v161, v163, v161
	v_add_f32_e32 v163, v92, v132
	v_mul_f32_e32 v163, 0xbfb8aa3b, v163
	v_exp_f32_e32 v163, v163
	v_cvt_pk_bf16_f32 v188, v157, v161
	v_lshlrev_b32_e32 v157, 16, v189
	v_and_b32_e32 v161, 0xffff0000, v189
	v_add_f32_e32 v163, 1.0, v163
	v_rcp_f32_e32 v163, v163
	s_nop 0
	v_mul_f32_e32 v157, v163, v157
	v_add_f32_e32 v163, v93, v133
	v_mul_f32_e32 v163, 0xbfb8aa3b, v163
	v_exp_f32_e32 v163, v163
	s_nop 0
	v_add_f32_e32 v163, 1.0, v163
	v_rcp_f32_e32 v163, v163
	s_nop 0
	v_mul_f32_e32 v161, v163, v161
	v_cvt_pk_bf16_f32 v189, v157, v161
	global_store_dwordx4 v[182:183], v[186:189], off offset:1536
	v_lshlrev_b64 v[182:183], 9, v[166:167]
	v_add_f32_e32 v163, v78, v134
	v_lshl_add_u64 v[186:187], v[198:199], 0, v[182:183]
	global_load_dwordx4 v[188:191], v[186:187], off
	v_mul_f32_e32 v163, 0xbfb8aa3b, v163
	v_exp_f32_e32 v163, v163
	v_lshlrev_b64 v[182:183], 11, v[166:167]
	v_lshl_add_u64 v[182:183], s[52:53], 0, v[182:183]
	v_lshl_add_u64 v[192:193], v[182:183], 0, v[184:185]
	v_add_f32_e32 v163, 1.0, v163
	v_rcp_f32_e32 v163, v163
	v_lshl_add_u64 v[182:183], v[192:193], 0, s[30:31]
	v_add_co_u32_e32 v192, vcc, s88, v192
	s_waitcnt vmcnt(0) lgkmcnt(0)
	v_lshlrev_b32_e32 v157, 16, v188
	v_mul_f32_e32 v157, v163, v157
	v_add_f32_e32 v163, v79, v135
	v_mul_f32_e32 v163, 0xbfb8aa3b, v163
	v_exp_f32_e32 v163, v163
	v_and_b32_e32 v161, 0xffff0000, v188
	v_addc_co_u32_e32 v193, vcc, 0, v193, vcc
	v_add_f32_e32 v163, 1.0, v163
	v_rcp_f32_e32 v163, v163
	s_nop 0
	v_mul_f32_e32 v161, v163, v161
	v_add_f32_e32 v163, v80, v136
	v_mul_f32_e32 v163, 0xbfb8aa3b, v163
	v_exp_f32_e32 v163, v163
	v_cvt_pk_bf16_f32 v188, v157, v161
	v_lshlrev_b32_e32 v157, 16, v189
	v_and_b32_e32 v161, 0xffff0000, v189
	v_add_f32_e32 v163, 1.0, v163
	v_rcp_f32_e32 v163, v163
	s_nop 0
	v_mul_f32_e32 v157, v163, v157
	v_add_f32_e32 v163, v81, v137
	v_mul_f32_e32 v163, 0xbfb8aa3b, v163
	v_exp_f32_e32 v163, v163
	s_nop 0
	v_add_f32_e32 v163, 1.0, v163
	v_rcp_f32_e32 v163, v163
	s_nop 0
	v_mul_f32_e32 v161, v163, v161
	v_add_f32_e32 v163, v74, v130
	v_mul_f32_e32 v163, 0xbfb8aa3b, v163
	v_exp_f32_e32 v163, v163
	v_cvt_pk_bf16_f32 v189, v157, v161
	v_lshlrev_b32_e32 v157, 16, v190
	v_and_b32_e32 v161, 0xffff0000, v190
	v_add_f32_e32 v163, 1.0, v163
	v_rcp_f32_e32 v163, v163
	s_nop 0
	v_mul_f32_e32 v157, v163, v157
	v_add_f32_e32 v163, v75, v131
	v_mul_f32_e32 v163, 0xbfb8aa3b, v163
	v_exp_f32_e32 v163, v163
	s_nop 0
	v_add_f32_e32 v163, 1.0, v163
	v_rcp_f32_e32 v163, v163
	s_nop 0
	v_mul_f32_e32 v161, v163, v161
	v_add_f32_e32 v163, v76, v132
	v_mul_f32_e32 v163, 0xbfb8aa3b, v163
	v_exp_f32_e32 v163, v163
	v_cvt_pk_bf16_f32 v190, v157, v161
	v_lshlrev_b32_e32 v157, 16, v191
	v_and_b32_e32 v161, 0xffff0000, v191
	v_add_f32_e32 v163, 1.0, v163
	v_rcp_f32_e32 v163, v163
	s_nop 0
	v_mul_f32_e32 v157, v163, v157
	v_add_f32_e32 v163, v77, v133
	v_mul_f32_e32 v163, 0xbfb8aa3b, v163
	v_exp_f32_e32 v163, v163
	s_nop 0
	v_add_f32_e32 v163, 1.0, v163
	v_rcp_f32_e32 v163, v163
	s_nop 0
	v_mul_f32_e32 v161, v163, v161
	v_cvt_pk_bf16_f32 v191, v157, v161
	global_store_dwordx4 v[192:193], v[188:191], off offset:1536
	v_add_f32_e32 v163, v62, v134
	v_mul_f32_e32 v163, 0xbfb8aa3b, v163
	v_lshlrev_b64 v[188:189], 9, v[164:165]
	v_lshl_add_u64 v[190:191], v[198:199], 0, v[188:189]
	global_load_dwordx4 v[192:195], v[190:191], off
	v_exp_f32_e32 v163, v163
	v_lshlrev_b64 v[188:189], 11, v[164:165]
	v_lshl_add_u64 v[188:189], s[52:53], 0, v[188:189]
	v_lshl_add_u64 v[196:197], v[188:189], 0, v[184:185]
	v_add_f32_e32 v163, 1.0, v163
	v_rcp_f32_e32 v163, v163
	v_lshl_add_u64 v[188:189], v[196:197], 0, s[30:31]
	v_add_co_u32_e32 v196, vcc, s88, v196
	v_add_f32_e32 v165, v46, v134
	s_nop 0
	v_addc_co_u32_e32 v197, vcc, 0, v197, vcc
	v_mul_f32_e32 v165, 0xbfb8aa3b, v165
	v_exp_f32_e32 v165, v165
	s_waitcnt vmcnt(0) lgkmcnt(0)
	v_lshlrev_b32_e32 v157, 16, v192
	v_mul_f32_e32 v157, v163, v157
	v_add_f32_e32 v163, v63, v135
	v_mul_f32_e32 v163, 0xbfb8aa3b, v163
	v_exp_f32_e32 v163, v163
	v_and_b32_e32 v161, 0xffff0000, v192
	v_add_f32_e32 v165, 1.0, v165
	v_rcp_f32_e32 v165, v165
	v_add_f32_e32 v163, 1.0, v163
	v_rcp_f32_e32 v163, v163
	s_nop 0
	v_mul_f32_e32 v161, v163, v161
	v_add_f32_e32 v163, v64, v136
	v_mul_f32_e32 v163, 0xbfb8aa3b, v163
	v_exp_f32_e32 v163, v163
	v_cvt_pk_bf16_f32 v192, v157, v161
	v_lshlrev_b32_e32 v157, 16, v193
	v_and_b32_e32 v161, 0xffff0000, v193
	v_add_f32_e32 v163, 1.0, v163
	v_rcp_f32_e32 v163, v163
	s_nop 0
	v_mul_f32_e32 v157, v163, v157
	v_add_f32_e32 v163, v65, v137
	v_mul_f32_e32 v163, 0xbfb8aa3b, v163
	v_exp_f32_e32 v163, v163
	s_nop 0
	v_add_f32_e32 v163, 1.0, v163
	v_rcp_f32_e32 v163, v163
	s_nop 0
	v_mul_f32_e32 v161, v163, v161
	v_add_f32_e32 v163, v58, v130
	v_mul_f32_e32 v163, 0xbfb8aa3b, v163
	v_exp_f32_e32 v163, v163
	v_cvt_pk_bf16_f32 v193, v157, v161
	v_lshlrev_b32_e32 v157, 16, v194
	v_and_b32_e32 v161, 0xffff0000, v194
	v_add_f32_e32 v163, 1.0, v163
	v_rcp_f32_e32 v163, v163
	s_nop 0
	v_mul_f32_e32 v157, v163, v157
	v_add_f32_e32 v163, v59, v131
	v_mul_f32_e32 v163, 0xbfb8aa3b, v163
	v_exp_f32_e32 v163, v163
	s_nop 0
	v_add_f32_e32 v163, 1.0, v163
	v_rcp_f32_e32 v163, v163
	s_nop 0
	v_mul_f32_e32 v161, v163, v161
	v_add_f32_e32 v163, v60, v132
	v_mul_f32_e32 v163, 0xbfb8aa3b, v163
	v_exp_f32_e32 v163, v163
	v_cvt_pk_bf16_f32 v194, v157, v161
	v_lshlrev_b32_e32 v157, 16, v195
	v_and_b32_e32 v161, 0xffff0000, v195
	v_add_f32_e32 v163, 1.0, v163
	v_rcp_f32_e32 v163, v163
	s_nop 0
	v_mul_f32_e32 v157, v163, v157
	v_add_f32_e32 v163, v61, v133
	v_mul_f32_e32 v163, 0xbfb8aa3b, v163
	v_exp_f32_e32 v163, v163
	s_nop 0
	v_add_f32_e32 v163, 1.0, v163
	v_rcp_f32_e32 v163, v163
	s_nop 0
	v_mul_f32_e32 v161, v163, v161
	v_ashrrev_i32_e32 v163, 31, v162
	v_cvt_pk_bf16_f32 v195, v157, v161
	global_store_dwordx4 v[196:197], v[192:195], off offset:1536
	s_nop 1
	v_lshlrev_b64 v[192:193], 9, v[162:163]
	v_lshl_add_u64 v[194:195], v[198:199], 0, v[192:193]
	global_load_dwordx4 v[200:203], v[194:195], off
	v_lshlrev_b64 v[192:193], 11, v[162:163]
	v_lshl_add_u64 v[192:193], s[52:53], 0, v[192:193]
	v_lshl_add_u64 v[196:197], v[192:193], 0, v[184:185]
	v_lshl_add_u64 v[192:193], v[196:197], 0, s[30:31]
	v_add_co_u32_e32 v196, vcc, s88, v196
	s_waitcnt vmcnt(0) lgkmcnt(0)
	v_lshlrev_b32_e32 v157, 16, v200
	v_mul_f32_e32 v157, v165, v157
	v_add_f32_e32 v165, v47, v135
	v_mul_f32_e32 v165, 0xbfb8aa3b, v165
	v_exp_f32_e32 v165, v165
	v_and_b32_e32 v161, 0xffff0000, v200
	v_addc_co_u32_e32 v197, vcc, 0, v197, vcc
	v_add_f32_e32 v165, 1.0, v165
	v_rcp_f32_e32 v165, v165
	s_nop 0
	v_mul_f32_e32 v161, v165, v161
	v_add_f32_e32 v165, v48, v136
	v_mul_f32_e32 v165, 0xbfb8aa3b, v165
	v_exp_f32_e32 v165, v165
	v_cvt_pk_bf16_f32 v200, v157, v161
	v_lshlrev_b32_e32 v157, 16, v201
	v_and_b32_e32 v161, 0xffff0000, v201
	v_add_f32_e32 v165, 1.0, v165
	v_rcp_f32_e32 v165, v165
	s_nop 0
	v_mul_f32_e32 v157, v165, v157
	v_add_f32_e32 v165, v49, v137
	v_mul_f32_e32 v165, 0xbfb8aa3b, v165
	v_exp_f32_e32 v165, v165
	s_nop 0
	v_add_f32_e32 v165, 1.0, v165
	v_rcp_f32_e32 v165, v165
	s_nop 0
	v_mul_f32_e32 v161, v165, v161
	v_add_f32_e32 v165, v42, v130
	v_mul_f32_e32 v165, 0xbfb8aa3b, v165
	v_exp_f32_e32 v165, v165
	v_cvt_pk_bf16_f32 v201, v157, v161
	v_lshlrev_b32_e32 v157, 16, v202
	v_and_b32_e32 v161, 0xffff0000, v202
	v_add_f32_e32 v165, 1.0, v165
	v_rcp_f32_e32 v165, v165
	s_nop 0
	v_mul_f32_e32 v157, v165, v157
	v_add_f32_e32 v165, v43, v131
	v_mul_f32_e32 v165, 0xbfb8aa3b, v165
	v_exp_f32_e32 v165, v165
	s_nop 0
	v_add_f32_e32 v165, 1.0, v165
	v_rcp_f32_e32 v165, v165
	s_nop 0
	v_mul_f32_e32 v161, v165, v161
	v_add_f32_e32 v165, v44, v132
	v_mul_f32_e32 v165, 0xbfb8aa3b, v165
	v_exp_f32_e32 v165, v165
	v_cvt_pk_bf16_f32 v202, v157, v161
	v_lshlrev_b32_e32 v157, 16, v203
	v_and_b32_e32 v161, 0xffff0000, v203
	v_add_f32_e32 v165, 1.0, v165
	v_rcp_f32_e32 v165, v165
	s_nop 0
	v_mul_f32_e32 v157, v165, v157
	v_add_f32_e32 v165, v45, v133
	v_mul_f32_e32 v165, 0xbfb8aa3b, v165
	v_exp_f32_e32 v165, v165
	s_nop 0
	v_add_f32_e32 v165, 1.0, v165
	v_rcp_f32_e32 v165, v165
	s_nop 0
	v_mul_f32_e32 v161, v165, v161
	v_cvt_pk_bf16_f32 v203, v157, v161
	v_ashrrev_i32_e32 v161, 31, v160
	global_store_dwordx4 v[196:197], v[200:203], off offset:1536
	v_lshlrev_b64 v[196:197], 9, v[160:161]
	v_add_f32_e32 v165, v30, v134
	v_lshl_add_u64 v[200:201], v[198:199], 0, v[196:197]
	global_load_dwordx4 v[226:229], v[200:201], off
	v_mul_f32_e32 v165, 0xbfb8aa3b, v165
	v_exp_f32_e32 v165, v165
	v_lshlrev_b64 v[196:197], 11, v[160:161]
	v_lshl_add_u64 v[196:197], s[52:53], 0, v[196:197]
	v_lshl_add_u64 v[202:203], v[196:197], 0, v[184:185]
	v_add_f32_e32 v165, 1.0, v165
	v_rcp_f32_e32 v165, v165
	v_lshl_add_u64 v[196:197], v[202:203], 0, s[30:31]
	v_add_co_u32_e32 v202, vcc, s88, v202
	v_add_f32_e32 v134, v14, v134
	s_nop 0
	v_addc_co_u32_e32 v203, vcc, 0, v203, vcc
	v_mul_f32_e32 v134, 0xbfb8aa3b, v134
	v_exp_f32_e32 v134, v134
	s_waitcnt vmcnt(0) lgkmcnt(0)
	v_lshlrev_b32_e32 v157, 16, v226
	v_mul_f32_e32 v157, v165, v157
	v_add_f32_e32 v165, v31, v135
	v_mul_f32_e32 v165, 0xbfb8aa3b, v165
	v_exp_f32_e32 v165, v165
	v_and_b32_e32 v163, 0xffff0000, v226
	v_add_f32_e32 v135, v15, v135
	v_mul_f32_e32 v135, 0xbfb8aa3b, v135
	v_add_f32_e32 v165, 1.0, v165
	v_rcp_f32_e32 v165, v165
	v_exp_f32_e32 v135, v135
	v_add_f32_e32 v134, 1.0, v134
	v_rcp_f32_e32 v134, v134
	v_mul_f32_e32 v163, v165, v163
	v_add_f32_e32 v165, v32, v136
	v_mul_f32_e32 v165, 0xbfb8aa3b, v165
	v_exp_f32_e32 v165, v165
	v_cvt_pk_bf16_f32 v226, v157, v163
	v_lshlrev_b32_e32 v157, 16, v227
	v_and_b32_e32 v163, 0xffff0000, v227
	v_add_f32_e32 v165, 1.0, v165
	v_rcp_f32_e32 v165, v165
	v_add_f32_e32 v136, v16, v136
	v_mul_f32_e32 v136, 0xbfb8aa3b, v136
	v_exp_f32_e32 v136, v136
	v_mul_f32_e32 v157, v165, v157
	v_add_f32_e32 v165, v33, v137
	v_mul_f32_e32 v165, 0xbfb8aa3b, v165
	v_exp_f32_e32 v165, v165
	v_add_f32_e32 v135, 1.0, v135
	v_rcp_f32_e32 v135, v135
	v_add_f32_e32 v136, 1.0, v136
	v_add_f32_e32 v165, 1.0, v165
	v_rcp_f32_e32 v165, v165
	v_rcp_f32_e32 v136, v136
	v_mul_f32_e32 v163, v165, v163
	v_add_f32_e32 v165, v26, v130
	v_mul_f32_e32 v165, 0xbfb8aa3b, v165
	v_exp_f32_e32 v165, v165
	v_cvt_pk_bf16_f32 v227, v157, v163
	v_lshlrev_b32_e32 v157, 16, v228
	v_and_b32_e32 v163, 0xffff0000, v228
	v_add_f32_e32 v165, 1.0, v165
	v_rcp_f32_e32 v165, v165
	v_add_f32_e32 v130, v10, v130
	v_mul_f32_e32 v130, 0xbfb8aa3b, v130
	v_exp_f32_e32 v130, v130
	v_mul_f32_e32 v157, v165, v157
	v_add_f32_e32 v165, v27, v131
	v_mul_f32_e32 v165, 0xbfb8aa3b, v165
	v_exp_f32_e32 v165, v165
	v_add_f32_e32 v131, v11, v131
	v_mul_f32_e32 v131, 0xbfb8aa3b, v131
	v_exp_f32_e32 v131, v131
	v_add_f32_e32 v165, 1.0, v165
	v_rcp_f32_e32 v165, v165
	v_add_f32_e32 v130, 1.0, v130
	v_rcp_f32_e32 v130, v130
	v_add_f32_e32 v131, 1.0, v131
	v_mul_f32_e32 v163, v165, v163
	v_add_f32_e32 v165, v28, v132
	v_mul_f32_e32 v165, 0xbfb8aa3b, v165
	v_exp_f32_e32 v165, v165
	v_cvt_pk_bf16_f32 v228, v157, v163
	v_lshlrev_b32_e32 v157, 16, v229
	v_and_b32_e32 v163, 0xffff0000, v229
	v_add_f32_e32 v165, 1.0, v165
	v_rcp_f32_e32 v165, v165
	v_add_f32_e32 v132, v12, v132
	v_mul_f32_e32 v132, 0xbfb8aa3b, v132
	v_exp_f32_e32 v132, v132
	v_mul_f32_e32 v157, v165, v157
	v_add_f32_e32 v165, v29, v133
	v_mul_f32_e32 v165, 0xbfb8aa3b, v165
	v_exp_f32_e32 v165, v165
	v_rcp_f32_e32 v131, v131
	v_add_f32_e32 v132, 1.0, v132
	v_rcp_f32_e32 v132, v132
	v_add_f32_e32 v165, 1.0, v165
	v_rcp_f32_e32 v165, v165
	s_nop 0
	v_mul_f32_e32 v163, v165, v163
	v_cvt_pk_bf16_f32 v229, v157, v163
	global_store_dwordx4 v[202:203], v[226:229], off offset:1536
	v_add_u32_e32 v202, 0xb0, v156
	v_ashrrev_i32_e32 v203, 31, v202
	v_lshlrev_b64 v[226:227], 9, v[202:203]
	v_lshl_add_u64 v[198:199], v[198:199], 0, v[226:227]
	global_load_dwordx4 v[226:229], v[198:199], off
	s_waitcnt vmcnt(0) lgkmcnt(0)
	v_lshlrev_b32_e32 v157, 16, v226
	v_and_b32_e32 v161, 0xffff0000, v226
	v_mul_f32_e32 v134, v134, v157
	v_mul_f32_e32 v135, v135, v161
	v_cvt_pk_bf16_f32 v134, v134, v135
	v_lshlrev_b32_e32 v135, 16, v227
	v_mul_f32_e32 v135, v136, v135
	v_add_f32_e32 v136, v17, v137
	v_mul_f32_e32 v136, 0xbfb8aa3b, v136
	v_exp_f32_e32 v136, v136
	v_and_b32_e32 v157, 0xffff0000, v227
	v_and_b32_e32 v137, 0xffff0000, v228
	v_mul_f32_e32 v131, v131, v137
	v_add_f32_e32 v136, 1.0, v136
	v_rcp_f32_e32 v136, v136
	s_nop 0
	v_mul_f32_e32 v136, v136, v157
	v_cvt_pk_bf16_f32 v135, v135, v136
	v_lshlrev_b32_e32 v136, 16, v228
	v_mul_f32_e32 v130, v130, v136
	v_cvt_pk_bf16_f32 v136, v130, v131
	v_lshlrev_b32_e32 v130, 16, v229
	v_mul_f32_e32 v130, v132, v130
	v_add_f32_e32 v132, v13, v133
	v_mul_f32_e32 v132, 0xbfb8aa3b, v132
	v_exp_f32_e32 v132, v132
	v_and_b32_e32 v131, 0xffff0000, v229
	v_add_f32_e32 v132, 1.0, v132
	v_rcp_f32_e32 v132, v132
	s_nop 0
	v_mul_f32_e32 v131, v132, v131
	v_cvt_pk_bf16_f32 v137, v130, v131
	v_lshlrev_b64 v[130:131], 11, v[202:203]
	v_lshl_add_u64 v[130:131], s[52:53], 0, v[130:131]
	v_lshl_add_u64 v[130:131], v[130:131], 0, v[184:185]
	v_lshl_add_u64 v[184:185], v[130:131], 0, s[30:31]
	v_add_co_u32_e32 v130, vcc, s88, v130
	s_nop 1
	v_addc_co_u32_e32 v131, vcc, 0, v131, vcc
	global_store_dwordx4 v[130:131], v[134:137], off offset:1536
	global_load_dwordx4 v[134:137], v[138:139], off offset:512
	global_load_dwordx4 v[130:133], v[138:139], off offset:528
	s_nop 0
	global_load_dwordx4 v[138:141], v[140:141], off offset:256
	s_waitcnt vmcnt(0) lgkmcnt(0)
	v_add_f32_e32 v161, v118, v134
	v_mul_f32_e32 v161, 0xbfb8aa3b, v161
	v_exp_f32_e32 v161, v161
	v_lshlrev_b32_e32 v157, 16, v138
	v_and_b32_e32 v138, 0xffff0000, v138
	v_add_f32_e32 v161, 1.0, v161
	v_rcp_f32_e32 v161, v161
	s_nop 0
	v_mul_f32_e32 v157, v161, v157
	v_add_f32_e32 v161, v119, v135
	v_mul_f32_e32 v161, 0xbfb8aa3b, v161
	v_exp_f32_e32 v161, v161
	s_nop 0
	v_add_f32_e32 v161, 1.0, v161
	v_rcp_f32_e32 v161, v161
	s_nop 0
	v_mul_f32_e32 v138, v161, v138
	v_add_f32_e32 v161, v120, v136
	v_mul_f32_e32 v161, 0xbfb8aa3b, v161
	v_exp_f32_e32 v161, v161
	v_cvt_pk_bf16_f32 v138, v157, v138
	v_lshlrev_b32_e32 v157, 16, v139
	v_and_b32_e32 v139, 0xffff0000, v139
	v_add_f32_e32 v161, 1.0, v161
	v_rcp_f32_e32 v161, v161
	s_nop 0
	v_mul_f32_e32 v157, v161, v157
	v_add_f32_e32 v161, v121, v137
	v_mul_f32_e32 v161, 0xbfb8aa3b, v161
	v_exp_f32_e32 v161, v161
	s_nop 0
	v_add_f32_e32 v161, 1.0, v161
	v_rcp_f32_e32 v161, v161
	s_nop 0
	v_mul_f32_e32 v139, v161, v139
	v_add_f32_e32 v161, v114, v130
	v_mul_f32_e32 v161, 0xbfb8aa3b, v161
	v_exp_f32_e32 v161, v161
	v_cvt_pk_bf16_f32 v139, v157, v139
	v_lshlrev_b32_e32 v157, 16, v140
	v_and_b32_e32 v140, 0xffff0000, v140
	v_add_f32_e32 v161, 1.0, v161
	v_rcp_f32_e32 v161, v161
	s_nop 0
	v_mul_f32_e32 v157, v161, v157
	v_add_f32_e32 v161, v115, v131
	v_mul_f32_e32 v161, 0xbfb8aa3b, v161
	v_exp_f32_e32 v161, v161
	s_nop 0
	v_add_f32_e32 v161, 1.0, v161
	v_rcp_f32_e32 v161, v161
	s_nop 0
	v_mul_f32_e32 v140, v161, v140
	v_add_f32_e32 v161, v116, v132
	v_mul_f32_e32 v161, 0xbfb8aa3b, v161
	v_exp_f32_e32 v161, v161
	v_cvt_pk_bf16_f32 v140, v157, v140
	v_lshlrev_b32_e32 v157, 16, v141
	v_and_b32_e32 v141, 0xffff0000, v141
	v_add_f32_e32 v161, 1.0, v161
	v_rcp_f32_e32 v161, v161
	s_nop 0
	v_mul_f32_e32 v157, v161, v157
	v_add_f32_e32 v161, v117, v133
	v_mul_f32_e32 v161, 0xbfb8aa3b, v161
	v_exp_f32_e32 v161, v161
	s_nop 0
	v_add_f32_e32 v161, 1.0, v161
	v_rcp_f32_e32 v161, v161
	s_nop 0
	v_mul_f32_e32 v141, v161, v141
	v_cvt_pk_bf16_f32 v141, v157, v141
	global_store_dwordx4 v[172:173], v[138:141], off offset:256
	global_load_dwordx4 v[138:141], v[176:177], off offset:256
	v_add_f32_e32 v161, v102, v134
	v_mul_f32_e32 v161, 0xbfb8aa3b, v161
	v_exp_f32_e32 v161, v161
	s_waitcnt vmcnt(0) lgkmcnt(0)
	v_lshlrev_b32_e32 v157, 16, v138
	v_add_f32_e32 v161, 1.0, v161
	v_rcp_f32_e32 v161, v161
	v_and_b32_e32 v138, 0xffff0000, v138
	v_mul_f32_e32 v157, v161, v157
	v_add_f32_e32 v161, v103, v135
	v_mul_f32_e32 v161, 0xbfb8aa3b, v161
	v_exp_f32_e32 v161, v161
	s_nop 0
	v_add_f32_e32 v161, 1.0, v161
	v_rcp_f32_e32 v161, v161
	s_nop 0
	v_mul_f32_e32 v138, v161, v138
	v_add_f32_e32 v161, v104, v136
	v_mul_f32_e32 v161, 0xbfb8aa3b, v161
	v_exp_f32_e32 v161, v161
	v_cvt_pk_bf16_f32 v138, v157, v138
	v_lshlrev_b32_e32 v157, 16, v139
	v_and_b32_e32 v139, 0xffff0000, v139
	v_add_f32_e32 v161, 1.0, v161
	v_rcp_f32_e32 v161, v161
	s_nop 0
	v_mul_f32_e32 v157, v161, v157
	v_add_f32_e32 v161, v105, v137
	v_mul_f32_e32 v161, 0xbfb8aa3b, v161
	v_exp_f32_e32 v161, v161
	s_nop 0
	v_add_f32_e32 v161, 1.0, v161
	v_rcp_f32_e32 v161, v161
	s_nop 0
	v_mul_f32_e32 v139, v161, v139
	v_add_f32_e32 v161, v98, v130
	v_mul_f32_e32 v161, 0xbfb8aa3b, v161
	v_exp_f32_e32 v161, v161
	v_cvt_pk_bf16_f32 v139, v157, v139
	v_lshlrev_b32_e32 v157, 16, v140
	v_and_b32_e32 v140, 0xffff0000, v140
	v_add_f32_e32 v161, 1.0, v161
	v_rcp_f32_e32 v161, v161
	s_nop 0
	v_mul_f32_e32 v157, v161, v157
	v_add_f32_e32 v161, v99, v131
	v_mul_f32_e32 v161, 0xbfb8aa3b, v161
	v_exp_f32_e32 v161, v161
	s_nop 0
	v_add_f32_e32 v161, 1.0, v161
	v_rcp_f32_e32 v161, v161
	s_nop 0
	v_mul_f32_e32 v140, v161, v140
	v_add_f32_e32 v161, v100, v132
	v_mul_f32_e32 v161, 0xbfb8aa3b, v161
	v_exp_f32_e32 v161, v161
	v_cvt_pk_bf16_f32 v140, v157, v140
	v_lshlrev_b32_e32 v157, 16, v141
	v_and_b32_e32 v141, 0xffff0000, v141
	v_add_f32_e32 v161, 1.0, v161
	v_rcp_f32_e32 v161, v161
	s_nop 0
	v_mul_f32_e32 v157, v161, v157
	v_add_f32_e32 v161, v101, v133
	v_mul_f32_e32 v161, 0xbfb8aa3b, v161
	v_exp_f32_e32 v161, v161
	s_nop 0
	v_add_f32_e32 v161, 1.0, v161
	v_rcp_f32_e32 v161, v161
	s_nop 0
	v_mul_f32_e32 v141, v161, v141
	v_cvt_pk_bf16_f32 v141, v157, v141
	global_store_dwordx4 v[174:175], v[138:141], off offset:256
	global_load_dwordx4 v[138:141], v[180:181], off offset:256
	v_add_f32_e32 v161, v86, v134
	v_mul_f32_e32 v161, 0xbfb8aa3b, v161
	v_exp_f32_e32 v161, v161
	s_waitcnt vmcnt(0) lgkmcnt(0)
	v_lshlrev_b32_e32 v157, 16, v138
	v_add_f32_e32 v161, 1.0, v161
	v_rcp_f32_e32 v161, v161
	v_and_b32_e32 v138, 0xffff0000, v138
	v_mul_f32_e32 v157, v161, v157
	v_add_f32_e32 v161, v87, v135
	v_mul_f32_e32 v161, 0xbfb8aa3b, v161
	v_exp_f32_e32 v161, v161
	s_nop 0
	v_add_f32_e32 v161, 1.0, v161
	v_rcp_f32_e32 v161, v161
	s_nop 0
	v_mul_f32_e32 v138, v161, v138
	v_add_f32_e32 v161, v88, v136
	v_mul_f32_e32 v161, 0xbfb8aa3b, v161
	v_exp_f32_e32 v161, v161
	v_cvt_pk_bf16_f32 v138, v157, v138
	v_lshlrev_b32_e32 v157, 16, v139
	v_and_b32_e32 v139, 0xffff0000, v139
	v_add_f32_e32 v161, 1.0, v161
	v_rcp_f32_e32 v161, v161
	s_nop 0
	v_mul_f32_e32 v157, v161, v157
	v_add_f32_e32 v161, v89, v137
	v_mul_f32_e32 v161, 0xbfb8aa3b, v161
	v_exp_f32_e32 v161, v161
	s_nop 0
	v_add_f32_e32 v161, 1.0, v161
	v_rcp_f32_e32 v161, v161
	s_nop 0
	v_mul_f32_e32 v139, v161, v139
	v_add_f32_e32 v161, v82, v130
	v_mul_f32_e32 v161, 0xbfb8aa3b, v161
	v_exp_f32_e32 v161, v161
	v_cvt_pk_bf16_f32 v139, v157, v139
	v_lshlrev_b32_e32 v157, 16, v140
	v_and_b32_e32 v140, 0xffff0000, v140
	v_add_f32_e32 v161, 1.0, v161
	v_rcp_f32_e32 v161, v161
	s_nop 0
	v_mul_f32_e32 v157, v161, v157
	v_add_f32_e32 v161, v83, v131
	v_mul_f32_e32 v161, 0xbfb8aa3b, v161
	v_exp_f32_e32 v161, v161
	s_nop 0
	v_add_f32_e32 v161, 1.0, v161
	v_rcp_f32_e32 v161, v161
	s_nop 0
	v_mul_f32_e32 v140, v161, v140
	v_add_f32_e32 v161, v84, v132
	v_mul_f32_e32 v161, 0xbfb8aa3b, v161
	v_exp_f32_e32 v161, v161
	v_cvt_pk_bf16_f32 v140, v157, v140
	v_lshlrev_b32_e32 v157, 16, v141
	v_and_b32_e32 v141, 0xffff0000, v141
	v_add_f32_e32 v161, 1.0, v161
	v_rcp_f32_e32 v161, v161
	s_nop 0
	v_mul_f32_e32 v157, v161, v157
	v_add_f32_e32 v161, v85, v133
	v_mul_f32_e32 v161, 0xbfb8aa3b, v161
	v_exp_f32_e32 v161, v161
	s_nop 0
	v_add_f32_e32 v161, 1.0, v161
	v_rcp_f32_e32 v161, v161
	s_nop 0
	v_mul_f32_e32 v141, v161, v141
	v_cvt_pk_bf16_f32 v141, v157, v141
	global_store_dwordx4 v[178:179], v[138:141], off offset:256
	global_load_dwordx4 v[138:141], v[186:187], off offset:256
	v_add_f32_e32 v161, v70, v134
	v_mul_f32_e32 v161, 0xbfb8aa3b, v161
	v_exp_f32_e32 v161, v161
	s_waitcnt vmcnt(0) lgkmcnt(0)
	v_lshlrev_b32_e32 v157, 16, v138
	v_add_f32_e32 v161, 1.0, v161
	v_rcp_f32_e32 v161, v161
	v_and_b32_e32 v138, 0xffff0000, v138
	v_mul_f32_e32 v157, v161, v157
	v_add_f32_e32 v161, v71, v135
	v_mul_f32_e32 v161, 0xbfb8aa3b, v161
	v_exp_f32_e32 v161, v161
	s_nop 0
	v_add_f32_e32 v161, 1.0, v161
	v_rcp_f32_e32 v161, v161
	s_nop 0
	v_mul_f32_e32 v138, v161, v138
	v_add_f32_e32 v161, v72, v136
	v_mul_f32_e32 v161, 0xbfb8aa3b, v161
	v_exp_f32_e32 v161, v161
	v_cvt_pk_bf16_f32 v138, v157, v138
	v_lshlrev_b32_e32 v157, 16, v139
	v_and_b32_e32 v139, 0xffff0000, v139
	v_add_f32_e32 v161, 1.0, v161
	v_rcp_f32_e32 v161, v161
	s_nop 0
	v_mul_f32_e32 v157, v161, v157
	v_add_f32_e32 v161, v73, v137
	v_mul_f32_e32 v161, 0xbfb8aa3b, v161
	v_exp_f32_e32 v161, v161
	s_nop 0
	v_add_f32_e32 v161, 1.0, v161
	v_rcp_f32_e32 v161, v161
	s_nop 0
	v_mul_f32_e32 v139, v161, v139
	v_add_f32_e32 v161, v66, v130
	v_mul_f32_e32 v161, 0xbfb8aa3b, v161
	v_exp_f32_e32 v161, v161
	v_cvt_pk_bf16_f32 v139, v157, v139
	v_lshlrev_b32_e32 v157, 16, v140
	v_and_b32_e32 v140, 0xffff0000, v140
	v_add_f32_e32 v161, 1.0, v161
	v_rcp_f32_e32 v161, v161
	s_nop 0
	v_mul_f32_e32 v157, v161, v157
	v_add_f32_e32 v161, v67, v131
	v_mul_f32_e32 v161, 0xbfb8aa3b, v161
	v_exp_f32_e32 v161, v161
	s_nop 0
	v_add_f32_e32 v161, 1.0, v161
	v_rcp_f32_e32 v161, v161
	s_nop 0
	v_mul_f32_e32 v140, v161, v140
	v_add_f32_e32 v161, v68, v132
	v_mul_f32_e32 v161, 0xbfb8aa3b, v161
	v_exp_f32_e32 v161, v161
	v_cvt_pk_bf16_f32 v140, v157, v140
	v_lshlrev_b32_e32 v157, 16, v141
	v_and_b32_e32 v141, 0xffff0000, v141
	v_add_f32_e32 v161, 1.0, v161
	v_rcp_f32_e32 v161, v161
	s_nop 0
	v_mul_f32_e32 v157, v161, v157
	v_add_f32_e32 v161, v69, v133
	v_mul_f32_e32 v161, 0xbfb8aa3b, v161
	v_exp_f32_e32 v161, v161
	s_nop 0
	v_add_f32_e32 v161, 1.0, v161
	v_rcp_f32_e32 v161, v161
	s_nop 0
	v_mul_f32_e32 v141, v161, v141
	v_cvt_pk_bf16_f32 v141, v157, v141
	global_store_dwordx4 v[182:183], v[138:141], off offset:256
	global_load_dwordx4 v[138:141], v[190:191], off offset:256
	v_add_f32_e32 v161, v54, v134
	v_mul_f32_e32 v161, 0xbfb8aa3b, v161
	v_exp_f32_e32 v161, v161
	s_waitcnt vmcnt(0) lgkmcnt(0)
	v_lshlrev_b32_e32 v157, 16, v138
	v_add_f32_e32 v161, 1.0, v161
	v_rcp_f32_e32 v161, v161
	v_and_b32_e32 v138, 0xffff0000, v138
	v_mul_f32_e32 v157, v161, v157
	v_add_f32_e32 v161, v55, v135
	v_mul_f32_e32 v161, 0xbfb8aa3b, v161
	v_exp_f32_e32 v161, v161
	s_nop 0
	v_add_f32_e32 v161, 1.0, v161
	v_rcp_f32_e32 v161, v161
	s_nop 0
	v_mul_f32_e32 v138, v161, v138
	v_add_f32_e32 v161, v56, v136
	v_mul_f32_e32 v161, 0xbfb8aa3b, v161
	v_exp_f32_e32 v161, v161
	v_cvt_pk_bf16_f32 v138, v157, v138
	v_lshlrev_b32_e32 v157, 16, v139
	v_and_b32_e32 v139, 0xffff0000, v139
	v_add_f32_e32 v161, 1.0, v161
	v_rcp_f32_e32 v161, v161
	s_nop 0
	v_mul_f32_e32 v157, v161, v157
	v_add_f32_e32 v161, v57, v137
	v_mul_f32_e32 v161, 0xbfb8aa3b, v161
	v_exp_f32_e32 v161, v161
	s_nop 0
	v_add_f32_e32 v161, 1.0, v161
	v_rcp_f32_e32 v161, v161
	s_nop 0
	v_mul_f32_e32 v139, v161, v139
	v_add_f32_e32 v161, v50, v130
	v_mul_f32_e32 v161, 0xbfb8aa3b, v161
	v_exp_f32_e32 v161, v161
	v_cvt_pk_bf16_f32 v139, v157, v139
	v_lshlrev_b32_e32 v157, 16, v140
	v_and_b32_e32 v140, 0xffff0000, v140
	v_add_f32_e32 v161, 1.0, v161
	v_rcp_f32_e32 v161, v161
	s_nop 0
	v_mul_f32_e32 v157, v161, v157
	v_add_f32_e32 v161, v51, v131
	v_mul_f32_e32 v161, 0xbfb8aa3b, v161
	v_exp_f32_e32 v161, v161
	s_nop 0
	v_add_f32_e32 v161, 1.0, v161
	v_rcp_f32_e32 v161, v161
	s_nop 0
	v_mul_f32_e32 v140, v161, v140
	v_add_f32_e32 v161, v52, v132
	v_mul_f32_e32 v161, 0xbfb8aa3b, v161
	v_exp_f32_e32 v161, v161
	v_cvt_pk_bf16_f32 v140, v157, v140
	v_lshlrev_b32_e32 v157, 16, v141
	v_and_b32_e32 v141, 0xffff0000, v141
	v_add_f32_e32 v161, 1.0, v161
	v_rcp_f32_e32 v161, v161
	s_nop 0
	v_mul_f32_e32 v157, v161, v157
	v_add_f32_e32 v161, v53, v133
	v_mul_f32_e32 v161, 0xbfb8aa3b, v161
	v_exp_f32_e32 v161, v161
	s_nop 0
	v_add_f32_e32 v161, 1.0, v161
	v_rcp_f32_e32 v161, v161
	s_nop 0
	v_mul_f32_e32 v141, v161, v141
	v_cvt_pk_bf16_f32 v141, v157, v141
	global_store_dwordx4 v[188:189], v[138:141], off offset:256
	global_load_dwordx4 v[138:141], v[194:195], off offset:256
	v_add_f32_e32 v161, v38, v134
	v_mul_f32_e32 v161, 0xbfb8aa3b, v161
	v_exp_f32_e32 v161, v161
	s_waitcnt vmcnt(0) lgkmcnt(0)
	v_lshlrev_b32_e32 v157, 16, v138
	v_add_f32_e32 v161, 1.0, v161
	v_rcp_f32_e32 v161, v161
	v_and_b32_e32 v138, 0xffff0000, v138
	v_mul_f32_e32 v157, v161, v157
	v_add_f32_e32 v161, v39, v135
	v_mul_f32_e32 v161, 0xbfb8aa3b, v161
	v_exp_f32_e32 v161, v161
	s_nop 0
	v_add_f32_e32 v161, 1.0, v161
	v_rcp_f32_e32 v161, v161
	s_nop 0
	v_mul_f32_e32 v138, v161, v138
	v_add_f32_e32 v161, v40, v136
	v_mul_f32_e32 v161, 0xbfb8aa3b, v161
	v_exp_f32_e32 v161, v161
	v_cvt_pk_bf16_f32 v138, v157, v138
	v_lshlrev_b32_e32 v157, 16, v139
	v_and_b32_e32 v139, 0xffff0000, v139
	v_add_f32_e32 v161, 1.0, v161
	v_rcp_f32_e32 v161, v161
	s_nop 0
	v_mul_f32_e32 v157, v161, v157
	v_add_f32_e32 v161, v41, v137
	v_mul_f32_e32 v161, 0xbfb8aa3b, v161
	v_exp_f32_e32 v161, v161
	s_nop 0
	v_add_f32_e32 v161, 1.0, v161
	v_rcp_f32_e32 v161, v161
	s_nop 0
	v_mul_f32_e32 v139, v161, v139
	v_add_f32_e32 v161, v34, v130
	v_mul_f32_e32 v161, 0xbfb8aa3b, v161
	v_exp_f32_e32 v161, v161
	v_cvt_pk_bf16_f32 v139, v157, v139
	v_lshlrev_b32_e32 v157, 16, v140
	v_and_b32_e32 v140, 0xffff0000, v140
	v_add_f32_e32 v161, 1.0, v161
	v_rcp_f32_e32 v161, v161
	s_nop 0
	v_mul_f32_e32 v157, v161, v157
	v_add_f32_e32 v161, v35, v131
	v_mul_f32_e32 v161, 0xbfb8aa3b, v161
	v_exp_f32_e32 v161, v161
	s_nop 0
	v_add_f32_e32 v161, 1.0, v161
	v_rcp_f32_e32 v161, v161
	s_nop 0
	v_mul_f32_e32 v140, v161, v140
	v_add_f32_e32 v161, v36, v132
	v_mul_f32_e32 v161, 0xbfb8aa3b, v161
	v_exp_f32_e32 v161, v161
	v_cvt_pk_bf16_f32 v140, v157, v140
	v_lshlrev_b32_e32 v157, 16, v141
	v_and_b32_e32 v141, 0xffff0000, v141
	v_add_f32_e32 v161, 1.0, v161
	v_rcp_f32_e32 v161, v161
	s_nop 0
	v_mul_f32_e32 v157, v161, v157
	v_add_f32_e32 v161, v37, v133
	v_mul_f32_e32 v161, 0xbfb8aa3b, v161
	v_exp_f32_e32 v161, v161
	s_nop 0
	v_add_f32_e32 v161, 1.0, v161
	v_rcp_f32_e32 v161, v161
	s_nop 0
	v_mul_f32_e32 v141, v161, v141
	v_cvt_pk_bf16_f32 v141, v157, v141
	global_store_dwordx4 v[192:193], v[138:141], off offset:256
	global_load_dwordx4 v[138:141], v[200:201], off offset:256
	v_add_f32_e32 v161, v22, v134
	v_mul_f32_e32 v161, 0xbfb8aa3b, v161
	v_exp_f32_e32 v161, v161
	v_add_f32_e32 v134, v6, v134
	v_mul_f32_e32 v134, 0xbfb8aa3b, v134
	v_exp_f32_e32 v134, v134
	v_add_f32_e32 v161, 1.0, v161
	v_rcp_f32_e32 v161, v161
	v_add_f32_e32 v134, 1.0, v134
	v_rcp_f32_e32 v134, v134
	s_waitcnt vmcnt(0) lgkmcnt(0)
	v_lshlrev_b32_e32 v157, 16, v138
	v_mul_f32_e32 v157, v161, v157
	v_add_f32_e32 v161, v23, v135
	v_mul_f32_e32 v161, 0xbfb8aa3b, v161
	v_exp_f32_e32 v161, v161
	v_and_b32_e32 v138, 0xffff0000, v138
	v_add_f32_e32 v135, v7, v135
	v_mul_f32_e32 v135, 0xbfb8aa3b, v135
	v_add_f32_e32 v161, 1.0, v161
	v_rcp_f32_e32 v161, v161
	v_exp_f32_e32 v135, v135
	v_mul_f32_e32 v138, v161, v138
	v_add_f32_e32 v161, v24, v136
	v_mul_f32_e32 v161, 0xbfb8aa3b, v161
	v_exp_f32_e32 v161, v161
	v_cvt_pk_bf16_f32 v138, v157, v138
	v_lshlrev_b32_e32 v157, 16, v139
	v_and_b32_e32 v139, 0xffff0000, v139
	v_add_f32_e32 v161, 1.0, v161
	v_rcp_f32_e32 v161, v161
	v_add_f32_e32 v136, v8, v136
	v_mul_f32_e32 v136, 0xbfb8aa3b, v136
	v_exp_f32_e32 v136, v136
	v_mul_f32_e32 v157, v161, v157
	v_add_f32_e32 v161, v25, v137
	v_mul_f32_e32 v161, 0xbfb8aa3b, v161
	v_exp_f32_e32 v161, v161
	v_add_f32_e32 v135, 1.0, v135
	v_rcp_f32_e32 v135, v135
	v_add_f32_e32 v136, 1.0, v136
	v_add_f32_e32 v161, 1.0, v161
	v_rcp_f32_e32 v161, v161
	v_rcp_f32_e32 v136, v136
	v_mul_f32_e32 v139, v161, v139
	v_add_f32_e32 v161, v18, v130
	v_mul_f32_e32 v161, 0xbfb8aa3b, v161
	v_exp_f32_e32 v161, v161
	v_cvt_pk_bf16_f32 v139, v157, v139
	v_lshlrev_b32_e32 v157, 16, v140
	v_and_b32_e32 v140, 0xffff0000, v140
	v_add_f32_e32 v161, 1.0, v161
	v_rcp_f32_e32 v161, v161
	v_add_f32_e32 v130, v2, v130
	v_mul_f32_e32 v130, 0xbfb8aa3b, v130
	v_exp_f32_e32 v130, v130
	v_mul_f32_e32 v157, v161, v157
	v_add_f32_e32 v161, v19, v131
	v_mul_f32_e32 v161, 0xbfb8aa3b, v161
	v_exp_f32_e32 v161, v161
	v_add_f32_e32 v131, v3, v131
	v_mul_f32_e32 v131, 0xbfb8aa3b, v131
	v_exp_f32_e32 v131, v131
	v_add_f32_e32 v161, 1.0, v161
	v_rcp_f32_e32 v161, v161
	v_add_f32_e32 v130, 1.0, v130
	v_rcp_f32_e32 v130, v130
	v_add_f32_e32 v131, 1.0, v131
	v_mul_f32_e32 v140, v161, v140
	v_add_f32_e32 v161, v20, v132
	v_mul_f32_e32 v161, 0xbfb8aa3b, v161
	v_exp_f32_e32 v161, v161
	v_cvt_pk_bf16_f32 v140, v157, v140
	v_lshlrev_b32_e32 v157, 16, v141
	v_and_b32_e32 v141, 0xffff0000, v141
	v_add_f32_e32 v161, 1.0, v161
	v_rcp_f32_e32 v161, v161
	v_add_f32_e32 v132, v4, v132
	v_mul_f32_e32 v132, 0xbfb8aa3b, v132
	v_exp_f32_e32 v132, v132
	v_mul_f32_e32 v157, v161, v157
	v_add_f32_e32 v161, v21, v133
	v_mul_f32_e32 v161, 0xbfb8aa3b, v161
	v_exp_f32_e32 v161, v161
	v_rcp_f32_e32 v131, v131
	v_add_f32_e32 v132, 1.0, v132
	v_rcp_f32_e32 v132, v132
	v_add_f32_e32 v161, 1.0, v161
	v_rcp_f32_e32 v161, v161
	s_nop 0
	v_mul_f32_e32 v141, v161, v141
	v_cvt_pk_bf16_f32 v141, v157, v141
	global_store_dwordx4 v[196:197], v[138:141], off offset:256
	global_load_dwordx4 v[138:141], v[198:199], off offset:256
	s_waitcnt vmcnt(0) lgkmcnt(0)
	v_lshlrev_b32_e32 v157, 16, v138
	v_and_b32_e32 v138, 0xffff0000, v138
	v_mul_f32_e32 v134, v134, v157
	v_mul_f32_e32 v135, v135, v138
	v_cvt_pk_bf16_f32 v134, v134, v135
	v_lshlrev_b32_e32 v135, 16, v139
	v_mul_f32_e32 v135, v136, v135
	v_add_f32_e32 v136, v9, v137
	v_mul_f32_e32 v136, 0xbfb8aa3b, v136
	v_exp_f32_e32 v136, v136
	v_and_b32_e32 v138, 0xffff0000, v139
	v_and_b32_e32 v137, 0xffff0000, v140
	v_mul_f32_e32 v131, v131, v137
	v_add_f32_e32 v136, 1.0, v136
	v_rcp_f32_e32 v136, v136
	s_nop 0
	v_mul_f32_e32 v136, v136, v138
	v_cvt_pk_bf16_f32 v135, v135, v136
	v_lshlrev_b32_e32 v136, 16, v140
	v_mul_f32_e32 v130, v130, v136
	v_cvt_pk_bf16_f32 v136, v130, v131
	v_lshlrev_b32_e32 v130, 16, v141
	v_mul_f32_e32 v130, v132, v130
	v_add_f32_e32 v132, v5, v133
	v_mul_f32_e32 v132, 0xbfb8aa3b, v132
	v_exp_f32_e32 v132, v132
	v_and_b32_e32 v131, 0xffff0000, v141
	v_add_f32_e32 v132, 1.0, v132
	v_rcp_f32_e32 v132, v132
	s_nop 0
	v_mul_f32_e32 v131, v132, v131
	v_cvt_pk_bf16_f32 v137, v130, v131
	global_store_dwordx4 v[184:185], v[134:137], off offset:256

.LBB0_717:
	s_nop 0
	v_lshl_add_u64 v[130:131], v[158:159], 1, s[10:11]
	s_mov_b64 s[10:11], 0xe000000
	v_lshl_add_u64 v[130:131], v[130:131], 0, s[10:11]
	v_mad_i64_i32 v[132:133], s[10:11], s63, v156, 0
	v_lshl_add_u64 v[132:133], v[132:133], 1, v[130:131]
	s_and_b64 vcc, exec, s[38:39]
	v_cvt_pk_bf16_f32 v126, v126, v127
	v_cvt_pk_bf16_f32 v127, v128, v129
	v_cvt_pk_bf16_f32 v128, v122, v123
	v_cvt_pk_bf16_f32 v129, v124, v125
	global_store_dwordx4 v[132:133], v[126:129], off
	s_cbranch_vccnz .LBB0_719
	v_max_f32_e32 v118, v118, v118
	v_max_f32_e32 v114, v114, v114
	v_max_f32_e32 v119, v119, v119
	v_max_f32_e32 v115, v115, v115
	v_max_f32_e32 v120, v120, v120
	v_max_f32_e32 v116, v116, v116
	v_max_f32_e32 v121, v121, v121
	v_max_f32_e32 v117, v117, v117
	v_max_f32_e32 v118, 0, v118
	v_max_f32_e32 v114, 0, v114
	v_max_f32_e32 v119, 0, v119
	v_max_f32_e32 v115, 0, v115
	v_max_f32_e32 v120, 0, v120
	v_max_f32_e32 v116, 0, v116
	v_max_f32_e32 v121, 0, v121
	v_max_f32_e32 v117, 0, v117
	v_mul_f32_e32 v118, v118, v118
	v_mul_f32_e32 v114, v114, v114
	v_mul_f32_e32 v119, v119, v119
	v_mul_f32_e32 v115, v115, v115
	v_mul_f32_e32 v120, v120, v120
	v_mul_f32_e32 v116, v116, v116
	v_mul_f32_e32 v121, v121, v121
	v_mul_f32_e32 v117, v117, v117
.LBB0_719:
	s_and_b64 vcc, exec, s[38:39]
	v_cvt_pk_bf16_f32 v118, v118, v119
	v_cvt_pk_bf16_f32 v119, v120, v121
	v_cvt_pk_bf16_f32 v120, v114, v115
	v_cvt_pk_bf16_f32 v121, v116, v117
	global_store_dwordx4 v[132:133], v[118:121], off offset:256
	s_cbranch_vccnz .LBB0_721
	v_max_f32_e32 v110, v110, v110
	v_max_f32_e32 v106, v106, v106
	v_max_f32_e32 v111, v111, v111
	v_max_f32_e32 v107, v107, v107
	v_max_f32_e32 v112, v112, v112
	v_max_f32_e32 v108, v108, v108
	v_max_f32_e32 v113, v113, v113
	v_max_f32_e32 v109, v109, v109
	v_max_f32_e32 v110, 0, v110
	v_max_f32_e32 v106, 0, v106
	v_max_f32_e32 v111, 0, v111
	v_max_f32_e32 v107, 0, v107
	v_max_f32_e32 v112, 0, v112
	v_max_f32_e32 v108, 0, v108
	v_max_f32_e32 v113, 0, v113
	v_max_f32_e32 v109, 0, v109
	v_mul_f32_e32 v110, v110, v110
	v_mul_f32_e32 v106, v106, v106
	v_mul_f32_e32 v111, v111, v111
	v_mul_f32_e32 v107, v107, v107
	v_mul_f32_e32 v112, v112, v112
	v_mul_f32_e32 v108, v108, v108
	v_mul_f32_e32 v113, v113, v113
	v_mul_f32_e32 v109, v109, v109
.LBB0_721:
	v_mad_i64_i32 v[114:115], s[10:11], s63, v170, 0
	v_lshl_add_u64 v[114:115], v[114:115], 1, v[130:131]
	s_and_b64 vcc, exec, s[38:39]
	v_cvt_pk_bf16_f32 v110, v110, v111
	v_cvt_pk_bf16_f32 v111, v112, v113
	v_cvt_pk_bf16_f32 v112, v106, v107
	v_cvt_pk_bf16_f32 v113, v108, v109
	global_store_dwordx4 v[114:115], v[110:113], off
	s_cbranch_vccnz .LBB0_723
	v_max_f32_e32 v102, v102, v102
	v_max_f32_e32 v98, v98, v98
	v_max_f32_e32 v103, v103, v103
	v_max_f32_e32 v99, v99, v99
	v_max_f32_e32 v104, v104, v104
	v_max_f32_e32 v100, v100, v100
	v_max_f32_e32 v105, v105, v105
	v_max_f32_e32 v101, v101, v101
	v_max_f32_e32 v102, 0, v102
	v_max_f32_e32 v98, 0, v98
	v_max_f32_e32 v103, 0, v103
	v_max_f32_e32 v99, 0, v99
	v_max_f32_e32 v104, 0, v104
	v_max_f32_e32 v100, 0, v100
	v_max_f32_e32 v105, 0, v105
	v_max_f32_e32 v101, 0, v101
	v_mul_f32_e32 v102, v102, v102
	v_mul_f32_e32 v98, v98, v98
	v_mul_f32_e32 v103, v103, v103
	v_mul_f32_e32 v99, v99, v99
	v_mul_f32_e32 v104, v104, v104
	v_mul_f32_e32 v100, v100, v100
	v_mul_f32_e32 v105, v105, v105
	v_mul_f32_e32 v101, v101, v101
.LBB0_723:
	s_and_b64 vcc, exec, s[38:39]
	v_cvt_pk_bf16_f32 v102, v102, v103
	v_cvt_pk_bf16_f32 v103, v104, v105
	v_cvt_pk_bf16_f32 v104, v98, v99
	v_cvt_pk_bf16_f32 v105, v100, v101
	global_store_dwordx4 v[114:115], v[102:105], off offset:256
	s_cbranch_vccnz .LBB0_725
	v_max_f32_e32 v94, v94, v94
	v_max_f32_e32 v90, v90, v90
	v_max_f32_e32 v95, v95, v95
	v_max_f32_e32 v91, v91, v91
	v_max_f32_e32 v96, v96, v96
	v_max_f32_e32 v92, v92, v92
	v_max_f32_e32 v97, v97, v97
	v_max_f32_e32 v93, v93, v93
	v_max_f32_e32 v94, 0, v94
	v_max_f32_e32 v90, 0, v90
	v_max_f32_e32 v95, 0, v95
	v_max_f32_e32 v91, 0, v91
	v_max_f32_e32 v96, 0, v96
	v_max_f32_e32 v92, 0, v92
	v_max_f32_e32 v97, 0, v97
	v_max_f32_e32 v93, 0, v93
	v_mul_f32_e32 v94, v94, v94
	v_mul_f32_e32 v90, v90, v90
	v_mul_f32_e32 v95, v95, v95
	v_mul_f32_e32 v91, v91, v91
	v_mul_f32_e32 v96, v96, v96
	v_mul_f32_e32 v92, v92, v92
	v_mul_f32_e32 v97, v97, v97
	v_mul_f32_e32 v93, v93, v93
.LBB0_725:
	v_mad_i64_i32 v[98:99], s[10:11], s63, v168, 0
	v_lshl_add_u64 v[98:99], v[98:99], 1, v[130:131]
	s_and_b64 vcc, exec, s[38:39]
	v_cvt_pk_bf16_f32 v94, v94, v95
	v_cvt_pk_bf16_f32 v95, v96, v97
	v_cvt_pk_bf16_f32 v96, v90, v91
	v_cvt_pk_bf16_f32 v97, v92, v93
	global_store_dwordx4 v[98:99], v[94:97], off
	s_cbranch_vccnz .LBB0_727
	v_max_f32_e32 v86, v86, v86
	v_max_f32_e32 v82, v82, v82
	v_max_f32_e32 v87, v87, v87
	v_max_f32_e32 v83, v83, v83
	v_max_f32_e32 v88, v88, v88
	v_max_f32_e32 v84, v84, v84
	v_max_f32_e32 v89, v89, v89
	v_max_f32_e32 v85, v85, v85
	v_max_f32_e32 v86, 0, v86
	v_max_f32_e32 v82, 0, v82
	v_max_f32_e32 v87, 0, v87
	v_max_f32_e32 v83, 0, v83
	v_max_f32_e32 v88, 0, v88
	v_max_f32_e32 v84, 0, v84
	v_max_f32_e32 v89, 0, v89
	v_max_f32_e32 v85, 0, v85
	v_mul_f32_e32 v86, v86, v86
	v_mul_f32_e32 v82, v82, v82
	v_mul_f32_e32 v87, v87, v87
	v_mul_f32_e32 v83, v83, v83
	v_mul_f32_e32 v88, v88, v88
	v_mul_f32_e32 v84, v84, v84
	v_mul_f32_e32 v89, v89, v89
	v_mul_f32_e32 v85, v85, v85
.LBB0_727:
	s_and_b64 vcc, exec, s[38:39]
	v_cvt_pk_bf16_f32 v86, v86, v87
	v_cvt_pk_bf16_f32 v87, v88, v89
	v_cvt_pk_bf16_f32 v88, v82, v83
	v_cvt_pk_bf16_f32 v89, v84, v85
	global_store_dwordx4 v[98:99], v[86:89], off offset:256
	s_cbranch_vccnz .LBB0_729
	v_max_f32_e32 v78, v78, v78
	v_max_f32_e32 v74, v74, v74
	v_max_f32_e32 v79, v79, v79
	v_max_f32_e32 v75, v75, v75
	v_max_f32_e32 v80, v80, v80
	v_max_f32_e32 v76, v76, v76
	v_max_f32_e32 v81, v81, v81
	v_max_f32_e32 v77, v77, v77
	v_max_f32_e32 v78, 0, v78
	v_max_f32_e32 v74, 0, v74
	v_max_f32_e32 v79, 0, v79
	v_max_f32_e32 v75, 0, v75
	v_max_f32_e32 v80, 0, v80
	v_max_f32_e32 v76, 0, v76
	v_max_f32_e32 v81, 0, v81
	v_max_f32_e32 v77, 0, v77
	v_mul_f32_e32 v78, v78, v78
	v_mul_f32_e32 v74, v74, v74
	v_mul_f32_e32 v79, v79, v79
	v_mul_f32_e32 v75, v75, v75
	v_mul_f32_e32 v80, v80, v80
	v_mul_f32_e32 v76, v76, v76
	v_mul_f32_e32 v81, v81, v81
	v_mul_f32_e32 v77, v77, v77
.LBB0_729:
	v_mad_i64_i32 v[82:83], s[10:11], s63, v166, 0
	v_lshl_add_u64 v[82:83], v[82:83], 1, v[130:131]
	s_and_b64 vcc, exec, s[38:39]
	v_cvt_pk_bf16_f32 v78, v78, v79
	v_cvt_pk_bf16_f32 v79, v80, v81
	v_cvt_pk_bf16_f32 v80, v74, v75
	v_cvt_pk_bf16_f32 v81, v76, v77
	global_store_dwordx4 v[82:83], v[78:81], off
	s_cbranch_vccnz .LBB0_731
	v_max_f32_e32 v70, v70, v70
	v_max_f32_e32 v66, v66, v66
	v_max_f32_e32 v71, v71, v71
	v_max_f32_e32 v67, v67, v67
	v_max_f32_e32 v72, v72, v72
	v_max_f32_e32 v68, v68, v68
	v_max_f32_e32 v73, v73, v73
	v_max_f32_e32 v69, v69, v69
	v_max_f32_e32 v70, 0, v70
	v_max_f32_e32 v66, 0, v66
	v_max_f32_e32 v71, 0, v71
	v_max_f32_e32 v67, 0, v67
	v_max_f32_e32 v72, 0, v72
	v_max_f32_e32 v68, 0, v68
	v_max_f32_e32 v73, 0, v73
	v_max_f32_e32 v69, 0, v69
	v_mul_f32_e32 v70, v70, v70
	v_mul_f32_e32 v66, v66, v66
	v_mul_f32_e32 v71, v71, v71
	v_mul_f32_e32 v67, v67, v67
	v_mul_f32_e32 v72, v72, v72
	v_mul_f32_e32 v68, v68, v68
	v_mul_f32_e32 v73, v73, v73
	v_mul_f32_e32 v69, v69, v69
.LBB0_731:
	s_and_b64 vcc, exec, s[38:39]
	v_cvt_pk_bf16_f32 v70, v70, v71
	v_cvt_pk_bf16_f32 v71, v72, v73
	v_cvt_pk_bf16_f32 v72, v66, v67
	v_cvt_pk_bf16_f32 v73, v68, v69
	global_store_dwordx4 v[82:83], v[70:73], off offset:256
	s_cbranch_vccnz .LBB0_733
	v_max_f32_e32 v62, v62, v62
	v_max_f32_e32 v58, v58, v58
	v_max_f32_e32 v63, v63, v63
	v_max_f32_e32 v59, v59, v59
	v_max_f32_e32 v64, v64, v64
	v_max_f32_e32 v60, v60, v60
	v_max_f32_e32 v65, v65, v65
	v_max_f32_e32 v61, v61, v61
	v_max_f32_e32 v62, 0, v62
	v_max_f32_e32 v58, 0, v58
	v_max_f32_e32 v63, 0, v63
	v_max_f32_e32 v59, 0, v59
	v_max_f32_e32 v64, 0, v64
	v_max_f32_e32 v60, 0, v60
	v_max_f32_e32 v65, 0, v65
	v_max_f32_e32 v61, 0, v61
	v_mul_f32_e32 v62, v62, v62
	v_mul_f32_e32 v58, v58, v58
	v_mul_f32_e32 v63, v63, v63
	v_mul_f32_e32 v59, v59, v59
	v_mul_f32_e32 v64, v64, v64
	v_mul_f32_e32 v60, v60, v60
	v_mul_f32_e32 v65, v65, v65
	v_mul_f32_e32 v61, v61, v61
.LBB0_733:
	v_mad_i64_i32 v[66:67], s[10:11], s63, v164, 0
	v_lshl_add_u64 v[66:67], v[66:67], 1, v[130:131]
	s_and_b64 vcc, exec, s[38:39]
	v_cvt_pk_bf16_f32 v62, v62, v63
	v_cvt_pk_bf16_f32 v63, v64, v65
	v_cvt_pk_bf16_f32 v64, v58, v59
	v_cvt_pk_bf16_f32 v65, v60, v61
	global_store_dwordx4 v[66:67], v[62:65], off
	s_cbranch_vccnz .LBB0_735
	v_max_f32_e32 v54, v54, v54
	v_max_f32_e32 v50, v50, v50
	v_max_f32_e32 v55, v55, v55
	v_max_f32_e32 v51, v51, v51
	v_max_f32_e32 v56, v56, v56
	v_max_f32_e32 v52, v52, v52
	v_max_f32_e32 v57, v57, v57
	v_max_f32_e32 v53, v53, v53
	v_max_f32_e32 v54, 0, v54
	v_max_f32_e32 v50, 0, v50
	v_max_f32_e32 v55, 0, v55
	v_max_f32_e32 v51, 0, v51
	v_max_f32_e32 v56, 0, v56
	v_max_f32_e32 v52, 0, v52
	v_max_f32_e32 v57, 0, v57
	v_max_f32_e32 v53, 0, v53
	v_mul_f32_e32 v54, v54, v54
	v_mul_f32_e32 v50, v50, v50
	v_mul_f32_e32 v55, v55, v55
	v_mul_f32_e32 v51, v51, v51
	v_mul_f32_e32 v56, v56, v56
	v_mul_f32_e32 v52, v52, v52
	v_mul_f32_e32 v57, v57, v57
	v_mul_f32_e32 v53, v53, v53
.LBB0_735:
	s_and_b64 vcc, exec, s[38:39]
	v_cvt_pk_bf16_f32 v54, v54, v55
	v_cvt_pk_bf16_f32 v55, v56, v57
	v_cvt_pk_bf16_f32 v56, v50, v51
	v_cvt_pk_bf16_f32 v57, v52, v53
	global_store_dwordx4 v[66:67], v[54:57], off offset:256
	s_cbranch_vccnz .LBB0_737
	v_max_f32_e32 v46, v46, v46
	v_max_f32_e32 v42, v42, v42
	v_max_f32_e32 v47, v47, v47
	v_max_f32_e32 v43, v43, v43
	v_max_f32_e32 v48, v48, v48
	v_max_f32_e32 v44, v44, v44
	v_max_f32_e32 v49, v49, v49
	v_max_f32_e32 v45, v45, v45
	v_max_f32_e32 v46, 0, v46
	v_max_f32_e32 v42, 0, v42
	v_max_f32_e32 v47, 0, v47
	v_max_f32_e32 v43, 0, v43
	v_max_f32_e32 v48, 0, v48
	v_max_f32_e32 v44, 0, v44
	v_max_f32_e32 v49, 0, v49
	v_max_f32_e32 v45, 0, v45
	v_mul_f32_e32 v46, v46, v46
	v_mul_f32_e32 v42, v42, v42
	v_mul_f32_e32 v47, v47, v47
	v_mul_f32_e32 v43, v43, v43
	v_mul_f32_e32 v48, v48, v48
	v_mul_f32_e32 v44, v44, v44
	v_mul_f32_e32 v49, v49, v49
	v_mul_f32_e32 v45, v45, v45
.LBB0_737:
	v_mad_i64_i32 v[50:51], s[10:11], s63, v162, 0
	v_lshl_add_u64 v[50:51], v[50:51], 1, v[130:131]
	s_and_b64 vcc, exec, s[38:39]
	v_cvt_pk_bf16_f32 v46, v46, v47
	v_cvt_pk_bf16_f32 v47, v48, v49
	v_cvt_pk_bf16_f32 v48, v42, v43
	v_cvt_pk_bf16_f32 v49, v44, v45
	global_store_dwordx4 v[50:51], v[46:49], off
	s_cbranch_vccnz .LBB0_739
	v_max_f32_e32 v38, v38, v38
	v_max_f32_e32 v34, v34, v34
	v_max_f32_e32 v39, v39, v39
	v_max_f32_e32 v35, v35, v35
	v_max_f32_e32 v40, v40, v40
	v_max_f32_e32 v36, v36, v36
	v_max_f32_e32 v41, v41, v41
	v_max_f32_e32 v37, v37, v37
	v_max_f32_e32 v38, 0, v38
	v_max_f32_e32 v34, 0, v34
	v_max_f32_e32 v39, 0, v39
	v_max_f32_e32 v35, 0, v35
	v_max_f32_e32 v40, 0, v40
	v_max_f32_e32 v36, 0, v36
	v_max_f32_e32 v41, 0, v41
	v_max_f32_e32 v37, 0, v37
	v_mul_f32_e32 v38, v38, v38
	v_mul_f32_e32 v34, v34, v34
	v_mul_f32_e32 v39, v39, v39
	v_mul_f32_e32 v35, v35, v35
	v_mul_f32_e32 v40, v40, v40
	v_mul_f32_e32 v36, v36, v36
	v_mul_f32_e32 v41, v41, v41
	v_mul_f32_e32 v37, v37, v37
.LBB0_739:
	s_and_b64 vcc, exec, s[38:39]
	v_cvt_pk_bf16_f32 v38, v38, v39
	v_cvt_pk_bf16_f32 v39, v40, v41
	v_cvt_pk_bf16_f32 v40, v34, v35
	v_cvt_pk_bf16_f32 v41, v36, v37
	global_store_dwordx4 v[50:51], v[38:41], off offset:256
	s_cbranch_vccnz .LBB0_741
	v_max_f32_e32 v30, v30, v30
	v_max_f32_e32 v26, v26, v26
	v_max_f32_e32 v31, v31, v31
	v_max_f32_e32 v27, v27, v27
	v_max_f32_e32 v32, v32, v32
	v_max_f32_e32 v28, v28, v28
	v_max_f32_e32 v33, v33, v33
	v_max_f32_e32 v29, v29, v29
	v_max_f32_e32 v30, 0, v30
	v_max_f32_e32 v26, 0, v26
	v_max_f32_e32 v31, 0, v31
	v_max_f32_e32 v27, 0, v27
	v_max_f32_e32 v32, 0, v32
	v_max_f32_e32 v28, 0, v28
	v_max_f32_e32 v33, 0, v33
	v_max_f32_e32 v29, 0, v29
	v_mul_f32_e32 v30, v30, v30
	v_mul_f32_e32 v26, v26, v26
	v_mul_f32_e32 v31, v31, v31
	v_mul_f32_e32 v27, v27, v27
	v_mul_f32_e32 v32, v32, v32
	v_mul_f32_e32 v28, v28, v28
	v_mul_f32_e32 v33, v33, v33
	v_mul_f32_e32 v29, v29, v29
.LBB0_741:
	v_mad_i64_i32 v[34:35], s[10:11], s63, v160, 0
	v_lshl_add_u64 v[34:35], v[34:35], 1, v[130:131]
	s_and_b64 vcc, exec, s[38:39]
	v_cvt_pk_bf16_f32 v30, v30, v31
	v_cvt_pk_bf16_f32 v31, v32, v33
	v_cvt_pk_bf16_f32 v32, v26, v27
	v_cvt_pk_bf16_f32 v33, v28, v29
	global_store_dwordx4 v[34:35], v[30:33], off
	s_cbranch_vccnz .LBB0_743
	v_max_f32_e32 v22, v22, v22
	v_max_f32_e32 v18, v18, v18
	v_max_f32_e32 v23, v23, v23
	v_max_f32_e32 v19, v19, v19
	v_max_f32_e32 v24, v24, v24
	v_max_f32_e32 v20, v20, v20
	v_max_f32_e32 v25, v25, v25
	v_max_f32_e32 v21, v21, v21
	v_max_f32_e32 v22, 0, v22
	v_max_f32_e32 v18, 0, v18
	v_max_f32_e32 v23, 0, v23
	v_max_f32_e32 v19, 0, v19
	v_max_f32_e32 v24, 0, v24
	v_max_f32_e32 v20, 0, v20
	v_max_f32_e32 v25, 0, v25
	v_max_f32_e32 v21, 0, v21
	v_mul_f32_e32 v22, v22, v22
	v_mul_f32_e32 v18, v18, v18
	v_mul_f32_e32 v23, v23, v23
	v_mul_f32_e32 v19, v19, v19
	v_mul_f32_e32 v24, v24, v24
	v_mul_f32_e32 v20, v20, v20
	v_mul_f32_e32 v25, v25, v25
	v_mul_f32_e32 v21, v21, v21
.LBB0_743:
	s_and_b64 vcc, exec, s[38:39]
	v_cvt_pk_bf16_f32 v22, v22, v23
	v_cvt_pk_bf16_f32 v23, v24, v25
	v_cvt_pk_bf16_f32 v24, v18, v19
	v_cvt_pk_bf16_f32 v25, v20, v21
	global_store_dwordx4 v[34:35], v[22:25], off offset:256
	s_cbranch_vccnz .LBB0_745
	v_max_f32_e32 v14, v14, v14
	v_max_f32_e32 v10, v10, v10
	v_max_f32_e32 v15, v15, v15
	v_max_f32_e32 v11, v11, v11
	v_max_f32_e32 v16, v16, v16
	v_max_f32_e32 v12, v12, v12
	v_max_f32_e32 v17, v17, v17
	v_max_f32_e32 v13, v13, v13
	v_max_f32_e32 v14, 0, v14
	v_max_f32_e32 v10, 0, v10
	v_max_f32_e32 v15, 0, v15
	v_max_f32_e32 v11, 0, v11
	v_max_f32_e32 v16, 0, v16
	v_max_f32_e32 v12, 0, v12
	v_max_f32_e32 v17, 0, v17
	v_max_f32_e32 v13, 0, v13
	v_mul_f32_e32 v14, v14, v14
	v_mul_f32_e32 v10, v10, v10
	v_mul_f32_e32 v15, v15, v15
	v_mul_f32_e32 v11, v11, v11
	v_mul_f32_e32 v16, v16, v16
	v_mul_f32_e32 v12, v12, v12
	v_mul_f32_e32 v17, v17, v17
	v_mul_f32_e32 v13, v13, v13
.LBB0_745:
	v_add_u32_e32 v18, 0xb0, v156
	v_mad_i64_i32 v[18:19], s[10:11], s63, v18, 0
	v_lshl_add_u64 v[18:19], v[18:19], 1, v[130:131]
	s_and_b64 vcc, exec, s[38:39]
	v_cvt_pk_bf16_f32 v14, v14, v15
	v_cvt_pk_bf16_f32 v15, v16, v17
	v_cvt_pk_bf16_f32 v16, v10, v11
	v_cvt_pk_bf16_f32 v17, v12, v13
	global_store_dwordx4 v[18:19], v[14:17], off
	s_cbranch_vccnz .LBB0_747
	v_max_f32_e32 v6, v6, v6
	v_max_f32_e32 v2, v2, v2
	v_max_f32_e32 v7, v7, v7
	v_max_f32_e32 v3, v3, v3
	v_max_f32_e32 v8, v8, v8
	v_max_f32_e32 v4, v4, v4
	v_max_f32_e32 v9, v9, v9
	v_max_f32_e32 v5, v5, v5
	v_max_f32_e32 v6, 0, v6
	v_max_f32_e32 v2, 0, v2
	v_max_f32_e32 v7, 0, v7
	v_max_f32_e32 v3, 0, v3
	v_max_f32_e32 v8, 0, v8
	v_max_f32_e32 v4, 0, v4
	v_max_f32_e32 v9, 0, v9
	v_max_f32_e32 v5, 0, v5
	v_mul_f32_e32 v6, v6, v6
	v_mul_f32_e32 v2, v2, v2
	v_mul_f32_e32 v7, v7, v7
	v_mul_f32_e32 v3, v3, v3
	v_mul_f32_e32 v8, v8, v8
	v_mul_f32_e32 v4, v4, v4
	v_mul_f32_e32 v9, v9, v9
	v_mul_f32_e32 v5, v5, v5
.LBB0_747:
	v_cvt_pk_bf16_f32 v6, v6, v7
	v_cvt_pk_bf16_f32 v7, v8, v9
	v_cvt_pk_bf16_f32 v8, v2, v3
	v_cvt_pk_bf16_f32 v9, v4, v5
	global_store_dwordx4 v[18:19], v[6:9], off offset:256

.LBB0_762:
	v_mov_b32_e32 v0, s59
	ds_read_b64 v[6:7], v0
	v_readlane_b32 s11, v244, 38
	s_waitcnt lgkmcnt(0)
	v_readfirstlane_b32 s1, v6
	v_readfirstlane_b32 s0, v7
	s_add_u32 s1, s1, s11
	s_mul_hi_u32 s11, s26, 0x1720000
	s_addc_u32 s0, s0, s11
	s_add_u32 s11, s1, 0x2000000
	s_addc_u32 s12, s0, 0
	s_cmpk_gt_i32 s4, 0x48f
	s_mov_b64 s[0:1], -1
	s_cbranch_scc0 .LBB0_776
	s_cmpk_gt_u32 s4, 0x68f
	s_cbranch_scc0 .LBB0_773
	s_cmpk_gt_u32 s4, 0xe8f
	s_cbranch_scc0 .LBB0_770
	s_cmpk_gt_u32 s4, 0x168f
	s_cbranch_scc0 .LBB0_767
	v_readlane_b32 s0, v245, 60
	v_readlane_b32 s22, v244, 39
	v_readlane_b32 s23, v244, 40
	v_mov_b32_e32 v0, s0
	ds_read_b64 v[6:7], v0
	v_lshlrev_b32_e32 v0, 2, v2
	s_waitcnt lgkmcnt(0)
	v_readfirstlane_b32 s1, v6
	v_readfirstlane_b32 s0, v7
	s_add_u32 s13, s1, s22
	s_addc_u32 s17, s0, s23
	s_and_b32 s0, s5, 0xe0
	s_and_b32 s1, s7, 0x7c0
	s_lshl_b32 s20, s0, 2
	s_add_u32 s22, s13, s20
	v_or_b32_e32 v13, s1, v3
	s_addc_u32 s23, s17, 0
	v_lshl_add_u64 v[6:7], s[22:23], 0, v[0:1]
	v_lshlrev_b32_e32 v0, 10, v13
	v_lshl_add_u64 v[6:7], v[6:7], 0, v[0:1]
	v_add_co_u32_e32 v14, vcc, s91, v6
	s_movk_i32 s13, 0x2000
	s_nop 0
	v_addc_co_u32_e32 v15, vcc, 0, v7, vcc
	global_load_dword v0, v[6:7], off
	global_load_dword v13, v[6:7], off offset:2048
	global_load_dword v16, v[14:15], off
	global_load_dword v17, v[14:15], off offset:2048
	v_add_co_u32_e32 v14, vcc, s13, v6
	s_movk_i32 s13, 0x3000
	s_nop 0
	v_addc_co_u32_e32 v15, vcc, 0, v7, vcc
	global_load_dword v18, v[14:15], off
	global_load_dword v19, v[14:15], off offset:2048
	v_add_co_u32_e32 v14, vcc, s13, v6
	s_movk_i32 s13, 0x4000
	s_nop 0
	v_addc_co_u32_e32 v15, vcc, 0, v7, vcc
	global_load_dword v20, v[14:15], off
	global_load_dword v21, v[14:15], off offset:2048
	v_add_co_u32_e32 v14, vcc, s13, v6
	s_movk_i32 s13, 0x5000
	s_nop 0
	v_addc_co_u32_e32 v15, vcc, 0, v7, vcc
	global_load_dword v22, v[14:15], off
	global_load_dword v23, v[14:15], off offset:2048
	v_add_co_u32_e32 v14, vcc, s13, v6
	s_movk_i32 s13, 0x6000
	s_nop 0
	v_addc_co_u32_e32 v15, vcc, 0, v7, vcc
	global_load_dword v24, v[14:15], off
	global_load_dword v25, v[14:15], off offset:2048
	v_add_co_u32_e32 v14, vcc, s13, v6
	s_movk_i32 s13, 0x7000
	s_nop 0
	v_addc_co_u32_e32 v15, vcc, 0, v7, vcc
	global_load_dword v26, v[14:15], off
	global_load_dword v27, v[14:15], off offset:2048
	v_add_co_u32_e32 v14, vcc, s13, v6
	s_mov_b32 s13, 0x9000
	s_nop 0
	v_addc_co_u32_e32 v15, vcc, 0, v7, vcc
	global_load_dword v28, v[14:15], off
	global_load_dword v29, v[14:15], off offset:2048
	v_add_co_u32_e32 v14, vcc, s25, v6
	s_lshl_b32 s1, s1, 1
	s_nop 0
	v_addc_co_u32_e32 v15, vcc, 0, v7, vcc
	global_load_dword v30, v[14:15], off
	global_load_dword v31, v[14:15], off offset:2048
	v_add_co_u32_e32 v14, vcc, s13, v6
	s_mov_b32 s13, 0xa000
	s_nop 0
	v_addc_co_u32_e32 v15, vcc, 0, v7, vcc
	global_load_dword v32, v[14:15], off
	global_load_dword v33, v[14:15], off offset:2048
	v_add_co_u32_e32 v14, vcc, s13, v6
	s_mov_b32 s13, 0xb000
	s_nop 0
	v_addc_co_u32_e32 v15, vcc, 0, v7, vcc
	global_load_dword v34, v[14:15], off
	global_load_dword v35, v[14:15], off offset:2048
	v_add_co_u32_e32 v14, vcc, s13, v6
	s_mov_b32 s13, 0xc000
	s_nop 0
	v_addc_co_u32_e32 v15, vcc, 0, v7, vcc
	global_load_dword v36, v[14:15], off
	global_load_dword v37, v[14:15], off offset:2048
	v_add_co_u32_e32 v14, vcc, s13, v6
	s_mov_b32 s13, 0xd000
	s_nop 0
	v_addc_co_u32_e32 v15, vcc, 0, v7, vcc
	global_load_dword v38, v[14:15], off
	global_load_dword v39, v[14:15], off offset:2048
	v_add_co_u32_e32 v14, vcc, s13, v6
	s_mov_b32 s13, 0xe000
	s_nop 0
	v_addc_co_u32_e32 v15, vcc, 0, v7, vcc
	global_load_dword v40, v[14:15], off
	global_load_dword v41, v[14:15], off offset:2048
	v_add_co_u32_e32 v14, vcc, s13, v6
	s_mov_b32 s13, 0xf000
	s_nop 0
	v_addc_co_u32_e32 v15, vcc, 0, v7, vcc
	v_add_co_u32_e32 v6, vcc, s13, v6
	global_load_dword v42, v[14:15], off
	s_nop 0
	global_load_dword v14, v[14:15], off offset:2048
	v_addc_co_u32_e32 v7, vcc, 0, v7, vcc
	global_load_dword v15, v[6:7], off
	s_nop 0
	global_load_dword v6, v[6:7], off offset:2048
	s_waitcnt vmcnt(0) lgkmcnt(0)
	ds_write2_b32 v5, v0, v13 offset1:66
	ds_write2_b32 v5, v16, v17 offset0:132 offset1:198
	v_add_u32_e32 v0, 0x400, v5
	ds_write2_b32 v0, v18, v19 offset0:8 offset1:74
	ds_write2_b32 v0, v20, v21 offset0:140 offset1:206
	v_add_u32_e32 v0, 0x800, v5
	ds_write2_b32 v0, v22, v23 offset0:16 offset1:82
	ds_write2_b32 v0, v24, v25 offset0:148 offset1:214
	v_add_u32_e32 v0, 0xc00, v5
	ds_write2_b32 v0, v26, v27 offset0:24 offset1:90
	ds_write2_b32 v0, v28, v29 offset0:156 offset1:222
	v_add_u32_e32 v0, 0x1000, v5
	ds_write2_b32 v0, v30, v31 offset0:32 offset1:98
	ds_write2_b32 v0, v32, v33 offset0:164 offset1:230
	v_add_u32_e32 v0, 0x1400, v5
	ds_write2_b32 v0, v34, v35 offset0:40 offset1:106
	ds_write2_b32 v0, v36, v37 offset0:172 offset1:238
	v_add_u32_e32 v0, 0x1800, v5
	ds_write2_b32 v0, v38, v39 offset0:48 offset1:114
	ds_write2_b32 v0, v40, v41 offset0:180 offset1:246
	v_add_u32_e32 v0, 0x1c00, v5
	ds_write2_b32 v0, v42, v14 offset0:56 offset1:122
	ds_write2_b32 v0, v15, v6 offset0:188 offset1:254
	s_add_u32 s22, s11, s1
	s_waitcnt lgkmcnt(0)
	s_addc_u32 s23, s12, 0
	v_lshlrev_b32_e32 v0, 1, v4
	v_lshl_add_u64 v[6:7], s[22:23], 0, v[0:1]
	ds_read_b32 v0, v9
	ds_read_b32 v13, v9 offset:132
	s_mov_b64 s[22:23], 0x1700000
	v_lshl_add_u64 v[6:7], v[6:7], 0, s[22:23]
	s_waitcnt lgkmcnt(0)
	v_cvt_pk_bf16_f32 v14, v0, v13
	ds_read_b32 v0, v9 offset:264
	ds_read_b32 v13, v9 offset:396
	s_waitcnt lgkmcnt(0)
	v_cvt_pk_bf16_f32 v15, v0, v13
	ds_read_b32 v0, v9 offset:528
	ds_read_b32 v13, v9 offset:660
	s_waitcnt lgkmcnt(0)
	v_cvt_pk_bf16_f32 v16, v0, v13
	ds_read_b32 v0, v9 offset:792
	ds_read_b32 v13, v9 offset:924
	s_waitcnt lgkmcnt(0)
	v_cvt_pk_bf16_f32 v17, v0, v13
	v_or_b32_e32 v0, s0, v8
	v_lshlrev_b32_e32 v0, 9, v0
	v_lshl_add_u64 v[18:19], v[6:7], 0, v[0:1]
	global_store_dwordx4 v[18:19], v[14:17], off
	ds_read_b32 v0, v9 offset:32
	ds_read_b32 v13, v9 offset:164
	s_waitcnt lgkmcnt(0)
	v_cvt_pk_bf16_f32 v14, v0, v13
	ds_read_b32 v0, v9 offset:296
	ds_read_b32 v13, v9 offset:428
	s_waitcnt lgkmcnt(0)
	v_cvt_pk_bf16_f32 v15, v0, v13
	ds_read_b32 v0, v9 offset:560
	ds_read_b32 v13, v9 offset:692
	s_waitcnt lgkmcnt(0)
	v_cvt_pk_bf16_f32 v16, v0, v13
	ds_read_b32 v0, v9 offset:824
	ds_read_b32 v13, v9 offset:956
	s_waitcnt lgkmcnt(0)
	v_cvt_pk_bf16_f32 v17, v0, v13
	v_or_b32_e32 v0, s0, v10
	v_lshlrev_b32_e32 v0, 9, v0
	v_lshl_add_u64 v[18:19], v[6:7], 0, v[0:1]
	global_store_dwordx4 v[18:19], v[14:17], off
	ds_read_b32 v0, v9 offset:64
	ds_read_b32 v13, v9 offset:196
	s_waitcnt lgkmcnt(0)
	v_cvt_pk_bf16_f32 v14, v0, v13
	ds_read_b32 v0, v9 offset:328
	ds_read_b32 v13, v9 offset:460
	s_waitcnt lgkmcnt(0)
	v_cvt_pk_bf16_f32 v15, v0, v13
	ds_read_b32 v0, v9 offset:592
	ds_read_b32 v13, v9 offset:724
	s_waitcnt lgkmcnt(0)
	v_cvt_pk_bf16_f32 v16, v0, v13
	ds_read_b32 v0, v9 offset:856
	ds_read_b32 v13, v9 offset:988
	s_waitcnt lgkmcnt(0)
	v_cvt_pk_bf16_f32 v17, v0, v13
	v_or_b32_e32 v0, s0, v11
	v_lshlrev_b32_e32 v0, 9, v0
	v_lshl_add_u64 v[18:19], v[6:7], 0, v[0:1]
	global_store_dwordx4 v[18:19], v[14:17], off
	ds_read_b32 v0, v9 offset:96
	ds_read_b32 v13, v9 offset:228
	s_waitcnt lgkmcnt(0)
	v_cvt_pk_bf16_f32 v14, v0, v13
	ds_read_b32 v0, v9 offset:360
	ds_read_b32 v13, v9 offset:492
	s_waitcnt lgkmcnt(0)
	v_cvt_pk_bf16_f32 v15, v0, v13
	ds_read_b32 v0, v9 offset:624
	ds_read_b32 v13, v9 offset:756
	s_waitcnt lgkmcnt(0)
	v_cvt_pk_bf16_f32 v16, v0, v13
	ds_read_b32 v0, v9 offset:888
	ds_read_b32 v13, v9 offset:1020
	s_waitcnt lgkmcnt(0)
	v_cvt_pk_bf16_f32 v17, v0, v13
	v_or_b32_e32 v0, s0, v12
	v_lshlrev_b32_e32 v0, 9, v0
	v_lshl_add_u64 v[6:7], v[6:7], 0, v[0:1]
	global_store_dwordx4 v[6:7], v[14:17], off
	s_waitcnt lgkmcnt(0)
	s_mov_b64 s[0:1], 0
.LBB0_767:
	s_andn2_b64 vcc, exec, s[0:1]
	s_cbranch_vccnz .LBB0_769
	v_readlane_b32 s0, v245, 61
	v_readlane_b32 s22, v244, 41
	v_readlane_b32 s23, v244, 42
	v_mov_b32_e32 v0, s0
	ds_read_b64 v[6:7], v0
	v_lshlrev_b32_e32 v0, 2, v2
	s_waitcnt lgkmcnt(0)
	v_readfirstlane_b32 s1, v6
	v_readfirstlane_b32 s0, v7
	s_add_u32 s13, s1, s22
	s_addc_u32 s17, s0, s23
	s_add_i32 s0, s5, 0xfffe2e00
	s_and_b32 s0, s0, 0x3e0
	s_and_b32 s1, s9, 0x1ffc0
	s_lshl_b32 s20, s0, 2
	s_add_u32 s22, s13, s20
	v_or_b32_e32 v13, s1, v3
	s_addc_u32 s23, s17, 0
	v_lshl_add_u64 v[6:7], s[22:23], 0, v[0:1]
	v_lshlrev_b32_e32 v0, 12, v13
	v_lshl_add_u64 v[6:7], v[6:7], 0, v[0:1]
	s_movk_i32 s13, 0x2000
	v_add_co_u32_e32 v14, vcc, s13, v6
	s_movk_i32 s13, 0x4000
	s_nop 0
	v_addc_co_u32_e32 v15, vcc, 0, v7, vcc
	global_load_dword v0, v[6:7], off
	global_load_dword v13, v[14:15], off
	v_add_co_u32_e32 v14, vcc, s13, v6
	s_movk_i32 s13, 0x6000
	s_nop 0
	v_addc_co_u32_e32 v15, vcc, 0, v7, vcc
	global_load_dword v16, v[14:15], off
	v_add_co_u32_e32 v14, vcc, s13, v6
	s_mov_b32 s13, 0xa000
	s_nop 0
	v_addc_co_u32_e32 v15, vcc, 0, v7, vcc
	global_load_dword v17, v[14:15], off
	v_add_co_u32_e32 v14, vcc, s25, v6
	s_lshl_b32 s1, s1, 1
	s_nop 0
	v_addc_co_u32_e32 v15, vcc, 0, v7, vcc
	global_load_dword v18, v[14:15], off
	v_add_co_u32_e32 v14, vcc, s13, v6
	s_mov_b32 s13, 0xc000
	s_nop 0
	v_addc_co_u32_e32 v15, vcc, 0, v7, vcc
	global_load_dword v19, v[14:15], off
	v_add_co_u32_e32 v14, vcc, s13, v6
	s_mov_b32 s13, 0xe000
	s_nop 0
	v_addc_co_u32_e32 v15, vcc, 0, v7, vcc
	global_load_dword v20, v[14:15], off
	v_add_co_u32_e32 v14, vcc, s13, v6
	s_mov_b32 s13, 0x10000
	s_nop 0
	v_addc_co_u32_e32 v15, vcc, 0, v7, vcc
	global_load_dword v21, v[14:15], off
	v_add_co_u32_e32 v14, vcc, s13, v6
	s_mov_b32 s13, 0x12000
	s_nop 0
	v_addc_co_u32_e32 v15, vcc, 0, v7, vcc
	global_load_dword v22, v[14:15], off
	v_add_co_u32_e32 v14, vcc, s13, v6
	s_mov_b32 s13, 0x14000
	s_nop 0
	v_addc_co_u32_e32 v15, vcc, 0, v7, vcc
	global_load_dword v23, v[14:15], off
	v_add_co_u32_e32 v14, vcc, s13, v6
	s_mov_b32 s13, 0x16000
	s_nop 0
	v_addc_co_u32_e32 v15, vcc, 0, v7, vcc
	global_load_dword v24, v[14:15], off
	v_add_co_u32_e32 v14, vcc, s13, v6
	s_mov_b32 s13, 0x18000
	s_nop 0
	v_addc_co_u32_e32 v15, vcc, 0, v7, vcc
	global_load_dword v25, v[14:15], off
	v_add_co_u32_e32 v14, vcc, s13, v6
	s_mov_b32 s13, 0x1a000
	s_nop 0
	v_addc_co_u32_e32 v15, vcc, 0, v7, vcc
	global_load_dword v26, v[14:15], off
	v_add_co_u32_e32 v14, vcc, s13, v6
	s_mov_b32 s13, 0x1c000
	s_nop 0
	v_addc_co_u32_e32 v15, vcc, 0, v7, vcc
	global_load_dword v27, v[14:15], off
	v_add_co_u32_e32 v14, vcc, s13, v6
	s_mov_b32 s13, 0x1e000
	s_nop 0
	v_addc_co_u32_e32 v15, vcc, 0, v7, vcc
	global_load_dword v28, v[14:15], off
	v_add_co_u32_e32 v14, vcc, s13, v6
	s_mov_b32 s13, 0x20000
	s_nop 0
	v_addc_co_u32_e32 v15, vcc, 0, v7, vcc
	global_load_dword v29, v[14:15], off
	v_add_co_u32_e32 v14, vcc, s13, v6
	s_mov_b32 s13, 0x22000
	s_nop 0
	v_addc_co_u32_e32 v15, vcc, 0, v7, vcc
	global_load_dword v30, v[14:15], off
	v_add_co_u32_e32 v14, vcc, s13, v6
	s_mov_b32 s13, 0x24000
	s_nop 0
	v_addc_co_u32_e32 v15, vcc, 0, v7, vcc
	global_load_dword v31, v[14:15], off
	v_add_co_u32_e32 v14, vcc, s13, v6
	s_mov_b32 s13, 0x26000
	s_nop 0
	v_addc_co_u32_e32 v15, vcc, 0, v7, vcc
	global_load_dword v32, v[14:15], off
	v_add_co_u32_e32 v14, vcc, s13, v6
	s_mov_b32 s13, 0x28000
	s_nop 0
	v_addc_co_u32_e32 v15, vcc, 0, v7, vcc
	global_load_dword v33, v[14:15], off
	v_add_co_u32_e32 v14, vcc, s13, v6
	s_mov_b32 s13, 0x2a000
	s_nop 0
	v_addc_co_u32_e32 v15, vcc, 0, v7, vcc
	global_load_dword v34, v[14:15], off
	v_add_co_u32_e32 v14, vcc, s13, v6
	s_mov_b32 s13, 0x2c000
	s_nop 0
	v_addc_co_u32_e32 v15, vcc, 0, v7, vcc
	global_load_dword v35, v[14:15], off
	v_add_co_u32_e32 v14, vcc, s13, v6
	s_mov_b32 s13, 0x2e000
	s_nop 0
	v_addc_co_u32_e32 v15, vcc, 0, v7, vcc
	global_load_dword v36, v[14:15], off
	v_add_co_u32_e32 v14, vcc, s13, v6
	s_mov_b32 s13, 0x30000
	s_nop 0
	v_addc_co_u32_e32 v15, vcc, 0, v7, vcc
	global_load_dword v37, v[14:15], off
	v_add_co_u32_e32 v14, vcc, s13, v6
	s_mov_b32 s13, 0x32000
	s_nop 0
	v_addc_co_u32_e32 v15, vcc, 0, v7, vcc
	global_load_dword v38, v[14:15], off
	v_add_co_u32_e32 v14, vcc, s13, v6
	s_mov_b32 s13, 0x34000
	s_nop 0
	v_addc_co_u32_e32 v15, vcc, 0, v7, vcc
	global_load_dword v39, v[14:15], off
	v_add_co_u32_e32 v14, vcc, s13, v6
	s_mov_b32 s13, 0x36000
	s_nop 0
	v_addc_co_u32_e32 v15, vcc, 0, v7, vcc
	global_load_dword v40, v[14:15], off
	v_add_co_u32_e32 v14, vcc, s13, v6
	s_mov_b32 s13, 0x38000
	s_nop 0
	v_addc_co_u32_e32 v15, vcc, 0, v7, vcc
	global_load_dword v41, v[14:15], off
	v_add_co_u32_e32 v14, vcc, s13, v6
	s_mov_b32 s13, 0x3a000
	s_nop 0
	v_addc_co_u32_e32 v15, vcc, 0, v7, vcc
	global_load_dword v42, v[14:15], off
	v_add_co_u32_e32 v14, vcc, s13, v6
	s_mov_b32 s13, 0x3c000
	s_nop 0
	v_addc_co_u32_e32 v15, vcc, 0, v7, vcc
	global_load_dword v43, v[14:15], off
	v_add_co_u32_e32 v14, vcc, s13, v6
	s_mov_b32 s13, 0x3e000
	s_nop 0
	v_addc_co_u32_e32 v15, vcc, 0, v7, vcc
	v_add_co_u32_e32 v6, vcc, s13, v6
	global_load_dword v14, v[14:15], off
	s_nop 0
	v_addc_co_u32_e32 v7, vcc, 0, v7, vcc
	global_load_dword v6, v[6:7], off
	s_waitcnt vmcnt(0) lgkmcnt(0)
	ds_write2_b32 v5, v0, v13 offset1:66
	ds_write2_b32 v5, v16, v17 offset0:132 offset1:198
	v_add_u32_e32 v0, 0x400, v5
	ds_write2_b32 v0, v18, v19 offset0:8 offset1:74
	ds_write2_b32 v0, v20, v21 offset0:140 offset1:206
	v_add_u32_e32 v0, 0x800, v5
	ds_write2_b32 v0, v22, v23 offset0:16 offset1:82
	ds_write2_b32 v0, v24, v25 offset0:148 offset1:214
	v_add_u32_e32 v0, 0xc00, v5
	ds_write2_b32 v0, v26, v27 offset0:24 offset1:90
	ds_write2_b32 v0, v28, v29 offset0:156 offset1:222
	v_add_u32_e32 v0, 0x1000, v5
	ds_write2_b32 v0, v30, v31 offset0:32 offset1:98
	ds_write2_b32 v0, v32, v33 offset0:164 offset1:230
	v_add_u32_e32 v0, 0x1400, v5
	ds_write2_b32 v0, v34, v35 offset0:40 offset1:106
	ds_write2_b32 v0, v36, v37 offset0:172 offset1:238
	v_add_u32_e32 v0, 0x1800, v5
	ds_write2_b32 v0, v38, v39 offset0:48 offset1:114
	ds_write2_b32 v0, v40, v41 offset0:180 offset1:246
	v_add_u32_e32 v0, 0x1c00, v5
	ds_write2_b32 v0, v42, v43 offset0:56 offset1:122
	ds_write2_b32 v0, v14, v6 offset0:188 offset1:254
	s_add_u32 s22, s11, s1
	s_waitcnt lgkmcnt(0)
	s_addc_u32 s23, s12, 0
	v_lshlrev_b32_e32 v0, 1, v4
	v_lshl_add_u64 v[6:7], s[22:23], 0, v[0:1]
	ds_read_b32 v0, v9
	ds_read_b32 v13, v9 offset:132
	s_mov_b64 s[22:23], 0xf00000
	v_lshl_add_u64 v[6:7], v[6:7], 0, s[22:23]
	s_waitcnt lgkmcnt(0)
	v_cvt_pk_bf16_f32 v14, v0, v13
	ds_read_b32 v0, v9 offset:264
	ds_read_b32 v13, v9 offset:396
	s_waitcnt lgkmcnt(0)
	v_cvt_pk_bf16_f32 v15, v0, v13
	ds_read_b32 v0, v9 offset:528
	ds_read_b32 v13, v9 offset:660
	s_waitcnt lgkmcnt(0)
	v_cvt_pk_bf16_f32 v16, v0, v13
	ds_read_b32 v0, v9 offset:792
	ds_read_b32 v13, v9 offset:924
	s_waitcnt lgkmcnt(0)
	v_cvt_pk_bf16_f32 v17, v0, v13
	v_or_b32_e32 v0, s0, v8
	v_lshlrev_b32_e32 v0, 13, v0
	v_lshl_add_u64 v[18:19], v[6:7], 0, v[0:1]
	global_store_dwordx4 v[18:19], v[14:17], off
	ds_read_b32 v0, v9 offset:32
	ds_read_b32 v13, v9 offset:164
	s_waitcnt lgkmcnt(0)
	v_cvt_pk_bf16_f32 v14, v0, v13
	ds_read_b32 v0, v9 offset:296
	ds_read_b32 v13, v9 offset:428
	s_waitcnt lgkmcnt(0)
	v_cvt_pk_bf16_f32 v15, v0, v13
	ds_read_b32 v0, v9 offset:560
	ds_read_b32 v13, v9 offset:692
	s_waitcnt lgkmcnt(0)
	v_cvt_pk_bf16_f32 v16, v0, v13
	ds_read_b32 v0, v9 offset:824
	ds_read_b32 v13, v9 offset:956
	s_waitcnt lgkmcnt(0)
	v_cvt_pk_bf16_f32 v17, v0, v13
	v_or_b32_e32 v0, s0, v10
	v_lshlrev_b32_e32 v0, 13, v0
	v_lshl_add_u64 v[18:19], v[6:7], 0, v[0:1]
	global_store_dwordx4 v[18:19], v[14:17], off
	ds_read_b32 v0, v9 offset:64
	ds_read_b32 v13, v9 offset:196
	s_waitcnt lgkmcnt(0)
	v_cvt_pk_bf16_f32 v14, v0, v13
	ds_read_b32 v0, v9 offset:328
	ds_read_b32 v13, v9 offset:460
	s_waitcnt lgkmcnt(0)
	v_cvt_pk_bf16_f32 v15, v0, v13
	ds_read_b32 v0, v9 offset:592
	ds_read_b32 v13, v9 offset:724
	s_waitcnt lgkmcnt(0)
	v_cvt_pk_bf16_f32 v16, v0, v13
	ds_read_b32 v0, v9 offset:856
	ds_read_b32 v13, v9 offset:988
	s_waitcnt lgkmcnt(0)
	v_cvt_pk_bf16_f32 v17, v0, v13
	v_or_b32_e32 v0, s0, v11
	v_lshlrev_b32_e32 v0, 13, v0
	v_lshl_add_u64 v[18:19], v[6:7], 0, v[0:1]
	global_store_dwordx4 v[18:19], v[14:17], off
	ds_read_b32 v0, v9 offset:96
	ds_read_b32 v13, v9 offset:228
	s_waitcnt lgkmcnt(0)
	v_cvt_pk_bf16_f32 v14, v0, v13
	ds_read_b32 v0, v9 offset:360
	ds_read_b32 v13, v9 offset:492
	s_waitcnt lgkmcnt(0)
	v_cvt_pk_bf16_f32 v15, v0, v13
	ds_read_b32 v0, v9 offset:624
	ds_read_b32 v13, v9 offset:756
	s_waitcnt lgkmcnt(0)
	v_cvt_pk_bf16_f32 v16, v0, v13
	ds_read_b32 v0, v9 offset:888
	ds_read_b32 v13, v9 offset:1020
	s_waitcnt lgkmcnt(0)
	v_cvt_pk_bf16_f32 v17, v0, v13
	v_or_b32_e32 v0, s0, v12
	v_lshlrev_b32_e32 v0, 13, v0
	v_lshl_add_u64 v[6:7], v[6:7], 0, v[0:1]
	global_store_dwordx4 v[6:7], v[14:17], off
	s_waitcnt lgkmcnt(0)

.LBB0_770:
	s_andn2_b64 vcc, exec, s[0:1]
	s_cbranch_vccnz .LBB0_772
	v_readlane_b32 s1, v245, 62
	s_add_i32 s0, s4, 0xfffff970
	v_readlane_b32 s22, v244, 41
	v_mov_b32_e32 v0, s1
	ds_read_b64 v[6:7], v0
	v_readlane_b32 s23, v244, 42
	v_lshlrev_b32_e32 v0, 2, v2
	s_waitcnt lgkmcnt(0)
	v_readfirstlane_b32 s13, v6
	v_readfirstlane_b32 s1, v7
	s_add_u32 s13, s13, s22
	s_addc_u32 s17, s1, s23
	s_lshr_b32 s0, s0, 1
	s_and_b32 s1, s0, 0x7fc0
	s_add_i32 s0, s5, 0xffff2e00
	s_and_b32 s0, s0, 0xfe0
	s_lshl_b32 s20, s0, 2
	s_add_u32 s22, s13, s20
	v_or_b32_e32 v13, s1, v3
	s_addc_u32 s23, s17, 0
	v_lshl_add_u64 v[6:7], s[22:23], 0, v[0:1]
	v_lshlrev_b32_e32 v0, 14, v13
	v_lshl_add_u64 v[6:7], v[6:7], 0, v[0:1]
	v_add_co_u32_e32 v14, vcc, s25, v6
	s_mov_b32 s13, 0x10000
	s_nop 0
	v_addc_co_u32_e32 v15, vcc, 0, v7, vcc
	global_load_dword v0, v[6:7], off
	global_load_dword v13, v[14:15], off
	v_add_co_u32_e32 v14, vcc, s13, v6
	s_mov_b32 s13, 0x18000
	s_nop 0
	v_addc_co_u32_e32 v15, vcc, 0, v7, vcc
	global_load_dword v16, v[14:15], off
	v_add_co_u32_e32 v14, vcc, s13, v6
	s_mov_b32 s13, 0x20000
	s_nop 0
	v_addc_co_u32_e32 v15, vcc, 0, v7, vcc
	global_load_dword v17, v[14:15], off
	v_add_co_u32_e32 v14, vcc, s13, v6
	s_mov_b32 s13, 0x28000
	s_nop 0
	v_addc_co_u32_e32 v15, vcc, 0, v7, vcc
	global_load_dword v18, v[14:15], off
	v_add_co_u32_e32 v14, vcc, s13, v6
	s_mov_b32 s13, 0x30000
	s_nop 0
	v_addc_co_u32_e32 v15, vcc, 0, v7, vcc
	global_load_dword v19, v[14:15], off
	v_add_co_u32_e32 v14, vcc, s13, v6
	s_mov_b32 s13, 0x38000
	s_nop 0
	v_addc_co_u32_e32 v15, vcc, 0, v7, vcc
	global_load_dword v20, v[14:15], off
	v_add_co_u32_e32 v14, vcc, s13, v6
	s_mov_b32 s13, 0x40000
	s_nop 0
	v_addc_co_u32_e32 v15, vcc, 0, v7, vcc
	global_load_dword v21, v[14:15], off
	v_add_co_u32_e32 v14, vcc, s13, v6
	s_mov_b32 s13, 0x48000
	s_nop 0
	v_addc_co_u32_e32 v15, vcc, 0, v7, vcc
	global_load_dword v22, v[14:15], off
	v_add_co_u32_e32 v14, vcc, s13, v6
	s_mov_b32 s13, 0x50000
	s_nop 0
	v_addc_co_u32_e32 v15, vcc, 0, v7, vcc
	global_load_dword v23, v[14:15], off
	v_add_co_u32_e32 v14, vcc, s13, v6
	s_mov_b32 s13, 0x58000
	s_nop 0
	v_addc_co_u32_e32 v15, vcc, 0, v7, vcc
	global_load_dword v24, v[14:15], off
	v_add_co_u32_e32 v14, vcc, s13, v6
	s_mov_b32 s13, 0x60000
	s_nop 0
	v_addc_co_u32_e32 v15, vcc, 0, v7, vcc
	global_load_dword v25, v[14:15], off
	v_add_co_u32_e32 v14, vcc, s13, v6
	s_mov_b32 s13, 0x68000
	s_nop 0
	v_addc_co_u32_e32 v15, vcc, 0, v7, vcc
	global_load_dword v26, v[14:15], off
	v_add_co_u32_e32 v14, vcc, s13, v6
	s_mov_b32 s13, 0x70000
	s_nop 0
	v_addc_co_u32_e32 v15, vcc, 0, v7, vcc
	global_load_dword v27, v[14:15], off
	v_add_co_u32_e32 v14, vcc, s13, v6
	s_mov_b32 s13, 0x78000
	s_nop 0
	v_addc_co_u32_e32 v15, vcc, 0, v7, vcc
	global_load_dword v28, v[14:15], off
	v_add_co_u32_e32 v14, vcc, s13, v6
	s_mov_b32 s13, 0x80000
	s_nop 0
	v_addc_co_u32_e32 v15, vcc, 0, v7, vcc
	global_load_dword v29, v[14:15], off
	v_add_co_u32_e32 v14, vcc, s13, v6
	s_mov_b32 s13, 0x88000
	s_nop 0
	v_addc_co_u32_e32 v15, vcc, 0, v7, vcc
	global_load_dword v30, v[14:15], off
	v_add_co_u32_e32 v14, vcc, s13, v6
	s_mov_b32 s13, 0x90000
	s_nop 0
	v_addc_co_u32_e32 v15, vcc, 0, v7, vcc
	global_load_dword v31, v[14:15], off
	v_add_co_u32_e32 v14, vcc, s13, v6
	s_mov_b32 s13, 0x98000
	s_nop 0
	v_addc_co_u32_e32 v15, vcc, 0, v7, vcc
	global_load_dword v32, v[14:15], off
	v_add_co_u32_e32 v14, vcc, s13, v6
	s_mov_b32 s13, 0xa0000
	s_nop 0
	v_addc_co_u32_e32 v15, vcc, 0, v7, vcc
	global_load_dword v33, v[14:15], off
	v_add_co_u32_e32 v14, vcc, s13, v6
	s_mov_b32 s13, 0xa8000
	s_nop 0
	v_addc_co_u32_e32 v15, vcc, 0, v7, vcc
	global_load_dword v34, v[14:15], off
	v_add_co_u32_e32 v14, vcc, s13, v6
	s_mov_b32 s13, 0xb0000
	s_nop 0
	v_addc_co_u32_e32 v15, vcc, 0, v7, vcc
	global_load_dword v35, v[14:15], off
	v_add_co_u32_e32 v14, vcc, s13, v6
	s_mov_b32 s13, 0xb8000
	s_nop 0
	v_addc_co_u32_e32 v15, vcc, 0, v7, vcc
	global_load_dword v36, v[14:15], off
	v_add_co_u32_e32 v14, vcc, s13, v6
	s_mov_b32 s13, 0xc0000
	s_nop 0
	v_addc_co_u32_e32 v15, vcc, 0, v7, vcc
	global_load_dword v37, v[14:15], off
	v_add_co_u32_e32 v14, vcc, s13, v6
	s_mov_b32 s13, 0xc8000
	s_nop 0
	v_addc_co_u32_e32 v15, vcc, 0, v7, vcc
	global_load_dword v38, v[14:15], off
	v_add_co_u32_e32 v14, vcc, s13, v6
	s_mov_b32 s13, 0xd0000
	s_nop 0
	v_addc_co_u32_e32 v15, vcc, 0, v7, vcc
	global_load_dword v39, v[14:15], off
	v_add_co_u32_e32 v14, vcc, s13, v6
	s_mov_b32 s13, 0xd8000
	s_nop 0
	v_addc_co_u32_e32 v15, vcc, 0, v7, vcc
	global_load_dword v40, v[14:15], off
	v_add_co_u32_e32 v14, vcc, s13, v6
	s_mov_b32 s13, 0xe0000
	s_nop 0
	v_addc_co_u32_e32 v15, vcc, 0, v7, vcc
	global_load_dword v41, v[14:15], off
	v_add_co_u32_e32 v14, vcc, s13, v6
	s_mov_b32 s13, 0xe8000
	s_nop 0
	v_addc_co_u32_e32 v15, vcc, 0, v7, vcc
	global_load_dword v42, v[14:15], off
	v_add_co_u32_e32 v14, vcc, s13, v6
	s_mov_b32 s13, 0xf0000
	s_nop 0
	v_addc_co_u32_e32 v15, vcc, 0, v7, vcc
	global_load_dword v43, v[14:15], off
	v_add_co_u32_e32 v14, vcc, s13, v6
	s_mov_b32 s13, 0xf8000
	s_nop 0
	v_addc_co_u32_e32 v15, vcc, 0, v7, vcc
	v_add_co_u32_e32 v6, vcc, s13, v6
	global_load_dword v14, v[14:15], off
	s_nop 0
	v_addc_co_u32_e32 v7, vcc, 0, v7, vcc
	global_load_dword v6, v[6:7], off
	s_waitcnt vmcnt(0) lgkmcnt(0)
	ds_write2_b32 v5, v0, v13 offset1:66
	ds_write2_b32 v5, v16, v17 offset0:132 offset1:198
	v_add_u32_e32 v0, 0x400, v5
	ds_write2_b32 v0, v18, v19 offset0:8 offset1:74
	ds_write2_b32 v0, v20, v21 offset0:140 offset1:206
	v_add_u32_e32 v0, 0x800, v5
	ds_write2_b32 v0, v22, v23 offset0:16 offset1:82
	ds_write2_b32 v0, v24, v25 offset0:148 offset1:214
	v_add_u32_e32 v0, 0xc00, v5
	ds_write2_b32 v0, v26, v27 offset0:24 offset1:90
	ds_write2_b32 v0, v28, v29 offset0:156 offset1:222
	v_add_u32_e32 v0, 0x1000, v5
	ds_write2_b32 v0, v30, v31 offset0:32 offset1:98
	ds_write2_b32 v0, v32, v33 offset0:164 offset1:230
	v_add_u32_e32 v0, 0x1400, v5
	ds_write2_b32 v0, v34, v35 offset0:40 offset1:106
	ds_write2_b32 v0, v36, v37 offset0:172 offset1:238
	v_add_u32_e32 v0, 0x1800, v5
	ds_write2_b32 v0, v38, v39 offset0:48 offset1:114
	ds_write2_b32 v0, v40, v41 offset0:180 offset1:246
	v_add_u32_e32 v0, 0x1c00, v5
	s_lshl_b32 s1, s1, 1
	ds_write2_b32 v0, v42, v43 offset0:56 offset1:122
	ds_write2_b32 v0, v14, v6 offset0:188 offset1:254
	s_add_u32 s22, s11, s1
	s_waitcnt lgkmcnt(0)
	s_addc_u32 s23, s12, 0
	v_lshlrev_b32_e32 v0, 1, v4
	v_lshl_add_u64 v[6:7], s[22:23], 0, v[0:1]
	ds_read_b32 v0, v9
	ds_read_b32 v13, v9 offset:132
	s_mov_b64 s[22:23], 0x700000
	v_lshl_add_u64 v[6:7], v[6:7], 0, s[22:23]
	s_waitcnt lgkmcnt(0)
	v_cvt_pk_bf16_f32 v14, v0, v13
	ds_read_b32 v0, v9 offset:264
	ds_read_b32 v13, v9 offset:396
	s_waitcnt lgkmcnt(0)
	v_cvt_pk_bf16_f32 v15, v0, v13
	ds_read_b32 v0, v9 offset:528
	ds_read_b32 v13, v9 offset:660
	s_waitcnt lgkmcnt(0)
	v_cvt_pk_bf16_f32 v16, v0, v13
	ds_read_b32 v0, v9 offset:792
	ds_read_b32 v13, v9 offset:924
	s_waitcnt lgkmcnt(0)
	v_cvt_pk_bf16_f32 v17, v0, v13
	v_or_b32_e32 v0, s0, v8
	v_lshlrev_b32_e32 v0, 11, v0
	v_lshl_add_u64 v[18:19], v[6:7], 0, v[0:1]
	global_store_dwordx4 v[18:19], v[14:17], off
	ds_read_b32 v0, v9 offset:32
	ds_read_b32 v13, v9 offset:164
	s_waitcnt lgkmcnt(0)
	v_cvt_pk_bf16_f32 v14, v0, v13
	ds_read_b32 v0, v9 offset:296
	ds_read_b32 v13, v9 offset:428
	s_waitcnt lgkmcnt(0)
	v_cvt_pk_bf16_f32 v15, v0, v13
	ds_read_b32 v0, v9 offset:560
	ds_read_b32 v13, v9 offset:692
	s_waitcnt lgkmcnt(0)
	v_cvt_pk_bf16_f32 v16, v0, v13
	ds_read_b32 v0, v9 offset:824
	ds_read_b32 v13, v9 offset:956
	s_waitcnt lgkmcnt(0)
	v_cvt_pk_bf16_f32 v17, v0, v13
	v_or_b32_e32 v0, s0, v10
	v_lshlrev_b32_e32 v0, 11, v0
	v_lshl_add_u64 v[18:19], v[6:7], 0, v[0:1]
	global_store_dwordx4 v[18:19], v[14:17], off
	ds_read_b32 v0, v9 offset:64
	ds_read_b32 v13, v9 offset:196
	s_waitcnt lgkmcnt(0)
	v_cvt_pk_bf16_f32 v14, v0, v13
	ds_read_b32 v0, v9 offset:328
	ds_read_b32 v13, v9 offset:460
	s_waitcnt lgkmcnt(0)
	v_cvt_pk_bf16_f32 v15, v0, v13
	ds_read_b32 v0, v9 offset:592
	ds_read_b32 v13, v9 offset:724
	s_waitcnt lgkmcnt(0)
	v_cvt_pk_bf16_f32 v16, v0, v13
	ds_read_b32 v0, v9 offset:856
	ds_read_b32 v13, v9 offset:988
	s_waitcnt lgkmcnt(0)
	v_cvt_pk_bf16_f32 v17, v0, v13
	v_or_b32_e32 v0, s0, v11
	v_lshlrev_b32_e32 v0, 11, v0
	v_lshl_add_u64 v[18:19], v[6:7], 0, v[0:1]
	global_store_dwordx4 v[18:19], v[14:17], off
	ds_read_b32 v0, v9 offset:96
	ds_read_b32 v13, v9 offset:228
	s_waitcnt lgkmcnt(0)
	v_cvt_pk_bf16_f32 v14, v0, v13
	ds_read_b32 v0, v9 offset:360
	ds_read_b32 v13, v9 offset:492
	s_waitcnt lgkmcnt(0)
	v_cvt_pk_bf16_f32 v15, v0, v13
	ds_read_b32 v0, v9 offset:624
	ds_read_b32 v13, v9 offset:756
	s_waitcnt lgkmcnt(0)
	v_cvt_pk_bf16_f32 v16, v0, v13
	ds_read_b32 v0, v9 offset:888
	ds_read_b32 v13, v9 offset:1020
	s_waitcnt lgkmcnt(0)
	v_cvt_pk_bf16_f32 v17, v0, v13
	v_or_b32_e32 v0, s0, v12
	v_lshlrev_b32_e32 v0, 11, v0
	v_lshl_add_u64 v[6:7], v[6:7], 0, v[0:1]
	global_store_dwordx4 v[6:7], v[14:17], off
	s_waitcnt lgkmcnt(0)

.LBB0_773:
	s_andn2_b64 vcc, exec, s[0:1]
	s_cbranch_vccnz .LBB0_775
	v_readlane_b32 s0, v245, 63
	v_readlane_b32 s22, v244, 43
	v_readlane_b32 s23, v244, 44
	v_mov_b32_e32 v0, s0
	ds_read_b64 v[6:7], v0
	v_lshlrev_b32_e32 v0, 2, v2
	s_waitcnt lgkmcnt(0)
	v_readfirstlane_b32 s1, v6
	v_readfirstlane_b32 s0, v7
	s_add_u32 s13, s1, s22
	s_addc_u32 s17, s0, s23
	s_add_i32 s0, s9, 0x1400
	s_and_b32 s1, s0, 0x1ffc0
	s_add_i32 s0, s5, 0xffff6e00
	s_and_b32 s0, s0, 0x3e0
	s_lshl_b32 s20, s0, 2
	s_add_u32 s22, s13, s20
	v_or_b32_e32 v13, s1, v3
	s_addc_u32 s23, s17, 0
	v_lshl_add_u64 v[6:7], s[22:23], 0, v[0:1]
	v_lshlrev_b32_e32 v0, 12, v13
	v_lshl_add_u64 v[6:7], v[6:7], 0, v[0:1]
	s_movk_i32 s13, 0x2000
	v_add_co_u32_e32 v14, vcc, s13, v6
	s_movk_i32 s13, 0x4000
	s_nop 0
	v_addc_co_u32_e32 v15, vcc, 0, v7, vcc
	global_load_dword v0, v[6:7], off
	global_load_dword v13, v[14:15], off
	v_add_co_u32_e32 v14, vcc, s13, v6
	s_movk_i32 s13, 0x6000
	s_nop 0
	v_addc_co_u32_e32 v15, vcc, 0, v7, vcc
	global_load_dword v16, v[14:15], off
	v_add_co_u32_e32 v14, vcc, s13, v6
	s_mov_b32 s13, 0xa000
	s_nop 0
	v_addc_co_u32_e32 v15, vcc, 0, v7, vcc
	global_load_dword v17, v[14:15], off
	v_add_co_u32_e32 v14, vcc, s25, v6
	s_lshl_b32 s1, s1, 1
	s_nop 0
	v_addc_co_u32_e32 v15, vcc, 0, v7, vcc
	global_load_dword v18, v[14:15], off
	v_add_co_u32_e32 v14, vcc, s13, v6
	s_mov_b32 s13, 0xc000
	s_nop 0
	v_addc_co_u32_e32 v15, vcc, 0, v7, vcc
	global_load_dword v19, v[14:15], off
	v_add_co_u32_e32 v14, vcc, s13, v6
	s_mov_b32 s13, 0xe000
	s_nop 0
	v_addc_co_u32_e32 v15, vcc, 0, v7, vcc
	global_load_dword v20, v[14:15], off
	v_add_co_u32_e32 v14, vcc, s13, v6
	s_mov_b32 s13, 0x10000
	s_nop 0
	v_addc_co_u32_e32 v15, vcc, 0, v7, vcc
	global_load_dword v21, v[14:15], off
	v_add_co_u32_e32 v14, vcc, s13, v6
	s_mov_b32 s13, 0x12000
	s_nop 0
	v_addc_co_u32_e32 v15, vcc, 0, v7, vcc
	global_load_dword v22, v[14:15], off
	v_add_co_u32_e32 v14, vcc, s13, v6
	s_mov_b32 s13, 0x14000
	s_nop 0
	v_addc_co_u32_e32 v15, vcc, 0, v7, vcc
	global_load_dword v23, v[14:15], off
	v_add_co_u32_e32 v14, vcc, s13, v6
	s_mov_b32 s13, 0x16000
	s_nop 0
	v_addc_co_u32_e32 v15, vcc, 0, v7, vcc
	global_load_dword v24, v[14:15], off
	v_add_co_u32_e32 v14, vcc, s13, v6
	s_mov_b32 s13, 0x18000
	s_nop 0
	v_addc_co_u32_e32 v15, vcc, 0, v7, vcc
	global_load_dword v25, v[14:15], off
	v_add_co_u32_e32 v14, vcc, s13, v6
	s_mov_b32 s13, 0x1a000
	s_nop 0
	v_addc_co_u32_e32 v15, vcc, 0, v7, vcc
	global_load_dword v26, v[14:15], off
	v_add_co_u32_e32 v14, vcc, s13, v6
	s_mov_b32 s13, 0x1c000
	s_nop 0
	v_addc_co_u32_e32 v15, vcc, 0, v7, vcc
	global_load_dword v27, v[14:15], off
	v_add_co_u32_e32 v14, vcc, s13, v6
	s_mov_b32 s13, 0x1e000
	s_nop 0
	v_addc_co_u32_e32 v15, vcc, 0, v7, vcc
	global_load_dword v28, v[14:15], off
	v_add_co_u32_e32 v14, vcc, s13, v6
	s_mov_b32 s13, 0x20000
	s_nop 0
	v_addc_co_u32_e32 v15, vcc, 0, v7, vcc
	global_load_dword v29, v[14:15], off
	v_add_co_u32_e32 v14, vcc, s13, v6
	s_mov_b32 s13, 0x22000
	s_nop 0
	v_addc_co_u32_e32 v15, vcc, 0, v7, vcc
	global_load_dword v30, v[14:15], off
	v_add_co_u32_e32 v14, vcc, s13, v6
	s_mov_b32 s13, 0x24000
	s_nop 0
	v_addc_co_u32_e32 v15, vcc, 0, v7, vcc
	global_load_dword v31, v[14:15], off
	v_add_co_u32_e32 v14, vcc, s13, v6
	s_mov_b32 s13, 0x26000
	s_nop 0
	v_addc_co_u32_e32 v15, vcc, 0, v7, vcc
	global_load_dword v32, v[14:15], off
	v_add_co_u32_e32 v14, vcc, s13, v6
	s_mov_b32 s13, 0x28000
	s_nop 0
	v_addc_co_u32_e32 v15, vcc, 0, v7, vcc
	global_load_dword v33, v[14:15], off
	v_add_co_u32_e32 v14, vcc, s13, v6
	s_mov_b32 s13, 0x2a000
	s_nop 0
	v_addc_co_u32_e32 v15, vcc, 0, v7, vcc
	global_load_dword v34, v[14:15], off
	v_add_co_u32_e32 v14, vcc, s13, v6
	s_mov_b32 s13, 0x2c000
	s_nop 0
	v_addc_co_u32_e32 v15, vcc, 0, v7, vcc
	global_load_dword v35, v[14:15], off
	v_add_co_u32_e32 v14, vcc, s13, v6
	s_mov_b32 s13, 0x2e000
	s_nop 0
	v_addc_co_u32_e32 v15, vcc, 0, v7, vcc
	global_load_dword v36, v[14:15], off
	v_add_co_u32_e32 v14, vcc, s13, v6
	s_mov_b32 s13, 0x30000
	s_nop 0
	v_addc_co_u32_e32 v15, vcc, 0, v7, vcc
	global_load_dword v37, v[14:15], off
	v_add_co_u32_e32 v14, vcc, s13, v6
	s_mov_b32 s13, 0x32000
	s_nop 0
	v_addc_co_u32_e32 v15, vcc, 0, v7, vcc
	global_load_dword v38, v[14:15], off
	v_add_co_u32_e32 v14, vcc, s13, v6
	s_mov_b32 s13, 0x34000
	s_nop 0
	v_addc_co_u32_e32 v15, vcc, 0, v7, vcc
	global_load_dword v39, v[14:15], off
	v_add_co_u32_e32 v14, vcc, s13, v6
	s_mov_b32 s13, 0x36000
	s_nop 0
	v_addc_co_u32_e32 v15, vcc, 0, v7, vcc
	global_load_dword v40, v[14:15], off
	v_add_co_u32_e32 v14, vcc, s13, v6
	s_mov_b32 s13, 0x38000
	s_nop 0
	v_addc_co_u32_e32 v15, vcc, 0, v7, vcc
	global_load_dword v41, v[14:15], off
	v_add_co_u32_e32 v14, vcc, s13, v6
	s_mov_b32 s13, 0x3a000
	s_nop 0
	v_addc_co_u32_e32 v15, vcc, 0, v7, vcc
	global_load_dword v42, v[14:15], off
	v_add_co_u32_e32 v14, vcc, s13, v6
	s_mov_b32 s13, 0x3c000
	s_nop 0
	v_addc_co_u32_e32 v15, vcc, 0, v7, vcc
	global_load_dword v43, v[14:15], off
	v_add_co_u32_e32 v14, vcc, s13, v6
	s_mov_b32 s13, 0x3e000
	s_nop 0
	v_addc_co_u32_e32 v15, vcc, 0, v7, vcc
	v_add_co_u32_e32 v6, vcc, s13, v6
	global_load_dword v14, v[14:15], off
	s_nop 0
	v_addc_co_u32_e32 v7, vcc, 0, v7, vcc
	global_load_dword v6, v[6:7], off
	s_waitcnt vmcnt(0) lgkmcnt(0)
	ds_write2_b32 v5, v0, v13 offset1:66
	ds_write2_b32 v5, v16, v17 offset0:132 offset1:198
	v_add_u32_e32 v0, 0x400, v5
	ds_write2_b32 v0, v18, v19 offset0:8 offset1:74
	ds_write2_b32 v0, v20, v21 offset0:140 offset1:206
	v_add_u32_e32 v0, 0x800, v5
	ds_write2_b32 v0, v22, v23 offset0:16 offset1:82
	ds_write2_b32 v0, v24, v25 offset0:148 offset1:214
	v_add_u32_e32 v0, 0xc00, v5
	ds_write2_b32 v0, v26, v27 offset0:24 offset1:90
	ds_write2_b32 v0, v28, v29 offset0:156 offset1:222
	v_add_u32_e32 v0, 0x1000, v5
	ds_write2_b32 v0, v30, v31 offset0:32 offset1:98
	ds_write2_b32 v0, v32, v33 offset0:164 offset1:230
	v_add_u32_e32 v0, 0x1400, v5
	ds_write2_b32 v0, v34, v35 offset0:40 offset1:106
	ds_write2_b32 v0, v36, v37 offset0:172 offset1:238
	v_add_u32_e32 v0, 0x1800, v5
	ds_write2_b32 v0, v38, v39 offset0:48 offset1:114
	ds_write2_b32 v0, v40, v41 offset0:180 offset1:246
	v_add_u32_e32 v0, 0x1c00, v5
	ds_write2_b32 v0, v42, v43 offset0:56 offset1:122
	ds_write2_b32 v0, v14, v6 offset0:188 offset1:254
	s_add_u32 s22, s11, s1
	s_waitcnt lgkmcnt(0)
	s_addc_u32 s23, s12, 0
	v_lshlrev_b32_e32 v0, 1, v4
	v_lshl_add_u64 v[6:7], s[22:23], 0, v[0:1]
	ds_read_b32 v0, v9
	ds_read_b32 v13, v9 offset:132
	s_mov_b64 s[22:23], 0x500000
	v_lshl_add_u64 v[6:7], v[6:7], 0, s[22:23]
	s_waitcnt lgkmcnt(0)
	v_cvt_pk_bf16_f32 v14, v0, v13
	ds_read_b32 v0, v9 offset:264
	ds_read_b32 v13, v9 offset:396
	s_waitcnt lgkmcnt(0)
	v_cvt_pk_bf16_f32 v15, v0, v13
	ds_read_b32 v0, v9 offset:528
	ds_read_b32 v13, v9 offset:660
	s_waitcnt lgkmcnt(0)
	v_cvt_pk_bf16_f32 v16, v0, v13
	ds_read_b32 v0, v9 offset:792
	ds_read_b32 v13, v9 offset:924
	s_waitcnt lgkmcnt(0)
	v_cvt_pk_bf16_f32 v17, v0, v13
	v_or_b32_e32 v0, s0, v8
	v_lshlrev_b32_e32 v0, 11, v0
	v_lshl_add_u64 v[18:19], v[6:7], 0, v[0:1]
	global_store_dwordx4 v[18:19], v[14:17], off
	ds_read_b32 v0, v9 offset:32
	ds_read_b32 v13, v9 offset:164
	s_waitcnt lgkmcnt(0)
	v_cvt_pk_bf16_f32 v14, v0, v13
	ds_read_b32 v0, v9 offset:296
	ds_read_b32 v13, v9 offset:428
	s_waitcnt lgkmcnt(0)
	v_cvt_pk_bf16_f32 v15, v0, v13
	ds_read_b32 v0, v9 offset:560
	ds_read_b32 v13, v9 offset:692
	s_waitcnt lgkmcnt(0)
	v_cvt_pk_bf16_f32 v16, v0, v13
	ds_read_b32 v0, v9 offset:824
	ds_read_b32 v13, v9 offset:956
	s_waitcnt lgkmcnt(0)
	v_cvt_pk_bf16_f32 v17, v0, v13
	v_or_b32_e32 v0, s0, v10
	v_lshlrev_b32_e32 v0, 11, v0
	v_lshl_add_u64 v[18:19], v[6:7], 0, v[0:1]
	global_store_dwordx4 v[18:19], v[14:17], off
	ds_read_b32 v0, v9 offset:64
	ds_read_b32 v13, v9 offset:196
	s_waitcnt lgkmcnt(0)
	v_cvt_pk_bf16_f32 v14, v0, v13
	ds_read_b32 v0, v9 offset:328
	ds_read_b32 v13, v9 offset:460
	s_waitcnt lgkmcnt(0)
	v_cvt_pk_bf16_f32 v15, v0, v13
	ds_read_b32 v0, v9 offset:592
	ds_read_b32 v13, v9 offset:724
	s_waitcnt lgkmcnt(0)
	v_cvt_pk_bf16_f32 v16, v0, v13
	ds_read_b32 v0, v9 offset:856
	ds_read_b32 v13, v9 offset:988
	s_waitcnt lgkmcnt(0)
	v_cvt_pk_bf16_f32 v17, v0, v13
	v_or_b32_e32 v0, s0, v11
	v_lshlrev_b32_e32 v0, 11, v0
	v_lshl_add_u64 v[18:19], v[6:7], 0, v[0:1]
	global_store_dwordx4 v[18:19], v[14:17], off
	ds_read_b32 v0, v9 offset:96
	ds_read_b32 v13, v9 offset:228
	s_waitcnt lgkmcnt(0)
	v_cvt_pk_bf16_f32 v14, v0, v13
	ds_read_b32 v0, v9 offset:360
	ds_read_b32 v13, v9 offset:492
	s_waitcnt lgkmcnt(0)
	v_cvt_pk_bf16_f32 v15, v0, v13
	ds_read_b32 v0, v9 offset:624
	ds_read_b32 v13, v9 offset:756
	s_waitcnt lgkmcnt(0)
	v_cvt_pk_bf16_f32 v16, v0, v13
	ds_read_b32 v0, v9 offset:888
	ds_read_b32 v13, v9 offset:1020
	s_waitcnt lgkmcnt(0)
	v_cvt_pk_bf16_f32 v17, v0, v13
	v_or_b32_e32 v0, s0, v12
	v_lshlrev_b32_e32 v0, 11, v0
	v_lshl_add_u64 v[6:7], v[6:7], 0, v[0:1]
	global_store_dwordx4 v[6:7], v[14:17], off
	s_waitcnt lgkmcnt(0)

.LBB0_776:
	s_andn2_b64 vcc, exec, s[0:1]
	s_cbranch_vccnz .LBB0_761
	v_readlane_b32 s0, v244, 0
	s_mul_i32 s13, s26, 0x920000
	s_nop 0
	v_mov_b32_e32 v0, s0
	ds_read_b64 v[6:7], v0
	s_waitcnt lgkmcnt(0)
	v_readfirstlane_b32 s1, v6
	v_readfirstlane_b32 s0, v7
	s_add_u32 s1, s1, s13
	s_mul_hi_u32 s13, s26, 0x920000
	s_addc_u32 s17, s0, s13
	s_mul_hi_i32 s0, s4, 0xe070381d
	s_add_i32 s0, s0, s4
	s_lshr_b32 s13, s0, 31
	s_ashr_i32 s0, s0, 6
	s_add_i32 s13, s0, s13
	s_mul_i32 s0, s13, 0xffffffb7
	s_mul_i32 s20, s13, 0x49
	s_add_i32 s23, s4, s0
	s_lshl_b32 s0, s13, 6
	s_mulk_i32 s13, 0xf6e0
	s_add_i32 s22, s5, s13
	s_cmp_gt_i32 s23, 48
	s_cselect_b64 s[26:27], -1, 0
	v_cndmask_b32_e64 v0, 0, -1, s[26:27]
	v_or_b32_e32 v13, s0, v3
	v_readfirstlane_b32 s13, v0
	s_sub_i32 s13, s13, s20
	s_add_i32 s13, s4, s13
	s_lshl_b32 s13, s13, 5
	s_cmp_lg_u32 s23, 48
	s_cselect_b32 s13, s13, 0x900
	s_ashr_i32 s23, s22, 31
	s_lshl_b64 s[22:23], s[22:23], 2
	s_add_u32 s22, s1, s22
	s_addc_u32 s23, s17, s23
	v_lshlrev_b32_e32 v0, 2, v2
	v_lshl_add_u64 v[6:7], s[22:23], 0, v[0:1]
	v_mad_i64_i32 v[14:15], s[22:23], v13, s18, v[6:7]
	global_load_dword v0, v[14:15], off
	v_or_b32_e32 v14, 2, v13
	v_mad_i64_i32 v[14:15], s[22:23], v14, s18, v[6:7]
	global_load_dword v16, v[14:15], off
	v_or_b32_e32 v14, 4, v13
	v_mad_i64_i32 v[14:15], s[22:23], v14, s18, v[6:7]
	global_load_dword v17, v[14:15], off
	v_or_b32_e32 v14, 6, v13
	v_mad_i64_i32 v[14:15], s[22:23], v14, s18, v[6:7]
	global_load_dword v18, v[14:15], off
	v_or_b32_e32 v14, 8, v13
	v_mad_i64_i32 v[14:15], s[22:23], v14, s18, v[6:7]
	global_load_dword v19, v[14:15], off
	v_or_b32_e32 v14, 10, v13
	v_mad_i64_i32 v[14:15], s[22:23], v14, s18, v[6:7]
	global_load_dword v20, v[14:15], off
	v_or_b32_e32 v14, 12, v13
	v_mad_i64_i32 v[14:15], s[22:23], v14, s18, v[6:7]
	global_load_dword v21, v[14:15], off
	v_or_b32_e32 v14, 14, v13
	v_mad_i64_i32 v[14:15], s[22:23], v14, s18, v[6:7]
	global_load_dword v22, v[14:15], off
	v_or_b32_e32 v14, 16, v13
	v_mad_i64_i32 v[14:15], s[22:23], v14, s18, v[6:7]
	global_load_dword v23, v[14:15], off
	v_or_b32_e32 v14, 18, v13
	v_mad_i64_i32 v[14:15], s[22:23], v14, s18, v[6:7]
	global_load_dword v24, v[14:15], off
	v_or_b32_e32 v14, 20, v13
	v_mad_i64_i32 v[14:15], s[22:23], v14, s18, v[6:7]
	global_load_dword v25, v[14:15], off
	v_or_b32_e32 v14, 22, v13
	v_mad_i64_i32 v[14:15], s[22:23], v14, s18, v[6:7]
	global_load_dword v26, v[14:15], off
	v_or_b32_e32 v14, 24, v13
	v_mad_i64_i32 v[14:15], s[22:23], v14, s18, v[6:7]
	global_load_dword v27, v[14:15], off
	v_or_b32_e32 v14, 26, v13
	v_mad_i64_i32 v[14:15], s[22:23], v14, s18, v[6:7]
	global_load_dword v28, v[14:15], off
	v_or_b32_e32 v14, 28, v13
	v_mad_i64_i32 v[14:15], s[22:23], v14, s18, v[6:7]
	global_load_dword v29, v[14:15], off
	v_or_b32_e32 v14, 30, v13
	v_mad_i64_i32 v[14:15], s[22:23], v14, s18, v[6:7]
	global_load_dword v30, v[14:15], off
	v_or_b32_e32 v14, 32, v13
	v_mad_i64_i32 v[14:15], s[22:23], v14, s18, v[6:7]
	global_load_dword v31, v[14:15], off
	v_or_b32_e32 v14, 34, v13
	v_mad_i64_i32 v[14:15], s[22:23], v14, s18, v[6:7]
	global_load_dword v32, v[14:15], off
	v_or_b32_e32 v14, 36, v13
	v_mad_i64_i32 v[14:15], s[22:23], v14, s18, v[6:7]
	global_load_dword v33, v[14:15], off
	v_or_b32_e32 v14, 38, v13
	v_mad_i64_i32 v[14:15], s[22:23], v14, s18, v[6:7]
	global_load_dword v34, v[14:15], off
	v_or_b32_e32 v14, 40, v13
	v_mad_i64_i32 v[14:15], s[22:23], v14, s18, v[6:7]
	global_load_dword v35, v[14:15], off
	v_or_b32_e32 v14, 42, v13
	v_mad_i64_i32 v[14:15], s[22:23], v14, s18, v[6:7]
	global_load_dword v36, v[14:15], off
	v_or_b32_e32 v14, 44, v13
	v_mad_i64_i32 v[14:15], s[22:23], v14, s18, v[6:7]
	global_load_dword v37, v[14:15], off
	v_or_b32_e32 v14, 46, v13
	v_mad_i64_i32 v[14:15], s[22:23], v14, s18, v[6:7]
	global_load_dword v38, v[14:15], off
	v_or_b32_e32 v14, 48, v13
	v_mad_i64_i32 v[14:15], s[22:23], v14, s18, v[6:7]
	global_load_dword v39, v[14:15], off
	v_or_b32_e32 v14, 50, v13
	v_mad_i64_i32 v[14:15], s[22:23], v14, s18, v[6:7]
	global_load_dword v40, v[14:15], off
	v_or_b32_e32 v14, 52, v13
	v_mad_i64_i32 v[14:15], s[22:23], v14, s18, v[6:7]
	global_load_dword v41, v[14:15], off
	v_or_b32_e32 v14, 54, v13
	v_mad_i64_i32 v[14:15], s[22:23], v14, s18, v[6:7]
	global_load_dword v42, v[14:15], off
	v_or_b32_e32 v14, 56, v13
	v_mad_i64_i32 v[14:15], s[22:23], v14, s18, v[6:7]
	global_load_dword v43, v[14:15], off
	v_or_b32_e32 v14, 58, v13
	v_mad_i64_i32 v[14:15], s[22:23], v14, s18, v[6:7]
	global_load_dword v44, v[14:15], off
	v_or_b32_e32 v14, 60, v13
	v_or_b32_e32 v13, 62, v13
	v_mad_i64_i32 v[14:15], s[22:23], v14, s18, v[6:7]
	v_mad_i64_i32 v[6:7], s[22:23], v13, s18, v[6:7]
	global_load_dword v14, v[14:15], off
	s_ashr_i32 s1, s0, 31
	global_load_dword v6, v[6:7], off
	s_waitcnt vmcnt(0) lgkmcnt(0)
	ds_write2_b32 v5, v0, v16 offset1:66
	ds_write2_b32 v5, v17, v18 offset0:132 offset1:198
	v_add_u32_e32 v0, 0x400, v5
	ds_write2_b32 v0, v19, v20 offset0:8 offset1:74
	ds_write2_b32 v0, v21, v22 offset0:140 offset1:206
	v_add_u32_e32 v0, 0x800, v5
	ds_write2_b32 v0, v23, v24 offset0:16 offset1:82
	ds_write2_b32 v0, v25, v26 offset0:148 offset1:214
	v_add_u32_e32 v0, 0xc00, v5
	ds_write2_b32 v0, v27, v28 offset0:24 offset1:90
	ds_write2_b32 v0, v29, v30 offset0:156 offset1:222
	v_add_u32_e32 v0, 0x1000, v5
	ds_write2_b32 v0, v31, v32 offset0:32 offset1:98
	ds_write2_b32 v0, v33, v34 offset0:164 offset1:230
	v_add_u32_e32 v0, 0x1400, v5
	ds_write2_b32 v0, v35, v36 offset0:40 offset1:106
	ds_write2_b32 v0, v37, v38 offset0:172 offset1:238
	v_add_u32_e32 v0, 0x1800, v5
	ds_write2_b32 v0, v39, v40 offset0:48 offset1:114
	ds_write2_b32 v0, v41, v42 offset0:180 offset1:246
	v_add_u32_e32 v0, 0x1c00, v5
	s_lshl_b64 s[0:1], s[0:1], 1
	ds_write2_b32 v0, v43, v44 offset0:56 offset1:122
	ds_write2_b32 v0, v14, v6 offset0:188 offset1:254
	s_add_u32 s0, s11, s0
	s_waitcnt lgkmcnt(0)
	s_addc_u32 s1, s12, s1
	v_lshlrev_b32_e32 v0, 1, v4
	v_lshl_add_u64 v[6:7], s[0:1], 0, v[0:1]
	ds_read_b32 v0, v9
	ds_read_b32 v13, v9 offset:132
	v_or_b32_e32 v18, s13, v8
	v_ashrrev_i32_e32 v19, 31, v18
	v_lshlrev_b64 v[18:19], 11, v[18:19]
	v_lshl_add_u64 v[18:19], v[6:7], 0, v[18:19]
	s_waitcnt lgkmcnt(0)
	v_cvt_pk_bf16_f32 v14, v0, v13
	ds_read_b32 v0, v9 offset:264
	ds_read_b32 v13, v9 offset:396
	v_readlane_b32 s26, v244, 46
	v_readlane_b32 s27, v244, 47
	s_waitcnt lgkmcnt(0)
	v_cvt_pk_bf16_f32 v15, v0, v13
	ds_read_b32 v0, v9 offset:528
	ds_read_b32 v13, v9 offset:660
	s_waitcnt lgkmcnt(0)
	v_cvt_pk_bf16_f32 v16, v0, v13
	ds_read_b32 v0, v9 offset:792
	ds_read_b32 v13, v9 offset:924
	s_waitcnt lgkmcnt(0)
	v_cvt_pk_bf16_f32 v17, v0, v13
	global_store_dwordx4 v[18:19], v[14:17], off
	ds_read_b32 v0, v9 offset:32
	ds_read_b32 v13, v9 offset:164
	v_or_b32_e32 v18, s13, v10
	v_ashrrev_i32_e32 v19, 31, v18
	v_lshlrev_b64 v[18:19], 11, v[18:19]
	v_lshl_add_u64 v[18:19], v[6:7], 0, v[18:19]
	s_waitcnt lgkmcnt(0)
	v_cvt_pk_bf16_f32 v14, v0, v13
	ds_read_b32 v0, v9 offset:296
	ds_read_b32 v13, v9 offset:428
	s_waitcnt lgkmcnt(0)
	v_cvt_pk_bf16_f32 v15, v0, v13
	ds_read_b32 v0, v9 offset:560
	ds_read_b32 v13, v9 offset:692
	s_waitcnt lgkmcnt(0)
	v_cvt_pk_bf16_f32 v16, v0, v13
	ds_read_b32 v0, v9 offset:824
	ds_read_b32 v13, v9 offset:956
	s_waitcnt lgkmcnt(0)
	v_cvt_pk_bf16_f32 v17, v0, v13
	global_store_dwordx4 v[18:19], v[14:17], off
	ds_read_b32 v0, v9 offset:64
	ds_read_b32 v13, v9 offset:196
	v_or_b32_e32 v18, s13, v11
	v_ashrrev_i32_e32 v19, 31, v18
	v_lshlrev_b64 v[18:19], 11, v[18:19]
	v_lshl_add_u64 v[18:19], v[6:7], 0, v[18:19]
	s_waitcnt lgkmcnt(0)
	v_cvt_pk_bf16_f32 v14, v0, v13
	ds_read_b32 v0, v9 offset:328
	ds_read_b32 v13, v9 offset:460
	s_waitcnt lgkmcnt(0)
	v_cvt_pk_bf16_f32 v15, v0, v13
	ds_read_b32 v0, v9 offset:592
	ds_read_b32 v13, v9 offset:724
	s_waitcnt lgkmcnt(0)
	v_cvt_pk_bf16_f32 v16, v0, v13
	ds_read_b32 v0, v9 offset:856
	ds_read_b32 v13, v9 offset:988
	s_waitcnt lgkmcnt(0)
	v_cvt_pk_bf16_f32 v17, v0, v13
	global_store_dwordx4 v[18:19], v[14:17], off
	ds_read_b32 v0, v9 offset:96
	ds_read_b32 v13, v9 offset:228
	v_or_b32_e32 v18, s13, v12
	v_ashrrev_i32_e32 v19, 31, v18
	v_lshlrev_b64 v[18:19], 11, v[18:19]
	v_lshl_add_u64 v[6:7], v[6:7], 0, v[18:19]
	s_waitcnt lgkmcnt(0)
	v_cvt_pk_bf16_f32 v14, v0, v13
	ds_read_b32 v0, v9 offset:360
	ds_read_b32 v13, v9 offset:492
	s_waitcnt lgkmcnt(0)
	v_cvt_pk_bf16_f32 v15, v0, v13
	ds_read_b32 v0, v9 offset:624
	ds_read_b32 v13, v9 offset:756
	s_waitcnt lgkmcnt(0)
	v_cvt_pk_bf16_f32 v16, v0, v13
	ds_read_b32 v0, v9 offset:888
	ds_read_b32 v13, v9 offset:1020
	s_waitcnt lgkmcnt(0)
	v_cvt_pk_bf16_f32 v17, v0, v13
	global_store_dwordx4 v[6:7], v[14:17], off
	s_waitcnt lgkmcnt(0)
	s_branch .LBB0_761
.LBB0_778:
	s_andn2_b64 vcc, exec, s[28:29]
	s_cbranch_vccnz .LBB0_784
	v_mov_b32_e32 v36, v204
	s_mov_b32 s7, s53
	v_mov_b32_e32 v0, s59
	s_waitcnt vmcnt(0) lgkmcnt(0)
	s_barrier
	ds_read_b64 v[2:3], v0
	v_ashrrev_i32_e32 v0, 6, v36
	s_cmpk_gt_i32 s7, 0x87f
	v_readfirstlane_b32 s4, v0
	s_waitcnt lgkmcnt(0)
	v_readfirstlane_b32 s1, v3
	v_readfirstlane_b32 s0, v2
	s_cbranch_scc1 .LBB0_784
	v_readlane_b32 s5, v244, 37
	s_add_u32 s5, s0, s5
	s_addc_u32 s6, s1, 0
	s_lshl_b32 s8, s4, 7
	s_ashr_i32 s9, s8, 31
	s_lshl_b64 s[8:9], s[8:9], 1
	s_add_u32 s10, s5, s8
	v_and_b32_e32 v40, 15, v36
	s_addc_u32 s11, s6, s9
	v_and_b32_e32 v0, 48, v36
	v_lshl_add_u64 v[2:3], s[10:11], 0, v[0:1]
	v_lshlrev_b32_e32 v4, 11, v40
	v_mov_b32_e32 v5, v1
	v_lshl_add_u64 v[2:3], v[2:3], 0, v[4:5]
	s_mov_b32 s5, 0x2480000
	v_add_co_u32_e32 v18, vcc, s5, v2
	s_mov_b32 s5, 0x2488000
	s_nop 0
	v_addc_co_u32_e32 v19, vcc, 0, v3, vcc
	s_mov_b64 s[10:11], 0x2480000
	v_add_co_u32_e32 v30, vcc, s5, v2
	v_lshl_add_u64 v[22:23], v[2:3], 0, s[10:11]
	s_nop 0
	v_addc_co_u32_e32 v31, vcc, 0, v3, vcc
	global_load_dwordx4 v[2:5], v[30:31], off
	global_load_dwordx4 v[6:9], v[30:31], off offset:64
	global_load_dwordx4 v[10:13], v[22:23], off offset:64
	global_load_dwordx4 v[14:17], v[22:23], off offset:128
	s_nop 0
	global_load_dwordx4 v[18:21], v[18:19], off
	s_nop 0
	global_load_dwordx4 v[22:25], v[22:23], off offset:192
	s_nop 0
	global_load_dwordx4 v[26:29], v[30:31], off offset:128
	s_nop 0
	global_load_dwordx4 v[30:33], v[30:31], off offset:192
	s_add_u32 s8, s0, s8
	v_and_b32_e32 v34, 63, v36
	s_addc_u32 s9, s1, s9
	v_lshl_add_u32 v41, v34, 4, 0
	v_lshl_add_u64 v[34:35], s[8:9], 0, v[0:1]
	v_bfe_u32 v43, v36, 6, 1
	v_lshrrev_b32_e32 v0, 2, v36
	v_and_b32_e32 v38, 12, v0
	v_lshlrev_b32_e32 v0, 5, v43
	v_ashrrev_i32_e32 v39, 7, v36
	v_lshl_add_u64 v[36:37], s[0:1], 0, v[0:1]
	v_lshlrev_b32_e32 v0, 1, v40
	v_lshl_add_u64 v[36:37], v[36:37], 0, v[0:1]
	s_mov_b64 s[0:1], 0xe001200
	s_mov_b64 s[8:9], 0x8800000
	v_lshl_add_u64 v[36:37], v[36:37], 0, s[0:1]
	v_lshl_add_u32 v0, v39, 11, v41
	v_lshlrev_b32_e32 v43, 10, v43
	v_readlane_b32 s0, v245, 42
	v_lshl_add_u64 v[34:35], v[34:35], 0, s[8:9]
	s_lshl_b32 s4, s4, 13
	v_mul_lo_u32 v42, v39, s54
	v_mad_u64_u32 v[38:39], s[0:1], s0, v39, v[38:39]
	s_lshl_b32 s5, s7, 4
	v_add_u32_e32 v0, v0, v43
	s_branch .LBB0_782

.LBB0_782:
	v_add_u32_e32 v44, s5, v40
	v_ashrrev_i32_e32 v45, 31, v44
	v_lshlrev_b64 v[44:45], 11, v[44:45]
	v_lshl_add_u64 v[80:81], v[34:35], 0, v[44:45]
	global_load_dwordx4 v[44:47], v[80:81], off
	global_load_dwordx4 v[60:63], v[80:81], off offset:64
	s_add_i32 s6, s7, s54
	s_cmpk_lt_i32 s6, 0x880
	s_cselect_b32 s0, s6, s7
	v_lshl_or_b32 v52, s0, 4, v40
	v_ashrrev_i32_e32 v53, 31, v52
	v_lshlrev_b64 v[52:53], 11, v[52:53]
	v_lshl_add_u64 v[82:83], v[34:35], 0, v[52:53]
	global_load_dwordx4 v[52:55], v[82:83], off
	global_load_dwordx4 v[76:79], v[80:81], off offset:128
	s_add_i32 s0, s83, s7
	s_cmpk_lt_i32 s0, 0x880
	s_cselect_b32 s0, s0, s7
	v_lshl_or_b32 v64, s0, 4, v40
	v_ashrrev_i32_e32 v65, 31, v64
	v_lshlrev_b64 v[64:65], 11, v[64:65]
	v_lshl_add_u64 v[84:85], v[34:35], 0, v[64:65]
	global_load_dwordx4 v[68:71], v[82:83], off offset:64
	s_mul_i32 s0, s54, 3
	s_add_i32 s0, s0, s7
	s_cmpk_lt_i32 s0, 0x880
	s_cselect_b32 s0, s0, s7
	v_lshl_or_b32 v72, s0, 4, v40
	v_ashrrev_i32_e32 v73, 31, v72
	v_lshlrev_b64 v[72:73], 11, v[72:73]
	v_lshl_add_u64 v[86:87], v[34:35], 0, v[72:73]
	v_add_u32_e32 v39, s4, v41
	s_movk_i32 s0, 0x880
	s_waitcnt vmcnt(0) lgkmcnt(0)
	v_mfma_f32_16x16x32_bf16 v[48:51], v[44:47], v[18:21], 0
	v_mfma_f32_16x16x32_bf16 v[44:47], v[44:47], v[2:5], 0
	v_mfma_f32_16x16x32_bf16 v[48:51], v[60:63], v[10:13], v[48:51]
	v_mfma_f32_16x16x32_bf16 v[44:47], v[60:63], v[6:9], v[44:47]
	global_load_dwordx4 v[60:63], v[84:85], off
	v_mfma_f32_16x16x32_bf16 v[48:51], v[76:79], v[14:17], v[48:51]
	v_mfma_f32_16x16x32_bf16 v[44:47], v[76:79], v[26:29], v[44:47]
	global_load_dwordx4 v[76:79], v[84:85], off offset:64
	v_mfma_f32_16x16x32_bf16 v[56:59], v[52:55], v[18:21], 0
	v_mfma_f32_16x16x32_bf16 v[52:55], v[52:55], v[2:5], 0
	s_waitcnt vmcnt(0) lgkmcnt(0)
	v_mfma_f32_16x16x32_bf16 v[64:67], v[60:63], v[18:21], 0
	v_mfma_f32_16x16x32_bf16 v[60:63], v[60:63], v[2:5], 0
	v_mfma_f32_16x16x32_bf16 v[64:67], v[76:79], v[10:13], v[64:67]
	v_mfma_f32_16x16x32_bf16 v[60:63], v[76:79], v[6:9], v[60:63]
	global_load_dwordx4 v[76:79], v[82:83], off offset:128
	v_mfma_f32_16x16x32_bf16 v[56:59], v[68:71], v[10:13], v[56:59]
	v_mfma_f32_16x16x32_bf16 v[52:55], v[68:71], v[6:9], v[52:55]
	global_load_dwordx4 v[68:71], v[86:87], off
	s_waitcnt vmcnt(0) lgkmcnt(0)
	v_mfma_f32_16x16x32_bf16 v[56:59], v[76:79], v[14:17], v[56:59]
	v_mfma_f32_16x16x32_bf16 v[52:55], v[76:79], v[26:29], v[52:55]
	global_load_dwordx4 v[76:79], v[80:81], off offset:192
	v_mfma_f32_16x16x32_bf16 v[72:75], v[68:71], v[18:21], 0
	v_mfma_f32_16x16x32_bf16 v[68:71], v[68:71], v[2:5], 0
	s_waitcnt vmcnt(0) lgkmcnt(0)
	v_mfma_f32_16x16x32_bf16 v[48:51], v[76:79], v[22:25], v[48:51]
	v_mfma_f32_16x16x32_bf16 v[44:47], v[76:79], v[30:33], v[44:47]
	global_load_dwordx4 v[76:79], v[84:85], off offset:128
	s_waitcnt vmcnt(0) lgkmcnt(0)
	v_mfma_f32_16x16x32_bf16 v[64:67], v[76:79], v[14:17], v[64:67]
	v_mfma_f32_16x16x32_bf16 v[60:63], v[76:79], v[26:29], v[60:63]
	global_load_dwordx4 v[76:79], v[82:83], off offset:192
	s_nop 0
	global_load_dwordx4 v[80:83], v[86:87], off offset:192
	s_waitcnt vmcnt(0) lgkmcnt(0)
	v_mfma_f32_16x16x32_bf16 v[56:59], v[76:79], v[22:25], v[56:59]
	v_mfma_f32_16x16x32_bf16 v[52:55], v[76:79], v[30:33], v[52:55]
	global_load_dwordx4 v[76:79], v[84:85], off offset:192
	s_waitcnt vmcnt(0) lgkmcnt(0)
	v_mfma_f32_16x16x32_bf16 v[64:67], v[76:79], v[22:25], v[64:67]
	v_mfma_f32_16x16x32_bf16 v[60:63], v[76:79], v[30:33], v[60:63]
	global_load_dwordx4 v[76:79], v[86:87], off offset:64
	s_waitcnt vmcnt(0) lgkmcnt(0)
	v_mfma_f32_16x16x32_bf16 v[72:75], v[76:79], v[10:13], v[72:75]
	v_mfma_f32_16x16x32_bf16 v[68:71], v[76:79], v[6:9], v[68:71]
	global_load_dwordx4 v[76:79], v[86:87], off offset:128
	ds_write_b128 v39, v[48:51]
	ds_write_b128 v39, v[44:47] offset:1024
	ds_write_b128 v39, v[56:59] offset:2048
	ds_write_b128 v39, v[52:55] offset:3072
	s_waitcnt vmcnt(0) lgkmcnt(0)
	v_mfma_f32_16x16x32_bf16 v[72:75], v[76:79], v[14:17], v[72:75]
	v_mfma_f32_16x16x32_bf16 v[48:51], v[76:79], v[26:29], v[68:71]
	v_mfma_f32_16x16x32_bf16 v[44:47], v[80:83], v[22:25], v[72:75]
	ds_write_b128 v39, v[64:67] offset:4096
	ds_write_b128 v39, v[60:63] offset:5120
	s_nop 5
	ds_write_b128 v39, v[44:47] offset:6144
	v_mfma_f32_16x16x32_bf16 v[44:47], v[80:83], v[30:33], v[48:51]
	s_nop 7
	ds_write_b128 v39, v[44:47] offset:7168
	v_add_u32_e32 v39, s7, v42
	v_cmp_gt_i32_e32 vcc, s0, v39
	s_waitcnt lgkmcnt(0)
	s_barrier
	s_and_saveexec_b64 s[0:1], vcc
	s_cbranch_execz .LBB0_781
	ds_read_b128 v[44:47], v0
	s_waitcnt lgkmcnt(0)
	v_add_f32_e32 v39, 0, v44
	v_add_f32_e32 v43, 0, v45
	v_add_f32_e32 v48, 0, v46
	v_add_f32_e32 v49, 0, v47
	ds_read_b128 v[44:47], v0 offset:8192
	s_waitcnt lgkmcnt(0)
	v_add_f32_e32 v49, v49, v47
	v_add_f32_e32 v48, v48, v46
	v_add_f32_e32 v43, v43, v45
	v_add_f32_e32 v39, v39, v44
	ds_read_b128 v[44:47], v0 offset:16384
	s_waitcnt lgkmcnt(0)
	v_add_f32_e32 v39, v39, v44
	v_add_f32_e32 v43, v43, v45
	v_add_f32_e32 v48, v48, v46
	v_add_f32_e32 v49, v49, v47
	ds_read_b128 v[44:47], v0 offset:24576
	s_waitcnt lgkmcnt(0)
	v_add_f32_e32 v49, v49, v47
	v_add_f32_e32 v48, v48, v46
	v_add_f32_e32 v43, v43, v45
	v_add_f32_e32 v39, v39, v44
	ds_read_b128 v[44:47], v0 offset:32768
	s_waitcnt lgkmcnt(0)
	v_add_f32_e32 v39, v39, v44
	v_add_f32_e32 v43, v43, v45
	v_add_f32_e32 v48, v48, v46
	v_add_f32_e32 v49, v49, v47
	ds_read_b128 v[44:47], v0 offset:40960
	s_waitcnt lgkmcnt(0)
	v_add_f32_e32 v49, v49, v47
	v_add_f32_e32 v48, v48, v46
	v_add_f32_e32 v43, v43, v45
	v_add_f32_e32 v39, v39, v44
	ds_read_b128 v[44:47], v0 offset:49152
	s_waitcnt lgkmcnt(0)
	v_add_f32_e32 v39, v39, v44
	v_add_f32_e32 v43, v43, v45
	v_add_f32_e32 v48, v48, v46
	v_add_f32_e32 v49, v49, v47
	ds_read_b128 v[44:47], v0 offset:57344
	s_waitcnt lgkmcnt(0)
	v_add_f32_e32 v46, v48, v46
	v_add_f32_e32 v39, v39, v44
	v_add_u32_e32 v48, s5, v38
	v_add_f32_e32 v43, v43, v45
	v_cvt_pk_bf16_f32 v39, v39, s0
	v_mad_i64_i32 v[44:45], s[8:9], v48, s94, v[36:37]
	global_store_short v[44:45], v39, off
	v_cvt_pk_bf16_f32 v39, v43, s0
	v_add_u32_e32 v43, 1, v48
	v_mad_i64_i32 v[44:45], s[8:9], v43, s94, v[36:37]
	v_add_u32_e32 v43, 2, v48
	v_add_f32_e32 v47, v49, v47
	global_store_short v[44:45], v39, off
	v_cvt_pk_bf16_f32 v39, v46, s0
	v_mad_i64_i32 v[44:45], s[8:9], v43, s94, v[36:37]
	v_add_u32_e32 v43, 3, v48
	global_store_short v[44:45], v39, off
	v_cvt_pk_bf16_f32 v39, v47, s0
	v_mad_i64_i32 v[44:45], s[8:9], v43, s94, v[36:37]
	global_store_short v[44:45], v39, off
	s_branch .LBB0_781

.LBB0_796:
	v_mov_b32_e32 v6, v204
	s_mov_b32 s13, s53
	s_lshl_b32 s13, s13, 3
	v_readfirstlane_b32 s6, v6
	s_ashr_i32 s6, s6, 6
	s_add_i32 s6, s13, s6
	s_cmp_gt_i32 s6, 0x87ff
	s_cbranch_scc1 .LBB0_804
	v_readlane_b32 s22, v244, 33
	v_readlane_b32 s23, v244, 34
	s_lshl_b64 s[22:23], s[22:23], 2
	s_add_u32 s12, s12, s22
	s_addc_u32 s13, s7, s23
	v_readlane_b32 s22, v244, 35
	v_readlane_b32 s23, v244, 36
	s_lshl_b64 s[22:23], s[22:23], 2
	s_add_u32 s7, s11, s22
	s_addc_u32 s20, s10, s23
	s_add_u32 s17, s7, 0x100000
	s_addc_u32 s20, s20, 0
	s_add_i32 s78, s6, 0xffff8000
	s_ashr_i32 s7, s6, 31
	s_cmp_lt_i32 s6, 0x8000
	s_cselect_b32 s23, s7, 0
	s_cselect_b32 s22, s6, s78
	s_cselect_b32 s25, s1, s5
	s_cselect_b32 s26, s0, s4
	s_lshl_b64 s[22:23], s[22:23], 12
	v_lshlrev_b32_e32 v0, 2, v6
	s_add_u32 s22, s26, s22
	v_and_b32_e32 v54, 0xfc, v0
	s_addc_u32 s23, s25, s23
	v_lshlrev_b32_e32 v0, 2, v54
	v_lshl_add_u64 v[2:3], s[22:23], 0, v[0:1]
	s_waitcnt vmcnt(0)
	global_load_dwordx4 v[30:33], v[2:3], off
	global_load_dwordx4 v[18:21], v[2:3], off offset:1024
	global_load_dwordx4 v[10:13], v[2:3], off offset:2048
	s_nop 0
	global_load_dwordx4 v[2:5], v[2:3], off offset:3072
	s_cmp_lg_u64 s[8:9], 0
	s_cselect_b64 s[26:27], -1, 0
	v_lshl_add_u64 v[56:57], s[8:9], 0, v[0:1]
	s_lshl_b64 s[8:9], s[6:7], 11
	v_lshl_add_u64 v[58:59], s[12:13], 0, v[0:1]
	v_and_b32_e32 v0, 63, v6
	s_add_u32 s8, s11, s8
	v_lshlrev_b32_e32 v0, 3, v0
	s_addc_u32 s9, s10, s9
	v_lshl_add_u64 v[6:7], s[8:9], 0, v[0:1]
	s_mov_b64 s[8:9], 0x8800000
	v_or_b32_e32 v8, 0x100, v54
	v_or_b32_e32 v14, 0x200, v54
	v_or_b32_e32 v16, 0x300, v54
	v_lshl_add_u64 v[60:61], v[6:7], 0, s[8:9]
	s_add_i32 s22, s6, s60
	v_mov_b32_e32 v6, 0
	s_ashr_i32 s23, s22, 31
	s_xor_b64 s[6:7], s[26:27], -1
	v_lshlrev_b32_e32 v62, 2, v8
	v_lshlrev_b32_e32 v64, 2, v14
	v_lshlrev_b32_e32 v66, 2, v16
	v_mov_b32_e32 v7, v6
	v_mov_b32_e32 v8, v6
	v_mov_b32_e32 v9, v6
	v_mov_b32_e32 v14, v6
	v_mov_b32_e32 v15, v6
	v_mov_b32_e32 v16, v6
	v_mov_b32_e32 v17, v6
	v_mov_b32_e32 v22, v6
	v_mov_b32_e32 v23, v6
	v_mov_b32_e32 v24, v6
	v_mov_b32_e32 v25, v6
	v_mov_b32_e32 v26, v6
	v_mov_b32_e32 v27, v6
	v_mov_b32_e32 v28, v6
	v_mov_b32_e32 v29, v6
	s_branch .LBB0_799
.LBB0_798:
	s_min_i32 s10, s26, 0x8000
	s_ashr_i32 s10, s10, 12
	s_mul_hi_i32 s11, s10, 0x6000
	s_mulk_i32 s10, 0x6000
	s_add_u32 s12, s17, s10
	s_addc_u32 s13, s20, s11
	s_add_u32 s10, s12, 0x1000
	s_addc_u32 s11, s13, 0
	v_lshl_add_u64 v[38:39], s[10:11], 0, v[0:1]
	global_load_dwordx4 v[34:37], v[58:59], off
	v_lshl_add_u64 v[46:47], s[12:13], 0, v[0:1]
	global_load_dwordx4 v[38:41], v[38:39], off
	s_waitcnt vmcnt(0) lgkmcnt(0)
	v_mul_f32_e32 v0, v31, v31
	global_load_dwordx4 v[42:45], v[46:47], off
	v_mul_f32_e32 v48, v33, v33
	v_mul_f32_e32 v49, v19, v19
	v_mul_f32_e32 v50, v21, v21
	v_mul_f32_e32 v51, v11, v11
	v_mul_f32_e32 v52, v13, v13
	v_fmac_f32_e32 v0, v30, v30
	v_fmac_f32_e32 v48, v32, v32
	v_fmac_f32_e32 v49, v18, v18
	v_fmac_f32_e32 v50, v20, v20
	v_mul_f32_e32 v53, v3, v3
	v_mul_f32_e32 v55, v5, v5
	v_fmac_f32_e32 v51, v10, v10
	v_fmac_f32_e32 v52, v12, v12
	v_add_f32_e32 v0, v0, v48
	v_add_f32_e32 v48, v49, v50
	v_fmac_f32_e32 v53, v2, v2
	v_fmac_f32_e32 v55, v4, v4
	v_add_f32_e32 v49, v51, v52
	v_add_f32_e32 v0, v0, v48
	v_add_f32_e32 v50, v53, v55
	v_add_f32_e32 v0, v49, v0
	v_add_f32_e32 v0, v50, v0
	ds_bpermute_b32 v48, v205, v0
	v_mov_b32_e32 v63, v1
	v_mov_b32_e32 v65, v1
	v_mov_b32_e32 v67, v1
	s_add_u32 s22, s22, s60
	s_waitcnt lgkmcnt(0)
	v_add_f32_e32 v0, v0, v48
	ds_bpermute_b32 v48, v206, v0
	s_mov_b32 s78, s25
	s_addc_u32 s23, s23, s61
	s_and_b64 vcc, exec, s[8:9]
	s_waitcnt lgkmcnt(0)
	v_add_f32_e32 v0, v0, v48
	ds_bpermute_b32 v48, v207, v0
	s_waitcnt lgkmcnt(0)
	v_add_f32_e32 v0, v0, v48
	ds_bpermute_b32 v48, v208, v0
	s_waitcnt lgkmcnt(0)
	v_add_f32_e32 v0, v0, v48
	ds_bpermute_b32 v48, v209, v0
	s_waitcnt lgkmcnt(0)
	v_add_f32_e32 v0, v0, v48
	ds_bpermute_b32 v48, v215, v0
	s_waitcnt lgkmcnt(0)
	v_add_f32_e32 v0, v0, v48
	v_fmamk_f32 v0, v0, 0x3a800000, v210
	v_rsq_f32_e32 v0, v0
	s_nop 0
	v_mul_f32_e32 v33, v33, v0
	v_mul_f32_e32 v32, v32, v0
	v_mul_f32_e32 v31, v31, v0
	v_mul_f32_e32 v30, v30, v0
	v_mul_f32_e32 v21, v21, v0
	v_mul_f32_e32 v20, v20, v0
	v_mul_f32_e32 v19, v19, v0
	v_mul_f32_e32 v18, v18, v0
	v_mul_f32_e32 v13, v13, v0
	v_mul_f32_e32 v12, v12, v0
	v_mul_f32_e32 v11, v11, v0
	v_mul_f32_e32 v10, v10, v0
	v_mul_f32_e32 v30, v34, v30
	v_mul_f32_e32 v31, v35, v31
	v_mul_f32_e32 v32, v36, v32
	v_mul_f32_e32 v33, v37, v33
	v_add_f32_e32 v34, 1.0, v38
	v_add_f32_e32 v35, 1.0, v39
	v_add_f32_e32 v36, 1.0, v40
	v_add_f32_e32 v37, 1.0, v41
	s_waitcnt vmcnt(0)
	v_fma_f32 v33, v37, v33, v45
	v_fma_f32 v32, v36, v32, v44
	v_fma_f32 v31, v35, v31, v43
	v_fmac_f32_e32 v42, v34, v30
	v_cvt_pk_bf16_f32 v30, v42, v31
	v_cvt_pk_bf16_f32 v31, v32, v33
	global_store_dwordx2 v[60:61], v[30:31], off
	global_load_dwordx4 v[30:33], v[58:59], off offset:1024
	v_lshl_add_u64 v[34:35], s[10:11], 0, v[62:63]
	global_load_dwordx4 v[34:37], v[34:35], off
	s_nop 0
	global_load_dwordx4 v[38:41], v[46:47], off offset:1024
	v_mul_f32_e32 v48, v3, v0
	v_mov_b32_e32 v3, v27
	s_waitcnt vmcnt(0) lgkmcnt(0)
	v_mul_f32_e32 v18, v30, v18
	v_mul_f32_e32 v19, v31, v19
	v_mul_f32_e32 v20, v32, v20
	v_mul_f32_e32 v21, v33, v21
	v_add_f32_e32 v30, 1.0, v34
	v_add_f32_e32 v31, 1.0, v35
	v_add_f32_e32 v32, 1.0, v36
	v_add_f32_e32 v33, 1.0, v37
	v_fma_f32 v21, v33, v21, v41
	v_fma_f32 v20, v32, v20, v40
	v_fma_f32 v19, v31, v19, v39
	v_fmac_f32_e32 v38, v30, v18
	v_cvt_pk_bf16_f32 v18, v38, v19
	v_cvt_pk_bf16_f32 v19, v20, v21
	global_store_dwordx2 v[60:61], v[18:19], off offset:512
	global_load_dwordx4 v[18:21], v[58:59], off offset:2048
	v_lshl_add_u64 v[30:31], s[10:11], 0, v[64:65]
	global_load_dwordx4 v[30:33], v[30:31], off
	s_nop 0
	global_load_dwordx4 v[34:37], v[46:47], off offset:2048
	s_waitcnt vmcnt(0) lgkmcnt(0)
	v_mul_f32_e32 v10, v18, v10
	v_mul_f32_e32 v11, v19, v11
	v_mul_f32_e32 v12, v20, v12
	v_mul_f32_e32 v13, v21, v13
	v_add_f32_e32 v18, 1.0, v30
	v_add_f32_e32 v19, 1.0, v31
	v_add_f32_e32 v20, 1.0, v32
	v_add_f32_e32 v21, 1.0, v33
	v_fma_f32 v13, v21, v13, v37
	v_fma_f32 v12, v20, v12, v36
	v_fma_f32 v11, v19, v11, v35
	v_fmac_f32_e32 v34, v18, v10
	v_cvt_pk_bf16_f32 v10, v34, v11
	v_cvt_pk_bf16_f32 v11, v12, v13
	global_store_dwordx2 v[60:61], v[10:11], off offset:1024
	global_load_dwordx4 v[34:37], v[58:59], off offset:3072
	v_lshl_add_u64 v[10:11], s[10:11], 0, v[66:67]
	global_load_dwordx4 v[38:41], v[10:11], off
	global_load_dwordx4 v[42:45], v[46:47], off offset:3072
	v_mul_f32_e32 v46, v5, v0
	v_mul_f32_e32 v47, v4, v0
	v_mul_f32_e32 v0, v2, v0
	v_mov_b32_e32 v30, v6
	v_mov_b32_e32 v31, v7
	v_mov_b32_e32 v32, v8
	v_mov_b32_e32 v33, v9
	v_mov_b32_e32 v18, v14
	v_mov_b32_e32 v19, v15
	v_mov_b32_e32 v20, v16
	v_mov_b32_e32 v21, v17
	v_mov_b32_e32 v10, v22
	v_mov_b32_e32 v11, v23
	v_mov_b32_e32 v12, v24
	v_mov_b32_e32 v13, v25
	v_mov_b32_e32 v2, v26
	v_mov_b32_e32 v4, v28
	v_mov_b32_e32 v5, v29
	s_waitcnt vmcnt(0) lgkmcnt(0)
	v_mul_f32_e32 v0, v0, v34
	v_mul_f32_e32 v34, v48, v35
	v_mul_f32_e32 v35, v47, v36
	v_mul_f32_e32 v36, v46, v37
	v_add_f32_e32 v37, 1.0, v38
	v_add_f32_e32 v38, 1.0, v39
	v_add_f32_e32 v39, 1.0, v40
	v_add_f32_e32 v40, 1.0, v41
	v_fma_f32 v36, v36, v40, v45
	v_fma_f32 v35, v35, v39, v44
	v_fma_f32 v34, v34, v38, v43
	v_fmac_f32_e32 v42, v0, v37
	v_cvt_pk_bf16_f32 v34, v42, v34
	v_cvt_pk_bf16_f32 v35, v35, v36
	global_store_dwordx2 v[60:61], v[34:35], off offset:1536
	v_lshl_add_u64 v[60:61], v[60:61], 0, s[80:81]
	s_cbranch_vccnz .LBB0_803
.LBB0_799:
	s_add_i32 s25, s60, s78
	s_add_i32 s10, s25, 0x8000
	s_cmp_gt_i32 s10, 0x87ff
	s_cselect_b64 s[8:9], -1, 0
	s_and_b64 vcc, exec, s[8:9]
	v_lshlrev_b32_e32 v0, 2, v54
	s_cbranch_vccnz .LBB0_801
	s_cmp_lt_i32 s10, 0x8000
	s_cselect_b32 s11, s23, 0
	s_cselect_b32 s10, s22, s25
	s_cselect_b32 s12, s1, s5
	s_cselect_b32 s13, s0, s4
	s_lshl_b64 s[10:11], s[10:11], 12
	s_add_u32 s10, s13, s10
	s_addc_u32 s11, s12, s11
	v_lshl_add_u64 v[26:27], s[10:11], 0, v[0:1]
	global_load_dwordx4 v[6:9], v[26:27], off
	global_load_dwordx4 v[14:17], v[26:27], off offset:1024
	global_load_dwordx4 v[22:25], v[26:27], off offset:2048
	s_nop 0
	global_load_dwordx4 v[26:29], v[26:27], off offset:3072
.LBB0_801:
	s_add_i32 s26, s78, 0x8000
	s_cmp_lt_i32 s26, 0x8000
	s_cselect_b64 s[10:11], -1, 0
	s_or_b64 s[10:11], s[6:7], s[10:11]
	s_and_b64 vcc, exec, s[10:11]
	s_cbranch_vccnz .LBB0_798
	v_mov_b32_e32 v34, s59
	ds_read_b64 v[34:35], v34
	s_lshl_b64 s[10:11], s[78:79], 12
	s_mov_b64 s[28:29], 0xcc00000
	v_mov_b32_e32 v63, v1
	v_mov_b32_e32 v65, v1
	s_waitcnt lgkmcnt(0)
	v_readfirstlane_b32 s12, v34
	v_readfirstlane_b32 s13, v35
	s_add_u32 s12, s12, s10
	s_addc_u32 s13, s13, s11
	s_add_u32 s10, s12, 0xd400000
	v_lshl_add_u64 v[68:69], s[12:13], 0, v[0:1]
	s_addc_u32 s11, s13, 0
	v_add_co_u32_e32 v34, vcc, s89, v68
	s_add_u32 s12, s12, 0x1f800000
	s_nop 0
	v_addc_co_u32_e32 v35, vcc, 0, v69, vcc
	s_addc_u32 s13, s13, 0
	v_lshl_add_u64 v[38:39], s[10:11], 0, v[0:1]
	v_add_co_u32_e32 v42, vcc, s44, v68
	global_load_dwordx4 v[34:37], v[34:35], off
	s_nop 0
	v_addc_co_u32_e32 v43, vcc, 0, v69, vcc
	global_load_dwordx4 v[38:41], v[38:39], off
	v_lshl_add_u64 v[46:47], s[12:13], 0, v[0:1]
	global_load_dwordx4 v[42:45], v[42:43], off
	s_nop 0
	global_load_dwordx4 v[46:49], v[46:47], off
	s_nop 0
	global_load_dwordx4 v[50:53], v[56:57], off
	v_lshl_add_u64 v[88:89], v[68:69], 0, s[28:29]
	s_mov_b64 s[28:29], 0x1f000000
	v_lshl_add_u64 v[70:71], v[68:69], 0, s[28:29]
	v_add_co_u32_e32 v90, vcc, s90, v68
	v_lshl_add_u64 v[80:81], s[10:11], 0, v[62:63]
	v_lshl_add_u64 v[84:85], s[12:13], 0, v[62:63]
	v_addc_co_u32_e32 v91, vcc, 0, v69, vcc
	global_load_dwordx4 v[72:75], v[88:89], off offset:1024
	global_load_dwordx4 v[76:79], v[70:71], off offset:1024
	s_nop 0
	global_load_dwordx4 v[80:83], v[80:81], off
	s_mov_b64 s[28:29], 0x8000000
	global_load_dwordx4 v[84:87], v[84:85], off
	v_lshl_add_u64 v[68:69], v[68:69], 0, s[28:29]
	s_waitcnt vmcnt(0) lgkmcnt(0)
	v_add_f32_e32 v37, v37, v41
	v_add_f32_e32 v36, v36, v40
	v_add_f32_e32 v35, v35, v39
	v_add_f32_e32 v34, v34, v38
	v_add_f32_e32 v38, v45, v49
	v_add_f32_e32 v39, v44, v48
	v_add_f32_e32 v40, v43, v47
	v_add_f32_e32 v41, v42, v46
	v_add_f32_e32 v34, v34, v41
	v_add_f32_e32 v35, v35, v40
	v_add_f32_e32 v36, v36, v39
	v_add_f32_e32 v37, v37, v38
	v_fmac_f32_e32 v33, v53, v37
	v_fmac_f32_e32 v32, v52, v36
	v_fmac_f32_e32 v31, v51, v35
	v_fmac_f32_e32 v30, v50, v34
	global_store_dwordx4 v[90:91], v[30:33], off
	global_load_dwordx4 v[50:53], v[56:57], off offset:1024
	v_lshl_add_u64 v[42:43], s[10:11], 0, v[64:65]
	global_load_dwordx4 v[38:41], v[88:89], off offset:2048
	global_load_dwordx4 v[34:37], v[70:71], off offset:2048
	global_load_dwordx4 v[46:49], v[42:43], off
	v_lshl_add_u64 v[42:43], s[12:13], 0, v[64:65]
	v_add_f32_e32 v55, v75, v83
	v_add_f32_e32 v63, v74, v82
	v_add_f32_e32 v65, v73, v81
	v_add_f32_e32 v67, v72, v80
	v_add_f32_e32 v72, v79, v87
	v_add_f32_e32 v73, v78, v86
	v_add_f32_e32 v74, v77, v85
	v_add_f32_e32 v75, v76, v84
	v_add_f32_e32 v67, v67, v75
	v_add_f32_e32 v65, v65, v74
	v_add_f32_e32 v63, v63, v73
	v_add_f32_e32 v55, v55, v72
	global_load_dwordx4 v[42:45], v[42:43], off
	s_waitcnt vmcnt(0) lgkmcnt(0)
	v_fmac_f32_e32 v21, v53, v55
	v_fmac_f32_e32 v20, v52, v63
	v_fmac_f32_e32 v19, v51, v65
	v_fmac_f32_e32 v18, v50, v67
	global_store_dwordx4 v[68:69], v[18:21], off offset:1024
	global_load_dwordx4 v[50:53], v[56:57], off offset:2048
	v_mov_b32_e32 v67, v1
	v_lshl_add_u64 v[80:81], s[10:11], 0, v[66:67]
	v_add_f32_e32 v41, v41, v49
	v_add_f32_e32 v40, v40, v48
	v_add_f32_e32 v39, v39, v47
	v_add_f32_e32 v38, v38, v46
	global_load_dwordx4 v[72:75], v[88:89], off offset:3072
	global_load_dwordx4 v[76:79], v[70:71], off offset:3072
	s_nop 0
	global_load_dwordx4 v[80:83], v[80:81], off
	v_lshl_add_u64 v[70:71], s[12:13], 0, v[66:67]
	global_load_dwordx4 v[84:87], v[70:71], off
	v_add_f32_e32 v37, v37, v45
	v_add_f32_e32 v36, v36, v44
	v_add_f32_e32 v35, v35, v43
	v_add_f32_e32 v34, v34, v42
	v_add_f32_e32 v34, v38, v34
	v_add_f32_e32 v35, v39, v35
	v_add_f32_e32 v36, v40, v36
	v_add_f32_e32 v37, v41, v37
	s_waitcnt vmcnt(0) lgkmcnt(0)
	v_fmac_f32_e32 v13, v53, v37
	v_fmac_f32_e32 v12, v52, v36
	v_fmac_f32_e32 v11, v51, v35
	v_fmac_f32_e32 v10, v50, v34
	global_store_dwordx4 v[68:69], v[10:13], off offset:2048
	global_load_dwordx4 v[34:37], v[56:57], off offset:3072
	v_add_f32_e32 v38, v75, v83
	v_add_f32_e32 v39, v74, v82
	v_add_f32_e32 v40, v73, v81
	v_add_f32_e32 v41, v72, v80
	v_add_f32_e32 v42, v79, v87
	v_add_f32_e32 v43, v78, v86
	v_add_f32_e32 v44, v77, v85
	v_add_f32_e32 v45, v76, v84
	v_add_f32_e32 v41, v41, v45
	v_add_f32_e32 v40, v40, v44
	v_add_f32_e32 v39, v39, v43
	v_add_f32_e32 v38, v38, v42
	s_waitcnt vmcnt(0) lgkmcnt(0)
	v_fmac_f32_e32 v5, v37, v38
	v_fmac_f32_e32 v4, v36, v39
	v_fmac_f32_e32 v3, v35, v40
	v_fmac_f32_e32 v2, v34, v41
	global_store_dwordx4 v[68:69], v[2:5], off offset:3072
	s_branch .LBB0_798

.LBB0_809:
	v_mov_b64_e32 v[12:13], s[56:57]
	global_load_dword v2, v[12:13], off offset:1024 sc1
	s_waitcnt lgkmcnt(0)
	global_load_dword v0, v[12:13], off offset:1280 sc1
	global_load_dword v3, v[12:13], off offset:1536 sc1
	s_or_b64 s[10:11], s[10:11], exec
	s_or_b64 s[8:9], s[8:9], exec
	s_waitcnt vmcnt(0) lgkmcnt(0)
	v_add_u32_e32 v4, v0, v2
	v_add_u32_e32 v5, v4, v3
	global_load_dword v4, v[12:13], off offset:1792 sc1
	s_waitcnt vmcnt(0) lgkmcnt(0)
	v_add_u32_e32 v6, v5, v4
	global_load_dword v5, v[12:13], off offset:2048 sc1
	s_waitcnt vmcnt(0) lgkmcnt(0)
	v_add_u32_e32 v7, v6, v5
	global_load_dword v6, v[12:13], off offset:2304 sc1
	s_waitcnt vmcnt(0) lgkmcnt(0)
	v_add_u32_e32 v8, v7, v6
	global_load_dword v7, v[12:13], off offset:2560 sc1
	s_waitcnt vmcnt(0) lgkmcnt(0)
	v_add_u32_e32 v9, v8, v7
	global_load_dword v8, v[12:13], off offset:2816 sc1
	s_waitcnt vmcnt(0) lgkmcnt(0)
	v_add_u32_e32 v10, v9, v8
	global_load_dword v9, v[12:13], off offset:3072 sc1
	s_waitcnt vmcnt(0) lgkmcnt(0)
	v_add_u32_e32 v11, v10, v9
	global_load_dword v10, v[12:13], off offset:3328 sc1
	s_waitcnt vmcnt(0) lgkmcnt(0)
	v_add_u32_e32 v14, v11, v10
	global_load_dword v11, v[12:13], off offset:3584 sc1
	s_waitcnt vmcnt(0) lgkmcnt(0)
	v_add_u32_e32 v14, v14, v11
	global_load_dword v12, v[12:13], off offset:3840 sc1
	s_waitcnt vmcnt(0) lgkmcnt(0)
	v_add_u32_e32 v16, v14, v12
	v_mov_b64_e32 v[14:15], s[64:65]
	global_load_dword v13, v[14:15], off sc1
	v_mov_b64_e32 v[14:15], s[66:67]
	global_load_dword v14, v[14:15], off sc1
	s_waitcnt vmcnt(0) lgkmcnt(0)
	v_add_u32_e32 v16, v16, v13
	v_add_u32_e32 v18, v16, v14
	v_mov_b64_e32 v[16:17], s[68:69]
	global_load_dword v15, v[16:17], off sc1
	v_mov_b64_e32 v[16:17], s[70:71]
	global_load_dword v16, v[16:17], off sc1
	s_waitcnt vmcnt(0) lgkmcnt(0)
	v_add_u32_e32 v18, v18, v15
	v_add_u32_e32 v17, v18, v16
	v_cmp_ne_u32_e32 vcc, s55, v17
	s_and_saveexec_b64 s[12:13], vcc
	s_cbranch_execz .LBB0_808
	s_and_b32 s20, s17, 0xff
	s_mov_b64 s[36:37], -1
	s_cmp_eq_u32 s20, 0
	s_mov_b64 s[40:41], -1
	s_mov_b64 s[38:39], -1
	s_sleep 1
	s_cbranch_scc1 .LBB0_812
	s_and_saveexec_b64 s[42:43], s[40:41]
	s_cbranch_execz .LBB0_807
	s_branch .LBB0_815
.LBB0_812:
	v_mov_b64_e32 v[18:19], s[74:75]
	global_load_dword v17, v[18:19], off sc1
	s_mov_b64 s[40:41], 0
	s_waitcnt vmcnt(0) lgkmcnt(0)
	v_cmp_eq_u32_e32 vcc, 0, v17
	s_and_saveexec_b64 s[42:43], vcc
	s_cmp_lt_u32 s17, 0x400001
	s_cselect_b64 s[22:23], -1, 0
	s_xor_b64 s[38:39], exec, -1
	s_and_b64 s[40:41], s[22:23], exec
	s_or_b64 exec, exec, s[42:43]
	s_and_saveexec_b64 s[42:43], s[40:41]
	s_cbranch_execz .LBB0_807

.LBB0_819:
	flat_atomic_add v4, v[142:143], v214 sc0
	v_cvt_f32_u32_e32 v3, v2
	v_sub_u32_e32 v5, 0, v2
	v_rcp_iflag_f32_e32 v3, v3
	s_nop 0
	v_mul_f32_e32 v3, 0x4f7ffffe, v3
	v_cvt_u32_f32_e32 v3, v3
	v_mul_lo_u32 v5, v5, v3
	v_mul_hi_u32 v5, v3, v5
	v_add_u32_e32 v3, v3, v5
	s_waitcnt vmcnt(0) lgkmcnt(0)
	v_mul_hi_u32 v3, v4, v3
	v_mul_lo_u32 v5, v3, v2
	v_sub_u32_e32 v5, v4, v5
	v_cmp_ge_u32_e32 vcc, v5, v2
	v_add_u32_e32 v6, 1, v3
	s_nop 0
	v_cndmask_b32_e32 v3, v3, v6, vcc
	v_sub_u32_e32 v6, v5, v2
	v_cndmask_b32_e32 v5, v5, v6, vcc
	v_cmp_ge_u32_e32 vcc, v5, v2
	v_add_u32_e32 v5, 1, v3
	v_add_u32_e32 v6, 1, v4
	v_cndmask_b32_e32 v3, v3, v5, vcc
	v_mad_u64_u32 v[4:5], s[4:5], v2, v3, v[2:3]
	v_cmp_ne_u32_e32 vcc, v6, v4
	s_and_saveexec_b64 s[4:5], vcc
	s_xor_b64 s[4:5], exec, s[4:5]
	s_cbranch_execz .LBB0_832
	global_load_dword v0, v[144:145], off sc1
	s_waitcnt vmcnt(0) lgkmcnt(0)
	v_cmp_eq_u32_e32 vcc, v0, v3
	s_and_saveexec_b64 s[6:7], vcc
	s_cbranch_execz .LBB0_831
	s_mov_b32 s17, 1
	s_mov_b64 s[8:9], 0
	s_branch .LBB0_823

.LBB0_823:
	s_and_b32 s20, s17, 0xff
	s_mov_b64 s[36:37], -1
	s_cmp_lg_u32 s20, 0
	s_mov_b64 s[38:39], -1
	s_sleep 1
	s_cbranch_scc1 .LBB0_827
	v_mov_b64_e32 v[4:5], s[74:75]
	global_load_dword v0, v[4:5], off sc1
	s_mov_b64 s[38:39], 0
	s_mov_b64 s[40:41], -1
	s_waitcnt vmcnt(0) lgkmcnt(0)
	v_cmp_eq_u32_e32 vcc, 0, v0
	s_and_saveexec_b64 s[42:43], vcc
	s_cmp_lt_u32 s17, 0x400001
	s_cselect_b64 s[22:23], -1, 0
	s_xor_b64 s[40:41], exec, -1
	s_and_b64 s[38:39], s[22:23], exec
	s_or_b64 exec, exec, s[42:43]
.LBB0_827:
	s_andn2_b64 s[12:13], s[12:13], exec
	s_and_b64 s[22:23], s[40:41], exec
	s_or_b64 s[12:13], s[12:13], s[22:23]
	s_and_saveexec_b64 s[40:41], s[38:39]
	s_cbranch_execz .LBB0_822
	global_load_dword v0, v[144:145], off sc1
	s_add_i32 s17, s17, 1
	s_or_b64 s[12:13], s[12:13], exec
	s_waitcnt vmcnt(0) lgkmcnt(0)
	v_cmp_ne_u32_e32 vcc, v0, v3
	s_orn2_b64 s[36:37], vcc, exec
	s_branch .LBB0_822

.LBB0_832:
	s_andn2_saveexec_b64 s[4:5], s[4:5]
	s_cbranch_execz .LBB0_139
	v_readlane_b32 s4, v245, 38
	v_readlane_b32 s5, v245, 39
	buffer_wbl2 sc1
	s_waitcnt vmcnt(0)
	v_sub_u32_e32 v4, 0, v0
	v_mov_b64_e32 v[2:3], s[4:5]
	flat_atomic_add v2, v[2:3], v214 sc0
	v_cvt_f32_u32_e32 v3, v0
	s_mov_b64 s[6:7], -1
	v_rcp_iflag_f32_e32 v3, v3
	s_nop 0
	v_mul_f32_e32 v3, 0x4f7ffffe, v3
	v_cvt_u32_f32_e32 v3, v3
	v_mul_lo_u32 v4, v4, v3
	v_mul_hi_u32 v4, v3, v4
	v_add_u32_e32 v3, v3, v4
	s_waitcnt vmcnt(0) lgkmcnt(0)
	v_mul_hi_u32 v3, v2, v3
	v_mul_lo_u32 v4, v3, v0
	v_sub_u32_e32 v4, v2, v4
	v_cmp_ge_u32_e32 vcc, v4, v0
	v_add_u32_e32 v5, 1, v3
	s_nop 0
	v_cndmask_b32_e32 v3, v3, v5, vcc
	v_sub_u32_e32 v5, v4, v0
	v_cndmask_b32_e32 v4, v4, v5, vcc
	v_cmp_ge_u32_e32 vcc, v4, v0
	v_add_u32_e32 v4, 1, v3
	v_add_u32_e32 v5, 1, v2
	v_cndmask_b32_e32 v4, v3, v4, vcc
	v_mad_u64_u32 v[2:3], s[4:5], v0, v4, v[0:1]
	v_cmp_ne_u32_e32 vcc, v5, v2
	v_mov_b64_e32 v[2:3], s[76:77]
	s_and_saveexec_b64 s[4:5], vcc
	s_cbranch_execz .LBB0_845
	v_mov_b64_e32 v[2:3], s[76:77]
	global_load_dword v0, v[2:3], off sc1
	s_mov_b64 s[8:9], 0
	s_waitcnt vmcnt(0) lgkmcnt(0)
	v_cmp_eq_u32_e32 vcc, v0, v4
	s_and_saveexec_b64 s[6:7], vcc
	s_cbranch_execz .LBB0_844
	s_mov_b32 s17, 1
	s_branch .LBB0_837

.LBB0_839:
	v_mov_b64_e32 v[2:3], s[74:75]
	global_load_dword v0, v[2:3], off sc1
	s_mov_b64 s[38:39], 0
	s_mov_b64 s[36:37], -1
	s_waitcnt vmcnt(0) lgkmcnt(0)
	v_cmp_eq_u32_e32 vcc, 0, v0
	s_and_saveexec_b64 s[40:41], vcc
	s_cmp_lt_u32 s17, 0x400001
	s_cselect_b64 s[22:23], -1, 0
	s_xor_b64 s[36:37], exec, -1
	s_and_b64 s[38:39], s[22:23], exec
	s_or_b64 exec, exec, s[40:41]
	s_and_saveexec_b64 s[40:41], s[38:39]
	s_cbranch_execz .LBB0_836
.LBB0_842:
	v_mov_b64_e32 v[2:3], s[76:77]
	global_load_dword v0, v[2:3], off sc1
	s_add_i32 s17, s17, 1
	s_or_b64 s[36:37], s[36:37], exec
	s_waitcnt vmcnt(0) lgkmcnt(0)
	v_cmp_ne_u32_e32 vcc, v0, v4
	s_orn2_b64 s[12:13], vcc, exec
	s_branch .LBB0_836

.LBB0_851:
	global_load_dwordx4 v[6:9], v[2:3], off
	global_load_dwordx4 v[10:13], v[2:3], off offset:1024
	global_load_dwordx4 v[14:17], v[2:3], off offset:2048
	global_load_dwordx4 v[18:21], v[2:3], off offset:3072
	global_load_dwordx4 v[22:25], v[0:1], off
	s_add_i32 s0, s0, s60
	s_cmp_lt_i32 s0, 0x8000
	s_waitcnt vmcnt(0) lgkmcnt(0)
	v_mul_f32_e32 v26, v7, v7
	v_mul_f32_e32 v27, v9, v9
	v_mul_f32_e32 v28, v11, v11
	v_mul_f32_e32 v29, v13, v13
	v_mul_f32_e32 v30, v15, v15
	v_mul_f32_e32 v31, v17, v17
	v_fmac_f32_e32 v26, v6, v6
	v_fmac_f32_e32 v27, v8, v8
	v_fmac_f32_e32 v28, v10, v10
	v_fmac_f32_e32 v29, v12, v12
	v_mul_f32_e32 v32, v19, v19
	v_mul_f32_e32 v33, v21, v21
	v_fmac_f32_e32 v30, v14, v14
	v_fmac_f32_e32 v31, v16, v16
	v_add_f32_e32 v26, v26, v27
	v_add_f32_e32 v27, v28, v29
	v_fmac_f32_e32 v32, v18, v18
	v_fmac_f32_e32 v33, v20, v20
	v_add_f32_e32 v28, v30, v31
	v_add_f32_e32 v26, v26, v27
	v_add_f32_e32 v29, v32, v33
	v_add_f32_e32 v26, v26, v28
	v_add_f32_e32 v26, v26, v29
	ds_bpermute_b32 v27, v205, v26
	s_waitcnt lgkmcnt(0)
	v_add_f32_e32 v26, v26, v27
	ds_bpermute_b32 v27, v206, v26
	s_waitcnt lgkmcnt(0)
	v_add_f32_e32 v26, v26, v27
	ds_bpermute_b32 v27, v207, v26
	s_waitcnt lgkmcnt(0)
	v_add_f32_e32 v26, v26, v27
	ds_bpermute_b32 v27, v208, v26
	s_waitcnt lgkmcnt(0)
	v_add_f32_e32 v26, v26, v27
	ds_bpermute_b32 v27, v209, v26
	s_waitcnt lgkmcnt(0)
	v_add_f32_e32 v26, v26, v27
	ds_bpermute_b32 v27, v4, v26
	s_waitcnt lgkmcnt(0)
	v_add_f32_e32 v26, v26, v27
	v_fmamk_f32 v26, v26, 0x3a800000, v5
	v_rsq_f32_e32 v26, v26
	s_nop 0
	v_mul_f32_e32 v6, v6, v26
	v_mul_f32_e32 v7, v7, v26
	v_mul_f32_e32 v8, v8, v26
	v_mul_f32_e32 v9, v9, v26
	v_mul_f32_e32 v9, v25, v9
	v_mul_f32_e32 v8, v24, v8
	v_mul_f32_e32 v7, v23, v7
	v_mul_f32_e32 v6, v22, v6
	global_store_dwordx4 v[2:3], v[6:9], off
	global_load_dwordx4 v[6:9], v[0:1], off offset:1024
	v_mul_f32_e32 v10, v10, v26
	v_mul_f32_e32 v11, v11, v26
	v_mul_f32_e32 v12, v12, v26
	v_mul_f32_e32 v13, v13, v26
	s_waitcnt vmcnt(0) lgkmcnt(0)
	v_mul_f32_e32 v9, v9, v13
	v_mul_f32_e32 v8, v8, v12
	v_mul_f32_e32 v7, v7, v11
	v_mul_f32_e32 v6, v6, v10
	global_store_dwordx4 v[2:3], v[6:9], off offset:1024
	global_load_dwordx4 v[6:9], v[0:1], off offset:2048
	v_mul_f32_e32 v10, v14, v26
	v_mul_f32_e32 v11, v15, v26
	v_mul_f32_e32 v12, v16, v26
	v_mul_f32_e32 v13, v17, v26
	s_waitcnt vmcnt(0) lgkmcnt(0)
	v_mul_f32_e32 v9, v9, v13
	v_mul_f32_e32 v8, v8, v12
	v_mul_f32_e32 v7, v7, v11
	v_mul_f32_e32 v6, v6, v10
	global_store_dwordx4 v[2:3], v[6:9], off offset:2048
	global_load_dwordx4 v[6:9], v[0:1], off offset:3072
	v_mul_f32_e32 v10, v18, v26
	v_mul_f32_e32 v11, v19, v26
	v_mul_f32_e32 v12, v20, v26
	v_mul_f32_e32 v13, v21, v26
	s_waitcnt vmcnt(0) lgkmcnt(0)
	v_mul_f32_e32 v9, v9, v13
	v_mul_f32_e32 v8, v8, v12
	v_mul_f32_e32 v7, v7, v11
	v_mul_f32_e32 v6, v6, v10
	global_store_dwordx4 v[2:3], v[6:9], off offset:3072
	v_lshl_add_u64 v[2:3], v[2:3], 0, s[2:3]
	s_cbranch_scc1 .LBB0_851
